# hoist first-iteration epilogue loads (residual/E/sse) into the tile header before the K loop
# baseline (speedup 1.0000x reference)
; __device__ __forceinline__ float bflo(unsigned w) { return __uint_as_float(w << 16); }
; __device__ __forceinline__ float bfhi(unsigned w) { return __uint_as_float(w & 0xffff0000u); }
;     __device__ __forceinline__ void operator()(const f32x4 (&acc)[2][2][4][2], const Unit& u, int wr, int wc, int fr, int fq) const {
;     ...
;             for (int m = 0; m < 4; ++m) { const int row = row0 + ai * HALF + m * 16; const size_t off = (size_t)row * D + col0; float sq = 0.f; u32x4 w[2];
;                 const float sc = rsin ? __builtin_amdgcn_rcpf(rsin[row] * (1.f / D) + EPS) : 1.0f;
;                 u32x4 rr[2]; if (R) load_pair_lines(R, D, row, fr, col0, rr[0], rr[1]);
; #pragma unroll
;                 for (int bj = 0; bj < 2; ++bj) { f32x4 r0, r1;
;                     if (R) { const u32x4 rw = rr[bj]; r0 = (f32x4){bflo(rw.x), bfhi(rw.x), bflo(rw.y), bfhi(rw.y)}; r1 = (f32x4){bflo(rw.z), bfhi(rw.z), bflo(rw.w), bfhi(rw.w)}; }
;                     else { const float* rp = (row < 8192 ? src_p + off : src_s + (off - (size_t)8192 * D)) + 8 * bj; r0 = *(const f32x4*)rp; r1 = *(const f32x4*)(rp + 4); }
; template <class Epi>
; __device__ __forceinline__ void gemm_phase(LAS unsigned char* lds, const Gemm g, const StaticOrder& S, const Epi& E) {
;     ...
; #pragma unroll
;         for (int a = 0; a < 2; ++a)
; #pragma unroll
;             for (int b = 0; b < 2; ++b)
; #pragma unroll
;                 for (int m = 0; m < 4; ++m)
; #pragma unroll
;                     for (int n = 0; n < 2; ++n) acc[a][b][m][n] = (f32x4){0.f, 0.f, 0.f, 0.f};
;         cur = nxt; cA = nA; cB = nB; ++ui;
.LBB0_612:
	s_ashr_i32 s43, s42, 31
	s_xor_b64 s[46:47], s[58:59], -1
	s_lshl_b64 s[44:45], s[42:43], 20
	s_add_u32 s44, s61, s44
	s_addc_u32 s45, s62, s45
	s_and_b64 s[48:49], s[58:59], exec
	s_cselect_b32 s43, s45, s55
	s_cselect_b32 s51, s44, s54
	s_ashr_i32 s41, s40, 31
	s_lshl_b64 s[48:49], s[40:41], 20
	s_add_u32 s48, s63, s48
	s_addc_u32 s49, s64, s49
	s_and_b64 s[58:59], s[58:59], exec
	s_cselect_b32 s41, s49, s57
	s_cselect_b32 s85, s48, s56
	s_add_u32 s54, s54, 0x80080
	s_addc_u32 s55, s55, 0
	s_add_u32 s86, s56, 0x100
	v_mov_b32_e32 v0, 0
	s_addc_u32 s87, s57, 0
	s_mov_b32 s88, -2
	s_waitcnt lgkmcnt(0)
	v_mov_b32_e32 v1, v0
	v_mov_b32_e32 v2, v0
	v_mov_b32_e32 v3, v0
	v_mov_b32_e32 v4, v0
	v_mov_b32_e32 v5, v0
	v_mov_b32_e32 v6, v0
	v_mov_b32_e32 v7, v0
	v_mov_b32_e32 v16, v0
	v_mov_b32_e32 v17, v0
	v_mov_b32_e32 v18, v0
	v_mov_b32_e32 v19, v0
	s_waitcnt vmcnt(0)
	v_mov_b32_e32 v20, v0
	v_mov_b32_e32 v21, v0
	v_mov_b32_e32 v22, v0
	v_mov_b32_e32 v23, v0
	v_mov_b32_e32 v32, v0
	v_mov_b32_e32 v33, v0
	v_mov_b32_e32 v34, v0
	v_mov_b32_e32 v35, v0
	v_mov_b32_e32 v36, v0
	v_mov_b32_e32 v37, v0
	v_mov_b32_e32 v38, v0
	v_mov_b32_e32 v39, v0
	v_mov_b32_e32 v48, v0
	v_mov_b32_e32 v49, v0
	v_mov_b32_e32 v50, v0
	v_mov_b32_e32 v51, v0
	v_mov_b32_e32 v52, v0
	v_mov_b32_e32 v53, v0
	v_mov_b32_e32 v54, v0
	v_mov_b32_e32 v55, v0
	v_mov_b32_e32 v8, v0
	v_mov_b32_e32 v9, v0
	v_mov_b32_e32 v10, v0
	v_mov_b32_e32 v11, v0
	v_mov_b32_e32 v12, v0
	v_mov_b32_e32 v13, v0
	v_mov_b32_e32 v14, v0
	v_mov_b32_e32 v15, v0
	v_mov_b32_e32 v24, v0
	v_mov_b32_e32 v25, v0
	v_mov_b32_e32 v26, v0
	v_mov_b32_e32 v27, v0
	v_mov_b32_e32 v28, v0
	v_mov_b32_e32 v29, v0
	v_mov_b32_e32 v30, v0
	v_mov_b32_e32 v31, v0
	v_mov_b32_e32 v40, v0
	v_mov_b32_e32 v41, v0
	v_mov_b32_e32 v42, v0
	v_mov_b32_e32 v43, v0
	v_mov_b32_e32 v44, v0
	v_mov_b32_e32 v45, v0
	v_mov_b32_e32 v46, v0
	v_mov_b32_e32 v47, v0
	v_mov_b32_e32 v56, v0
	v_mov_b32_e32 v57, v0
	v_mov_b32_e32 v58, v0
	v_mov_b32_e32 v59, v0
	v_mov_b32_e32 v60, v0
	v_mov_b32_e32 v61, v0
	v_mov_b32_e32 v62, v0
	v_mov_b32_e32 v63, v0
	v_mov_b32_e32 v64, v0
	v_mov_b32_e32 v65, v0
	v_mov_b32_e32 v66, v0
	v_mov_b32_e32 v67, v0
	v_mov_b32_e32 v68, v0
	v_mov_b32_e32 v69, v0
	v_mov_b32_e32 v70, v0
	v_mov_b32_e32 v71, v0
	v_mov_b32_e32 v80, v0
	v_mov_b32_e32 v81, v0
	v_mov_b32_e32 v82, v0
	v_mov_b32_e32 v83, v0
	v_mov_b32_e32 v84, v0
	v_mov_b32_e32 v85, v0
	v_mov_b32_e32 v86, v0
	v_mov_b32_e32 v87, v0
	v_mov_b32_e32 v96, v0
	v_mov_b32_e32 v97, v0
	v_mov_b32_e32 v98, v0
	v_mov_b32_e32 v99, v0
	v_mov_b32_e32 v100, v0
	v_mov_b32_e32 v101, v0
	v_mov_b32_e32 v102, v0
	v_mov_b32_e32 v103, v0
	v_mov_b32_e32 v112, v0
	v_mov_b32_e32 v113, v0
	v_mov_b32_e32 v114, v0
	v_mov_b32_e32 v115, v0
	v_mov_b32_e32 v116, v0
	v_mov_b32_e32 v117, v0
	v_mov_b32_e32 v118, v0
	v_mov_b32_e32 v119, v0
	v_mov_b32_e32 v72, v0
	v_mov_b32_e32 v73, v0
	v_mov_b32_e32 v74, v0
	v_mov_b32_e32 v75, v0
	v_mov_b32_e32 v76, v0
	v_mov_b32_e32 v77, v0
	v_mov_b32_e32 v78, v0
	v_mov_b32_e32 v79, v0
	v_mov_b32_e32 v88, v0
	v_mov_b32_e32 v89, v0
	v_mov_b32_e32 v90, v0
	v_mov_b32_e32 v91, v0
	v_mov_b32_e32 v92, v0
	v_mov_b32_e32 v93, v0
	v_mov_b32_e32 v94, v0
	v_mov_b32_e32 v95, v0
	v_mov_b32_e32 v104, v0
	v_mov_b32_e32 v105, v0
	v_mov_b32_e32 v106, v0
	v_mov_b32_e32 v107, v0
	v_mov_b32_e32 v108, v0
	v_mov_b32_e32 v109, v0
	v_mov_b32_e32 v110, v0
	v_mov_b32_e32 v111, v0
	v_mov_b32_e32 v120, v0
	v_mov_b32_e32 v121, v0
	v_mov_b32_e32 v122, v0
	v_mov_b32_e32 v123, v0
	v_mov_b32_e32 v124, v0
	v_mov_b32_e32 v125, v0
	v_mov_b32_e32 v126, v0
	v_mov_b32_e32 v127, v0
	s_lshl_b32 s33, s52, 8
	s_add_i32 s33, s33, s74
	v_or_b32_e32 v146, s33, v150
	v_lshl_or_b32 v148, s50, 8, v154
	v_ashrrev_i32_e32 v147, 31, v146
	v_ashrrev_i32_e32 v149, 31, v148
	v_lshlrev_b64 v[158:159], 11, v[146:147]
	v_lshl_add_u64 v[158:159], v[158:159], 0, v[148:149]
	v_lshlrev_b64 v[158:159], 2, v[158:159]
	v_lshl_add_u64 v[160:161], s[16:17], 0, v[158:159]
	v_lshl_add_u64 v[158:159], s[18:19], 0, v[158:159]
	v_lshl_add_u64 v[158:159], v[158:159], 0, s[38:39]
	v_cmp_gt_i32_e32 vcc, s70, v146
	s_nop 1
	v_cndmask_b32_e32 v163, v159, v161, vcc
	v_cndmask_b32_e32 v162, v158, v160, vcc
	global_load_dwordx4 v[232:235], v[162:163], off
	global_load_dwordx4 v[236:239], v[162:163], off offset:16
; #define PG8_STAGE(bufoff, gbase, voff) do { _Pragma("unroll") for (int _i = 0; _i < 2; ++_i) \
;         __builtin_amdgcn_global_load_lds((const unsigned*)((const char*)(gbase) + (voff)[_i]), (LAS unsigned*)(lds + (bufoff) + ldsw + _i * 8192), 16, 0, 0); } while (0)
; #define PG8_LDA(dst, b, h) do { _Pragma("unroll") for (int m = 0; m < 4; ++m) _Pragma("unroll") for (int k = 0; k < 2; ++k) dst[m][k] = *(const LAS bf16x8*)(lds + PG8_SA(b, h) + aoff + m * 2048 + k * 1024); } while (0)
; #define PG8_LDB(dst, b, h) do { _Pragma("unroll") for (int n = 0; n < 2; ++n) _Pragma("unroll") for (int k = 0; k < 2; ++k) dst[n][k] = *(const LAS bf16x8*)(lds + PG8_SB(b, h) + boff + n * 2048 + k * 1024); } while (0)
; #define PG8_MMA(ai, bj, At, Bt) do { __builtin_amdgcn_s_setprio(1); _Pragma("unroll") for (int m = 0; m < 4; ++m) _Pragma("unroll") for (int n = 0; n < 2; ++n) _Pragma("unroll") for (int k = 0; k < 2; ++k) \
;         acc[ai][bj][m][n] = __builtin_amdgcn_mfma_f32_16x16x32_bf16(Bt[n][k], At[m][k], acc[ai][bj][m][n], 0, 0, 0); __builtin_amdgcn_s_setprio(0); } while (0)
; #define PG8_WAIT_L(n) asm volatile("s_waitcnt lgkmcnt(" #n ")" ::: "memory")
; #define PG8_BAR __builtin_amdgcn_s_barrier()
; #define PG8_SCHED __builtin_amdgcn_sched_barrier(0)
; template <class Epi>
; __device__ __forceinline__ void gemm_phase(LAS unsigned char* lds, const Gemm g, const StaticOrder& S, const Epi& E) {
;     ...
;             PG8_LDB(B0, 0, 0); PG8_SCHED; PG8_LDA(At, 0, 0); PG8_STAGE(PG8_SA(1, 1), a1 + hstep, voffA);
;             PG8_WAIT_L(8); PG8_BAR; PG8_WAIT_L(0); PG8_MMA(0, 0, At, B0); PG8_BAR; PG8_SCHED;
;             PG8_LDB(B1, 0, 1); PG8_STAGE(PG8_SB(0, 0), b2, voffB0);
;             PG8_BAR; PG8_WAIT_L(0); PG8_MMA(0, 1, At, B1); PG8_BAR;
;             PG8_LDA(At, 0, 1); PG8_STAGE(PG8_SA(0, 0), a2, voffA);
;             PG8_BAR; PG8_WAIT_L(0); PG8_MMA(1, 0, At, B0); PG8_BAR; PG8_SCHED;
.LBB0_613:
	ds_read_b128 v[146:149], v155
	ds_read_b128 v[158:161], v155 offset:1024
	ds_read_b128 v[162:165], v155 offset:2048
	ds_read_b128 v[166:169], v155 offset:3072
	s_add_u32 s33, s54, 0xfff80080
	s_addc_u32 s56, s55, -1
	s_cmp_eq_u32 s88, 28
	s_cselect_b32 s57, s43, s56
	s_cselect_b32 s56, s51, s33
	s_cselect_b32 s59, s41, s87
	s_cselect_b32 s58, s85, s86
	v_lshl_add_u64 v[204:205], s[54:55], 0, v[140:141]
	s_add_i32 m0, s53, 0xc000
	ds_read_b128 v[170:173], v156
	ds_read_b128 v[174:177], v156 offset:1024
	ds_read_b128 v[178:181], v156 offset:2048
	ds_read_b128 v[182:185], v156 offset:3072
	ds_read_b128 v[186:189], v156 offset:4096
	ds_read_b128 v[190:193], v156 offset:5120
	ds_read_b128 v[194:197], v156 offset:6144
	ds_read_b128 v[198:201], v156 offset:7168
	global_load_lds_dwordx4 v[204:205], off
	v_lshl_add_u64 v[204:205], s[54:55], 0, v[142:143]
	s_add_i32 m0, s53, 0xe000
	s_nop 0
	global_load_lds_dwordx4 v[204:205], off
	s_waitcnt lgkmcnt(8)
	s_barrier
	s_waitcnt lgkmcnt(0)
	v_mfma_f32_16x16x32_bf16 v[124:127], v[146:149], v[170:173], v[124:127]
	v_mfma_f32_16x16x32_bf16 v[120:123], v[162:165], v[170:173], v[120:123]
	v_mfma_f32_16x16x32_bf16 v[108:111], v[146:149], v[178:181], v[108:111]
	v_mfma_f32_16x16x32_bf16 v[104:107], v[162:165], v[178:181], v[104:107]
	v_mfma_f32_16x16x32_bf16 v[92:95], v[146:149], v[186:189], v[92:95]
	v_mfma_f32_16x16x32_bf16 v[88:91], v[162:165], v[186:189], v[88:91]
	v_mfma_f32_16x16x32_bf16 v[76:79], v[146:149], v[194:197], v[76:79]
	v_mfma_f32_16x16x32_bf16 v[72:75], v[162:165], v[194:197], v[72:75]
	v_mfma_f32_16x16x32_bf16 v[124:127], v[158:161], v[174:177], v[124:127]
	v_mfma_f32_16x16x32_bf16 v[120:123], v[166:169], v[174:177], v[120:123]
	v_mfma_f32_16x16x32_bf16 v[108:111], v[158:161], v[182:185], v[108:111]
	v_mfma_f32_16x16x32_bf16 v[104:107], v[166:169], v[182:185], v[104:107]
	v_mfma_f32_16x16x32_bf16 v[92:95], v[158:161], v[190:193], v[92:95]
	v_mfma_f32_16x16x32_bf16 v[88:91], v[166:169], v[190:193], v[88:91]
	v_mfma_f32_16x16x32_bf16 v[76:79], v[158:161], v[198:201], v[76:79]
	v_mfma_f32_16x16x32_bf16 v[72:75], v[166:169], v[198:201], v[72:75]
	s_barrier
	s_add_i32 s33, s79, s65
	v_lshl_add_u64 v[220:221], s[58:59], 0, v[130:131]
	s_mov_b32 m0, s33
	ds_read_b128 v[204:207], v157
	ds_read_b128 v[208:211], v157 offset:1024
	ds_read_b128 v[212:215], v157 offset:2048
	ds_read_b128 v[216:219], v157 offset:3072
	global_load_lds_dwordx4 v[220:221], off
	v_lshl_add_u64 v[222:223], s[58:59], 0, v[136:137]
	s_add_i32 m0, s33, 0x2000
	s_nop 0
	global_load_lds_dwordx4 v[222:223], off
	s_barrier
	s_waitcnt lgkmcnt(0)
	v_mfma_f32_16x16x32_bf16 v[116:119], v[204:207], v[170:173], v[116:119]
	v_mfma_f32_16x16x32_bf16 v[112:115], v[212:215], v[170:173], v[112:115]
	v_mfma_f32_16x16x32_bf16 v[100:103], v[204:207], v[178:181], v[100:103]
	v_mfma_f32_16x16x32_bf16 v[96:99], v[212:215], v[178:181], v[96:99]
	v_mfma_f32_16x16x32_bf16 v[84:87], v[204:207], v[186:189], v[84:87]
	v_mfma_f32_16x16x32_bf16 v[80:83], v[212:215], v[186:189], v[80:83]
	v_mfma_f32_16x16x32_bf16 v[68:71], v[204:207], v[194:197], v[68:71]
	v_mfma_f32_16x16x32_bf16 v[64:67], v[212:215], v[194:197], v[64:67]
	v_mfma_f32_16x16x32_bf16 v[116:119], v[208:211], v[174:177], v[116:119]
	v_mfma_f32_16x16x32_bf16 v[112:115], v[216:219], v[174:177], v[112:115]
	v_mfma_f32_16x16x32_bf16 v[100:103], v[208:211], v[182:185], v[100:103]
	v_mfma_f32_16x16x32_bf16 v[96:99], v[216:219], v[182:185], v[96:99]
	v_mfma_f32_16x16x32_bf16 v[84:87], v[208:211], v[190:193], v[84:87]
	v_mfma_f32_16x16x32_bf16 v[80:83], v[216:219], v[190:193], v[80:83]
	v_mfma_f32_16x16x32_bf16 v[68:71], v[208:211], v[198:201], v[68:71]
	v_mfma_f32_16x16x32_bf16 v[64:67], v[216:219], v[198:201], v[64:67]
	s_mov_b32 m0, s53
	v_lshl_add_u64 v[224:225], s[56:57], 0, v[128:129]
	s_barrier
	ds_read_b128 v[170:173], v156 offset:16384
	ds_read_b128 v[174:177], v156 offset:17408
	ds_read_b128 v[178:181], v156 offset:18432
	ds_read_b128 v[182:185], v156 offset:19456
	ds_read_b128 v[186:189], v156 offset:20480
	ds_read_b128 v[190:193], v156 offset:21504
	ds_read_b128 v[194:197], v156 offset:22528
	ds_read_b128 v[198:201], v156 offset:23552
	global_load_lds_dwordx4 v[224:225], off
	v_lshl_add_u64 v[226:227], s[56:57], 0, v[134:135]
	s_mov_b32 m0, s66
	s_nop 0
	global_load_lds_dwordx4 v[226:227], off
	s_barrier
	s_waitcnt lgkmcnt(0)
	v_mfma_f32_16x16x32_bf16 v[60:63], v[146:149], v[170:173], v[60:63]
	v_mfma_f32_16x16x32_bf16 v[56:59], v[162:165], v[170:173], v[56:59]
	v_mfma_f32_16x16x32_bf16 v[44:47], v[146:149], v[178:181], v[44:47]
	v_mfma_f32_16x16x32_bf16 v[40:43], v[162:165], v[178:181], v[40:43]
	v_mfma_f32_16x16x32_bf16 v[28:31], v[146:149], v[186:189], v[28:31]
	v_mfma_f32_16x16x32_bf16 v[24:27], v[162:165], v[186:189], v[24:27]
	v_mfma_f32_16x16x32_bf16 v[12:15], v[146:149], v[194:197], v[12:15]
	v_mfma_f32_16x16x32_bf16 v[8:11], v[162:165], v[194:197], v[8:11]
	v_mfma_f32_16x16x32_bf16 v[60:63], v[158:161], v[174:177], v[60:63]
	v_mfma_f32_16x16x32_bf16 v[56:59], v[166:169], v[174:177], v[56:59]
	v_mfma_f32_16x16x32_bf16 v[44:47], v[158:161], v[182:185], v[44:47]
	v_mfma_f32_16x16x32_bf16 v[40:43], v[166:169], v[182:185], v[40:43]
	v_mfma_f32_16x16x32_bf16 v[28:31], v[158:161], v[190:193], v[28:31]
	v_mfma_f32_16x16x32_bf16 v[24:27], v[166:169], v[190:193], v[24:27]
	v_mfma_f32_16x16x32_bf16 v[12:15], v[158:161], v[198:201], v[12:15]
	v_mfma_f32_16x16x32_bf16 v[8:11], v[166:169], v[198:201], v[8:11]
	s_barrier
; #define PG8_STAGE(bufoff, gbase, voff) do { _Pragma("unroll") for (int _i = 0; _i < 2; ++_i) \
;         __builtin_amdgcn_global_load_lds((const unsigned*)((const char*)(gbase) + (voff)[_i]), (LAS unsigned*)(lds + (bufoff) + ldsw + _i * 8192), 16, 0, 0); } while (0)
; #define PG8_LDA(dst, b, h) do { _Pragma("unroll") for (int m = 0; m < 4; ++m) _Pragma("unroll") for (int k = 0; k < 2; ++k) dst[m][k] = *(const LAS bf16x8*)(lds + PG8_SA(b, h) + aoff + m * 2048 + k * 1024); } while (0)
; #define PG8_LDB(dst, b, h) do { _Pragma("unroll") for (int n = 0; n < 2; ++n) _Pragma("unroll") for (int k = 0; k < 2; ++k) dst[n][k] = *(const LAS bf16x8*)(lds + PG8_SB(b, h) + boff + n * 2048 + k * 1024); } while (0)
; #define PG8_MMA(ai, bj, At, Bt) do { __builtin_amdgcn_s_setprio(1); _Pragma("unroll") for (int m = 0; m < 4; ++m) _Pragma("unroll") for (int n = 0; n < 2; ++n) _Pragma("unroll") for (int k = 0; k < 2; ++k) \
;         acc[ai][bj][m][n] = __builtin_amdgcn_mfma_f32_16x16x32_bf16(Bt[n][k], At[m][k], acc[ai][bj][m][n], 0, 0, 0); __builtin_amdgcn_s_setprio(0); } while (0)
; #define PG8_WAIT_V(n) asm volatile("s_waitcnt vmcnt(" #n ")" ::: "memory")
; #define PG8_WAIT_L(n) asm volatile("s_waitcnt lgkmcnt(" #n ")" ::: "memory")
; #define PG8_BAR __builtin_amdgcn_s_barrier()
; #define PG8_SCHED __builtin_amdgcn_sched_barrier(0)
; template <class Epi>
; __device__ __forceinline__ void gemm_phase(LAS unsigned char* lds, const Gemm g, const StaticOrder& S, const Epi& E) {
;     ...
;             PG8_STAGE(PG8_SB(0, 1), b2, voffB1);
;             PG8_WAIT_V(6); PG8_BAR; PG8_MMA(1, 1, At, B1); PG8_BAR;
;             PG8_LDB(B0, 1, 0); PG8_SCHED; PG8_LDA(At, 1, 0); PG8_STAGE(PG8_SA(0, 1), a2 + hstep, voffA);
;             PG8_WAIT_L(8); PG8_BAR; PG8_WAIT_L(0); PG8_MMA(0, 0, At, B0); PG8_BAR; PG8_SCHED;
;             PG8_LDB(B1, 1, 1); PG8_STAGE(PG8_SB(1, 0), b3, voffB0);
;             PG8_BAR; PG8_WAIT_L(0); PG8_MMA(0, 1, At, B1); PG8_BAR;
;             PG8_LDA(At, 1, 1); PG8_STAGE(PG8_SA(1, 0), a3, voffA);
;             PG8_BAR; PG8_WAIT_L(0); PG8_MMA(1, 0, At, B0); PG8_BAR; PG8_SCHED;
	s_add_i32 s33, s80, s65
	v_lshl_add_u64 v[228:229], s[58:59], 0, v[132:133]
	s_mov_b32 m0, s33
	v_lshl_add_u64 v[230:231], s[58:59], 0, v[138:139]
	global_load_lds_dwordx4 v[228:229], off
	s_add_i32 m0, s33, 0x2000
	s_nop 0
	global_load_lds_dwordx4 v[230:231], off
	s_add_i32 s33, 0, 0x18000
	v_add_u32_e32 v166, s33, v151
	ds_read_b128 v[146:149], v166
	ds_read_b128 v[158:161], v166 offset:1024
	ds_read_b128 v[162:165], v166 offset:2048
	ds_read_b128 v[166:169], v166 offset:3072
	s_waitcnt vmcnt(6)
	s_barrier
	v_mfma_f32_16x16x32_bf16 v[52:55], v[204:207], v[170:173], v[52:55]
	v_mfma_f32_16x16x32_bf16 v[48:51], v[212:215], v[170:173], v[48:51]
	v_mfma_f32_16x16x32_bf16 v[36:39], v[204:207], v[178:181], v[36:39]
	v_mfma_f32_16x16x32_bf16 v[32:35], v[212:215], v[178:181], v[32:35]
	v_mfma_f32_16x16x32_bf16 v[20:23], v[204:207], v[186:189], v[20:23]
	v_mfma_f32_16x16x32_bf16 v[16:19], v[212:215], v[186:189], v[16:19]
	v_mfma_f32_16x16x32_bf16 v[4:7], v[204:207], v[194:197], v[4:7]
	v_mfma_f32_16x16x32_bf16 v[0:3], v[212:215], v[194:197], v[0:3]
	v_mfma_f32_16x16x32_bf16 v[52:55], v[208:211], v[174:177], v[52:55]
	v_mfma_f32_16x16x32_bf16 v[48:51], v[216:219], v[174:177], v[48:51]
	v_mfma_f32_16x16x32_bf16 v[36:39], v[208:211], v[182:185], v[36:39]
	v_mfma_f32_16x16x32_bf16 v[32:35], v[216:219], v[182:185], v[32:35]
	v_mfma_f32_16x16x32_bf16 v[20:23], v[208:211], v[190:193], v[20:23]
	v_mfma_f32_16x16x32_bf16 v[16:19], v[216:219], v[190:193], v[16:19]
	v_mfma_f32_16x16x32_bf16 v[4:7], v[208:211], v[198:201], v[4:7]
	v_mfma_f32_16x16x32_bf16 v[0:3], v[216:219], v[198:201], v[0:3]
	s_barrier
	s_add_u32 s56, s56, 0x80000
	s_addc_u32 s57, s57, 0
	s_mov_b32 m0, s67
	v_lshl_add_u64 v[204:205], s[56:57], 0, v[128:129]
	ds_read_b128 v[170:173], v156 offset:32768
	ds_read_b128 v[174:177], v156 offset:33792
	ds_read_b128 v[178:181], v156 offset:34816
	ds_read_b128 v[182:185], v156 offset:35840
	ds_read_b128 v[186:189], v156 offset:36864
	ds_read_b128 v[190:193], v156 offset:37888
	ds_read_b128 v[194:197], v156 offset:38912
	ds_read_b128 v[198:201], v156 offset:39936
	global_load_lds_dwordx4 v[204:205], off
	v_lshl_add_u64 v[204:205], s[56:57], 0, v[134:135]
	s_mov_b32 m0, s68
	s_nop 0
	global_load_lds_dwordx4 v[204:205], off
	s_waitcnt lgkmcnt(8)
	s_barrier
	s_waitcnt lgkmcnt(0)
	v_mfma_f32_16x16x32_bf16 v[124:127], v[146:149], v[170:173], v[124:127]
	v_mfma_f32_16x16x32_bf16 v[120:123], v[162:165], v[170:173], v[120:123]
	v_mfma_f32_16x16x32_bf16 v[108:111], v[146:149], v[178:181], v[108:111]
	v_mfma_f32_16x16x32_bf16 v[104:107], v[162:165], v[178:181], v[104:107]
	v_mfma_f32_16x16x32_bf16 v[92:95], v[146:149], v[186:189], v[92:95]
	v_mfma_f32_16x16x32_bf16 v[88:91], v[162:165], v[186:189], v[88:91]
	v_mfma_f32_16x16x32_bf16 v[76:79], v[146:149], v[194:197], v[76:79]
	v_mfma_f32_16x16x32_bf16 v[72:75], v[162:165], v[194:197], v[72:75]
	v_mfma_f32_16x16x32_bf16 v[124:127], v[158:161], v[174:177], v[124:127]
	v_mfma_f32_16x16x32_bf16 v[120:123], v[166:169], v[174:177], v[120:123]
	v_mfma_f32_16x16x32_bf16 v[108:111], v[158:161], v[182:185], v[108:111]
	v_mfma_f32_16x16x32_bf16 v[104:107], v[166:169], v[182:185], v[104:107]
	v_mfma_f32_16x16x32_bf16 v[92:95], v[158:161], v[190:193], v[92:95]
	v_mfma_f32_16x16x32_bf16 v[88:91], v[166:169], v[190:193], v[88:91]
	v_mfma_f32_16x16x32_bf16 v[76:79], v[158:161], v[198:201], v[76:79]
	v_mfma_f32_16x16x32_bf16 v[72:75], v[166:169], v[198:201], v[72:75]
	s_barrier
	s_add_i32 s56, 0, 0x1c000
	s_add_i32 s33, s33, s65
	v_add_u32_e32 v216, s56, v151
	v_lshl_add_u64 v[220:221], v[220:221], 0, s[36:37]
	s_mov_b32 m0, s33
	ds_read_b128 v[204:207], v216
	ds_read_b128 v[208:211], v216 offset:1024
	ds_read_b128 v[212:215], v216 offset:2048
	ds_read_b128 v[216:219], v216 offset:3072
	global_load_lds_dwordx4 v[220:221], off
	v_lshl_add_u64 v[220:221], v[222:223], 0, s[36:37]
	s_add_i32 m0, s33, 0x2000
	s_nop 0
	global_load_lds_dwordx4 v[220:221], off
	s_barrier
	s_waitcnt lgkmcnt(0)
	v_mfma_f32_16x16x32_bf16 v[116:119], v[204:207], v[170:173], v[116:119]
	v_mfma_f32_16x16x32_bf16 v[112:115], v[212:215], v[170:173], v[112:115]
	v_mfma_f32_16x16x32_bf16 v[100:103], v[204:207], v[178:181], v[100:103]
	v_mfma_f32_16x16x32_bf16 v[96:99], v[212:215], v[178:181], v[96:99]
	v_mfma_f32_16x16x32_bf16 v[84:87], v[204:207], v[186:189], v[84:87]
	v_mfma_f32_16x16x32_bf16 v[80:83], v[212:215], v[186:189], v[80:83]
	v_mfma_f32_16x16x32_bf16 v[68:71], v[204:207], v[194:197], v[68:71]
	v_mfma_f32_16x16x32_bf16 v[64:67], v[212:215], v[194:197], v[64:67]
	v_mfma_f32_16x16x32_bf16 v[116:119], v[208:211], v[174:177], v[116:119]
	v_mfma_f32_16x16x32_bf16 v[112:115], v[216:219], v[174:177], v[112:115]
	v_mfma_f32_16x16x32_bf16 v[100:103], v[208:211], v[182:185], v[100:103]
	v_mfma_f32_16x16x32_bf16 v[96:99], v[216:219], v[182:185], v[96:99]
	v_mfma_f32_16x16x32_bf16 v[84:87], v[208:211], v[190:193], v[84:87]
	v_mfma_f32_16x16x32_bf16 v[80:83], v[216:219], v[190:193], v[80:83]
	v_mfma_f32_16x16x32_bf16 v[68:71], v[208:211], v[198:201], v[68:71]
	v_mfma_f32_16x16x32_bf16 v[64:67], v[216:219], v[198:201], v[64:67]
	s_mov_b32 m0, s72
	v_lshl_add_u64 v[220:221], v[224:225], 0, s[36:37]
	s_barrier
	ds_read_b128 v[170:173], v156 offset:49152
	ds_read_b128 v[174:177], v156 offset:50176
	ds_read_b128 v[178:181], v156 offset:51200
	ds_read_b128 v[182:185], v156 offset:52224
	ds_read_b128 v[186:189], v156 offset:53248
	ds_read_b128 v[190:193], v156 offset:54272
	ds_read_b128 v[194:197], v156 offset:55296
	ds_read_b128 v[198:201], v156 offset:56320
	global_load_lds_dwordx4 v[220:221], off
	v_lshl_add_u64 v[220:221], v[226:227], 0, s[36:37]
	s_mov_b32 m0, s73
	s_nop 0
	global_load_lds_dwordx4 v[220:221], off
	s_barrier
; __device__ __forceinline__ float bflo(unsigned w) { return __uint_as_float(w << 16); }
; __device__ __forceinline__ float bfhi(unsigned w) { return __uint_as_float(w & 0xffff0000u); }
; #define PG8_STAGE(bufoff, gbase, voff) do { _Pragma("unroll") for (int _i = 0; _i < 2; ++_i) \
;         __builtin_amdgcn_global_load_lds((const unsigned*)((const char*)(gbase) + (voff)[_i]), (LAS unsigned*)(lds + (bufoff) + ldsw + _i * 8192), 16, 0, 0); } while (0)
; #define PG8_MMA(ai, bj, At, Bt) do { __builtin_amdgcn_s_setprio(1); _Pragma("unroll") for (int m = 0; m < 4; ++m) _Pragma("unroll") for (int n = 0; n < 2; ++n) _Pragma("unroll") for (int k = 0; k < 2; ++k) \
;         acc[ai][bj][m][n] = __builtin_amdgcn_mfma_f32_16x16x32_bf16(Bt[n][k], At[m][k], acc[ai][bj][m][n], 0, 0, 0); __builtin_amdgcn_s_setprio(0); } while (0)
; #define PG8_WAIT_V(n) asm volatile("s_waitcnt vmcnt(" #n ")" ::: "memory")
; #define PG8_WAIT_L(n) asm volatile("s_waitcnt lgkmcnt(" #n ")" ::: "memory")
;     __device__ __forceinline__ void operator()(const f32x4 (&acc)[2][2][4][2], const Unit& u, int wr, int wc, int fr, int fq) const {
;     ...
;             for (int m = 0; m < 4; ++m) { const int row = row0 + ai * HALF + m * 16; const size_t off = (size_t)row * D + col0; float sq = 0.f; u32x4 w[2];
;                 const float sc = rsin ? __builtin_amdgcn_rcpf(rsin[row] * (1.f / D) + EPS) : 1.0f;
;                 u32x4 rr[2]; if (R) load_pair_lines(R, D, row, fr, col0, rr[0], rr[1]);
; #pragma unroll
;                 for (int bj = 0; bj < 2; ++bj) { f32x4 r0, r1;
;                     if (R) { const u32x4 rw = rr[bj]; r0 = (f32x4){bflo(rw.x), bfhi(rw.x), bflo(rw.y), bfhi(rw.y)}; r1 = (f32x4){bflo(rw.z), bfhi(rw.z), bflo(rw.w), bfhi(rw.w)}; }
;                     else { const float* rp = (row < 8192 ? src_p + off : src_s + (off - (size_t)8192 * D)) + 8 * bj; r0 = *(const f32x4*)rp; r1 = *(const f32x4*)(rp + 4); }
;                     const f32x4 o0 = r0 + acc[ai][bj][m][0] * sc, o1 = r1 + acc[ai][bj][m][1] * sc;
; template <class Epi>
; __device__ __forceinline__ void gemm_phase(LAS unsigned char* lds, const Gemm g, const StaticOrder& S, const Epi& E) {
;     ...
;             PG8_BAR; PG8_WAIT_L(0); PG8_MMA(1, 0, At, B0); PG8_BAR; PG8_SCHED;
;             PG8_STAGE(PG8_SB(1, 1), b3, voffB1);
;             PG8_WAIT_V(6); PG8_BAR; PG8_MMA(1, 1, At, B1); PG8_BAR;
;         }
	s_waitcnt lgkmcnt(0)
	v_mfma_f32_16x16x32_bf16 v[60:63], v[146:149], v[170:173], v[60:63]
	v_mfma_f32_16x16x32_bf16 v[56:59], v[162:165], v[170:173], v[56:59]
	v_mfma_f32_16x16x32_bf16 v[44:47], v[146:149], v[178:181], v[44:47]
	v_mfma_f32_16x16x32_bf16 v[40:43], v[162:165], v[178:181], v[40:43]
	v_mfma_f32_16x16x32_bf16 v[28:31], v[146:149], v[186:189], v[28:31]
	v_mfma_f32_16x16x32_bf16 v[24:27], v[162:165], v[186:189], v[24:27]
	v_mfma_f32_16x16x32_bf16 v[12:15], v[146:149], v[194:197], v[12:15]
	v_mfma_f32_16x16x32_bf16 v[8:11], v[162:165], v[194:197], v[8:11]
	v_mfma_f32_16x16x32_bf16 v[60:63], v[158:161], v[174:177], v[60:63]
	v_mfma_f32_16x16x32_bf16 v[56:59], v[166:169], v[174:177], v[56:59]
	v_mfma_f32_16x16x32_bf16 v[44:47], v[158:161], v[182:185], v[44:47]
	v_mfma_f32_16x16x32_bf16 v[40:43], v[166:169], v[182:185], v[40:43]
	v_mfma_f32_16x16x32_bf16 v[28:31], v[158:161], v[190:193], v[28:31]
	v_mfma_f32_16x16x32_bf16 v[24:27], v[166:169], v[190:193], v[24:27]
	v_mfma_f32_16x16x32_bf16 v[12:15], v[158:161], v[198:201], v[12:15]
	v_mfma_f32_16x16x32_bf16 v[8:11], v[166:169], v[198:201], v[8:11]
	s_barrier
	s_add_i32 s33, s56, s65
	v_lshl_add_u64 v[146:147], v[228:229], 0, s[36:37]
	s_mov_b32 m0, s33
	s_nop 0
	global_load_lds_dwordx4 v[146:147], off
	v_lshl_add_u64 v[146:147], v[230:231], 0, s[36:37]
	s_add_i32 m0, s33, 0x2000
	s_nop 0
	global_load_lds_dwordx4 v[146:147], off
	s_waitcnt vmcnt(6)
	s_barrier
	v_mfma_f32_16x16x32_bf16 v[52:55], v[204:207], v[170:173], v[52:55]
	v_mfma_f32_16x16x32_bf16 v[48:51], v[212:215], v[170:173], v[48:51]
	v_mfma_f32_16x16x32_bf16 v[36:39], v[204:207], v[178:181], v[36:39]
	v_mfma_f32_16x16x32_bf16 v[32:35], v[212:215], v[178:181], v[32:35]
	v_mfma_f32_16x16x32_bf16 v[20:23], v[204:207], v[186:189], v[20:23]
	v_mfma_f32_16x16x32_bf16 v[16:19], v[212:215], v[186:189], v[16:19]
	v_mfma_f32_16x16x32_bf16 v[4:7], v[204:207], v[194:197], v[4:7]
	v_mfma_f32_16x16x32_bf16 v[0:3], v[212:215], v[194:197], v[0:3]
	v_mfma_f32_16x16x32_bf16 v[52:55], v[208:211], v[174:177], v[52:55]
	v_mfma_f32_16x16x32_bf16 v[48:51], v[216:219], v[174:177], v[48:51]
	v_mfma_f32_16x16x32_bf16 v[36:39], v[208:211], v[182:185], v[36:39]
	v_mfma_f32_16x16x32_bf16 v[32:35], v[216:219], v[182:185], v[32:35]
	v_mfma_f32_16x16x32_bf16 v[20:23], v[208:211], v[190:193], v[20:23]
	v_mfma_f32_16x16x32_bf16 v[16:19], v[216:219], v[190:193], v[16:19]
	v_mfma_f32_16x16x32_bf16 v[4:7], v[208:211], v[198:201], v[4:7]
	v_mfma_f32_16x16x32_bf16 v[0:3], v[216:219], v[198:201], v[0:3]
	s_add_i32 s88, s88, 2
	s_add_u32 s54, s54, 0x100
	s_addc_u32 s55, s55, 0
	s_add_u32 s86, s86, 0x100
	s_addc_u32 s87, s87, 0
	s_cmp_gt_u32 s88, 29
	s_barrier
	s_cbranch_scc0 .LBB0_613
	s_lshl_b32 s33, s52, 8
	s_add_i32 s33, s33, s74
	v_or_b32_e32 v146, s33, v150
	v_lshl_or_b32 v148, s50, 8, v154
	v_ashrrev_i32_e32 v147, 31, v146
	v_ashrrev_i32_e32 v149, 31, v148
	v_lshlrev_b64 v[158:159], 11, v[146:147]
	v_lshl_add_u64 v[158:159], v[158:159], 0, v[148:149]
	v_lshlrev_b64 v[158:159], 2, v[158:159]
	v_lshl_add_u64 v[160:161], s[16:17], 0, v[158:159]
	v_lshl_add_u64 v[158:159], s[18:19], 0, v[158:159]
	v_lshl_add_u64 v[158:159], v[158:159], 0, s[38:39]
	v_cmp_gt_i32_e32 vcc, s70, v146
	v_mov_b32_e32 v183, 0
	v_mov_b32_e32 v184, 0
	v_cndmask_b32_e32 v167, v159, v161, vcc
	v_cndmask_b32_e32 v166, v158, v160, vcc
	s_waitcnt vmcnt(8)
	s_nop 0
	v_mov_b64_e32 v[158:159], v[232:233]
	v_mov_b64_e32 v[160:161], v[234:235]
	s_nop 1
	s_nop 0
	v_mov_b64_e32 v[162:163], v[236:237]
	v_mov_b64_e32 v[164:165], v[238:239]
	s_nop 1
	v_or_b32_e32 v188, 16, v146
	v_ashrrev_i32_e32 v189, 31, v188
	v_lshlrev_b64 v[190:191], 11, v[188:189]
	v_lshl_add_u64 v[190:191], v[190:191], 0, v[148:149]
	v_lshlrev_b64 v[190:191], 2, v[190:191]
	v_lshl_add_u64 v[192:193], s[16:17], 0, v[190:191]
	v_lshl_add_u64 v[190:191], s[18:19], 0, v[190:191]
	v_lshl_add_u64 v[190:191], v[190:191], 0, s[38:39]
	v_cmp_gt_i32_e32 vcc, s70, v188
	s_nop 1
	v_cndmask_b32_e32 v195, v191, v193, vcc
	v_cndmask_b32_e32 v194, v190, v192, vcc
	global_load_dwordx4 v[196:199], v[194:195], off
	global_load_dwordx4 v[204:207], v[194:195], off offset:16
	global_load_dwordx4 v[208:211], v[194:195], off offset:32
	global_load_dwordx4 v[212:215], v[194:195], off offset:48
	v_or_b32_e32 v188, 32, v146
	v_ashrrev_i32_e32 v189, 31, v188
	v_lshlrev_b64 v[190:191], 11, v[188:189]
	v_lshl_add_u64 v[190:191], v[190:191], 0, v[148:149]
	v_lshlrev_b64 v[190:191], 2, v[190:191]
	v_lshl_add_u64 v[192:193], s[16:17], 0, v[190:191]
	v_lshl_add_u64 v[190:191], s[18:19], 0, v[190:191]
	v_lshl_add_u64 v[190:191], v[190:191], 0, s[38:39]
	v_cmp_gt_i32_e32 vcc, s70, v188
	s_nop 1
	v_cndmask_b32_e32 v195, v191, v193, vcc
	v_cndmask_b32_e32 v194, v190, v192, vcc
	global_load_dwordx4 v[216:219], v[194:195], off
	global_load_dwordx4 v[220:223], v[194:195], off offset:16
	global_load_dwordx4 v[224:227], v[194:195], off offset:32
	global_load_dwordx4 v[228:231], v[194:195], off offset:48
	v_or_b32_e32 v188, 48, v146
	v_ashrrev_i32_e32 v189, 31, v188
	v_lshlrev_b64 v[190:191], 11, v[188:189]
	v_lshl_add_u64 v[190:191], v[190:191], 0, v[148:149]
	v_lshlrev_b64 v[190:191], 2, v[190:191]
	v_lshl_add_u64 v[192:193], s[16:17], 0, v[190:191]
	v_lshl_add_u64 v[190:191], s[18:19], 0, v[190:191]
	v_lshl_add_u64 v[190:191], v[190:191], 0, s[38:39]
	v_cmp_gt_i32_e32 vcc, s70, v188
	s_nop 1
	v_cndmask_b32_e32 v195, v191, v193, vcc
	v_cndmask_b32_e32 v194, v190, v192, vcc
	global_load_dwordx4 v[232:235], v[194:195], off
	global_load_dwordx4 v[236:239], v[194:195], off offset:16
	global_load_dwordx4 v[240:243], v[194:195], off offset:32
; __device__ __forceinline__ unsigned cvt_pk_bf16(float lo, float hi) { unsigned r; asm volatile("v_cvt_pk_bf16_f32 %0, %1, %2" : "=v"(r) : "v"(lo), "v"(hi)); return r; }
; __device__ __forceinline__ float bflo(unsigned w) { return __uint_as_float(w << 16); }
; __device__ __forceinline__ float bfhi(unsigned w) { return __uint_as_float(w & 0xffff0000u); }
;     __device__ __forceinline__ void operator()(const f32x4 (&acc)[2][2][4][2], const Unit& u, int wr, int wc, int fr, int fq) const {
;     ...
;             for (int m = 0; m < 4; ++m) { const int row = row0 + ai * HALF + m * 16; const size_t off = (size_t)row * D + col0; float sq = 0.f; u32x4 w[2];
;                 const float sc = rsin ? __builtin_amdgcn_rcpf(rsin[row] * (1.f / D) + EPS) : 1.0f;
;                 u32x4 rr[2]; if (R) load_pair_lines(R, D, row, fr, col0, rr[0], rr[1]);
; #pragma unroll
;                 for (int bj = 0; bj < 2; ++bj) { f32x4 r0, r1;
;                     if (R) { const u32x4 rw = rr[bj]; r0 = (f32x4){bflo(rw.x), bfhi(rw.x), bflo(rw.y), bfhi(rw.y)}; r1 = (f32x4){bflo(rw.z), bfhi(rw.z), bflo(rw.w), bfhi(rw.w)}; }
;                     else { const float* rp = (row < 8192 ? src_p + off : src_s + (off - (size_t)8192 * D)) + 8 * bj; r0 = *(const f32x4*)rp; r1 = *(const f32x4*)(rp + 4); }
;                     const f32x4 o0 = r0 + acc[ai][bj][m][0] * sc, o1 = r1 + acc[ai][bj][m][1] * sc;
;                     sq += (o0[0] * o0[0] + o0[1] * o0[1]) + (o0[2] * o0[2] + o0[3] * o0[3]) + (o1[0] * o1[0] + o1[1] * o1[1]) + (o1[2] * o1[2] + o1[3] * o1[3]);
;                     w[bj].x = cvt_pk_bf16(o0[0], o0[1]); w[bj].y = cvt_pk_bf16(o0[2], o0[3]); w[bj].z = cvt_pk_bf16(o1[0], o1[1]); w[bj].w = cvt_pk_bf16(o1[2], o1[3]); }
;                 store_pair_lines(O, D, row, fr, col0, w[0], w[1]);
;                 if (ssout) { sq += __shfl_xor(sq, 16); sq += __shfl_xor(sq, 32); if (fq == 0) unsafeAtomicAdd(ssout + row, sq); } }
	global_load_dwordx4 v[244:247], v[194:195], off offset:48
	v_pk_add_f32 v[168:169], v[126:127], v[160:161]
	v_pk_add_f32 v[170:171], v[124:125], v[158:159]
	v_pk_add_f32 v[164:165], v[122:123], v[164:165]
	v_pk_add_f32 v[162:163], v[120:121], v[162:163]
	v_cvt_pk_bf16_f32 v123, v170, v171
	v_cvt_pk_bf16_f32 v176, v168, v169
	v_mul_f32_e32 v171, v171, v171
	v_cvt_pk_bf16_f32 v177, v162, v163
	v_cvt_pk_bf16_f32 v178, v164, v165
	global_load_dwordx4 v[124:127], v[166:167], off offset:32
	global_load_dwordx4 v[158:161], v[166:167], off offset:48
	v_mul_f32_e32 v169, v169, v169
	v_and_b32_e32 v121, 64, v203
	v_mul_f32_e32 v163, v163, v163
	v_fmac_f32_e32 v171, v170, v170
	v_fmac_f32_e32 v169, v168, v168
	v_xor_b32_e32 v122, 16, v203
	v_add_u32_e32 v172, 64, v121
	v_mul_f32_e32 v165, v165, v165
	v_fmac_f32_e32 v163, v162, v162
	v_add_f32_e32 v162, v171, v169
	v_cmp_lt_i32_e32 vcc, v122, v172
	v_fmac_f32_e32 v165, v164, v164
	v_add_f32_e32 v162, v163, v162
	v_cndmask_b32_e32 v122, v203, v122, vcc
	v_add_f32_e32 v162, v165, v162
	v_xor_b32_e32 v167, 32, v203
	v_lshlrev_b32_e32 v122, 2, v122
	v_or_b32_e32 v166, s33, v152
	v_cmp_lt_i32_e32 vcc, v167, v172
	v_or_b32_e32 v120, v148, v153
	v_ashrrev_i32_e32 v121, 31, v120
	v_cndmask_b32_e32 v187, v203, v167, vcc
	v_ashrrev_i32_e32 v167, 31, v166
	v_or_b32_e32 v174, 8, v166
	v_lshlrev_b64 v[166:167], 12, v[166:167]
	v_lshlrev_b64 v[172:173], 1, v[120:121]
	v_lshl_add_u64 v[166:167], s[10:11], 0, v[166:167]
	v_lshl_add_u64 v[166:167], v[166:167], 0, v[172:173]
	v_ashrrev_i32_e32 v175, 31, v174
	v_mov_b32_dpp v179, v123 row_ror:8 row_mask:0xf bank_mask:0xf
	v_mov_b32_dpp v180, v176 row_ror:8 row_mask:0xf bank_mask:0xf
	v_mov_b32_dpp v181, v177 row_ror:8 row_mask:0xf bank_mask:0xf
	v_mov_b32_dpp v182, v178 row_ror:8 row_mask:0xf bank_mask:0xf
	s_waitcnt vmcnt(0)
	v_pk_add_f32 v[126:127], v[118:119], v[126:127]
	v_pk_add_f32 v[124:125], v[116:117], v[124:125]
	v_pk_add_f32 v[112:113], v[112:113], v[158:159]
	v_cvt_pk_bf16_f32 v116, v124, v125
	v_cvt_pk_bf16_f32 v117, v126, v127
	v_mul_f32_e32 v125, v125, v125
	v_mul_f32_e32 v127, v127, v127
	v_pk_add_f32 v[114:115], v[114:115], v[160:161]
	v_mul_f32_e32 v158, v113, v113
	v_fmac_f32_e32 v125, v124, v124
	v_fmac_f32_e32 v127, v126, v126
	v_cvt_pk_bf16_f32 v118, v112, v113
	v_cvt_pk_bf16_f32 v119, v114, v115
	v_mul_f32_e32 v115, v115, v115
	v_fmac_f32_e32 v158, v112, v112
	v_add_f32_e32 v112, v125, v127
	v_fmac_f32_e32 v115, v114, v114
	v_add_f32_e32 v112, v158, v112
	v_add_f32_e32 v112, v115, v112
	v_add_f32_e32 v124, v162, v112
	v_mov_b32_e32 v125, v124
	s_nop 1
	v_permlane16_swap_b32_e32 v125, v124
	v_mov_b32_dpp v183, v116 row_ror:8 row_mask:0xf bank_mask:0xf
	v_mov_b32_dpp v184, v117 row_ror:8 row_mask:0xf bank_mask:0xf
	v_mov_b32_dpp v185, v118 row_ror:8 row_mask:0xf bank_mask:0xf
	v_mov_b32_dpp v186, v119 row_ror:8 row_mask:0xf bank_mask:0xf
	v_cndmask_b32_e64 v113, v184, v176, s[6:7]
	v_cndmask_b32_e64 v115, v186, v178, s[6:7]
	v_cndmask_b32_e64 v112, v183, v123, s[6:7]
	v_cndmask_b32_e64 v114, v185, v177, s[6:7]
	global_store_dwordx4 v[166:167], v[112:115], off
	v_cndmask_b32_e64 v117, v117, v180, s[6:7]
	v_cndmask_b32_e64 v119, v119, v182, s[6:7]
	s_waitcnt lgkmcnt(0)
	v_add_f32_e32 v112, v124, v125
	v_lshlrev_b32_e32 v114, 2, v187
	v_mov_b32_e32 v113, v112
	s_nop 1
	v_permlane32_swap_b32_e32 v113, v112
	v_lshlrev_b64 v[124:125], 12, v[174:175]
	v_lshl_add_u64 v[124:125], s[10:11], 0, v[124:125]
	v_cndmask_b32_e64 v116, v116, v179, s[6:7]
	v_cndmask_b32_e64 v118, v118, v181, s[6:7]
	v_lshl_add_u64 v[124:125], v[124:125], 0, v[172:173]
	global_store_dwordx4 v[124:125], v[116:119], off
	s_and_saveexec_b64 s[50:51], s[8:9]
	s_cbranch_execz .LBB0_616
	s_waitcnt lgkmcnt(0)
	v_add_f32_e32 v115, v112, v113
	v_lshl_add_u64 v[112:113], v[146:147], 2, s[12:13]
	global_atomic_add_f32 v[112:113], v115, off
.LBB0_616:
	s_or_b64 exec, exec, s[50:51]
	v_or_b32_e32 v112, 16, v146
	s_waitcnt lgkmcnt(0)
	v_ashrrev_i32_e32 v113, 31, v112
	v_lshlrev_b64 v[116:117], 11, v[112:113]
	v_lshl_add_u64 v[116:117], v[116:117], 0, v[148:149]
	v_lshlrev_b64 v[116:117], 2, v[116:117]
	v_lshl_add_u64 v[118:119], s[16:17], 0, v[116:117]
	v_lshl_add_u64 v[116:117], s[18:19], 0, v[116:117]
	v_lshl_add_u64 v[116:117], v[116:117], 0, s[38:39]
	v_cmp_gt_i32_e32 vcc, s70, v112
	v_mov_b32_e32 v165, 0
	v_mov_b32_e32 v166, 0
	v_cndmask_b32_e32 v159, v117, v119, vcc
	v_cndmask_b32_e32 v158, v116, v118, vcc
	s_waitcnt vmcnt(12)
	s_nop 0
	v_mov_b64_e32 v[116:117], v[196:197]
	v_mov_b64_e32 v[118:119], v[198:199]
	v_mov_b64_e32 v[124:125], v[204:205]
	v_mov_b64_e32 v[126:127], v[206:207]
	s_waitcnt vmcnt(2)
	v_pk_add_f32 v[118:119], v[110:111], v[118:119]
	v_pk_add_f32 v[116:117], v[108:109], v[116:117]
	s_waitcnt vmcnt(2)
; __device__ __forceinline__ unsigned cvt_pk_bf16(float lo, float hi) { unsigned r; asm volatile("v_cvt_pk_bf16_f32 %0, %1, %2" : "=v"(r) : "v"(lo), "v"(hi)); return r; }
; __device__ __forceinline__ float bflo(unsigned w) { return __uint_as_float(w << 16); }
; __device__ __forceinline__ float bfhi(unsigned w) { return __uint_as_float(w & 0xffff0000u); }
;     __device__ __forceinline__ void operator()(const f32x4 (&acc)[2][2][4][2], const Unit& u, int wr, int wc, int fr, int fq) const {
;     ...
;             for (int m = 0; m < 4; ++m) { const int row = row0 + ai * HALF + m * 16; const size_t off = (size_t)row * D + col0; float sq = 0.f; u32x4 w[2];
;                 const float sc = rsin ? __builtin_amdgcn_rcpf(rsin[row] * (1.f / D) + EPS) : 1.0f;
;                 u32x4 rr[2]; if (R) load_pair_lines(R, D, row, fr, col0, rr[0], rr[1]);
; #pragma unroll
;                 for (int bj = 0; bj < 2; ++bj) { f32x4 r0, r1;
;                     if (R) { const u32x4 rw = rr[bj]; r0 = (f32x4){bflo(rw.x), bfhi(rw.x), bflo(rw.y), bfhi(rw.y)}; r1 = (f32x4){bflo(rw.z), bfhi(rw.z), bflo(rw.w), bfhi(rw.w)}; }
;                     else { const float* rp = (row < 8192 ? src_p + off : src_s + (off - (size_t)8192 * D)) + 8 * bj; r0 = *(const f32x4*)rp; r1 = *(const f32x4*)(rp + 4); }
;                     const f32x4 o0 = r0 + acc[ai][bj][m][0] * sc, o1 = r1 + acc[ai][bj][m][1] * sc;
;                     sq += (o0[0] * o0[0] + o0[1] * o0[1]) + (o0[2] * o0[2] + o0[3] * o0[3]) + (o1[0] * o1[0] + o1[1] * o1[1]) + (o1[2] * o1[2] + o1[3] * o1[3]);
;                     w[bj].x = cvt_pk_bf16(o0[0], o0[1]); w[bj].y = cvt_pk_bf16(o0[2], o0[3]); w[bj].z = cvt_pk_bf16(o1[0], o1[1]); w[bj].w = cvt_pk_bf16(o1[2], o1[3]); }
;                 store_pair_lines(O, D, row, fr, col0, w[0], w[1]);
;                 if (ssout) { sq += __shfl_xor(sq, 16); sq += __shfl_xor(sq, 32); if (fq == 0) unsafeAtomicAdd(ssout + row, sq); } }
	v_pk_add_f32 v[126:127], v[106:107], v[126:127]
	v_pk_add_f32 v[124:125], v[104:105], v[124:125]
	v_cvt_pk_bf16_f32 v115, v116, v117
	v_cvt_pk_bf16_f32 v123, v118, v119
	v_mul_f32_e32 v117, v117, v117
	v_cvt_pk_bf16_f32 v147, v124, v125
	v_cvt_pk_bf16_f32 v160, v126, v127
	v_mov_b64_e32 v[104:105], v[208:209]
	v_mov_b64_e32 v[106:107], v[210:211]
	v_mov_b64_e32 v[108:109], v[212:213]
	v_mov_b64_e32 v[110:111], v[214:215]
	s_nop 1
	v_add_u32_e32 v188, 0x80, v146
	v_ashrrev_i32_e32 v189, 31, v188
	v_lshlrev_b64 v[190:191], 11, v[188:189]
	v_lshl_add_u64 v[190:191], v[190:191], 0, v[148:149]
	v_lshlrev_b64 v[190:191], 2, v[190:191]
	v_lshl_add_u64 v[192:193], s[16:17], 0, v[190:191]
	v_lshl_add_u64 v[190:191], s[18:19], 0, v[190:191]
	v_lshl_add_u64 v[190:191], v[190:191], 0, s[38:39]
	v_cmp_gt_i32_e32 vcc, s81, v146
	s_nop 1
	v_cndmask_b32_e32 v195, v191, v193, vcc
	v_cndmask_b32_e32 v194, v190, v192, vcc
	global_load_dwordx4 v[196:199], v[194:195], off
	global_load_dwordx4 v[204:207], v[194:195], off offset:16
	global_load_dwordx4 v[208:211], v[194:195], off offset:32
	global_load_dwordx4 v[212:215], v[194:195], off offset:48
	v_mul_f32_e32 v119, v119, v119
	v_mul_f32_e32 v125, v125, v125
	v_fmac_f32_e32 v117, v116, v116
	v_fmac_f32_e32 v119, v118, v118
	v_mul_f32_e32 v127, v127, v127
	v_fmac_f32_e32 v125, v124, v124
	v_add_f32_e32 v116, v117, v119
	v_fmac_f32_e32 v127, v126, v126
	v_add_f32_e32 v116, v125, v116
	v_add_f32_e32 v116, v127, v116
	v_sub_u32_e32 v158, v112, v150
	v_add_u32_e32 v158, v158, v152
	v_ashrrev_i32_e32 v159, 31, v158
	v_lshlrev_b64 v[158:159], 12, v[158:159]
	v_lshl_add_u64 v[158:159], s[10:11], 0, v[158:159]
	v_lshl_add_u64 v[158:159], v[120:121], 1, v[158:159]
	v_mov_b32_dpp v161, v115 row_ror:8 row_mask:0xf bank_mask:0xf
	v_mov_b32_dpp v162, v123 row_ror:8 row_mask:0xf bank_mask:0xf
	v_mov_b32_dpp v163, v147 row_ror:8 row_mask:0xf bank_mask:0xf
	v_mov_b32_dpp v164, v160 row_ror:8 row_mask:0xf bank_mask:0xf
	s_waitcnt vmcnt(6)
	v_pk_add_f32 v[102:103], v[102:103], v[106:107]
	v_pk_add_f32 v[104:105], v[100:101], v[104:105]
	s_waitcnt vmcnt(6)
	v_pk_add_f32 v[106:107], v[98:99], v[110:111]
	v_pk_add_f32 v[96:97], v[96:97], v[108:109]
	v_cvt_pk_bf16_f32 v98, v104, v105
	v_mul_f32_e32 v105, v105, v105
	v_mul_f32_e32 v108, v103, v103
	v_cvt_pk_bf16_f32 v99, v102, v103
	v_cvt_pk_bf16_f32 v100, v96, v97
	v_mul_f32_e32 v97, v97, v97
	v_fmac_f32_e32 v105, v104, v104
	v_fmac_f32_e32 v108, v102, v102
	v_cvt_pk_bf16_f32 v101, v106, v107
	v_mul_f32_e32 v107, v107, v107
	v_fmac_f32_e32 v97, v96, v96
	v_add_f32_e32 v96, v105, v108
	v_fmac_f32_e32 v107, v106, v106
	v_add_f32_e32 v96, v97, v96
	v_add_f32_e32 v96, v107, v96
	v_add_f32_e32 v96, v116, v96
	v_mov_b32_e32 v97, v96
	s_nop 1
	v_permlane16_swap_b32_e32 v97, v96
	v_mov_b32_dpp v165, v98 row_ror:8 row_mask:0xf bank_mask:0xf
	v_mov_b32_dpp v166, v99 row_ror:8 row_mask:0xf bank_mask:0xf
	v_mov_b32_dpp v167, v100 row_ror:8 row_mask:0xf bank_mask:0xf
	v_mov_b32_dpp v168, v101 row_ror:8 row_mask:0xf bank_mask:0xf
	s_waitcnt lgkmcnt(0)
	v_add_f32_e32 v96, v96, v97
	v_mov_b32_e32 v97, v96
	s_nop 1
	v_permlane32_swap_b32_e32 v97, v96
	v_cndmask_b32_e64 v103, v166, v123, s[6:7]
	v_cndmask_b32_e64 v105, v168, v160, s[6:7]
	v_cndmask_b32_e64 v102, v165, v115, s[6:7]
	v_cndmask_b32_e64 v104, v167, v147, s[6:7]
	global_store_dwordx4 v[158:159], v[102:105], off
	v_cndmask_b32_e64 v99, v99, v162, s[6:7]
	v_cndmask_b32_e64 v101, v101, v164, s[6:7]
	v_add_co_u32_e32 v102, vcc, s69, v158
	v_cndmask_b32_e64 v98, v98, v161, s[6:7]
	v_cndmask_b32_e64 v100, v100, v163, s[6:7]
	v_addc_co_u32_e32 v103, vcc, 0, v159, vcc
	global_store_dwordx4 v[102:103], v[98:101], off
	s_and_saveexec_b64 s[50:51], s[8:9]
	s_cbranch_execz .LBB0_618
	s_waitcnt lgkmcnt(0)
	v_add_f32_e32 v98, v96, v97
	v_lshl_add_u64 v[96:97], v[112:113], 2, s[12:13]
	global_atomic_add_f32 v[96:97], v98, off
.LBB0_618:
	s_or_b64 exec, exec, s[50:51]
	v_or_b32_e32 v96, 32, v146
	s_waitcnt lgkmcnt(0)
	v_ashrrev_i32_e32 v97, 31, v96
	v_lshlrev_b64 v[98:99], 11, v[96:97]
	v_lshl_add_u64 v[98:99], v[98:99], 0, v[148:149]
	v_lshlrev_b64 v[98:99], 2, v[98:99]
	v_lshl_add_u64 v[100:101], s[16:17], 0, v[98:99]
	v_lshl_add_u64 v[98:99], s[18:19], 0, v[98:99]
	v_lshl_add_u64 v[98:99], v[98:99], 0, s[38:39]
	v_cmp_gt_i32_e32 vcc, s70, v96
	v_mov_b32_e32 v117, 0
	v_mov_b32_e32 v118, 0
	v_cndmask_b32_e32 v107, v99, v101, vcc
	v_cndmask_b32_e32 v106, v98, v100, vcc
	s_waitcnt vmcnt(14)
	s_nop 0
	v_mov_b64_e32 v[98:99], v[216:217]
	v_mov_b64_e32 v[100:101], v[218:219]
	v_mov_b64_e32 v[102:103], v[220:221]
	v_mov_b64_e32 v[104:105], v[222:223]
	s_waitcnt vmcnt(8)
	v_pk_add_f32 v[100:101], v[94:95], v[100:101]
	v_pk_add_f32 v[98:99], v[92:93], v[98:99]
	s_waitcnt vmcnt(8)
; __device__ __forceinline__ unsigned cvt_pk_bf16(float lo, float hi) { unsigned r; asm volatile("v_cvt_pk_bf16_f32 %0, %1, %2" : "=v"(r) : "v"(lo), "v"(hi)); return r; }
; __device__ __forceinline__ float bflo(unsigned w) { return __uint_as_float(w << 16); }
; __device__ __forceinline__ float bfhi(unsigned w) { return __uint_as_float(w & 0xffff0000u); }
;     __device__ __forceinline__ void operator()(const f32x4 (&acc)[2][2][4][2], const Unit& u, int wr, int wc, int fr, int fq) const {
;     ...
;             for (int m = 0; m < 4; ++m) { const int row = row0 + ai * HALF + m * 16; const size_t off = (size_t)row * D + col0; float sq = 0.f; u32x4 w[2];
;                 const float sc = rsin ? __builtin_amdgcn_rcpf(rsin[row] * (1.f / D) + EPS) : 1.0f;
;                 u32x4 rr[2]; if (R) load_pair_lines(R, D, row, fr, col0, rr[0], rr[1]);
; #pragma unroll
;                 for (int bj = 0; bj < 2; ++bj) { f32x4 r0, r1;
;                     if (R) { const u32x4 rw = rr[bj]; r0 = (f32x4){bflo(rw.x), bfhi(rw.x), bflo(rw.y), bfhi(rw.y)}; r1 = (f32x4){bflo(rw.z), bfhi(rw.z), bflo(rw.w), bfhi(rw.w)}; }
;                     else { const float* rp = (row < 8192 ? src_p + off : src_s + (off - (size_t)8192 * D)) + 8 * bj; r0 = *(const f32x4*)rp; r1 = *(const f32x4*)(rp + 4); }
;                     const f32x4 o0 = r0 + acc[ai][bj][m][0] * sc, o1 = r1 + acc[ai][bj][m][1] * sc;
;                     sq += (o0[0] * o0[0] + o0[1] * o0[1]) + (o0[2] * o0[2] + o0[3] * o0[3]) + (o1[0] * o1[0] + o1[1] * o1[1]) + (o1[2] * o1[2] + o1[3] * o1[3]);
;                     w[bj].x = cvt_pk_bf16(o0[0], o0[1]); w[bj].y = cvt_pk_bf16(o0[2], o0[3]); w[bj].z = cvt_pk_bf16(o1[0], o1[1]); w[bj].w = cvt_pk_bf16(o1[2], o1[3]); }
;                 store_pair_lines(O, D, row, fr, col0, w[0], w[1]);
;                 if (ssout) { sq += __shfl_xor(sq, 16); sq += __shfl_xor(sq, 32); if (fq == 0) unsafeAtomicAdd(ssout + row, sq); } }
	v_pk_add_f32 v[104:105], v[90:91], v[104:105]
	v_pk_add_f32 v[102:103], v[88:89], v[102:103]
	v_cvt_pk_bf16_f32 v108, v98, v99
	v_cvt_pk_bf16_f32 v109, v100, v101
	v_mul_f32_e32 v99, v99, v99
	v_cvt_pk_bf16_f32 v110, v102, v103
	v_cvt_pk_bf16_f32 v111, v104, v105
	v_mov_b64_e32 v[88:89], v[224:225]
	v_mov_b64_e32 v[90:91], v[226:227]
	v_mov_b64_e32 v[92:93], v[228:229]
	v_mov_b64_e32 v[94:95], v[230:231]
	s_nop 1
	v_add_u32_e32 v188, 0x90, v146
	v_ashrrev_i32_e32 v189, 31, v188
	v_lshlrev_b64 v[190:191], 11, v[188:189]
	v_lshl_add_u64 v[190:191], v[190:191], 0, v[148:149]
	v_lshlrev_b64 v[190:191], 2, v[190:191]
	v_lshl_add_u64 v[192:193], s[16:17], 0, v[190:191]
	v_lshl_add_u64 v[190:191], s[18:19], 0, v[190:191]
	v_lshl_add_u64 v[190:191], v[190:191], 0, s[38:39]
	v_cmp_gt_i32_e32 vcc, s82, v146
	s_nop 1
	v_cndmask_b32_e32 v195, v191, v193, vcc
	v_cndmask_b32_e32 v194, v190, v192, vcc
	global_load_dwordx4 v[216:219], v[194:195], off
	global_load_dwordx4 v[220:223], v[194:195], off offset:16
	global_load_dwordx4 v[224:227], v[194:195], off offset:32
	global_load_dwordx4 v[228:231], v[194:195], off offset:48
	v_mul_f32_e32 v101, v101, v101
	v_mul_f32_e32 v103, v103, v103
	v_fmac_f32_e32 v99, v98, v98
	v_fmac_f32_e32 v101, v100, v100
	v_mul_f32_e32 v105, v105, v105
	v_fmac_f32_e32 v103, v102, v102
	v_add_f32_e32 v98, v99, v101
	v_fmac_f32_e32 v105, v104, v104
	v_add_f32_e32 v98, v103, v98
	v_add_f32_e32 v98, v105, v98
	v_sub_u32_e32 v106, v96, v150
	v_add_u32_e32 v106, v106, v152
	v_ashrrev_i32_e32 v107, 31, v106
	v_lshlrev_b64 v[106:107], 12, v[106:107]
	v_lshl_add_u64 v[106:107], s[10:11], 0, v[106:107]
	v_lshl_add_u64 v[106:107], v[120:121], 1, v[106:107]
	v_mov_b32_dpp v112, v108 row_ror:8 row_mask:0xf bank_mask:0xf
	v_mov_b32_dpp v113, v109 row_ror:8 row_mask:0xf bank_mask:0xf
	v_mov_b32_dpp v115, v110 row_ror:8 row_mask:0xf bank_mask:0xf
	v_mov_b32_dpp v116, v111 row_ror:8 row_mask:0xf bank_mask:0xf
	s_waitcnt vmcnt(12)
	v_pk_add_f32 v[86:87], v[86:87], v[90:91]
	v_pk_add_f32 v[88:89], v[84:85], v[88:89]
	s_waitcnt vmcnt(12)
	v_pk_add_f32 v[90:91], v[82:83], v[94:95]
	v_pk_add_f32 v[80:81], v[80:81], v[92:93]
	v_cvt_pk_bf16_f32 v82, v88, v89
	v_mul_f32_e32 v89, v89, v89
	v_mul_f32_e32 v92, v87, v87
	v_cvt_pk_bf16_f32 v83, v86, v87
	v_cvt_pk_bf16_f32 v84, v80, v81
	v_mul_f32_e32 v81, v81, v81
	v_fmac_f32_e32 v89, v88, v88
	v_fmac_f32_e32 v92, v86, v86
	v_cvt_pk_bf16_f32 v85, v90, v91
	v_mul_f32_e32 v91, v91, v91
	v_fmac_f32_e32 v81, v80, v80
	v_add_f32_e32 v80, v89, v92
	v_fmac_f32_e32 v91, v90, v90
	v_add_f32_e32 v80, v81, v80
	v_add_f32_e32 v80, v91, v80
	v_add_f32_e32 v80, v98, v80
	v_mov_b32_e32 v81, v80
	s_nop 1
	v_permlane16_swap_b32_e32 v81, v80
	v_mov_b32_dpp v117, v82 row_ror:8 row_mask:0xf bank_mask:0xf
	v_mov_b32_dpp v118, v83 row_ror:8 row_mask:0xf bank_mask:0xf
	v_mov_b32_dpp v119, v84 row_ror:8 row_mask:0xf bank_mask:0xf
	v_mov_b32_dpp v123, v85 row_ror:8 row_mask:0xf bank_mask:0xf
	s_waitcnt lgkmcnt(0)
	v_add_f32_e32 v80, v80, v81
	v_mov_b32_e32 v81, v80
	s_nop 1
	v_permlane32_swap_b32_e32 v81, v80
	v_cndmask_b32_e64 v87, v118, v109, s[6:7]
	v_cndmask_b32_e64 v89, v123, v111, s[6:7]
	v_cndmask_b32_e64 v86, v117, v108, s[6:7]
	v_cndmask_b32_e64 v88, v119, v110, s[6:7]
	global_store_dwordx4 v[106:107], v[86:89], off
	v_cndmask_b32_e64 v83, v83, v113, s[6:7]
	v_cndmask_b32_e64 v85, v85, v116, s[6:7]
	v_add_co_u32_e32 v86, vcc, s69, v106
	v_cndmask_b32_e64 v82, v82, v112, s[6:7]
	v_cndmask_b32_e64 v84, v84, v115, s[6:7]
	v_addc_co_u32_e32 v87, vcc, 0, v107, vcc
	global_store_dwordx4 v[86:87], v[82:85], off
	s_and_saveexec_b64 s[50:51], s[8:9]
	s_cbranch_execz .LBB0_620
	s_waitcnt lgkmcnt(0)
	v_add_f32_e32 v82, v80, v81
	v_lshl_add_u64 v[80:81], v[96:97], 2, s[12:13]
	global_atomic_add_f32 v[80:81], v82, off
.LBB0_620:
	s_or_b64 exec, exec, s[50:51]
	v_or_b32_e32 v80, 48, v146
	s_waitcnt lgkmcnt(0)
	v_ashrrev_i32_e32 v81, 31, v80
	v_lshlrev_b64 v[82:83], 11, v[80:81]
	v_lshl_add_u64 v[82:83], v[82:83], 0, v[148:149]
	v_lshlrev_b64 v[82:83], 2, v[82:83]
	v_lshl_add_u64 v[84:85], s[16:17], 0, v[82:83]
	v_lshl_add_u64 v[82:83], s[18:19], 0, v[82:83]
	v_lshl_add_u64 v[82:83], v[82:83], 0, s[38:39]
	v_cmp_gt_i32_e32 vcc, s70, v80
	v_mov_b32_e32 v100, 0
	v_mov_b32_e32 v101, 0
	v_cndmask_b32_e32 v91, v83, v85, vcc
	v_cndmask_b32_e32 v90, v82, v84, vcc
	s_waitcnt vmcnt(16)
	s_nop 0
	v_mov_b64_e32 v[82:83], v[232:233]
	v_mov_b64_e32 v[84:85], v[234:235]
	v_mov_b64_e32 v[86:87], v[236:237]
	v_mov_b64_e32 v[88:89], v[238:239]
	s_waitcnt vmcnt(14)
	v_pk_add_f32 v[84:85], v[78:79], v[84:85]
	v_pk_add_f32 v[82:83], v[76:77], v[82:83]
	s_waitcnt vmcnt(14)
	v_pk_add_f32 v[88:89], v[74:75], v[88:89]
	v_pk_add_f32 v[86:87], v[72:73], v[86:87]
	v_cvt_pk_bf16_f32 v92, v82, v83
	v_cvt_pk_bf16_f32 v93, v84, v85
	v_mul_f32_e32 v83, v83, v83
	v_cvt_pk_bf16_f32 v94, v86, v87
	v_cvt_pk_bf16_f32 v95, v88, v89
	v_mov_b64_e32 v[72:73], v[240:241]
	v_mov_b64_e32 v[74:75], v[242:243]
	v_mov_b64_e32 v[76:77], v[244:245]
	v_mov_b64_e32 v[78:79], v[246:247]
	s_nop 1
	v_add_u32_e32 v188, 0xa0, v146
	v_ashrrev_i32_e32 v189, 31, v188
	v_lshlrev_b64 v[190:191], 11, v[188:189]
	v_lshl_add_u64 v[190:191], v[190:191], 0, v[148:149]
	v_lshlrev_b64 v[190:191], 2, v[190:191]
	v_lshl_add_u64 v[192:193], s[16:17], 0, v[190:191]
	v_lshl_add_u64 v[190:191], s[18:19], 0, v[190:191]
	v_lshl_add_u64 v[190:191], v[190:191], 0, s[38:39]
	v_cmp_gt_i32_e32 vcc, s83, v146
	s_nop 1
	v_cndmask_b32_e32 v195, v191, v193, vcc
	v_cndmask_b32_e32 v194, v190, v192, vcc
	global_load_dwordx4 v[232:235], v[194:195], off
	global_load_dwordx4 v[236:239], v[194:195], off offset:16
	global_load_dwordx4 v[240:243], v[194:195], off offset:32
	global_load_dwordx4 v[244:247], v[194:195], off offset:48
	v_mul_f32_e32 v85, v85, v85
	v_mul_f32_e32 v87, v87, v87
	v_fmac_f32_e32 v83, v82, v82
	v_fmac_f32_e32 v85, v84, v84
	v_mul_f32_e32 v89, v89, v89
	v_fmac_f32_e32 v87, v86, v86
	v_add_f32_e32 v82, v83, v85
	v_fmac_f32_e32 v89, v88, v88
	v_add_f32_e32 v82, v87, v82
	v_add_f32_e32 v82, v89, v82
	v_sub_u32_e32 v90, v80, v150
	v_add_u32_e32 v90, v90, v152
	v_ashrrev_i32_e32 v91, 31, v90
	v_lshlrev_b64 v[90:91], 12, v[90:91]
	v_lshl_add_u64 v[90:91], s[10:11], 0, v[90:91]
	v_lshl_add_u64 v[90:91], v[120:121], 1, v[90:91]
	v_mov_b32_dpp v96, v92 row_ror:8 row_mask:0xf bank_mask:0xf
	v_mov_b32_dpp v97, v93 row_ror:8 row_mask:0xf bank_mask:0xf
	v_mov_b32_dpp v98, v94 row_ror:8 row_mask:0xf bank_mask:0xf
	v_mov_b32_dpp v99, v95 row_ror:8 row_mask:0xf bank_mask:0xf
	s_waitcnt vmcnt(18)
; __device__ __forceinline__ unsigned cvt_pk_bf16(float lo, float hi) { unsigned r; asm volatile("v_cvt_pk_bf16_f32 %0, %1, %2" : "=v"(r) : "v"(lo), "v"(hi)); return r; }
; __device__ __forceinline__ float bflo(unsigned w) { return __uint_as_float(w << 16); }
; __device__ __forceinline__ float bfhi(unsigned w) { return __uint_as_float(w & 0xffff0000u); }
;     __device__ __forceinline__ void operator()(const f32x4 (&acc)[2][2][4][2], const Unit& u, int wr, int wc, int fr, int fq) const {
;     ...
;             for (int m = 0; m < 4; ++m) { const int row = row0 + ai * HALF + m * 16; const size_t off = (size_t)row * D + col0; float sq = 0.f; u32x4 w[2];
;                 const float sc = rsin ? __builtin_amdgcn_rcpf(rsin[row] * (1.f / D) + EPS) : 1.0f;
;                 u32x4 rr[2]; if (R) load_pair_lines(R, D, row, fr, col0, rr[0], rr[1]);
; #pragma unroll
;                 for (int bj = 0; bj < 2; ++bj) { f32x4 r0, r1;
;                     if (R) { const u32x4 rw = rr[bj]; r0 = (f32x4){bflo(rw.x), bfhi(rw.x), bflo(rw.y), bfhi(rw.y)}; r1 = (f32x4){bflo(rw.z), bfhi(rw.z), bflo(rw.w), bfhi(rw.w)}; }
;                     else { const float* rp = (row < 8192 ? src_p + off : src_s + (off - (size_t)8192 * D)) + 8 * bj; r0 = *(const f32x4*)rp; r1 = *(const f32x4*)(rp + 4); }
;                     const f32x4 o0 = r0 + acc[ai][bj][m][0] * sc, o1 = r1 + acc[ai][bj][m][1] * sc;
;                     sq += (o0[0] * o0[0] + o0[1] * o0[1]) + (o0[2] * o0[2] + o0[3] * o0[3]) + (o1[0] * o1[0] + o1[1] * o1[1]) + (o1[2] * o1[2] + o1[3] * o1[3]);
;                     w[bj].x = cvt_pk_bf16(o0[0], o0[1]); w[bj].y = cvt_pk_bf16(o0[2], o0[3]); w[bj].z = cvt_pk_bf16(o1[0], o1[1]); w[bj].w = cvt_pk_bf16(o1[2], o1[3]); }
;                 store_pair_lines(O, D, row, fr, col0, w[0], w[1]);
;                 if (ssout) { sq += __shfl_xor(sq, 16); sq += __shfl_xor(sq, 32); if (fq == 0) unsafeAtomicAdd(ssout + row, sq); } }
	v_pk_add_f32 v[70:71], v[70:71], v[74:75]
	v_pk_add_f32 v[72:73], v[68:69], v[72:73]
	s_waitcnt vmcnt(18)
	v_pk_add_f32 v[74:75], v[66:67], v[78:79]
	v_pk_add_f32 v[64:65], v[64:65], v[76:77]
	v_cvt_pk_bf16_f32 v66, v72, v73
	v_mul_f32_e32 v73, v73, v73
	v_mul_f32_e32 v76, v71, v71
	v_cvt_pk_bf16_f32 v67, v70, v71
	v_cvt_pk_bf16_f32 v68, v64, v65
	v_mul_f32_e32 v65, v65, v65
	v_fmac_f32_e32 v73, v72, v72
	v_fmac_f32_e32 v76, v70, v70
	v_cvt_pk_bf16_f32 v69, v74, v75
	v_mul_f32_e32 v75, v75, v75
	v_fmac_f32_e32 v65, v64, v64
	v_add_f32_e32 v64, v73, v76
	v_fmac_f32_e32 v75, v74, v74
	v_add_f32_e32 v64, v65, v64
	v_add_f32_e32 v64, v75, v64
	v_add_f32_e32 v64, v82, v64
	v_mov_b32_e32 v65, v64
	s_nop 1
	v_permlane16_swap_b32_e32 v65, v64
	v_mov_b32_dpp v100, v66 row_ror:8 row_mask:0xf bank_mask:0xf
	v_mov_b32_dpp v101, v67 row_ror:8 row_mask:0xf bank_mask:0xf
	v_mov_b32_dpp v102, v68 row_ror:8 row_mask:0xf bank_mask:0xf
	v_mov_b32_dpp v103, v69 row_ror:8 row_mask:0xf bank_mask:0xf
	s_waitcnt lgkmcnt(0)
	v_add_f32_e32 v64, v64, v65
	v_mov_b32_e32 v65, v64
	s_nop 1
	v_permlane32_swap_b32_e32 v65, v64
	v_cndmask_b32_e64 v71, v101, v93, s[6:7]
	v_cndmask_b32_e64 v73, v103, v95, s[6:7]
	v_cndmask_b32_e64 v70, v100, v92, s[6:7]
	v_cndmask_b32_e64 v72, v102, v94, s[6:7]
	global_store_dwordx4 v[90:91], v[70:73], off
	v_cndmask_b32_e64 v67, v67, v97, s[6:7]
	v_cndmask_b32_e64 v69, v69, v99, s[6:7]
	v_add_co_u32_e32 v70, vcc, s69, v90
	v_cndmask_b32_e64 v66, v66, v96, s[6:7]
	v_cndmask_b32_e64 v68, v68, v98, s[6:7]
	v_addc_co_u32_e32 v71, vcc, 0, v91, vcc
	global_store_dwordx4 v[70:71], v[66:69], off
	s_and_saveexec_b64 s[50:51], s[8:9]
	s_cbranch_execz .LBB0_622
	s_waitcnt lgkmcnt(0)
	v_add_f32_e32 v66, v64, v65
	v_lshl_add_u64 v[64:65], v[80:81], 2, s[12:13]
	global_atomic_add_f32 v[64:65], v66, off
.LBB0_622:
	s_or_b64 exec, exec, s[50:51]
	v_add_u32_e32 v64, 0x80, v146
	s_waitcnt lgkmcnt(0)
	v_ashrrev_i32_e32 v65, 31, v64
	v_lshlrev_b64 v[66:67], 11, v[64:65]
	v_lshl_add_u64 v[66:67], v[66:67], 0, v[148:149]
	v_lshlrev_b64 v[66:67], 2, v[66:67]
	v_lshl_add_u64 v[68:69], s[16:17], 0, v[66:67]
	v_lshl_add_u64 v[66:67], s[18:19], 0, v[66:67]
	v_lshl_add_u64 v[66:67], v[66:67], 0, s[38:39]
	v_cmp_gt_i32_e32 vcc, s81, v146
	v_mov_b32_e32 v84, 0
	v_mov_b32_e32 v85, 0
	v_cndmask_b32_e32 v75, v67, v69, vcc
	v_cndmask_b32_e32 v74, v66, v68, vcc
	s_waitcnt vmcnt(14)
	s_nop 0
	v_mov_b64_e32 v[66:67], v[196:197]
	v_mov_b64_e32 v[68:69], v[198:199]
	v_mov_b64_e32 v[70:71], v[204:205]
	v_mov_b64_e32 v[72:73], v[206:207]
	s_waitcnt vmcnt(20)
	v_pk_add_f32 v[68:69], v[62:63], v[68:69]
	v_pk_add_f32 v[66:67], v[60:61], v[66:67]
	s_waitcnt vmcnt(20)
	v_pk_add_f32 v[72:73], v[58:59], v[72:73]
	v_pk_add_f32 v[70:71], v[56:57], v[70:71]
	v_cvt_pk_bf16_f32 v76, v66, v67
	v_cvt_pk_bf16_f32 v77, v68, v69
	v_mul_f32_e32 v67, v67, v67
	v_cvt_pk_bf16_f32 v78, v70, v71
	v_cvt_pk_bf16_f32 v79, v72, v73
	v_mov_b64_e32 v[56:57], v[208:209]
	v_mov_b64_e32 v[58:59], v[210:211]
	v_mov_b64_e32 v[60:61], v[212:213]
	v_mov_b64_e32 v[62:63], v[214:215]
	s_nop 1
	v_add_u32_e32 v188, 0xb0, v146
	v_ashrrev_i32_e32 v189, 31, v188
	v_lshlrev_b64 v[190:191], 11, v[188:189]
	v_lshl_add_u64 v[190:191], v[190:191], 0, v[148:149]
	v_lshlrev_b64 v[190:191], 2, v[190:191]
	v_lshl_add_u64 v[192:193], s[16:17], 0, v[190:191]
	v_lshl_add_u64 v[190:191], s[18:19], 0, v[190:191]
	v_lshl_add_u64 v[190:191], v[190:191], 0, s[38:39]
	v_cmp_gt_i32_e32 vcc, s84, v146
	s_nop 1
	v_cndmask_b32_e32 v195, v191, v193, vcc
	v_cndmask_b32_e32 v194, v190, v192, vcc
	global_load_dwordx4 v[196:199], v[194:195], off
	global_load_dwordx4 v[204:207], v[194:195], off offset:16
	global_load_dwordx4 v[208:211], v[194:195], off offset:32
	global_load_dwordx4 v[212:215], v[194:195], off offset:48
	v_mul_f32_e32 v69, v69, v69
	v_mul_f32_e32 v71, v71, v71
	v_fmac_f32_e32 v67, v66, v66
	v_fmac_f32_e32 v69, v68, v68
	v_mul_f32_e32 v73, v73, v73
	v_fmac_f32_e32 v71, v70, v70
	v_add_f32_e32 v66, v67, v69
	v_fmac_f32_e32 v73, v72, v72
	v_add_f32_e32 v66, v71, v66
	v_add_f32_e32 v66, v73, v66
	v_sub_u32_e32 v74, v64, v150
	v_add_u32_e32 v74, v74, v152
	v_ashrrev_i32_e32 v75, 31, v74
	v_lshlrev_b64 v[74:75], 12, v[74:75]
	v_lshl_add_u64 v[74:75], s[10:11], 0, v[74:75]
	v_lshl_add_u64 v[74:75], v[120:121], 1, v[74:75]
	v_mov_b32_dpp v80, v76 row_ror:8 row_mask:0xf bank_mask:0xf
	v_mov_b32_dpp v81, v77 row_ror:8 row_mask:0xf bank_mask:0xf
	v_mov_b32_dpp v82, v78 row_ror:8 row_mask:0xf bank_mask:0xf
	v_mov_b32_dpp v83, v79 row_ror:8 row_mask:0xf bank_mask:0xf
	s_waitcnt vmcnt(24)
	v_pk_add_f32 v[54:55], v[54:55], v[58:59]
	v_pk_add_f32 v[56:57], v[52:53], v[56:57]
	s_waitcnt vmcnt(24)
	v_pk_add_f32 v[58:59], v[50:51], v[62:63]
	v_pk_add_f32 v[48:49], v[48:49], v[60:61]
	v_cvt_pk_bf16_f32 v50, v56, v57
	v_mul_f32_e32 v57, v57, v57
	v_mul_f32_e32 v60, v55, v55
	v_cvt_pk_bf16_f32 v51, v54, v55
	v_cvt_pk_bf16_f32 v52, v48, v49
	v_mul_f32_e32 v49, v49, v49
	v_fmac_f32_e32 v57, v56, v56
	v_fmac_f32_e32 v60, v54, v54
	v_cvt_pk_bf16_f32 v53, v58, v59
	v_mul_f32_e32 v59, v59, v59
	v_fmac_f32_e32 v49, v48, v48
	v_add_f32_e32 v48, v57, v60
	v_fmac_f32_e32 v59, v58, v58
	v_add_f32_e32 v48, v49, v48
	v_add_f32_e32 v48, v59, v48
	v_add_f32_e32 v48, v66, v48
	v_mov_b32_e32 v49, v48
	s_nop 1
	v_permlane16_swap_b32_e32 v49, v48
	v_mov_b32_dpp v84, v50 row_ror:8 row_mask:0xf bank_mask:0xf
	v_mov_b32_dpp v85, v51 row_ror:8 row_mask:0xf bank_mask:0xf
	v_mov_b32_dpp v86, v52 row_ror:8 row_mask:0xf bank_mask:0xf
	v_mov_b32_dpp v87, v53 row_ror:8 row_mask:0xf bank_mask:0xf
	s_waitcnt lgkmcnt(0)
	v_add_f32_e32 v48, v48, v49
	v_mov_b32_e32 v49, v48
	s_nop 1
	v_permlane32_swap_b32_e32 v49, v48
	v_cndmask_b32_e64 v55, v85, v77, s[6:7]
	v_cndmask_b32_e64 v57, v87, v79, s[6:7]
	v_cndmask_b32_e64 v54, v84, v76, s[6:7]
	v_cndmask_b32_e64 v56, v86, v78, s[6:7]
	global_store_dwordx4 v[74:75], v[54:57], off
	v_cndmask_b32_e64 v51, v51, v81, s[6:7]
	v_cndmask_b32_e64 v53, v53, v83, s[6:7]
	v_add_co_u32_e32 v54, vcc, s69, v74
	v_cndmask_b32_e64 v50, v50, v80, s[6:7]
	v_cndmask_b32_e64 v52, v52, v82, s[6:7]
	v_addc_co_u32_e32 v55, vcc, 0, v75, vcc
	global_store_dwordx4 v[54:55], v[50:53], off
	s_and_saveexec_b64 s[50:51], s[8:9]
	s_cbranch_execz .LBB0_624
	s_waitcnt lgkmcnt(0)
	v_add_f32_e32 v50, v48, v49
	v_lshl_add_u64 v[48:49], v[64:65], 2, s[12:13]
	global_atomic_add_f32 v[48:49], v50, off
; __device__ __forceinline__ unsigned cvt_pk_bf16(float lo, float hi) { unsigned r; asm volatile("v_cvt_pk_bf16_f32 %0, %1, %2" : "=v"(r) : "v"(lo), "v"(hi)); return r; }
; __device__ __forceinline__ float bflo(unsigned w) { return __uint_as_float(w << 16); }
; __device__ __forceinline__ float bfhi(unsigned w) { return __uint_as_float(w & 0xffff0000u); }
;     __device__ __forceinline__ void operator()(const f32x4 (&acc)[2][2][4][2], const Unit& u, int wr, int wc, int fr, int fq) const {
;     ...
;             for (int m = 0; m < 4; ++m) { const int row = row0 + ai * HALF + m * 16; const size_t off = (size_t)row * D + col0; float sq = 0.f; u32x4 w[2];
;                 const float sc = rsin ? __builtin_amdgcn_rcpf(rsin[row] * (1.f / D) + EPS) : 1.0f;
;                 u32x4 rr[2]; if (R) load_pair_lines(R, D, row, fr, col0, rr[0], rr[1]);
; #pragma unroll
;                 for (int bj = 0; bj < 2; ++bj) { f32x4 r0, r1;
;                     if (R) { const u32x4 rw = rr[bj]; r0 = (f32x4){bflo(rw.x), bfhi(rw.x), bflo(rw.y), bfhi(rw.y)}; r1 = (f32x4){bflo(rw.z), bfhi(rw.z), bflo(rw.w), bfhi(rw.w)}; }
;                     else { const float* rp = (row < 8192 ? src_p + off : src_s + (off - (size_t)8192 * D)) + 8 * bj; r0 = *(const f32x4*)rp; r1 = *(const f32x4*)(rp + 4); }
;                     const f32x4 o0 = r0 + acc[ai][bj][m][0] * sc, o1 = r1 + acc[ai][bj][m][1] * sc;
;                     sq += (o0[0] * o0[0] + o0[1] * o0[1]) + (o0[2] * o0[2] + o0[3] * o0[3]) + (o1[0] * o1[0] + o1[1] * o1[1]) + (o1[2] * o1[2] + o1[3] * o1[3]);
;                     w[bj].x = cvt_pk_bf16(o0[0], o0[1]); w[bj].y = cvt_pk_bf16(o0[2], o0[3]); w[bj].z = cvt_pk_bf16(o1[0], o1[1]); w[bj].w = cvt_pk_bf16(o1[2], o1[3]); }
;                 store_pair_lines(O, D, row, fr, col0, w[0], w[1]);
;                 if (ssout) { sq += __shfl_xor(sq, 16); sq += __shfl_xor(sq, 32); if (fq == 0) unsafeAtomicAdd(ssout + row, sq); } }
.LBB0_624:
	s_or_b64 exec, exec, s[50:51]
	v_add_u32_e32 v48, 0x90, v146
	s_waitcnt lgkmcnt(0)
	v_ashrrev_i32_e32 v49, 31, v48
	v_lshlrev_b64 v[50:51], 11, v[48:49]
	v_lshl_add_u64 v[50:51], v[50:51], 0, v[148:149]
	v_lshlrev_b64 v[50:51], 2, v[50:51]
	v_lshl_add_u64 v[52:53], s[16:17], 0, v[50:51]
	v_lshl_add_u64 v[50:51], s[18:19], 0, v[50:51]
	v_lshl_add_u64 v[50:51], v[50:51], 0, s[38:39]
	v_cmp_gt_i32_e32 vcc, s82, v146
	v_mov_b32_e32 v68, 0
	v_mov_b32_e32 v69, 0
	v_cndmask_b32_e32 v59, v51, v53, vcc
	v_cndmask_b32_e32 v58, v50, v52, vcc
	s_waitcnt vmcnt(14)
	s_nop 0
	v_mov_b64_e32 v[50:51], v[216:217]
	v_mov_b64_e32 v[52:53], v[218:219]
	v_mov_b64_e32 v[54:55], v[220:221]
	v_mov_b64_e32 v[56:57], v[222:223]
	s_waitcnt vmcnt(26)
	v_pk_add_f32 v[52:53], v[46:47], v[52:53]
	v_pk_add_f32 v[50:51], v[44:45], v[50:51]
	s_waitcnt vmcnt(26)
	v_pk_add_f32 v[56:57], v[42:43], v[56:57]
	v_pk_add_f32 v[54:55], v[40:41], v[54:55]
	v_cvt_pk_bf16_f32 v60, v50, v51
	v_cvt_pk_bf16_f32 v61, v52, v53
	v_mul_f32_e32 v51, v51, v51
	v_cvt_pk_bf16_f32 v62, v54, v55
	v_cvt_pk_bf16_f32 v63, v56, v57
	v_mov_b64_e32 v[40:41], v[224:225]
	v_mov_b64_e32 v[42:43], v[226:227]
	v_mov_b64_e32 v[44:45], v[228:229]
	v_mov_b64_e32 v[46:47], v[230:231]
	s_nop 1
	v_mul_f32_e32 v53, v53, v53
	v_mul_f32_e32 v55, v55, v55
	v_fmac_f32_e32 v51, v50, v50
	v_fmac_f32_e32 v53, v52, v52
	v_mul_f32_e32 v57, v57, v57
	v_fmac_f32_e32 v55, v54, v54
	v_add_f32_e32 v50, v51, v53
	v_fmac_f32_e32 v57, v56, v56
	v_add_f32_e32 v50, v55, v50
	v_add_f32_e32 v50, v57, v50
	v_sub_u32_e32 v58, v48, v150
	v_add_u32_e32 v58, v58, v152
	v_ashrrev_i32_e32 v59, 31, v58
	v_lshlrev_b64 v[58:59], 12, v[58:59]
	v_lshl_add_u64 v[58:59], s[10:11], 0, v[58:59]
	v_lshl_add_u64 v[58:59], v[120:121], 1, v[58:59]
	v_mov_b32_dpp v64, v60 row_ror:8 row_mask:0xf bank_mask:0xf
	v_mov_b32_dpp v65, v61 row_ror:8 row_mask:0xf bank_mask:0xf
	v_mov_b32_dpp v66, v62 row_ror:8 row_mask:0xf bank_mask:0xf
	v_mov_b32_dpp v67, v63 row_ror:8 row_mask:0xf bank_mask:0xf
	s_waitcnt vmcnt(26)
	v_pk_add_f32 v[38:39], v[38:39], v[42:43]
	v_pk_add_f32 v[40:41], v[36:37], v[40:41]
	s_waitcnt vmcnt(26)
	v_pk_add_f32 v[42:43], v[34:35], v[46:47]
	v_pk_add_f32 v[32:33], v[32:33], v[44:45]
	v_cvt_pk_bf16_f32 v34, v40, v41
	v_mul_f32_e32 v41, v41, v41
	v_mul_f32_e32 v44, v39, v39
	v_cvt_pk_bf16_f32 v35, v38, v39
	v_cvt_pk_bf16_f32 v36, v32, v33
	v_mul_f32_e32 v33, v33, v33
	v_fmac_f32_e32 v41, v40, v40
	v_fmac_f32_e32 v44, v38, v38
	v_cvt_pk_bf16_f32 v37, v42, v43
	v_mul_f32_e32 v43, v43, v43
	v_fmac_f32_e32 v33, v32, v32
	v_add_f32_e32 v32, v41, v44
	v_fmac_f32_e32 v43, v42, v42
	v_add_f32_e32 v32, v33, v32
	v_add_f32_e32 v32, v43, v32
	v_add_f32_e32 v32, v50, v32
	v_mov_b32_e32 v33, v32
	s_nop 1
	v_permlane16_swap_b32_e32 v33, v32
	v_mov_b32_dpp v68, v34 row_ror:8 row_mask:0xf bank_mask:0xf
	v_mov_b32_dpp v69, v35 row_ror:8 row_mask:0xf bank_mask:0xf
	v_mov_b32_dpp v70, v36 row_ror:8 row_mask:0xf bank_mask:0xf
	v_mov_b32_dpp v71, v37 row_ror:8 row_mask:0xf bank_mask:0xf
	s_waitcnt lgkmcnt(0)
	v_add_f32_e32 v32, v32, v33
	v_mov_b32_e32 v33, v32
	s_nop 1
	v_permlane32_swap_b32_e32 v33, v32
	v_cndmask_b32_e64 v39, v69, v61, s[6:7]
	v_cndmask_b32_e64 v41, v71, v63, s[6:7]
	v_cndmask_b32_e64 v38, v68, v60, s[6:7]
	v_cndmask_b32_e64 v40, v70, v62, s[6:7]
	global_store_dwordx4 v[58:59], v[38:41], off
	v_cndmask_b32_e64 v35, v35, v65, s[6:7]
	v_cndmask_b32_e64 v37, v37, v67, s[6:7]
	v_add_co_u32_e32 v38, vcc, s69, v58
	v_cndmask_b32_e64 v34, v34, v64, s[6:7]
	v_cndmask_b32_e64 v36, v36, v66, s[6:7]
	v_addc_co_u32_e32 v39, vcc, 0, v59, vcc
	global_store_dwordx4 v[38:39], v[34:37], off
	s_and_saveexec_b64 s[50:51], s[8:9]
	s_cbranch_execz .LBB0_626
	s_waitcnt lgkmcnt(0)
	v_add_f32_e32 v34, v32, v33
	v_lshl_add_u64 v[32:33], v[48:49], 2, s[12:13]
	global_atomic_add_f32 v[32:33], v34, off
.LBB0_626:
	s_or_b64 exec, exec, s[50:51]
	v_add_u32_e32 v32, 0xa0, v146
	s_waitcnt lgkmcnt(0)
	v_ashrrev_i32_e32 v33, 31, v32
	v_lshlrev_b64 v[34:35], 11, v[32:33]
	v_lshl_add_u64 v[34:35], v[34:35], 0, v[148:149]
	v_lshlrev_b64 v[34:35], 2, v[34:35]
	v_lshl_add_u64 v[36:37], s[16:17], 0, v[34:35]
	v_lshl_add_u64 v[34:35], s[18:19], 0, v[34:35]
	v_lshl_add_u64 v[34:35], v[34:35], 0, s[38:39]
	v_cmp_gt_i32_e32 vcc, s83, v146
	v_mov_b32_e32 v52, 0
	v_mov_b32_e32 v53, 0
	v_cndmask_b32_e32 v43, v35, v37, vcc
	v_cndmask_b32_e32 v42, v34, v36, vcc
	s_waitcnt vmcnt(10)
	s_nop 0
	v_mov_b64_e32 v[34:35], v[232:233]
	v_mov_b64_e32 v[36:37], v[234:235]
	v_mov_b64_e32 v[38:39], v[236:237]
	v_mov_b64_e32 v[40:41], v[238:239]
	s_waitcnt vmcnt(28)
	v_pk_add_f32 v[36:37], v[30:31], v[36:37]
	v_pk_add_f32 v[34:35], v[28:29], v[34:35]
	s_waitcnt vmcnt(28)
	v_pk_add_f32 v[40:41], v[26:27], v[40:41]
	v_pk_add_f32 v[38:39], v[24:25], v[38:39]
	v_cvt_pk_bf16_f32 v44, v34, v35
	v_cvt_pk_bf16_f32 v45, v36, v37
	v_mul_f32_e32 v35, v35, v35
	v_cvt_pk_bf16_f32 v46, v38, v39
	v_cvt_pk_bf16_f32 v47, v40, v41
	v_mov_b64_e32 v[24:25], v[240:241]
	v_mov_b64_e32 v[26:27], v[242:243]
	v_mov_b64_e32 v[28:29], v[244:245]
	v_mov_b64_e32 v[30:31], v[246:247]
	s_nop 1
	v_mul_f32_e32 v37, v37, v37
	v_mul_f32_e32 v39, v39, v39
	v_fmac_f32_e32 v35, v34, v34
	v_fmac_f32_e32 v37, v36, v36
	v_mul_f32_e32 v41, v41, v41
	v_fmac_f32_e32 v39, v38, v38
	v_add_f32_e32 v34, v35, v37
	v_fmac_f32_e32 v41, v40, v40
	v_add_f32_e32 v34, v39, v34
	v_add_f32_e32 v34, v41, v34
	v_sub_u32_e32 v42, v32, v150
	v_add_u32_e32 v42, v42, v152
	v_ashrrev_i32_e32 v43, 31, v42
	v_lshlrev_b64 v[42:43], 12, v[42:43]
	v_lshl_add_u64 v[42:43], s[10:11], 0, v[42:43]
	v_lshl_add_u64 v[42:43], v[120:121], 1, v[42:43]
	v_mov_b32_dpp v48, v44 row_ror:8 row_mask:0xf bank_mask:0xf
	v_mov_b32_dpp v49, v45 row_ror:8 row_mask:0xf bank_mask:0xf
	v_mov_b32_dpp v50, v46 row_ror:8 row_mask:0xf bank_mask:0xf
	v_mov_b32_dpp v51, v47 row_ror:8 row_mask:0xf bank_mask:0xf
	s_waitcnt vmcnt(28)
; __device__ __forceinline__ unsigned cvt_pk_bf16(float lo, float hi) { unsigned r; asm volatile("v_cvt_pk_bf16_f32 %0, %1, %2" : "=v"(r) : "v"(lo), "v"(hi)); return r; }
; __device__ __forceinline__ float bflo(unsigned w) { return __uint_as_float(w << 16); }
; __device__ __forceinline__ float bfhi(unsigned w) { return __uint_as_float(w & 0xffff0000u); }
;     __device__ __forceinline__ void operator()(const f32x4 (&acc)[2][2][4][2], const Unit& u, int wr, int wc, int fr, int fq) const {
;     ...
;             for (int m = 0; m < 4; ++m) { const int row = row0 + ai * HALF + m * 16; const size_t off = (size_t)row * D + col0; float sq = 0.f; u32x4 w[2];
;                 const float sc = rsin ? __builtin_amdgcn_rcpf(rsin[row] * (1.f / D) + EPS) : 1.0f;
;                 u32x4 rr[2]; if (R) load_pair_lines(R, D, row, fr, col0, rr[0], rr[1]);
; #pragma unroll
;                 for (int bj = 0; bj < 2; ++bj) { f32x4 r0, r1;
;                     if (R) { const u32x4 rw = rr[bj]; r0 = (f32x4){bflo(rw.x), bfhi(rw.x), bflo(rw.y), bfhi(rw.y)}; r1 = (f32x4){bflo(rw.z), bfhi(rw.z), bflo(rw.w), bfhi(rw.w)}; }
;                     else { const float* rp = (row < 8192 ? src_p + off : src_s + (off - (size_t)8192 * D)) + 8 * bj; r0 = *(const f32x4*)rp; r1 = *(const f32x4*)(rp + 4); }
;                     const f32x4 o0 = r0 + acc[ai][bj][m][0] * sc, o1 = r1 + acc[ai][bj][m][1] * sc;
;                     sq += (o0[0] * o0[0] + o0[1] * o0[1]) + (o0[2] * o0[2] + o0[3] * o0[3]) + (o1[0] * o1[0] + o1[1] * o1[1]) + (o1[2] * o1[2] + o1[3] * o1[3]);
;                     w[bj].x = cvt_pk_bf16(o0[0], o0[1]); w[bj].y = cvt_pk_bf16(o0[2], o0[3]); w[bj].z = cvt_pk_bf16(o1[0], o1[1]); w[bj].w = cvt_pk_bf16(o1[2], o1[3]); }
;                 store_pair_lines(O, D, row, fr, col0, w[0], w[1]);
;                 if (ssout) { sq += __shfl_xor(sq, 16); sq += __shfl_xor(sq, 32); if (fq == 0) unsafeAtomicAdd(ssout + row, sq); } }
	v_pk_add_f32 v[22:23], v[22:23], v[26:27]
	v_pk_add_f32 v[24:25], v[20:21], v[24:25]
	s_waitcnt vmcnt(28)
	v_pk_add_f32 v[26:27], v[18:19], v[30:31]
	v_pk_add_f32 v[16:17], v[16:17], v[28:29]
	v_cvt_pk_bf16_f32 v18, v24, v25
	v_mul_f32_e32 v25, v25, v25
	v_mul_f32_e32 v28, v23, v23
	v_cvt_pk_bf16_f32 v19, v22, v23
	v_cvt_pk_bf16_f32 v20, v16, v17
	v_mul_f32_e32 v17, v17, v17
	v_fmac_f32_e32 v25, v24, v24
	v_fmac_f32_e32 v28, v22, v22
	v_cvt_pk_bf16_f32 v21, v26, v27
	v_mul_f32_e32 v27, v27, v27
	v_fmac_f32_e32 v17, v16, v16
	v_add_f32_e32 v16, v25, v28
	v_fmac_f32_e32 v27, v26, v26
	v_add_f32_e32 v16, v17, v16
	v_add_f32_e32 v16, v27, v16
	v_add_f32_e32 v16, v34, v16
	v_mov_b32_e32 v17, v16
	s_nop 1
	v_permlane16_swap_b32_e32 v17, v16
	v_mov_b32_dpp v52, v18 row_ror:8 row_mask:0xf bank_mask:0xf
	v_mov_b32_dpp v53, v19 row_ror:8 row_mask:0xf bank_mask:0xf
	v_mov_b32_dpp v54, v20 row_ror:8 row_mask:0xf bank_mask:0xf
	v_mov_b32_dpp v55, v21 row_ror:8 row_mask:0xf bank_mask:0xf
	s_waitcnt lgkmcnt(0)
	v_add_f32_e32 v16, v16, v17
	v_mov_b32_e32 v17, v16
	s_nop 1
	v_permlane32_swap_b32_e32 v17, v16
	v_cndmask_b32_e64 v23, v53, v45, s[6:7]
	v_cndmask_b32_e64 v25, v55, v47, s[6:7]
	v_cndmask_b32_e64 v22, v52, v44, s[6:7]
	v_cndmask_b32_e64 v24, v54, v46, s[6:7]
	global_store_dwordx4 v[42:43], v[22:25], off
	v_cndmask_b32_e64 v19, v19, v49, s[6:7]
	v_cndmask_b32_e64 v21, v21, v51, s[6:7]
	v_add_co_u32_e32 v22, vcc, s69, v42
	v_cndmask_b32_e64 v18, v18, v48, s[6:7]
	v_cndmask_b32_e64 v20, v20, v50, s[6:7]
	v_addc_co_u32_e32 v23, vcc, 0, v43, vcc
	global_store_dwordx4 v[22:23], v[18:21], off
	s_and_saveexec_b64 s[50:51], s[8:9]
	s_cbranch_execz .LBB0_628
	s_waitcnt lgkmcnt(0)
	v_add_f32_e32 v18, v16, v17
	v_lshl_add_u64 v[16:17], v[32:33], 2, s[12:13]
	global_atomic_add_f32 v[16:17], v18, off
.LBB0_628:
	s_or_b64 exec, exec, s[50:51]
	v_add_u32_e32 v16, 0xb0, v146
	s_waitcnt lgkmcnt(0)
	v_ashrrev_i32_e32 v17, 31, v16
	v_lshlrev_b64 v[18:19], 11, v[16:17]
	v_lshl_add_u64 v[18:19], v[18:19], 0, v[148:149]
	v_lshlrev_b64 v[18:19], 2, v[18:19]
	v_lshl_add_u64 v[20:21], s[16:17], 0, v[18:19]
	v_lshl_add_u64 v[18:19], s[18:19], 0, v[18:19]
	v_lshl_add_u64 v[18:19], v[18:19], 0, s[38:39]
	v_cmp_gt_i32_e32 vcc, s84, v146
	v_mov_b32_e32 v36, 0
	v_mov_b32_e32 v37, 0
	v_cndmask_b32_e32 v27, v19, v21, vcc
	v_cndmask_b32_e32 v26, v18, v20, vcc
	s_waitcnt vmcnt(6)
	s_nop 0
	v_mov_b64_e32 v[18:19], v[196:197]
	v_mov_b64_e32 v[20:21], v[198:199]
	v_mov_b64_e32 v[22:23], v[204:205]
	v_mov_b64_e32 v[24:25], v[206:207]
	s_waitcnt vmcnt(30)
	v_pk_add_f32 v[20:21], v[14:15], v[20:21]
	v_pk_add_f32 v[18:19], v[12:13], v[18:19]
	s_waitcnt vmcnt(30)
	v_pk_add_f32 v[24:25], v[10:11], v[24:25]
	v_pk_add_f32 v[22:23], v[8:9], v[22:23]
	v_cvt_pk_bf16_f32 v28, v18, v19
	v_cvt_pk_bf16_f32 v29, v20, v21
	v_mul_f32_e32 v19, v19, v19
	v_cvt_pk_bf16_f32 v30, v22, v23
	v_cvt_pk_bf16_f32 v31, v24, v25
	v_mov_b64_e32 v[8:9], v[208:209]
	v_mov_b64_e32 v[10:11], v[210:211]
	v_mov_b64_e32 v[12:13], v[212:213]
	v_mov_b64_e32 v[14:15], v[214:215]
	s_nop 1
	v_mul_f32_e32 v21, v21, v21
	v_mul_f32_e32 v23, v23, v23
	v_fmac_f32_e32 v19, v18, v18
	v_fmac_f32_e32 v21, v20, v20
	v_mul_f32_e32 v25, v25, v25
	v_fmac_f32_e32 v23, v22, v22
	v_add_f32_e32 v18, v19, v21
	v_fmac_f32_e32 v25, v24, v24
	v_add_f32_e32 v18, v23, v18
	v_add_f32_e32 v18, v25, v18
	v_sub_u32_e32 v26, v16, v150
	v_add_u32_e32 v26, v26, v152
	v_ashrrev_i32_e32 v27, 31, v26
	v_lshlrev_b64 v[26:27], 12, v[26:27]
	v_lshl_add_u64 v[26:27], s[10:11], 0, v[26:27]
	v_lshl_add_u64 v[26:27], v[120:121], 1, v[26:27]
	v_mov_b32_dpp v32, v28 row_ror:8 row_mask:0xf bank_mask:0xf
	v_mov_b32_dpp v33, v29 row_ror:8 row_mask:0xf bank_mask:0xf
	v_mov_b32_dpp v34, v30 row_ror:8 row_mask:0xf bank_mask:0xf
	v_mov_b32_dpp v35, v31 row_ror:8 row_mask:0xf bank_mask:0xf
	s_waitcnt vmcnt(30)
	v_pk_add_f32 v[6:7], v[6:7], v[10:11]
	v_pk_add_f32 v[8:9], v[4:5], v[8:9]
	s_waitcnt vmcnt(30)
	v_pk_add_f32 v[10:11], v[2:3], v[14:15]
	v_pk_add_f32 v[0:1], v[0:1], v[12:13]
	v_cvt_pk_bf16_f32 v2, v8, v9
	v_mul_f32_e32 v9, v9, v9
	v_mul_f32_e32 v12, v7, v7
	v_cvt_pk_bf16_f32 v3, v6, v7
	v_cvt_pk_bf16_f32 v4, v0, v1
	v_mul_f32_e32 v1, v1, v1
	v_fmac_f32_e32 v9, v8, v8
	v_fmac_f32_e32 v12, v6, v6
	v_cvt_pk_bf16_f32 v5, v10, v11
	v_mul_f32_e32 v11, v11, v11
	v_fmac_f32_e32 v1, v0, v0
	v_add_f32_e32 v0, v9, v12
	v_fmac_f32_e32 v11, v10, v10
	v_add_f32_e32 v0, v1, v0
	v_add_f32_e32 v0, v11, v0
	v_add_f32_e32 v0, v18, v0
	v_mov_b32_e32 v1, v0
	s_nop 1
	v_permlane16_swap_b32_e32 v1, v0
	v_mov_b32_dpp v36, v2 row_ror:8 row_mask:0xf bank_mask:0xf
	v_mov_b32_dpp v37, v3 row_ror:8 row_mask:0xf bank_mask:0xf
	v_mov_b32_dpp v38, v4 row_ror:8 row_mask:0xf bank_mask:0xf
	v_mov_b32_dpp v39, v5 row_ror:8 row_mask:0xf bank_mask:0xf
	s_waitcnt lgkmcnt(0)
	v_add_f32_e32 v0, v0, v1
	v_mov_b32_e32 v1, v0
	s_nop 1
	v_permlane32_swap_b32_e32 v1, v0
	v_cndmask_b32_e64 v7, v37, v29, s[6:7]
	v_cndmask_b32_e64 v9, v39, v31, s[6:7]
	v_cndmask_b32_e64 v6, v36, v28, s[6:7]
	v_cndmask_b32_e64 v8, v38, v30, s[6:7]
	global_store_dwordx4 v[26:27], v[6:9], off
	v_cndmask_b32_e64 v3, v3, v33, s[6:7]
	v_cndmask_b32_e64 v5, v5, v35, s[6:7]
	v_add_co_u32_e32 v6, vcc, s69, v26
	v_cndmask_b32_e64 v2, v2, v32, s[6:7]
	v_cndmask_b32_e64 v4, v4, v34, s[6:7]
	v_addc_co_u32_e32 v7, vcc, 0, v27, vcc
	global_store_dwordx4 v[6:7], v[2:5], off
	s_and_saveexec_b64 s[50:51], s[8:9]
	s_cbranch_execz .LBB0_604
	s_waitcnt lgkmcnt(0)
	v_add_f32_e32 v2, v0, v1
	v_lshl_add_u64 v[0:1], v[16:17], 2, s[12:13]
	global_atomic_add_f32 v[0:1], v2, off
	s_branch .LBB0_604

;     __device__ __forceinline__ void operator()(const f32x4 (&acc)[2][2][4][2], const Unit& u, int wr, int wc, int fr, int fq) const {
;     ...
;             for (int m = 0; m < 4; ++m) { const int row = row0 + ai * HALF + m * 16; const size_t off = (size_t)row * D + col0; float sq = 0.f; u32x4 w[2];
;                 const float sc = rsin ? __builtin_amdgcn_rcpf(rsin[row] * (1.f / D) + EPS) : 1.0f;
;                 u32x4 rr[2]; if (R) load_pair_lines(R, D, row, fr, col0, rr[0], rr[1]);
; template <class Epi>
; __device__ __forceinline__ void gemm_phase(LAS unsigned char* lds, const Gemm g, const StaticOrder& S, const Epi& E) {
;     ...
; #pragma unroll
;         for (int a = 0; a < 2; ++a)
; #pragma unroll
;             for (int b = 0; b < 2; ++b)
; #pragma unroll
;                 for (int m = 0; m < 4; ++m)
; #pragma unroll
;                     for (int n = 0; n < 2; ++n) acc[a][b][m][n] = (f32x4){0.f, 0.f, 0.f, 0.f};
;         cur = nxt; cA = nA; cB = nB; ++ui;
.LBB0_805:
	s_ashr_i32 s41, s40, 31
	s_xor_b64 s[44:45], s[54:55], -1
	s_lshl_b64 s[42:43], s[40:41], 22
	s_add_u32 s42, s58, s42
	s_addc_u32 s43, s59, s43
	s_and_b64 s[46:47], s[54:55], exec
	s_cselect_b32 s41, s43, s51
	s_cselect_b32 s75, s42, s50
	s_ashr_i32 s39, s38, 31
	s_lshl_b64 s[46:47], s[38:39], 22
	s_add_u32 s46, s60, s46
	s_addc_u32 s47, s61, s47
	s_and_b64 s[54:55], s[54:55], exec
	s_cselect_b32 s39, s47, s53
	s_cselect_b32 s77, s46, s52
	s_add_u32 s50, s50, 0x200080
	s_addc_u32 s51, s51, 0
	s_add_u32 s78, s52, 0x100
	v_mov_b32_e32 v0, 0
	s_addc_u32 s79, s53, 0
	s_mov_b32 s80, -2
	v_mov_b32_e32 v1, v0
	v_mov_b32_e32 v2, v0
	v_mov_b32_e32 v3, v0
	v_mov_b32_e32 v4, v0
	v_mov_b32_e32 v5, v0
	v_mov_b32_e32 v6, v0
	v_mov_b32_e32 v7, v0
	v_mov_b32_e32 v16, v0
	v_mov_b32_e32 v17, v0
	v_mov_b32_e32 v18, v0
	v_mov_b32_e32 v19, v0
	v_mov_b32_e32 v20, v0
	v_mov_b32_e32 v21, v0
	v_mov_b32_e32 v22, v0
	v_mov_b32_e32 v23, v0
	v_mov_b32_e32 v32, v0
	v_mov_b32_e32 v33, v0
	v_mov_b32_e32 v34, v0
	v_mov_b32_e32 v35, v0
	v_mov_b32_e32 v36, v0
	v_mov_b32_e32 v37, v0
	v_mov_b32_e32 v38, v0
	v_mov_b32_e32 v39, v0
	v_mov_b32_e32 v48, v0
	v_mov_b32_e32 v49, v0
	v_mov_b32_e32 v50, v0
	v_mov_b32_e32 v51, v0
	v_mov_b32_e32 v52, v0
	v_mov_b32_e32 v53, v0
	v_mov_b32_e32 v54, v0
	v_mov_b32_e32 v55, v0
	v_mov_b32_e32 v8, v0
	v_mov_b32_e32 v9, v0
	v_mov_b32_e32 v10, v0
	v_mov_b32_e32 v11, v0
	v_mov_b32_e32 v12, v0
	v_mov_b32_e32 v13, v0
	v_mov_b32_e32 v14, v0
	v_mov_b32_e32 v15, v0
	v_mov_b32_e32 v24, v0
	v_mov_b32_e32 v25, v0
	v_mov_b32_e32 v26, v0
	v_mov_b32_e32 v27, v0
	v_mov_b32_e32 v28, v0
	v_mov_b32_e32 v29, v0
	v_mov_b32_e32 v30, v0
	v_mov_b32_e32 v31, v0
	v_mov_b32_e32 v40, v0
	v_mov_b32_e32 v41, v0
	v_mov_b32_e32 v42, v0
	v_mov_b32_e32 v43, v0
	v_mov_b32_e32 v44, v0
	v_mov_b32_e32 v45, v0
	v_mov_b32_e32 v46, v0
	v_mov_b32_e32 v47, v0
	v_mov_b32_e32 v56, v0
	v_mov_b32_e32 v57, v0
	v_mov_b32_e32 v58, v0
	v_mov_b32_e32 v59, v0
	v_mov_b32_e32 v60, v0
	v_mov_b32_e32 v61, v0
	v_mov_b32_e32 v62, v0
	v_mov_b32_e32 v63, v0
	v_mov_b32_e32 v64, v0
	v_mov_b32_e32 v65, v0
	v_mov_b32_e32 v66, v0
	v_mov_b32_e32 v67, v0
	v_mov_b32_e32 v68, v0
	v_mov_b32_e32 v69, v0
	v_mov_b32_e32 v70, v0
	v_mov_b32_e32 v71, v0
	v_mov_b32_e32 v80, v0
	v_mov_b32_e32 v81, v0
	v_mov_b32_e32 v82, v0
	v_mov_b32_e32 v83, v0
	v_mov_b32_e32 v84, v0
	v_mov_b32_e32 v85, v0
	v_mov_b32_e32 v86, v0
	v_mov_b32_e32 v87, v0
	v_mov_b32_e32 v96, v0
	v_mov_b32_e32 v97, v0
	v_mov_b32_e32 v98, v0
	v_mov_b32_e32 v99, v0
	v_mov_b32_e32 v100, v0
	v_mov_b32_e32 v101, v0
	v_mov_b32_e32 v102, v0
	v_mov_b32_e32 v103, v0
	v_mov_b32_e32 v112, v0
	v_mov_b32_e32 v113, v0
	v_mov_b32_e32 v114, v0
	v_mov_b32_e32 v115, v0
	v_mov_b32_e32 v116, v0
	v_mov_b32_e32 v117, v0
	v_mov_b32_e32 v118, v0
	v_mov_b32_e32 v119, v0
	v_mov_b32_e32 v72, v0
	v_mov_b32_e32 v73, v0
	v_mov_b32_e32 v74, v0
	v_mov_b32_e32 v75, v0
	v_mov_b32_e32 v76, v0
	v_mov_b32_e32 v77, v0
	v_mov_b32_e32 v78, v0
	v_mov_b32_e32 v79, v0
	v_mov_b32_e32 v88, v0
	v_mov_b32_e32 v89, v0
	v_mov_b32_e32 v90, v0
	v_mov_b32_e32 v91, v0
	v_mov_b32_e32 v92, v0
	v_mov_b32_e32 v93, v0
	v_mov_b32_e32 v94, v0
	v_mov_b32_e32 v95, v0
	v_mov_b32_e32 v104, v0
	v_mov_b32_e32 v105, v0
	v_mov_b32_e32 v106, v0
	v_mov_b32_e32 v107, v0
	v_mov_b32_e32 v108, v0
	v_mov_b32_e32 v109, v0
	v_mov_b32_e32 v110, v0
	v_mov_b32_e32 v111, v0
	v_mov_b32_e32 v120, v0
	v_mov_b32_e32 v121, v0
	v_mov_b32_e32 v122, v0
	v_mov_b32_e32 v123, v0
	v_mov_b32_e32 v124, v0
	v_mov_b32_e32 v125, v0
	v_mov_b32_e32 v126, v0
	v_mov_b32_e32 v127, v0
	s_lshl_b32 s33, s48, 8
	s_add_i32 s33, s33, s69
	v_or_b32_e32 v162, s33, v154
	v_ashrrev_i32_e32 v163, 31, v162
	v_lshl_or_b32 v146, s74, 8, v155
	v_lshlrev_b64 v[164:165], 12, v[162:163]
	v_or_b32_e32 v162, 8, v162
	v_or_b32_e32 v150, s33, v152
	v_ashrrev_i32_e32 v147, 31, v146
	v_ashrrev_i32_e32 v163, 31, v162
	v_ashrrev_i32_e32 v151, 31, v150
	v_lshl_add_u64 v[160:161], s[16:17], 0, v[164:165]
	v_lshlrev_b64 v[146:147], 1, v[146:147]
	v_lshlrev_b64 v[166:167], 12, v[162:163]
	v_lshl_add_u64 v[148:149], v[150:151], 2, s[10:11]
	v_lshl_add_u64 v[160:161], v[160:161], 0, v[146:147]
	v_lshl_add_u64 v[162:163], s[16:17], 0, v[166:167]
	global_load_dword v232, v[148:149], off
	global_load_dwordx4 v[236:239], v[160:161], off
	v_lshl_add_u64 v[162:163], v[162:163], 0, v[146:147]
	global_load_dwordx4 v[240:243], v[162:163], off
; #define PG8_STAGE(bufoff, gbase, voff) do { _Pragma("unroll") for (int _i = 0; _i < 2; ++_i) \
;         __builtin_amdgcn_global_load_lds((const unsigned*)((const char*)(gbase) + (voff)[_i]), (LAS unsigned*)(lds + (bufoff) + ldsw + _i * 8192), 16, 0, 0); } while (0)
; #define PG8_LDA(dst, b, h) do { _Pragma("unroll") for (int m = 0; m < 4; ++m) _Pragma("unroll") for (int k = 0; k < 2; ++k) dst[m][k] = *(const LAS bf16x8*)(lds + PG8_SA(b, h) + aoff + m * 2048 + k * 1024); } while (0)
; #define PG8_LDB(dst, b, h) do { _Pragma("unroll") for (int n = 0; n < 2; ++n) _Pragma("unroll") for (int k = 0; k < 2; ++k) dst[n][k] = *(const LAS bf16x8*)(lds + PG8_SB(b, h) + boff + n * 2048 + k * 1024); } while (0)
; #define PG8_MMA(ai, bj, At, Bt) do { __builtin_amdgcn_s_setprio(1); _Pragma("unroll") for (int m = 0; m < 4; ++m) _Pragma("unroll") for (int n = 0; n < 2; ++n) _Pragma("unroll") for (int k = 0; k < 2; ++k) \
;         acc[ai][bj][m][n] = __builtin_amdgcn_mfma_f32_16x16x32_bf16(Bt[n][k], At[m][k], acc[ai][bj][m][n], 0, 0, 0); __builtin_amdgcn_s_setprio(0); } while (0)
; #define PG8_WAIT_L(n) asm volatile("s_waitcnt lgkmcnt(" #n ")" ::: "memory")
; #define PG8_BAR __builtin_amdgcn_s_barrier()
; #define PG8_SCHED __builtin_amdgcn_sched_barrier(0)
; template <class Epi>
; __device__ __forceinline__ void gemm_phase(LAS unsigned char* lds, const Gemm g, const StaticOrder& S, const Epi& E) {
;     ...
;             PG8_LDB(B0, 0, 0); PG8_SCHED; PG8_LDA(At, 0, 0); PG8_STAGE(PG8_SA(1, 1), a1 + hstep, voffA);
;             PG8_WAIT_L(8); PG8_BAR; PG8_WAIT_L(0); PG8_MMA(0, 0, At, B0); PG8_BAR; PG8_SCHED;
;             PG8_LDB(B1, 0, 1); PG8_STAGE(PG8_SB(0, 0), b2, voffB0);
;             PG8_BAR; PG8_WAIT_L(0); PG8_MMA(0, 1, At, B1); PG8_BAR;
;             PG8_LDA(At, 0, 1); PG8_STAGE(PG8_SA(0, 0), a2, voffA);
;             PG8_BAR; PG8_WAIT_L(0); PG8_MMA(1, 0, At, B0); PG8_BAR; PG8_SCHED;
.LBB0_806:
	ds_read_b128 v[146:149], v156
	ds_read_b128 v[160:163], v156 offset:1024
	ds_read_b128 v[164:167], v156 offset:2048
	ds_read_b128 v[168:171], v156 offset:3072
	s_add_u32 s33, s50, 0xffe00080
	s_addc_u32 s52, s51, -1
	s_cmpk_eq_i32 s80, 0x7c
	s_cselect_b32 s53, s41, s52
	s_cselect_b32 s52, s75, s33
	s_cselect_b32 s55, s39, s79
	s_cselect_b32 s54, s77, s78
	v_lshl_add_u64 v[150:151], s[50:51], 0, v[140:141]
	s_add_i32 m0, s49, 0xc000
	ds_read_b128 v[172:175], v157
	ds_read_b128 v[176:179], v157 offset:1024
	ds_read_b128 v[180:183], v157 offset:2048
	ds_read_b128 v[184:187], v157 offset:3072
	ds_read_b128 v[188:191], v157 offset:4096
	ds_read_b128 v[192:195], v157 offset:5120
	ds_read_b128 v[196:199], v157 offset:6144
	ds_read_b128 v[204:207], v157 offset:7168
	global_load_lds_dwordx4 v[150:151], off
	v_lshl_add_u64 v[150:151], s[50:51], 0, v[142:143]
	s_add_i32 m0, s49, 0xe000
	s_nop 0
	global_load_lds_dwordx4 v[150:151], off
	s_waitcnt lgkmcnt(8)
	s_barrier
	s_waitcnt lgkmcnt(0)
	v_mfma_f32_16x16x32_bf16 v[124:127], v[146:149], v[172:175], v[124:127]
	v_mfma_f32_16x16x32_bf16 v[120:123], v[164:167], v[172:175], v[120:123]
	v_mfma_f32_16x16x32_bf16 v[108:111], v[146:149], v[180:183], v[108:111]
	v_mfma_f32_16x16x32_bf16 v[104:107], v[164:167], v[180:183], v[104:107]
	v_mfma_f32_16x16x32_bf16 v[92:95], v[146:149], v[188:191], v[92:95]
	v_mfma_f32_16x16x32_bf16 v[88:91], v[164:167], v[188:191], v[88:91]
	v_mfma_f32_16x16x32_bf16 v[76:79], v[146:149], v[196:199], v[76:79]
	v_mfma_f32_16x16x32_bf16 v[72:75], v[164:167], v[196:199], v[72:75]
	v_mfma_f32_16x16x32_bf16 v[124:127], v[160:163], v[176:179], v[124:127]
	v_mfma_f32_16x16x32_bf16 v[120:123], v[168:171], v[176:179], v[120:123]
	v_mfma_f32_16x16x32_bf16 v[108:111], v[160:163], v[184:187], v[108:111]
	v_mfma_f32_16x16x32_bf16 v[104:107], v[168:171], v[184:187], v[104:107]
	v_mfma_f32_16x16x32_bf16 v[92:95], v[160:163], v[192:195], v[92:95]
	v_mfma_f32_16x16x32_bf16 v[88:91], v[168:171], v[192:195], v[88:91]
	v_mfma_f32_16x16x32_bf16 v[76:79], v[160:163], v[204:207], v[76:79]
	v_mfma_f32_16x16x32_bf16 v[72:75], v[168:171], v[204:207], v[72:75]
	s_barrier
	s_add_i32 s33, s72, s62
	v_lshl_add_u64 v[150:151], s[54:55], 0, v[130:131]
	s_mov_b32 m0, s33
	ds_read_b128 v[208:211], v158
	ds_read_b128 v[212:215], v158 offset:1024
	ds_read_b128 v[216:219], v158 offset:2048
	ds_read_b128 v[220:223], v158 offset:3072
	global_load_lds_dwordx4 v[150:151], off
	v_lshl_add_u64 v[200:201], s[54:55], 0, v[136:137]
	s_add_i32 m0, s33, 0x2000
	s_nop 0
	global_load_lds_dwordx4 v[200:201], off
	s_barrier
	s_waitcnt lgkmcnt(0)
	v_mfma_f32_16x16x32_bf16 v[116:119], v[208:211], v[172:175], v[116:119]
	v_mfma_f32_16x16x32_bf16 v[112:115], v[216:219], v[172:175], v[112:115]
	v_mfma_f32_16x16x32_bf16 v[100:103], v[208:211], v[180:183], v[100:103]
	v_mfma_f32_16x16x32_bf16 v[96:99], v[216:219], v[180:183], v[96:99]
	v_mfma_f32_16x16x32_bf16 v[84:87], v[208:211], v[188:191], v[84:87]
	v_mfma_f32_16x16x32_bf16 v[80:83], v[216:219], v[188:191], v[80:83]
	v_mfma_f32_16x16x32_bf16 v[68:71], v[208:211], v[196:199], v[68:71]
	v_mfma_f32_16x16x32_bf16 v[64:67], v[216:219], v[196:199], v[64:67]
	v_mfma_f32_16x16x32_bf16 v[116:119], v[212:215], v[176:179], v[116:119]
	v_mfma_f32_16x16x32_bf16 v[112:115], v[220:223], v[176:179], v[112:115]
	v_mfma_f32_16x16x32_bf16 v[100:103], v[212:215], v[184:187], v[100:103]
	v_mfma_f32_16x16x32_bf16 v[96:99], v[220:223], v[184:187], v[96:99]
	v_mfma_f32_16x16x32_bf16 v[84:87], v[212:215], v[192:195], v[84:87]
	v_mfma_f32_16x16x32_bf16 v[80:83], v[220:223], v[192:195], v[80:83]
	v_mfma_f32_16x16x32_bf16 v[68:71], v[212:215], v[204:207], v[68:71]
	v_mfma_f32_16x16x32_bf16 v[64:67], v[220:223], v[204:207], v[64:67]
	s_mov_b32 m0, s49
	v_lshl_add_u64 v[224:225], s[52:53], 0, v[128:129]
	s_barrier
	ds_read_b128 v[172:175], v157 offset:16384
	ds_read_b128 v[176:179], v157 offset:17408
	ds_read_b128 v[180:183], v157 offset:18432
	ds_read_b128 v[184:187], v157 offset:19456
	ds_read_b128 v[188:191], v157 offset:20480
	ds_read_b128 v[192:195], v157 offset:21504
	ds_read_b128 v[196:199], v157 offset:22528
	ds_read_b128 v[204:207], v157 offset:23552
	global_load_lds_dwordx4 v[224:225], off
	v_lshl_add_u64 v[226:227], s[52:53], 0, v[134:135]
	s_mov_b32 m0, s63
	s_nop 0
	global_load_lds_dwordx4 v[226:227], off
	s_barrier
	s_waitcnt lgkmcnt(0)
	v_mfma_f32_16x16x32_bf16 v[60:63], v[146:149], v[172:175], v[60:63]
	v_mfma_f32_16x16x32_bf16 v[56:59], v[164:167], v[172:175], v[56:59]
	v_mfma_f32_16x16x32_bf16 v[44:47], v[146:149], v[180:183], v[44:47]
	v_mfma_f32_16x16x32_bf16 v[40:43], v[164:167], v[180:183], v[40:43]
	v_mfma_f32_16x16x32_bf16 v[28:31], v[146:149], v[188:191], v[28:31]
	v_mfma_f32_16x16x32_bf16 v[24:27], v[164:167], v[188:191], v[24:27]
	v_mfma_f32_16x16x32_bf16 v[12:15], v[146:149], v[196:199], v[12:15]
	v_mfma_f32_16x16x32_bf16 v[8:11], v[164:167], v[196:199], v[8:11]
	v_mfma_f32_16x16x32_bf16 v[60:63], v[160:163], v[176:179], v[60:63]
	v_mfma_f32_16x16x32_bf16 v[56:59], v[168:171], v[176:179], v[56:59]
	v_mfma_f32_16x16x32_bf16 v[44:47], v[160:163], v[184:187], v[44:47]
	v_mfma_f32_16x16x32_bf16 v[40:43], v[168:171], v[184:187], v[40:43]
	v_mfma_f32_16x16x32_bf16 v[28:31], v[160:163], v[192:195], v[28:31]
	v_mfma_f32_16x16x32_bf16 v[24:27], v[168:171], v[192:195], v[24:27]
	v_mfma_f32_16x16x32_bf16 v[12:15], v[160:163], v[204:207], v[12:15]
	v_mfma_f32_16x16x32_bf16 v[8:11], v[168:171], v[204:207], v[8:11]
	s_barrier
; #define PG8_STAGE(bufoff, gbase, voff) do { _Pragma("unroll") for (int _i = 0; _i < 2; ++_i) \
;         __builtin_amdgcn_global_load_lds((const unsigned*)((const char*)(gbase) + (voff)[_i]), (LAS unsigned*)(lds + (bufoff) + ldsw + _i * 8192), 16, 0, 0); } while (0)
; #define PG8_LDA(dst, b, h) do { _Pragma("unroll") for (int m = 0; m < 4; ++m) _Pragma("unroll") for (int k = 0; k < 2; ++k) dst[m][k] = *(const LAS bf16x8*)(lds + PG8_SA(b, h) + aoff + m * 2048 + k * 1024); } while (0)
; #define PG8_LDB(dst, b, h) do { _Pragma("unroll") for (int n = 0; n < 2; ++n) _Pragma("unroll") for (int k = 0; k < 2; ++k) dst[n][k] = *(const LAS bf16x8*)(lds + PG8_SB(b, h) + boff + n * 2048 + k * 1024); } while (0)
; #define PG8_MMA(ai, bj, At, Bt) do { __builtin_amdgcn_s_setprio(1); _Pragma("unroll") for (int m = 0; m < 4; ++m) _Pragma("unroll") for (int n = 0; n < 2; ++n) _Pragma("unroll") for (int k = 0; k < 2; ++k) \
;         acc[ai][bj][m][n] = __builtin_amdgcn_mfma_f32_16x16x32_bf16(Bt[n][k], At[m][k], acc[ai][bj][m][n], 0, 0, 0); __builtin_amdgcn_s_setprio(0); } while (0)
; #define PG8_WAIT_V(n) asm volatile("s_waitcnt vmcnt(" #n ")" ::: "memory")
; #define PG8_WAIT_L(n) asm volatile("s_waitcnt lgkmcnt(" #n ")" ::: "memory")
; #define PG8_BAR __builtin_amdgcn_s_barrier()
; #define PG8_SCHED __builtin_amdgcn_sched_barrier(0)
; template <class Epi>
; __device__ __forceinline__ void gemm_phase(LAS unsigned char* lds, const Gemm g, const StaticOrder& S, const Epi& E) {
;     ...
;             PG8_STAGE(PG8_SB(0, 1), b2, voffB1);
;             PG8_WAIT_V(6); PG8_BAR; PG8_MMA(1, 1, At, B1); PG8_BAR;
;             PG8_LDB(B0, 1, 0); PG8_SCHED; PG8_LDA(At, 1, 0); PG8_STAGE(PG8_SA(0, 1), a2 + hstep, voffA);
;             PG8_WAIT_L(8); PG8_BAR; PG8_WAIT_L(0); PG8_MMA(0, 0, At, B0); PG8_BAR; PG8_SCHED;
;             PG8_LDB(B1, 1, 1); PG8_STAGE(PG8_SB(1, 0), b3, voffB0);
;             PG8_BAR; PG8_WAIT_L(0); PG8_MMA(0, 1, At, B1); PG8_BAR;
;             PG8_LDA(At, 1, 1); PG8_STAGE(PG8_SA(1, 0), a3, voffA);
;             PG8_BAR; PG8_WAIT_L(0); PG8_MMA(1, 0, At, B0); PG8_BAR; PG8_SCHED;
	s_add_i32 s33, s73, s62
	v_lshl_add_u64 v[228:229], s[54:55], 0, v[132:133]
	s_mov_b32 m0, s33
	v_lshl_add_u64 v[230:231], s[54:55], 0, v[138:139]
	global_load_lds_dwordx4 v[228:229], off
	s_add_i32 m0, s33, 0x2000
	s_nop 0
	global_load_lds_dwordx4 v[230:231], off
	s_add_i32 s33, 0, 0x18000
	v_add_u32_e32 v168, s33, v153
	ds_read_b128 v[146:149], v168
	ds_read_b128 v[160:163], v168 offset:1024
	ds_read_b128 v[164:167], v168 offset:2048
	ds_read_b128 v[168:171], v168 offset:3072
	s_waitcnt vmcnt(6)
	s_barrier
	v_mfma_f32_16x16x32_bf16 v[52:55], v[208:211], v[172:175], v[52:55]
	v_mfma_f32_16x16x32_bf16 v[48:51], v[216:219], v[172:175], v[48:51]
	v_mfma_f32_16x16x32_bf16 v[36:39], v[208:211], v[180:183], v[36:39]
	v_mfma_f32_16x16x32_bf16 v[32:35], v[216:219], v[180:183], v[32:35]
	v_mfma_f32_16x16x32_bf16 v[20:23], v[208:211], v[188:191], v[20:23]
	v_mfma_f32_16x16x32_bf16 v[16:19], v[216:219], v[188:191], v[16:19]
	v_mfma_f32_16x16x32_bf16 v[4:7], v[208:211], v[196:199], v[4:7]
	v_mfma_f32_16x16x32_bf16 v[0:3], v[216:219], v[196:199], v[0:3]
	v_mfma_f32_16x16x32_bf16 v[52:55], v[212:215], v[176:179], v[52:55]
	v_mfma_f32_16x16x32_bf16 v[48:51], v[220:223], v[176:179], v[48:51]
	v_mfma_f32_16x16x32_bf16 v[36:39], v[212:215], v[184:187], v[36:39]
	v_mfma_f32_16x16x32_bf16 v[32:35], v[220:223], v[184:187], v[32:35]
	v_mfma_f32_16x16x32_bf16 v[20:23], v[212:215], v[192:195], v[20:23]
	v_mfma_f32_16x16x32_bf16 v[16:19], v[220:223], v[192:195], v[16:19]
	v_mfma_f32_16x16x32_bf16 v[4:7], v[212:215], v[204:207], v[4:7]
	v_mfma_f32_16x16x32_bf16 v[0:3], v[220:223], v[204:207], v[0:3]
	s_barrier
	s_add_u32 s52, s52, 0x200000
	s_addc_u32 s53, s53, 0
	s_mov_b32 m0, s64
	v_lshl_add_u64 v[208:209], s[52:53], 0, v[128:129]
	ds_read_b128 v[172:175], v157 offset:32768
	ds_read_b128 v[176:179], v157 offset:33792
	ds_read_b128 v[180:183], v157 offset:34816
	ds_read_b128 v[184:187], v157 offset:35840
	ds_read_b128 v[188:191], v157 offset:36864
	ds_read_b128 v[192:195], v157 offset:37888
	ds_read_b128 v[196:199], v157 offset:38912
	ds_read_b128 v[204:207], v157 offset:39936
	global_load_lds_dwordx4 v[208:209], off
	v_lshl_add_u64 v[208:209], s[52:53], 0, v[134:135]
	s_mov_b32 m0, s65
	s_nop 0
	global_load_lds_dwordx4 v[208:209], off
	s_waitcnt lgkmcnt(8)
	s_barrier
	s_waitcnt lgkmcnt(0)
	v_mfma_f32_16x16x32_bf16 v[124:127], v[146:149], v[172:175], v[124:127]
	v_mfma_f32_16x16x32_bf16 v[120:123], v[164:167], v[172:175], v[120:123]
	v_mfma_f32_16x16x32_bf16 v[108:111], v[146:149], v[180:183], v[108:111]
	v_mfma_f32_16x16x32_bf16 v[104:107], v[164:167], v[180:183], v[104:107]
	v_mfma_f32_16x16x32_bf16 v[92:95], v[146:149], v[188:191], v[92:95]
	v_mfma_f32_16x16x32_bf16 v[88:91], v[164:167], v[188:191], v[88:91]
	v_mfma_f32_16x16x32_bf16 v[76:79], v[146:149], v[196:199], v[76:79]
	v_mfma_f32_16x16x32_bf16 v[72:75], v[164:167], v[196:199], v[72:75]
	v_mfma_f32_16x16x32_bf16 v[124:127], v[160:163], v[176:179], v[124:127]
	v_mfma_f32_16x16x32_bf16 v[120:123], v[168:171], v[176:179], v[120:123]
	v_mfma_f32_16x16x32_bf16 v[108:111], v[160:163], v[184:187], v[108:111]
	v_mfma_f32_16x16x32_bf16 v[104:107], v[168:171], v[184:187], v[104:107]
	v_mfma_f32_16x16x32_bf16 v[92:95], v[160:163], v[192:195], v[92:95]
	v_mfma_f32_16x16x32_bf16 v[88:91], v[168:171], v[192:195], v[88:91]
	v_mfma_f32_16x16x32_bf16 v[76:79], v[160:163], v[204:207], v[76:79]
	v_mfma_f32_16x16x32_bf16 v[72:75], v[168:171], v[204:207], v[72:75]
	s_barrier
	s_add_i32 s52, 0, 0x1c000
	s_add_i32 s33, s33, s62
	v_add_u32_e32 v220, s52, v153
	v_lshl_add_u64 v[150:151], v[150:151], 0, s[18:19]
	s_mov_b32 m0, s33
	ds_read_b128 v[208:211], v220
	ds_read_b128 v[212:215], v220 offset:1024
	ds_read_b128 v[216:219], v220 offset:2048
	ds_read_b128 v[220:223], v220 offset:3072
	global_load_lds_dwordx4 v[150:151], off
	v_lshl_add_u64 v[150:151], v[200:201], 0, s[18:19]
	s_add_i32 m0, s33, 0x2000
	s_nop 0
	global_load_lds_dwordx4 v[150:151], off
	s_barrier
	s_waitcnt lgkmcnt(0)
	v_mfma_f32_16x16x32_bf16 v[116:119], v[208:211], v[172:175], v[116:119]
	v_mfma_f32_16x16x32_bf16 v[112:115], v[216:219], v[172:175], v[112:115]
	v_mfma_f32_16x16x32_bf16 v[100:103], v[208:211], v[180:183], v[100:103]
	v_mfma_f32_16x16x32_bf16 v[96:99], v[216:219], v[180:183], v[96:99]
	v_mfma_f32_16x16x32_bf16 v[84:87], v[208:211], v[188:191], v[84:87]
	v_mfma_f32_16x16x32_bf16 v[80:83], v[216:219], v[188:191], v[80:83]
	v_mfma_f32_16x16x32_bf16 v[68:71], v[208:211], v[196:199], v[68:71]
	v_mfma_f32_16x16x32_bf16 v[64:67], v[216:219], v[196:199], v[64:67]
	v_mfma_f32_16x16x32_bf16 v[116:119], v[212:215], v[176:179], v[116:119]
	v_mfma_f32_16x16x32_bf16 v[112:115], v[220:223], v[176:179], v[112:115]
	v_mfma_f32_16x16x32_bf16 v[100:103], v[212:215], v[184:187], v[100:103]
	v_mfma_f32_16x16x32_bf16 v[96:99], v[220:223], v[184:187], v[96:99]
	v_mfma_f32_16x16x32_bf16 v[84:87], v[212:215], v[192:195], v[84:87]
	v_mfma_f32_16x16x32_bf16 v[80:83], v[220:223], v[192:195], v[80:83]
	v_mfma_f32_16x16x32_bf16 v[68:71], v[212:215], v[204:207], v[68:71]
	v_mfma_f32_16x16x32_bf16 v[64:67], v[220:223], v[204:207], v[64:67]
	s_mov_b32 m0, s67
	v_lshl_add_u64 v[150:151], v[224:225], 0, s[18:19]
	s_barrier
	ds_read_b128 v[172:175], v157 offset:49152
	ds_read_b128 v[176:179], v157 offset:50176
	ds_read_b128 v[180:183], v157 offset:51200
	ds_read_b128 v[184:187], v157 offset:52224
	ds_read_b128 v[188:191], v157 offset:53248
	ds_read_b128 v[192:195], v157 offset:54272
	ds_read_b128 v[196:199], v157 offset:55296
	ds_read_b128 v[204:207], v157 offset:56320
	global_load_lds_dwordx4 v[150:151], off
	v_lshl_add_u64 v[150:151], v[226:227], 0, s[18:19]
	s_mov_b32 m0, s68
	s_nop 0
	global_load_lds_dwordx4 v[150:151], off
	s_barrier
; __device__ __forceinline__ float bflo(unsigned w) { return __uint_as_float(w << 16); }
; __device__ __forceinline__ float bfhi(unsigned w) { return __uint_as_float(w & 0xffff0000u); }
; #define PG8_STAGE(bufoff, gbase, voff) do { _Pragma("unroll") for (int _i = 0; _i < 2; ++_i) \
;         __builtin_amdgcn_global_load_lds((const unsigned*)((const char*)(gbase) + (voff)[_i]), (LAS unsigned*)(lds + (bufoff) + ldsw + _i * 8192), 16, 0, 0); } while (0)
; #define PG8_MMA(ai, bj, At, Bt) do { __builtin_amdgcn_s_setprio(1); _Pragma("unroll") for (int m = 0; m < 4; ++m) _Pragma("unroll") for (int n = 0; n < 2; ++n) _Pragma("unroll") for (int k = 0; k < 2; ++k) \
;         acc[ai][bj][m][n] = __builtin_amdgcn_mfma_f32_16x16x32_bf16(Bt[n][k], At[m][k], acc[ai][bj][m][n], 0, 0, 0); __builtin_amdgcn_s_setprio(0); } while (0)
; #define PG8_WAIT_V(n) asm volatile("s_waitcnt vmcnt(" #n ")" ::: "memory")
; #define PG8_WAIT_L(n) asm volatile("s_waitcnt lgkmcnt(" #n ")" ::: "memory")
; #define PG8_BAR __builtin_amdgcn_s_barrier()
; #define PG8_SCHED __builtin_amdgcn_sched_barrier(0)
;     __device__ __forceinline__ void operator()(const f32x4 (&acc)[2][2][4][2], const Unit& u, int wr, int wc, int fr, int fq) const {
;     ...
;             for (int m = 0; m < 4; ++m) { const int row = row0 + ai * HALF + m * 16; const size_t off = (size_t)row * D + col0; float sq = 0.f; u32x4 w[2];
;                 const float sc = rsin ? __builtin_amdgcn_rcpf(rsin[row] * (1.f / D) + EPS) : 1.0f;
;                 u32x4 rr[2]; if (R) load_pair_lines(R, D, row, fr, col0, rr[0], rr[1]);
; #pragma unroll
;                 for (int bj = 0; bj < 2; ++bj) { f32x4 r0, r1;
;                     if (R) { const u32x4 rw = rr[bj]; r0 = (f32x4){bflo(rw.x), bfhi(rw.x), bflo(rw.y), bfhi(rw.y)}; r1 = (f32x4){bflo(rw.z), bfhi(rw.z), bflo(rw.w), bfhi(rw.w)}; }
; template <class Epi>
; __device__ __forceinline__ void gemm_phase(LAS unsigned char* lds, const Gemm g, const StaticOrder& S, const Epi& E) {
;     ...
;             PG8_BAR; PG8_WAIT_L(0); PG8_MMA(1, 0, At, B0); PG8_BAR; PG8_SCHED;
;             PG8_STAGE(PG8_SB(1, 1), b3, voffB1);
;             PG8_WAIT_V(6); PG8_BAR; PG8_MMA(1, 1, At, B1); PG8_BAR;
;         }
	s_waitcnt lgkmcnt(0)
	v_mfma_f32_16x16x32_bf16 v[60:63], v[146:149], v[172:175], v[60:63]
	v_mfma_f32_16x16x32_bf16 v[56:59], v[164:167], v[172:175], v[56:59]
	v_mfma_f32_16x16x32_bf16 v[44:47], v[146:149], v[180:183], v[44:47]
	v_mfma_f32_16x16x32_bf16 v[40:43], v[164:167], v[180:183], v[40:43]
	v_mfma_f32_16x16x32_bf16 v[28:31], v[146:149], v[188:191], v[28:31]
	v_mfma_f32_16x16x32_bf16 v[24:27], v[164:167], v[188:191], v[24:27]
	v_mfma_f32_16x16x32_bf16 v[12:15], v[146:149], v[196:199], v[12:15]
	v_mfma_f32_16x16x32_bf16 v[8:11], v[164:167], v[196:199], v[8:11]
	v_mfma_f32_16x16x32_bf16 v[60:63], v[160:163], v[176:179], v[60:63]
	v_mfma_f32_16x16x32_bf16 v[56:59], v[168:171], v[176:179], v[56:59]
	v_mfma_f32_16x16x32_bf16 v[44:47], v[160:163], v[184:187], v[44:47]
	v_mfma_f32_16x16x32_bf16 v[40:43], v[168:171], v[184:187], v[40:43]
	v_mfma_f32_16x16x32_bf16 v[28:31], v[160:163], v[192:195], v[28:31]
	v_mfma_f32_16x16x32_bf16 v[24:27], v[168:171], v[192:195], v[24:27]
	v_mfma_f32_16x16x32_bf16 v[12:15], v[160:163], v[204:207], v[12:15]
	v_mfma_f32_16x16x32_bf16 v[8:11], v[168:171], v[204:207], v[8:11]
	s_barrier
	s_add_i32 s33, s52, s62
	v_lshl_add_u64 v[146:147], v[228:229], 0, s[18:19]
	s_mov_b32 m0, s33
	s_nop 0
	global_load_lds_dwordx4 v[146:147], off
	v_lshl_add_u64 v[146:147], v[230:231], 0, s[18:19]
	s_add_i32 m0, s33, 0x2000
	s_nop 0
	global_load_lds_dwordx4 v[146:147], off
	s_waitcnt vmcnt(6)
	s_barrier
	v_mfma_f32_16x16x32_bf16 v[52:55], v[208:211], v[172:175], v[52:55]
	v_mfma_f32_16x16x32_bf16 v[48:51], v[216:219], v[172:175], v[48:51]
	v_mfma_f32_16x16x32_bf16 v[36:39], v[208:211], v[180:183], v[36:39]
	v_mfma_f32_16x16x32_bf16 v[32:35], v[216:219], v[180:183], v[32:35]
	v_mfma_f32_16x16x32_bf16 v[20:23], v[208:211], v[188:191], v[20:23]
	v_mfma_f32_16x16x32_bf16 v[16:19], v[216:219], v[188:191], v[16:19]
	v_mfma_f32_16x16x32_bf16 v[4:7], v[208:211], v[196:199], v[4:7]
	v_mfma_f32_16x16x32_bf16 v[0:3], v[216:219], v[196:199], v[0:3]
	v_mfma_f32_16x16x32_bf16 v[52:55], v[212:215], v[176:179], v[52:55]
	v_mfma_f32_16x16x32_bf16 v[48:51], v[220:223], v[176:179], v[48:51]
	v_mfma_f32_16x16x32_bf16 v[36:39], v[212:215], v[184:187], v[36:39]
	v_mfma_f32_16x16x32_bf16 v[32:35], v[220:223], v[184:187], v[32:35]
	v_mfma_f32_16x16x32_bf16 v[20:23], v[212:215], v[192:195], v[20:23]
	v_mfma_f32_16x16x32_bf16 v[16:19], v[220:223], v[192:195], v[16:19]
	v_mfma_f32_16x16x32_bf16 v[4:7], v[212:215], v[204:207], v[4:7]
	v_mfma_f32_16x16x32_bf16 v[0:3], v[220:223], v[204:207], v[0:3]
	s_add_i32 s80, s80, 2
	s_add_u32 s50, s50, 0x100
	s_addc_u32 s51, s51, 0
	s_add_u32 s78, s78, 0x100
	s_addc_u32 s79, s79, 0
	s_cmpk_gt_u32 s80, 0x7d
	s_barrier
	s_cbranch_scc0 .LBB0_806
	s_lshl_b32 s33, s48, 8
	s_add_i32 s33, s33, s69
	v_or_b32_e32 v164, s33, v154
	v_ashrrev_i32_e32 v165, 31, v164
	v_lshl_or_b32 v146, s74, 8, v155
	v_lshlrev_b64 v[168:169], 12, v[164:165]
	v_or_b32_e32 v164, 8, v164
	v_or_b32_e32 v150, s33, v152
	v_ashrrev_i32_e32 v147, 31, v146
	v_ashrrev_i32_e32 v165, 31, v164
	v_ashrrev_i32_e32 v151, 31, v150
	v_lshl_add_u64 v[160:161], s[16:17], 0, v[168:169]
	v_lshlrev_b64 v[146:147], 1, v[146:147]
	v_lshlrev_b64 v[170:171], 12, v[164:165]
	v_lshl_add_u64 v[148:149], v[150:151], 2, s[10:11]
	v_lshl_add_u64 v[160:161], v[160:161], 0, v[146:147]
	v_lshl_add_u64 v[164:165], s[16:17], 0, v[170:171]
	s_waitcnt vmcnt(8)
	s_nop 0
	v_mov_b32_e32 v151, v232
	s_nop 1
	s_nop 0
	s_nop 0
	v_mov_b64_e32 v[160:161], v[236:237]
	v_mov_b64_e32 v[162:163], v[238:239]
	s_nop 1
	v_lshl_add_u64 v[164:165], v[164:165], 0, v[146:147]
	s_nop 0
	v_mov_b64_e32 v[164:165], v[240:241]
	v_mov_b64_e32 v[166:167], v[242:243]
	s_nop 1
	v_or_b32_e32 v190, 16, v150
	v_ashrrev_i32_e32 v191, 31, v190
	v_lshl_add_u64 v[192:193], v[190:191], 2, s[10:11]
	v_sub_u32_e32 v190, v190, v152
	v_add_u32_e32 v190, v190, v154
	v_ashrrev_i32_e32 v191, 31, v190
	v_lshlrev_b64 v[196:197], 12, v[190:191]
	v_lshl_add_u64 v[190:191], s[16:17], 0, v[196:197]
	v_lshl_add_u64 v[198:199], v[196:197], 0, s[36:37]
	v_lshl_add_u64 v[190:191], v[190:191], 0, v[146:147]
	v_lshl_add_u64 v[194:195], s[16:17], 0, v[198:199]
	global_load_dword v204, v[192:193], off
	global_load_dwordx4 v[208:211], v[190:191], off
	v_lshl_add_u64 v[194:195], v[194:195], 0, v[146:147]
	global_load_dwordx4 v[212:215], v[194:195], off
	v_or_b32_e32 v190, 32, v150
	v_ashrrev_i32_e32 v191, 31, v190
	v_lshl_add_u64 v[192:193], v[190:191], 2, s[10:11]
	v_sub_u32_e32 v190, v190, v152
	v_add_u32_e32 v190, v190, v154
	v_ashrrev_i32_e32 v191, 31, v190
	v_lshlrev_b64 v[196:197], 12, v[190:191]
	v_lshl_add_u64 v[190:191], s[16:17], 0, v[196:197]
	v_lshl_add_u64 v[198:199], v[196:197], 0, s[36:37]
	v_lshl_add_u64 v[190:191], v[190:191], 0, v[146:147]
	v_lshl_add_u64 v[194:195], s[16:17], 0, v[198:199]
	global_load_dword v205, v[192:193], off
	global_load_dwordx4 v[216:219], v[190:191], off
	v_lshl_add_u64 v[194:195], v[194:195], 0, v[146:147]
	global_load_dwordx4 v[220:223], v[194:195], off
	v_or_b32_e32 v190, 48, v150
	v_ashrrev_i32_e32 v191, 31, v190
	v_lshl_add_u64 v[192:193], v[190:191], 2, s[10:11]
	v_sub_u32_e32 v190, v190, v152
	v_add_u32_e32 v190, v190, v154
	v_ashrrev_i32_e32 v191, 31, v190
	v_lshlrev_b64 v[196:197], 12, v[190:191]
	v_lshl_add_u64 v[190:191], s[16:17], 0, v[196:197]
	v_lshl_add_u64 v[198:199], v[196:197], 0, s[36:37]
	v_lshl_add_u64 v[190:191], v[190:191], 0, v[146:147]
	v_lshl_add_u64 v[194:195], s[16:17], 0, v[198:199]
	global_load_dword v206, v[192:193], off
	global_load_dwordx4 v[224:227], v[190:191], off
	v_lshl_add_u64 v[194:195], v[194:195], 0, v[146:147]
	global_load_dwordx4 v[228:231], v[194:195], off
; __device__ __forceinline__ unsigned cvt_pk_bf16(float lo, float hi) { unsigned r; asm volatile("v_cvt_pk_bf16_f32 %0, %1, %2" : "=v"(r) : "v"(lo), "v"(hi)); return r; }
; __device__ __forceinline__ float bflo(unsigned w) { return __uint_as_float(w << 16); }
; __device__ __forceinline__ float bfhi(unsigned w) { return __uint_as_float(w & 0xffff0000u); }
;     __device__ __forceinline__ void operator()(const f32x4 (&acc)[2][2][4][2], const Unit& u, int wr, int wc, int fr, int fq) const {
;     ...
;             for (int m = 0; m < 4; ++m) { const int row = row0 + ai * HALF + m * 16; const size_t off = (size_t)row * D + col0; float sq = 0.f; u32x4 w[2];
;                 const float sc = rsin ? __builtin_amdgcn_rcpf(rsin[row] * (1.f / D) + EPS) : 1.0f;
;                 u32x4 rr[2]; if (R) load_pair_lines(R, D, row, fr, col0, rr[0], rr[1]);
; #pragma unroll
;                 for (int bj = 0; bj < 2; ++bj) { f32x4 r0, r1;
;                     if (R) { const u32x4 rw = rr[bj]; r0 = (f32x4){bflo(rw.x), bfhi(rw.x), bflo(rw.y), bfhi(rw.y)}; r1 = (f32x4){bflo(rw.z), bfhi(rw.z), bflo(rw.w), bfhi(rw.w)}; }
;                     else { const float* rp = (row < 8192 ? src_p + off : src_s + (off - (size_t)8192 * D)) + 8 * bj; r0 = *(const f32x4*)rp; r1 = *(const f32x4*)(rp + 4); }
;                     const f32x4 o0 = r0 + acc[ai][bj][m][0] * sc, o1 = r1 + acc[ai][bj][m][1] * sc;
;                     sq += (o0[0] * o0[0] + o0[1] * o0[1]) + (o0[2] * o0[2] + o0[3] * o0[3]) + (o1[0] * o1[0] + o1[1] * o1[1]) + (o1[2] * o1[2] + o1[3] * o1[3]);
;                     w[bj].x = cvt_pk_bf16(o0[0], o0[1]); w[bj].y = cvt_pk_bf16(o0[2], o0[3]); w[bj].z = cvt_pk_bf16(o1[0], o1[1]); w[bj].w = cvt_pk_bf16(o1[2], o1[3]); }
;                 store_pair_lines(O, D, row, fr, col0, w[0], w[1]);
	v_sub_u32_e32 v190, v150, v152
	v_add_u32_e32 v199, v190, v154
	v_add_u32_e32 v190, 0x80, v199
	v_ashrrev_i32_e32 v191, 31, v190
	v_lshlrev_b64 v[194:195], 12, v[190:191]
	v_lshl_add_u64 v[190:191], s[16:17], 0, v[194:195]
	v_lshl_add_u64 v[196:197], v[194:195], 0, s[36:37]
	v_lshl_add_u64 v[190:191], v[190:191], 0, v[146:147]
	v_lshl_add_u64 v[192:193], s[16:17], 0, v[196:197]
	global_load_dword v207, v[148:149], off offset:512
	global_load_dwordx4 v[232:235], v[190:191], off
	v_lshl_add_u64 v[192:193], v[192:193], 0, v[146:147]
	global_load_dwordx4 v[236:239], v[192:193], off
	v_sub_u32_e32 v198, v150, v152
	v_add_u32_e32 v201, v198, v154
	v_add_u32_e32 v190, 0x90, v201
	v_ashrrev_i32_e32 v191, 31, v190
	v_lshlrev_b64 v[194:195], 12, v[190:191]
	v_lshl_add_u64 v[190:191], s[16:17], 0, v[194:195]
	v_lshl_add_u64 v[196:197], v[194:195], 0, s[36:37]
	v_lshl_add_u64 v[190:191], v[190:191], 0, v[146:147]
	v_lshl_add_u64 v[192:193], s[16:17], 0, v[196:197]
	global_load_dword v240, v[148:149], off offset:576
	global_load_dwordx4 v[244:247], v[190:191], off
	v_lshl_add_u64 v[192:193], v[192:193], 0, v[146:147]
	global_load_dwordx4 v[248:251], v[192:193], off
	s_and_b64 vcc, exec, s[44:45]
	s_mov_b32 s74, s38
	s_mov_b32 s48, s40
	s_mov_b64 s[52:53], s[46:47]
	s_mov_b64 s[50:51], s[42:43]
	v_fmamk_f32 v151, v151, 0x3a000000, v159
	v_rcp_f32_e32 v172, v151
	v_mov_b32_dpp v173, v160 row_ror:8 row_mask:0xf bank_mask:0xf
	v_mov_b32_dpp v174, v161 row_ror:8 row_mask:0xf bank_mask:0xf
	v_mov_b32_dpp v175, v162 row_ror:8 row_mask:0xf bank_mask:0xf
	v_mov_b32_dpp v177, v164 row_ror:8 row_mask:0xf bank_mask:0xf
	v_mov_b32_dpp v178, v165 row_ror:8 row_mask:0xf bank_mask:0xf
	v_mov_b32_dpp v179, v166 row_ror:8 row_mask:0xf bank_mask:0xf
	v_mov_b32_dpp v176, v163 row_ror:8 row_mask:0xf bank_mask:0xf
	v_mov_b32_dpp v180, v167 row_ror:8 row_mask:0xf bank_mask:0xf
	v_cndmask_b32_e64 v166, v166, v175, s[6:7]
	v_cndmask_b32_e64 v165, v165, v174, s[6:7]
	v_cndmask_b32_e64 v164, v164, v173, s[6:7]
	v_cndmask_b32_e64 v179, v179, v162, s[6:7]
	v_cndmask_b32_e64 v178, v178, v161, s[6:7]
	v_cndmask_b32_e64 v175, v177, v160, s[6:7]
	v_cndmask_b32_e64 v151, v167, v176, s[6:7]
	v_cndmask_b32_e64 v173, v180, v163, s[6:7]
	v_lshlrev_b32_e32 v160, 16, v164
	v_and_b32_e32 v161, 0xffff0000, v164
	v_lshlrev_b32_e32 v162, 16, v165
	v_and_b32_e32 v163, 0xffff0000, v165
	v_lshlrev_b32_e32 v174, 16, v175
	v_and_b32_e32 v175, 0xffff0000, v175
	v_lshlrev_b32_e32 v176, 16, v178
	v_and_b32_e32 v177, 0xffff0000, v178
	v_lshlrev_b32_e32 v178, 16, v179
	v_and_b32_e32 v179, 0xffff0000, v179
	v_lshlrev_b32_e32 v164, 16, v166
	v_and_b32_e32 v165, 0xffff0000, v166
	v_lshlrev_b32_e32 v166, 16, v151
	v_and_b32_e32 v167, 0xffff0000, v151
	v_lshlrev_b32_e32 v180, 16, v173
	v_and_b32_e32 v181, 0xffff0000, v173
	v_pk_fma_f32 v[118:119], v[118:119], v[172:173], v[162:163] op_sel_hi:[1,0,1]
	v_pk_fma_f32 v[116:117], v[116:117], v[172:173], v[160:161] op_sel_hi:[1,0,1]
	v_pk_fma_f32 v[124:125], v[124:125], v[172:173], v[174:175] op_sel_hi:[1,0,1]
	v_pk_fma_f32 v[120:121], v[120:121], v[172:173], v[178:179] op_sel_hi:[1,0,1]
	v_pk_fma_f32 v[114:115], v[114:115], v[172:173], v[166:167] op_sel_hi:[1,0,1]
	v_pk_fma_f32 v[112:113], v[112:113], v[172:173], v[164:165] op_sel_hi:[1,0,1]
	v_pk_fma_f32 v[126:127], v[126:127], v[172:173], v[176:177] op_sel_hi:[1,0,1]
	v_pk_fma_f32 v[122:123], v[122:123], v[172:173], v[180:181] op_sel_hi:[1,0,1]
	v_cvt_pk_bf16_f32 v124, v124, v125
	v_cvt_pk_bf16_f32 v125, v126, v127
	v_cvt_pk_bf16_f32 v120, v120, v121
	v_cvt_pk_bf16_f32 v121, v122, v123
	v_cvt_pk_bf16_f32 v116, v116, v117
	v_cvt_pk_bf16_f32 v117, v118, v119
	v_cvt_pk_bf16_f32 v118, v112, v113
	v_cvt_pk_bf16_f32 v119, v114, v115
	s_nop 0
	v_mov_b32_dpp v184, v120 row_ror:8 row_mask:0xf bank_mask:0xf
	v_mov_b32_dpp v185, v121 row_ror:8 row_mask:0xf bank_mask:0xf
	v_mov_b32_dpp v188, v118 row_ror:8 row_mask:0xf bank_mask:0xf
	v_mov_b32_dpp v189, v119 row_ror:8 row_mask:0xf bank_mask:0xf
	v_mov_b32_dpp v186, v116 row_ror:8 row_mask:0xf bank_mask:0xf
	v_mov_b32_dpp v187, v117 row_ror:8 row_mask:0xf bank_mask:0xf
	v_cndmask_b32_e64 v114, v188, v120, s[6:7]
	v_cndmask_b32_e64 v115, v189, v121, s[6:7]
	v_lshl_add_u64 v[120:121], s[8:9], 0, v[168:169]
	v_cndmask_b32_e64 v112, v186, v124, s[6:7]
	v_cndmask_b32_e64 v113, v187, v125, s[6:7]
	v_lshl_add_u64 v[120:121], v[120:121], 0, v[146:147]
	v_mov_b32_dpp v182, v124 row_ror:8 row_mask:0xf bank_mask:0xf
	v_mov_b32_dpp v183, v125 row_ror:8 row_mask:0xf bank_mask:0xf
	global_store_dwordx4 v[120:121], v[112:115], off
	v_cndmask_b32_e64 v116, v116, v182, s[6:7]
	v_cndmask_b32_e64 v117, v117, v183, s[6:7]
	v_lshl_add_u64 v[112:113], s[8:9], 0, v[170:171]
	v_cndmask_b32_e64 v118, v118, v184, s[6:7]
	v_cndmask_b32_e64 v119, v119, v185, s[6:7]
	v_lshl_add_u64 v[112:113], v[112:113], 0, v[146:147]
	global_store_dwordx4 v[112:113], v[116:119], off
	v_or_b32_e32 v112, 16, v150
	v_ashrrev_i32_e32 v113, 31, v112
	v_lshl_add_u64 v[114:115], v[112:113], 2, s[10:11]
	v_sub_u32_e32 v112, v112, v152
	v_add_u32_e32 v112, v112, v154
	v_ashrrev_i32_e32 v113, 31, v112
	v_lshlrev_b64 v[120:121], 12, v[112:113]
	v_lshl_add_u64 v[112:113], s[16:17], 0, v[120:121]
	v_lshl_add_u64 v[122:123], v[120:121], 0, s[36:37]
	v_lshl_add_u64 v[112:113], v[112:113], 0, v[146:147]
	v_lshl_add_u64 v[116:117], s[16:17], 0, v[122:123]
	s_waitcnt vmcnt(14)
; __device__ __forceinline__ unsigned cvt_pk_bf16(float lo, float hi) { unsigned r; asm volatile("v_cvt_pk_bf16_f32 %0, %1, %2" : "=v"(r) : "v"(lo), "v"(hi)); return r; }
; __device__ __forceinline__ float bflo(unsigned w) { return __uint_as_float(w << 16); }
; __device__ __forceinline__ float bfhi(unsigned w) { return __uint_as_float(w & 0xffff0000u); }
;     __device__ __forceinline__ void operator()(const f32x4 (&acc)[2][2][4][2], const Unit& u, int wr, int wc, int fr, int fq) const {
;     ...
;             for (int m = 0; m < 4; ++m) { const int row = row0 + ai * HALF + m * 16; const size_t off = (size_t)row * D + col0; float sq = 0.f; u32x4 w[2];
;                 const float sc = rsin ? __builtin_amdgcn_rcpf(rsin[row] * (1.f / D) + EPS) : 1.0f;
;                 u32x4 rr[2]; if (R) load_pair_lines(R, D, row, fr, col0, rr[0], rr[1]);
; #pragma unroll
;                 for (int bj = 0; bj < 2; ++bj) { f32x4 r0, r1;
;                     if (R) { const u32x4 rw = rr[bj]; r0 = (f32x4){bflo(rw.x), bfhi(rw.x), bflo(rw.y), bfhi(rw.y)}; r1 = (f32x4){bflo(rw.z), bfhi(rw.z), bflo(rw.w), bfhi(rw.w)}; }
;                     else { const float* rp = (row < 8192 ? src_p + off : src_s + (off - (size_t)8192 * D)) + 8 * bj; r0 = *(const f32x4*)rp; r1 = *(const f32x4*)(rp + 4); }
;                     const f32x4 o0 = r0 + acc[ai][bj][m][0] * sc, o1 = r1 + acc[ai][bj][m][1] * sc;
;                     sq += (o0[0] * o0[0] + o0[1] * o0[1]) + (o0[2] * o0[2] + o0[3] * o0[3]) + (o1[0] * o1[0] + o1[1] * o1[1]) + (o1[2] * o1[2] + o1[3] * o1[3]);
;                     w[bj].x = cvt_pk_bf16(o0[0], o0[1]); w[bj].y = cvt_pk_bf16(o0[2], o0[3]); w[bj].z = cvt_pk_bf16(o1[0], o1[1]); w[bj].w = cvt_pk_bf16(o1[2], o1[3]); }
;                 store_pair_lines(O, D, row, fr, col0, w[0], w[1]);
	s_nop 0
	v_mov_b32_e32 v124, v204
	s_nop 0
	v_mov_b64_e32 v[112:113], v[208:209]
	v_mov_b64_e32 v[114:115], v[210:211]
	v_lshl_add_u64 v[116:117], v[116:117], 0, v[146:147]
	v_mov_b64_e32 v[116:117], v[212:213]
	v_mov_b64_e32 v[118:119], v[214:215]
	s_nop 1
	v_sub_u32_e32 v198, v150, v152
	v_add_u32_e32 v201, v198, v154
	v_add_u32_e32 v190, 0xa0, v201
	v_ashrrev_i32_e32 v191, 31, v190
	v_lshlrev_b64 v[194:195], 12, v[190:191]
	v_lshl_add_u64 v[196:197], v[194:195], 0, s[36:37]
	global_load_dword v204, v[148:149], off offset:640
	v_lshl_add_u64 v[190:191], s[16:17], 0, v[194:195]
	v_lshl_add_u64 v[192:193], s[16:17], 0, v[196:197]
	v_lshl_add_u64 v[190:191], v[190:191], 0, v[146:147]
	v_lshl_add_u64 v[192:193], v[192:193], 0, v[146:147]
	global_load_dwordx4 v[208:211], v[190:191], off
	global_load_dwordx4 v[212:215], v[192:193], off
	v_fmamk_f32 v124, v124, 0x3a000000, v159
	v_rcp_f32_e32 v124, v124
	v_mov_b32_dpp v125, v112 row_ror:8 row_mask:0xf bank_mask:0xf
	v_mov_b32_dpp v126, v113 row_ror:8 row_mask:0xf bank_mask:0xf
	v_mov_b32_dpp v127, v114 row_ror:8 row_mask:0xf bank_mask:0xf
	v_mov_b32_dpp v151, v115 row_ror:8 row_mask:0xf bank_mask:0xf
	v_mov_b32_dpp v160, v116 row_ror:8 row_mask:0xf bank_mask:0xf
	v_mov_b32_dpp v161, v117 row_ror:8 row_mask:0xf bank_mask:0xf
	v_mov_b32_dpp v162, v118 row_ror:8 row_mask:0xf bank_mask:0xf
	v_mov_b32_dpp v163, v119 row_ror:8 row_mask:0xf bank_mask:0xf
	v_cndmask_b32_e64 v163, v163, v115, s[6:7]
	v_cndmask_b32_e64 v162, v162, v114, s[6:7]
	v_cndmask_b32_e64 v115, v161, v113, s[6:7]
	v_cndmask_b32_e64 v113, v160, v112, s[6:7]
	v_cndmask_b32_e64 v151, v119, v151, s[6:7]
	v_cndmask_b32_e64 v164, v118, v127, s[6:7]
	v_cndmask_b32_e64 v161, v117, v126, s[6:7]
	v_cndmask_b32_e64 v125, v116, v125, s[6:7]
	v_lshlrev_b32_e32 v112, 16, v113
	v_and_b32_e32 v113, 0xffff0000, v113
	v_lshlrev_b32_e32 v116, 16, v162
	v_and_b32_e32 v117, 0xffff0000, v162
	v_lshlrev_b32_e32 v118, 16, v163
	v_and_b32_e32 v119, 0xffff0000, v163
	v_lshlrev_b32_e32 v126, 16, v125
	v_and_b32_e32 v127, 0xffff0000, v125
	v_lshlrev_b32_e32 v160, 16, v161
	v_and_b32_e32 v161, 0xffff0000, v161
	v_lshlrev_b32_e32 v162, 16, v164
	v_and_b32_e32 v163, 0xffff0000, v164
	v_lshlrev_b32_e32 v164, 16, v151
	v_and_b32_e32 v165, 0xffff0000, v151
	v_lshlrev_b32_e32 v114, 16, v115
	v_and_b32_e32 v115, 0xffff0000, v115
	v_pk_fma_f32 v[108:109], v[108:109], v[124:125], v[112:113] op_sel_hi:[1,0,1]
	v_pk_fma_f32 v[104:105], v[104:105], v[124:125], v[116:117] op_sel_hi:[1,0,1]
	v_pk_fma_f32 v[102:103], v[102:103], v[124:125], v[160:161] op_sel_hi:[1,0,1]
	v_pk_fma_f32 v[100:101], v[100:101], v[124:125], v[126:127] op_sel_hi:[1,0,1]
	v_pk_fma_f32 v[98:99], v[98:99], v[124:125], v[164:165] op_sel_hi:[1,0,1]
	v_pk_fma_f32 v[110:111], v[110:111], v[124:125], v[114:115] op_sel_hi:[1,0,1]
	v_pk_fma_f32 v[106:107], v[106:107], v[124:125], v[118:119] op_sel_hi:[1,0,1]
	v_pk_fma_f32 v[96:97], v[96:97], v[124:125], v[162:163] op_sel_hi:[1,0,1]
	v_cvt_pk_bf16_f32 v108, v108, v109
	v_cvt_pk_bf16_f32 v109, v110, v111
	v_cvt_pk_bf16_f32 v104, v104, v105
	v_cvt_pk_bf16_f32 v105, v106, v107
	v_cvt_pk_bf16_f32 v100, v100, v101
	v_cvt_pk_bf16_f32 v101, v102, v103
	s_nop 0
	v_cvt_pk_bf16_f32 v102, v96, v97
	v_cvt_pk_bf16_f32 v103, v98, v99
	v_mov_b32_e32 v98, 0
	v_mov_b32_dpp v98, v102 row_ror:8 row_mask:0xf bank_mask:0xf
	v_mov_b32_dpp v99, v103 row_ror:8 row_mask:0xf bank_mask:0xf
	v_mov_b32_dpp v107, v104 row_ror:8 row_mask:0xf bank_mask:0xf
	v_mov_b32_dpp v110, v105 row_ror:8 row_mask:0xf bank_mask:0xf
	v_mov_b32_dpp v96, v100 row_ror:8 row_mask:0xf bank_mask:0xf
	v_mov_b32_dpp v97, v101 row_ror:8 row_mask:0xf bank_mask:0xf
	v_cndmask_b32_e64 v98, v98, v104, s[6:7]
	v_cndmask_b32_e64 v99, v99, v105, s[6:7]
	v_lshl_add_u64 v[104:105], s[8:9], 0, v[120:121]
	v_cndmask_b32_e64 v96, v96, v108, s[6:7]
	v_cndmask_b32_e64 v97, v97, v109, s[6:7]
	v_lshl_add_u64 v[104:105], v[104:105], 0, v[146:147]
	v_mov_b32_dpp v166, v108 row_ror:8 row_mask:0xf bank_mask:0xf
	v_mov_b32_dpp v106, v109 row_ror:8 row_mask:0xf bank_mask:0xf
	global_store_dwordx4 v[104:105], v[96:99], off
	v_cndmask_b32_e64 v100, v100, v166, s[6:7]
	v_cndmask_b32_e64 v101, v101, v106, s[6:7]
	v_lshl_add_u64 v[96:97], s[8:9], 0, v[122:123]
	v_cndmask_b32_e64 v102, v102, v107, s[6:7]
	v_cndmask_b32_e64 v103, v103, v110, s[6:7]
	v_lshl_add_u64 v[96:97], v[96:97], 0, v[146:147]
	global_store_dwordx4 v[96:97], v[100:103], off
	v_or_b32_e32 v96, 32, v150
	v_ashrrev_i32_e32 v97, 31, v96
	v_lshl_add_u64 v[98:99], v[96:97], 2, s[10:11]
	v_sub_u32_e32 v96, v96, v152
	v_add_u32_e32 v96, v96, v154
	v_ashrrev_i32_e32 v97, 31, v96
	v_lshlrev_b64 v[104:105], 12, v[96:97]
	v_lshl_add_u64 v[96:97], s[16:17], 0, v[104:105]
	v_lshl_add_u64 v[106:107], v[104:105], 0, s[36:37]
	v_lshl_add_u64 v[96:97], v[96:97], 0, v[146:147]
	v_lshl_add_u64 v[100:101], s[16:17], 0, v[106:107]
	s_waitcnt vmcnt(16)
; __device__ __forceinline__ unsigned cvt_pk_bf16(float lo, float hi) { unsigned r; asm volatile("v_cvt_pk_bf16_f32 %0, %1, %2" : "=v"(r) : "v"(lo), "v"(hi)); return r; }
; __device__ __forceinline__ float bflo(unsigned w) { return __uint_as_float(w << 16); }
; __device__ __forceinline__ float bfhi(unsigned w) { return __uint_as_float(w & 0xffff0000u); }
;     const bool lo = fr < 8;
;     const int r1 = row - fr + (fr & 7), cb = col0 + (lo ? 0 : boff);
;     const u32x4 l1 = *(const u32x4*)(P + (size_t)r1 * ld + cb), l2 = *(const u32x4*)(P + (size_t)(r1 + 8) * ld + cb);
;     const u32x4 s1 = {dpp_ror8(l1.x), dpp_ror8(l1.y), dpp_ror8(l1.z), dpp_ror8(l1.w)}, s2 = {dpp_ror8(l2.x), dpp_ror8(l2.y), dpp_ror8(l2.z), dpp_ror8(l2.w)};
;     wA = lo ? l1 : s2; wB = lo ? s1 : l2;
;     __device__ __forceinline__ void operator()(const f32x4 (&acc)[2][2][4][2], const Unit& u, int wr, int wc, int fr, int fq) const {
;     ...
;             for (int m = 0; m < 4; ++m) { const int row = row0 + ai * HALF + m * 16; const size_t off = (size_t)row * D + col0; float sq = 0.f; u32x4 w[2];
;                 const float sc = rsin ? __builtin_amdgcn_rcpf(rsin[row] * (1.f / D) + EPS) : 1.0f;
;                 u32x4 rr[2]; if (R) load_pair_lines(R, D, row, fr, col0, rr[0], rr[1]);
; #pragma unroll
;                 for (int bj = 0; bj < 2; ++bj) { f32x4 r0, r1;
;                     if (R) { const u32x4 rw = rr[bj]; r0 = (f32x4){bflo(rw.x), bfhi(rw.x), bflo(rw.y), bfhi(rw.y)}; r1 = (f32x4){bflo(rw.z), bfhi(rw.z), bflo(rw.w), bfhi(rw.w)}; }
;                     else { const float* rp = (row < 8192 ? src_p + off : src_s + (off - (size_t)8192 * D)) + 8 * bj; r0 = *(const f32x4*)rp; r1 = *(const f32x4*)(rp + 4); }
;                     const f32x4 o0 = r0 + acc[ai][bj][m][0] * sc, o1 = r1 + acc[ai][bj][m][1] * sc;
;                     sq += (o0[0] * o0[0] + o0[1] * o0[1]) + (o0[2] * o0[2] + o0[3] * o0[3]) + (o1[0] * o1[0] + o1[1] * o1[1]) + (o1[2] * o1[2] + o1[3] * o1[3]);
;                     w[bj].x = cvt_pk_bf16(o0[0], o0[1]); w[bj].y = cvt_pk_bf16(o0[2], o0[3]); w[bj].z = cvt_pk_bf16(o1[0], o1[1]); w[bj].w = cvt_pk_bf16(o1[2], o1[3]); }
;                 store_pair_lines(O, D, row, fr, col0, w[0], w[1]);
;                 if (ssout) { sq += __shfl_xor(sq, 16); sq += __shfl_xor(sq, 32); if (fq == 0) unsafeAtomicAdd(ssout + row, sq); } }
	s_nop 0
	v_mov_b32_e32 v108, v205
	s_nop 0
	v_mov_b64_e32 v[96:97], v[216:217]
	v_mov_b64_e32 v[98:99], v[218:219]
	v_lshl_add_u64 v[100:101], v[100:101], 0, v[146:147]
	v_mov_b64_e32 v[100:101], v[220:221]
	v_mov_b64_e32 v[102:103], v[222:223]
	s_nop 1
	v_sub_u32_e32 v198, v150, v152
	v_add_u32_e32 v201, v198, v154
	v_add_u32_e32 v190, 0xb0, v201
	v_ashrrev_i32_e32 v191, 31, v190
	v_lshlrev_b64 v[194:195], 12, v[190:191]
	v_lshl_add_u64 v[196:197], v[194:195], 0, s[36:37]
	global_load_dword v205, v[148:149], off offset:704
	v_lshl_add_u64 v[190:191], s[16:17], 0, v[194:195]
	v_lshl_add_u64 v[192:193], s[16:17], 0, v[196:197]
	v_lshl_add_u64 v[190:191], v[190:191], 0, v[146:147]
	v_lshl_add_u64 v[192:193], v[192:193], 0, v[146:147]
	global_load_dwordx4 v[216:219], v[190:191], off
	global_load_dwordx4 v[220:223], v[192:193], off
	v_fmamk_f32 v108, v108, 0x3a000000, v159
	v_rcp_f32_e32 v108, v108
	v_mov_b32_dpp v109, v96 row_ror:8 row_mask:0xf bank_mask:0xf
	v_mov_b32_dpp v113, v100 row_ror:8 row_mask:0xf bank_mask:0xf
	v_mov_b32_dpp v114, v101 row_ror:8 row_mask:0xf bank_mask:0xf
	v_mov_b32_dpp v115, v102 row_ror:8 row_mask:0xf bank_mask:0xf
	v_mov_b32_dpp v116, v103 row_ror:8 row_mask:0xf bank_mask:0xf
	v_mov_b32_dpp v110, v97 row_ror:8 row_mask:0xf bank_mask:0xf
	v_mov_b32_dpp v111, v98 row_ror:8 row_mask:0xf bank_mask:0xf
	v_mov_b32_dpp v112, v99 row_ror:8 row_mask:0xf bank_mask:0xf
	v_cndmask_b32_e64 v116, v116, v99, s[6:7]
	v_cndmask_b32_e64 v115, v115, v98, s[6:7]
	v_cndmask_b32_e64 v99, v114, v97, s[6:7]
	v_cndmask_b32_e64 v97, v113, v96, s[6:7]
	v_cndmask_b32_e64 v114, v103, v112, s[6:7]
	v_cndmask_b32_e64 v117, v102, v111, s[6:7]
	v_cndmask_b32_e64 v113, v101, v110, s[6:7]
	v_cndmask_b32_e64 v109, v100, v109, s[6:7]
	v_lshlrev_b32_e32 v96, 16, v97
	v_and_b32_e32 v97, 0xffff0000, v97
	v_lshlrev_b32_e32 v98, 16, v99
	v_and_b32_e32 v99, 0xffff0000, v99
	v_lshlrev_b32_e32 v100, 16, v115
	v_and_b32_e32 v101, 0xffff0000, v115
	v_lshlrev_b32_e32 v102, 16, v116
	v_and_b32_e32 v103, 0xffff0000, v116
	v_pk_fma_f32 v[94:95], v[94:95], v[108:109], v[98:99] op_sel_hi:[1,0,1]
	v_pk_fma_f32 v[92:93], v[92:93], v[108:109], v[96:97] op_sel_hi:[1,0,1]
	v_pk_fma_f32 v[90:91], v[90:91], v[108:109], v[102:103] op_sel_hi:[1,0,1]
	v_pk_fma_f32 v[88:89], v[88:89], v[108:109], v[100:101] op_sel_hi:[1,0,1]
	v_lshlrev_b32_e32 v110, 16, v109
	v_and_b32_e32 v111, 0xffff0000, v109
	v_lshlrev_b32_e32 v112, 16, v113
	v_and_b32_e32 v113, 0xffff0000, v113
	v_cvt_pk_bf16_f32 v92, v92, v93
	v_cvt_pk_bf16_f32 v93, v94, v95
	v_cvt_pk_bf16_f32 v94, v88, v89
	v_cvt_pk_bf16_f32 v95, v90, v91
	v_lshlrev_b32_e32 v88, 16, v117
	v_and_b32_e32 v89, 0xffff0000, v117
	v_lshlrev_b32_e32 v90, 16, v114
	v_and_b32_e32 v91, 0xffff0000, v114
	v_pk_fma_f32 v[86:87], v[86:87], v[108:109], v[112:113] op_sel_hi:[1,0,1]
	v_pk_fma_f32 v[84:85], v[84:85], v[108:109], v[110:111] op_sel_hi:[1,0,1]
	v_pk_fma_f32 v[82:83], v[82:83], v[108:109], v[90:91] op_sel_hi:[1,0,1]
	v_pk_fma_f32 v[80:81], v[80:81], v[108:109], v[88:89] op_sel_hi:[1,0,1]
	v_cvt_pk_bf16_f32 v84, v84, v85
	v_cvt_pk_bf16_f32 v85, v86, v87
	v_cvt_pk_bf16_f32 v86, v80, v81
	v_cvt_pk_bf16_f32 v87, v82, v83
	s_nop 0
	v_mov_b32_dpp v88, v92 row_ror:8 row_mask:0xf bank_mask:0xf
	v_mov_b32_dpp v89, v93 row_ror:8 row_mask:0xf bank_mask:0xf
	v_mov_b32_dpp v80, v84 row_ror:8 row_mask:0xf bank_mask:0xf
	v_mov_b32_dpp v81, v85 row_ror:8 row_mask:0xf bank_mask:0xf
	v_mov_b32_dpp v82, v86 row_ror:8 row_mask:0xf bank_mask:0xf
	v_mov_b32_dpp v83, v87 row_ror:8 row_mask:0xf bank_mask:0xf
	v_cndmask_b32_e64 v84, v84, v88, s[6:7]
	v_cndmask_b32_e64 v85, v85, v89, s[6:7]
	v_lshl_add_u64 v[88:89], s[8:9], 0, v[104:105]
	v_cndmask_b32_e64 v80, v80, v92, s[6:7]
	v_cndmask_b32_e64 v81, v81, v93, s[6:7]
	v_cndmask_b32_e64 v82, v82, v94, s[6:7]
	v_cndmask_b32_e64 v83, v83, v95, s[6:7]
	v_lshl_add_u64 v[88:89], v[88:89], 0, v[146:147]
	v_mov_b32_dpp v90, v94 row_ror:8 row_mask:0xf bank_mask:0xf
	v_mov_b32_dpp v91, v95 row_ror:8 row_mask:0xf bank_mask:0xf
	global_store_dwordx4 v[88:89], v[80:83], off
	v_cndmask_b32_e64 v86, v86, v90, s[6:7]
	v_cndmask_b32_e64 v87, v87, v91, s[6:7]
	v_lshl_add_u64 v[80:81], s[8:9], 0, v[106:107]
	v_lshl_add_u64 v[80:81], v[80:81], 0, v[146:147]
	global_store_dwordx4 v[80:81], v[84:87], off
	v_or_b32_e32 v80, 48, v150
	v_ashrrev_i32_e32 v81, 31, v80
	v_lshl_add_u64 v[82:83], v[80:81], 2, s[10:11]
	v_sub_u32_e32 v80, v80, v152
	v_add_u32_e32 v80, v80, v154
	v_ashrrev_i32_e32 v81, 31, v80
	v_lshlrev_b64 v[88:89], 12, v[80:81]
	v_lshl_add_u64 v[80:81], s[16:17], 0, v[88:89]
	v_lshl_add_u64 v[90:91], v[88:89], 0, s[36:37]
	v_lshl_add_u64 v[80:81], v[80:81], 0, v[146:147]
	v_lshl_add_u64 v[84:85], s[16:17], 0, v[90:91]
	s_waitcnt vmcnt(18)
; __device__ __forceinline__ unsigned cvt_pk_bf16(float lo, float hi) { unsigned r; asm volatile("v_cvt_pk_bf16_f32 %0, %1, %2" : "=v"(r) : "v"(lo), "v"(hi)); return r; }
; __device__ __forceinline__ float bflo(unsigned w) { return __uint_as_float(w << 16); }
; __device__ __forceinline__ void store_pair_lines(bf16_t* O, int ldc, int row, int fr, int col0, u32x4 wA, u32x4 wB) {
;     const u32x4 sA = {dpp_ror8(wA.x), dpp_ror8(wA.y), dpp_ror8(wA.z), dpp_ror8(wA.w)}, sB = {dpp_ror8(wB.x), dpp_ror8(wB.y), dpp_ror8(wB.z), dpp_ror8(wB.w)};
;     const bool lo = fr < 8;
;     const u32x4 o1 = lo ? wA : sB, o2 = lo ? sA : wB;
;     const int r1 = row - fr + (fr & 7), cb = col0 + (lo ? 0 : 8);
;     *(u32x4*)(O + (size_t)r1 * ldc + cb) = o1;
;     *(u32x4*)(O + (size_t)(r1 + 8) * ldc + cb) = o2;
; }
;     __device__ __forceinline__ void operator()(const f32x4 (&acc)[2][2][4][2], const Unit& u, int wr, int wc, int fr, int fq) const {
;     ...
;             for (int m = 0; m < 4; ++m) { const int row = row0 + ai * HALF + m * 16; const size_t off = (size_t)row * D + col0; float sq = 0.f; u32x4 w[2];
;                 const float sc = rsin ? __builtin_amdgcn_rcpf(rsin[row] * (1.f / D) + EPS) : 1.0f;
;                 u32x4 rr[2]; if (R) load_pair_lines(R, D, row, fr, col0, rr[0], rr[1]);
; #pragma unroll
;                 for (int bj = 0; bj < 2; ++bj) { f32x4 r0, r1;
;                     if (R) { const u32x4 rw = rr[bj]; r0 = (f32x4){bflo(rw.x), bfhi(rw.x), bflo(rw.y), bfhi(rw.y)}; r1 = (f32x4){bflo(rw.z), bfhi(rw.z), bflo(rw.w), bfhi(rw.w)}; }
;                     else { const float* rp = (row < 8192 ? src_p + off : src_s + (off - (size_t)8192 * D)) + 8 * bj; r0 = *(const f32x4*)rp; r1 = *(const f32x4*)(rp + 4); }
;                     const f32x4 o0 = r0 + acc[ai][bj][m][0] * sc, o1 = r1 + acc[ai][bj][m][1] * sc;
;                     sq += (o0[0] * o0[0] + o0[1] * o0[1]) + (o0[2] * o0[2] + o0[3] * o0[3]) + (o1[0] * o1[0] + o1[1] * o1[1]) + (o1[2] * o1[2] + o1[3] * o1[3]);
;                     w[bj].x = cvt_pk_bf16(o0[0], o0[1]); w[bj].y = cvt_pk_bf16(o0[2], o0[3]); w[bj].z = cvt_pk_bf16(o1[0], o1[1]); w[bj].w = cvt_pk_bf16(o1[2], o1[3]); }
;                 store_pair_lines(O, D, row, fr, col0, w[0], w[1]);
;                 if (ssout) { sq += __shfl_xor(sq, 16); sq += __shfl_xor(sq, 32); if (fq == 0) unsafeAtomicAdd(ssout + row, sq); } }
	s_nop 0
	v_mov_b32_e32 v92, v206
	s_nop 0
	v_mov_b64_e32 v[80:81], v[224:225]
	v_mov_b64_e32 v[82:83], v[226:227]
	v_lshl_add_u64 v[84:85], v[84:85], 0, v[146:147]
	v_mov_b64_e32 v[84:85], v[228:229]
	v_mov_b64_e32 v[86:87], v[230:231]
	s_nop 1
	v_fmamk_f32 v92, v92, 0x3a000000, v159
	v_rcp_f32_e32 v92, v92
	v_mov_b32_dpp v93, v80 row_ror:8 row_mask:0xf bank_mask:0xf
	v_mov_b32_dpp v97, v84 row_ror:8 row_mask:0xf bank_mask:0xf
	v_mov_b32_dpp v98, v85 row_ror:8 row_mask:0xf bank_mask:0xf
	v_mov_b32_dpp v99, v86 row_ror:8 row_mask:0xf bank_mask:0xf
	v_mov_b32_dpp v100, v87 row_ror:8 row_mask:0xf bank_mask:0xf
	v_mov_b32_dpp v94, v81 row_ror:8 row_mask:0xf bank_mask:0xf
	v_mov_b32_dpp v95, v82 row_ror:8 row_mask:0xf bank_mask:0xf
	v_mov_b32_dpp v96, v83 row_ror:8 row_mask:0xf bank_mask:0xf
	v_cndmask_b32_e64 v100, v100, v83, s[6:7]
	v_cndmask_b32_e64 v99, v99, v82, s[6:7]
	v_cndmask_b32_e64 v83, v98, v81, s[6:7]
	v_cndmask_b32_e64 v81, v97, v80, s[6:7]
	v_cndmask_b32_e64 v96, v87, v96, s[6:7]
	v_cndmask_b32_e64 v95, v86, v95, s[6:7]
	v_cndmask_b32_e64 v94, v85, v94, s[6:7]
	v_cndmask_b32_e64 v93, v84, v93, s[6:7]
	v_lshlrev_b32_e32 v80, 16, v81
	v_and_b32_e32 v81, 0xffff0000, v81
	v_lshlrev_b32_e32 v82, 16, v83
	v_and_b32_e32 v83, 0xffff0000, v83
	v_lshlrev_b32_e32 v84, 16, v99
	v_and_b32_e32 v85, 0xffff0000, v99
	v_lshlrev_b32_e32 v86, 16, v100
	v_and_b32_e32 v87, 0xffff0000, v100
	v_pk_fma_f32 v[78:79], v[78:79], v[92:93], v[82:83] op_sel_hi:[1,0,1]
	v_pk_fma_f32 v[76:77], v[76:77], v[92:93], v[80:81] op_sel_hi:[1,0,1]
	v_pk_fma_f32 v[74:75], v[74:75], v[92:93], v[86:87] op_sel_hi:[1,0,1]
	v_pk_fma_f32 v[72:73], v[72:73], v[92:93], v[84:85] op_sel_hi:[1,0,1]
	v_cvt_pk_bf16_f32 v80, v76, v77
	v_cvt_pk_bf16_f32 v81, v78, v79
	v_lshlrev_b32_e32 v76, 16, v95
	v_cvt_pk_bf16_f32 v82, v72, v73
	v_cvt_pk_bf16_f32 v83, v74, v75
	v_lshlrev_b32_e32 v72, 16, v93
	v_and_b32_e32 v73, 0xffff0000, v93
	v_lshlrev_b32_e32 v74, 16, v94
	v_and_b32_e32 v75, 0xffff0000, v94
	v_and_b32_e32 v77, 0xffff0000, v95
	v_lshlrev_b32_e32 v78, 16, v96
	v_and_b32_e32 v79, 0xffff0000, v96
	v_pk_fma_f32 v[70:71], v[70:71], v[92:93], v[74:75] op_sel_hi:[1,0,1]
	v_pk_fma_f32 v[68:69], v[68:69], v[92:93], v[72:73] op_sel_hi:[1,0,1]
	v_pk_fma_f32 v[66:67], v[66:67], v[92:93], v[78:79] op_sel_hi:[1,0,1]
	v_pk_fma_f32 v[64:65], v[64:65], v[92:93], v[76:77] op_sel_hi:[1,0,1]
	v_cvt_pk_bf16_f32 v68, v68, v69
	v_cvt_pk_bf16_f32 v69, v70, v71
	v_cvt_pk_bf16_f32 v70, v64, v65
	v_cvt_pk_bf16_f32 v71, v66, v67
	s_nop 0
	v_mov_b32_dpp v72, v80 row_ror:8 row_mask:0xf bank_mask:0xf
	v_mov_b32_dpp v73, v81 row_ror:8 row_mask:0xf bank_mask:0xf
	v_mov_b32_dpp v64, v68 row_ror:8 row_mask:0xf bank_mask:0xf
	v_mov_b32_dpp v65, v69 row_ror:8 row_mask:0xf bank_mask:0xf
	v_mov_b32_dpp v66, v70 row_ror:8 row_mask:0xf bank_mask:0xf
	v_mov_b32_dpp v67, v71 row_ror:8 row_mask:0xf bank_mask:0xf
	v_cndmask_b32_e64 v68, v68, v72, s[6:7]
	v_cndmask_b32_e64 v69, v69, v73, s[6:7]
	v_lshl_add_u64 v[72:73], s[8:9], 0, v[88:89]
	v_cndmask_b32_e64 v64, v64, v80, s[6:7]
	v_cndmask_b32_e64 v65, v65, v81, s[6:7]
	v_cndmask_b32_e64 v66, v66, v82, s[6:7]
	v_cndmask_b32_e64 v67, v67, v83, s[6:7]
	v_lshl_add_u64 v[72:73], v[72:73], 0, v[146:147]
	v_mov_b32_dpp v74, v82 row_ror:8 row_mask:0xf bank_mask:0xf
	v_mov_b32_dpp v75, v83 row_ror:8 row_mask:0xf bank_mask:0xf
	global_store_dwordx4 v[72:73], v[64:67], off
	v_cndmask_b32_e64 v70, v70, v74, s[6:7]
	v_cndmask_b32_e64 v71, v71, v75, s[6:7]
	v_lshl_add_u64 v[64:65], s[8:9], 0, v[90:91]
	v_lshl_add_u64 v[64:65], v[64:65], 0, v[146:147]
	global_store_dwordx4 v[64:65], v[68:71], off
	v_sub_u32_e32 v64, v150, v152
	v_add_u32_e32 v77, v64, v154
	v_add_u32_e32 v64, 0x80, v77
	v_ashrrev_i32_e32 v65, 31, v64
	v_lshlrev_b64 v[72:73], 12, v[64:65]
	v_lshl_add_u64 v[64:65], s[16:17], 0, v[72:73]
	v_lshl_add_u64 v[74:75], v[72:73], 0, s[36:37]
	v_lshl_add_u64 v[64:65], v[64:65], 0, v[146:147]
	v_lshl_add_u64 v[68:69], s[16:17], 0, v[74:75]
	s_waitcnt vmcnt(17)
	s_nop 0
	v_mov_b32_e32 v76, v207
	s_nop 0
	v_mov_b64_e32 v[64:65], v[232:233]
	v_mov_b64_e32 v[66:67], v[234:235]
	v_lshl_add_u64 v[68:69], v[68:69], 0, v[146:147]
	v_mov_b64_e32 v[68:69], v[236:237]
	v_mov_b64_e32 v[70:71], v[238:239]
	s_nop 1
	v_fmamk_f32 v76, v76, 0x3a000000, v159
	v_rcp_f32_e32 v76, v76
	v_mov_b32_dpp v78, v64 row_ror:8 row_mask:0xf bank_mask:0xf
	v_mov_b32_dpp v82, v68 row_ror:8 row_mask:0xf bank_mask:0xf
	v_mov_b32_dpp v83, v69 row_ror:8 row_mask:0xf bank_mask:0xf
	v_mov_b32_dpp v84, v70 row_ror:8 row_mask:0xf bank_mask:0xf
	v_mov_b32_dpp v85, v71 row_ror:8 row_mask:0xf bank_mask:0xf
	v_mov_b32_dpp v79, v65 row_ror:8 row_mask:0xf bank_mask:0xf
	v_mov_b32_dpp v80, v66 row_ror:8 row_mask:0xf bank_mask:0xf
	v_mov_b32_dpp v81, v67 row_ror:8 row_mask:0xf bank_mask:0xf
	v_cndmask_b32_e64 v85, v85, v67, s[6:7]
	v_cndmask_b32_e64 v84, v84, v66, s[6:7]
	v_cndmask_b32_e64 v67, v83, v65, s[6:7]
	v_cndmask_b32_e64 v65, v82, v64, s[6:7]
	v_cndmask_b32_e64 v81, v71, v81, s[6:7]
	v_cndmask_b32_e64 v80, v70, v80, s[6:7]
	v_cndmask_b32_e64 v79, v69, v79, s[6:7]
	v_cndmask_b32_e64 v78, v68, v78, s[6:7]
	v_lshlrev_b32_e32 v64, 16, v65
	v_and_b32_e32 v65, 0xffff0000, v65
	v_lshlrev_b32_e32 v66, 16, v67
	v_and_b32_e32 v67, 0xffff0000, v67
	v_lshlrev_b32_e32 v68, 16, v84
	v_and_b32_e32 v69, 0xffff0000, v84
	v_lshlrev_b32_e32 v70, 16, v85
	v_and_b32_e32 v71, 0xffff0000, v85
	v_pk_fma_f32 v[62:63], v[62:63], v[76:77], v[66:67] op_sel_hi:[1,0,1]
	v_pk_fma_f32 v[60:61], v[60:61], v[76:77], v[64:65] op_sel_hi:[1,0,1]
	v_pk_fma_f32 v[58:59], v[58:59], v[76:77], v[70:71] op_sel_hi:[1,0,1]
	v_pk_fma_f32 v[56:57], v[56:57], v[76:77], v[68:69] op_sel_hi:[1,0,1]
; __device__ __forceinline__ unsigned cvt_pk_bf16(float lo, float hi) { unsigned r; asm volatile("v_cvt_pk_bf16_f32 %0, %1, %2" : "=v"(r) : "v"(lo), "v"(hi)); return r; }
; __device__ __forceinline__ float bflo(unsigned w) { return __uint_as_float(w << 16); }
; __device__ __forceinline__ void store_pair_lines(bf16_t* O, int ldc, int row, int fr, int col0, u32x4 wA, u32x4 wB) {
;     const u32x4 sA = {dpp_ror8(wA.x), dpp_ror8(wA.y), dpp_ror8(wA.z), dpp_ror8(wA.w)}, sB = {dpp_ror8(wB.x), dpp_ror8(wB.y), dpp_ror8(wB.z), dpp_ror8(wB.w)};
;     const bool lo = fr < 8;
;     const u32x4 o1 = lo ? wA : sB, o2 = lo ? sA : wB;
;     const int r1 = row - fr + (fr & 7), cb = col0 + (lo ? 0 : 8);
;     *(u32x4*)(O + (size_t)r1 * ldc + cb) = o1;
;     *(u32x4*)(O + (size_t)(r1 + 8) * ldc + cb) = o2;
; }
;     __device__ __forceinline__ void operator()(const f32x4 (&acc)[2][2][4][2], const Unit& u, int wr, int wc, int fr, int fq) const {
;     ...
;             for (int m = 0; m < 4; ++m) { const int row = row0 + ai * HALF + m * 16; const size_t off = (size_t)row * D + col0; float sq = 0.f; u32x4 w[2];
;                 const float sc = rsin ? __builtin_amdgcn_rcpf(rsin[row] * (1.f / D) + EPS) : 1.0f;
;                 u32x4 rr[2]; if (R) load_pair_lines(R, D, row, fr, col0, rr[0], rr[1]);
; #pragma unroll
;                 for (int bj = 0; bj < 2; ++bj) { f32x4 r0, r1;
;                     if (R) { const u32x4 rw = rr[bj]; r0 = (f32x4){bflo(rw.x), bfhi(rw.x), bflo(rw.y), bfhi(rw.y)}; r1 = (f32x4){bflo(rw.z), bfhi(rw.z), bflo(rw.w), bfhi(rw.w)}; }
;                     else { const float* rp = (row < 8192 ? src_p + off : src_s + (off - (size_t)8192 * D)) + 8 * bj; r0 = *(const f32x4*)rp; r1 = *(const f32x4*)(rp + 4); }
;                     const f32x4 o0 = r0 + acc[ai][bj][m][0] * sc, o1 = r1 + acc[ai][bj][m][1] * sc;
;                     sq += (o0[0] * o0[0] + o0[1] * o0[1]) + (o0[2] * o0[2] + o0[3] * o0[3]) + (o1[0] * o1[0] + o1[1] * o1[1]) + (o1[2] * o1[2] + o1[3] * o1[3]);
;                     w[bj].x = cvt_pk_bf16(o0[0], o0[1]); w[bj].y = cvt_pk_bf16(o0[2], o0[3]); w[bj].z = cvt_pk_bf16(o1[0], o1[1]); w[bj].w = cvt_pk_bf16(o1[2], o1[3]); }
;                 store_pair_lines(O, D, row, fr, col0, w[0], w[1]);
;                 if (ssout) { sq += __shfl_xor(sq, 16); sq += __shfl_xor(sq, 32); if (fq == 0) unsafeAtomicAdd(ssout + row, sq); } }
	v_cvt_pk_bf16_f32 v64, v60, v61
	v_cvt_pk_bf16_f32 v65, v62, v63
	v_lshlrev_b32_e32 v60, 16, v80
	v_cvt_pk_bf16_f32 v66, v56, v57
	v_cvt_pk_bf16_f32 v67, v58, v59
	v_lshlrev_b32_e32 v56, 16, v78
	v_and_b32_e32 v57, 0xffff0000, v78
	v_lshlrev_b32_e32 v58, 16, v79
	v_and_b32_e32 v59, 0xffff0000, v79
	v_and_b32_e32 v61, 0xffff0000, v80
	v_lshlrev_b32_e32 v62, 16, v81
	v_and_b32_e32 v63, 0xffff0000, v81
	v_pk_fma_f32 v[54:55], v[54:55], v[76:77], v[58:59] op_sel_hi:[1,0,1]
	v_pk_fma_f32 v[52:53], v[52:53], v[76:77], v[56:57] op_sel_hi:[1,0,1]
	v_pk_fma_f32 v[50:51], v[50:51], v[76:77], v[62:63] op_sel_hi:[1,0,1]
	v_pk_fma_f32 v[48:49], v[48:49], v[76:77], v[60:61] op_sel_hi:[1,0,1]
	v_cvt_pk_bf16_f32 v52, v52, v53
	v_cvt_pk_bf16_f32 v53, v54, v55
	v_cvt_pk_bf16_f32 v54, v48, v49
	v_cvt_pk_bf16_f32 v55, v50, v51
	s_nop 0
	v_mov_b32_dpp v56, v64 row_ror:8 row_mask:0xf bank_mask:0xf
	v_mov_b32_dpp v57, v65 row_ror:8 row_mask:0xf bank_mask:0xf
	v_mov_b32_dpp v48, v52 row_ror:8 row_mask:0xf bank_mask:0xf
	v_mov_b32_dpp v49, v53 row_ror:8 row_mask:0xf bank_mask:0xf
	v_mov_b32_dpp v50, v54 row_ror:8 row_mask:0xf bank_mask:0xf
	v_mov_b32_dpp v51, v55 row_ror:8 row_mask:0xf bank_mask:0xf
	v_cndmask_b32_e64 v52, v52, v56, s[6:7]
	v_cndmask_b32_e64 v53, v53, v57, s[6:7]
	v_lshl_add_u64 v[56:57], s[8:9], 0, v[72:73]
	v_cndmask_b32_e64 v48, v48, v64, s[6:7]
	v_cndmask_b32_e64 v49, v49, v65, s[6:7]
	v_cndmask_b32_e64 v50, v50, v66, s[6:7]
	v_cndmask_b32_e64 v51, v51, v67, s[6:7]
	v_lshl_add_u64 v[56:57], v[56:57], 0, v[146:147]
	v_mov_b32_dpp v58, v66 row_ror:8 row_mask:0xf bank_mask:0xf
	v_mov_b32_dpp v59, v67 row_ror:8 row_mask:0xf bank_mask:0xf
	global_store_dwordx4 v[56:57], v[48:51], off
	v_cndmask_b32_e64 v54, v54, v58, s[6:7]
	v_cndmask_b32_e64 v55, v55, v59, s[6:7]
	v_lshl_add_u64 v[48:49], s[8:9], 0, v[74:75]
	v_lshl_add_u64 v[48:49], v[48:49], 0, v[146:147]
	global_store_dwordx4 v[48:49], v[52:55], off
	v_add_u32_e32 v48, 0x90, v77
	v_ashrrev_i32_e32 v49, 31, v48
	v_lshlrev_b64 v[56:57], 12, v[48:49]
	v_lshl_add_u64 v[48:49], s[16:17], 0, v[56:57]
	v_lshl_add_u64 v[58:59], v[56:57], 0, s[36:37]
	v_lshl_add_u64 v[48:49], v[48:49], 0, v[146:147]
	v_lshl_add_u64 v[52:53], s[16:17], 0, v[58:59]
	s_waitcnt vmcnt(16)
	s_nop 0
	v_mov_b32_e32 v60, v240
	s_nop 0
	v_mov_b64_e32 v[48:49], v[244:245]
	v_mov_b64_e32 v[50:51], v[246:247]
	v_lshl_add_u64 v[52:53], v[52:53], 0, v[146:147]
	v_mov_b64_e32 v[52:53], v[248:249]
	v_mov_b64_e32 v[54:55], v[250:251]
	s_nop 1
	v_fmamk_f32 v60, v60, 0x3a000000, v159
	v_rcp_f32_e32 v60, v60
	v_mov_b32_dpp v61, v48 row_ror:8 row_mask:0xf bank_mask:0xf
	v_mov_b32_dpp v65, v52 row_ror:8 row_mask:0xf bank_mask:0xf
	v_mov_b32_dpp v66, v53 row_ror:8 row_mask:0xf bank_mask:0xf
	v_mov_b32_dpp v67, v54 row_ror:8 row_mask:0xf bank_mask:0xf
	v_mov_b32_dpp v68, v55 row_ror:8 row_mask:0xf bank_mask:0xf
	v_mov_b32_dpp v62, v49 row_ror:8 row_mask:0xf bank_mask:0xf
	v_mov_b32_dpp v63, v50 row_ror:8 row_mask:0xf bank_mask:0xf
	v_mov_b32_dpp v64, v51 row_ror:8 row_mask:0xf bank_mask:0xf
	v_cndmask_b32_e64 v68, v68, v51, s[6:7]
	v_cndmask_b32_e64 v67, v67, v50, s[6:7]
	v_cndmask_b32_e64 v51, v66, v49, s[6:7]
	v_cndmask_b32_e64 v49, v65, v48, s[6:7]
	v_cndmask_b32_e64 v64, v55, v64, s[6:7]
	v_cndmask_b32_e64 v63, v54, v63, s[6:7]
	v_cndmask_b32_e64 v62, v53, v62, s[6:7]
	v_cndmask_b32_e64 v61, v52, v61, s[6:7]
	v_lshlrev_b32_e32 v48, 16, v49
	v_and_b32_e32 v49, 0xffff0000, v49
	v_lshlrev_b32_e32 v50, 16, v51
	v_and_b32_e32 v51, 0xffff0000, v51
	v_lshlrev_b32_e32 v52, 16, v67
	v_and_b32_e32 v53, 0xffff0000, v67
	v_lshlrev_b32_e32 v54, 16, v68
	v_and_b32_e32 v55, 0xffff0000, v68
	v_pk_fma_f32 v[46:47], v[46:47], v[60:61], v[50:51] op_sel_hi:[1,0,1]
	v_pk_fma_f32 v[44:45], v[44:45], v[60:61], v[48:49] op_sel_hi:[1,0,1]
	v_pk_fma_f32 v[42:43], v[42:43], v[60:61], v[54:55] op_sel_hi:[1,0,1]
	v_pk_fma_f32 v[40:41], v[40:41], v[60:61], v[52:53] op_sel_hi:[1,0,1]
	v_cvt_pk_bf16_f32 v48, v44, v45
	v_cvt_pk_bf16_f32 v49, v46, v47
	v_lshlrev_b32_e32 v44, 16, v63
	v_cvt_pk_bf16_f32 v50, v40, v41
	v_cvt_pk_bf16_f32 v51, v42, v43
	v_lshlrev_b32_e32 v40, 16, v61
	v_and_b32_e32 v41, 0xffff0000, v61
	v_lshlrev_b32_e32 v42, 16, v62
	v_and_b32_e32 v43, 0xffff0000, v62
	v_and_b32_e32 v45, 0xffff0000, v63
	v_lshlrev_b32_e32 v46, 16, v64
	v_and_b32_e32 v47, 0xffff0000, v64
	v_pk_fma_f32 v[38:39], v[38:39], v[60:61], v[42:43] op_sel_hi:[1,0,1]
	v_pk_fma_f32 v[36:37], v[36:37], v[60:61], v[40:41] op_sel_hi:[1,0,1]
	v_pk_fma_f32 v[34:35], v[34:35], v[60:61], v[46:47] op_sel_hi:[1,0,1]
	v_pk_fma_f32 v[32:33], v[32:33], v[60:61], v[44:45] op_sel_hi:[1,0,1]
	v_cvt_pk_bf16_f32 v36, v36, v37
	v_cvt_pk_bf16_f32 v37, v38, v39
	v_cvt_pk_bf16_f32 v38, v32, v33
	v_cvt_pk_bf16_f32 v39, v34, v35
	s_nop 0
	v_mov_b32_dpp v40, v48 row_ror:8 row_mask:0xf bank_mask:0xf
	v_mov_b32_dpp v41, v49 row_ror:8 row_mask:0xf bank_mask:0xf
	v_mov_b32_dpp v32, v36 row_ror:8 row_mask:0xf bank_mask:0xf
	v_mov_b32_dpp v33, v37 row_ror:8 row_mask:0xf bank_mask:0xf
	v_mov_b32_dpp v34, v38 row_ror:8 row_mask:0xf bank_mask:0xf
	v_mov_b32_dpp v35, v39 row_ror:8 row_mask:0xf bank_mask:0xf
	v_cndmask_b32_e64 v36, v36, v40, s[6:7]
	v_cndmask_b32_e64 v37, v37, v41, s[6:7]
	v_lshl_add_u64 v[40:41], s[8:9], 0, v[56:57]
	v_cndmask_b32_e64 v32, v32, v48, s[6:7]
	v_cndmask_b32_e64 v33, v33, v49, s[6:7]
	v_cndmask_b32_e64 v34, v34, v50, s[6:7]
	v_cndmask_b32_e64 v35, v35, v51, s[6:7]
	v_lshl_add_u64 v[40:41], v[40:41], 0, v[146:147]
	v_mov_b32_dpp v42, v50 row_ror:8 row_mask:0xf bank_mask:0xf
	v_mov_b32_dpp v43, v51 row_ror:8 row_mask:0xf bank_mask:0xf
	global_store_dwordx4 v[40:41], v[32:35], off
	v_cndmask_b32_e64 v38, v38, v42, s[6:7]
	v_cndmask_b32_e64 v39, v39, v43, s[6:7]
	v_lshl_add_u64 v[32:33], s[8:9], 0, v[58:59]
	v_lshl_add_u64 v[32:33], v[32:33], 0, v[146:147]
	global_store_dwordx4 v[32:33], v[36:39], off
	v_add_u32_e32 v32, 0xa0, v77
	v_ashrrev_i32_e32 v33, 31, v32
	v_lshlrev_b64 v[40:41], 12, v[32:33]
	v_lshl_add_u64 v[42:43], v[40:41], 0, s[36:37]
	s_waitcnt vmcnt(13)
; __device__ __forceinline__ unsigned cvt_pk_bf16(float lo, float hi) { unsigned r; asm volatile("v_cvt_pk_bf16_f32 %0, %1, %2" : "=v"(r) : "v"(lo), "v"(hi)); return r; }
; __device__ __forceinline__ float bflo(unsigned w) { return __uint_as_float(w << 16); }
; __device__ __forceinline__ void store_pair_lines(bf16_t* O, int ldc, int row, int fr, int col0, u32x4 wA, u32x4 wB) {
;     const u32x4 sA = {dpp_ror8(wA.x), dpp_ror8(wA.y), dpp_ror8(wA.z), dpp_ror8(wA.w)}, sB = {dpp_ror8(wB.x), dpp_ror8(wB.y), dpp_ror8(wB.z), dpp_ror8(wB.w)};
;     const bool lo = fr < 8;
;     const u32x4 o1 = lo ? wA : sB, o2 = lo ? sA : wB;
;     const int r1 = row - fr + (fr & 7), cb = col0 + (lo ? 0 : 8);
;     *(u32x4*)(O + (size_t)r1 * ldc + cb) = o1;
;     *(u32x4*)(O + (size_t)(r1 + 8) * ldc + cb) = o2;
; }
;     __device__ __forceinline__ void operator()(const f32x4 (&acc)[2][2][4][2], const Unit& u, int wr, int wc, int fr, int fq) const {
;     ...
;             for (int m = 0; m < 4; ++m) { const int row = row0 + ai * HALF + m * 16; const size_t off = (size_t)row * D + col0; float sq = 0.f; u32x4 w[2];
;                 const float sc = rsin ? __builtin_amdgcn_rcpf(rsin[row] * (1.f / D) + EPS) : 1.0f;
;                 u32x4 rr[2]; if (R) load_pair_lines(R, D, row, fr, col0, rr[0], rr[1]);
; #pragma unroll
;                 for (int bj = 0; bj < 2; ++bj) { f32x4 r0, r1;
;                     if (R) { const u32x4 rw = rr[bj]; r0 = (f32x4){bflo(rw.x), bfhi(rw.x), bflo(rw.y), bfhi(rw.y)}; r1 = (f32x4){bflo(rw.z), bfhi(rw.z), bflo(rw.w), bfhi(rw.w)}; }
;                     else { const float* rp = (row < 8192 ? src_p + off : src_s + (off - (size_t)8192 * D)) + 8 * bj; r0 = *(const f32x4*)rp; r1 = *(const f32x4*)(rp + 4); }
;                     const f32x4 o0 = r0 + acc[ai][bj][m][0] * sc, o1 = r1 + acc[ai][bj][m][1] * sc;
;                     sq += (o0[0] * o0[0] + o0[1] * o0[1]) + (o0[2] * o0[2] + o0[3] * o0[3]) + (o1[0] * o1[0] + o1[1] * o1[1]) + (o1[2] * o1[2] + o1[3] * o1[3]);
;                     w[bj].x = cvt_pk_bf16(o0[0], o0[1]); w[bj].y = cvt_pk_bf16(o0[2], o0[3]); w[bj].z = cvt_pk_bf16(o1[0], o1[1]); w[bj].w = cvt_pk_bf16(o1[2], o1[3]); }
;                 store_pair_lines(O, D, row, fr, col0, w[0], w[1]);
;                 if (ssout) { sq += __shfl_xor(sq, 16); sq += __shfl_xor(sq, 32); if (fq == 0) unsafeAtomicAdd(ssout + row, sq); } }
	s_nop 0
	v_mov_b32_e32 v44, v204
	v_lshl_add_u64 v[32:33], s[16:17], 0, v[40:41]
	v_lshl_add_u64 v[36:37], s[16:17], 0, v[42:43]
	v_lshl_add_u64 v[32:33], v[32:33], 0, v[146:147]
	v_lshl_add_u64 v[36:37], v[36:37], 0, v[146:147]
	v_mov_b64_e32 v[32:33], v[208:209]
	v_mov_b64_e32 v[34:35], v[210:211]
	v_mov_b64_e32 v[36:37], v[212:213]
	v_mov_b64_e32 v[38:39], v[214:215]
	s_nop 1
	v_fmamk_f32 v44, v44, 0x3a000000, v159
	v_rcp_f32_e32 v44, v44
	v_mov_b32_dpp v45, v32 row_ror:8 row_mask:0xf bank_mask:0xf
	v_mov_b32_dpp v46, v33 row_ror:8 row_mask:0xf bank_mask:0xf
	v_mov_b32_dpp v49, v36 row_ror:8 row_mask:0xf bank_mask:0xf
	v_mov_b32_dpp v50, v37 row_ror:8 row_mask:0xf bank_mask:0xf
	v_mov_b32_dpp v51, v38 row_ror:8 row_mask:0xf bank_mask:0xf
	v_mov_b32_dpp v52, v39 row_ror:8 row_mask:0xf bank_mask:0xf
	v_mov_b32_dpp v47, v34 row_ror:8 row_mask:0xf bank_mask:0xf
	v_mov_b32_dpp v48, v35 row_ror:8 row_mask:0xf bank_mask:0xf
	v_cndmask_b32_e64 v52, v52, v35, s[6:7]
	v_cndmask_b32_e64 v51, v51, v34, s[6:7]
	v_cndmask_b32_e64 v35, v50, v33, s[6:7]
	v_cndmask_b32_e64 v33, v49, v32, s[6:7]
	v_cndmask_b32_e64 v48, v39, v48, s[6:7]
	v_cndmask_b32_e64 v47, v38, v47, s[6:7]
	v_cndmask_b32_e64 v46, v37, v46, s[6:7]
	v_cndmask_b32_e64 v45, v36, v45, s[6:7]
	v_lshlrev_b32_e32 v32, 16, v33
	v_and_b32_e32 v33, 0xffff0000, v33
	v_lshlrev_b32_e32 v34, 16, v35
	v_and_b32_e32 v35, 0xffff0000, v35
	v_lshlrev_b32_e32 v36, 16, v51
	v_and_b32_e32 v37, 0xffff0000, v51
	v_lshlrev_b32_e32 v38, 16, v52
	v_and_b32_e32 v39, 0xffff0000, v52
	v_pk_fma_f32 v[30:31], v[30:31], v[44:45], v[34:35] op_sel_hi:[1,0,1]
	v_pk_fma_f32 v[28:29], v[28:29], v[44:45], v[32:33] op_sel_hi:[1,0,1]
	v_pk_fma_f32 v[26:27], v[26:27], v[44:45], v[38:39] op_sel_hi:[1,0,1]
	v_pk_fma_f32 v[24:25], v[24:25], v[44:45], v[36:37] op_sel_hi:[1,0,1]
	v_cvt_pk_bf16_f32 v32, v28, v29
	v_cvt_pk_bf16_f32 v33, v30, v31
	v_lshlrev_b32_e32 v28, 16, v47
	v_cvt_pk_bf16_f32 v34, v24, v25
	v_cvt_pk_bf16_f32 v35, v26, v27
	v_lshlrev_b32_e32 v24, 16, v45
	v_and_b32_e32 v25, 0xffff0000, v45
	v_lshlrev_b32_e32 v26, 16, v46
	v_and_b32_e32 v27, 0xffff0000, v46
	v_and_b32_e32 v29, 0xffff0000, v47
	v_lshlrev_b32_e32 v30, 16, v48
	v_and_b32_e32 v31, 0xffff0000, v48
	v_pk_fma_f32 v[22:23], v[22:23], v[44:45], v[26:27] op_sel_hi:[1,0,1]
	v_pk_fma_f32 v[20:21], v[20:21], v[44:45], v[24:25] op_sel_hi:[1,0,1]
	v_pk_fma_f32 v[18:19], v[18:19], v[44:45], v[30:31] op_sel_hi:[1,0,1]
	v_pk_fma_f32 v[16:17], v[16:17], v[44:45], v[28:29] op_sel_hi:[1,0,1]
	v_cvt_pk_bf16_f32 v20, v20, v21
	v_cvt_pk_bf16_f32 v21, v22, v23
	v_cvt_pk_bf16_f32 v22, v16, v17
	v_cvt_pk_bf16_f32 v23, v18, v19
	s_nop 0
	v_mov_b32_dpp v24, v32 row_ror:8 row_mask:0xf bank_mask:0xf
	v_mov_b32_dpp v25, v33 row_ror:8 row_mask:0xf bank_mask:0xf
	v_mov_b32_dpp v16, v20 row_ror:8 row_mask:0xf bank_mask:0xf
	v_mov_b32_dpp v17, v21 row_ror:8 row_mask:0xf bank_mask:0xf
	v_mov_b32_dpp v18, v22 row_ror:8 row_mask:0xf bank_mask:0xf
	v_mov_b32_dpp v19, v23 row_ror:8 row_mask:0xf bank_mask:0xf
	v_cndmask_b32_e64 v20, v20, v24, s[6:7]
	v_cndmask_b32_e64 v21, v21, v25, s[6:7]
	v_lshl_add_u64 v[24:25], s[8:9], 0, v[40:41]
	v_cndmask_b32_e64 v16, v16, v32, s[6:7]
	v_cndmask_b32_e64 v17, v17, v33, s[6:7]
	v_cndmask_b32_e64 v18, v18, v34, s[6:7]
	v_cndmask_b32_e64 v19, v19, v35, s[6:7]
	v_lshl_add_u64 v[24:25], v[24:25], 0, v[146:147]
	v_mov_b32_dpp v26, v34 row_ror:8 row_mask:0xf bank_mask:0xf
	v_mov_b32_dpp v27, v35 row_ror:8 row_mask:0xf bank_mask:0xf
	global_store_dwordx4 v[24:25], v[16:19], off
	v_cndmask_b32_e64 v22, v22, v26, s[6:7]
	v_cndmask_b32_e64 v23, v23, v27, s[6:7]
	v_lshl_add_u64 v[16:17], s[8:9], 0, v[42:43]
	v_lshl_add_u64 v[16:17], v[16:17], 0, v[146:147]
	global_store_dwordx4 v[16:17], v[20:23], off
	v_add_u32_e32 v16, 0xb0, v77
	v_ashrrev_i32_e32 v17, 31, v16
	v_lshlrev_b64 v[24:25], 12, v[16:17]
	v_lshl_add_u64 v[26:27], v[24:25], 0, s[36:37]
	s_waitcnt vmcnt(10)
; __device__ __forceinline__ unsigned cvt_pk_bf16(float lo, float hi) { unsigned r; asm volatile("v_cvt_pk_bf16_f32 %0, %1, %2" : "=v"(r) : "v"(lo), "v"(hi)); return r; }
;     __device__ __forceinline__ void operator()(const f32x4 (&acc)[2][2][4][2], const Unit& u, int wr, int wc, int fr, int fq) const {
;     ...
;             for (int m = 0; m < 4; ++m) { const int row = row0 + ai * HALF + m * 16; const size_t off = (size_t)row * D + col0; float sq = 0.f; u32x4 w[2];
;                 const float sc = rsin ? __builtin_amdgcn_rcpf(rsin[row] * (1.f / D) + EPS) : 1.0f;
;                 u32x4 rr[2]; if (R) load_pair_lines(R, D, row, fr, col0, rr[0], rr[1]);
; #pragma unroll
;                 for (int bj = 0; bj < 2; ++bj) { f32x4 r0, r1;
;                     if (R) { const u32x4 rw = rr[bj]; r0 = (f32x4){bflo(rw.x), bfhi(rw.x), bflo(rw.y), bfhi(rw.y)}; r1 = (f32x4){bflo(rw.z), bfhi(rw.z), bflo(rw.w), bfhi(rw.w)}; }
;                     else { const float* rp = (row < 8192 ? src_p + off : src_s + (off - (size_t)8192 * D)) + 8 * bj; r0 = *(const f32x4*)rp; r1 = *(const f32x4*)(rp + 4); }
;                     const f32x4 o0 = r0 + acc[ai][bj][m][0] * sc, o1 = r1 + acc[ai][bj][m][1] * sc;
;                     sq += (o0[0] * o0[0] + o0[1] * o0[1]) + (o0[2] * o0[2] + o0[3] * o0[3]) + (o1[0] * o1[0] + o1[1] * o1[1]) + (o1[2] * o1[2] + o1[3] * o1[3]);
;                     w[bj].x = cvt_pk_bf16(o0[0], o0[1]); w[bj].y = cvt_pk_bf16(o0[2], o0[3]); w[bj].z = cvt_pk_bf16(o1[0], o1[1]); w[bj].w = cvt_pk_bf16(o1[2], o1[3]); }
;                 store_pair_lines(O, D, row, fr, col0, w[0], w[1]);
;                 if (ssout) { sq += __shfl_xor(sq, 16); sq += __shfl_xor(sq, 32); if (fq == 0) unsafeAtomicAdd(ssout + row, sq); } }
; template <class Epi>
; __device__ __forceinline__ void gemm_phase(LAS unsigned char* lds, const Gemm g, const StaticOrder& S, const Epi& E) {
;     ...
;         E(acc, cur, wr, wc, fr, fq);
;         if (!has_next) break;
; #pragma unroll
;         for (int a = 0; a < 2; ++a)
; #pragma unroll
;             for (int b = 0; b < 2; ++b)
; #pragma unroll
;                 for (int m = 0; m < 4; ++m)
; #pragma unroll
;                     for (int n = 0; n < 2; ++n) acc[a][b][m][n] = (f32x4){0.f, 0.f, 0.f, 0.f};
;         cur = nxt; cA = nA; cB = nB; ++ui;
;     }
;     PG8_WAIT_V(0);
;     if (wr == 0) PG8_BAR;
;     PG8_BAR;
	s_nop 0
	v_mov_b32_e32 v28, v205
	v_lshl_add_u64 v[16:17], s[16:17], 0, v[24:25]
	v_lshl_add_u64 v[20:21], s[16:17], 0, v[26:27]
	v_lshl_add_u64 v[16:17], v[16:17], 0, v[146:147]
	v_lshl_add_u64 v[20:21], v[20:21], 0, v[146:147]
	v_mov_b64_e32 v[16:17], v[216:217]
	v_mov_b64_e32 v[18:19], v[218:219]
	v_mov_b64_e32 v[20:21], v[220:221]
	v_mov_b64_e32 v[22:23], v[222:223]
	s_nop 1
	v_fmamk_f32 v28, v28, 0x3a000000, v159
	v_rcp_f32_e32 v28, v28
	v_mov_b32_dpp v29, v16 row_ror:8 row_mask:0xf bank_mask:0xf
	v_mov_b32_dpp v30, v17 row_ror:8 row_mask:0xf bank_mask:0xf
	v_mov_b32_dpp v33, v20 row_ror:8 row_mask:0xf bank_mask:0xf
	v_mov_b32_dpp v34, v21 row_ror:8 row_mask:0xf bank_mask:0xf
	v_mov_b32_dpp v35, v22 row_ror:8 row_mask:0xf bank_mask:0xf
	v_mov_b32_dpp v36, v23 row_ror:8 row_mask:0xf bank_mask:0xf
	v_mov_b32_dpp v31, v18 row_ror:8 row_mask:0xf bank_mask:0xf
	v_mov_b32_dpp v32, v19 row_ror:8 row_mask:0xf bank_mask:0xf
	v_cndmask_b32_e64 v36, v36, v19, s[6:7]
	v_cndmask_b32_e64 v35, v35, v18, s[6:7]
	v_cndmask_b32_e64 v19, v34, v17, s[6:7]
	v_cndmask_b32_e64 v17, v33, v16, s[6:7]
	v_cndmask_b32_e64 v32, v23, v32, s[6:7]
	v_cndmask_b32_e64 v31, v22, v31, s[6:7]
	v_cndmask_b32_e64 v30, v21, v30, s[6:7]
	v_cndmask_b32_e64 v29, v20, v29, s[6:7]
	v_lshlrev_b32_e32 v16, 16, v17
	v_and_b32_e32 v17, 0xffff0000, v17
	v_lshlrev_b32_e32 v18, 16, v19
	v_and_b32_e32 v19, 0xffff0000, v19
	v_lshlrev_b32_e32 v20, 16, v35
	v_and_b32_e32 v21, 0xffff0000, v35
	v_lshlrev_b32_e32 v22, 16, v36
	v_and_b32_e32 v23, 0xffff0000, v36
	v_pk_fma_f32 v[14:15], v[14:15], v[28:29], v[18:19] op_sel_hi:[1,0,1]
	v_pk_fma_f32 v[12:13], v[12:13], v[28:29], v[16:17] op_sel_hi:[1,0,1]
	v_pk_fma_f32 v[10:11], v[10:11], v[28:29], v[22:23] op_sel_hi:[1,0,1]
	v_pk_fma_f32 v[8:9], v[8:9], v[28:29], v[20:21] op_sel_hi:[1,0,1]
	v_cvt_pk_bf16_f32 v16, v12, v13
	v_cvt_pk_bf16_f32 v17, v14, v15
	v_lshlrev_b32_e32 v12, 16, v31
	v_cvt_pk_bf16_f32 v18, v8, v9
	v_cvt_pk_bf16_f32 v19, v10, v11
	v_lshlrev_b32_e32 v8, 16, v29
	v_and_b32_e32 v9, 0xffff0000, v29
	v_lshlrev_b32_e32 v10, 16, v30
	v_and_b32_e32 v11, 0xffff0000, v30
	v_and_b32_e32 v13, 0xffff0000, v31
	v_lshlrev_b32_e32 v14, 16, v32
	v_and_b32_e32 v15, 0xffff0000, v32
	v_pk_fma_f32 v[6:7], v[6:7], v[28:29], v[10:11] op_sel_hi:[1,0,1]
	v_pk_fma_f32 v[4:5], v[4:5], v[28:29], v[8:9] op_sel_hi:[1,0,1]
	v_pk_fma_f32 v[2:3], v[2:3], v[28:29], v[14:15] op_sel_hi:[1,0,1]
	v_pk_fma_f32 v[0:1], v[0:1], v[28:29], v[12:13] op_sel_hi:[1,0,1]
	v_cvt_pk_bf16_f32 v4, v4, v5
	v_cvt_pk_bf16_f32 v5, v6, v7
	v_cvt_pk_bf16_f32 v6, v0, v1
	v_cvt_pk_bf16_f32 v7, v2, v3
	s_nop 0
	v_mov_b32_dpp v8, v16 row_ror:8 row_mask:0xf bank_mask:0xf
	v_mov_b32_dpp v9, v17 row_ror:8 row_mask:0xf bank_mask:0xf
	v_mov_b32_dpp v0, v4 row_ror:8 row_mask:0xf bank_mask:0xf
	v_mov_b32_dpp v1, v5 row_ror:8 row_mask:0xf bank_mask:0xf
	v_mov_b32_dpp v2, v6 row_ror:8 row_mask:0xf bank_mask:0xf
	v_mov_b32_dpp v3, v7 row_ror:8 row_mask:0xf bank_mask:0xf
	v_cndmask_b32_e64 v4, v4, v8, s[6:7]
	v_cndmask_b32_e64 v5, v5, v9, s[6:7]
	v_lshl_add_u64 v[8:9], s[8:9], 0, v[24:25]
	v_cndmask_b32_e64 v0, v0, v16, s[6:7]
	v_cndmask_b32_e64 v1, v1, v17, s[6:7]
	v_cndmask_b32_e64 v2, v2, v18, s[6:7]
	v_cndmask_b32_e64 v3, v3, v19, s[6:7]
	v_lshl_add_u64 v[8:9], v[8:9], 0, v[146:147]
	v_mov_b32_dpp v10, v18 row_ror:8 row_mask:0xf bank_mask:0xf
	v_mov_b32_dpp v11, v19 row_ror:8 row_mask:0xf bank_mask:0xf
	global_store_dwordx4 v[8:9], v[0:3], off
	v_cndmask_b32_e64 v6, v6, v10, s[6:7]
	v_cndmask_b32_e64 v7, v7, v11, s[6:7]
	v_lshl_add_u64 v[0:1], s[8:9], 0, v[26:27]
	v_lshl_add_u64 v[0:1], v[0:1], 0, v[146:147]
	global_store_dwordx4 v[0:1], v[4:7], off
	s_cbranch_vccz .LBB0_798
	s_waitcnt vmcnt(0)
	s_cmpk_gt_u32 s56, 0xff
	s_cbranch_scc1 .LBB0_810
	s_barrier

;     __device__ __forceinline__ void operator()(const f32x4 (&acc)[2][2][4][2], const Unit& u, int wr, int wc, int fr, int fq) const {
;     ...
;             for (int m = 0; m < 4; ++m) { const int row = row0 + ai * HALF + m * 16; const size_t off = (size_t)row * D + col0; const float ri = __builtin_amdgcn_rsqf(sse[row] * (1.f / D) + EPS); float sq = 0.f; u32x4 w[2];
;                 u32x4 rr[2], ee[2]; load_pair_lines(R, D, row, fr, col0, rr[0], rr[1]); load_pair_lines(E, D, row, fr, col0, ee[0], ee[1]);
; template <class Epi>
; __device__ __forceinline__ void gemm_phase(LAS unsigned char* lds, const Gemm g, const StaticOrder& S, const Epi& E) {
;     ...
; #pragma unroll
;         for (int a = 0; a < 2; ++a)
; #pragma unroll
;             for (int b = 0; b < 2; ++b)
; #pragma unroll
;                 for (int m = 0; m < 4; ++m)
; #pragma unroll
;                     for (int n = 0; n < 2; ++n) acc[a][b][m][n] = (f32x4){0.f, 0.f, 0.f, 0.f};
;         cur = nxt; cA = nA; cB = nB; ++ui;
.LBB0_881:
	s_ashr_i32 s49, s48, 31
	s_xor_b64 s[52:53], s[64:65], -1
	s_lshl_b64 s[50:51], s[48:49], 20
	s_add_u32 s50, s16, s50
	s_addc_u32 s51, s17, s51
	s_and_b64 s[54:55], s[64:65], exec
	s_cselect_b32 s49, s51, s61
	s_cselect_b32 s57, s50, s60
	s_ashr_i32 s47, s46, 31
	s_lshl_b64 s[54:55], s[46:47], 20
	s_add_u32 s54, s67, s54
	s_addc_u32 s55, s68, s55
	s_and_b64 s[64:65], s[64:65], exec
	s_cselect_b32 s47, s55, s63
	s_cselect_b32 s83, s54, s62
	s_add_u32 s60, s60, 0x80080
	s_addc_u32 s61, s61, 0
	s_add_u32 s84, s62, 0x100
	v_mov_b32_e32 v0, 0
	s_addc_u32 s85, s63, 0
	s_mov_b32 s86, -2
	s_waitcnt lgkmcnt(0)
	v_mov_b32_e32 v1, v0
	v_mov_b32_e32 v2, v0
	v_mov_b32_e32 v3, v0
	v_mov_b32_e32 v4, v0
	v_mov_b32_e32 v5, v0
	v_mov_b32_e32 v6, v0
	v_mov_b32_e32 v7, v0
	v_mov_b32_e32 v16, v0
	v_mov_b32_e32 v17, v0
	v_mov_b32_e32 v18, v0
	v_mov_b32_e32 v19, v0
	v_mov_b32_e32 v20, v0
	v_mov_b32_e32 v21, v0
	v_mov_b32_e32 v22, v0
	v_mov_b32_e32 v23, v0
	v_mov_b32_e32 v36, v0
	v_mov_b32_e32 v37, v0
	v_mov_b32_e32 v38, v0
	v_mov_b32_e32 v39, v0
	v_mov_b32_e32 v44, v0
	v_mov_b32_e32 v45, v0
	v_mov_b32_e32 v46, v0
	v_mov_b32_e32 v47, v0
	v_mov_b32_e32 v64, v0
	v_mov_b32_e32 v65, v0
	v_mov_b32_e32 v66, v0
	v_mov_b32_e32 v67, v0
	v_mov_b32_e32 v68, v0
	v_mov_b32_e32 v69, v0
	v_mov_b32_e32 v70, v0
	v_mov_b32_e32 v71, v0
	v_mov_b32_e32 v8, v0
	v_mov_b32_e32 v9, v0
	v_mov_b32_e32 v10, v0
	v_mov_b32_e32 v11, v0
	v_mov_b32_e32 v12, v0
	v_mov_b32_e32 v13, v0
	v_mov_b32_e32 v14, v0
	v_mov_b32_e32 v15, v0
	v_mov_b32_e32 v24, v0
	v_mov_b32_e32 v25, v0
	v_mov_b32_e32 v26, v0
	v_mov_b32_e32 v27, v0
	v_mov_b32_e32 v28, v0
	v_mov_b32_e32 v29, v0
	v_mov_b32_e32 v30, v0
	v_mov_b32_e32 v31, v0
	v_mov_b32_e32 v56, v0
	v_mov_b32_e32 v57, v0
	v_mov_b32_e32 v58, v0
	v_mov_b32_e32 v59, v0
	v_mov_b32_e32 v60, v0
	v_mov_b32_e32 v61, v0
	v_mov_b32_e32 v62, v0
	v_mov_b32_e32 v63, v0
	v_mov_b32_e32 v72, v0
	v_mov_b32_e32 v73, v0
	v_mov_b32_e32 v74, v0
	v_mov_b32_e32 v75, v0
	v_mov_b32_e32 v76, v0
	v_mov_b32_e32 v77, v0
	v_mov_b32_e32 v78, v0
	v_mov_b32_e32 v79, v0
	v_mov_b32_e32 v80, v0
	v_mov_b32_e32 v81, v0
	v_mov_b32_e32 v82, v0
	v_mov_b32_e32 v83, v0
	v_mov_b32_e32 v84, v0
	v_mov_b32_e32 v85, v0
	v_mov_b32_e32 v86, v0
	v_mov_b32_e32 v87, v0
	v_mov_b32_e32 v96, v0
	v_mov_b32_e32 v97, v0
	v_mov_b32_e32 v98, v0
	v_mov_b32_e32 v99, v0
	v_mov_b32_e32 v100, v0
	v_mov_b32_e32 v101, v0
	v_mov_b32_e32 v102, v0
	v_mov_b32_e32 v103, v0
	v_mov_b32_e32 v112, v0
	v_mov_b32_e32 v113, v0
	v_mov_b32_e32 v114, v0
	v_mov_b32_e32 v115, v0
	v_mov_b32_e32 v116, v0
	v_mov_b32_e32 v117, v0
	v_mov_b32_e32 v118, v0
	v_mov_b32_e32 v119, v0
	v_mov_b32_e32 v128, v0
	v_mov_b32_e32 v129, v0
	v_mov_b32_e32 v130, v0
	v_mov_b32_e32 v131, v0
	v_mov_b32_e32 v132, v0
	v_mov_b32_e32 v133, v0
	v_mov_b32_e32 v134, v0
	v_mov_b32_e32 v135, v0
	v_mov_b32_e32 v88, v0
	v_mov_b32_e32 v89, v0
	v_mov_b32_e32 v90, v0
	v_mov_b32_e32 v91, v0
	v_mov_b32_e32 v92, v0
	v_mov_b32_e32 v93, v0
	v_mov_b32_e32 v94, v0
	v_mov_b32_e32 v95, v0
	v_mov_b32_e32 v104, v0
	v_mov_b32_e32 v105, v0
	v_mov_b32_e32 v106, v0
	v_mov_b32_e32 v107, v0
	v_mov_b32_e32 v108, v0
	v_mov_b32_e32 v109, v0
	v_mov_b32_e32 v110, v0
	v_mov_b32_e32 v111, v0
	v_mov_b32_e32 v120, v0
	v_mov_b32_e32 v121, v0
	v_mov_b32_e32 v122, v0
	v_mov_b32_e32 v123, v0
	v_mov_b32_e32 v124, v0
	v_mov_b32_e32 v125, v0
	v_mov_b32_e32 v126, v0
	v_mov_b32_e32 v127, v0
	v_mov_b32_e32 v136, v0
	v_mov_b32_e32 v137, v0
	v_mov_b32_e32 v138, v0
	v_mov_b32_e32 v139, v0
	v_mov_b32_e32 v140, v0
	v_mov_b32_e32 v141, v0
	v_mov_b32_e32 v142, v0
	v_mov_b32_e32 v143, v0
	s_lshl_b32 s33, s58, 8
	s_add_i32 s33, s33, s77
	v_lshl_or_b32 v32, s56, 8, v176
	v_or_b32_e32 v40, s33, v174
	v_or_b32_e32 v34, v32, v175
	v_ashrrev_i32_e32 v41, 31, v40
	v_ashrrev_i32_e32 v35, 31, v34
	v_lshlrev_b64 v[54:55], 12, v[40:41]
	v_lshl_add_u64 v[42:43], s[16:17], 0, v[54:55]
	v_lshlrev_b64 v[48:49], 1, v[34:35]
	v_lshl_add_u64 v[34:35], v[42:43], 0, v[48:49]
	global_load_dwordx4 v[236:239], v[34:35], off
	v_or_b32_e32 v34, 8, v40
	v_ashrrev_i32_e32 v35, 31, v34
	v_or_b32_e32 v50, s33, v172
	v_lshlrev_b64 v[162:163], 12, v[34:35]
	v_ashrrev_i32_e32 v51, 31, v50
	v_lshl_add_u64 v[34:35], s[16:17], 0, v[162:163]
	v_lshl_add_u64 v[52:53], v[50:51], 2, s[40:41]
	v_lshl_add_u64 v[34:35], v[34:35], 0, v[48:49]
	global_load_dword v234, v[52:53], off
	v_lshl_add_u64 v[40:41], s[38:39], 0, v[54:55]
	global_load_dwordx4 v[240:243], v[34:35], off
	v_lshl_add_u64 v[34:35], s[38:39], 0, v[162:163]
	v_lshl_add_u64 v[40:41], v[40:41], 0, v[48:49]
	v_lshl_add_u64 v[34:35], v[34:35], 0, v[48:49]
	global_load_dwordx4 v[244:247], v[40:41], off
	global_load_dwordx4 v[248:251], v[34:35], off
; #define PG8_STAGE(bufoff, gbase, voff) do { _Pragma("unroll") for (int _i = 0; _i < 2; ++_i) \
;         __builtin_amdgcn_global_load_lds((const unsigned*)((const char*)(gbase) + (voff)[_i]), (LAS unsigned*)(lds + (bufoff) + ldsw + _i * 8192), 16, 0, 0); } while (0)
; #define PG8_LDA(dst, b, h) do { _Pragma("unroll") for (int m = 0; m < 4; ++m) _Pragma("unroll") for (int k = 0; k < 2; ++k) dst[m][k] = *(const LAS bf16x8*)(lds + PG8_SA(b, h) + aoff + m * 2048 + k * 1024); } while (0)
; #define PG8_LDB(dst, b, h) do { _Pragma("unroll") for (int n = 0; n < 2; ++n) _Pragma("unroll") for (int k = 0; k < 2; ++k) dst[n][k] = *(const LAS bf16x8*)(lds + PG8_SB(b, h) + boff + n * 2048 + k * 1024); } while (0)
; #define PG8_MMA(ai, bj, At, Bt) do { __builtin_amdgcn_s_setprio(1); _Pragma("unroll") for (int m = 0; m < 4; ++m) _Pragma("unroll") for (int n = 0; n < 2; ++n) _Pragma("unroll") for (int k = 0; k < 2; ++k) \
;         acc[ai][bj][m][n] = __builtin_amdgcn_mfma_f32_16x16x32_bf16(Bt[n][k], At[m][k], acc[ai][bj][m][n], 0, 0, 0); __builtin_amdgcn_s_setprio(0); } while (0)
; #define PG8_WAIT_V(n) asm volatile("s_waitcnt vmcnt(" #n ")" ::: "memory")
; #define PG8_WAIT_L(n) asm volatile("s_waitcnt lgkmcnt(" #n ")" ::: "memory")
; #define PG8_BAR __builtin_amdgcn_s_barrier()
; template <class Epi>
; __device__ __forceinline__ void gemm_phase(LAS unsigned char* lds, const Gemm g, const StaticOrder& S, const Epi& E) {
;     ...
;         for (int t = 0; t < nt; t += 2) {
;             const bool last = (t == nt - 2);
;             const char* a1 = cA + (size_t)(t + 1) * kstep;
;             const char* a2 = last ? nA : cA + (size_t)(t + 2) * kstep; const char* b2 = last ? nB : cB + (size_t)(t + 2) * kstep;
;             const char* a3 = a2 + kstep; const char* b3 = b2 + kstep;
;             PG8_LDB(B0, 0, 0); PG8_SCHED; PG8_LDA(At, 0, 0); PG8_STAGE(PG8_SA(1, 1), a1 + hstep, voffA);
;             PG8_WAIT_L(8); PG8_BAR; PG8_WAIT_L(0); PG8_MMA(0, 0, At, B0); PG8_BAR; PG8_SCHED;
;             PG8_LDB(B1, 0, 1); PG8_STAGE(PG8_SB(0, 0), b2, voffB0);
;             PG8_BAR; PG8_WAIT_L(0); PG8_MMA(0, 1, At, B1); PG8_BAR;
;             PG8_LDA(At, 0, 1); PG8_STAGE(PG8_SA(0, 0), a2, voffA);
;             PG8_BAR; PG8_WAIT_L(0); PG8_MMA(1, 0, At, B0); PG8_BAR; PG8_SCHED;
;             PG8_STAGE(PG8_SB(0, 1), b2, voffB1);
;             PG8_WAIT_V(6); PG8_BAR; PG8_MMA(1, 1, At, B1); PG8_BAR;
.LBB0_882:
	ds_read_b128 v[32:35], v177
	ds_read_b128 v[40:43], v177 offset:1024
	ds_read_b128 v[48:51], v177 offset:2048
	ds_read_b128 v[52:55], v177 offset:3072
	s_add_u32 s33, s60, 0xfff80080
	s_addc_u32 s62, s61, -1
	s_cmp_eq_u32 s86, 28
	s_cselect_b32 s63, s49, s62
	s_cselect_b32 s62, s57, s33
	s_cselect_b32 s65, s47, s85
	s_cselect_b32 s64, s83, s84
	v_lshl_add_u64 v[170:171], s[60:61], 0, v[156:157]
	s_add_i32 m0, s59, 0xc000
	ds_read_b128 v[162:165], v178
	ds_read_b128 v[166:169], v178 offset:1024
	ds_read_b128 v[182:185], v178 offset:2048
	ds_read_b128 v[186:189], v178 offset:3072
	ds_read_b128 v[190:193], v178 offset:4096
	ds_read_b128 v[194:197], v178 offset:5120
	ds_read_b128 v[198:201], v178 offset:6144
	ds_read_b128 v[204:207], v178 offset:7168
	global_load_lds_dwordx4 v[170:171], off
	v_lshl_add_u64 v[170:171], s[60:61], 0, v[158:159]
	s_add_i32 m0, s59, 0xe000
	s_nop 0
	global_load_lds_dwordx4 v[170:171], off
	s_waitcnt lgkmcnt(8)
	s_barrier
	s_waitcnt lgkmcnt(0)
	v_mfma_f32_16x16x32_bf16 v[140:143], v[32:35], v[162:165], v[140:143]
	v_mfma_f32_16x16x32_bf16 v[136:139], v[48:51], v[162:165], v[136:139]
	v_mfma_f32_16x16x32_bf16 v[124:127], v[32:35], v[182:185], v[124:127]
	v_mfma_f32_16x16x32_bf16 v[120:123], v[48:51], v[182:185], v[120:123]
	v_mfma_f32_16x16x32_bf16 v[108:111], v[32:35], v[190:193], v[108:111]
	v_mfma_f32_16x16x32_bf16 v[104:107], v[48:51], v[190:193], v[104:107]
	v_mfma_f32_16x16x32_bf16 v[92:95], v[32:35], v[198:201], v[92:95]
	v_mfma_f32_16x16x32_bf16 v[88:91], v[48:51], v[198:201], v[88:91]
	v_mfma_f32_16x16x32_bf16 v[140:143], v[40:43], v[166:169], v[140:143]
	v_mfma_f32_16x16x32_bf16 v[136:139], v[52:55], v[166:169], v[136:139]
	v_mfma_f32_16x16x32_bf16 v[124:127], v[40:43], v[186:189], v[124:127]
	v_mfma_f32_16x16x32_bf16 v[120:123], v[52:55], v[186:189], v[120:123]
	v_mfma_f32_16x16x32_bf16 v[108:111], v[40:43], v[194:197], v[108:111]
	v_mfma_f32_16x16x32_bf16 v[104:107], v[52:55], v[194:197], v[104:107]
	v_mfma_f32_16x16x32_bf16 v[92:95], v[40:43], v[204:207], v[92:95]
	v_mfma_f32_16x16x32_bf16 v[88:91], v[52:55], v[204:207], v[88:91]
	s_barrier
	s_add_i32 s33, s81, s69
	v_lshl_add_u64 v[170:171], s[64:65], 0, v[146:147]
	s_mov_b32 m0, s33
	ds_read_b128 v[208:211], v179
	ds_read_b128 v[212:215], v179 offset:1024
	ds_read_b128 v[216:219], v179 offset:2048
	ds_read_b128 v[220:223], v179 offset:3072
	global_load_lds_dwordx4 v[170:171], off
	v_lshl_add_u64 v[224:225], s[64:65], 0, v[152:153]
	s_add_i32 m0, s33, 0x2000
	s_nop 0
	global_load_lds_dwordx4 v[224:225], off
	s_barrier
	s_waitcnt lgkmcnt(0)
	v_mfma_f32_16x16x32_bf16 v[132:135], v[208:211], v[162:165], v[132:135]
	v_mfma_f32_16x16x32_bf16 v[128:131], v[216:219], v[162:165], v[128:131]
	v_mfma_f32_16x16x32_bf16 v[116:119], v[208:211], v[182:185], v[116:119]
	v_mfma_f32_16x16x32_bf16 v[112:115], v[216:219], v[182:185], v[112:115]
	v_mfma_f32_16x16x32_bf16 v[100:103], v[208:211], v[190:193], v[100:103]
	v_mfma_f32_16x16x32_bf16 v[96:99], v[216:219], v[190:193], v[96:99]
	v_mfma_f32_16x16x32_bf16 v[84:87], v[208:211], v[198:201], v[84:87]
	v_mfma_f32_16x16x32_bf16 v[80:83], v[216:219], v[198:201], v[80:83]
	v_mfma_f32_16x16x32_bf16 v[132:135], v[212:215], v[166:169], v[132:135]
	v_mfma_f32_16x16x32_bf16 v[128:131], v[220:223], v[166:169], v[128:131]
	v_mfma_f32_16x16x32_bf16 v[116:119], v[212:215], v[186:189], v[116:119]
	v_mfma_f32_16x16x32_bf16 v[112:115], v[220:223], v[186:189], v[112:115]
	v_mfma_f32_16x16x32_bf16 v[100:103], v[212:215], v[194:197], v[100:103]
	v_mfma_f32_16x16x32_bf16 v[96:99], v[220:223], v[194:197], v[96:99]
	v_mfma_f32_16x16x32_bf16 v[84:87], v[212:215], v[204:207], v[84:87]
	v_mfma_f32_16x16x32_bf16 v[80:83], v[220:223], v[204:207], v[80:83]
	s_mov_b32 m0, s59
	v_lshl_add_u64 v[226:227], s[62:63], 0, v[144:145]
	s_barrier
	ds_read_b128 v[162:165], v178 offset:16384
	ds_read_b128 v[166:169], v178 offset:17408
	ds_read_b128 v[182:185], v178 offset:18432
	ds_read_b128 v[186:189], v178 offset:19456
	ds_read_b128 v[190:193], v178 offset:20480
	ds_read_b128 v[194:197], v178 offset:21504
	ds_read_b128 v[198:201], v178 offset:22528
	ds_read_b128 v[204:207], v178 offset:23552
	global_load_lds_dwordx4 v[226:227], off
	v_lshl_add_u64 v[228:229], s[62:63], 0, v[150:151]
	s_mov_b32 m0, s70
	s_nop 0
	global_load_lds_dwordx4 v[228:229], off
	s_barrier
	s_waitcnt lgkmcnt(0)
	v_mfma_f32_16x16x32_bf16 v[76:79], v[32:35], v[162:165], v[76:79]
	v_mfma_f32_16x16x32_bf16 v[72:75], v[48:51], v[162:165], v[72:75]
	v_mfma_f32_16x16x32_bf16 v[60:63], v[32:35], v[182:185], v[60:63]
	v_mfma_f32_16x16x32_bf16 v[56:59], v[48:51], v[182:185], v[56:59]
	v_mfma_f32_16x16x32_bf16 v[28:31], v[32:35], v[190:193], v[28:31]
	v_mfma_f32_16x16x32_bf16 v[24:27], v[48:51], v[190:193], v[24:27]
	v_mfma_f32_16x16x32_bf16 v[12:15], v[32:35], v[198:201], v[12:15]
	v_mfma_f32_16x16x32_bf16 v[8:11], v[48:51], v[198:201], v[8:11]
	v_mfma_f32_16x16x32_bf16 v[76:79], v[40:43], v[166:169], v[76:79]
	v_mfma_f32_16x16x32_bf16 v[72:75], v[52:55], v[166:169], v[72:75]
	v_mfma_f32_16x16x32_bf16 v[60:63], v[40:43], v[186:189], v[60:63]
	v_mfma_f32_16x16x32_bf16 v[56:59], v[52:55], v[186:189], v[56:59]
	v_mfma_f32_16x16x32_bf16 v[28:31], v[40:43], v[194:197], v[28:31]
	v_mfma_f32_16x16x32_bf16 v[24:27], v[52:55], v[194:197], v[24:27]
	v_mfma_f32_16x16x32_bf16 v[12:15], v[40:43], v[204:207], v[12:15]
	v_mfma_f32_16x16x32_bf16 v[8:11], v[52:55], v[204:207], v[8:11]
	s_barrier
	s_add_i32 s33, s82, s69
	v_lshl_add_u64 v[230:231], s[64:65], 0, v[148:149]
	s_mov_b32 m0, s33
	v_lshl_add_u64 v[232:233], s[64:65], 0, v[154:155]
	global_load_lds_dwordx4 v[230:231], off
	s_add_i32 m0, s33, 0x2000
	s_nop 0
	global_load_lds_dwordx4 v[232:233], off
	s_waitcnt vmcnt(6)
	s_barrier
; #define PG8_STAGE(bufoff, gbase, voff) do { _Pragma("unroll") for (int _i = 0; _i < 2; ++_i) \
;         __builtin_amdgcn_global_load_lds((const unsigned*)((const char*)(gbase) + (voff)[_i]), (LAS unsigned*)(lds + (bufoff) + ldsw + _i * 8192), 16, 0, 0); } while (0)
; #define PG8_LDA(dst, b, h) do { _Pragma("unroll") for (int m = 0; m < 4; ++m) _Pragma("unroll") for (int k = 0; k < 2; ++k) dst[m][k] = *(const LAS bf16x8*)(lds + PG8_SA(b, h) + aoff + m * 2048 + k * 1024); } while (0)
; #define PG8_LDB(dst, b, h) do { _Pragma("unroll") for (int n = 0; n < 2; ++n) _Pragma("unroll") for (int k = 0; k < 2; ++k) dst[n][k] = *(const LAS bf16x8*)(lds + PG8_SB(b, h) + boff + n * 2048 + k * 1024); } while (0)
; #define PG8_MMA(ai, bj, At, Bt) do { __builtin_amdgcn_s_setprio(1); _Pragma("unroll") for (int m = 0; m < 4; ++m) _Pragma("unroll") for (int n = 0; n < 2; ++n) _Pragma("unroll") for (int k = 0; k < 2; ++k) \
;         acc[ai][bj][m][n] = __builtin_amdgcn_mfma_f32_16x16x32_bf16(Bt[n][k], At[m][k], acc[ai][bj][m][n], 0, 0, 0); __builtin_amdgcn_s_setprio(0); } while (0)
; #define PG8_WAIT_V(n) asm volatile("s_waitcnt vmcnt(" #n ")" ::: "memory")
; #define PG8_WAIT_L(n) asm volatile("s_waitcnt lgkmcnt(" #n ")" ::: "memory")
; #define PG8_BAR __builtin_amdgcn_s_barrier()
; #define PG8_SCHED __builtin_amdgcn_sched_barrier(0)
; template <class Epi>
; __device__ __forceinline__ void gemm_phase(LAS unsigned char* lds, const Gemm g, const StaticOrder& S, const Epi& E) {
;     ...
;             PG8_WAIT_V(6); PG8_BAR; PG8_MMA(1, 1, At, B1); PG8_BAR;
;             PG8_LDB(B0, 1, 0); PG8_SCHED; PG8_LDA(At, 1, 0); PG8_STAGE(PG8_SA(0, 1), a2 + hstep, voffA);
;             PG8_WAIT_L(8); PG8_BAR; PG8_WAIT_L(0); PG8_MMA(0, 0, At, B0); PG8_BAR; PG8_SCHED;
;             PG8_LDB(B1, 1, 1); PG8_STAGE(PG8_SB(1, 0), b3, voffB0);
;             PG8_BAR; PG8_WAIT_L(0); PG8_MMA(0, 1, At, B1); PG8_BAR;
;             PG8_LDA(At, 1, 1); PG8_STAGE(PG8_SA(1, 0), a3, voffA);
;             PG8_BAR; PG8_WAIT_L(0); PG8_MMA(1, 0, At, B0); PG8_BAR; PG8_SCHED;
	v_mfma_f32_16x16x32_bf16 v[44:47], v[208:211], v[182:185], v[44:47]
	v_mfma_f32_16x16x32_bf16 v[36:39], v[216:219], v[182:185], v[36:39]
	v_mfma_f32_16x16x32_bf16 v[20:23], v[208:211], v[190:193], v[20:23]
	v_mfma_f32_16x16x32_bf16 v[16:19], v[216:219], v[190:193], v[16:19]
	v_mfma_f32_16x16x32_bf16 v[4:7], v[208:211], v[198:201], v[4:7]
	v_mfma_f32_16x16x32_bf16 v[0:3], v[216:219], v[198:201], v[0:3]
	v_mfma_f32_16x16x32_bf16 v[32:35], v[208:211], v[162:165], v[68:71]
	v_mfma_f32_16x16x32_bf16 v[40:43], v[216:219], v[162:165], v[64:67]
	v_mfma_f32_16x16x32_bf16 v[44:47], v[212:215], v[186:189], v[44:47]
	v_mfma_f32_16x16x32_bf16 v[36:39], v[220:223], v[186:189], v[36:39]
	v_mfma_f32_16x16x32_bf16 v[20:23], v[212:215], v[194:197], v[20:23]
	v_mfma_f32_16x16x32_bf16 v[16:19], v[220:223], v[194:197], v[16:19]
	v_mfma_f32_16x16x32_bf16 v[4:7], v[212:215], v[204:207], v[4:7]
	v_mfma_f32_16x16x32_bf16 v[0:3], v[220:223], v[204:207], v[0:3]
	v_mfma_f32_16x16x32_bf16 v[32:35], v[212:215], v[166:169], v[32:35]
	v_mfma_f32_16x16x32_bf16 v[40:43], v[220:223], v[166:169], v[40:43]
	s_add_i32 s33, 0, 0x18000
	v_add_u32_e32 v68, s33, v173
	s_barrier
	ds_read_b128 v[48:51], v68
	ds_read_b128 v[52:55], v68 offset:1024
	ds_read_b128 v[64:67], v68 offset:2048
	ds_read_b128 v[68:71], v68 offset:3072
	s_add_u32 s62, s62, 0x80000
	s_addc_u32 s63, s63, 0
	s_mov_b32 m0, s71
	v_lshl_add_u64 v[208:209], s[62:63], 0, v[144:145]
	ds_read_b128 v[162:165], v178 offset:32768
	ds_read_b128 v[166:169], v178 offset:33792
	ds_read_b128 v[182:185], v178 offset:34816
	ds_read_b128 v[186:189], v178 offset:35840
	ds_read_b128 v[190:193], v178 offset:36864
	ds_read_b128 v[194:197], v178 offset:37888
	ds_read_b128 v[198:201], v178 offset:38912
	ds_read_b128 v[204:207], v178 offset:39936
	global_load_lds_dwordx4 v[208:209], off
	v_lshl_add_u64 v[208:209], s[62:63], 0, v[150:151]
	s_mov_b32 m0, s72
	s_nop 0
	global_load_lds_dwordx4 v[208:209], off
	s_waitcnt lgkmcnt(8)
	s_barrier
	s_waitcnt lgkmcnt(0)
	v_mfma_f32_16x16x32_bf16 v[140:143], v[48:51], v[162:165], v[140:143]
	v_mfma_f32_16x16x32_bf16 v[136:139], v[64:67], v[162:165], v[136:139]
	v_mfma_f32_16x16x32_bf16 v[124:127], v[48:51], v[182:185], v[124:127]
	v_mfma_f32_16x16x32_bf16 v[120:123], v[64:67], v[182:185], v[120:123]
	v_mfma_f32_16x16x32_bf16 v[108:111], v[48:51], v[190:193], v[108:111]
	v_mfma_f32_16x16x32_bf16 v[104:107], v[64:67], v[190:193], v[104:107]
	v_mfma_f32_16x16x32_bf16 v[92:95], v[48:51], v[198:201], v[92:95]
	v_mfma_f32_16x16x32_bf16 v[88:91], v[64:67], v[198:201], v[88:91]
	v_mfma_f32_16x16x32_bf16 v[140:143], v[52:55], v[166:169], v[140:143]
	v_mfma_f32_16x16x32_bf16 v[136:139], v[68:71], v[166:169], v[136:139]
	v_mfma_f32_16x16x32_bf16 v[124:127], v[52:55], v[186:189], v[124:127]
	v_mfma_f32_16x16x32_bf16 v[120:123], v[68:71], v[186:189], v[120:123]
	v_mfma_f32_16x16x32_bf16 v[108:111], v[52:55], v[194:197], v[108:111]
	v_mfma_f32_16x16x32_bf16 v[104:107], v[68:71], v[194:197], v[104:107]
	v_mfma_f32_16x16x32_bf16 v[92:95], v[52:55], v[204:207], v[92:95]
	v_mfma_f32_16x16x32_bf16 v[88:91], v[68:71], v[204:207], v[88:91]
	s_barrier
	s_add_i32 s62, 0, 0x1c000
	s_add_i32 s33, s33, s69
	v_add_u32_e32 v181, s62, v173
	v_lshl_add_u64 v[170:171], v[170:171], 0, s[42:43]
	s_mov_b32 m0, s33
	ds_read_b128 v[208:211], v181
	ds_read_b128 v[212:215], v181 offset:1024
	ds_read_b128 v[216:219], v181 offset:2048
	ds_read_b128 v[220:223], v181 offset:3072
	global_load_lds_dwordx4 v[170:171], off
	v_lshl_add_u64 v[170:171], v[224:225], 0, s[42:43]
	s_add_i32 m0, s33, 0x2000
	s_nop 0
	global_load_lds_dwordx4 v[170:171], off
	s_barrier
	s_waitcnt lgkmcnt(0)
	v_mfma_f32_16x16x32_bf16 v[132:135], v[208:211], v[162:165], v[132:135]
	v_mfma_f32_16x16x32_bf16 v[128:131], v[216:219], v[162:165], v[128:131]
	v_mfma_f32_16x16x32_bf16 v[116:119], v[208:211], v[182:185], v[116:119]
	v_mfma_f32_16x16x32_bf16 v[112:115], v[216:219], v[182:185], v[112:115]
	v_mfma_f32_16x16x32_bf16 v[100:103], v[208:211], v[190:193], v[100:103]
	v_mfma_f32_16x16x32_bf16 v[96:99], v[216:219], v[190:193], v[96:99]
	v_mfma_f32_16x16x32_bf16 v[84:87], v[208:211], v[198:201], v[84:87]
	v_mfma_f32_16x16x32_bf16 v[80:83], v[216:219], v[198:201], v[80:83]
	v_mfma_f32_16x16x32_bf16 v[132:135], v[212:215], v[166:169], v[132:135]
	v_mfma_f32_16x16x32_bf16 v[128:131], v[220:223], v[166:169], v[128:131]
	v_mfma_f32_16x16x32_bf16 v[116:119], v[212:215], v[186:189], v[116:119]
	v_mfma_f32_16x16x32_bf16 v[112:115], v[220:223], v[186:189], v[112:115]
	v_mfma_f32_16x16x32_bf16 v[100:103], v[212:215], v[194:197], v[100:103]
	v_mfma_f32_16x16x32_bf16 v[96:99], v[220:223], v[194:197], v[96:99]
	v_mfma_f32_16x16x32_bf16 v[84:87], v[212:215], v[204:207], v[84:87]
	v_mfma_f32_16x16x32_bf16 v[80:83], v[220:223], v[204:207], v[80:83]
	s_mov_b32 m0, s74
	v_lshl_add_u64 v[170:171], v[226:227], 0, s[42:43]
	s_barrier
	ds_read_b128 v[162:165], v178 offset:49152
	ds_read_b128 v[166:169], v178 offset:50176
	ds_read_b128 v[182:185], v178 offset:51200
	ds_read_b128 v[186:189], v178 offset:52224
	ds_read_b128 v[190:193], v178 offset:53248
	ds_read_b128 v[194:197], v178 offset:54272
	ds_read_b128 v[198:201], v178 offset:55296
	ds_read_b128 v[204:207], v178 offset:56320
	global_load_lds_dwordx4 v[170:171], off
	v_lshl_add_u64 v[170:171], v[228:229], 0, s[42:43]
	s_mov_b32 m0, s75
	s_nop 0
	global_load_lds_dwordx4 v[170:171], off
	s_barrier
; __device__ __forceinline__ float bflo(unsigned w) { return __uint_as_float(w << 16); }
; __device__ __forceinline__ float bfhi(unsigned w) { return __uint_as_float(w & 0xffff0000u); }
; #define PG8_STAGE(bufoff, gbase, voff) do { _Pragma("unroll") for (int _i = 0; _i < 2; ++_i) \
;         __builtin_amdgcn_global_load_lds((const unsigned*)((const char*)(gbase) + (voff)[_i]), (LAS unsigned*)(lds + (bufoff) + ldsw + _i * 8192), 16, 0, 0); } while (0)
; #define PG8_WAIT_V(n) asm volatile("s_waitcnt vmcnt(" #n ")" ::: "memory")
;     __device__ __forceinline__ void operator()(const f32x4 (&acc)[2][2][4][2], const Unit& u, int wr, int wc, int fr, int fq) const {
;     ...
;         f32x4 gv[2][2];
; #pragma unroll
;         for (int bj = 0; bj < 2; ++bj) { gv[bj][0] = *(const f32x4*)(g + col0 + 8 * bj); gv[bj][1] = *(const f32x4*)(g + col0 + 8 * bj + 4); }
; #pragma unroll
;         for (int ai = 0; ai < 2; ++ai)
; #pragma unroll
;             for (int m = 0; m < 4; ++m) { const int row = row0 + ai * HALF + m * 16; const size_t off = (size_t)row * D + col0; const float ri = __builtin_amdgcn_rsqf(sse[row] * (1.f / D) + EPS); float sq = 0.f; u32x4 w[2];
;                 u32x4 rr[2], ee[2]; load_pair_lines(R, D, row, fr, col0, rr[0], rr[1]); load_pair_lines(E, D, row, fr, col0, ee[0], ee[1]);
; #pragma unroll
;                 for (int bj = 0; bj < 2; ++bj) { const u32x4 rw = rr[bj], ew = ee[bj];
;                     const float r[8] = {bflo(rw.x), bfhi(rw.x), bflo(rw.y), bfhi(rw.y), bflo(rw.z), bfhi(rw.z), bflo(rw.w), bfhi(rw.w)};
;                     const float e[8] = {bflo(ew.x), bfhi(ew.x), bflo(ew.y), bfhi(ew.y), bflo(ew.z), bfhi(ew.z), bflo(ew.w), bfhi(ew.w)};
;                     float o[8];
; #pragma unroll
;                     for (int j = 0; j < 8; ++j) { const float a = acc[ai][bj][m][j >> 2][j & 3]; const float gg = gv[bj][j >> 2][j & 3];
;                         o[j] = r[j] + e[j] * ri * gg * __builtin_amdgcn_rcpf(1.f + __builtin_amdgcn_exp2f(-a * LOG2E)); }
; template <class Epi>
; __device__ __forceinline__ void gemm_phase(LAS unsigned char* lds, const Gemm g, const StaticOrder& S, const Epi& E) {
;     ...
;             PG8_BAR; PG8_WAIT_L(0); PG8_MMA(1, 0, At, B0); PG8_BAR; PG8_SCHED;
;             PG8_STAGE(PG8_SB(1, 1), b3, voffB1);
;             PG8_WAIT_V(6); PG8_BAR; PG8_MMA(1, 1, At, B1); PG8_BAR;
;         }
	s_waitcnt lgkmcnt(0)
	v_mfma_f32_16x16x32_bf16 v[76:79], v[48:51], v[162:165], v[76:79]
	v_mfma_f32_16x16x32_bf16 v[72:75], v[64:67], v[162:165], v[72:75]
	v_mfma_f32_16x16x32_bf16 v[60:63], v[48:51], v[182:185], v[60:63]
	v_mfma_f32_16x16x32_bf16 v[56:59], v[64:67], v[182:185], v[56:59]
	v_mfma_f32_16x16x32_bf16 v[28:31], v[48:51], v[190:193], v[28:31]
	v_mfma_f32_16x16x32_bf16 v[24:27], v[64:67], v[190:193], v[24:27]
	v_mfma_f32_16x16x32_bf16 v[12:15], v[48:51], v[198:201], v[12:15]
	v_mfma_f32_16x16x32_bf16 v[8:11], v[64:67], v[198:201], v[8:11]
	v_mfma_f32_16x16x32_bf16 v[76:79], v[52:55], v[166:169], v[76:79]
	v_mfma_f32_16x16x32_bf16 v[72:75], v[68:71], v[166:169], v[72:75]
	v_mfma_f32_16x16x32_bf16 v[60:63], v[52:55], v[186:189], v[60:63]
	v_mfma_f32_16x16x32_bf16 v[56:59], v[68:71], v[186:189], v[56:59]
	v_mfma_f32_16x16x32_bf16 v[28:31], v[52:55], v[194:197], v[28:31]
	v_mfma_f32_16x16x32_bf16 v[24:27], v[68:71], v[194:197], v[24:27]
	v_mfma_f32_16x16x32_bf16 v[12:15], v[52:55], v[204:207], v[12:15]
	v_mfma_f32_16x16x32_bf16 v[8:11], v[68:71], v[204:207], v[8:11]
	s_barrier
	s_add_i32 s33, s62, s69
	v_lshl_add_u64 v[48:49], v[230:231], 0, s[42:43]
	s_mov_b32 m0, s33
	s_nop 0
	global_load_lds_dwordx4 v[48:49], off
	v_lshl_add_u64 v[48:49], v[232:233], 0, s[42:43]
	s_add_i32 m0, s33, 0x2000
	s_nop 0
	global_load_lds_dwordx4 v[48:49], off
	s_waitcnt vmcnt(6)
	s_barrier
	v_mfma_f32_16x16x32_bf16 v[32:35], v[208:211], v[162:165], v[32:35]
	v_mfma_f32_16x16x32_bf16 v[68:71], v[212:215], v[166:169], v[32:35]
	v_mfma_f32_16x16x32_bf16 v[32:35], v[216:219], v[162:165], v[40:43]
	v_mfma_f32_16x16x32_bf16 v[64:67], v[220:223], v[166:169], v[32:35]
	v_mfma_f32_16x16x32_bf16 v[32:35], v[208:211], v[182:185], v[44:47]
	v_mfma_f32_16x16x32_bf16 v[44:47], v[212:215], v[186:189], v[32:35]
	v_mfma_f32_16x16x32_bf16 v[32:35], v[216:219], v[182:185], v[36:39]
	v_mfma_f32_16x16x32_bf16 v[20:23], v[208:211], v[190:193], v[20:23]
	v_mfma_f32_16x16x32_bf16 v[16:19], v[216:219], v[190:193], v[16:19]
	v_mfma_f32_16x16x32_bf16 v[4:7], v[208:211], v[198:201], v[4:7]
	v_mfma_f32_16x16x32_bf16 v[0:3], v[216:219], v[198:201], v[0:3]
	v_mfma_f32_16x16x32_bf16 v[36:39], v[220:223], v[186:189], v[32:35]
	v_mfma_f32_16x16x32_bf16 v[20:23], v[212:215], v[194:197], v[20:23]
	v_mfma_f32_16x16x32_bf16 v[16:19], v[220:223], v[194:197], v[16:19]
	v_mfma_f32_16x16x32_bf16 v[4:7], v[212:215], v[204:207], v[4:7]
	v_mfma_f32_16x16x32_bf16 v[0:3], v[220:223], v[204:207], v[0:3]
	s_add_i32 s86, s86, 2
	s_add_u32 s60, s60, 0x100
	s_addc_u32 s61, s61, 0
	s_add_u32 s84, s84, 0x100
	s_addc_u32 s85, s85, 0
	s_cmp_gt_u32 s86, 29
	s_barrier
	s_cbranch_scc0 .LBB0_882
	s_lshl_b32 s33, s58, 8
	s_add_i32 s33, s33, s77
	v_lshl_or_b32 v32, s56, 8, v176
	v_or_b32_e32 v40, s33, v174
	v_or_b32_e32 v34, v32, v175
	v_ashrrev_i32_e32 v41, 31, v40
	v_ashrrev_i32_e32 v35, 31, v34
	v_lshlrev_b64 v[168:169], 12, v[40:41]
	v_lshl_add_u64 v[42:43], s[16:17], 0, v[168:169]
	v_lshlrev_b64 v[162:163], 1, v[34:35]
	v_lshl_add_u64 v[34:35], v[42:43], 0, v[162:163]
	s_waitcnt vmcnt(8)
	s_nop 0
	v_mov_b64_e32 v[182:183], v[236:237]
	v_mov_b64_e32 v[184:185], v[238:239]
	s_nop 1
	v_or_b32_e32 v34, 8, v40
	v_ashrrev_i32_e32 v35, 31, v34
	v_or_b32_e32 v164, s33, v172
	v_lshlrev_b64 v[170:171], 12, v[34:35]
	v_ashrrev_i32_e32 v165, 31, v164
	v_lshl_add_u64 v[34:35], s[16:17], 0, v[170:171]
	v_lshl_add_u64 v[166:167], v[164:165], 2, s[40:41]
	v_lshl_add_u64 v[34:35], v[34:35], 0, v[162:163]
	s_nop 0
	v_mov_b32_e32 v181, v234
	s_nop 1
	v_lshl_add_u64 v[40:41], s[38:39], 0, v[168:169]
	s_nop 0
	v_mov_b64_e32 v[190:191], v[240:241]
	v_mov_b64_e32 v[192:193], v[242:243]
	s_nop 1
	v_lshl_add_u64 v[34:35], s[38:39], 0, v[170:171]
	v_lshl_add_u64 v[40:41], v[40:41], 0, v[162:163]
	v_lshl_add_u64 v[34:35], v[34:35], 0, v[162:163]
	s_nop 0
	v_mov_b64_e32 v[186:187], v[244:245]
	v_mov_b64_e32 v[188:189], v[246:247]
	s_nop 1
	s_nop 0
	v_mov_b64_e32 v[194:195], v[248:249]
	v_mov_b64_e32 v[196:197], v[250:251]
	s_nop 1
	v_ashrrev_i32_e32 v33, 31, v32
	v_lshl_add_u64 v[40:41], v[32:33], 2, s[10:11]
	global_load_dwordx4 v[52:55], v[40:41], off
	global_load_dwordx4 v[48:51], v[40:41], off offset:16
	global_load_dwordx4 v[32:35], v[40:41], off offset:48
	s_nop 0
	global_load_dwordx4 v[40:43], v[40:41], off offset:32
	v_or_b32_e32 v216, 16, v164
	v_ashrrev_i32_e32 v217, 31, v216
	v_lshl_add_u64 v[218:219], v[216:217], 2, s[40:41]
	global_load_dword v226, v[218:219], off
	v_sub_u32_e32 v218, v216, v172
	v_add_u32_e32 v218, v218, v174
	v_ashrrev_i32_e32 v219, 31, v218
	v_lshlrev_b64 v[218:219], 12, v[218:219]
	v_lshl_add_u64 v[220:221], s[16:17], 0, v[218:219]
	v_lshl_add_u64 v[220:221], v[220:221], 0, v[162:163]
	global_load_dwordx4 v[228:231], v[220:221], off
	v_lshl_add_u64 v[220:221], s[38:39], 0, v[218:219]
	v_lshl_add_u64 v[220:221], v[220:221], 0, v[162:163]
	global_load_dwordx4 v[232:235], v[220:221], off
	v_lshl_add_u64 v[220:221], v[218:219], 0, s[44:45]
	v_lshl_add_u64 v[224:225], s[38:39], 0, v[220:221]
	v_lshl_add_u64 v[222:223], s[16:17], 0, v[220:221]
	v_lshl_add_u64 v[224:225], v[224:225], 0, v[162:163]
	v_lshl_add_u64 v[222:223], v[222:223], 0, v[162:163]
	global_load_dwordx4 v[236:239], v[224:225], off
	global_load_dwordx4 v[240:243], v[222:223], off
	v_mul_f32_e32 v140, 0xbfb8aa3b, v140
	v_exp_f32_e32 v140, v140
	v_mul_f32_e32 v141, 0xbfb8aa3b, v141
	v_exp_f32_e32 v141, v141
	v_add_f32_e32 v140, 1.0, v140
	v_rcp_f32_e32 v140, v140
	v_add_f32_e32 v141, 1.0, v141
	v_rcp_f32_e32 v141, v141
	v_mul_f32_e32 v136, 0xbfb8aa3b, v136
	v_exp_f32_e32 v136, v136
	v_mul_f32_e32 v137, 0xbfb8aa3b, v137
	v_exp_f32_e32 v137, v137
	v_add_f32_e32 v136, 1.0, v136
	v_rcp_f32_e32 v136, v136
	v_add_f32_e32 v137, 1.0, v137
	v_mul_f32_e32 v132, 0xbfb8aa3b, v132
	v_rcp_f32_e32 v137, v137
	v_exp_f32_e32 v132, v132
	v_mul_f32_e32 v133, 0xbfb8aa3b, v133
	v_exp_f32_e32 v133, v133
	v_add_f32_e32 v132, 1.0, v132
	v_rcp_f32_e32 v132, v132
	v_add_f32_e32 v133, 1.0, v133
	v_rcp_f32_e32 v133, v133
	v_mul_f32_e32 v128, 0xbfb8aa3b, v128
	v_exp_f32_e32 v128, v128
	v_mul_f32_e32 v129, 0xbfb8aa3b, v129
	v_exp_f32_e32 v129, v129
	v_add_f32_e32 v128, 1.0, v128
	v_rcp_f32_e32 v128, v128
	v_add_f32_e32 v129, 1.0, v129
	v_rcp_f32_e32 v129, v129
	s_waitcnt vmcnt(5)
; __device__ __forceinline__ unsigned cvt_pk_bf16(float lo, float hi) { unsigned r; asm volatile("v_cvt_pk_bf16_f32 %0, %1, %2" : "=v"(r) : "v"(lo), "v"(hi)); return r; }
; __device__ __forceinline__ float bflo(unsigned w) { return __uint_as_float(w << 16); }
; __device__ __forceinline__ float bfhi(unsigned w) { return __uint_as_float(w & 0xffff0000u); }
;     __device__ __forceinline__ void operator()(const f32x4 (&acc)[2][2][4][2], const Unit& u, int wr, int wc, int fr, int fq) const {
;     ...
;                 for (int bj = 0; bj < 2; ++bj) { const u32x4 rw = rr[bj], ew = ee[bj];
;                     const float r[8] = {bflo(rw.x), bfhi(rw.x), bflo(rw.y), bfhi(rw.y), bflo(rw.z), bfhi(rw.z), bflo(rw.w), bfhi(rw.w)};
;                     const float e[8] = {bflo(ew.x), bfhi(ew.x), bflo(ew.y), bfhi(ew.y), bflo(ew.z), bfhi(ew.z), bflo(ew.w), bfhi(ew.w)};
;                     float o[8];
; #pragma unroll
;                     for (int j = 0; j < 8; ++j) { const float a = acc[ai][bj][m][j >> 2][j & 3]; const float gg = gv[bj][j >> 2][j & 3];
;                         o[j] = r[j] + e[j] * ri * gg * __builtin_amdgcn_rcpf(1.f + __builtin_amdgcn_exp2f(-a * LOG2E)); }
;                     if (OUT) { *(f32x4*)(OUT + off + 8 * bj) = (f32x4){o[0], o[1], o[2], o[3]}; *(f32x4*)(OUT + off + 8 * bj + 4) = (f32x4){o[4], o[5], o[6], o[7]}; }
;                     else { sq += (o[0] * o[0] + o[1] * o[1]) + (o[2] * o[2] + o[3] * o[3]) + (o[4] * o[4] + o[5] * o[5]) + (o[6] * o[6] + o[7] * o[7]);
;                         w[bj].x = cvt_pk_bf16(o[0], o[1]); w[bj].y = cvt_pk_bf16(o[2], o[3]); w[bj].z = cvt_pk_bf16(o[4], o[5]); w[bj].w = cvt_pk_bf16(o[6], o[7]); } }
	v_mov_b32_dpp v198, v182 row_ror:8 row_mask:0xf bank_mask:0xf
	v_mov_b32_dpp v199, v183 row_ror:8 row_mask:0xf bank_mask:0xf
	v_mov_b32_dpp v200, v184 row_ror:8 row_mask:0xf bank_mask:0xf
	v_mov_b32_dpp v201, v185 row_ror:8 row_mask:0xf bank_mask:0xf
	v_fmamk_f32 v181, v181, 0x3a000000, v180
	v_rsq_f32_e32 v181, v181
	v_mov_b32_dpp v204, v190 row_ror:8 row_mask:0xf bank_mask:0xf
	v_cndmask_b32_e64 v182, v204, v182, s[6:7]
	v_cndmask_b32_e64 v190, v190, v198, s[6:7]
	v_lshlrev_b32_e32 v198, 16, v182
	v_mov_b32_dpp v208, v186 row_ror:8 row_mask:0xf bank_mask:0xf
	v_mov_b32_dpp v212, v194 row_ror:8 row_mask:0xf bank_mask:0xf
	v_cndmask_b32_e64 v186, v212, v186, s[6:7]
	v_lshlrev_b32_e32 v204, 16, v186
	v_mul_f32_e32 v204, v181, v204
	v_and_b32_e32 v186, 0xffff0000, v186
	v_mul_f32_e32 v204, v52, v204
	v_fmac_f32_e32 v198, v140, v204
	v_mul_f32_e32 v140, v181, v186
	v_and_b32_e32 v182, 0xffff0000, v182
	v_mul_f32_e32 v140, v53, v140
	v_fmac_f32_e32 v182, v141, v140
	v_mul_f32_e32 v140, 0xbfb8aa3b, v142
	v_exp_f32_e32 v140, v140
	v_mul_f32_e32 v142, 0xbfb8aa3b, v143
	v_exp_f32_e32 v142, v142
	v_mov_b32_dpp v213, v195 row_ror:8 row_mask:0xf bank_mask:0xf
	v_add_f32_e32 v140, 1.0, v140
	v_mov_b32_dpp v209, v187 row_ror:8 row_mask:0xf bank_mask:0xf
	v_mov_b32_dpp v205, v191 row_ror:8 row_mask:0xf bank_mask:0xf
	v_cndmask_b32_e64 v187, v213, v187, s[6:7]
	v_rcp_f32_e32 v140, v140
	v_cndmask_b32_e64 v183, v205, v183, s[6:7]
	v_lshlrev_b32_e32 v205, 16, v187
	v_add_f32_e32 v142, 1.0, v142
	v_mul_f32_e32 v141, v181, v205
	v_rcp_f32_e32 v142, v142
	v_cndmask_b32_e64 v191, v191, v199, s[6:7]
	v_mov_b32_dpp v214, v196 row_ror:8 row_mask:0xf bank_mask:0xf
	v_lshlrev_b32_e32 v199, 16, v183
	v_and_b32_e32 v187, 0xffff0000, v187
	v_mul_f32_e32 v141, v54, v141
	v_mov_b32_dpp v210, v188 row_ror:8 row_mask:0xf bank_mask:0xf
	v_mov_b32_dpp v206, v192 row_ror:8 row_mask:0xf bank_mask:0xf
	v_cndmask_b32_e64 v188, v214, v188, s[6:7]
	v_fmac_f32_e32 v199, v140, v141
	v_mul_f32_e32 v140, v181, v187
	v_cndmask_b32_e64 v184, v206, v184, s[6:7]
	v_and_b32_e32 v183, 0xffff0000, v183
	v_lshlrev_b32_e32 v206, 16, v188
	v_mul_f32_e32 v140, v55, v140
	v_fmac_f32_e32 v183, v142, v140
	v_mul_f32_e32 v140, v181, v206
	v_cndmask_b32_e64 v192, v192, v200, s[6:7]
	v_lshlrev_b32_e32 v200, 16, v184
	v_and_b32_e32 v188, 0xffff0000, v188
	v_mul_f32_e32 v140, v48, v140
	v_fmac_f32_e32 v200, v136, v140
	v_mul_f32_e32 v136, v181, v188
	v_and_b32_e32 v184, 0xffff0000, v184
	v_mul_f32_e32 v136, v49, v136
	v_fmac_f32_e32 v184, v137, v136
	v_mul_f32_e32 v136, 0xbfb8aa3b, v138
	v_cndmask_b32_e64 v194, v194, v208, s[6:7]
	v_exp_f32_e32 v136, v136
	v_mul_f32_e32 v138, 0xbfb8aa3b, v139
	v_lshlrev_b32_e32 v187, 16, v194
	v_exp_f32_e32 v138, v138
	v_mul_f32_e32 v187, v181, v187
	v_lshlrev_b32_e32 v141, 16, v190
	v_and_b32_e32 v188, 0xffff0000, v194
	v_mul_f32_e32 v187, v40, v187
	v_mov_b32_dpp v215, v197 row_ror:8 row_mask:0xf bank_mask:0xf
	v_add_f32_e32 v136, 1.0, v136
	v_fmac_f32_e32 v141, v132, v187
	v_mul_f32_e32 v132, v181, v188
	v_mov_b32_dpp v211, v189 row_ror:8 row_mask:0xf bank_mask:0xf
	v_mov_b32_dpp v207, v193 row_ror:8 row_mask:0xf bank_mask:0xf
	v_cndmask_b32_e64 v189, v215, v189, s[6:7]
	v_rcp_f32_e32 v136, v136
	v_and_b32_e32 v142, 0xffff0000, v190
	v_mul_f32_e32 v132, v41, v132
	v_cndmask_b32_e64 v185, v207, v185, s[6:7]
	v_lshlrev_b32_e32 v207, 16, v189
	v_add_f32_e32 v138, 1.0, v138
	v_fmac_f32_e32 v142, v133, v132
	v_mul_f32_e32 v132, 0xbfb8aa3b, v134
	v_mul_f32_e32 v137, v181, v207
	v_rcp_f32_e32 v138, v138
	v_exp_f32_e32 v132, v132
	v_cndmask_b32_e64 v193, v193, v201, s[6:7]
	v_lshlrev_b32_e32 v201, 16, v185
	v_and_b32_e32 v189, 0xffff0000, v189
	v_mul_f32_e32 v137, v50, v137
	v_mul_f32_e32 v134, 0xbfb8aa3b, v135
	v_fmac_f32_e32 v201, v136, v137
	v_mul_f32_e32 v136, v181, v189
	v_exp_f32_e32 v134, v134
	v_and_b32_e32 v185, 0xffff0000, v185
	v_mul_f32_e32 v136, v51, v136
	v_fmac_f32_e32 v185, v138, v136
	v_mul_f32_e32 v136, v182, v182
	v_mul_f32_e32 v137, v183, v183
	v_add_f32_e32 v132, 1.0, v132
	v_cndmask_b32_e64 v195, v195, v209, s[6:7]
	v_fmac_f32_e32 v136, v198, v198
	v_fmac_f32_e32 v137, v199, v199
	v_rcp_f32_e32 v132, v132
	v_add_f32_e32 v136, v136, v137
	v_mul_f32_e32 v137, v184, v184
	v_lshlrev_b32_e32 v189, 16, v195
	v_add_f32_e32 v134, 1.0, v134
	v_fmac_f32_e32 v137, v200, v200
	v_mul_f32_e32 v133, v181, v189
	v_rcp_f32_e32 v134, v134
	v_add_f32_e32 v136, v137, v136
	v_mul_f32_e32 v137, v185, v185
	v_lshlrev_b32_e32 v143, 16, v191
	v_and_b32_e32 v190, 0xffff0000, v195
	v_mul_f32_e32 v133, v42, v133
	v_cndmask_b32_e64 v196, v196, v210, s[6:7]
	v_fmac_f32_e32 v137, v201, v201
	v_fmac_f32_e32 v143, v132, v133
	v_mul_f32_e32 v132, v181, v190
	v_add_f32_e32 v136, v137, v136
	v_cvt_pk_bf16_f32 v137, v198, v182
	v_and_b32_e32 v182, 0xffff0000, v191
	v_lshlrev_b32_e32 v191, 16, v196
	v_mul_f32_e32 v132, v43, v132
	v_fmac_f32_e32 v182, v134, v132
	v_mul_f32_e32 v132, v181, v191
	v_cvt_pk_bf16_f32 v138, v199, v183
	v_cvt_pk_bf16_f32 v139, v200, v184
	v_lshlrev_b32_e32 v183, 16, v192
	v_and_b32_e32 v184, 0xffff0000, v192
	v_and_b32_e32 v192, 0xffff0000, v196
	v_mul_f32_e32 v132, v32, v132
	v_fmac_f32_e32 v183, v128, v132
	v_mul_f32_e32 v128, v181, v192
	v_mul_f32_e32 v128, v33, v128
	v_fmac_f32_e32 v184, v129, v128
	v_mul_f32_e32 v128, 0xbfb8aa3b, v130
	v_exp_f32_e32 v128, v128
	v_mul_f32_e32 v130, 0xbfb8aa3b, v131
	v_exp_f32_e32 v130, v130
	v_cndmask_b32_e64 v197, v197, v211, s[6:7]
	v_add_f32_e32 v128, 1.0, v128
	v_rcp_f32_e32 v128, v128
	v_cvt_pk_bf16_f32 v140, v201, v185
	v_lshlrev_b32_e32 v185, 16, v193
	v_and_b32_e32 v186, 0xffff0000, v193
	v_lshlrev_b32_e32 v193, 16, v197
; __device__ __forceinline__ unsigned cvt_pk_bf16(float lo, float hi) { unsigned r; asm volatile("v_cvt_pk_bf16_f32 %0, %1, %2" : "=v"(r) : "v"(lo), "v"(hi)); return r; }
;     __device__ __forceinline__ void operator()(const f32x4 (&acc)[2][2][4][2], const Unit& u, int wr, int wc, int fr, int fq) const {
;     ...
;             for (int m = 0; m < 4; ++m) { const int row = row0 + ai * HALF + m * 16; const size_t off = (size_t)row * D + col0; const float ri = __builtin_amdgcn_rsqf(sse[row] * (1.f / D) + EPS); float sq = 0.f; u32x4 w[2];
;                 u32x4 rr[2], ee[2]; load_pair_lines(R, D, row, fr, col0, rr[0], rr[1]); load_pair_lines(E, D, row, fr, col0, ee[0], ee[1]);
;     ...
;                     else { sq += (o[0] * o[0] + o[1] * o[1]) + (o[2] * o[2] + o[3] * o[3]) + (o[4] * o[4] + o[5] * o[5]) + (o[6] * o[6] + o[7] * o[7]);
;                         w[bj].x = cvt_pk_bf16(o[0], o[1]); w[bj].y = cvt_pk_bf16(o[2], o[3]); w[bj].z = cvt_pk_bf16(o[4], o[5]); w[bj].w = cvt_pk_bf16(o[6], o[7]); } }
;                 if (!OUT) { store_pair_lines(O, D, row, fr, col0, w[0], w[1]);
;                     sq += __shfl_xor(sq, 16); sq += __shfl_xor(sq, 32); if (fq == 0) unsafeAtomicAdd(ssout + row, sq); } }
	v_add_f32_e32 v130, 1.0, v130
	v_mul_f32_e32 v129, v181, v193
	v_rcp_f32_e32 v130, v130
	v_and_b32_e32 v194, 0xffff0000, v197
	v_mul_f32_e32 v129, v34, v129
	v_fmac_f32_e32 v185, v128, v129
	v_mul_f32_e32 v128, v181, v194
	v_mul_f32_e32 v128, v35, v128
	v_fmac_f32_e32 v186, v130, v128
	v_mul_f32_e32 v128, v142, v142
	v_mul_f32_e32 v129, v182, v182
	v_fmac_f32_e32 v128, v141, v141
	v_fmac_f32_e32 v129, v143, v143
	v_add_f32_e32 v128, v128, v129
	v_mul_f32_e32 v129, v184, v184
	v_fmac_f32_e32 v129, v183, v183
	v_add_f32_e32 v128, v129, v128
	v_mul_f32_e32 v129, v186, v186
	v_fmac_f32_e32 v129, v185, v185
	v_add_f32_e32 v128, v129, v128
	v_add_f32_e32 v135, v128, v136
	v_cvt_pk_bf16_f32 v128, v141, v142
	v_cvt_pk_bf16_f32 v129, v143, v182
	v_mov_b32_dpp v143, v138 row_ror:8 row_mask:0xf bank_mask:0xf
	v_mov_b32_dpp v130, v128 row_ror:8 row_mask:0xf bank_mask:0xf
	v_mov_b32_dpp v134, v137 row_ror:8 row_mask:0xf bank_mask:0xf
	v_cndmask_b32_e64 v130, v130, v137, s[6:7]
	v_mov_b32_dpp v131, v129 row_ror:8 row_mask:0xf bank_mask:0xf
	v_cndmask_b32_e64 v137, v129, v143, s[6:7]
	v_and_b32_e32 v129, 64, v203
	v_cndmask_b32_e64 v136, v128, v134, s[6:7]
	v_xor_b32_e32 v128, 16, v203
	v_add_u32_e32 v143, 64, v129
	v_cmp_lt_i32_e32 vcc, v128, v143
	v_cvt_pk_bf16_f32 v141, v183, v184
	v_mov_b32_e32 v181, 0
	v_mov_b32_e32 v133, 0
	v_cndmask_b32_e32 v128, v203, v128, vcc
	v_lshlrev_b32_e32 v134, 2, v128
	v_mov_b32_e32 v183, v135
	s_nop 1
	v_permlane16_swap_b32_e32 v183, v135
	v_cvt_pk_bf16_f32 v142, v185, v186
	v_mov_b32_dpp v181, v139 row_ror:8 row_mask:0xf bank_mask:0xf
	v_mov_b32_e32 v182, 0
	v_mov_b32_dpp v133, v142 row_ror:8 row_mask:0xf bank_mask:0xf
	v_lshl_add_u64 v[128:129], s[36:37], 0, v[168:169]
	v_mov_b32_dpp v182, v140 row_ror:8 row_mask:0xf bank_mask:0xf
	v_mov_b32_dpp v132, v141 row_ror:8 row_mask:0xf bank_mask:0xf
	v_cndmask_b32_e64 v131, v131, v138, s[6:7]
	v_cndmask_b32_e64 v133, v133, v140, s[6:7]
	v_cndmask_b32_e64 v138, v141, v181, s[6:7]
	v_lshl_add_u64 v[140:141], v[128:129], 0, v[162:163]
	v_xor_b32_e32 v129, 32, v203
	v_cmp_lt_i32_e32 vcc, v129, v143
	s_waitcnt lgkmcnt(0)
	v_add_f32_e32 v128, v135, v183
	v_cndmask_b32_e64 v132, v132, v139, s[6:7]
	v_cndmask_b32_e32 v129, v203, v129, vcc
	v_lshlrev_b32_e32 v135, 2, v129
	v_mov_b32_e32 v129, v128
	s_nop 1
	v_permlane32_swap_b32_e32 v129, v128
	global_store_dwordx4 v[140:141], v[130:133], off
	v_cndmask_b32_e64 v139, v142, v182, s[6:7]
	s_nop 0
	v_lshl_add_u64 v[130:131], s[36:37], 0, v[170:171]
	v_lshl_add_u64 v[130:131], v[130:131], 0, v[162:163]
	global_store_dwordx4 v[130:131], v[136:139], off
	s_and_saveexec_b64 s[56:57], s[8:9]
	s_cbranch_execz .LBB0_885
	v_lshl_add_u64 v[130:131], v[164:165], 2, s[18:19]
	s_waitcnt lgkmcnt(0)
	v_add_f32_e32 v128, v128, v129
	global_atomic_add_f32 v[130:131], v128, off
.LBB0_885:
	s_or_b64 exec, exec, s[56:57]
	v_or_b32_e32 v128, 16, v164
	s_waitcnt lgkmcnt(0)
	v_ashrrev_i32_e32 v129, 31, v128
	v_lshl_add_u64 v[130:131], v[128:129], 2, s[40:41]
	s_waitcnt vmcnt(2)
	s_nop 0
	v_mov_b32_e32 v165, v226
	v_sub_u32_e32 v130, v128, v172
	v_add_u32_e32 v130, v130, v174
	v_ashrrev_i32_e32 v131, 31, v130
	v_lshlrev_b64 v[130:131], 12, v[130:131]
	v_lshl_add_u64 v[132:133], s[16:17], 0, v[130:131]
	v_lshl_add_u64 v[132:133], v[132:133], 0, v[162:163]
	v_mov_b64_e32 v[136:137], v[228:229]
	v_mov_b64_e32 v[138:139], v[230:231]
	v_lshl_add_u64 v[132:133], s[38:39], 0, v[130:131]
	v_lshl_add_u64 v[132:133], v[132:133], 0, v[162:163]
	v_mov_b64_e32 v[140:141], v[232:233]
	v_mov_b64_e32 v[142:143], v[234:235]
	v_lshl_add_u64 v[132:133], v[130:131], 0, s[44:45]
	v_lshl_add_u64 v[182:183], s[38:39], 0, v[132:133]
	v_lshl_add_u64 v[168:169], s[16:17], 0, v[132:133]
	v_lshl_add_u64 v[182:183], v[182:183], 0, v[162:163]
	v_lshl_add_u64 v[168:169], v[168:169], 0, v[162:163]
	v_mov_b64_e32 v[182:183], v[236:237]
	v_mov_b64_e32 v[184:185], v[238:239]
	v_mul_f32_e32 v124, 0xbfb8aa3b, v124
	v_mov_b64_e32 v[168:169], v[240:241]
	v_mov_b64_e32 v[170:171], v[242:243]
	s_nop 1
	v_or_b32_e32 v216, 32, v164
	v_ashrrev_i32_e32 v217, 31, v216
	v_lshl_add_u64 v[218:219], v[216:217], 2, s[40:41]
	global_load_dword v226, v[218:219], off
	v_sub_u32_e32 v218, v216, v172
	v_add_u32_e32 v218, v218, v174
	v_ashrrev_i32_e32 v219, 31, v218
	v_lshlrev_b64 v[218:219], 12, v[218:219]
	v_lshl_add_u64 v[220:221], s[16:17], 0, v[218:219]
	v_lshl_add_u64 v[220:221], v[220:221], 0, v[162:163]
	global_load_dwordx4 v[228:231], v[220:221], off
	v_lshl_add_u64 v[220:221], s[38:39], 0, v[218:219]
	v_lshl_add_u64 v[220:221], v[220:221], 0, v[162:163]
	global_load_dwordx4 v[232:235], v[220:221], off
	v_lshl_add_u64 v[220:221], v[218:219], 0, s[44:45]
	v_lshl_add_u64 v[224:225], s[38:39], 0, v[220:221]
	v_lshl_add_u64 v[222:223], s[16:17], 0, v[220:221]
	v_lshl_add_u64 v[224:225], v[224:225], 0, v[162:163]
	v_lshl_add_u64 v[222:223], v[222:223], 0, v[162:163]
	global_load_dwordx4 v[236:239], v[224:225], off
	global_load_dwordx4 v[240:243], v[222:223], off
	v_exp_f32_e32 v124, v124
	v_mul_f32_e32 v125, 0xbfb8aa3b, v125
	v_exp_f32_e32 v125, v125
	v_add_f32_e32 v124, 1.0, v124
	v_rcp_f32_e32 v124, v124
	v_add_f32_e32 v125, 1.0, v125
	v_rcp_f32_e32 v125, v125
	v_mul_f32_e32 v120, 0xbfb8aa3b, v120
	v_exp_f32_e32 v120, v120
	v_mul_f32_e32 v121, 0xbfb8aa3b, v121
	v_exp_f32_e32 v121, v121
	v_add_f32_e32 v120, 1.0, v120
	v_rcp_f32_e32 v120, v120
	v_add_f32_e32 v121, 1.0, v121
	v_mul_f32_e32 v116, 0xbfb8aa3b, v116
	v_rcp_f32_e32 v121, v121
	v_exp_f32_e32 v116, v116
	v_mul_f32_e32 v117, 0xbfb8aa3b, v117
	v_exp_f32_e32 v117, v117
	v_add_f32_e32 v116, 1.0, v116
	v_rcp_f32_e32 v116, v116
	v_add_f32_e32 v117, 1.0, v117
	v_rcp_f32_e32 v117, v117
	v_mul_f32_e32 v112, 0xbfb8aa3b, v112
	v_exp_f32_e32 v112, v112
	v_mul_f32_e32 v113, 0xbfb8aa3b, v113
	v_exp_f32_e32 v113, v113
	v_add_f32_e32 v112, 1.0, v112
	v_rcp_f32_e32 v112, v112
	v_add_f32_e32 v113, 1.0, v113
	v_rcp_f32_e32 v113, v113
	s_waitcnt vmcnt(12)
; __device__ __forceinline__ unsigned cvt_pk_bf16(float lo, float hi) { unsigned r; asm volatile("v_cvt_pk_bf16_f32 %0, %1, %2" : "=v"(r) : "v"(lo), "v"(hi)); return r; }
; __device__ __forceinline__ float bflo(unsigned w) { return __uint_as_float(w << 16); }
; __device__ __forceinline__ float bfhi(unsigned w) { return __uint_as_float(w & 0xffff0000u); }
;     __device__ __forceinline__ void operator()(const f32x4 (&acc)[2][2][4][2], const Unit& u, int wr, int wc, int fr, int fq) const {
;     ...
;                 for (int bj = 0; bj < 2; ++bj) { const u32x4 rw = rr[bj], ew = ee[bj];
;                     const float r[8] = {bflo(rw.x), bfhi(rw.x), bflo(rw.y), bfhi(rw.y), bflo(rw.z), bfhi(rw.z), bflo(rw.w), bfhi(rw.w)};
;                     const float e[8] = {bflo(ew.x), bfhi(ew.x), bflo(ew.y), bfhi(ew.y), bflo(ew.z), bfhi(ew.z), bflo(ew.w), bfhi(ew.w)};
;                     float o[8];
; #pragma unroll
;                     for (int j = 0; j < 8; ++j) { const float a = acc[ai][bj][m][j >> 2][j & 3]; const float gg = gv[bj][j >> 2][j & 3];
;                         o[j] = r[j] + e[j] * ri * gg * __builtin_amdgcn_rcpf(1.f + __builtin_amdgcn_exp2f(-a * LOG2E)); }
;                     if (OUT) { *(f32x4*)(OUT + off + 8 * bj) = (f32x4){o[0], o[1], o[2], o[3]}; *(f32x4*)(OUT + off + 8 * bj + 4) = (f32x4){o[4], o[5], o[6], o[7]}; }
;                     else { sq += (o[0] * o[0] + o[1] * o[1]) + (o[2] * o[2] + o[3] * o[3]) + (o[4] * o[4] + o[5] * o[5]) + (o[6] * o[6] + o[7] * o[7]);
;                         w[bj].x = cvt_pk_bf16(o[0], o[1]); w[bj].y = cvt_pk_bf16(o[2], o[3]); w[bj].z = cvt_pk_bf16(o[4], o[5]); w[bj].w = cvt_pk_bf16(o[6], o[7]); } }
	v_fmamk_f32 v165, v165, 0x3a000000, v180
	v_rsq_f32_e32 v165, v165
	s_waitcnt vmcnt(12)
	v_mov_b32_dpp v181, v136 row_ror:8 row_mask:0xf bank_mask:0xf
	v_mov_b32_dpp v186, v137 row_ror:8 row_mask:0xf bank_mask:0xf
	v_mov_b32_dpp v187, v138 row_ror:8 row_mask:0xf bank_mask:0xf
	s_waitcnt vmcnt(12)
	v_mov_b32_dpp v193, v140 row_ror:8 row_mask:0xf bank_mask:0xf
	v_mov_b32_dpp v196, v143 row_ror:8 row_mask:0xf bank_mask:0xf
	v_mov_b32_dpp v194, v141 row_ror:8 row_mask:0xf bank_mask:0xf
	v_mov_b32_dpp v195, v142 row_ror:8 row_mask:0xf bank_mask:0xf
	v_mov_b32_dpp v188, v139 row_ror:8 row_mask:0xf bank_mask:0xf
	s_waitcnt vmcnt(12)
	v_mov_b32_dpp v197, v182 row_ror:8 row_mask:0xf bank_mask:0xf
	v_cndmask_b32_e64 v140, v197, v140, s[6:7]
	s_waitcnt vmcnt(12)
	v_mov_b32_dpp v189, v168 row_ror:8 row_mask:0xf bank_mask:0xf
	v_cndmask_b32_e64 v136, v189, v136, s[6:7]
	v_lshlrev_b32_e32 v189, 16, v140
	v_mul_f32_e32 v189, v165, v189
	v_cndmask_b32_e64 v168, v168, v181, s[6:7]
	v_mov_b32_dpp v200, v185 row_ror:8 row_mask:0xf bank_mask:0xf
	v_cndmask_b32_e64 v181, v185, v196, s[6:7]
	v_lshlrev_b32_e32 v185, 16, v136
	v_and_b32_e32 v140, 0xffff0000, v140
	v_mul_f32_e32 v189, v52, v189
	v_fmac_f32_e32 v185, v124, v189
	v_mul_f32_e32 v124, v165, v140
	v_and_b32_e32 v136, 0xffff0000, v136
	v_mul_f32_e32 v124, v53, v124
	v_fmac_f32_e32 v136, v125, v124
	v_mul_f32_e32 v124, 0xbfb8aa3b, v126
	v_exp_f32_e32 v124, v124
	v_mul_f32_e32 v126, 0xbfb8aa3b, v127
	v_exp_f32_e32 v126, v126
	v_mov_b32_dpp v198, v183 row_ror:8 row_mask:0xf bank_mask:0xf
	v_add_f32_e32 v124, 1.0, v124
	v_mov_b32_dpp v190, v169 row_ror:8 row_mask:0xf bank_mask:0xf
	v_cndmask_b32_e64 v141, v198, v141, s[6:7]
	v_rcp_f32_e32 v124, v124
	v_cndmask_b32_e64 v137, v190, v137, s[6:7]
	v_lshlrev_b32_e32 v190, 16, v141
	v_add_f32_e32 v126, 1.0, v126
	v_mul_f32_e32 v125, v165, v190
	v_rcp_f32_e32 v126, v126
	v_cndmask_b32_e64 v169, v169, v186, s[6:7]
	v_mov_b32_dpp v199, v184 row_ror:8 row_mask:0xf bank_mask:0xf
	v_lshlrev_b32_e32 v186, 16, v137
	v_and_b32_e32 v141, 0xffff0000, v141
	v_mul_f32_e32 v125, v54, v125
	v_mov_b32_dpp v191, v170 row_ror:8 row_mask:0xf bank_mask:0xf
	v_cndmask_b32_e64 v142, v199, v142, s[6:7]
	v_fmac_f32_e32 v186, v124, v125
	v_mul_f32_e32 v124, v165, v141
	v_cndmask_b32_e64 v138, v191, v138, s[6:7]
	v_and_b32_e32 v137, 0xffff0000, v137
	v_lshlrev_b32_e32 v191, 16, v142
	v_mul_f32_e32 v124, v55, v124
	v_fmac_f32_e32 v137, v126, v124
	v_mul_f32_e32 v124, v165, v191
	v_cndmask_b32_e64 v170, v170, v187, s[6:7]
	v_lshlrev_b32_e32 v187, 16, v138
	v_and_b32_e32 v142, 0xffff0000, v142
	v_mul_f32_e32 v124, v48, v124
	v_fmac_f32_e32 v187, v120, v124
	v_mul_f32_e32 v120, v165, v142
	v_and_b32_e32 v138, 0xffff0000, v138
	v_mul_f32_e32 v120, v49, v120
	v_fmac_f32_e32 v138, v121, v120
	v_mul_f32_e32 v120, 0xbfb8aa3b, v122
	v_cndmask_b32_e64 v182, v182, v193, s[6:7]
	v_exp_f32_e32 v120, v120
	v_mul_f32_e32 v122, 0xbfb8aa3b, v123
	v_lshlrev_b32_e32 v141, 16, v182
	v_exp_f32_e32 v122, v122
	v_mul_f32_e32 v141, v165, v141
	v_lshlrev_b32_e32 v125, 16, v168
	v_and_b32_e32 v142, 0xffff0000, v182
	v_mul_f32_e32 v141, v40, v141
	v_add_f32_e32 v120, 1.0, v120
	v_fmac_f32_e32 v125, v116, v141
	v_mul_f32_e32 v116, v165, v142
	v_mov_b32_dpp v192, v171 row_ror:8 row_mask:0xf bank_mask:0xf
	v_cndmask_b32_e64 v143, v200, v143, s[6:7]
	v_rcp_f32_e32 v120, v120
	v_and_b32_e32 v126, 0xffff0000, v168
	v_mul_f32_e32 v116, v41, v116
	v_cndmask_b32_e64 v139, v192, v139, s[6:7]
	v_lshlrev_b32_e32 v192, 16, v143
	v_add_f32_e32 v122, 1.0, v122
	v_fmac_f32_e32 v126, v117, v116
	v_mul_f32_e32 v116, 0xbfb8aa3b, v118
	v_mul_f32_e32 v121, v165, v192
	v_rcp_f32_e32 v122, v122
	v_exp_f32_e32 v116, v116
	v_cndmask_b32_e64 v171, v171, v188, s[6:7]
	v_lshlrev_b32_e32 v188, 16, v139
	v_and_b32_e32 v143, 0xffff0000, v143
	v_mul_f32_e32 v121, v50, v121
	v_mul_f32_e32 v118, 0xbfb8aa3b, v119
	v_fmac_f32_e32 v188, v120, v121
	v_mul_f32_e32 v120, v165, v143
	v_exp_f32_e32 v118, v118
	v_and_b32_e32 v139, 0xffff0000, v139
	v_mul_f32_e32 v120, v51, v120
	v_fmac_f32_e32 v139, v122, v120
	v_mul_f32_e32 v120, v136, v136
	v_mul_f32_e32 v121, v137, v137
	v_add_f32_e32 v116, 1.0, v116
	v_cndmask_b32_e64 v183, v183, v194, s[6:7]
	v_fmac_f32_e32 v120, v185, v185
	v_fmac_f32_e32 v121, v186, v186
	v_rcp_f32_e32 v116, v116
	v_add_f32_e32 v120, v120, v121
	v_mul_f32_e32 v121, v138, v138
	v_lshlrev_b32_e32 v143, 16, v183
	v_add_f32_e32 v118, 1.0, v118
	v_fmac_f32_e32 v121, v187, v187
	v_mul_f32_e32 v117, v165, v143
	v_rcp_f32_e32 v118, v118
	v_add_f32_e32 v120, v121, v120
	v_mul_f32_e32 v121, v139, v139
	v_lshlrev_b32_e32 v127, 16, v169
	v_and_b32_e32 v168, 0xffff0000, v183
	v_mul_f32_e32 v117, v42, v117
	v_cndmask_b32_e64 v184, v184, v195, s[6:7]
	v_fmac_f32_e32 v121, v188, v188
	v_fmac_f32_e32 v127, v116, v117
	v_mul_f32_e32 v116, v165, v168
	v_add_f32_e32 v120, v121, v120
	v_cvt_pk_bf16_f32 v121, v185, v136
	v_and_b32_e32 v136, 0xffff0000, v169
	v_lshlrev_b32_e32 v169, 16, v184
	v_mul_f32_e32 v116, v43, v116
	v_fmac_f32_e32 v136, v118, v116
	v_mul_f32_e32 v116, v165, v169
	v_cvt_pk_bf16_f32 v122, v186, v137
	v_cvt_pk_bf16_f32 v123, v187, v138
	v_lshlrev_b32_e32 v137, 16, v170
	v_and_b32_e32 v138, 0xffff0000, v170
	v_and_b32_e32 v170, 0xffff0000, v184
	v_mul_f32_e32 v116, v32, v116
	v_fmac_f32_e32 v137, v112, v116
	v_mul_f32_e32 v112, v165, v170
	v_mul_f32_e32 v112, v33, v112
	v_fmac_f32_e32 v138, v113, v112
	v_mul_f32_e32 v112, 0xbfb8aa3b, v114
	v_exp_f32_e32 v112, v112
	v_mul_f32_e32 v114, 0xbfb8aa3b, v115
	v_exp_f32_e32 v114, v114
	v_cvt_pk_bf16_f32 v124, v188, v139
	v_add_f32_e32 v112, 1.0, v112
	v_rcp_f32_e32 v112, v112
; __device__ __forceinline__ unsigned cvt_pk_bf16(float lo, float hi) { unsigned r; asm volatile("v_cvt_pk_bf16_f32 %0, %1, %2" : "=v"(r) : "v"(lo), "v"(hi)); return r; }
;     __device__ __forceinline__ void operator()(const f32x4 (&acc)[2][2][4][2], const Unit& u, int wr, int wc, int fr, int fq) const {
;     ...
;             for (int m = 0; m < 4; ++m) { const int row = row0 + ai * HALF + m * 16; const size_t off = (size_t)row * D + col0; const float ri = __builtin_amdgcn_rsqf(sse[row] * (1.f / D) + EPS); float sq = 0.f; u32x4 w[2];
;                 u32x4 rr[2], ee[2]; load_pair_lines(R, D, row, fr, col0, rr[0], rr[1]); load_pair_lines(E, D, row, fr, col0, ee[0], ee[1]);
;     ...
;                     else { sq += (o[0] * o[0] + o[1] * o[1]) + (o[2] * o[2] + o[3] * o[3]) + (o[4] * o[4] + o[5] * o[5]) + (o[6] * o[6] + o[7] * o[7]);
;                         w[bj].x = cvt_pk_bf16(o[0], o[1]); w[bj].y = cvt_pk_bf16(o[2], o[3]); w[bj].z = cvt_pk_bf16(o[4], o[5]); w[bj].w = cvt_pk_bf16(o[6], o[7]); } }
;                 if (!OUT) { store_pair_lines(O, D, row, fr, col0, w[0], w[1]);
;                     sq += __shfl_xor(sq, 16); sq += __shfl_xor(sq, 32); if (fq == 0) unsafeAtomicAdd(ssout + row, sq); } }
	v_lshlrev_b32_e32 v139, 16, v171
	v_and_b32_e32 v140, 0xffff0000, v171
	v_lshlrev_b32_e32 v171, 16, v181
	v_add_f32_e32 v114, 1.0, v114
	v_mul_f32_e32 v113, v165, v171
	v_rcp_f32_e32 v114, v114
	v_and_b32_e32 v181, 0xffff0000, v181
	v_mul_f32_e32 v113, v34, v113
	v_fmac_f32_e32 v139, v112, v113
	v_mul_f32_e32 v112, v165, v181
	v_mul_f32_e32 v112, v35, v112
	v_fmac_f32_e32 v140, v114, v112
	v_mul_f32_e32 v112, v126, v126
	v_mul_f32_e32 v113, v136, v136
	v_fmac_f32_e32 v112, v125, v125
	v_fmac_f32_e32 v113, v127, v127
	v_add_f32_e32 v112, v112, v113
	v_mul_f32_e32 v113, v138, v138
	v_fmac_f32_e32 v113, v137, v137
	v_add_f32_e32 v112, v113, v112
	v_mul_f32_e32 v113, v140, v140
	v_fmac_f32_e32 v113, v139, v139
	v_add_f32_e32 v112, v113, v112
	v_add_f32_e32 v141, v112, v120
	v_cvt_pk_bf16_f32 v112, v125, v126
	v_cvt_pk_bf16_f32 v113, v127, v136
	v_cvt_pk_bf16_f32 v120, v137, v138
	v_cvt_pk_bf16_f32 v125, v139, v140
	v_mov_b32_e32 v127, 0
	v_mov_b32_e32 v118, 0
	v_mov_b32_dpp v117, v125 row_ror:8 row_mask:0xf bank_mask:0xf
	v_mov_b32_dpp v127, v124 row_ror:8 row_mask:0xf bank_mask:0xf
	v_cndmask_b32_e64 v117, v117, v124, s[6:7]
	ds_bpermute_b32 v124, v134, v141
	v_mov_b32_dpp v118, v121 row_ror:8 row_mask:0xf bank_mask:0xf
	v_mov_b32_dpp v119, v122 row_ror:8 row_mask:0xf bank_mask:0xf
	v_mov_b32_dpp v114, v112 row_ror:8 row_mask:0xf bank_mask:0xf
	v_mov_b32_dpp v115, v113 row_ror:8 row_mask:0xf bank_mask:0xf
	v_mov_b32_dpp v116, v120 row_ror:8 row_mask:0xf bank_mask:0xf
	v_cndmask_b32_e64 v118, v112, v118, s[6:7]
	v_cndmask_b32_e64 v119, v113, v119, s[6:7]
	v_lshl_add_u64 v[112:113], s[36:37], 0, v[130:131]
	v_mov_b32_dpp v126, v123 row_ror:8 row_mask:0xf bank_mask:0xf
	v_cndmask_b32_e64 v115, v115, v122, s[6:7]
	v_cndmask_b32_e64 v116, v116, v123, s[6:7]
	v_lshl_add_u64 v[122:123], v[112:113], 0, v[162:163]
	s_waitcnt lgkmcnt(0)
	v_add_f32_e32 v112, v141, v124
	v_mov_b32_e32 v113, v112
	s_nop 1
	v_permlane32_swap_b32_e32 v113, v112
	v_cndmask_b32_e64 v114, v114, v121, s[6:7]
	global_store_dwordx4 v[122:123], v[114:117], off
	v_cndmask_b32_e64 v120, v120, v126, s[6:7]
	v_cndmask_b32_e64 v121, v125, v127, s[6:7]
	v_lshl_add_u64 v[114:115], s[36:37], 0, v[132:133]
	v_lshl_add_u64 v[114:115], v[114:115], 0, v[162:163]
	global_store_dwordx4 v[114:115], v[118:121], off
	s_and_saveexec_b64 s[56:57], s[8:9]
	s_cbranch_execz .LBB0_887
	v_lshl_add_u64 v[114:115], v[128:129], 2, s[18:19]
	s_waitcnt lgkmcnt(0)
	v_add_f32_e32 v112, v112, v113
	global_atomic_add_f32 v[114:115], v112, off
.LBB0_887:
	s_or_b64 exec, exec, s[56:57]
	v_or_b32_e32 v112, 32, v164
	s_waitcnt lgkmcnt(0)
	v_ashrrev_i32_e32 v113, 31, v112
	v_lshl_add_u64 v[114:115], v[112:113], 2, s[40:41]
	s_waitcnt vmcnt(2)
	s_nop 0
	v_mov_b32_e32 v136, v226
	v_sub_u32_e32 v114, v112, v172
	v_add_u32_e32 v114, v114, v174
	v_ashrrev_i32_e32 v115, 31, v114
	v_lshlrev_b64 v[114:115], 12, v[114:115]
	v_lshl_add_u64 v[116:117], s[16:17], 0, v[114:115]
	v_lshl_add_u64 v[116:117], v[116:117], 0, v[162:163]
	v_mov_b64_e32 v[118:119], v[228:229]
	v_mov_b64_e32 v[120:121], v[230:231]
	v_lshl_add_u64 v[116:117], s[38:39], 0, v[114:115]
	v_lshl_add_u64 v[116:117], v[116:117], 0, v[162:163]
	v_mov_b64_e32 v[122:123], v[232:233]
	v_mov_b64_e32 v[124:125], v[234:235]
	v_lshl_add_u64 v[116:117], v[114:115], 0, s[44:45]
	v_lshl_add_u64 v[130:131], s[38:39], 0, v[116:117]
	v_lshl_add_u64 v[126:127], s[16:17], 0, v[116:117]
	v_lshl_add_u64 v[130:131], v[130:131], 0, v[162:163]
	v_lshl_add_u64 v[126:127], v[126:127], 0, v[162:163]
	v_mov_b64_e32 v[130:131], v[236:237]
	v_mov_b64_e32 v[132:133], v[238:239]
	v_mul_f32_e32 v108, 0xbfb8aa3b, v108
	v_mov_b64_e32 v[126:127], v[240:241]
	v_mov_b64_e32 v[128:129], v[242:243]
	s_nop 1
	v_or_b32_e32 v216, 48, v164
	v_ashrrev_i32_e32 v217, 31, v216
	v_lshl_add_u64 v[218:219], v[216:217], 2, s[40:41]
	global_load_dword v226, v[218:219], off
	v_sub_u32_e32 v218, v216, v172
	v_add_u32_e32 v218, v218, v174
	v_ashrrev_i32_e32 v219, 31, v218
	v_lshlrev_b64 v[218:219], 12, v[218:219]
	v_lshl_add_u64 v[220:221], s[16:17], 0, v[218:219]
	v_lshl_add_u64 v[220:221], v[220:221], 0, v[162:163]
	global_load_dwordx4 v[228:231], v[220:221], off
	v_lshl_add_u64 v[220:221], s[38:39], 0, v[218:219]
	v_lshl_add_u64 v[220:221], v[220:221], 0, v[162:163]
	global_load_dwordx4 v[232:235], v[220:221], off
	v_lshl_add_u64 v[220:221], v[218:219], 0, s[44:45]
	v_lshl_add_u64 v[224:225], s[38:39], 0, v[220:221]
	v_lshl_add_u64 v[222:223], s[16:17], 0, v[220:221]
	v_lshl_add_u64 v[224:225], v[224:225], 0, v[162:163]
	v_lshl_add_u64 v[222:223], v[222:223], 0, v[162:163]
	global_load_dwordx4 v[236:239], v[224:225], off
	global_load_dwordx4 v[240:243], v[222:223], off
	v_exp_f32_e32 v108, v108
	v_mul_f32_e32 v109, 0xbfb8aa3b, v109
	v_exp_f32_e32 v109, v109
	v_add_f32_e32 v108, 1.0, v108
	v_rcp_f32_e32 v108, v108
	v_add_f32_e32 v109, 1.0, v109
	v_rcp_f32_e32 v109, v109
	v_mul_f32_e32 v104, 0xbfb8aa3b, v104
	v_exp_f32_e32 v104, v104
	v_mul_f32_e32 v105, 0xbfb8aa3b, v105
	v_exp_f32_e32 v105, v105
	v_add_f32_e32 v104, 1.0, v104
	v_rcp_f32_e32 v104, v104
	v_add_f32_e32 v105, 1.0, v105
	v_mul_f32_e32 v100, 0xbfb8aa3b, v100
	v_rcp_f32_e32 v105, v105
	v_exp_f32_e32 v100, v100
	v_mul_f32_e32 v101, 0xbfb8aa3b, v101
	v_exp_f32_e32 v101, v101
	v_add_f32_e32 v100, 1.0, v100
	v_rcp_f32_e32 v100, v100
	v_add_f32_e32 v101, 1.0, v101
	v_rcp_f32_e32 v101, v101
	v_mul_f32_e32 v96, 0xbfb8aa3b, v96
	v_exp_f32_e32 v96, v96
	v_mul_f32_e32 v97, 0xbfb8aa3b, v97
	v_exp_f32_e32 v97, v97
	v_add_f32_e32 v96, 1.0, v96
	v_rcp_f32_e32 v96, v96
	v_add_f32_e32 v97, 1.0, v97
	v_rcp_f32_e32 v97, v97
	s_waitcnt vmcnt(19)
; __device__ __forceinline__ unsigned cvt_pk_bf16(float lo, float hi) { unsigned r; asm volatile("v_cvt_pk_bf16_f32 %0, %1, %2" : "=v"(r) : "v"(lo), "v"(hi)); return r; }
; __device__ __forceinline__ float bflo(unsigned w) { return __uint_as_float(w << 16); }
; __device__ __forceinline__ float bfhi(unsigned w) { return __uint_as_float(w & 0xffff0000u); }
;     __device__ __forceinline__ void operator()(const f32x4 (&acc)[2][2][4][2], const Unit& u, int wr, int wc, int fr, int fq) const {
;     ...
;                 for (int bj = 0; bj < 2; ++bj) { const u32x4 rw = rr[bj], ew = ee[bj];
;                     const float r[8] = {bflo(rw.x), bfhi(rw.x), bflo(rw.y), bfhi(rw.y), bflo(rw.z), bfhi(rw.z), bflo(rw.w), bfhi(rw.w)};
;                     const float e[8] = {bflo(ew.x), bfhi(ew.x), bflo(ew.y), bfhi(ew.y), bflo(ew.z), bfhi(ew.z), bflo(ew.w), bfhi(ew.w)};
;                     float o[8];
; #pragma unroll
;                     for (int j = 0; j < 8; ++j) { const float a = acc[ai][bj][m][j >> 2][j & 3]; const float gg = gv[bj][j >> 2][j & 3];
;                         o[j] = r[j] + e[j] * ri * gg * __builtin_amdgcn_rcpf(1.f + __builtin_amdgcn_exp2f(-a * LOG2E)); }
;                     if (OUT) { *(f32x4*)(OUT + off + 8 * bj) = (f32x4){o[0], o[1], o[2], o[3]}; *(f32x4*)(OUT + off + 8 * bj + 4) = (f32x4){o[4], o[5], o[6], o[7]}; }
;                     else { sq += (o[0] * o[0] + o[1] * o[1]) + (o[2] * o[2] + o[3] * o[3]) + (o[4] * o[4] + o[5] * o[5]) + (o[6] * o[6] + o[7] * o[7]);
;                         w[bj].x = cvt_pk_bf16(o[0], o[1]); w[bj].y = cvt_pk_bf16(o[2], o[3]); w[bj].z = cvt_pk_bf16(o[4], o[5]); w[bj].w = cvt_pk_bf16(o[6], o[7]); } }
	v_fmamk_f32 v136, v136, 0x3a000000, v180
	v_rsq_f32_e32 v136, v136
	s_waitcnt vmcnt(19)
	v_mov_b32_dpp v137, v118 row_ror:8 row_mask:0xf bank_mask:0xf
	v_mov_b32_dpp v138, v119 row_ror:8 row_mask:0xf bank_mask:0xf
	v_mov_b32_dpp v139, v120 row_ror:8 row_mask:0xf bank_mask:0xf
	s_waitcnt vmcnt(19)
	v_mov_b32_dpp v168, v122 row_ror:8 row_mask:0xf bank_mask:0xf
	v_mov_b32_dpp v169, v123 row_ror:8 row_mask:0xf bank_mask:0xf
	v_mov_b32_dpp v170, v124 row_ror:8 row_mask:0xf bank_mask:0xf
	v_mov_b32_dpp v171, v125 row_ror:8 row_mask:0xf bank_mask:0xf
	v_mov_b32_dpp v140, v121 row_ror:8 row_mask:0xf bank_mask:0xf
	s_waitcnt vmcnt(19)
	v_mov_b32_dpp v181, v130 row_ror:8 row_mask:0xf bank_mask:0xf
	v_cndmask_b32_e64 v122, v181, v122, s[6:7]
	s_waitcnt vmcnt(19)
	v_mov_b32_dpp v141, v126 row_ror:8 row_mask:0xf bank_mask:0xf
	v_cndmask_b32_e64 v118, v141, v118, s[6:7]
	v_lshlrev_b32_e32 v141, 16, v122
	v_mul_f32_e32 v141, v136, v141
	v_cndmask_b32_e64 v126, v126, v137, s[6:7]
	v_lshlrev_b32_e32 v137, 16, v118
	v_and_b32_e32 v122, 0xffff0000, v122
	v_mul_f32_e32 v141, v52, v141
	v_fmac_f32_e32 v137, v108, v141
	v_mul_f32_e32 v108, v136, v122
	v_and_b32_e32 v118, 0xffff0000, v118
	v_mul_f32_e32 v108, v53, v108
	v_fmac_f32_e32 v118, v109, v108
	v_mul_f32_e32 v108, 0xbfb8aa3b, v110
	v_exp_f32_e32 v108, v108
	v_mul_f32_e32 v110, 0xbfb8aa3b, v111
	v_exp_f32_e32 v110, v110
	v_mov_b32_dpp v182, v131 row_ror:8 row_mask:0xf bank_mask:0xf
	v_add_f32_e32 v108, 1.0, v108
	v_mov_b32_dpp v142, v127 row_ror:8 row_mask:0xf bank_mask:0xf
	v_cndmask_b32_e64 v123, v182, v123, s[6:7]
	v_rcp_f32_e32 v108, v108
	v_cndmask_b32_e64 v119, v142, v119, s[6:7]
	v_lshlrev_b32_e32 v142, 16, v123
	v_add_f32_e32 v110, 1.0, v110
	v_mul_f32_e32 v109, v136, v142
	v_rcp_f32_e32 v110, v110
	v_cndmask_b32_e64 v127, v127, v138, s[6:7]
	v_mov_b32_dpp v183, v132 row_ror:8 row_mask:0xf bank_mask:0xf
	v_lshlrev_b32_e32 v138, 16, v119
	v_and_b32_e32 v123, 0xffff0000, v123
	v_mul_f32_e32 v109, v54, v109
	v_mov_b32_dpp v143, v128 row_ror:8 row_mask:0xf bank_mask:0xf
	v_cndmask_b32_e64 v124, v183, v124, s[6:7]
	v_fmac_f32_e32 v138, v108, v109
	v_mul_f32_e32 v108, v136, v123
	v_cndmask_b32_e64 v120, v143, v120, s[6:7]
	v_and_b32_e32 v119, 0xffff0000, v119
	v_lshlrev_b32_e32 v143, 16, v124
	v_mul_f32_e32 v108, v55, v108
	v_fmac_f32_e32 v119, v110, v108
	v_mul_f32_e32 v108, v136, v143
	v_cndmask_b32_e64 v128, v128, v139, s[6:7]
	v_lshlrev_b32_e32 v139, 16, v120
	v_and_b32_e32 v124, 0xffff0000, v124
	v_mul_f32_e32 v108, v48, v108
	v_fmac_f32_e32 v139, v104, v108
	v_mul_f32_e32 v104, v136, v124
	v_and_b32_e32 v120, 0xffff0000, v120
	v_mul_f32_e32 v104, v49, v104
	v_fmac_f32_e32 v120, v105, v104
	v_mul_f32_e32 v104, 0xbfb8aa3b, v106
	v_cndmask_b32_e64 v130, v130, v168, s[6:7]
	v_exp_f32_e32 v104, v104
	v_mul_f32_e32 v106, 0xbfb8aa3b, v107
	v_lshlrev_b32_e32 v123, 16, v130
	v_exp_f32_e32 v106, v106
	v_mul_f32_e32 v123, v136, v123
	v_lshlrev_b32_e32 v109, 16, v126
	v_and_b32_e32 v124, 0xffff0000, v130
	v_mul_f32_e32 v123, v40, v123
	v_mov_b32_dpp v184, v133 row_ror:8 row_mask:0xf bank_mask:0xf
	v_add_f32_e32 v104, 1.0, v104
	v_fmac_f32_e32 v109, v100, v123
	v_mul_f32_e32 v100, v136, v124
	v_mov_b32_dpp v165, v129 row_ror:8 row_mask:0xf bank_mask:0xf
	v_cndmask_b32_e64 v125, v184, v125, s[6:7]
	v_rcp_f32_e32 v104, v104
	v_and_b32_e32 v110, 0xffff0000, v126
	v_mul_f32_e32 v100, v41, v100
	v_cndmask_b32_e64 v121, v165, v121, s[6:7]
	v_lshlrev_b32_e32 v165, 16, v125
	v_add_f32_e32 v106, 1.0, v106
	v_fmac_f32_e32 v110, v101, v100
	v_mul_f32_e32 v100, 0xbfb8aa3b, v102
	v_mul_f32_e32 v105, v136, v165
	v_rcp_f32_e32 v106, v106
	v_exp_f32_e32 v100, v100
	v_cndmask_b32_e64 v129, v129, v140, s[6:7]
	v_lshlrev_b32_e32 v140, 16, v121
	v_and_b32_e32 v125, 0xffff0000, v125
	v_mul_f32_e32 v105, v50, v105
	v_mul_f32_e32 v102, 0xbfb8aa3b, v103
	v_fmac_f32_e32 v140, v104, v105
	v_mul_f32_e32 v104, v136, v125
	v_exp_f32_e32 v102, v102
	v_and_b32_e32 v121, 0xffff0000, v121
	v_mul_f32_e32 v104, v51, v104
	v_fmac_f32_e32 v121, v106, v104
	v_mul_f32_e32 v104, v118, v118
	v_mul_f32_e32 v105, v119, v119
	v_add_f32_e32 v100, 1.0, v100
	v_cndmask_b32_e64 v131, v131, v169, s[6:7]
	v_fmac_f32_e32 v104, v137, v137
	v_fmac_f32_e32 v105, v138, v138
	v_rcp_f32_e32 v100, v100
	v_add_f32_e32 v104, v104, v105
	v_mul_f32_e32 v105, v120, v120
	v_lshlrev_b32_e32 v125, 16, v131
	v_add_f32_e32 v102, 1.0, v102
	v_fmac_f32_e32 v105, v139, v139
	v_mul_f32_e32 v101, v136, v125
	v_rcp_f32_e32 v102, v102
	v_add_f32_e32 v104, v105, v104
	v_mul_f32_e32 v105, v121, v121
	v_lshlrev_b32_e32 v111, 16, v127
	v_and_b32_e32 v126, 0xffff0000, v131
	v_mul_f32_e32 v101, v42, v101
	v_cndmask_b32_e64 v132, v132, v170, s[6:7]
	v_fmac_f32_e32 v105, v140, v140
	v_fmac_f32_e32 v111, v100, v101
	v_mul_f32_e32 v100, v136, v126
	v_add_f32_e32 v104, v105, v104
	v_cvt_pk_bf16_f32 v105, v137, v118
	v_and_b32_e32 v118, 0xffff0000, v127
	v_lshlrev_b32_e32 v127, 16, v132
	v_mul_f32_e32 v100, v43, v100
	v_fmac_f32_e32 v118, v102, v100
	v_mul_f32_e32 v100, v136, v127
	v_cvt_pk_bf16_f32 v106, v138, v119
	v_cvt_pk_bf16_f32 v107, v139, v120
	v_lshlrev_b32_e32 v119, 16, v128
	v_and_b32_e32 v120, 0xffff0000, v128
	v_and_b32_e32 v128, 0xffff0000, v132
	v_mul_f32_e32 v100, v32, v100
	v_fmac_f32_e32 v119, v96, v100
	v_mul_f32_e32 v96, v136, v128
	v_mul_f32_e32 v96, v33, v96
	v_fmac_f32_e32 v120, v97, v96
	v_mul_f32_e32 v96, 0xbfb8aa3b, v98
	v_exp_f32_e32 v96, v96
	v_mul_f32_e32 v98, 0xbfb8aa3b, v99
	v_exp_f32_e32 v98, v98
	v_cndmask_b32_e64 v133, v133, v171, s[6:7]
	v_add_f32_e32 v96, 1.0, v96
	v_rcp_f32_e32 v96, v96
	v_cvt_pk_bf16_f32 v108, v140, v121
	v_lshlrev_b32_e32 v121, 16, v129
; __device__ __forceinline__ unsigned cvt_pk_bf16(float lo, float hi) { unsigned r; asm volatile("v_cvt_pk_bf16_f32 %0, %1, %2" : "=v"(r) : "v"(lo), "v"(hi)); return r; }
;     __device__ __forceinline__ void operator()(const f32x4 (&acc)[2][2][4][2], const Unit& u, int wr, int wc, int fr, int fq) const {
;     ...
;             for (int m = 0; m < 4; ++m) { const int row = row0 + ai * HALF + m * 16; const size_t off = (size_t)row * D + col0; const float ri = __builtin_amdgcn_rsqf(sse[row] * (1.f / D) + EPS); float sq = 0.f; u32x4 w[2];
;                 u32x4 rr[2], ee[2]; load_pair_lines(R, D, row, fr, col0, rr[0], rr[1]); load_pair_lines(E, D, row, fr, col0, ee[0], ee[1]);
;     ...
;                     else { sq += (o[0] * o[0] + o[1] * o[1]) + (o[2] * o[2] + o[3] * o[3]) + (o[4] * o[4] + o[5] * o[5]) + (o[6] * o[6] + o[7] * o[7]);
;                         w[bj].x = cvt_pk_bf16(o[0], o[1]); w[bj].y = cvt_pk_bf16(o[2], o[3]); w[bj].z = cvt_pk_bf16(o[4], o[5]); w[bj].w = cvt_pk_bf16(o[6], o[7]); } }
;                 if (!OUT) { store_pair_lines(O, D, row, fr, col0, w[0], w[1]);
;                     sq += __shfl_xor(sq, 16); sq += __shfl_xor(sq, 32); if (fq == 0) unsafeAtomicAdd(ssout + row, sq); } }
	v_and_b32_e32 v122, 0xffff0000, v129
	v_lshlrev_b32_e32 v129, 16, v133
	v_add_f32_e32 v98, 1.0, v98
	v_mul_f32_e32 v97, v136, v129
	v_rcp_f32_e32 v98, v98
	v_and_b32_e32 v130, 0xffff0000, v133
	v_mul_f32_e32 v97, v34, v97
	v_fmac_f32_e32 v121, v96, v97
	v_mul_f32_e32 v96, v136, v130
	v_mul_f32_e32 v96, v35, v96
	v_fmac_f32_e32 v122, v98, v96
	v_mul_f32_e32 v96, v110, v110
	v_mul_f32_e32 v97, v118, v118
	v_fmac_f32_e32 v96, v109, v109
	v_fmac_f32_e32 v97, v111, v111
	v_add_f32_e32 v96, v96, v97
	v_mul_f32_e32 v97, v120, v120
	v_fmac_f32_e32 v97, v119, v119
	v_add_f32_e32 v96, v97, v96
	v_mul_f32_e32 v97, v122, v122
	v_fmac_f32_e32 v97, v121, v121
	v_add_f32_e32 v96, v97, v96
	v_add_f32_e32 v123, v96, v104
	v_cvt_pk_bf16_f32 v96, v109, v110
	v_cvt_pk_bf16_f32 v97, v111, v118
	v_cvt_pk_bf16_f32 v104, v119, v120
	v_cvt_pk_bf16_f32 v109, v121, v122
	v_mov_b32_e32 v111, 0
	v_mov_b32_e32 v102, 0
	v_mov_b32_dpp v101, v109 row_ror:8 row_mask:0xf bank_mask:0xf
	v_mov_b32_dpp v111, v108 row_ror:8 row_mask:0xf bank_mask:0xf
	v_cndmask_b32_e64 v101, v101, v108, s[6:7]
	ds_bpermute_b32 v108, v134, v123
	v_mov_b32_dpp v102, v105 row_ror:8 row_mask:0xf bank_mask:0xf
	v_mov_b32_dpp v103, v106 row_ror:8 row_mask:0xf bank_mask:0xf
	v_mov_b32_dpp v98, v96 row_ror:8 row_mask:0xf bank_mask:0xf
	v_mov_b32_dpp v99, v97 row_ror:8 row_mask:0xf bank_mask:0xf
	v_mov_b32_dpp v100, v104 row_ror:8 row_mask:0xf bank_mask:0xf
	v_cndmask_b32_e64 v102, v96, v102, s[6:7]
	v_cndmask_b32_e64 v103, v97, v103, s[6:7]
	v_lshl_add_u64 v[96:97], s[36:37], 0, v[114:115]
	v_mov_b32_dpp v110, v107 row_ror:8 row_mask:0xf bank_mask:0xf
	v_cndmask_b32_e64 v99, v99, v106, s[6:7]
	v_cndmask_b32_e64 v100, v100, v107, s[6:7]
	v_lshl_add_u64 v[106:107], v[96:97], 0, v[162:163]
	s_waitcnt lgkmcnt(0)
	v_add_f32_e32 v96, v123, v108
	v_mov_b32_e32 v97, v96
	s_nop 1
	v_permlane32_swap_b32_e32 v97, v96
	v_cndmask_b32_e64 v98, v98, v105, s[6:7]
	global_store_dwordx4 v[106:107], v[98:101], off
	v_cndmask_b32_e64 v104, v104, v110, s[6:7]
	v_cndmask_b32_e64 v105, v109, v111, s[6:7]
	v_lshl_add_u64 v[98:99], s[36:37], 0, v[116:117]
	v_lshl_add_u64 v[98:99], v[98:99], 0, v[162:163]
	global_store_dwordx4 v[98:99], v[102:105], off
	s_and_saveexec_b64 s[56:57], s[8:9]
	s_cbranch_execz .LBB0_889
	v_lshl_add_u64 v[98:99], v[112:113], 2, s[18:19]
	s_waitcnt lgkmcnt(0)
	v_add_f32_e32 v96, v96, v97
	global_atomic_add_f32 v[98:99], v96, off
.LBB0_889:
	s_or_b64 exec, exec, s[56:57]
	v_or_b32_e32 v96, 48, v164
	s_waitcnt lgkmcnt(0)
	v_ashrrev_i32_e32 v97, 31, v96
	v_lshl_add_u64 v[98:99], v[96:97], 2, s[40:41]
	s_waitcnt vmcnt(2)
	s_nop 0
	v_mov_b32_e32 v118, v226
	v_sub_u32_e32 v98, v96, v172
	v_add_u32_e32 v98, v98, v174
	v_ashrrev_i32_e32 v99, 31, v98
	v_lshlrev_b64 v[98:99], 12, v[98:99]
	v_lshl_add_u64 v[100:101], s[16:17], 0, v[98:99]
	v_lshl_add_u64 v[100:101], v[100:101], 0, v[162:163]
	v_mov_b64_e32 v[102:103], v[228:229]
	v_mov_b64_e32 v[104:105], v[230:231]
	v_lshl_add_u64 v[100:101], s[38:39], 0, v[98:99]
	v_lshl_add_u64 v[100:101], v[100:101], 0, v[162:163]
	v_mov_b64_e32 v[106:107], v[232:233]
	v_mov_b64_e32 v[108:109], v[234:235]
	v_lshl_add_u64 v[100:101], v[98:99], 0, s[44:45]
	v_lshl_add_u64 v[114:115], s[38:39], 0, v[100:101]
	v_lshl_add_u64 v[110:111], s[16:17], 0, v[100:101]
	v_lshl_add_u64 v[114:115], v[114:115], 0, v[162:163]
	v_lshl_add_u64 v[110:111], v[110:111], 0, v[162:163]
	v_mov_b64_e32 v[114:115], v[236:237]
	v_mov_b64_e32 v[116:117], v[238:239]
	v_mul_f32_e32 v92, 0xbfb8aa3b, v92
	v_mov_b64_e32 v[110:111], v[240:241]
	v_mov_b64_e32 v[112:113], v[242:243]
	s_nop 1
	v_add_u32_e32 v216, 0x80, v164
	v_sub_u32_e32 v218, v216, v172
	v_add_u32_e32 v218, v218, v174
	v_ashrrev_i32_e32 v219, 31, v218
	v_lshlrev_b64 v[218:219], 12, v[218:219]
	v_lshl_add_u64 v[220:221], s[16:17], 0, v[218:219]
	v_lshl_add_u64 v[220:221], v[220:221], 0, v[162:163]
	global_load_dwordx4 v[228:231], v[220:221], off
	v_lshl_add_u64 v[220:221], s[38:39], 0, v[218:219]
	v_lshl_add_u64 v[220:221], v[220:221], 0, v[162:163]
	global_load_dword v226, v[166:167], off offset:512
	global_load_dwordx4 v[232:235], v[220:221], off
	v_lshl_add_u64 v[220:221], v[218:219], 0, s[44:45]
	v_lshl_add_u64 v[224:225], s[38:39], 0, v[220:221]
	v_lshl_add_u64 v[222:223], s[16:17], 0, v[220:221]
	v_lshl_add_u64 v[224:225], v[224:225], 0, v[162:163]
	v_lshl_add_u64 v[222:223], v[222:223], 0, v[162:163]
	global_load_dwordx4 v[236:239], v[224:225], off
	global_load_dwordx4 v[240:243], v[222:223], off
	v_exp_f32_e32 v92, v92
	v_mul_f32_e32 v93, 0xbfb8aa3b, v93
	v_exp_f32_e32 v93, v93
	v_add_f32_e32 v92, 1.0, v92
	v_rcp_f32_e32 v92, v92
	v_add_f32_e32 v93, 1.0, v93
	v_rcp_f32_e32 v93, v93
	v_mul_f32_e32 v88, 0xbfb8aa3b, v88
	v_exp_f32_e32 v88, v88
	v_mul_f32_e32 v89, 0xbfb8aa3b, v89
	v_exp_f32_e32 v89, v89
	v_add_f32_e32 v88, 1.0, v88
	v_rcp_f32_e32 v88, v88
	v_add_f32_e32 v89, 1.0, v89
	v_mul_f32_e32 v84, 0xbfb8aa3b, v84
	v_rcp_f32_e32 v89, v89
	v_exp_f32_e32 v84, v84
	v_mul_f32_e32 v85, 0xbfb8aa3b, v85
	v_exp_f32_e32 v85, v85
	v_add_f32_e32 v84, 1.0, v84
	v_rcp_f32_e32 v84, v84
	v_add_f32_e32 v85, 1.0, v85
	v_rcp_f32_e32 v85, v85
	v_mul_f32_e32 v80, 0xbfb8aa3b, v80
	v_exp_f32_e32 v80, v80
	v_mul_f32_e32 v81, 0xbfb8aa3b, v81
	v_exp_f32_e32 v81, v81
	v_add_f32_e32 v80, 1.0, v80
	v_rcp_f32_e32 v80, v80
	v_add_f32_e32 v81, 1.0, v81
	v_rcp_f32_e32 v81, v81
	s_waitcnt vmcnt(26)
	v_fmamk_f32 v118, v118, 0x3a000000, v180
	v_rsq_f32_e32 v118, v118
	s_waitcnt vmcnt(26)
	v_mov_b32_dpp v119, v102 row_ror:8 row_mask:0xf bank_mask:0xf
	v_mov_b32_dpp v120, v103 row_ror:8 row_mask:0xf bank_mask:0xf
	v_mov_b32_dpp v121, v104 row_ror:8 row_mask:0xf bank_mask:0xf
	s_waitcnt vmcnt(26)
; __device__ __forceinline__ unsigned cvt_pk_bf16(float lo, float hi) { unsigned r; asm volatile("v_cvt_pk_bf16_f32 %0, %1, %2" : "=v"(r) : "v"(lo), "v"(hi)); return r; }
; __device__ __forceinline__ float bflo(unsigned w) { return __uint_as_float(w << 16); }
; __device__ __forceinline__ float bfhi(unsigned w) { return __uint_as_float(w & 0xffff0000u); }
;     __device__ __forceinline__ void operator()(const f32x4 (&acc)[2][2][4][2], const Unit& u, int wr, int wc, int fr, int fq) const {
;     ...
;                 for (int bj = 0; bj < 2; ++bj) { const u32x4 rw = rr[bj], ew = ee[bj];
;                     const float r[8] = {bflo(rw.x), bfhi(rw.x), bflo(rw.y), bfhi(rw.y), bflo(rw.z), bfhi(rw.z), bflo(rw.w), bfhi(rw.w)};
;                     const float e[8] = {bflo(ew.x), bfhi(ew.x), bflo(ew.y), bfhi(ew.y), bflo(ew.z), bfhi(ew.z), bflo(ew.w), bfhi(ew.w)};
;                     float o[8];
; #pragma unroll
;                     for (int j = 0; j < 8; ++j) { const float a = acc[ai][bj][m][j >> 2][j & 3]; const float gg = gv[bj][j >> 2][j & 3];
;                         o[j] = r[j] + e[j] * ri * gg * __builtin_amdgcn_rcpf(1.f + __builtin_amdgcn_exp2f(-a * LOG2E)); }
;                     if (OUT) { *(f32x4*)(OUT + off + 8 * bj) = (f32x4){o[0], o[1], o[2], o[3]}; *(f32x4*)(OUT + off + 8 * bj + 4) = (f32x4){o[4], o[5], o[6], o[7]}; }
;                     else { sq += (o[0] * o[0] + o[1] * o[1]) + (o[2] * o[2] + o[3] * o[3]) + (o[4] * o[4] + o[5] * o[5]) + (o[6] * o[6] + o[7] * o[7]);
;                         w[bj].x = cvt_pk_bf16(o[0], o[1]); w[bj].y = cvt_pk_bf16(o[2], o[3]); w[bj].z = cvt_pk_bf16(o[4], o[5]); w[bj].w = cvt_pk_bf16(o[6], o[7]); } }
;                 if (!OUT) { store_pair_lines(O, D, row, fr, col0, w[0], w[1]);
;                     sq += __shfl_xor(sq, 16); sq += __shfl_xor(sq, 32); if (fq == 0) unsafeAtomicAdd(ssout + row, sq); } }
	v_mov_b32_dpp v127, v106 row_ror:8 row_mask:0xf bank_mask:0xf
	v_mov_b32_dpp v128, v107 row_ror:8 row_mask:0xf bank_mask:0xf
	v_mov_b32_dpp v129, v108 row_ror:8 row_mask:0xf bank_mask:0xf
	v_mov_b32_dpp v130, v109 row_ror:8 row_mask:0xf bank_mask:0xf
	v_mov_b32_dpp v122, v105 row_ror:8 row_mask:0xf bank_mask:0xf
	s_waitcnt vmcnt(26)
	v_mov_b32_dpp v131, v114 row_ror:8 row_mask:0xf bank_mask:0xf
	v_cndmask_b32_e64 v106, v131, v106, s[6:7]
	s_waitcnt vmcnt(26)
	v_mov_b32_dpp v123, v110 row_ror:8 row_mask:0xf bank_mask:0xf
	v_cndmask_b32_e64 v102, v123, v102, s[6:7]
	v_lshlrev_b32_e32 v123, 16, v106
	v_mul_f32_e32 v123, v118, v123
	v_cndmask_b32_e64 v110, v110, v119, s[6:7]
	v_lshlrev_b32_e32 v119, 16, v102
	v_and_b32_e32 v106, 0xffff0000, v106
	v_mul_f32_e32 v123, v52, v123
	v_fmac_f32_e32 v119, v92, v123
	v_mul_f32_e32 v92, v118, v106
	v_and_b32_e32 v102, 0xffff0000, v102
	v_mul_f32_e32 v92, v53, v92
	v_fmac_f32_e32 v102, v93, v92
	v_mul_f32_e32 v92, 0xbfb8aa3b, v94
	v_exp_f32_e32 v92, v92
	v_mul_f32_e32 v94, 0xbfb8aa3b, v95
	v_exp_f32_e32 v94, v94
	v_mov_b32_dpp v132, v115 row_ror:8 row_mask:0xf bank_mask:0xf
	v_add_f32_e32 v92, 1.0, v92
	v_mov_b32_dpp v124, v111 row_ror:8 row_mask:0xf bank_mask:0xf
	v_cndmask_b32_e64 v107, v132, v107, s[6:7]
	v_rcp_f32_e32 v92, v92
	v_cndmask_b32_e64 v103, v124, v103, s[6:7]
	v_lshlrev_b32_e32 v124, 16, v107
	v_add_f32_e32 v94, 1.0, v94
	v_mul_f32_e32 v93, v118, v124
	v_rcp_f32_e32 v94, v94
	v_cndmask_b32_e64 v111, v111, v120, s[6:7]
	v_mov_b32_dpp v133, v116 row_ror:8 row_mask:0xf bank_mask:0xf
	v_lshlrev_b32_e32 v120, 16, v103
	v_and_b32_e32 v107, 0xffff0000, v107
	v_mul_f32_e32 v93, v54, v93
	v_mov_b32_dpp v125, v112 row_ror:8 row_mask:0xf bank_mask:0xf
	v_cndmask_b32_e64 v108, v133, v108, s[6:7]
	v_fmac_f32_e32 v120, v92, v93
	v_mul_f32_e32 v92, v118, v107
	v_cndmask_b32_e64 v104, v125, v104, s[6:7]
	v_and_b32_e32 v103, 0xffff0000, v103
	v_lshlrev_b32_e32 v125, 16, v108
	v_mul_f32_e32 v92, v55, v92
	v_fmac_f32_e32 v103, v94, v92
	v_mul_f32_e32 v92, v118, v125
	v_cndmask_b32_e64 v112, v112, v121, s[6:7]
	v_lshlrev_b32_e32 v121, 16, v104
	v_and_b32_e32 v108, 0xffff0000, v108
	v_mul_f32_e32 v92, v48, v92
	v_fmac_f32_e32 v121, v88, v92
	v_mul_f32_e32 v88, v118, v108
	v_and_b32_e32 v104, 0xffff0000, v104
	v_mul_f32_e32 v88, v49, v88
	v_fmac_f32_e32 v104, v89, v88
	v_mul_f32_e32 v88, 0xbfb8aa3b, v90
	v_cndmask_b32_e64 v114, v114, v127, s[6:7]
	v_exp_f32_e32 v88, v88
	v_mul_f32_e32 v90, 0xbfb8aa3b, v91
	v_lshlrev_b32_e32 v107, 16, v114
	v_exp_f32_e32 v90, v90
	v_mul_f32_e32 v107, v118, v107
	v_lshlrev_b32_e32 v93, 16, v110
	v_and_b32_e32 v108, 0xffff0000, v114
	v_mul_f32_e32 v107, v40, v107
	v_mov_b32_dpp v136, v117 row_ror:8 row_mask:0xf bank_mask:0xf
	v_add_f32_e32 v88, 1.0, v88
	v_fmac_f32_e32 v93, v84, v107
	v_mul_f32_e32 v84, v118, v108
	v_mov_b32_dpp v126, v113 row_ror:8 row_mask:0xf bank_mask:0xf
	v_cndmask_b32_e64 v109, v136, v109, s[6:7]
	v_rcp_f32_e32 v88, v88
	v_and_b32_e32 v94, 0xffff0000, v110
	v_mul_f32_e32 v84, v41, v84
	v_cndmask_b32_e64 v105, v126, v105, s[6:7]
	v_lshlrev_b32_e32 v126, 16, v109
	v_add_f32_e32 v90, 1.0, v90
	v_fmac_f32_e32 v94, v85, v84
	v_mul_f32_e32 v84, 0xbfb8aa3b, v86
	v_mul_f32_e32 v89, v118, v126
	v_rcp_f32_e32 v90, v90
	v_exp_f32_e32 v84, v84
	v_cndmask_b32_e64 v113, v113, v122, s[6:7]
	v_lshlrev_b32_e32 v122, 16, v105
	v_and_b32_e32 v109, 0xffff0000, v109
	v_mul_f32_e32 v89, v50, v89
	v_mul_f32_e32 v86, 0xbfb8aa3b, v87
	v_fmac_f32_e32 v122, v88, v89
	v_mul_f32_e32 v88, v118, v109
	v_exp_f32_e32 v86, v86
	v_and_b32_e32 v105, 0xffff0000, v105
	v_mul_f32_e32 v88, v51, v88
	v_fmac_f32_e32 v105, v90, v88
	v_mul_f32_e32 v88, v102, v102
	v_mul_f32_e32 v89, v103, v103
	v_add_f32_e32 v84, 1.0, v84
	v_cndmask_b32_e64 v115, v115, v128, s[6:7]
	v_fmac_f32_e32 v88, v119, v119
	v_fmac_f32_e32 v89, v120, v120
	v_rcp_f32_e32 v84, v84
	v_add_f32_e32 v88, v88, v89
	v_mul_f32_e32 v89, v104, v104
	v_lshlrev_b32_e32 v109, 16, v115
	v_add_f32_e32 v86, 1.0, v86
	v_fmac_f32_e32 v89, v121, v121
	v_mul_f32_e32 v85, v118, v109
	v_rcp_f32_e32 v86, v86
	v_add_f32_e32 v88, v89, v88
	v_mul_f32_e32 v89, v105, v105
	v_lshlrev_b32_e32 v95, 16, v111
	v_and_b32_e32 v110, 0xffff0000, v115
	v_mul_f32_e32 v85, v42, v85
	v_cndmask_b32_e64 v116, v116, v129, s[6:7]
	v_fmac_f32_e32 v89, v122, v122
	v_fmac_f32_e32 v95, v84, v85
	v_mul_f32_e32 v84, v118, v110
	v_add_f32_e32 v88, v89, v88
	v_cvt_pk_bf16_f32 v89, v119, v102
	v_and_b32_e32 v102, 0xffff0000, v111
	v_lshlrev_b32_e32 v111, 16, v116
	v_mul_f32_e32 v84, v43, v84
	v_fmac_f32_e32 v102, v86, v84
	v_mul_f32_e32 v84, v118, v111
	v_cvt_pk_bf16_f32 v90, v120, v103
	v_cvt_pk_bf16_f32 v91, v121, v104
	v_lshlrev_b32_e32 v103, 16, v112
	v_and_b32_e32 v104, 0xffff0000, v112
	v_and_b32_e32 v112, 0xffff0000, v116
	v_mul_f32_e32 v84, v32, v84
	v_fmac_f32_e32 v103, v80, v84
	v_mul_f32_e32 v80, v118, v112
	v_mul_f32_e32 v80, v33, v80
	v_fmac_f32_e32 v104, v81, v80
	v_mul_f32_e32 v80, 0xbfb8aa3b, v82
	v_exp_f32_e32 v80, v80
	v_mul_f32_e32 v82, 0xbfb8aa3b, v83
	v_exp_f32_e32 v82, v82
	v_cndmask_b32_e64 v117, v117, v130, s[6:7]
	v_add_f32_e32 v80, 1.0, v80
	v_rcp_f32_e32 v80, v80
	v_cvt_pk_bf16_f32 v92, v122, v105
	v_lshlrev_b32_e32 v105, 16, v113
	v_and_b32_e32 v106, 0xffff0000, v113
	v_lshlrev_b32_e32 v113, 16, v117
	v_add_f32_e32 v82, 1.0, v82
	v_mul_f32_e32 v81, v118, v113
	v_rcp_f32_e32 v82, v82
	v_and_b32_e32 v114, 0xffff0000, v117
	v_mul_f32_e32 v81, v34, v81
	v_fmac_f32_e32 v105, v80, v81
	v_mul_f32_e32 v80, v118, v114
	v_mul_f32_e32 v80, v35, v80
	v_fmac_f32_e32 v106, v82, v80
	v_mul_f32_e32 v80, v94, v94
	v_mul_f32_e32 v81, v102, v102
	v_fmac_f32_e32 v80, v93, v93
	v_fmac_f32_e32 v81, v95, v95
	v_add_f32_e32 v80, v80, v81
	v_mul_f32_e32 v81, v104, v104
	v_fmac_f32_e32 v81, v103, v103
	v_add_f32_e32 v80, v81, v80
	v_mul_f32_e32 v81, v106, v106
	v_fmac_f32_e32 v81, v105, v105
	v_add_f32_e32 v80, v81, v80
	v_add_f32_e32 v107, v80, v88
	v_cvt_pk_bf16_f32 v80, v93, v94
	v_cvt_pk_bf16_f32 v81, v95, v102
	v_cvt_pk_bf16_f32 v88, v103, v104
	v_cvt_pk_bf16_f32 v93, v105, v106
	v_mov_b32_e32 v95, 0
	v_mov_b32_e32 v86, 0
	v_mov_b32_dpp v85, v93 row_ror:8 row_mask:0xf bank_mask:0xf
	v_mov_b32_dpp v95, v92 row_ror:8 row_mask:0xf bank_mask:0xf
	v_cndmask_b32_e64 v85, v85, v92, s[6:7]
	ds_bpermute_b32 v92, v134, v107
	v_mov_b32_dpp v86, v89 row_ror:8 row_mask:0xf bank_mask:0xf
	v_mov_b32_dpp v87, v90 row_ror:8 row_mask:0xf bank_mask:0xf
	v_mov_b32_dpp v82, v80 row_ror:8 row_mask:0xf bank_mask:0xf
	v_mov_b32_dpp v83, v81 row_ror:8 row_mask:0xf bank_mask:0xf
	v_mov_b32_dpp v84, v88 row_ror:8 row_mask:0xf bank_mask:0xf
	v_cndmask_b32_e64 v86, v80, v86, s[6:7]
	v_cndmask_b32_e64 v87, v81, v87, s[6:7]
	v_lshl_add_u64 v[80:81], s[36:37], 0, v[98:99]
	v_mov_b32_dpp v94, v91 row_ror:8 row_mask:0xf bank_mask:0xf
	v_cndmask_b32_e64 v83, v83, v90, s[6:7]
	v_cndmask_b32_e64 v84, v84, v91, s[6:7]
	v_lshl_add_u64 v[90:91], v[80:81], 0, v[162:163]
	s_waitcnt lgkmcnt(0)
; __device__ __forceinline__ unsigned cvt_pk_bf16(float lo, float hi) { unsigned r; asm volatile("v_cvt_pk_bf16_f32 %0, %1, %2" : "=v"(r) : "v"(lo), "v"(hi)); return r; }
; __device__ __forceinline__ float bflo(unsigned w) { return __uint_as_float(w << 16); }
; __device__ __forceinline__ float bfhi(unsigned w) { return __uint_as_float(w & 0xffff0000u); }
;     __device__ __forceinline__ void operator()(const f32x4 (&acc)[2][2][4][2], const Unit& u, int wr, int wc, int fr, int fq) const {
;     ...
;             for (int m = 0; m < 4; ++m) { const int row = row0 + ai * HALF + m * 16; const size_t off = (size_t)row * D + col0; const float ri = __builtin_amdgcn_rsqf(sse[row] * (1.f / D) + EPS); float sq = 0.f; u32x4 w[2];
;                 u32x4 rr[2], ee[2]; load_pair_lines(R, D, row, fr, col0, rr[0], rr[1]); load_pair_lines(E, D, row, fr, col0, ee[0], ee[1]);
; #pragma unroll
;                 for (int bj = 0; bj < 2; ++bj) { const u32x4 rw = rr[bj], ew = ee[bj];
;                     const float r[8] = {bflo(rw.x), bfhi(rw.x), bflo(rw.y), bfhi(rw.y), bflo(rw.z), bfhi(rw.z), bflo(rw.w), bfhi(rw.w)};
;                     const float e[8] = {bflo(ew.x), bfhi(ew.x), bflo(ew.y), bfhi(ew.y), bflo(ew.z), bfhi(ew.z), bflo(ew.w), bfhi(ew.w)};
;                     float o[8];
; #pragma unroll
;                     for (int j = 0; j < 8; ++j) { const float a = acc[ai][bj][m][j >> 2][j & 3]; const float gg = gv[bj][j >> 2][j & 3];
;                         o[j] = r[j] + e[j] * ri * gg * __builtin_amdgcn_rcpf(1.f + __builtin_amdgcn_exp2f(-a * LOG2E)); }
;     ...
;                     else { sq += (o[0] * o[0] + o[1] * o[1]) + (o[2] * o[2] + o[3] * o[3]) + (o[4] * o[4] + o[5] * o[5]) + (o[6] * o[6] + o[7] * o[7]);
;                         w[bj].x = cvt_pk_bf16(o[0], o[1]); w[bj].y = cvt_pk_bf16(o[2], o[3]); w[bj].z = cvt_pk_bf16(o[4], o[5]); w[bj].w = cvt_pk_bf16(o[6], o[7]); } }
;                 if (!OUT) { store_pair_lines(O, D, row, fr, col0, w[0], w[1]);
;                     sq += __shfl_xor(sq, 16); sq += __shfl_xor(sq, 32); if (fq == 0) unsafeAtomicAdd(ssout + row, sq); } }
	v_add_f32_e32 v80, v107, v92
	v_mov_b32_e32 v81, v80
	s_nop 1
	v_permlane32_swap_b32_e32 v81, v80
	v_cndmask_b32_e64 v82, v82, v89, s[6:7]
	global_store_dwordx4 v[90:91], v[82:85], off
	v_cndmask_b32_e64 v88, v88, v94, s[6:7]
	v_cndmask_b32_e64 v89, v93, v95, s[6:7]
	v_lshl_add_u64 v[82:83], s[36:37], 0, v[100:101]
	v_lshl_add_u64 v[82:83], v[82:83], 0, v[162:163]
	global_store_dwordx4 v[82:83], v[86:89], off
	s_and_saveexec_b64 s[56:57], s[8:9]
	s_cbranch_execz .LBB0_891
	v_lshl_add_u64 v[82:83], v[96:97], 2, s[18:19]
	s_waitcnt lgkmcnt(0)
	v_add_f32_e32 v80, v80, v81
	global_atomic_add_f32 v[82:83], v80, off
.LBB0_891:
	s_or_b64 exec, exec, s[56:57]
	v_add_u32_e32 v80, 0x80, v164
	v_sub_u32_e32 v82, v80, v172
	v_add_u32_e32 v82, v82, v174
	v_ashrrev_i32_e32 v83, 31, v82
	v_lshlrev_b64 v[82:83], 12, v[82:83]
	v_lshl_add_u64 v[84:85], s[16:17], 0, v[82:83]
	v_lshl_add_u64 v[84:85], v[84:85], 0, v[162:163]
	s_waitcnt vmcnt(2)
	s_nop 0
	v_mov_b64_e32 v[86:87], v[228:229]
	v_mov_b64_e32 v[88:89], v[230:231]
	v_lshl_add_u64 v[84:85], s[38:39], 0, v[82:83]
	v_lshl_add_u64 v[84:85], v[84:85], 0, v[162:163]
	s_waitcnt lgkmcnt(0)
	v_mov_b32_e32 v81, v226
	v_mov_b64_e32 v[90:91], v[232:233]
	v_mov_b64_e32 v[92:93], v[234:235]
	v_lshl_add_u64 v[84:85], v[82:83], 0, s[44:45]
	v_lshl_add_u64 v[98:99], s[38:39], 0, v[84:85]
	v_lshl_add_u64 v[94:95], s[16:17], 0, v[84:85]
	v_lshl_add_u64 v[98:99], v[98:99], 0, v[162:163]
	v_lshl_add_u64 v[94:95], v[94:95], 0, v[162:163]
	v_mov_b64_e32 v[98:99], v[236:237]
	v_mov_b64_e32 v[100:101], v[238:239]
	v_mul_f32_e32 v76, 0xbfb8aa3b, v76
	v_mov_b64_e32 v[94:95], v[240:241]
	v_mov_b64_e32 v[96:97], v[242:243]
	s_nop 1
	v_add_u32_e32 v216, 0x90, v164
	v_sub_u32_e32 v218, v216, v172
	v_add_u32_e32 v218, v218, v174
	v_ashrrev_i32_e32 v219, 31, v218
	v_lshlrev_b64 v[218:219], 12, v[218:219]
	v_lshl_add_u64 v[220:221], s[16:17], 0, v[218:219]
	v_lshl_add_u64 v[220:221], v[220:221], 0, v[162:163]
	global_load_dwordx4 v[228:231], v[220:221], off
	v_lshl_add_u64 v[220:221], s[38:39], 0, v[218:219]
	v_lshl_add_u64 v[220:221], v[220:221], 0, v[162:163]
	global_load_dword v226, v[166:167], off offset:576
	global_load_dwordx4 v[232:235], v[220:221], off
	v_lshl_add_u64 v[220:221], v[218:219], 0, s[44:45]
	v_lshl_add_u64 v[224:225], s[38:39], 0, v[220:221]
	v_lshl_add_u64 v[222:223], s[16:17], 0, v[220:221]
	v_lshl_add_u64 v[224:225], v[224:225], 0, v[162:163]
	v_lshl_add_u64 v[222:223], v[222:223], 0, v[162:163]
	global_load_dwordx4 v[236:239], v[224:225], off
	global_load_dwordx4 v[240:243], v[222:223], off
	v_exp_f32_e32 v76, v76
	v_mul_f32_e32 v77, 0xbfb8aa3b, v77
	v_exp_f32_e32 v77, v77
	v_add_f32_e32 v76, 1.0, v76
	v_rcp_f32_e32 v76, v76
	v_add_f32_e32 v77, 1.0, v77
	v_rcp_f32_e32 v77, v77
	v_mul_f32_e32 v72, 0xbfb8aa3b, v72
	v_exp_f32_e32 v72, v72
	v_mul_f32_e32 v73, 0xbfb8aa3b, v73
	v_exp_f32_e32 v73, v73
	v_add_f32_e32 v72, 1.0, v72
	v_rcp_f32_e32 v72, v72
	v_add_f32_e32 v73, 1.0, v73
	v_mul_f32_e32 v68, 0xbfb8aa3b, v68
	v_rcp_f32_e32 v73, v73
	v_exp_f32_e32 v68, v68
	v_mul_f32_e32 v69, 0xbfb8aa3b, v69
	v_exp_f32_e32 v69, v69
	v_add_f32_e32 v68, 1.0, v68
	v_rcp_f32_e32 v68, v68
	v_add_f32_e32 v69, 1.0, v69
	v_rcp_f32_e32 v69, v69
	v_mul_f32_e32 v64, 0xbfb8aa3b, v64
	v_exp_f32_e32 v64, v64
	v_mul_f32_e32 v65, 0xbfb8aa3b, v65
	v_exp_f32_e32 v65, v65
	v_add_f32_e32 v64, 1.0, v64
	v_rcp_f32_e32 v64, v64
	v_add_f32_e32 v65, 1.0, v65
	v_rcp_f32_e32 v65, v65
	s_waitcnt vmcnt(33)
	v_mov_b32_dpp v102, v86 row_ror:8 row_mask:0xf bank_mask:0xf
	v_mov_b32_dpp v103, v87 row_ror:8 row_mask:0xf bank_mask:0xf
	v_mov_b32_dpp v104, v88 row_ror:8 row_mask:0xf bank_mask:0xf
	s_waitcnt vmcnt(33)
	v_fmamk_f32 v81, v81, 0x3a000000, v180
	v_rsq_f32_e32 v81, v81
	s_waitcnt vmcnt(33)
	v_mov_b32_dpp v110, v90 row_ror:8 row_mask:0xf bank_mask:0xf
	v_mov_b32_dpp v111, v91 row_ror:8 row_mask:0xf bank_mask:0xf
	v_mov_b32_dpp v112, v92 row_ror:8 row_mask:0xf bank_mask:0xf
	v_mov_b32_dpp v113, v93 row_ror:8 row_mask:0xf bank_mask:0xf
	v_mov_b32_dpp v105, v89 row_ror:8 row_mask:0xf bank_mask:0xf
	s_waitcnt vmcnt(33)
	v_mov_b32_dpp v114, v98 row_ror:8 row_mask:0xf bank_mask:0xf
	v_cndmask_b32_e64 v90, v114, v90, s[6:7]
	s_waitcnt vmcnt(33)
	v_mov_b32_dpp v106, v94 row_ror:8 row_mask:0xf bank_mask:0xf
	v_cndmask_b32_e64 v86, v106, v86, s[6:7]
	v_lshlrev_b32_e32 v106, 16, v90
	v_mul_f32_e32 v106, v81, v106
	v_cndmask_b32_e64 v94, v94, v102, s[6:7]
	v_lshlrev_b32_e32 v102, 16, v86
	v_and_b32_e32 v90, 0xffff0000, v90
	v_mul_f32_e32 v106, v52, v106
	v_fmac_f32_e32 v102, v76, v106
	v_mul_f32_e32 v76, v81, v90
	v_and_b32_e32 v86, 0xffff0000, v86
	v_mul_f32_e32 v76, v53, v76
	v_fmac_f32_e32 v86, v77, v76
	v_mul_f32_e32 v76, 0xbfb8aa3b, v78
	v_exp_f32_e32 v76, v76
	v_mul_f32_e32 v78, 0xbfb8aa3b, v79
	v_exp_f32_e32 v78, v78
	v_mov_b32_dpp v115, v99 row_ror:8 row_mask:0xf bank_mask:0xf
	v_add_f32_e32 v76, 1.0, v76
	v_mov_b32_dpp v107, v95 row_ror:8 row_mask:0xf bank_mask:0xf
	v_cndmask_b32_e64 v91, v115, v91, s[6:7]
	v_rcp_f32_e32 v76, v76
	v_cndmask_b32_e64 v87, v107, v87, s[6:7]
	v_lshlrev_b32_e32 v107, 16, v91
	v_add_f32_e32 v78, 1.0, v78
	v_mul_f32_e32 v77, v81, v107
	v_rcp_f32_e32 v78, v78
	v_cndmask_b32_e64 v95, v95, v103, s[6:7]
	v_mov_b32_dpp v116, v100 row_ror:8 row_mask:0xf bank_mask:0xf
	v_lshlrev_b32_e32 v103, 16, v87
	v_and_b32_e32 v91, 0xffff0000, v91
	v_mul_f32_e32 v77, v54, v77
	v_mov_b32_dpp v108, v96 row_ror:8 row_mask:0xf bank_mask:0xf
	v_cndmask_b32_e64 v92, v116, v92, s[6:7]
	v_fmac_f32_e32 v103, v76, v77
	v_mul_f32_e32 v76, v81, v91
	v_cndmask_b32_e64 v88, v108, v88, s[6:7]
	v_and_b32_e32 v87, 0xffff0000, v87
	v_lshlrev_b32_e32 v108, 16, v92
; __device__ __forceinline__ unsigned cvt_pk_bf16(float lo, float hi) { unsigned r; asm volatile("v_cvt_pk_bf16_f32 %0, %1, %2" : "=v"(r) : "v"(lo), "v"(hi)); return r; }
; __device__ __forceinline__ float bflo(unsigned w) { return __uint_as_float(w << 16); }
; __device__ __forceinline__ float bfhi(unsigned w) { return __uint_as_float(w & 0xffff0000u); }
;     __device__ __forceinline__ void operator()(const f32x4 (&acc)[2][2][4][2], const Unit& u, int wr, int wc, int fr, int fq) const {
;     ...
;                 for (int bj = 0; bj < 2; ++bj) { const u32x4 rw = rr[bj], ew = ee[bj];
;                     const float r[8] = {bflo(rw.x), bfhi(rw.x), bflo(rw.y), bfhi(rw.y), bflo(rw.z), bfhi(rw.z), bflo(rw.w), bfhi(rw.w)};
;                     const float e[8] = {bflo(ew.x), bfhi(ew.x), bflo(ew.y), bfhi(ew.y), bflo(ew.z), bfhi(ew.z), bflo(ew.w), bfhi(ew.w)};
;                     float o[8];
; #pragma unroll
;                     for (int j = 0; j < 8; ++j) { const float a = acc[ai][bj][m][j >> 2][j & 3]; const float gg = gv[bj][j >> 2][j & 3];
;                         o[j] = r[j] + e[j] * ri * gg * __builtin_amdgcn_rcpf(1.f + __builtin_amdgcn_exp2f(-a * LOG2E)); }
;                     if (OUT) { *(f32x4*)(OUT + off + 8 * bj) = (f32x4){o[0], o[1], o[2], o[3]}; *(f32x4*)(OUT + off + 8 * bj + 4) = (f32x4){o[4], o[5], o[6], o[7]}; }
;                     else { sq += (o[0] * o[0] + o[1] * o[1]) + (o[2] * o[2] + o[3] * o[3]) + (o[4] * o[4] + o[5] * o[5]) + (o[6] * o[6] + o[7] * o[7]);
;                         w[bj].x = cvt_pk_bf16(o[0], o[1]); w[bj].y = cvt_pk_bf16(o[2], o[3]); w[bj].z = cvt_pk_bf16(o[4], o[5]); w[bj].w = cvt_pk_bf16(o[6], o[7]); } }
;                 if (!OUT) { store_pair_lines(O, D, row, fr, col0, w[0], w[1]);
;                     sq += __shfl_xor(sq, 16); sq += __shfl_xor(sq, 32); if (fq == 0) unsafeAtomicAdd(ssout + row, sq); } }
	v_mul_f32_e32 v76, v55, v76
	v_fmac_f32_e32 v87, v78, v76
	v_mul_f32_e32 v76, v81, v108
	v_cndmask_b32_e64 v96, v96, v104, s[6:7]
	v_lshlrev_b32_e32 v104, 16, v88
	v_and_b32_e32 v92, 0xffff0000, v92
	v_mul_f32_e32 v76, v48, v76
	v_fmac_f32_e32 v104, v72, v76
	v_mul_f32_e32 v72, v81, v92
	v_and_b32_e32 v88, 0xffff0000, v88
	v_mul_f32_e32 v72, v49, v72
	v_fmac_f32_e32 v88, v73, v72
	v_mul_f32_e32 v72, 0xbfb8aa3b, v74
	v_cndmask_b32_e64 v98, v98, v110, s[6:7]
	v_exp_f32_e32 v72, v72
	v_mul_f32_e32 v74, 0xbfb8aa3b, v75
	v_lshlrev_b32_e32 v91, 16, v98
	v_exp_f32_e32 v74, v74
	v_mul_f32_e32 v91, v81, v91
	v_lshlrev_b32_e32 v77, 16, v94
	v_and_b32_e32 v92, 0xffff0000, v98
	v_mul_f32_e32 v91, v40, v91
	v_mov_b32_dpp v117, v101 row_ror:8 row_mask:0xf bank_mask:0xf
	v_add_f32_e32 v72, 1.0, v72
	v_fmac_f32_e32 v77, v68, v91
	v_mul_f32_e32 v68, v81, v92
	v_mov_b32_dpp v109, v97 row_ror:8 row_mask:0xf bank_mask:0xf
	v_cndmask_b32_e64 v93, v117, v93, s[6:7]
	v_rcp_f32_e32 v72, v72
	v_and_b32_e32 v78, 0xffff0000, v94
	v_mul_f32_e32 v68, v41, v68
	v_cndmask_b32_e64 v89, v109, v89, s[6:7]
	v_lshlrev_b32_e32 v109, 16, v93
	v_add_f32_e32 v74, 1.0, v74
	v_fmac_f32_e32 v78, v69, v68
	v_mul_f32_e32 v68, 0xbfb8aa3b, v70
	v_mul_f32_e32 v73, v81, v109
	v_rcp_f32_e32 v74, v74
	v_exp_f32_e32 v68, v68
	v_cndmask_b32_e64 v97, v97, v105, s[6:7]
	v_lshlrev_b32_e32 v105, 16, v89
	v_and_b32_e32 v93, 0xffff0000, v93
	v_mul_f32_e32 v73, v50, v73
	v_mul_f32_e32 v70, 0xbfb8aa3b, v71
	v_fmac_f32_e32 v105, v72, v73
	v_mul_f32_e32 v72, v81, v93
	v_exp_f32_e32 v70, v70
	v_and_b32_e32 v89, 0xffff0000, v89
	v_mul_f32_e32 v72, v51, v72
	v_fmac_f32_e32 v89, v74, v72
	v_mul_f32_e32 v72, v86, v86
	v_mul_f32_e32 v73, v87, v87
	v_add_f32_e32 v68, 1.0, v68
	v_cndmask_b32_e64 v99, v99, v111, s[6:7]
	v_fmac_f32_e32 v72, v102, v102
	v_fmac_f32_e32 v73, v103, v103
	v_rcp_f32_e32 v68, v68
	v_add_f32_e32 v72, v72, v73
	v_mul_f32_e32 v73, v88, v88
	v_lshlrev_b32_e32 v93, 16, v99
	v_add_f32_e32 v70, 1.0, v70
	v_fmac_f32_e32 v73, v104, v104
	v_mul_f32_e32 v69, v81, v93
	v_rcp_f32_e32 v70, v70
	v_add_f32_e32 v72, v73, v72
	v_mul_f32_e32 v73, v89, v89
	v_lshlrev_b32_e32 v79, 16, v95
	v_and_b32_e32 v94, 0xffff0000, v99
	v_mul_f32_e32 v69, v42, v69
	v_cndmask_b32_e64 v100, v100, v112, s[6:7]
	v_fmac_f32_e32 v73, v105, v105
	v_fmac_f32_e32 v79, v68, v69
	v_mul_f32_e32 v68, v81, v94
	v_add_f32_e32 v72, v73, v72
	v_cvt_pk_bf16_f32 v73, v102, v86
	v_and_b32_e32 v86, 0xffff0000, v95
	v_lshlrev_b32_e32 v95, 16, v100
	v_mul_f32_e32 v68, v43, v68
	v_fmac_f32_e32 v86, v70, v68
	v_mul_f32_e32 v68, v81, v95
	v_cvt_pk_bf16_f32 v74, v103, v87
	v_cvt_pk_bf16_f32 v75, v104, v88
	v_lshlrev_b32_e32 v87, 16, v96
	v_and_b32_e32 v88, 0xffff0000, v96
	v_and_b32_e32 v96, 0xffff0000, v100
	v_mul_f32_e32 v68, v32, v68
	v_fmac_f32_e32 v87, v64, v68
	v_mul_f32_e32 v64, v81, v96
	v_mul_f32_e32 v64, v33, v64
	v_fmac_f32_e32 v88, v65, v64
	v_mul_f32_e32 v64, 0xbfb8aa3b, v66
	v_exp_f32_e32 v64, v64
	v_mul_f32_e32 v66, 0xbfb8aa3b, v67
	v_exp_f32_e32 v66, v66
	v_cndmask_b32_e64 v101, v101, v113, s[6:7]
	v_add_f32_e32 v64, 1.0, v64
	v_rcp_f32_e32 v64, v64
	v_cvt_pk_bf16_f32 v76, v105, v89
	v_lshlrev_b32_e32 v89, 16, v97
	v_and_b32_e32 v90, 0xffff0000, v97
	v_lshlrev_b32_e32 v97, 16, v101
	v_add_f32_e32 v66, 1.0, v66
	v_mul_f32_e32 v65, v81, v97
	v_rcp_f32_e32 v66, v66
	v_and_b32_e32 v98, 0xffff0000, v101
	v_mul_f32_e32 v65, v34, v65
	v_fmac_f32_e32 v89, v64, v65
	v_mul_f32_e32 v64, v81, v98
	v_mul_f32_e32 v64, v35, v64
	v_fmac_f32_e32 v90, v66, v64
	v_mul_f32_e32 v64, v78, v78
	v_mul_f32_e32 v65, v86, v86
	v_fmac_f32_e32 v64, v77, v77
	v_fmac_f32_e32 v65, v79, v79
	v_add_f32_e32 v64, v64, v65
	v_mul_f32_e32 v65, v88, v88
	v_fmac_f32_e32 v65, v87, v87
	v_add_f32_e32 v64, v65, v64
	v_mul_f32_e32 v65, v90, v90
	v_fmac_f32_e32 v65, v89, v89
	v_add_f32_e32 v64, v65, v64
	v_add_f32_e32 v81, v64, v72
	v_cvt_pk_bf16_f32 v64, v77, v78
	v_cvt_pk_bf16_f32 v65, v79, v86
	v_cvt_pk_bf16_f32 v72, v87, v88
	v_cvt_pk_bf16_f32 v77, v89, v90
	v_mov_b32_e32 v79, 0
	v_mov_b32_e32 v70, 0
	v_mov_b32_dpp v69, v77 row_ror:8 row_mask:0xf bank_mask:0xf
	v_mov_b32_dpp v79, v76 row_ror:8 row_mask:0xf bank_mask:0xf
	v_cndmask_b32_e64 v69, v69, v76, s[6:7]
	v_mov_b32_e32 v76, v81
	s_nop 1
	v_permlane16_swap_b32_e32 v76, v81
	v_mov_b32_dpp v70, v73 row_ror:8 row_mask:0xf bank_mask:0xf
	v_mov_b32_dpp v71, v74 row_ror:8 row_mask:0xf bank_mask:0xf
	v_mov_b32_dpp v66, v64 row_ror:8 row_mask:0xf bank_mask:0xf
	v_mov_b32_dpp v67, v65 row_ror:8 row_mask:0xf bank_mask:0xf
	v_mov_b32_dpp v68, v72 row_ror:8 row_mask:0xf bank_mask:0xf
	v_cndmask_b32_e64 v70, v64, v70, s[6:7]
	v_cndmask_b32_e64 v71, v65, v71, s[6:7]
	v_lshl_add_u64 v[64:65], s[36:37], 0, v[82:83]
	v_mov_b32_dpp v78, v75 row_ror:8 row_mask:0xf bank_mask:0xf
	v_cndmask_b32_e64 v67, v67, v74, s[6:7]
	v_cndmask_b32_e64 v68, v68, v75, s[6:7]
	v_lshl_add_u64 v[74:75], v[64:65], 0, v[162:163]
	s_waitcnt lgkmcnt(0)
	v_add_f32_e32 v64, v81, v76
	v_mov_b32_e32 v65, v64
	s_nop 1
	v_permlane32_swap_b32_e32 v65, v64
	v_cndmask_b32_e64 v66, v66, v73, s[6:7]
	global_store_dwordx4 v[74:75], v[66:69], off
	v_cndmask_b32_e64 v72, v72, v78, s[6:7]
	v_cndmask_b32_e64 v73, v77, v79, s[6:7]
	v_lshl_add_u64 v[66:67], s[36:37], 0, v[84:85]
	v_lshl_add_u64 v[66:67], v[66:67], 0, v[162:163]
	global_store_dwordx4 v[66:67], v[70:73], off
	s_and_saveexec_b64 s[56:57], s[8:9]
	s_cbranch_execz .LBB0_893
	v_ashrrev_i32_e32 v81, 31, v80
	v_lshl_add_u64 v[66:67], v[80:81], 2, s[18:19]
	s_waitcnt lgkmcnt(0)
	v_add_f32_e32 v64, v64, v65
	global_atomic_add_f32 v[66:67], v64, off
; __device__ __forceinline__ unsigned cvt_pk_bf16(float lo, float hi) { unsigned r; asm volatile("v_cvt_pk_bf16_f32 %0, %1, %2" : "=v"(r) : "v"(lo), "v"(hi)); return r; }
; __device__ __forceinline__ float bflo(unsigned w) { return __uint_as_float(w << 16); }
; __device__ __forceinline__ float bfhi(unsigned w) { return __uint_as_float(w & 0xffff0000u); }
;     __device__ __forceinline__ void operator()(const f32x4 (&acc)[2][2][4][2], const Unit& u, int wr, int wc, int fr, int fq) const {
;     ...
;             for (int m = 0; m < 4; ++m) { const int row = row0 + ai * HALF + m * 16; const size_t off = (size_t)row * D + col0; const float ri = __builtin_amdgcn_rsqf(sse[row] * (1.f / D) + EPS); float sq = 0.f; u32x4 w[2];
;                 u32x4 rr[2], ee[2]; load_pair_lines(R, D, row, fr, col0, rr[0], rr[1]); load_pair_lines(E, D, row, fr, col0, ee[0], ee[1]);
; #pragma unroll
;                 for (int bj = 0; bj < 2; ++bj) { const u32x4 rw = rr[bj], ew = ee[bj];
;                     const float r[8] = {bflo(rw.x), bfhi(rw.x), bflo(rw.y), bfhi(rw.y), bflo(rw.z), bfhi(rw.z), bflo(rw.w), bfhi(rw.w)};
;                     const float e[8] = {bflo(ew.x), bfhi(ew.x), bflo(ew.y), bfhi(ew.y), bflo(ew.z), bfhi(ew.z), bflo(ew.w), bfhi(ew.w)};
;                     float o[8];
; #pragma unroll
;                     for (int j = 0; j < 8; ++j) { const float a = acc[ai][bj][m][j >> 2][j & 3]; const float gg = gv[bj][j >> 2][j & 3];
;                         o[j] = r[j] + e[j] * ri * gg * __builtin_amdgcn_rcpf(1.f + __builtin_amdgcn_exp2f(-a * LOG2E)); }
;                     if (OUT) { *(f32x4*)(OUT + off + 8 * bj) = (f32x4){o[0], o[1], o[2], o[3]}; *(f32x4*)(OUT + off + 8 * bj + 4) = (f32x4){o[4], o[5], o[6], o[7]}; }
;                     else { sq += (o[0] * o[0] + o[1] * o[1]) + (o[2] * o[2] + o[3] * o[3]) + (o[4] * o[4] + o[5] * o[5]) + (o[6] * o[6] + o[7] * o[7]);
;                         w[bj].x = cvt_pk_bf16(o[0], o[1]); w[bj].y = cvt_pk_bf16(o[2], o[3]); w[bj].z = cvt_pk_bf16(o[4], o[5]); w[bj].w = cvt_pk_bf16(o[6], o[7]); } }
.LBB0_893:
	s_or_b64 exec, exec, s[56:57]
	v_add_u32_e32 v64, 0x90, v164
	v_sub_u32_e32 v66, v64, v172
	v_add_u32_e32 v66, v66, v174
	v_ashrrev_i32_e32 v67, 31, v66
	v_lshlrev_b64 v[66:67], 12, v[66:67]
	v_lshl_add_u64 v[68:69], s[16:17], 0, v[66:67]
	v_lshl_add_u64 v[68:69], v[68:69], 0, v[162:163]
	s_waitcnt vmcnt(2)
	s_nop 0
	v_mov_b64_e32 v[70:71], v[228:229]
	v_mov_b64_e32 v[72:73], v[230:231]
	v_lshl_add_u64 v[68:69], s[38:39], 0, v[66:67]
	v_lshl_add_u64 v[68:69], v[68:69], 0, v[162:163]
	s_waitcnt lgkmcnt(0)
	v_mov_b32_e32 v65, v226
	v_mov_b64_e32 v[74:75], v[232:233]
	v_mov_b64_e32 v[76:77], v[234:235]
	v_lshl_add_u64 v[68:69], v[66:67], 0, s[44:45]
	v_lshl_add_u64 v[82:83], s[38:39], 0, v[68:69]
	v_lshl_add_u64 v[78:79], s[16:17], 0, v[68:69]
	v_lshl_add_u64 v[82:83], v[82:83], 0, v[162:163]
	v_lshl_add_u64 v[78:79], v[78:79], 0, v[162:163]
	v_mov_b64_e32 v[82:83], v[236:237]
	v_mov_b64_e32 v[84:85], v[238:239]
	v_mul_f32_e32 v60, 0xbfb8aa3b, v60
	v_mov_b64_e32 v[78:79], v[240:241]
	v_mov_b64_e32 v[80:81], v[242:243]
	s_nop 1
	v_add_u32_e32 v216, 0xa0, v164
	v_sub_u32_e32 v218, v216, v172
	v_add_u32_e32 v218, v218, v174
	v_ashrrev_i32_e32 v219, 31, v218
	v_lshlrev_b64 v[218:219], 12, v[218:219]
	v_lshl_add_u64 v[220:221], s[16:17], 0, v[218:219]
	v_lshl_add_u64 v[220:221], v[220:221], 0, v[162:163]
	global_load_dwordx4 v[228:231], v[220:221], off
	v_lshl_add_u64 v[220:221], s[38:39], 0, v[218:219]
	v_lshl_add_u64 v[220:221], v[220:221], 0, v[162:163]
	global_load_dword v226, v[166:167], off offset:640
	global_load_dwordx4 v[232:235], v[220:221], off
	v_lshl_add_u64 v[220:221], v[218:219], 0, s[44:45]
	v_lshl_add_u64 v[222:223], s[16:17], 0, v[220:221]
	v_lshl_add_u64 v[222:223], v[222:223], 0, v[162:163]
	global_load_dwordx4 v[236:239], v[222:223], off
	v_lshl_add_u64 v[222:223], s[38:39], 0, v[220:221]
	v_lshl_add_u64 v[222:223], v[222:223], 0, v[162:163]
	global_load_dwordx4 v[240:243], v[222:223], off
	v_exp_f32_e32 v60, v60
	v_mul_f32_e32 v61, 0xbfb8aa3b, v61
	v_exp_f32_e32 v61, v61
	v_add_f32_e32 v60, 1.0, v60
	v_rcp_f32_e32 v60, v60
	v_add_f32_e32 v61, 1.0, v61
	v_rcp_f32_e32 v61, v61
	v_mul_f32_e32 v56, 0xbfb8aa3b, v56
	v_exp_f32_e32 v56, v56
	v_mul_f32_e32 v57, 0xbfb8aa3b, v57
	v_exp_f32_e32 v57, v57
	v_add_f32_e32 v56, 1.0, v56
	v_rcp_f32_e32 v56, v56
	v_add_f32_e32 v57, 1.0, v57
	v_mul_f32_e32 v44, 0xbfb8aa3b, v44
	v_rcp_f32_e32 v57, v57
	v_exp_f32_e32 v44, v44
	v_mul_f32_e32 v45, 0xbfb8aa3b, v45
	v_exp_f32_e32 v45, v45
	v_add_f32_e32 v44, 1.0, v44
	v_rcp_f32_e32 v44, v44
	v_add_f32_e32 v45, 1.0, v45
	v_rcp_f32_e32 v45, v45
	v_mul_f32_e32 v36, 0xbfb8aa3b, v36
	v_exp_f32_e32 v36, v36
	v_mul_f32_e32 v37, 0xbfb8aa3b, v37
	v_exp_f32_e32 v37, v37
	v_add_f32_e32 v36, 1.0, v36
	v_rcp_f32_e32 v36, v36
	v_add_f32_e32 v37, 1.0, v37
	v_rcp_f32_e32 v37, v37
	s_waitcnt vmcnt(40)
	v_mov_b32_dpp v86, v70 row_ror:8 row_mask:0xf bank_mask:0xf
	v_mov_b32_dpp v87, v71 row_ror:8 row_mask:0xf bank_mask:0xf
	v_mov_b32_dpp v88, v72 row_ror:8 row_mask:0xf bank_mask:0xf
	s_waitcnt vmcnt(40)
	v_fmamk_f32 v65, v65, 0x3a000000, v180
	v_rsq_f32_e32 v65, v65
	s_waitcnt vmcnt(40)
	v_mov_b32_dpp v94, v74 row_ror:8 row_mask:0xf bank_mask:0xf
	v_mov_b32_dpp v95, v75 row_ror:8 row_mask:0xf bank_mask:0xf
	v_mov_b32_dpp v96, v76 row_ror:8 row_mask:0xf bank_mask:0xf
	v_mov_b32_dpp v97, v77 row_ror:8 row_mask:0xf bank_mask:0xf
	v_mov_b32_dpp v89, v73 row_ror:8 row_mask:0xf bank_mask:0xf
	s_waitcnt vmcnt(40)
	v_mov_b32_dpp v98, v82 row_ror:8 row_mask:0xf bank_mask:0xf
	v_cndmask_b32_e64 v74, v98, v74, s[6:7]
	s_waitcnt vmcnt(40)
	v_mov_b32_dpp v90, v78 row_ror:8 row_mask:0xf bank_mask:0xf
	v_cndmask_b32_e64 v70, v90, v70, s[6:7]
	v_lshlrev_b32_e32 v90, 16, v74
	v_mul_f32_e32 v90, v65, v90
	v_cndmask_b32_e64 v78, v78, v86, s[6:7]
	v_lshlrev_b32_e32 v86, 16, v70
	v_and_b32_e32 v74, 0xffff0000, v74
	v_mul_f32_e32 v90, v52, v90
	v_fmac_f32_e32 v86, v60, v90
	v_mul_f32_e32 v60, v65, v74
	v_and_b32_e32 v70, 0xffff0000, v70
	v_mul_f32_e32 v60, v53, v60
	v_fmac_f32_e32 v70, v61, v60
	v_mul_f32_e32 v60, 0xbfb8aa3b, v62
	v_exp_f32_e32 v60, v60
	v_mul_f32_e32 v62, 0xbfb8aa3b, v63
	v_exp_f32_e32 v62, v62
	v_mov_b32_dpp v99, v83 row_ror:8 row_mask:0xf bank_mask:0xf
	v_add_f32_e32 v60, 1.0, v60
	v_mov_b32_dpp v91, v79 row_ror:8 row_mask:0xf bank_mask:0xf
	v_cndmask_b32_e64 v75, v99, v75, s[6:7]
	v_rcp_f32_e32 v60, v60
	v_cndmask_b32_e64 v71, v91, v71, s[6:7]
	v_lshlrev_b32_e32 v91, 16, v75
	v_add_f32_e32 v62, 1.0, v62
	v_mul_f32_e32 v61, v65, v91
	v_rcp_f32_e32 v62, v62
	v_cndmask_b32_e64 v79, v79, v87, s[6:7]
	v_mov_b32_dpp v100, v84 row_ror:8 row_mask:0xf bank_mask:0xf
	v_lshlrev_b32_e32 v87, 16, v71
	v_and_b32_e32 v75, 0xffff0000, v75
	v_mul_f32_e32 v61, v54, v61
	v_mov_b32_dpp v92, v80 row_ror:8 row_mask:0xf bank_mask:0xf
	v_cndmask_b32_e64 v76, v100, v76, s[6:7]
	v_fmac_f32_e32 v87, v60, v61
	v_mul_f32_e32 v60, v65, v75
	v_cndmask_b32_e64 v72, v92, v72, s[6:7]
	v_and_b32_e32 v71, 0xffff0000, v71
	v_lshlrev_b32_e32 v92, 16, v76
	v_mul_f32_e32 v60, v55, v60
	v_fmac_f32_e32 v71, v62, v60
	v_mul_f32_e32 v60, v65, v92
	v_cndmask_b32_e64 v80, v80, v88, s[6:7]
	v_lshlrev_b32_e32 v88, 16, v72
	v_and_b32_e32 v76, 0xffff0000, v76
	v_mul_f32_e32 v60, v48, v60
	v_fmac_f32_e32 v88, v56, v60
	v_mul_f32_e32 v56, v65, v76
	v_and_b32_e32 v72, 0xffff0000, v72
	v_mul_f32_e32 v56, v49, v56
	v_fmac_f32_e32 v72, v57, v56
	v_mul_f32_e32 v56, 0xbfb8aa3b, v58
	v_cndmask_b32_e64 v82, v82, v94, s[6:7]
	v_exp_f32_e32 v56, v56
	v_mul_f32_e32 v58, 0xbfb8aa3b, v59
	v_lshlrev_b32_e32 v75, 16, v82
	v_exp_f32_e32 v58, v58
	v_mul_f32_e32 v75, v65, v75
	v_lshlrev_b32_e32 v61, 16, v78
; __device__ __forceinline__ unsigned cvt_pk_bf16(float lo, float hi) { unsigned r; asm volatile("v_cvt_pk_bf16_f32 %0, %1, %2" : "=v"(r) : "v"(lo), "v"(hi)); return r; }
;     __device__ __forceinline__ void operator()(const f32x4 (&acc)[2][2][4][2], const Unit& u, int wr, int wc, int fr, int fq) const {
;     ...
;                     for (int j = 0; j < 8; ++j) { const float a = acc[ai][bj][m][j >> 2][j & 3]; const float gg = gv[bj][j >> 2][j & 3];
;                         o[j] = r[j] + e[j] * ri * gg * __builtin_amdgcn_rcpf(1.f + __builtin_amdgcn_exp2f(-a * LOG2E)); }
;                     if (OUT) { *(f32x4*)(OUT + off + 8 * bj) = (f32x4){o[0], o[1], o[2], o[3]}; *(f32x4*)(OUT + off + 8 * bj + 4) = (f32x4){o[4], o[5], o[6], o[7]}; }
;                     else { sq += (o[0] * o[0] + o[1] * o[1]) + (o[2] * o[2] + o[3] * o[3]) + (o[4] * o[4] + o[5] * o[5]) + (o[6] * o[6] + o[7] * o[7]);
;                         w[bj].x = cvt_pk_bf16(o[0], o[1]); w[bj].y = cvt_pk_bf16(o[2], o[3]); w[bj].z = cvt_pk_bf16(o[4], o[5]); w[bj].w = cvt_pk_bf16(o[6], o[7]); } }
;                 if (!OUT) { store_pair_lines(O, D, row, fr, col0, w[0], w[1]);
;                     sq += __shfl_xor(sq, 16); sq += __shfl_xor(sq, 32); if (fq == 0) unsafeAtomicAdd(ssout + row, sq); } }
	v_and_b32_e32 v76, 0xffff0000, v82
	v_mul_f32_e32 v75, v40, v75
	v_mov_b32_dpp v101, v85 row_ror:8 row_mask:0xf bank_mask:0xf
	v_add_f32_e32 v56, 1.0, v56
	v_fmac_f32_e32 v61, v44, v75
	v_mul_f32_e32 v44, v65, v76
	v_mov_b32_dpp v93, v81 row_ror:8 row_mask:0xf bank_mask:0xf
	v_cndmask_b32_e64 v77, v101, v77, s[6:7]
	v_rcp_f32_e32 v56, v56
	v_and_b32_e32 v62, 0xffff0000, v78
	v_mul_f32_e32 v44, v41, v44
	v_cndmask_b32_e64 v73, v93, v73, s[6:7]
	v_lshlrev_b32_e32 v93, 16, v77
	v_add_f32_e32 v58, 1.0, v58
	v_fmac_f32_e32 v62, v45, v44
	v_mul_f32_e32 v44, 0xbfb8aa3b, v46
	v_mul_f32_e32 v57, v65, v93
	v_rcp_f32_e32 v58, v58
	v_exp_f32_e32 v44, v44
	v_cndmask_b32_e64 v81, v81, v89, s[6:7]
	v_lshlrev_b32_e32 v89, 16, v73
	v_and_b32_e32 v77, 0xffff0000, v77
	v_mul_f32_e32 v57, v50, v57
	v_mul_f32_e32 v46, 0xbfb8aa3b, v47
	v_fmac_f32_e32 v89, v56, v57
	v_mul_f32_e32 v56, v65, v77
	v_exp_f32_e32 v46, v46
	v_and_b32_e32 v73, 0xffff0000, v73
	v_mul_f32_e32 v56, v51, v56
	v_fmac_f32_e32 v73, v58, v56
	v_mul_f32_e32 v56, v70, v70
	v_mul_f32_e32 v57, v71, v71
	v_add_f32_e32 v44, 1.0, v44
	v_cndmask_b32_e64 v83, v83, v95, s[6:7]
	v_fmac_f32_e32 v56, v86, v86
	v_fmac_f32_e32 v57, v87, v87
	v_rcp_f32_e32 v44, v44
	v_add_f32_e32 v56, v56, v57
	v_mul_f32_e32 v57, v72, v72
	v_lshlrev_b32_e32 v77, 16, v83
	v_add_f32_e32 v46, 1.0, v46
	v_fmac_f32_e32 v57, v88, v88
	v_mul_f32_e32 v45, v65, v77
	v_rcp_f32_e32 v46, v46
	v_add_f32_e32 v56, v57, v56
	v_mul_f32_e32 v57, v73, v73
	v_lshlrev_b32_e32 v63, 16, v79
	v_and_b32_e32 v78, 0xffff0000, v83
	v_mul_f32_e32 v45, v42, v45
	v_cndmask_b32_e64 v84, v84, v96, s[6:7]
	v_fmac_f32_e32 v57, v89, v89
	v_fmac_f32_e32 v63, v44, v45
	v_mul_f32_e32 v44, v65, v78
	v_add_f32_e32 v56, v57, v56
	v_cvt_pk_bf16_f32 v57, v86, v70
	v_and_b32_e32 v70, 0xffff0000, v79
	v_lshlrev_b32_e32 v79, 16, v84
	v_mul_f32_e32 v44, v43, v44
	v_fmac_f32_e32 v70, v46, v44
	v_mul_f32_e32 v44, v65, v79
	v_cvt_pk_bf16_f32 v58, v87, v71
	v_cvt_pk_bf16_f32 v59, v88, v72
	v_lshlrev_b32_e32 v71, 16, v80
	v_and_b32_e32 v72, 0xffff0000, v80
	v_and_b32_e32 v80, 0xffff0000, v84
	v_mul_f32_e32 v44, v32, v44
	v_fmac_f32_e32 v71, v36, v44
	v_mul_f32_e32 v36, v65, v80
	v_mul_f32_e32 v36, v33, v36
	v_fmac_f32_e32 v72, v37, v36
	v_mul_f32_e32 v36, 0xbfb8aa3b, v38
	v_exp_f32_e32 v36, v36
	v_mul_f32_e32 v38, 0xbfb8aa3b, v39
	v_exp_f32_e32 v38, v38
	v_cndmask_b32_e64 v85, v85, v97, s[6:7]
	v_add_f32_e32 v36, 1.0, v36
	v_rcp_f32_e32 v36, v36
	v_cvt_pk_bf16_f32 v60, v89, v73
	v_lshlrev_b32_e32 v73, 16, v81
	v_and_b32_e32 v74, 0xffff0000, v81
	v_lshlrev_b32_e32 v81, 16, v85
	v_add_f32_e32 v38, 1.0, v38
	v_mul_f32_e32 v37, v65, v81
	v_rcp_f32_e32 v38, v38
	v_and_b32_e32 v82, 0xffff0000, v85
	v_mul_f32_e32 v37, v34, v37
	v_fmac_f32_e32 v73, v36, v37
	v_mul_f32_e32 v36, v65, v82
	v_mul_f32_e32 v36, v35, v36
	v_fmac_f32_e32 v74, v38, v36
	v_mul_f32_e32 v36, v62, v62
	v_mul_f32_e32 v37, v70, v70
	v_fmac_f32_e32 v36, v61, v61
	v_fmac_f32_e32 v37, v63, v63
	v_add_f32_e32 v36, v36, v37
	v_mul_f32_e32 v37, v72, v72
	v_fmac_f32_e32 v37, v71, v71
	v_add_f32_e32 v36, v37, v36
	v_mul_f32_e32 v37, v74, v74
	v_fmac_f32_e32 v37, v73, v73
	v_add_f32_e32 v36, v37, v36
	v_add_f32_e32 v65, v36, v56
	v_cvt_pk_bf16_f32 v36, v61, v62
	v_cvt_pk_bf16_f32 v37, v63, v70
	v_cvt_pk_bf16_f32 v38, v71, v72
	v_cvt_pk_bf16_f32 v39, v73, v74
	v_mov_b32_e32 v63, 0
	v_mov_b32_e32 v56, 0
	v_mov_b32_dpp v47, v39 row_ror:8 row_mask:0xf bank_mask:0xf
	v_mov_b32_dpp v63, v60 row_ror:8 row_mask:0xf bank_mask:0xf
	v_cndmask_b32_e64 v47, v47, v60, s[6:7]
	v_mov_b32_e32 v60, v65
	s_nop 1
	v_permlane16_swap_b32_e32 v60, v65
	v_mov_b32_dpp v56, v57 row_ror:8 row_mask:0xf bank_mask:0xf
	v_mov_b32_dpp v61, v58 row_ror:8 row_mask:0xf bank_mask:0xf
	v_mov_b32_dpp v44, v36 row_ror:8 row_mask:0xf bank_mask:0xf
	v_mov_b32_dpp v62, v59 row_ror:8 row_mask:0xf bank_mask:0xf
	v_mov_b32_dpp v45, v37 row_ror:8 row_mask:0xf bank_mask:0xf
	v_mov_b32_dpp v46, v38 row_ror:8 row_mask:0xf bank_mask:0xf
	v_cndmask_b32_e64 v44, v44, v57, s[6:7]
	v_cndmask_b32_e64 v56, v36, v56, s[6:7]
	v_cndmask_b32_e64 v57, v37, v61, s[6:7]
	v_lshl_add_u64 v[36:37], s[36:37], 0, v[66:67]
	v_cndmask_b32_e64 v45, v45, v58, s[6:7]
	v_cndmask_b32_e64 v46, v46, v59, s[6:7]
	v_cndmask_b32_e64 v58, v38, v62, s[6:7]
	v_cndmask_b32_e64 v59, v39, v63, s[6:7]
	v_lshl_add_u64 v[38:39], v[36:37], 0, v[162:163]
	s_waitcnt lgkmcnt(0)
	v_add_f32_e32 v36, v65, v60
	v_mov_b32_e32 v37, v36
	s_nop 1
	v_permlane32_swap_b32_e32 v37, v36
	global_store_dwordx4 v[38:39], v[44:47], off
	v_lshl_add_u64 v[38:39], s[36:37], 0, v[68:69]
	v_lshl_add_u64 v[38:39], v[38:39], 0, v[162:163]
	global_store_dwordx4 v[38:39], v[56:59], off
	s_and_saveexec_b64 s[56:57], s[8:9]
	s_cbranch_execz .LBB0_895
	v_ashrrev_i32_e32 v65, 31, v64
	v_lshl_add_u64 v[38:39], v[64:65], 2, s[18:19]
	s_waitcnt lgkmcnt(0)
	v_add_f32_e32 v36, v36, v37
	global_atomic_add_f32 v[38:39], v36, off
; __device__ __forceinline__ unsigned cvt_pk_bf16(float lo, float hi) { unsigned r; asm volatile("v_cvt_pk_bf16_f32 %0, %1, %2" : "=v"(r) : "v"(lo), "v"(hi)); return r; }
; __device__ __forceinline__ float bflo(unsigned w) { return __uint_as_float(w << 16); }
; __device__ __forceinline__ float bfhi(unsigned w) { return __uint_as_float(w & 0xffff0000u); }
;     __device__ __forceinline__ void operator()(const f32x4 (&acc)[2][2][4][2], const Unit& u, int wr, int wc, int fr, int fq) const {
;     ...
;             for (int m = 0; m < 4; ++m) { const int row = row0 + ai * HALF + m * 16; const size_t off = (size_t)row * D + col0; const float ri = __builtin_amdgcn_rsqf(sse[row] * (1.f / D) + EPS); float sq = 0.f; u32x4 w[2];
;                 u32x4 rr[2], ee[2]; load_pair_lines(R, D, row, fr, col0, rr[0], rr[1]); load_pair_lines(E, D, row, fr, col0, ee[0], ee[1]);
; #pragma unroll
;                 for (int bj = 0; bj < 2; ++bj) { const u32x4 rw = rr[bj], ew = ee[bj];
;                     const float r[8] = {bflo(rw.x), bfhi(rw.x), bflo(rw.y), bfhi(rw.y), bflo(rw.z), bfhi(rw.z), bflo(rw.w), bfhi(rw.w)};
;                     const float e[8] = {bflo(ew.x), bfhi(ew.x), bflo(ew.y), bfhi(ew.y), bflo(ew.z), bfhi(ew.z), bflo(ew.w), bfhi(ew.w)};
;                     float o[8];
; #pragma unroll
;                     for (int j = 0; j < 8; ++j) { const float a = acc[ai][bj][m][j >> 2][j & 3]; const float gg = gv[bj][j >> 2][j & 3];
;                         o[j] = r[j] + e[j] * ri * gg * __builtin_amdgcn_rcpf(1.f + __builtin_amdgcn_exp2f(-a * LOG2E)); }
;                     if (OUT) { *(f32x4*)(OUT + off + 8 * bj) = (f32x4){o[0], o[1], o[2], o[3]}; *(f32x4*)(OUT + off + 8 * bj + 4) = (f32x4){o[4], o[5], o[6], o[7]}; }
;                     else { sq += (o[0] * o[0] + o[1] * o[1]) + (o[2] * o[2] + o[3] * o[3]) + (o[4] * o[4] + o[5] * o[5]) + (o[6] * o[6] + o[7] * o[7]);
;                         w[bj].x = cvt_pk_bf16(o[0], o[1]); w[bj].y = cvt_pk_bf16(o[2], o[3]); w[bj].z = cvt_pk_bf16(o[4], o[5]); w[bj].w = cvt_pk_bf16(o[6], o[7]); } }
.LBB0_895:
	s_or_b64 exec, exec, s[56:57]
	v_add_u32_e32 v36, 0xa0, v164
	v_sub_u32_e32 v38, v36, v172
	v_add_u32_e32 v38, v38, v174
	v_ashrrev_i32_e32 v39, 31, v38
	v_lshlrev_b64 v[38:39], 12, v[38:39]
	v_lshl_add_u64 v[44:45], s[16:17], 0, v[38:39]
	v_lshl_add_u64 v[44:45], v[44:45], 0, v[162:163]
	s_waitcnt vmcnt(2)
	s_nop 0
	v_mov_b64_e32 v[56:57], v[228:229]
	v_mov_b64_e32 v[58:59], v[230:231]
	v_lshl_add_u64 v[44:45], s[38:39], 0, v[38:39]
	v_lshl_add_u64 v[44:45], v[44:45], 0, v[162:163]
	s_waitcnt lgkmcnt(0)
	v_mov_b32_e32 v37, v226
	v_mov_b64_e32 v[60:61], v[232:233]
	v_mov_b64_e32 v[62:63], v[234:235]
	v_lshl_add_u64 v[44:45], v[38:39], 0, s[44:45]
	v_lshl_add_u64 v[46:47], s[16:17], 0, v[44:45]
	v_lshl_add_u64 v[46:47], v[46:47], 0, v[162:163]
	v_mov_b64_e32 v[64:65], v[236:237]
	v_mov_b64_e32 v[66:67], v[238:239]
	v_lshl_add_u64 v[46:47], s[38:39], 0, v[44:45]
	v_lshl_add_u64 v[46:47], v[46:47], 0, v[162:163]
	v_mov_b64_e32 v[68:69], v[240:241]
	v_mov_b64_e32 v[70:71], v[242:243]
	s_nop 1
	v_add_u32_e32 v216, 0xb0, v164
	v_sub_u32_e32 v218, v216, v172
	v_add_u32_e32 v218, v218, v174
	v_ashrrev_i32_e32 v219, 31, v218
	v_lshlrev_b64 v[218:219], 12, v[218:219]
	v_lshl_add_u64 v[220:221], s[16:17], 0, v[218:219]
	v_lshl_add_u64 v[220:221], v[220:221], 0, v[162:163]
	global_load_dwordx4 v[228:231], v[220:221], off
	v_lshl_add_u64 v[220:221], s[38:39], 0, v[218:219]
	v_lshl_add_u64 v[220:221], v[220:221], 0, v[162:163]
	global_load_dword v226, v[166:167], off offset:704
	global_load_dwordx4 v[232:235], v[220:221], off
	v_lshl_add_u64 v[220:221], v[218:219], 0, s[44:45]
	v_lshl_add_u64 v[222:223], s[16:17], 0, v[220:221]
	v_lshl_add_u64 v[222:223], v[222:223], 0, v[162:163]
	global_load_dwordx4 v[236:239], v[222:223], off
	v_lshl_add_u64 v[222:223], s[38:39], 0, v[220:221]
	v_lshl_add_u64 v[222:223], v[222:223], 0, v[162:163]
	global_load_dwordx4 v[240:243], v[222:223], off
	v_mul_f32_e32 v28, 0xbfb8aa3b, v28
	v_exp_f32_e32 v28, v28
	v_mul_f32_e32 v29, 0xbfb8aa3b, v29
	v_exp_f32_e32 v29, v29
	v_add_f32_e32 v28, 1.0, v28
	v_rcp_f32_e32 v28, v28
	v_add_f32_e32 v29, 1.0, v29
	v_rcp_f32_e32 v29, v29
	v_mul_f32_e32 v24, 0xbfb8aa3b, v24
	v_exp_f32_e32 v24, v24
	v_mul_f32_e32 v25, 0xbfb8aa3b, v25
	v_exp_f32_e32 v25, v25
	v_add_f32_e32 v24, 1.0, v24
	v_rcp_f32_e32 v24, v24
	v_add_f32_e32 v25, 1.0, v25
	v_rcp_f32_e32 v25, v25
	v_mul_f32_e32 v20, 0xbfb8aa3b, v20
	v_exp_f32_e32 v20, v20
	v_mul_f32_e32 v21, 0xbfb8aa3b, v21
	v_exp_f32_e32 v21, v21
	v_mul_f32_e32 v16, 0xbfb8aa3b, v16
	v_add_f32_e32 v20, 1.0, v20
	v_rcp_f32_e32 v20, v20
	v_add_f32_e32 v21, 1.0, v21
	v_rcp_f32_e32 v21, v21
	v_exp_f32_e32 v16, v16
	v_mul_f32_e32 v17, 0xbfb8aa3b, v17
	v_exp_f32_e32 v17, v17
	v_add_f32_e32 v16, 1.0, v16
	v_rcp_f32_e32 v16, v16
	v_add_f32_e32 v17, 1.0, v17
	v_rcp_f32_e32 v17, v17
	s_waitcnt vmcnt(47)
	v_mov_b32_dpp v46, v56 row_ror:8 row_mask:0xf bank_mask:0xf
	v_mov_b32_dpp v47, v57 row_ror:8 row_mask:0xf bank_mask:0xf
	v_mov_b32_dpp v72, v58 row_ror:8 row_mask:0xf bank_mask:0xf
	s_waitcnt vmcnt(47)
	v_fmamk_f32 v37, v37, 0x3a000000, v180
	v_rsq_f32_e32 v37, v37
	s_waitcnt vmcnt(47)
	v_mov_b32_dpp v78, v60 row_ror:8 row_mask:0xf bank_mask:0xf
	v_mov_b32_dpp v80, v62 row_ror:8 row_mask:0xf bank_mask:0xf
	v_mov_b32_dpp v79, v61 row_ror:8 row_mask:0xf bank_mask:0xf
	s_waitcnt vmcnt(47)
	v_mov_b32_dpp v74, v64 row_ror:8 row_mask:0xf bank_mask:0xf
	v_cndmask_b32_e64 v56, v74, v56, s[6:7]
	v_mov_b32_dpp v75, v65 row_ror:8 row_mask:0xf bank_mask:0xf
	s_waitcnt vmcnt(47)
	v_mov_b32_dpp v82, v68 row_ror:8 row_mask:0xf bank_mask:0xf
	v_cndmask_b32_e64 v60, v82, v60, s[6:7]
	v_lshlrev_b32_e32 v74, 16, v60
	v_mul_f32_e32 v74, v37, v74
	v_cndmask_b32_e64 v47, v65, v47, s[6:7]
	v_mov_b32_dpp v84, v70 row_ror:8 row_mask:0xf bank_mask:0xf
	v_cndmask_b32_e64 v65, v70, v80, s[6:7]
	v_lshlrev_b32_e32 v70, 16, v56
	v_and_b32_e32 v60, 0xffff0000, v60
	v_mul_f32_e32 v74, v52, v74
	v_fmac_f32_e32 v70, v28, v74
	v_mul_f32_e32 v28, v37, v60
	v_and_b32_e32 v56, 0xffff0000, v56
	v_mul_f32_e32 v28, v53, v28
	v_fmac_f32_e32 v56, v29, v28
	v_mul_f32_e32 v28, 0xbfb8aa3b, v30
	v_exp_f32_e32 v28, v28
	v_mul_f32_e32 v30, 0xbfb8aa3b, v31
	v_exp_f32_e32 v30, v30
	v_mov_b32_dpp v83, v69 row_ror:8 row_mask:0xf bank_mask:0xf
	v_add_f32_e32 v28, 1.0, v28
	v_cndmask_b32_e64 v61, v83, v61, s[6:7]
	v_rcp_f32_e32 v28, v28
	v_cndmask_b32_e64 v57, v75, v57, s[6:7]
	v_lshlrev_b32_e32 v75, 16, v61
	v_add_f32_e32 v30, 1.0, v30
	v_mov_b32_dpp v81, v63 row_ror:8 row_mask:0xf bank_mask:0xf
	v_mul_f32_e32 v29, v37, v75
	v_rcp_f32_e32 v30, v30
	v_cndmask_b32_e64 v46, v64, v46, s[6:7]
	v_mov_b32_dpp v85, v71 row_ror:8 row_mask:0xf bank_mask:0xf
	v_cndmask_b32_e64 v64, v71, v81, s[6:7]
	v_lshlrev_b32_e32 v71, 16, v57
	v_and_b32_e32 v61, 0xffff0000, v61
	v_mul_f32_e32 v29, v54, v29
	v_mov_b32_dpp v76, v66 row_ror:8 row_mask:0xf bank_mask:0xf
	v_cndmask_b32_e64 v62, v84, v62, s[6:7]
	v_fmac_f32_e32 v71, v28, v29
	v_mul_f32_e32 v28, v37, v61
	v_cndmask_b32_e64 v58, v76, v58, s[6:7]
	v_and_b32_e32 v57, 0xffff0000, v57
	v_lshlrev_b32_e32 v76, 16, v62
	v_mul_f32_e32 v28, v55, v28
	v_fmac_f32_e32 v57, v30, v28
	v_mul_f32_e32 v28, v37, v76
	v_cndmask_b32_e64 v66, v66, v72, s[6:7]
	v_lshlrev_b32_e32 v72, 16, v58
	v_and_b32_e32 v62, 0xffff0000, v62
	v_mul_f32_e32 v28, v48, v28
	v_fmac_f32_e32 v72, v24, v28
	v_mul_f32_e32 v24, v37, v62
	v_and_b32_e32 v58, 0xffff0000, v58
	v_mul_f32_e32 v24, v49, v24
	v_fmac_f32_e32 v58, v25, v24
	v_mul_f32_e32 v24, 0xbfb8aa3b, v26
	v_exp_f32_e32 v24, v24
	v_mul_f32_e32 v26, 0xbfb8aa3b, v27
	v_exp_f32_e32 v26, v26
	v_mov_b32_dpp v77, v67 row_ror:8 row_mask:0xf bank_mask:0xf
; __device__ __forceinline__ unsigned cvt_pk_bf16(float lo, float hi) { unsigned r; asm volatile("v_cvt_pk_bf16_f32 %0, %1, %2" : "=v"(r) : "v"(lo), "v"(hi)); return r; }
;     __device__ __forceinline__ void operator()(const f32x4 (&acc)[2][2][4][2], const Unit& u, int wr, int wc, int fr, int fq) const {
;     ...
;                     for (int j = 0; j < 8; ++j) { const float a = acc[ai][bj][m][j >> 2][j & 3]; const float gg = gv[bj][j >> 2][j & 3];
;                         o[j] = r[j] + e[j] * ri * gg * __builtin_amdgcn_rcpf(1.f + __builtin_amdgcn_exp2f(-a * LOG2E)); }
;                     if (OUT) { *(f32x4*)(OUT + off + 8 * bj) = (f32x4){o[0], o[1], o[2], o[3]}; *(f32x4*)(OUT + off + 8 * bj + 4) = (f32x4){o[4], o[5], o[6], o[7]}; }
;                     else { sq += (o[0] * o[0] + o[1] * o[1]) + (o[2] * o[2] + o[3] * o[3]) + (o[4] * o[4] + o[5] * o[5]) + (o[6] * o[6] + o[7] * o[7]);
;                         w[bj].x = cvt_pk_bf16(o[0], o[1]); w[bj].y = cvt_pk_bf16(o[2], o[3]); w[bj].z = cvt_pk_bf16(o[4], o[5]); w[bj].w = cvt_pk_bf16(o[6], o[7]); } }
;                 if (!OUT) { store_pair_lines(O, D, row, fr, col0, w[0], w[1]);
;                     sq += __shfl_xor(sq, 16); sq += __shfl_xor(sq, 32); if (fq == 0) unsafeAtomicAdd(ssout + row, sq); } }
	v_add_f32_e32 v24, 1.0, v24
	v_cndmask_b32_e64 v63, v85, v63, s[6:7]
	v_rcp_f32_e32 v24, v24
	v_mov_b32_dpp v73, v59 row_ror:8 row_mask:0xf bank_mask:0xf
	v_cndmask_b32_e64 v59, v77, v59, s[6:7]
	v_lshlrev_b32_e32 v77, 16, v63
	v_add_f32_e32 v26, 1.0, v26
	v_mul_f32_e32 v25, v37, v77
	v_rcp_f32_e32 v26, v26
	v_cndmask_b32_e64 v67, v67, v73, s[6:7]
	v_lshlrev_b32_e32 v73, 16, v59
	v_and_b32_e32 v63, 0xffff0000, v63
	v_mul_f32_e32 v25, v50, v25
	v_fmac_f32_e32 v73, v24, v25
	v_mul_f32_e32 v24, v37, v63
	v_and_b32_e32 v59, 0xffff0000, v59
	v_mul_f32_e32 v24, v51, v24
	v_fmac_f32_e32 v59, v26, v24
	v_mul_f32_e32 v24, v56, v56
	v_mul_f32_e32 v25, v57, v57
	v_fmac_f32_e32 v24, v70, v70
	v_fmac_f32_e32 v25, v71, v71
	v_add_f32_e32 v24, v24, v25
	v_mul_f32_e32 v25, v58, v58
	v_fmac_f32_e32 v25, v72, v72
	v_add_f32_e32 v24, v25, v24
	v_mul_f32_e32 v25, v59, v59
	v_cndmask_b32_e64 v68, v68, v78, s[6:7]
	v_fmac_f32_e32 v25, v73, v73
	v_add_f32_e32 v24, v25, v24
	v_cvt_pk_bf16_f32 v25, v70, v56
	v_cvt_pk_bf16_f32 v26, v71, v57
	v_cvt_pk_bf16_f32 v27, v72, v58
	v_cvt_pk_bf16_f32 v28, v73, v59
	v_lshlrev_b32_e32 v59, 16, v68
	v_mul_f32_e32 v59, v37, v59
	v_lshlrev_b32_e32 v29, 16, v46
	v_and_b32_e32 v60, 0xffff0000, v68
	v_mul_f32_e32 v59, v40, v59
	v_fmac_f32_e32 v29, v20, v59
	v_mul_f32_e32 v20, v37, v60
	v_and_b32_e32 v30, 0xffff0000, v46
	v_mul_f32_e32 v20, v41, v20
	v_fmac_f32_e32 v30, v21, v20
	v_mul_f32_e32 v20, 0xbfb8aa3b, v22
	v_exp_f32_e32 v20, v20
	v_mul_f32_e32 v22, 0xbfb8aa3b, v23
	v_exp_f32_e32 v22, v22
	v_cndmask_b32_e64 v69, v69, v79, s[6:7]
	v_add_f32_e32 v20, 1.0, v20
	v_rcp_f32_e32 v20, v20
	v_lshlrev_b32_e32 v61, 16, v69
	v_add_f32_e32 v22, 1.0, v22
	v_mul_f32_e32 v21, v37, v61
	v_rcp_f32_e32 v22, v22
	v_lshlrev_b32_e32 v31, 16, v47
	v_and_b32_e32 v62, 0xffff0000, v69
	v_mul_f32_e32 v21, v42, v21
	v_fmac_f32_e32 v31, v20, v21
	v_mul_f32_e32 v20, v37, v62
	v_and_b32_e32 v46, 0xffff0000, v47
	v_lshlrev_b32_e32 v63, 16, v65
	v_mul_f32_e32 v20, v43, v20
	v_fmac_f32_e32 v46, v22, v20
	v_mul_f32_e32 v20, v37, v63
	v_lshlrev_b32_e32 v47, 16, v66
	v_and_b32_e32 v65, 0xffff0000, v65
	v_mul_f32_e32 v20, v32, v20
	v_fmac_f32_e32 v47, v16, v20
	v_mul_f32_e32 v16, v37, v65
	v_and_b32_e32 v56, 0xffff0000, v66
	v_mul_f32_e32 v16, v33, v16
	v_fmac_f32_e32 v56, v17, v16
	v_mul_f32_e32 v16, 0xbfb8aa3b, v18
	v_exp_f32_e32 v16, v16
	v_mul_f32_e32 v18, 0xbfb8aa3b, v19
	v_exp_f32_e32 v18, v18
	v_lshlrev_b32_e32 v66, 16, v64
	v_add_f32_e32 v16, 1.0, v16
	v_rcp_f32_e32 v16, v16
	v_add_f32_e32 v18, 1.0, v18
	v_mul_f32_e32 v17, v37, v66
	v_rcp_f32_e32 v18, v18
	v_lshlrev_b32_e32 v57, 16, v67
	v_and_b32_e32 v64, 0xffff0000, v64
	v_mul_f32_e32 v17, v34, v17
	v_fmac_f32_e32 v57, v16, v17
	v_mul_f32_e32 v16, v37, v64
	v_and_b32_e32 v58, 0xffff0000, v67
	v_mul_f32_e32 v16, v35, v16
	v_fmac_f32_e32 v58, v18, v16
	v_mul_f32_e32 v16, v30, v30
	v_mul_f32_e32 v17, v46, v46
	v_fmac_f32_e32 v16, v29, v29
	v_fmac_f32_e32 v17, v31, v31
	v_add_f32_e32 v16, v16, v17
	v_mul_f32_e32 v17, v56, v56
	v_fmac_f32_e32 v17, v47, v47
	v_add_f32_e32 v16, v17, v16
	v_mul_f32_e32 v17, v58, v58
	v_fmac_f32_e32 v17, v57, v57
	v_add_f32_e32 v16, v17, v16
	v_add_f32_e32 v37, v16, v24
	v_cvt_pk_bf16_f32 v16, v29, v30
	v_cvt_pk_bf16_f32 v17, v31, v46
	v_cvt_pk_bf16_f32 v24, v47, v56
	v_cvt_pk_bf16_f32 v29, v57, v58
	v_mov_b32_e32 v31, 0
	v_mov_b32_e32 v22, 0
	v_mov_b32_dpp v21, v29 row_ror:8 row_mask:0xf bank_mask:0xf
	v_mov_b32_dpp v31, v28 row_ror:8 row_mask:0xf bank_mask:0xf
	v_cndmask_b32_e64 v21, v21, v28, s[6:7]
	v_mov_b32_e32 v28, v37
	s_nop 1
	v_permlane16_swap_b32_e32 v28, v37
	v_mov_b32_dpp v22, v25 row_ror:8 row_mask:0xf bank_mask:0xf
	v_mov_b32_dpp v23, v26 row_ror:8 row_mask:0xf bank_mask:0xf
	v_mov_b32_dpp v18, v16 row_ror:8 row_mask:0xf bank_mask:0xf
	v_mov_b32_dpp v19, v17 row_ror:8 row_mask:0xf bank_mask:0xf
	v_mov_b32_dpp v20, v24 row_ror:8 row_mask:0xf bank_mask:0xf
	v_cndmask_b32_e64 v22, v16, v22, s[6:7]
	v_cndmask_b32_e64 v23, v17, v23, s[6:7]
	v_lshl_add_u64 v[16:17], s[36:37], 0, v[38:39]
	v_mov_b32_dpp v30, v27 row_ror:8 row_mask:0xf bank_mask:0xf
	v_cndmask_b32_e64 v19, v19, v26, s[6:7]
	v_cndmask_b32_e64 v20, v20, v27, s[6:7]
	v_lshl_add_u64 v[26:27], v[16:17], 0, v[162:163]
	s_waitcnt lgkmcnt(0)
	v_add_f32_e32 v16, v37, v28
	v_mov_b32_e32 v17, v16
	s_nop 1
	v_permlane32_swap_b32_e32 v17, v16
	v_cndmask_b32_e64 v18, v18, v25, s[6:7]
	global_store_dwordx4 v[26:27], v[18:21], off
	v_cndmask_b32_e64 v24, v24, v30, s[6:7]
	v_cndmask_b32_e64 v25, v29, v31, s[6:7]
	v_lshl_add_u64 v[18:19], s[36:37], 0, v[44:45]
	v_lshl_add_u64 v[18:19], v[18:19], 0, v[162:163]
	global_store_dwordx4 v[18:19], v[22:25], off
	s_and_saveexec_b64 s[56:57], s[8:9]
	s_cbranch_execz .LBB0_897
	v_ashrrev_i32_e32 v37, 31, v36
	v_lshl_add_u64 v[18:19], v[36:37], 2, s[18:19]
	s_waitcnt lgkmcnt(0)
	v_add_f32_e32 v16, v16, v17
	global_atomic_add_f32 v[18:19], v16, off
; __device__ __forceinline__ unsigned cvt_pk_bf16(float lo, float hi) { unsigned r; asm volatile("v_cvt_pk_bf16_f32 %0, %1, %2" : "=v"(r) : "v"(lo), "v"(hi)); return r; }
; __device__ __forceinline__ float bflo(unsigned w) { return __uint_as_float(w << 16); }
; __device__ __forceinline__ float bfhi(unsigned w) { return __uint_as_float(w & 0xffff0000u); }
;     __device__ __forceinline__ void operator()(const f32x4 (&acc)[2][2][4][2], const Unit& u, int wr, int wc, int fr, int fq) const {
;     ...
;             for (int m = 0; m < 4; ++m) { const int row = row0 + ai * HALF + m * 16; const size_t off = (size_t)row * D + col0; const float ri = __builtin_amdgcn_rsqf(sse[row] * (1.f / D) + EPS); float sq = 0.f; u32x4 w[2];
;                 u32x4 rr[2], ee[2]; load_pair_lines(R, D, row, fr, col0, rr[0], rr[1]); load_pair_lines(E, D, row, fr, col0, ee[0], ee[1]);
; #pragma unroll
;                 for (int bj = 0; bj < 2; ++bj) { const u32x4 rw = rr[bj], ew = ee[bj];
;                     const float r[8] = {bflo(rw.x), bfhi(rw.x), bflo(rw.y), bfhi(rw.y), bflo(rw.z), bfhi(rw.z), bflo(rw.w), bfhi(rw.w)};
;                     const float e[8] = {bflo(ew.x), bfhi(ew.x), bflo(ew.y), bfhi(ew.y), bflo(ew.z), bfhi(ew.z), bflo(ew.w), bfhi(ew.w)};
;                     float o[8];
; #pragma unroll
;                     for (int j = 0; j < 8; ++j) { const float a = acc[ai][bj][m][j >> 2][j & 3]; const float gg = gv[bj][j >> 2][j & 3];
;                         o[j] = r[j] + e[j] * ri * gg * __builtin_amdgcn_rcpf(1.f + __builtin_amdgcn_exp2f(-a * LOG2E)); }
;                     if (OUT) { *(f32x4*)(OUT + off + 8 * bj) = (f32x4){o[0], o[1], o[2], o[3]}; *(f32x4*)(OUT + off + 8 * bj + 4) = (f32x4){o[4], o[5], o[6], o[7]}; }
;                     else { sq += (o[0] * o[0] + o[1] * o[1]) + (o[2] * o[2] + o[3] * o[3]) + (o[4] * o[4] + o[5] * o[5]) + (o[6] * o[6] + o[7] * o[7]);
;                         w[bj].x = cvt_pk_bf16(o[0], o[1]); w[bj].y = cvt_pk_bf16(o[2], o[3]); w[bj].z = cvt_pk_bf16(o[4], o[5]); w[bj].w = cvt_pk_bf16(o[6], o[7]); } }
.LBB0_897:
	s_or_b64 exec, exec, s[56:57]
	v_add_u32_e32 v16, 0xb0, v164
	v_sub_u32_e32 v18, v16, v172
	v_add_u32_e32 v18, v18, v174
	v_ashrrev_i32_e32 v19, 31, v18
	v_lshlrev_b64 v[18:19], 12, v[18:19]
	v_lshl_add_u64 v[20:21], s[16:17], 0, v[18:19]
	v_lshl_add_u64 v[20:21], v[20:21], 0, v[162:163]
	s_waitcnt vmcnt(2)
	s_nop 0
	v_mov_b64_e32 v[22:23], v[228:229]
	v_mov_b64_e32 v[24:25], v[230:231]
	v_lshl_add_u64 v[20:21], s[38:39], 0, v[18:19]
	v_lshl_add_u64 v[20:21], v[20:21], 0, v[162:163]
	s_waitcnt lgkmcnt(0)
	v_mov_b32_e32 v17, v226
	v_mov_b64_e32 v[26:27], v[232:233]
	v_mov_b64_e32 v[28:29], v[234:235]
	v_lshl_add_u64 v[20:21], v[18:19], 0, s[44:45]
	v_lshl_add_u64 v[30:31], s[16:17], 0, v[20:21]
	v_lshl_add_u64 v[30:31], v[30:31], 0, v[162:163]
	v_mov_b64_e32 v[36:37], v[236:237]
	v_mov_b64_e32 v[38:39], v[238:239]
	v_lshl_add_u64 v[30:31], s[38:39], 0, v[20:21]
	v_lshl_add_u64 v[30:31], v[30:31], 0, v[162:163]
	v_mov_b64_e32 v[44:45], v[240:241]
	v_mov_b64_e32 v[46:47], v[242:243]
	s_nop 1
	v_mul_f32_e32 v12, 0xbfb8aa3b, v12
	v_exp_f32_e32 v12, v12
	v_mul_f32_e32 v13, 0xbfb8aa3b, v13
	v_exp_f32_e32 v13, v13
	v_add_f32_e32 v12, 1.0, v12
	v_rcp_f32_e32 v12, v12
	v_add_f32_e32 v13, 1.0, v13
	v_rcp_f32_e32 v13, v13
	v_mul_f32_e32 v8, 0xbfb8aa3b, v8
	v_exp_f32_e32 v8, v8
	v_mul_f32_e32 v9, 0xbfb8aa3b, v9
	v_exp_f32_e32 v9, v9
	v_add_f32_e32 v8, 1.0, v8
	v_rcp_f32_e32 v8, v8
	v_add_f32_e32 v9, 1.0, v9
	v_mul_f32_e32 v4, 0xbfb8aa3b, v4
	v_rcp_f32_e32 v9, v9
	v_exp_f32_e32 v4, v4
	v_mul_f32_e32 v5, 0xbfb8aa3b, v5
	v_exp_f32_e32 v5, v5
	v_add_f32_e32 v4, 1.0, v4
	v_rcp_f32_e32 v4, v4
	v_add_f32_e32 v5, 1.0, v5
	v_rcp_f32_e32 v5, v5
	v_mul_f32_e32 v0, 0xbfb8aa3b, v0
	v_exp_f32_e32 v0, v0
	v_mul_f32_e32 v1, 0xbfb8aa3b, v1
	v_exp_f32_e32 v1, v1
	v_add_f32_e32 v0, 1.0, v0
	v_rcp_f32_e32 v0, v0
	v_add_f32_e32 v1, 1.0, v1
	v_rcp_f32_e32 v1, v1
	s_waitcnt vmcnt(49)
	v_mov_b32_dpp v30, v22 row_ror:8 row_mask:0xf bank_mask:0xf
	v_mov_b32_dpp v31, v23 row_ror:8 row_mask:0xf bank_mask:0xf
	v_mov_b32_dpp v56, v24 row_ror:8 row_mask:0xf bank_mask:0xf
	s_waitcnt vmcnt(49)
	v_fmamk_f32 v17, v17, 0x3a000000, v180
	v_rsq_f32_e32 v17, v17
	s_waitcnt vmcnt(49)
	v_mov_b32_dpp v62, v26 row_ror:8 row_mask:0xf bank_mask:0xf
	v_mov_b32_dpp v64, v28 row_ror:8 row_mask:0xf bank_mask:0xf
	v_mov_b32_dpp v63, v27 row_ror:8 row_mask:0xf bank_mask:0xf
	s_waitcnt vmcnt(49)
	v_mov_b32_dpp v58, v36 row_ror:8 row_mask:0xf bank_mask:0xf
	v_cndmask_b32_e64 v22, v58, v22, s[6:7]
	v_mov_b32_dpp v59, v37 row_ror:8 row_mask:0xf bank_mask:0xf
	s_waitcnt vmcnt(49)
; __device__ __forceinline__ void store_pair_lines(bf16_t* O, int ldc, int row, int fr, int col0, u32x4 wA, u32x4 wB) {
;     const u32x4 sA = {dpp_ror8(wA.x), dpp_ror8(wA.y), dpp_ror8(wA.z), dpp_ror8(wA.w)}, sB = {dpp_ror8(wB.x), dpp_ror8(wB.y), dpp_ror8(wB.z), dpp_ror8(wB.w)};
;     const bool lo = fr < 8;
;     const u32x4 o1 = lo ? wA : sB, o2 = lo ? sA : wB;
;     const int r1 = row - fr + (fr & 7), cb = col0 + (lo ? 0 : 8);
;     *(u32x4*)(O + (size_t)r1 * ldc + cb) = o1;
;     __device__ __forceinline__ void operator()(const f32x4 (&acc)[2][2][4][2], const Unit& u, int wr, int wc, int fr, int fq) const {
;     ...
;             for (int m = 0; m < 4; ++m) { const int row = row0 + ai * HALF + m * 16; const size_t off = (size_t)row * D + col0; const float ri = __builtin_amdgcn_rsqf(sse[row] * (1.f / D) + EPS); float sq = 0.f; u32x4 w[2];
;                 u32x4 rr[2], ee[2]; load_pair_lines(R, D, row, fr, col0, rr[0], rr[1]); load_pair_lines(E, D, row, fr, col0, ee[0], ee[1]);
; #pragma unroll
;                 for (int bj = 0; bj < 2; ++bj) { const u32x4 rw = rr[bj], ew = ee[bj];
;                     const float r[8] = {bflo(rw.x), bfhi(rw.x), bflo(rw.y), bfhi(rw.y), bflo(rw.z), bfhi(rw.z), bflo(rw.w), bfhi(rw.w)};
;                     const float e[8] = {bflo(ew.x), bfhi(ew.x), bflo(ew.y), bfhi(ew.y), bflo(ew.z), bfhi(ew.z), bflo(ew.w), bfhi(ew.w)};
;                     float o[8];
; #pragma unroll
;                     for (int j = 0; j < 8; ++j) { const float a = acc[ai][bj][m][j >> 2][j & 3]; const float gg = gv[bj][j >> 2][j & 3];
;                         o[j] = r[j] + e[j] * ri * gg * __builtin_amdgcn_rcpf(1.f + __builtin_amdgcn_exp2f(-a * LOG2E)); }
;                     if (OUT) { *(f32x4*)(OUT + off + 8 * bj) = (f32x4){o[0], o[1], o[2], o[3]}; *(f32x4*)(OUT + off + 8 * bj + 4) = (f32x4){o[4], o[5], o[6], o[7]}; }
;                     else { sq += (o[0] * o[0] + o[1] * o[1]) + (o[2] * o[2] + o[3] * o[3]) + (o[4] * o[4] + o[5] * o[5]) + (o[6] * o[6] + o[7] * o[7]);
;                         w[bj].x = cvt_pk_bf16(o[0], o[1]); w[bj].y = cvt_pk_bf16(o[2], o[3]); w[bj].z = cvt_pk_bf16(o[4], o[5]); w[bj].w = cvt_pk_bf16(o[6], o[7]); } }
;                 if (!OUT) { store_pair_lines(O, D, row, fr, col0, w[0], w[1]);
;                     sq += __shfl_xor(sq, 16); sq += __shfl_xor(sq, 32); if (fq == 0) unsafeAtomicAdd(ssout + row, sq); } }
	v_mov_b32_dpp v66, v44 row_ror:8 row_mask:0xf bank_mask:0xf
	v_cndmask_b32_e64 v26, v66, v26, s[6:7]
	v_lshlrev_b32_e32 v58, 16, v26
	v_mul_f32_e32 v58, v17, v58
	v_cndmask_b32_e64 v31, v37, v31, s[6:7]
	v_mov_b32_dpp v68, v46 row_ror:8 row_mask:0xf bank_mask:0xf
	v_cndmask_b32_e64 v37, v46, v64, s[6:7]
	v_lshlrev_b32_e32 v46, 16, v22
	v_and_b32_e32 v26, 0xffff0000, v26
	v_mul_f32_e32 v52, v52, v58
	v_fmac_f32_e32 v46, v12, v52
	v_mul_f32_e32 v12, v17, v26
	v_and_b32_e32 v22, 0xffff0000, v22
	v_mul_f32_e32 v12, v53, v12
	v_fmac_f32_e32 v22, v13, v12
	v_mul_f32_e32 v12, 0xbfb8aa3b, v14
	v_exp_f32_e32 v12, v12
	v_mul_f32_e32 v14, 0xbfb8aa3b, v15
	v_exp_f32_e32 v14, v14
	v_mov_b32_dpp v67, v45 row_ror:8 row_mask:0xf bank_mask:0xf
	v_add_f32_e32 v12, 1.0, v12
	v_cndmask_b32_e64 v27, v67, v27, s[6:7]
	v_rcp_f32_e32 v12, v12
	v_cndmask_b32_e64 v23, v59, v23, s[6:7]
	v_lshlrev_b32_e32 v59, 16, v27
	v_add_f32_e32 v14, 1.0, v14
	v_mov_b32_dpp v65, v29 row_ror:8 row_mask:0xf bank_mask:0xf
	v_mul_f32_e32 v13, v17, v59
	v_rcp_f32_e32 v14, v14
	v_cndmask_b32_e64 v30, v36, v30, s[6:7]
	v_mov_b32_dpp v69, v47 row_ror:8 row_mask:0xf bank_mask:0xf
	v_cndmask_b32_e64 v36, v47, v65, s[6:7]
	v_lshlrev_b32_e32 v47, 16, v23
	v_and_b32_e32 v27, 0xffff0000, v27
	v_mul_f32_e32 v13, v54, v13
	v_mov_b32_dpp v60, v38 row_ror:8 row_mask:0xf bank_mask:0xf
	v_cndmask_b32_e64 v28, v68, v28, s[6:7]
	v_fmac_f32_e32 v47, v12, v13
	v_mul_f32_e32 v12, v17, v27
	v_cndmask_b32_e64 v24, v60, v24, s[6:7]
	v_and_b32_e32 v23, 0xffff0000, v23
	v_lshlrev_b32_e32 v60, 16, v28
	v_mul_f32_e32 v12, v55, v12
	v_fmac_f32_e32 v23, v14, v12
	v_mul_f32_e32 v12, v17, v60
	v_cndmask_b32_e64 v38, v38, v56, s[6:7]
	v_lshlrev_b32_e32 v56, 16, v24
	v_and_b32_e32 v28, 0xffff0000, v28
	v_mul_f32_e32 v12, v48, v12
	v_fmac_f32_e32 v56, v8, v12
	v_mul_f32_e32 v8, v17, v28
	v_and_b32_e32 v24, 0xffff0000, v24
	v_mul_f32_e32 v8, v49, v8
	v_fmac_f32_e32 v24, v9, v8
	v_mul_f32_e32 v8, 0xbfb8aa3b, v10
	v_cndmask_b32_e64 v44, v44, v62, s[6:7]
	v_exp_f32_e32 v8, v8
	v_mul_f32_e32 v10, 0xbfb8aa3b, v11
	v_lshlrev_b32_e32 v27, 16, v44
	v_exp_f32_e32 v10, v10
	v_mul_f32_e32 v27, v17, v27
	v_lshlrev_b32_e32 v13, 16, v30
	v_and_b32_e32 v28, 0xffff0000, v44
	v_mul_f32_e32 v27, v40, v27
	v_add_f32_e32 v8, 1.0, v8
	v_fmac_f32_e32 v13, v4, v27
	v_mul_f32_e32 v4, v17, v28
	v_mov_b32_dpp v61, v39 row_ror:8 row_mask:0xf bank_mask:0xf
	v_cndmask_b32_e64 v29, v69, v29, s[6:7]
	v_rcp_f32_e32 v8, v8
	v_and_b32_e32 v14, 0xffff0000, v30
	v_mul_f32_e32 v4, v41, v4
	v_mov_b32_dpp v57, v25 row_ror:8 row_mask:0xf bank_mask:0xf
	v_cndmask_b32_e64 v25, v61, v25, s[6:7]
	v_lshlrev_b32_e32 v61, 16, v29
	v_add_f32_e32 v10, 1.0, v10
	v_fmac_f32_e32 v14, v5, v4
	v_mul_f32_e32 v4, 0xbfb8aa3b, v6
	v_mul_f32_e32 v9, v17, v61
	v_rcp_f32_e32 v10, v10
	v_exp_f32_e32 v4, v4
	v_cndmask_b32_e64 v39, v39, v57, s[6:7]
	v_lshlrev_b32_e32 v57, 16, v25
	v_and_b32_e32 v29, 0xffff0000, v29
	v_mul_f32_e32 v9, v50, v9
	v_mul_f32_e32 v6, 0xbfb8aa3b, v7
	v_fmac_f32_e32 v57, v8, v9
	v_mul_f32_e32 v8, v17, v29
	v_exp_f32_e32 v6, v6
	v_and_b32_e32 v25, 0xffff0000, v25
	v_mul_f32_e32 v8, v51, v8
	v_fmac_f32_e32 v25, v10, v8
	v_mul_f32_e32 v8, v22, v22
	v_mul_f32_e32 v9, v23, v23
	v_add_f32_e32 v4, 1.0, v4
	v_cndmask_b32_e64 v45, v45, v63, s[6:7]
	v_fmac_f32_e32 v8, v46, v46
	v_fmac_f32_e32 v9, v47, v47
	v_rcp_f32_e32 v4, v4
	v_add_f32_e32 v8, v8, v9
	v_mul_f32_e32 v9, v24, v24
	v_lshlrev_b32_e32 v29, 16, v45
	v_add_f32_e32 v6, 1.0, v6
	v_fmac_f32_e32 v9, v56, v56
	v_mul_f32_e32 v5, v17, v29
	v_rcp_f32_e32 v6, v6
	v_add_f32_e32 v8, v9, v8
	v_mul_f32_e32 v9, v25, v25
	v_lshlrev_b32_e32 v15, 16, v31
	v_and_b32_e32 v30, 0xffff0000, v45
	v_mul_f32_e32 v5, v42, v5
	v_fmac_f32_e32 v9, v57, v57
	v_fmac_f32_e32 v15, v4, v5
	v_mul_f32_e32 v4, v17, v30
	v_add_f32_e32 v8, v9, v8
	v_cvt_pk_bf16_f32 v9, v46, v22
	v_and_b32_e32 v22, 0xffff0000, v31
	v_lshlrev_b32_e32 v31, 16, v37
	v_mul_f32_e32 v4, v43, v4
	v_fmac_f32_e32 v22, v6, v4
	v_mul_f32_e32 v4, v17, v31
	v_cvt_pk_bf16_f32 v10, v47, v23
	v_lshlrev_b32_e32 v23, 16, v38
	v_and_b32_e32 v37, 0xffff0000, v37
	v_mul_f32_e32 v4, v32, v4
	v_fmac_f32_e32 v23, v0, v4
	v_mul_f32_e32 v0, v17, v37
	v_cvt_pk_bf16_f32 v11, v56, v24
	v_and_b32_e32 v24, 0xffff0000, v38
	v_mul_f32_e32 v0, v33, v0
	v_fmac_f32_e32 v24, v1, v0
	v_mul_f32_e32 v0, 0xbfb8aa3b, v2
	v_exp_f32_e32 v0, v0
	v_mul_f32_e32 v2, 0xbfb8aa3b, v3
	v_exp_f32_e32 v2, v2
	v_lshlrev_b32_e32 v38, 16, v36
	v_add_f32_e32 v0, 1.0, v0
	v_rcp_f32_e32 v0, v0
	v_add_f32_e32 v2, 1.0, v2
	v_mul_f32_e32 v1, v17, v38
	v_rcp_f32_e32 v2, v2
	v_cvt_pk_bf16_f32 v12, v57, v25
	v_lshlrev_b32_e32 v25, 16, v39
	v_and_b32_e32 v36, 0xffff0000, v36
	v_mul_f32_e32 v1, v34, v1
	v_fmac_f32_e32 v25, v0, v1
	v_mul_f32_e32 v0, v17, v36
	v_and_b32_e32 v26, 0xffff0000, v39
	v_mul_f32_e32 v0, v35, v0
	v_fmac_f32_e32 v26, v2, v0
	v_mul_f32_e32 v0, v14, v14
	v_mul_f32_e32 v1, v22, v22
	v_fmac_f32_e32 v0, v13, v13
	v_fmac_f32_e32 v1, v15, v15
	v_add_f32_e32 v0, v0, v1
	v_mul_f32_e32 v1, v24, v24
	v_fmac_f32_e32 v1, v23, v23
	v_add_f32_e32 v0, v1, v0
	v_mul_f32_e32 v1, v26, v26
	v_fmac_f32_e32 v1, v25, v25
	v_add_f32_e32 v0, v1, v0
	v_add_f32_e32 v17, v0, v8
	v_cvt_pk_bf16_f32 v0, v13, v14
	v_cvt_pk_bf16_f32 v1, v15, v22
	v_cvt_pk_bf16_f32 v8, v23, v24
	v_cvt_pk_bf16_f32 v13, v25, v26
	v_mov_b32_e32 v15, 0
	v_mov_b32_e32 v6, 0
	v_mov_b32_dpp v5, v13 row_ror:8 row_mask:0xf bank_mask:0xf
	v_mov_b32_dpp v15, v12 row_ror:8 row_mask:0xf bank_mask:0xf
	v_cndmask_b32_e64 v5, v5, v12, s[6:7]
	v_mov_b32_e32 v12, v17
	s_nop 1
	v_permlane16_swap_b32_e32 v12, v17
	v_mov_b32_dpp v6, v9 row_ror:8 row_mask:0xf bank_mask:0xf
	v_mov_b32_dpp v7, v10 row_ror:8 row_mask:0xf bank_mask:0xf
	v_mov_b32_dpp v2, v0 row_ror:8 row_mask:0xf bank_mask:0xf
	v_mov_b32_dpp v3, v1 row_ror:8 row_mask:0xf bank_mask:0xf
	v_mov_b32_dpp v4, v8 row_ror:8 row_mask:0xf bank_mask:0xf
	v_cndmask_b32_e64 v6, v0, v6, s[6:7]
	v_cndmask_b32_e64 v7, v1, v7, s[6:7]
	v_lshl_add_u64 v[0:1], s[36:37], 0, v[18:19]
	v_mov_b32_dpp v14, v11 row_ror:8 row_mask:0xf bank_mask:0xf
	v_cndmask_b32_e64 v3, v3, v10, s[6:7]
	v_cndmask_b32_e64 v4, v4, v11, s[6:7]
	v_lshl_add_u64 v[10:11], v[0:1], 0, v[162:163]
	s_waitcnt lgkmcnt(0)
	v_add_f32_e32 v0, v17, v12
	v_mov_b32_e32 v1, v0
	s_nop 1
	v_permlane32_swap_b32_e32 v1, v0
	v_cndmask_b32_e64 v2, v2, v9, s[6:7]
	global_store_dwordx4 v[10:11], v[2:5], off
	v_cndmask_b32_e64 v8, v8, v14, s[6:7]
	v_cndmask_b32_e64 v9, v13, v15, s[6:7]
	v_lshl_add_u64 v[2:3], s[36:37], 0, v[20:21]
	v_lshl_add_u64 v[2:3], v[2:3], 0, v[162:163]
	global_store_dwordx4 v[2:3], v[6:9], off
	s_and_saveexec_b64 s[56:57], s[8:9]
	s_cbranch_execz .LBB0_873
	v_ashrrev_i32_e32 v17, 31, v16
	v_lshl_add_u64 v[2:3], v[16:17], 2, s[18:19]
	s_waitcnt lgkmcnt(0)
	v_add_f32_e32 v0, v0, v1
	global_atomic_add_f32 v[2:3], v0, off
	s_branch .LBB0_873

; #define PG8_STAGE(bufoff, gbase, voff) do { _Pragma("unroll") for (int _i = 0; _i < 2; ++_i) \
;         __builtin_amdgcn_global_load_lds((const unsigned*)((const char*)(gbase) + (voff)[_i]), (LAS unsigned*)(lds + (bufoff) + ldsw + _i * 8192), 16, 0, 0); } while (0)
; #define PG8_LDA(dst, b, h) do { _Pragma("unroll") for (int m = 0; m < 4; ++m) _Pragma("unroll") for (int k = 0; k < 2; ++k) dst[m][k] = *(const LAS bf16x8*)(lds + PG8_SA(b, h) + aoff + m * 2048 + k * 1024); } while (0)
; #define PG8_LDB(dst, b, h) do { _Pragma("unroll") for (int n = 0; n < 2; ++n) _Pragma("unroll") for (int k = 0; k < 2; ++k) dst[n][k] = *(const LAS bf16x8*)(lds + PG8_SB(b, h) + boff + n * 2048 + k * 1024); } while (0)
; #define PG8_MMA(ai, bj, At, Bt) do { __builtin_amdgcn_s_setprio(1); _Pragma("unroll") for (int m = 0; m < 4; ++m) _Pragma("unroll") for (int n = 0; n < 2; ++n) _Pragma("unroll") for (int k = 0; k < 2; ++k) \
;         acc[ai][bj][m][n] = __builtin_amdgcn_mfma_f32_16x16x32_bf16(Bt[n][k], At[m][k], acc[ai][bj][m][n], 0, 0, 0); __builtin_amdgcn_s_setprio(0); } while (0)
; template <class Epi>
; __device__ __forceinline__ void gemm_phase(LAS unsigned char* lds, const Gemm g, const StaticOrder& S, const Epi& E) {
;     ...
;     for (;;) {
;         const bool has_next = S.next(ui + 1, nxt);
;         const char* nA = has_next ? (const char*)g.A + (size_t)nxt.pm * tstep : cA; const char* nB = has_next ? (const char*)g.Bt + (size_t)nxt.pn * tstep : cB;
;         for (int t = 0; t < nt; t += 2) {
;             const bool last = (t == nt - 2);
;             const char* a1 = cA + (size_t)(t + 1) * kstep;
;             const char* a2 = last ? nA : cA + (size_t)(t + 2) * kstep; const char* b2 = last ? nB : cB + (size_t)(t + 2) * kstep;
;             const char* a3 = a2 + kstep; const char* b3 = b2 + kstep;
;             PG8_LDB(B0, 0, 0); PG8_SCHED; PG8_LDA(At, 0, 0); PG8_STAGE(PG8_SA(1, 1), a1 + hstep, voffA);
;             PG8_WAIT_L(8); PG8_BAR; PG8_WAIT_L(0); PG8_MMA(0, 0, At, B0); PG8_BAR; PG8_SCHED;
;     ...
; #pragma unroll
;         for (int a = 0; a < 2; ++a)
; #pragma unroll
;             for (int b = 0; b < 2; ++b)
; #pragma unroll
;                 for (int m = 0; m < 4; ++m)
; #pragma unroll
;                     for (int n = 0; n < 2; ++n) acc[a][b][m][n] = (f32x4){0.f, 0.f, 0.f, 0.f};
;         cur = nxt; cA = nA; cB = nB; ++ui;
.LBB0_961:
	s_ashr_i32 s37, s36, 31
	s_xor_b64 s[40:41], s[50:51], -1
	s_lshl_b64 s[38:39], s[36:37], 20
	s_add_u32 s38, s53, s38
	s_addc_u32 s39, s54, s39
	s_and_b64 s[42:43], s[50:51], exec
	s_cselect_b32 s37, s39, s47
	s_cselect_b32 s72, s38, s46
	s_ashr_i32 s19, s18, 31
	s_lshl_b64 s[42:43], s[18:19], 20
	s_add_u32 s42, s55, s42
	s_addc_u32 s43, s56, s43
	s_and_b64 s[50:51], s[50:51], exec
	s_cselect_b32 s19, s43, s49
	s_cselect_b32 s73, s42, s48
	s_add_u32 s46, s46, 0x80080
	s_addc_u32 s47, s47, 0
	s_add_u32 s74, s48, 0x100
	v_mov_b32_e32 v0, 0
	s_addc_u32 s75, s49, 0
	s_mov_b32 s77, -2
	v_mov_b32_e32 v1, v0
	v_mov_b32_e32 v2, v0
	v_mov_b32_e32 v3, v0
	v_mov_b32_e32 v4, v0
	v_mov_b32_e32 v5, v0
	v_mov_b32_e32 v6, v0
	v_mov_b32_e32 v7, v0
	v_mov_b32_e32 v16, v0
	v_mov_b32_e32 v17, v0
	v_mov_b32_e32 v18, v0
	v_mov_b32_e32 v19, v0
	v_mov_b32_e32 v20, v0
	v_mov_b32_e32 v21, v0
	v_mov_b32_e32 v22, v0
	v_mov_b32_e32 v23, v0
	v_mov_b32_e32 v32, v0
	v_mov_b32_e32 v33, v0
	v_mov_b32_e32 v34, v0
	v_mov_b32_e32 v35, v0
	v_mov_b32_e32 v36, v0
	v_mov_b32_e32 v37, v0
	v_mov_b32_e32 v38, v0
	v_mov_b32_e32 v39, v0
	v_mov_b32_e32 v48, v0
	v_mov_b32_e32 v49, v0
	v_mov_b32_e32 v50, v0
	v_mov_b32_e32 v51, v0
	v_mov_b32_e32 v52, v0
	v_mov_b32_e32 v53, v0
	v_mov_b32_e32 v54, v0
	v_mov_b32_e32 v55, v0
	v_mov_b32_e32 v8, v0
	v_mov_b32_e32 v9, v0
	v_mov_b32_e32 v10, v0
	v_mov_b32_e32 v11, v0
	v_mov_b32_e32 v12, v0
	v_mov_b32_e32 v13, v0
	v_mov_b32_e32 v14, v0
	v_mov_b32_e32 v15, v0
	v_mov_b32_e32 v24, v0
	v_mov_b32_e32 v25, v0
	v_mov_b32_e32 v26, v0
	v_mov_b32_e32 v27, v0
	v_mov_b32_e32 v28, v0
	v_mov_b32_e32 v29, v0
	v_mov_b32_e32 v30, v0
	v_mov_b32_e32 v31, v0
	v_mov_b32_e32 v40, v0
	v_mov_b32_e32 v41, v0
	v_mov_b32_e32 v42, v0
	v_mov_b32_e32 v43, v0
	v_mov_b32_e32 v44, v0
	v_mov_b32_e32 v45, v0
	v_mov_b32_e32 v46, v0
	v_mov_b32_e32 v47, v0
	v_mov_b32_e32 v56, v0
	v_mov_b32_e32 v57, v0
	v_mov_b32_e32 v58, v0
	v_mov_b32_e32 v59, v0
	v_mov_b32_e32 v60, v0
	v_mov_b32_e32 v61, v0
	v_mov_b32_e32 v62, v0
	v_mov_b32_e32 v63, v0
	v_mov_b32_e32 v64, v0
	v_mov_b32_e32 v65, v0
	v_mov_b32_e32 v66, v0
	v_mov_b32_e32 v67, v0
	v_mov_b32_e32 v68, v0
	v_mov_b32_e32 v69, v0
	v_mov_b32_e32 v70, v0
	v_mov_b32_e32 v71, v0
	v_mov_b32_e32 v80, v0
	v_mov_b32_e32 v81, v0
	v_mov_b32_e32 v82, v0
	v_mov_b32_e32 v83, v0
	v_mov_b32_e32 v84, v0
	v_mov_b32_e32 v85, v0
	v_mov_b32_e32 v86, v0
	v_mov_b32_e32 v87, v0
	v_mov_b32_e32 v96, v0
	v_mov_b32_e32 v97, v0
	v_mov_b32_e32 v98, v0
	v_mov_b32_e32 v99, v0
	v_mov_b32_e32 v100, v0
	v_mov_b32_e32 v101, v0
	v_mov_b32_e32 v102, v0
	v_mov_b32_e32 v103, v0
	v_mov_b32_e32 v112, v0
	v_mov_b32_e32 v113, v0
	v_mov_b32_e32 v114, v0
	v_mov_b32_e32 v115, v0
	v_mov_b32_e32 v116, v0
	v_mov_b32_e32 v117, v0
	v_mov_b32_e32 v118, v0
	v_mov_b32_e32 v119, v0
	v_mov_b32_e32 v72, v0
	v_mov_b32_e32 v73, v0
	v_mov_b32_e32 v74, v0
	v_mov_b32_e32 v75, v0
	v_mov_b32_e32 v76, v0
	v_mov_b32_e32 v77, v0
	v_mov_b32_e32 v78, v0
	v_mov_b32_e32 v79, v0
	v_mov_b32_e32 v88, v0
	v_mov_b32_e32 v89, v0
	v_mov_b32_e32 v90, v0
	v_mov_b32_e32 v91, v0
	v_mov_b32_e32 v92, v0
	v_mov_b32_e32 v93, v0
	v_mov_b32_e32 v94, v0
	v_mov_b32_e32 v95, v0
	v_mov_b32_e32 v104, v0
	v_mov_b32_e32 v105, v0
	v_mov_b32_e32 v106, v0
	v_mov_b32_e32 v107, v0
	v_mov_b32_e32 v108, v0
	v_mov_b32_e32 v109, v0
	v_mov_b32_e32 v110, v0
	v_mov_b32_e32 v111, v0
	v_mov_b32_e32 v120, v0
	v_mov_b32_e32 v121, v0
	v_mov_b32_e32 v122, v0
	v_mov_b32_e32 v123, v0
	v_mov_b32_e32 v124, v0
	v_mov_b32_e32 v125, v0
	v_mov_b32_e32 v126, v0
	v_mov_b32_e32 v127, v0
	s_lshl_b32 s51, s44, 8
	s_add_i32 s51, s51, s65
	v_or_b32_e32 v148, s51, v154
	v_ashrrev_i32_e32 v149, 31, v148
	v_lshl_add_u64 v[146:147], v[148:149], 2, s[10:11]
	global_load_dword v232, v[146:147], off
.LBB0_962:
	ds_read_b128 v[146:149], v158
	ds_read_b128 v[150:153], v158 offset:1024
	ds_read_b128 v[162:165], v158 offset:2048
	ds_read_b128 v[166:169], v158 offset:3072
	s_add_u32 s33, s46, 0xfff80080
	s_addc_u32 s48, s47, -1
	s_cmp_eq_u32 s77, 28
	s_cselect_b32 s49, s37, s48
	s_cselect_b32 s48, s72, s33
	s_cselect_b32 s51, s19, s75
	s_cselect_b32 s50, s73, s74
	v_lshl_add_u64 v[204:205], s[46:47], 0, v[140:141]
	s_add_i32 m0, s45, 0xc000
	ds_read_b128 v[170:173], v159
	ds_read_b128 v[174:177], v159 offset:1024
	ds_read_b128 v[178:181], v159 offset:2048
	ds_read_b128 v[182:185], v159 offset:3072
	ds_read_b128 v[186:189], v159 offset:4096
	ds_read_b128 v[190:193], v159 offset:5120
	ds_read_b128 v[194:197], v159 offset:6144
	ds_read_b128 v[198:201], v159 offset:7168
	global_load_lds_dwordx4 v[204:205], off
	v_lshl_add_u64 v[204:205], s[46:47], 0, v[142:143]
	s_add_i32 m0, s45, 0xe000
	s_nop 0
	global_load_lds_dwordx4 v[204:205], off
	s_waitcnt lgkmcnt(8)
	s_barrier
	s_waitcnt lgkmcnt(0)
	v_mfma_f32_16x16x32_bf16 v[124:127], v[146:149], v[170:173], v[124:127]
	v_mfma_f32_16x16x32_bf16 v[120:123], v[162:165], v[170:173], v[120:123]
	v_mfma_f32_16x16x32_bf16 v[108:111], v[146:149], v[178:181], v[108:111]
	v_mfma_f32_16x16x32_bf16 v[104:107], v[162:165], v[178:181], v[104:107]
	v_mfma_f32_16x16x32_bf16 v[92:95], v[146:149], v[186:189], v[92:95]
	v_mfma_f32_16x16x32_bf16 v[88:91], v[162:165], v[186:189], v[88:91]
	v_mfma_f32_16x16x32_bf16 v[76:79], v[146:149], v[194:197], v[76:79]
	v_mfma_f32_16x16x32_bf16 v[72:75], v[162:165], v[194:197], v[72:75]
	v_mfma_f32_16x16x32_bf16 v[124:127], v[150:153], v[174:177], v[124:127]
	v_mfma_f32_16x16x32_bf16 v[120:123], v[166:169], v[174:177], v[120:123]
	v_mfma_f32_16x16x32_bf16 v[108:111], v[150:153], v[182:185], v[108:111]
	v_mfma_f32_16x16x32_bf16 v[104:107], v[166:169], v[182:185], v[104:107]
	v_mfma_f32_16x16x32_bf16 v[92:95], v[150:153], v[190:193], v[92:95]
	v_mfma_f32_16x16x32_bf16 v[88:91], v[166:169], v[190:193], v[88:91]
	v_mfma_f32_16x16x32_bf16 v[76:79], v[150:153], v[198:201], v[76:79]
	v_mfma_f32_16x16x32_bf16 v[72:75], v[166:169], v[198:201], v[72:75]
	s_barrier
; #define PG8_STAGE(bufoff, gbase, voff) do { _Pragma("unroll") for (int _i = 0; _i < 2; ++_i) \
;         __builtin_amdgcn_global_load_lds((const unsigned*)((const char*)(gbase) + (voff)[_i]), (LAS unsigned*)(lds + (bufoff) + ldsw + _i * 8192), 16, 0, 0); } while (0)
; #define PG8_LDA(dst, b, h) do { _Pragma("unroll") for (int m = 0; m < 4; ++m) _Pragma("unroll") for (int k = 0; k < 2; ++k) dst[m][k] = *(const LAS bf16x8*)(lds + PG8_SA(b, h) + aoff + m * 2048 + k * 1024); } while (0)
; #define PG8_LDB(dst, b, h) do { _Pragma("unroll") for (int n = 0; n < 2; ++n) _Pragma("unroll") for (int k = 0; k < 2; ++k) dst[n][k] = *(const LAS bf16x8*)(lds + PG8_SB(b, h) + boff + n * 2048 + k * 1024); } while (0)
; #define PG8_MMA(ai, bj, At, Bt) do { __builtin_amdgcn_s_setprio(1); _Pragma("unroll") for (int m = 0; m < 4; ++m) _Pragma("unroll") for (int n = 0; n < 2; ++n) _Pragma("unroll") for (int k = 0; k < 2; ++k) \
;         acc[ai][bj][m][n] = __builtin_amdgcn_mfma_f32_16x16x32_bf16(Bt[n][k], At[m][k], acc[ai][bj][m][n], 0, 0, 0); __builtin_amdgcn_s_setprio(0); } while (0)
; #define PG8_WAIT_V(n) asm volatile("s_waitcnt vmcnt(" #n ")" ::: "memory")
; #define PG8_WAIT_L(n) asm volatile("s_waitcnt lgkmcnt(" #n ")" ::: "memory")
; #define PG8_BAR __builtin_amdgcn_s_barrier()
; #define PG8_SCHED __builtin_amdgcn_sched_barrier(0)
; template <class Epi>
; __device__ __forceinline__ void gemm_phase(LAS unsigned char* lds, const Gemm g, const StaticOrder& S, const Epi& E) {
;     ...
;             PG8_LDB(B1, 0, 1); PG8_STAGE(PG8_SB(0, 0), b2, voffB0);
;             PG8_BAR; PG8_WAIT_L(0); PG8_MMA(0, 1, At, B1); PG8_BAR;
;             PG8_LDA(At, 0, 1); PG8_STAGE(PG8_SA(0, 0), a2, voffA);
;             PG8_BAR; PG8_WAIT_L(0); PG8_MMA(1, 0, At, B0); PG8_BAR; PG8_SCHED;
;             PG8_STAGE(PG8_SB(0, 1), b2, voffB1);
;             PG8_WAIT_V(6); PG8_BAR; PG8_MMA(1, 1, At, B1); PG8_BAR;
;             PG8_LDB(B0, 1, 0); PG8_SCHED; PG8_LDA(At, 1, 0); PG8_STAGE(PG8_SA(0, 1), a2 + hstep, voffA);
;             PG8_WAIT_L(8); PG8_BAR; PG8_WAIT_L(0); PG8_MMA(0, 0, At, B0); PG8_BAR; PG8_SCHED;
	s_add_i32 s33, s68, s57
	v_lshl_add_u64 v[220:221], s[50:51], 0, v[134:135]
	s_mov_b32 m0, s33
	ds_read_b128 v[204:207], v160
	ds_read_b128 v[208:211], v160 offset:1024
	ds_read_b128 v[212:215], v160 offset:2048
	ds_read_b128 v[216:219], v160 offset:3072
	global_load_lds_dwordx4 v[220:221], off
	v_lshl_add_u64 v[222:223], s[50:51], 0, v[128:129]
	s_add_i32 m0, s33, 0x2000
	s_nop 0
	global_load_lds_dwordx4 v[222:223], off
	s_barrier
	s_waitcnt lgkmcnt(0)
	v_mfma_f32_16x16x32_bf16 v[116:119], v[204:207], v[170:173], v[116:119]
	v_mfma_f32_16x16x32_bf16 v[112:115], v[212:215], v[170:173], v[112:115]
	v_mfma_f32_16x16x32_bf16 v[100:103], v[204:207], v[178:181], v[100:103]
	v_mfma_f32_16x16x32_bf16 v[96:99], v[212:215], v[178:181], v[96:99]
	v_mfma_f32_16x16x32_bf16 v[84:87], v[204:207], v[186:189], v[84:87]
	v_mfma_f32_16x16x32_bf16 v[80:83], v[212:215], v[186:189], v[80:83]
	v_mfma_f32_16x16x32_bf16 v[68:71], v[204:207], v[194:197], v[68:71]
	v_mfma_f32_16x16x32_bf16 v[64:67], v[212:215], v[194:197], v[64:67]
	v_mfma_f32_16x16x32_bf16 v[116:119], v[208:211], v[174:177], v[116:119]
	v_mfma_f32_16x16x32_bf16 v[112:115], v[216:219], v[174:177], v[112:115]
	v_mfma_f32_16x16x32_bf16 v[100:103], v[208:211], v[182:185], v[100:103]
	v_mfma_f32_16x16x32_bf16 v[96:99], v[216:219], v[182:185], v[96:99]
	v_mfma_f32_16x16x32_bf16 v[84:87], v[208:211], v[190:193], v[84:87]
	v_mfma_f32_16x16x32_bf16 v[80:83], v[216:219], v[190:193], v[80:83]
	v_mfma_f32_16x16x32_bf16 v[68:71], v[208:211], v[198:201], v[68:71]
	v_mfma_f32_16x16x32_bf16 v[64:67], v[216:219], v[198:201], v[64:67]
	s_mov_b32 m0, s45
	v_lshl_add_u64 v[224:225], s[48:49], 0, v[138:139]
	s_barrier
	ds_read_b128 v[170:173], v159 offset:16384
	ds_read_b128 v[174:177], v159 offset:17408
	ds_read_b128 v[178:181], v159 offset:18432
	ds_read_b128 v[182:185], v159 offset:19456
	ds_read_b128 v[186:189], v159 offset:20480
	ds_read_b128 v[190:193], v159 offset:21504
	ds_read_b128 v[194:197], v159 offset:22528
	ds_read_b128 v[198:201], v159 offset:23552
	global_load_lds_dwordx4 v[224:225], off
	v_lshl_add_u64 v[226:227], s[48:49], 0, v[132:133]
	s_mov_b32 m0, s59
	s_nop 0
	global_load_lds_dwordx4 v[226:227], off
	s_barrier
	s_waitcnt lgkmcnt(0)
	v_mfma_f32_16x16x32_bf16 v[60:63], v[146:149], v[170:173], v[60:63]
	v_mfma_f32_16x16x32_bf16 v[56:59], v[162:165], v[170:173], v[56:59]
	v_mfma_f32_16x16x32_bf16 v[44:47], v[146:149], v[178:181], v[44:47]
	v_mfma_f32_16x16x32_bf16 v[40:43], v[162:165], v[178:181], v[40:43]
	v_mfma_f32_16x16x32_bf16 v[28:31], v[146:149], v[186:189], v[28:31]
	v_mfma_f32_16x16x32_bf16 v[24:27], v[162:165], v[186:189], v[24:27]
	v_mfma_f32_16x16x32_bf16 v[12:15], v[146:149], v[194:197], v[12:15]
	v_mfma_f32_16x16x32_bf16 v[8:11], v[162:165], v[194:197], v[8:11]
	v_mfma_f32_16x16x32_bf16 v[60:63], v[150:153], v[174:177], v[60:63]
	v_mfma_f32_16x16x32_bf16 v[56:59], v[166:169], v[174:177], v[56:59]
	v_mfma_f32_16x16x32_bf16 v[44:47], v[150:153], v[182:185], v[44:47]
	v_mfma_f32_16x16x32_bf16 v[40:43], v[166:169], v[182:185], v[40:43]
	v_mfma_f32_16x16x32_bf16 v[28:31], v[150:153], v[190:193], v[28:31]
	v_mfma_f32_16x16x32_bf16 v[24:27], v[166:169], v[190:193], v[24:27]
	v_mfma_f32_16x16x32_bf16 v[12:15], v[150:153], v[198:201], v[12:15]
	v_mfma_f32_16x16x32_bf16 v[8:11], v[166:169], v[198:201], v[8:11]
	s_barrier
	s_add_i32 s33, s69, s57
	v_lshl_add_u64 v[228:229], s[50:51], 0, v[136:137]
	s_mov_b32 m0, s33
	v_lshl_add_u64 v[230:231], s[50:51], 0, v[130:131]
	global_load_lds_dwordx4 v[228:229], off
	s_add_i32 m0, s33, 0x2000
	s_nop 0
	global_load_lds_dwordx4 v[230:231], off
	s_add_i32 s33, 0, 0x18000
	v_add_u32_e32 v166, s33, v155
	ds_read_b128 v[146:149], v166
	ds_read_b128 v[150:153], v166 offset:1024
	ds_read_b128 v[162:165], v166 offset:2048
	ds_read_b128 v[166:169], v166 offset:3072
	s_waitcnt vmcnt(6)
	s_barrier
	v_mfma_f32_16x16x32_bf16 v[52:55], v[204:207], v[170:173], v[52:55]
	v_mfma_f32_16x16x32_bf16 v[48:51], v[212:215], v[170:173], v[48:51]
	v_mfma_f32_16x16x32_bf16 v[36:39], v[204:207], v[178:181], v[36:39]
	v_mfma_f32_16x16x32_bf16 v[32:35], v[212:215], v[178:181], v[32:35]
	v_mfma_f32_16x16x32_bf16 v[20:23], v[204:207], v[186:189], v[20:23]
	v_mfma_f32_16x16x32_bf16 v[16:19], v[212:215], v[186:189], v[16:19]
	v_mfma_f32_16x16x32_bf16 v[4:7], v[204:207], v[194:197], v[4:7]
	v_mfma_f32_16x16x32_bf16 v[0:3], v[212:215], v[194:197], v[0:3]
	v_mfma_f32_16x16x32_bf16 v[52:55], v[208:211], v[174:177], v[52:55]
	v_mfma_f32_16x16x32_bf16 v[48:51], v[216:219], v[174:177], v[48:51]
	v_mfma_f32_16x16x32_bf16 v[36:39], v[208:211], v[182:185], v[36:39]
	v_mfma_f32_16x16x32_bf16 v[32:35], v[216:219], v[182:185], v[32:35]
	v_mfma_f32_16x16x32_bf16 v[20:23], v[208:211], v[190:193], v[20:23]
	v_mfma_f32_16x16x32_bf16 v[16:19], v[216:219], v[190:193], v[16:19]
	v_mfma_f32_16x16x32_bf16 v[4:7], v[208:211], v[198:201], v[4:7]
	v_mfma_f32_16x16x32_bf16 v[0:3], v[216:219], v[198:201], v[0:3]
	s_barrier
	s_add_u32 s48, s48, 0x80000
	s_addc_u32 s49, s49, 0
	s_mov_b32 m0, s60
	v_lshl_add_u64 v[204:205], s[48:49], 0, v[138:139]
	ds_read_b128 v[170:173], v159 offset:32768
	ds_read_b128 v[174:177], v159 offset:33792
	ds_read_b128 v[178:181], v159 offset:34816
	ds_read_b128 v[182:185], v159 offset:35840
	ds_read_b128 v[186:189], v159 offset:36864
	ds_read_b128 v[190:193], v159 offset:37888
	ds_read_b128 v[194:197], v159 offset:38912
	ds_read_b128 v[198:201], v159 offset:39936
	global_load_lds_dwordx4 v[204:205], off
	v_lshl_add_u64 v[204:205], s[48:49], 0, v[132:133]
	s_mov_b32 m0, s61
	s_nop 0
	global_load_lds_dwordx4 v[204:205], off
	s_waitcnt lgkmcnt(8)
	s_barrier
; #define PG8_STAGE(bufoff, gbase, voff) do { _Pragma("unroll") for (int _i = 0; _i < 2; ++_i) \
;         __builtin_amdgcn_global_load_lds((const unsigned*)((const char*)(gbase) + (voff)[_i]), (LAS unsigned*)(lds + (bufoff) + ldsw + _i * 8192), 16, 0, 0); } while (0)
; #define PG8_LDA(dst, b, h) do { _Pragma("unroll") for (int m = 0; m < 4; ++m) _Pragma("unroll") for (int k = 0; k < 2; ++k) dst[m][k] = *(const LAS bf16x8*)(lds + PG8_SA(b, h) + aoff + m * 2048 + k * 1024); } while (0)
; #define PG8_LDB(dst, b, h) do { _Pragma("unroll") for (int n = 0; n < 2; ++n) _Pragma("unroll") for (int k = 0; k < 2; ++k) dst[n][k] = *(const LAS bf16x8*)(lds + PG8_SB(b, h) + boff + n * 2048 + k * 1024); } while (0)
; #define PG8_MMA(ai, bj, At, Bt) do { __builtin_amdgcn_s_setprio(1); _Pragma("unroll") for (int m = 0; m < 4; ++m) _Pragma("unroll") for (int n = 0; n < 2; ++n) _Pragma("unroll") for (int k = 0; k < 2; ++k) \
;         acc[ai][bj][m][n] = __builtin_amdgcn_mfma_f32_16x16x32_bf16(Bt[n][k], At[m][k], acc[ai][bj][m][n], 0, 0, 0); __builtin_amdgcn_s_setprio(0); } while (0)
; #define PG8_WAIT_V(n) asm volatile("s_waitcnt vmcnt(" #n ")" ::: "memory")
; #define PG8_WAIT_L(n) asm volatile("s_waitcnt lgkmcnt(" #n ")" ::: "memory")
; #define PG8_BAR __builtin_amdgcn_s_barrier()
; #define PG8_SCHED __builtin_amdgcn_sched_barrier(0)
; template <class Epi>
; __device__ __forceinline__ void gemm_phase(LAS unsigned char* lds, const Gemm g, const StaticOrder& S, const Epi& E) {
;     ...
;             PG8_WAIT_L(8); PG8_BAR; PG8_WAIT_L(0); PG8_MMA(0, 0, At, B0); PG8_BAR; PG8_SCHED;
;             PG8_LDB(B1, 1, 1); PG8_STAGE(PG8_SB(1, 0), b3, voffB0);
;             PG8_BAR; PG8_WAIT_L(0); PG8_MMA(0, 1, At, B1); PG8_BAR;
;             PG8_LDA(At, 1, 1); PG8_STAGE(PG8_SA(1, 0), a3, voffA);
;             PG8_BAR; PG8_WAIT_L(0); PG8_MMA(1, 0, At, B0); PG8_BAR; PG8_SCHED;
;             PG8_STAGE(PG8_SB(1, 1), b3, voffB1);
;             PG8_WAIT_V(6); PG8_BAR; PG8_MMA(1, 1, At, B1); PG8_BAR;
	s_waitcnt lgkmcnt(0)
	v_mfma_f32_16x16x32_bf16 v[124:127], v[146:149], v[170:173], v[124:127]
	v_mfma_f32_16x16x32_bf16 v[120:123], v[162:165], v[170:173], v[120:123]
	v_mfma_f32_16x16x32_bf16 v[108:111], v[146:149], v[178:181], v[108:111]
	v_mfma_f32_16x16x32_bf16 v[104:107], v[162:165], v[178:181], v[104:107]
	v_mfma_f32_16x16x32_bf16 v[92:95], v[146:149], v[186:189], v[92:95]
	v_mfma_f32_16x16x32_bf16 v[88:91], v[162:165], v[186:189], v[88:91]
	v_mfma_f32_16x16x32_bf16 v[76:79], v[146:149], v[194:197], v[76:79]
	v_mfma_f32_16x16x32_bf16 v[72:75], v[162:165], v[194:197], v[72:75]
	v_mfma_f32_16x16x32_bf16 v[124:127], v[150:153], v[174:177], v[124:127]
	v_mfma_f32_16x16x32_bf16 v[120:123], v[166:169], v[174:177], v[120:123]
	v_mfma_f32_16x16x32_bf16 v[108:111], v[150:153], v[182:185], v[108:111]
	v_mfma_f32_16x16x32_bf16 v[104:107], v[166:169], v[182:185], v[104:107]
	v_mfma_f32_16x16x32_bf16 v[92:95], v[150:153], v[190:193], v[92:95]
	v_mfma_f32_16x16x32_bf16 v[88:91], v[166:169], v[190:193], v[88:91]
	v_mfma_f32_16x16x32_bf16 v[76:79], v[150:153], v[198:201], v[76:79]
	v_mfma_f32_16x16x32_bf16 v[72:75], v[166:169], v[198:201], v[72:75]
	s_barrier
	s_add_i32 s48, 0, 0x1c000
	s_add_i32 s33, s33, s57
	v_add_u32_e32 v216, s48, v155
	v_lshl_add_u64 v[220:221], v[220:221], 0, s[16:17]
	s_mov_b32 m0, s33
	ds_read_b128 v[204:207], v216
	ds_read_b128 v[208:211], v216 offset:1024
	ds_read_b128 v[212:215], v216 offset:2048
	ds_read_b128 v[216:219], v216 offset:3072
	global_load_lds_dwordx4 v[220:221], off
	v_lshl_add_u64 v[220:221], v[222:223], 0, s[16:17]
	s_add_i32 m0, s33, 0x2000
	s_nop 0
	global_load_lds_dwordx4 v[220:221], off
	s_barrier
	s_waitcnt lgkmcnt(0)
	v_mfma_f32_16x16x32_bf16 v[116:119], v[204:207], v[170:173], v[116:119]
	v_mfma_f32_16x16x32_bf16 v[112:115], v[212:215], v[170:173], v[112:115]
	v_mfma_f32_16x16x32_bf16 v[100:103], v[204:207], v[178:181], v[100:103]
	v_mfma_f32_16x16x32_bf16 v[96:99], v[212:215], v[178:181], v[96:99]
	v_mfma_f32_16x16x32_bf16 v[84:87], v[204:207], v[186:189], v[84:87]
	v_mfma_f32_16x16x32_bf16 v[80:83], v[212:215], v[186:189], v[80:83]
	v_mfma_f32_16x16x32_bf16 v[68:71], v[204:207], v[194:197], v[68:71]
	v_mfma_f32_16x16x32_bf16 v[64:67], v[212:215], v[194:197], v[64:67]
	v_mfma_f32_16x16x32_bf16 v[116:119], v[208:211], v[174:177], v[116:119]
	v_mfma_f32_16x16x32_bf16 v[112:115], v[216:219], v[174:177], v[112:115]
	v_mfma_f32_16x16x32_bf16 v[100:103], v[208:211], v[182:185], v[100:103]
	v_mfma_f32_16x16x32_bf16 v[96:99], v[216:219], v[182:185], v[96:99]
	v_mfma_f32_16x16x32_bf16 v[84:87], v[208:211], v[190:193], v[84:87]
	v_mfma_f32_16x16x32_bf16 v[80:83], v[216:219], v[190:193], v[80:83]
	v_mfma_f32_16x16x32_bf16 v[68:71], v[208:211], v[198:201], v[68:71]
	v_mfma_f32_16x16x32_bf16 v[64:67], v[216:219], v[198:201], v[64:67]
	s_mov_b32 m0, s63
	v_lshl_add_u64 v[220:221], v[224:225], 0, s[16:17]
	s_barrier
	ds_read_b128 v[170:173], v159 offset:49152
	ds_read_b128 v[174:177], v159 offset:50176
	ds_read_b128 v[178:181], v159 offset:51200
	ds_read_b128 v[182:185], v159 offset:52224
	ds_read_b128 v[186:189], v159 offset:53248
	ds_read_b128 v[190:193], v159 offset:54272
	ds_read_b128 v[194:197], v159 offset:55296
	ds_read_b128 v[198:201], v159 offset:56320
	global_load_lds_dwordx4 v[220:221], off
	v_lshl_add_u64 v[220:221], v[226:227], 0, s[16:17]
	s_mov_b32 m0, s64
	s_nop 0
	global_load_lds_dwordx4 v[220:221], off
	s_barrier
	s_waitcnt lgkmcnt(0)
	v_mfma_f32_16x16x32_bf16 v[60:63], v[146:149], v[170:173], v[60:63]
	v_mfma_f32_16x16x32_bf16 v[56:59], v[162:165], v[170:173], v[56:59]
	v_mfma_f32_16x16x32_bf16 v[44:47], v[146:149], v[178:181], v[44:47]
	v_mfma_f32_16x16x32_bf16 v[40:43], v[162:165], v[178:181], v[40:43]
	v_mfma_f32_16x16x32_bf16 v[28:31], v[146:149], v[186:189], v[28:31]
	v_mfma_f32_16x16x32_bf16 v[24:27], v[162:165], v[186:189], v[24:27]
	v_mfma_f32_16x16x32_bf16 v[12:15], v[146:149], v[194:197], v[12:15]
	v_mfma_f32_16x16x32_bf16 v[8:11], v[162:165], v[194:197], v[8:11]
	v_mfma_f32_16x16x32_bf16 v[60:63], v[150:153], v[174:177], v[60:63]
	v_mfma_f32_16x16x32_bf16 v[56:59], v[166:169], v[174:177], v[56:59]
	v_mfma_f32_16x16x32_bf16 v[44:47], v[150:153], v[182:185], v[44:47]
	v_mfma_f32_16x16x32_bf16 v[40:43], v[166:169], v[182:185], v[40:43]
	v_mfma_f32_16x16x32_bf16 v[28:31], v[150:153], v[190:193], v[28:31]
	v_mfma_f32_16x16x32_bf16 v[24:27], v[166:169], v[190:193], v[24:27]
	v_mfma_f32_16x16x32_bf16 v[12:15], v[150:153], v[198:201], v[12:15]
	v_mfma_f32_16x16x32_bf16 v[8:11], v[166:169], v[198:201], v[8:11]
	s_barrier
	s_add_i32 s33, s48, s57
	v_lshl_add_u64 v[146:147], v[228:229], 0, s[16:17]
	s_mov_b32 m0, s33
	s_nop 0
	global_load_lds_dwordx4 v[146:147], off
	v_lshl_add_u64 v[146:147], v[230:231], 0, s[16:17]
	s_add_i32 m0, s33, 0x2000
	s_nop 0
	global_load_lds_dwordx4 v[146:147], off
	s_waitcnt vmcnt(6)
	s_barrier
	v_mfma_f32_16x16x32_bf16 v[52:55], v[204:207], v[170:173], v[52:55]
	v_mfma_f32_16x16x32_bf16 v[48:51], v[212:215], v[170:173], v[48:51]
	v_mfma_f32_16x16x32_bf16 v[36:39], v[204:207], v[178:181], v[36:39]
	v_mfma_f32_16x16x32_bf16 v[32:35], v[212:215], v[178:181], v[32:35]
	v_mfma_f32_16x16x32_bf16 v[20:23], v[204:207], v[186:189], v[20:23]
	v_mfma_f32_16x16x32_bf16 v[16:19], v[212:215], v[186:189], v[16:19]
	v_mfma_f32_16x16x32_bf16 v[4:7], v[204:207], v[194:197], v[4:7]
	v_mfma_f32_16x16x32_bf16 v[0:3], v[212:215], v[194:197], v[0:3]
	v_mfma_f32_16x16x32_bf16 v[52:55], v[208:211], v[174:177], v[52:55]
	v_mfma_f32_16x16x32_bf16 v[48:51], v[216:219], v[174:177], v[48:51]
	v_mfma_f32_16x16x32_bf16 v[36:39], v[208:211], v[182:185], v[36:39]
	v_mfma_f32_16x16x32_bf16 v[32:35], v[216:219], v[182:185], v[32:35]
	v_mfma_f32_16x16x32_bf16 v[20:23], v[208:211], v[190:193], v[20:23]
	v_mfma_f32_16x16x32_bf16 v[16:19], v[216:219], v[190:193], v[16:19]
	v_mfma_f32_16x16x32_bf16 v[4:7], v[208:211], v[198:201], v[4:7]
	v_mfma_f32_16x16x32_bf16 v[0:3], v[216:219], v[198:201], v[0:3]
	s_add_i32 s77, s77, 2
	s_add_u32 s46, s46, 0x100
	s_addc_u32 s47, s47, 0
	s_add_u32 s74, s74, 0x100
	s_addc_u32 s75, s75, 0
	s_cmp_gt_u32 s77, 29
	s_barrier
; __device__ __forceinline__ unsigned cvt_pk_bf16(float lo, float hi) { unsigned r; asm volatile("v_cvt_pk_bf16_f32 %0, %1, %2" : "=v"(r) : "v"(lo), "v"(hi)); return r; }
; __device__ __forceinline__ unsigned dpp_ror8(unsigned x) { return (unsigned)__builtin_amdgcn_update_dpp(0, (int)x, 0x128, 0xf, 0xf, false); }
; __device__ __forceinline__ void store_pair_lines(bf16_t* O, int ldc, int row, int fr, int col0, u32x4 wA, u32x4 wB) {
;     const u32x4 sA = {dpp_ror8(wA.x), dpp_ror8(wA.y), dpp_ror8(wA.z), dpp_ror8(wA.w)}, sB = {dpp_ror8(wB.x), dpp_ror8(wB.y), dpp_ror8(wB.z), dpp_ror8(wB.w)};
;     const bool lo = fr < 8;
;     const u32x4 o1 = lo ? wA : sB, o2 = lo ? sA : wB;
;     const int r1 = row - fr + (fr & 7), cb = col0 + (lo ? 0 : 8);
;     *(u32x4*)(O + (size_t)r1 * ldc + cb) = o1;
;     *(u32x4*)(O + (size_t)(r1 + 8) * ldc + cb) = o2;
; }
;     __device__ __forceinline__ void operator()(const f32x4 (&acc)[2][2][4][2], const Unit& u, int wr, int wc, int fr, int fq) const {
;         const int row0 = u.pm * BM + wr * 64 + fr; const int col0 = u.pn * BM + wc * 64 + 16 * fq;
; #pragma unroll
;         for (int ai = 0; ai < 2; ++ai)
; #pragma unroll
;             for (int m = 0; m < 4; ++m) { const int row = row0 + ai * HALF + m * 16;
;                 const float rs = ssin ? __builtin_amdgcn_rsqf(ssin[row] * (1.f / D) + EPS) : 1.0f; float sq = 0.f; u32x4 w[2];
; #pragma unroll
;                 for (int bj = 0; bj < 2; ++bj) { f32x4 v0 = acc[ai][bj][m][0] * rs, v1 = acc[ai][bj][m][1] * rs;
;                     if (ACT == 1) {
; #pragma unroll
;                         for (int j = 0; j < 4; ++j) { const float a = fmaxf(v0[j], 0.f), b = fmaxf(v1[j], 0.f); v0[j] = a * a; v1[j] = b * b; } }
;                     sq += (v0[0] * v0[0] + v0[1] * v0[1]) + (v0[2] * v0[2] + v0[3] * v0[3]) + (v1[0] * v1[0] + v1[1] * v1[1]) + (v1[2] * v1[2] + v1[3] * v1[3]);
;                     w[bj].x = cvt_pk_bf16(v0[0], v0[1]); w[bj].y = cvt_pk_bf16(v0[2], v0[3]); w[bj].z = cvt_pk_bf16(v1[0], v1[1]); w[bj].w = cvt_pk_bf16(v1[2], v1[3]); }
;                 store_pair_lines(O, ldc, row, fr, col0, w[0], w[1]);
	s_cbranch_scc0 .LBB0_962
	s_lshl_b32 s19, s44, 8
	s_add_i32 s19, s19, s65
	v_or_b32_e32 v152, s19, v154
	v_ashrrev_i32_e32 v153, 31, v152
	v_lshl_add_u64 v[150:151], v[152:153], 2, s[10:11]
	s_waitcnt vmcnt(8)
	s_nop 0
	v_mov_b32_e32 v153, v232
	s_nop 1
	v_or_b32_e32 v180, 16, v152
	v_ashrrev_i32_e32 v181, 31, v180
	v_lshl_add_u64 v[182:183], v[180:181], 2, s[10:11]
	global_load_dword v179, v[182:183], off
	v_or_b32_e32 v180, 32, v152
	v_ashrrev_i32_e32 v181, 31, v180
	v_lshl_add_u64 v[182:183], v[180:181], 2, s[10:11]
	global_load_dword v184, v[182:183], off
	v_or_b32_e32 v180, 48, v152
	v_ashrrev_i32_e32 v181, 31, v180
	v_lshl_add_u64 v[182:183], v[180:181], 2, s[10:11]
	global_load_dword v185, v[182:183], off
	global_load_dword v186, v[150:151], off offset:512
	global_load_dword v187, v[150:151], off offset:576
	global_load_dword v188, v[150:151], off offset:640
	global_load_dword v189, v[150:151], off offset:704
	v_lshl_or_b32 v148, s71, 8, v157
	v_mov_b32_e32 v169, 0
	v_mov_b64_e32 v[146:147], s[8:9]
	v_ashrrev_i32_e32 v149, 31, v148
	v_or_b32_e32 v164, s19, v156
	v_lshlrev_b64 v[148:149], 1, v[148:149]
	v_mad_i64_i32 v[162:163], s[46:47], v164, s70, v[146:147]
	v_or_b32_e32 v165, 8, v164
	v_or_b32_e32 v164, 16, v152
	v_lshl_add_u64 v[162:163], v[162:163], 0, v[148:149]
	v_mad_i64_i32 v[166:167], s[46:47], v165, s70, v[146:147]
	v_ashrrev_i32_e32 v165, 31, v164
	v_lshl_add_u64 v[166:167], v[166:167], 0, v[148:149]
	v_lshl_add_u64 v[170:171], v[164:165], 2, s[10:11]
	s_and_b64 vcc, exec, s[40:41]
	s_mov_b32 s71, s18
	s_mov_b32 s44, s36
	s_mov_b64 s[48:49], s[42:43]
	v_fmamk_f32 v153, v153, 0x3a000000, v161
	v_rsq_f32_e32 v168, v153
	v_mov_b32_e32 v153, 0
	v_pk_mul_f32 v[124:125], v[124:125], v[168:169] op_sel_hi:[1,0]
	v_pk_mul_f32 v[120:121], v[120:121], v[168:169] op_sel_hi:[1,0]
	v_pk_mul_f32 v[118:119], v[118:119], v[168:169] op_sel_hi:[1,0]
	v_pk_mul_f32 v[116:117], v[116:117], v[168:169] op_sel_hi:[1,0]
	v_pk_mul_f32 v[126:127], v[126:127], v[168:169] op_sel_hi:[1,0]
	v_pk_mul_f32 v[122:123], v[122:123], v[168:169] op_sel_hi:[1,0]
	v_pk_mul_f32 v[114:115], v[114:115], v[168:169] op_sel_hi:[1,0]
	v_pk_mul_f32 v[112:113], v[112:113], v[168:169] op_sel_hi:[1,0]
	v_cvt_pk_bf16_f32 v124, v124, v125
	v_cvt_pk_bf16_f32 v125, v126, v127
	v_cvt_pk_bf16_f32 v120, v120, v121
	v_cvt_pk_bf16_f32 v121, v122, v123
	v_cvt_pk_bf16_f32 v116, v116, v117
	v_cvt_pk_bf16_f32 v117, v118, v119
	s_nop 0
	v_cvt_pk_bf16_f32 v118, v112, v113
	v_cvt_pk_bf16_f32 v119, v114, v115
	s_nop 0
	v_mov_b32_dpp v169, v124 row_ror:8 row_mask:0xf bank_mask:0xf
	v_mov_b32_dpp v172, v125 row_ror:8 row_mask:0xf bank_mask:0xf
	v_mov_b32_dpp v175, v116 row_ror:8 row_mask:0xf bank_mask:0xf
	v_mov_b32_dpp v176, v117 row_ror:8 row_mask:0xf bank_mask:0xf
	v_mov_b32_dpp v177, v118 row_ror:8 row_mask:0xf bank_mask:0xf
	v_mov_b32_dpp v178, v119 row_ror:8 row_mask:0xf bank_mask:0xf
	v_mov_b32_dpp v173, v120 row_ror:8 row_mask:0xf bank_mask:0xf
	v_mov_b32_dpp v174, v121 row_ror:8 row_mask:0xf bank_mask:0xf
	v_cndmask_b32_e64 v112, v175, v124, s[6:7]
	v_cndmask_b32_e64 v113, v176, v125, s[6:7]
	v_cndmask_b32_e64 v114, v177, v120, s[6:7]
	v_cndmask_b32_e64 v115, v178, v121, s[6:7]
	v_cndmask_b32_e64 v116, v116, v169, s[6:7]
	v_cndmask_b32_e64 v117, v117, v172, s[6:7]
	v_cndmask_b32_e64 v118, v118, v173, s[6:7]
	v_cndmask_b32_e64 v119, v119, v174, s[6:7]
	global_store_dwordx4 v[162:163], v[112:115], off
	global_store_dwordx4 v[166:167], v[116:119], off
	s_waitcnt vmcnt(8)
	s_nop 0
	v_mov_b32_e32 v118, v179
	s_nop 1
	v_or_b32_e32 v112, 32, v152
	v_mov_b32_e32 v119, 0
	v_sub_u32_e32 v114, v164, v154
	v_ashrrev_i32_e32 v113, 31, v112
	v_add_u32_e32 v120, v114, v156
	v_lshl_add_u64 v[114:115], v[112:113], 2, s[10:11]
	v_mad_i64_i32 v[116:117], s[46:47], v120, s70, v[146:147]
	v_add_u32_e32 v113, 8, v120
	v_lshl_add_u64 v[116:117], v[116:117], 0, v[148:149]
	v_mad_i64_i32 v[120:121], s[46:47], v113, s70, v[146:147]
	v_lshl_add_u64 v[120:121], v[120:121], 0, v[148:149]
	v_fmamk_f32 v118, v118, 0x3a000000, v161
	v_rsq_f32_e32 v118, v118
	s_nop 0
	v_pk_mul_f32 v[108:109], v[108:109], v[118:119] op_sel_hi:[1,0]
	v_pk_mul_f32 v[104:105], v[104:105], v[118:119] op_sel_hi:[1,0]
	v_pk_mul_f32 v[102:103], v[102:103], v[118:119] op_sel_hi:[1,0]
	v_pk_mul_f32 v[100:101], v[100:101], v[118:119] op_sel_hi:[1,0]
	v_pk_mul_f32 v[110:111], v[110:111], v[118:119] op_sel_hi:[1,0]
	v_pk_mul_f32 v[106:107], v[106:107], v[118:119] op_sel_hi:[1,0]
	v_pk_mul_f32 v[98:99], v[98:99], v[118:119] op_sel_hi:[1,0]
	v_pk_mul_f32 v[96:97], v[96:97], v[118:119] op_sel_hi:[1,0]
	v_cvt_pk_bf16_f32 v108, v108, v109
	v_cvt_pk_bf16_f32 v109, v110, v111
	v_cvt_pk_bf16_f32 v104, v104, v105
	v_cvt_pk_bf16_f32 v105, v106, v107
	v_cvt_pk_bf16_f32 v100, v100, v101
	v_cvt_pk_bf16_f32 v101, v102, v103
	s_nop 0
	v_cvt_pk_bf16_f32 v102, v96, v97
	v_cvt_pk_bf16_f32 v103, v98, v99
	s_nop 0
	v_mov_b32_dpp v119, v108 row_ror:8 row_mask:0xf bank_mask:0xf
	v_mov_b32_dpp v122, v109 row_ror:8 row_mask:0xf bank_mask:0xf
	v_mov_b32_dpp v125, v100 row_ror:8 row_mask:0xf bank_mask:0xf
	v_mov_b32_dpp v126, v101 row_ror:8 row_mask:0xf bank_mask:0xf
	v_mov_b32_dpp v127, v102 row_ror:8 row_mask:0xf bank_mask:0xf
	v_mov_b32_dpp v153, v103 row_ror:8 row_mask:0xf bank_mask:0xf
	v_mov_b32_dpp v123, v104 row_ror:8 row_mask:0xf bank_mask:0xf
	v_mov_b32_dpp v124, v105 row_ror:8 row_mask:0xf bank_mask:0xf
	v_cndmask_b32_e64 v96, v125, v108, s[6:7]
	v_cndmask_b32_e64 v97, v126, v109, s[6:7]
	v_cndmask_b32_e64 v98, v127, v104, s[6:7]
	v_cndmask_b32_e64 v99, v153, v105, s[6:7]
	v_cndmask_b32_e64 v100, v100, v119, s[6:7]
	v_cndmask_b32_e64 v101, v101, v122, s[6:7]
	v_cndmask_b32_e64 v102, v102, v123, s[6:7]
	v_cndmask_b32_e64 v103, v103, v124, s[6:7]
	global_store_dwordx4 v[116:117], v[96:99], off
	global_store_dwordx4 v[120:121], v[100:103], off
	s_waitcnt vmcnt(9)
; __device__ __forceinline__ unsigned cvt_pk_bf16(float lo, float hi) { unsigned r; asm volatile("v_cvt_pk_bf16_f32 %0, %1, %2" : "=v"(r) : "v"(lo), "v"(hi)); return r; }
; __device__ __forceinline__ unsigned dpp_ror8(unsigned x) { return (unsigned)__builtin_amdgcn_update_dpp(0, (int)x, 0x128, 0xf, 0xf, false); }
; __device__ __forceinline__ void store_pair_lines(bf16_t* O, int ldc, int row, int fr, int col0, u32x4 wA, u32x4 wB) {
;     const u32x4 sA = {dpp_ror8(wA.x), dpp_ror8(wA.y), dpp_ror8(wA.z), dpp_ror8(wA.w)}, sB = {dpp_ror8(wB.x), dpp_ror8(wB.y), dpp_ror8(wB.z), dpp_ror8(wB.w)};
;     const bool lo = fr < 8;
;     const u32x4 o1 = lo ? wA : sB, o2 = lo ? sA : wB;
;     const int r1 = row - fr + (fr & 7), cb = col0 + (lo ? 0 : 8);
;     *(u32x4*)(O + (size_t)r1 * ldc + cb) = o1;
;     *(u32x4*)(O + (size_t)(r1 + 8) * ldc + cb) = o2;
; }
;     __device__ __forceinline__ void operator()(const f32x4 (&acc)[2][2][4][2], const Unit& u, int wr, int wc, int fr, int fq) const {
;     ...
;             for (int m = 0; m < 4; ++m) { const int row = row0 + ai * HALF + m * 16;
;                 const float rs = ssin ? __builtin_amdgcn_rsqf(ssin[row] * (1.f / D) + EPS) : 1.0f; float sq = 0.f; u32x4 w[2];
; #pragma unroll
;                 for (int bj = 0; bj < 2; ++bj) { f32x4 v0 = acc[ai][bj][m][0] * rs, v1 = acc[ai][bj][m][1] * rs;
;                     if (ACT == 1) {
; #pragma unroll
;                         for (int j = 0; j < 4; ++j) { const float a = fmaxf(v0[j], 0.f), b = fmaxf(v1[j], 0.f); v0[j] = a * a; v1[j] = b * b; } }
;                     sq += (v0[0] * v0[0] + v0[1] * v0[1]) + (v0[2] * v0[2] + v0[3] * v0[3]) + (v1[0] * v1[0] + v1[1] * v1[1]) + (v1[2] * v1[2] + v1[3] * v1[3]);
;                     w[bj].x = cvt_pk_bf16(v0[0], v0[1]); w[bj].y = cvt_pk_bf16(v0[2], v0[3]); w[bj].z = cvt_pk_bf16(v1[0], v1[1]); w[bj].w = cvt_pk_bf16(v1[2], v1[3]); }
;                 store_pair_lines(O, ldc, row, fr, col0, w[0], w[1]);
	s_nop 0
	v_mov_b32_e32 v102, v184
	s_nop 1
	v_or_b32_e32 v96, 48, v152
	v_mov_b32_e32 v103, 0
	v_sub_u32_e32 v98, v112, v154
	v_ashrrev_i32_e32 v97, 31, v96
	v_add_u32_e32 v104, v98, v156
	v_lshl_add_u64 v[98:99], v[96:97], 2, s[10:11]
	v_mad_i64_i32 v[100:101], s[46:47], v104, s70, v[146:147]
	v_add_u32_e32 v97, 8, v104
	v_lshl_add_u64 v[100:101], v[100:101], 0, v[148:149]
	v_mad_i64_i32 v[104:105], s[46:47], v97, s70, v[146:147]
	v_lshl_add_u64 v[104:105], v[104:105], 0, v[148:149]
	v_fmamk_f32 v102, v102, 0x3a000000, v161
	v_rsq_f32_e32 v102, v102
	s_nop 0
	v_pk_mul_f32 v[92:93], v[92:93], v[102:103] op_sel_hi:[1,0]
	v_pk_mul_f32 v[88:89], v[88:89], v[102:103] op_sel_hi:[1,0]
	v_pk_mul_f32 v[86:87], v[86:87], v[102:103] op_sel_hi:[1,0]
	v_pk_mul_f32 v[84:85], v[84:85], v[102:103] op_sel_hi:[1,0]
	v_pk_mul_f32 v[94:95], v[94:95], v[102:103] op_sel_hi:[1,0]
	v_pk_mul_f32 v[90:91], v[90:91], v[102:103] op_sel_hi:[1,0]
	v_pk_mul_f32 v[82:83], v[82:83], v[102:103] op_sel_hi:[1,0]
	v_pk_mul_f32 v[80:81], v[80:81], v[102:103] op_sel_hi:[1,0]
	v_cvt_pk_bf16_f32 v92, v92, v93
	v_cvt_pk_bf16_f32 v93, v94, v95
	v_cvt_pk_bf16_f32 v88, v88, v89
	v_cvt_pk_bf16_f32 v89, v90, v91
	v_cvt_pk_bf16_f32 v84, v84, v85
	v_cvt_pk_bf16_f32 v85, v86, v87
	s_nop 0
	v_cvt_pk_bf16_f32 v86, v80, v81
	v_cvt_pk_bf16_f32 v87, v82, v83
	s_nop 0
	v_mov_b32_dpp v103, v92 row_ror:8 row_mask:0xf bank_mask:0xf
	v_mov_b32_dpp v106, v93 row_ror:8 row_mask:0xf bank_mask:0xf
	v_mov_b32_dpp v109, v84 row_ror:8 row_mask:0xf bank_mask:0xf
	v_mov_b32_dpp v110, v85 row_ror:8 row_mask:0xf bank_mask:0xf
	v_mov_b32_dpp v111, v86 row_ror:8 row_mask:0xf bank_mask:0xf
	v_mov_b32_dpp v113, v87 row_ror:8 row_mask:0xf bank_mask:0xf
	v_mov_b32_dpp v107, v88 row_ror:8 row_mask:0xf bank_mask:0xf
	v_mov_b32_dpp v108, v89 row_ror:8 row_mask:0xf bank_mask:0xf
	v_cndmask_b32_e64 v80, v109, v92, s[6:7]
	v_cndmask_b32_e64 v81, v110, v93, s[6:7]
	v_cndmask_b32_e64 v82, v111, v88, s[6:7]
	v_cndmask_b32_e64 v83, v113, v89, s[6:7]
	v_cndmask_b32_e64 v84, v84, v103, s[6:7]
	v_cndmask_b32_e64 v85, v85, v106, s[6:7]
	v_cndmask_b32_e64 v86, v86, v107, s[6:7]
	v_cndmask_b32_e64 v87, v87, v108, s[6:7]
	global_store_dwordx4 v[100:101], v[80:83], off
	global_store_dwordx4 v[104:105], v[84:87], off
	s_waitcnt vmcnt(10)
	s_nop 0
	v_mov_b32_e32 v82, v185
	s_nop 1
	v_mov_b32_e32 v83, 0
	v_sub_u32_e32 v80, v96, v154
	v_add_u32_e32 v84, v80, v156
	v_mad_i64_i32 v[80:81], s[46:47], v84, s70, v[146:147]
	v_add_u32_e32 v84, 8, v84
	v_lshl_add_u64 v[80:81], v[80:81], 0, v[148:149]
	v_mad_i64_i32 v[84:85], s[46:47], v84, s70, v[146:147]
	v_lshl_add_u64 v[84:85], v[84:85], 0, v[148:149]
	v_fmamk_f32 v82, v82, 0x3a000000, v161
	v_rsq_f32_e32 v82, v82
	s_nop 0
	v_pk_mul_f32 v[76:77], v[76:77], v[82:83] op_sel_hi:[1,0]
	v_pk_mul_f32 v[72:73], v[72:73], v[82:83] op_sel_hi:[1,0]
	v_pk_mul_f32 v[70:71], v[70:71], v[82:83] op_sel_hi:[1,0]
	v_pk_mul_f32 v[68:69], v[68:69], v[82:83] op_sel_hi:[1,0]
	v_pk_mul_f32 v[78:79], v[78:79], v[82:83] op_sel_hi:[1,0]
	v_pk_mul_f32 v[74:75], v[74:75], v[82:83] op_sel_hi:[1,0]
	v_pk_mul_f32 v[66:67], v[66:67], v[82:83] op_sel_hi:[1,0]
	v_pk_mul_f32 v[64:65], v[64:65], v[82:83] op_sel_hi:[1,0]
	v_cvt_pk_bf16_f32 v76, v76, v77
	v_cvt_pk_bf16_f32 v77, v78, v79
	v_cvt_pk_bf16_f32 v72, v72, v73
	v_cvt_pk_bf16_f32 v73, v74, v75
	v_cvt_pk_bf16_f32 v68, v68, v69
	v_cvt_pk_bf16_f32 v69, v70, v71
	s_nop 0
	v_cvt_pk_bf16_f32 v70, v64, v65
	v_cvt_pk_bf16_f32 v71, v66, v67
	s_nop 0
	v_mov_b32_dpp v83, v76 row_ror:8 row_mask:0xf bank_mask:0xf
	v_mov_b32_dpp v86, v77 row_ror:8 row_mask:0xf bank_mask:0xf
	v_mov_b32_dpp v89, v68 row_ror:8 row_mask:0xf bank_mask:0xf
	v_mov_b32_dpp v90, v69 row_ror:8 row_mask:0xf bank_mask:0xf
	v_mov_b32_dpp v91, v70 row_ror:8 row_mask:0xf bank_mask:0xf
	v_mov_b32_dpp v92, v71 row_ror:8 row_mask:0xf bank_mask:0xf
	v_mov_b32_dpp v87, v72 row_ror:8 row_mask:0xf bank_mask:0xf
	v_mov_b32_dpp v88, v73 row_ror:8 row_mask:0xf bank_mask:0xf
	v_cndmask_b32_e64 v64, v89, v76, s[6:7]
	v_cndmask_b32_e64 v65, v90, v77, s[6:7]
	v_cndmask_b32_e64 v66, v91, v72, s[6:7]
	v_cndmask_b32_e64 v67, v92, v73, s[6:7]
	v_cndmask_b32_e64 v68, v68, v83, s[6:7]
	v_cndmask_b32_e64 v69, v69, v86, s[6:7]
	v_cndmask_b32_e64 v70, v70, v87, s[6:7]
	v_cndmask_b32_e64 v71, v71, v88, s[6:7]
	global_store_dwordx4 v[80:81], v[64:67], off
	global_store_dwordx4 v[84:85], v[68:71], off
	s_waitcnt vmcnt(11)
	s_nop 0
	v_mov_b32_e32 v66, v186
	s_nop 1
	v_sub_u32_e32 v64, v152, v154
	v_mov_b32_e32 v67, 0
	v_add_u32_e32 v77, v64, v156
	v_add_u32_e32 v64, 0x80, v77
	v_add_u32_e32 v68, 0x88, v77
	v_mad_i64_i32 v[64:65], s[46:47], v64, s70, v[146:147]
	v_mad_i64_i32 v[68:69], s[46:47], v68, s70, v[146:147]
	v_lshl_add_u64 v[64:65], v[64:65], 0, v[148:149]
	v_lshl_add_u64 v[68:69], v[68:69], 0, v[148:149]
	v_fmamk_f32 v66, v66, 0x3a000000, v161
	v_rsq_f32_e32 v66, v66
	s_nop 0
	v_pk_mul_f32 v[60:61], v[60:61], v[66:67] op_sel_hi:[1,0]
	v_pk_mul_f32 v[56:57], v[56:57], v[66:67] op_sel_hi:[1,0]
	v_pk_mul_f32 v[54:55], v[54:55], v[66:67] op_sel_hi:[1,0]
	v_pk_mul_f32 v[52:53], v[52:53], v[66:67] op_sel_hi:[1,0]
	v_pk_mul_f32 v[62:63], v[62:63], v[66:67] op_sel_hi:[1,0]
	v_pk_mul_f32 v[58:59], v[58:59], v[66:67] op_sel_hi:[1,0]
	v_pk_mul_f32 v[50:51], v[50:51], v[66:67] op_sel_hi:[1,0]
	v_pk_mul_f32 v[48:49], v[48:49], v[66:67] op_sel_hi:[1,0]
	v_cvt_pk_bf16_f32 v60, v60, v61
	v_cvt_pk_bf16_f32 v61, v62, v63
	v_cvt_pk_bf16_f32 v56, v56, v57
	v_cvt_pk_bf16_f32 v57, v58, v59
	v_cvt_pk_bf16_f32 v52, v52, v53
	v_cvt_pk_bf16_f32 v53, v54, v55
	s_nop 0
	v_cvt_pk_bf16_f32 v54, v48, v49
	v_cvt_pk_bf16_f32 v55, v50, v51
	s_nop 0
	v_mov_b32_dpp v67, v60 row_ror:8 row_mask:0xf bank_mask:0xf
	v_mov_b32_dpp v70, v61 row_ror:8 row_mask:0xf bank_mask:0xf
	v_mov_b32_dpp v73, v52 row_ror:8 row_mask:0xf bank_mask:0xf
	v_mov_b32_dpp v74, v53 row_ror:8 row_mask:0xf bank_mask:0xf
	v_mov_b32_dpp v75, v54 row_ror:8 row_mask:0xf bank_mask:0xf
	v_mov_b32_dpp v76, v55 row_ror:8 row_mask:0xf bank_mask:0xf
	v_mov_b32_dpp v71, v56 row_ror:8 row_mask:0xf bank_mask:0xf
	v_mov_b32_dpp v72, v57 row_ror:8 row_mask:0xf bank_mask:0xf
	v_cndmask_b32_e64 v48, v73, v60, s[6:7]
	v_cndmask_b32_e64 v49, v74, v61, s[6:7]
	v_cndmask_b32_e64 v50, v75, v56, s[6:7]
	v_cndmask_b32_e64 v51, v76, v57, s[6:7]
	v_cndmask_b32_e64 v52, v52, v67, s[6:7]
	v_cndmask_b32_e64 v53, v53, v70, s[6:7]
	v_cndmask_b32_e64 v54, v54, v71, s[6:7]
	v_cndmask_b32_e64 v55, v55, v72, s[6:7]
	global_store_dwordx4 v[64:65], v[48:51], off
	global_store_dwordx4 v[68:69], v[52:55], off
	s_waitcnt vmcnt(12)
; __device__ __forceinline__ unsigned cvt_pk_bf16(float lo, float hi) { unsigned r; asm volatile("v_cvt_pk_bf16_f32 %0, %1, %2" : "=v"(r) : "v"(lo), "v"(hi)); return r; }
; #define PG8_WAIT_V(n) asm volatile("s_waitcnt vmcnt(" #n ")" ::: "memory")
; #define PG8_BAR __builtin_amdgcn_s_barrier()
;     __device__ __forceinline__ void operator()(const f32x4 (&acc)[2][2][4][2], const Unit& u, int wr, int wc, int fr, int fq) const {
;     ...
;             for (int m = 0; m < 4; ++m) { const int row = row0 + ai * HALF + m * 16;
;                 const float rs = ssin ? __builtin_amdgcn_rsqf(ssin[row] * (1.f / D) + EPS) : 1.0f; float sq = 0.f; u32x4 w[2];
; #pragma unroll
;                 for (int bj = 0; bj < 2; ++bj) { f32x4 v0 = acc[ai][bj][m][0] * rs, v1 = acc[ai][bj][m][1] * rs;
;                     if (ACT == 1) {
; #pragma unroll
;                         for (int j = 0; j < 4; ++j) { const float a = fmaxf(v0[j], 0.f), b = fmaxf(v1[j], 0.f); v0[j] = a * a; v1[j] = b * b; } }
;                     sq += (v0[0] * v0[0] + v0[1] * v0[1]) + (v0[2] * v0[2] + v0[3] * v0[3]) + (v1[0] * v1[0] + v1[1] * v1[1]) + (v1[2] * v1[2] + v1[3] * v1[3]);
;                     w[bj].x = cvt_pk_bf16(v0[0], v0[1]); w[bj].y = cvt_pk_bf16(v0[2], v0[3]); w[bj].z = cvt_pk_bf16(v1[0], v1[1]); w[bj].w = cvt_pk_bf16(v1[2], v1[3]); }
;                 store_pair_lines(O, ldc, row, fr, col0, w[0], w[1]);
; template <class Epi>
; __device__ __forceinline__ void gemm_phase(LAS unsigned char* lds, const Gemm g, const StaticOrder& S, const Epi& E) {
;     ...
;         E(acc, cur, wr, wc, fr, fq);
;         if (!has_next) break;
; #pragma unroll
;         for (int a = 0; a < 2; ++a)
; #pragma unroll
;             for (int b = 0; b < 2; ++b)
; #pragma unroll
;                 for (int m = 0; m < 4; ++m)
; #pragma unroll
;                     for (int n = 0; n < 2; ++n) acc[a][b][m][n] = (f32x4){0.f, 0.f, 0.f, 0.f};
;         cur = nxt; cA = nA; cB = nB; ++ui;
;     }
;     PG8_WAIT_V(0);
;     if (wr == 0) PG8_BAR;
;     PG8_BAR;
	s_nop 0
	v_mov_b32_e32 v50, v187
	s_nop 1
	v_mov_b32_e32 v51, 0
	v_add_u32_e32 v48, 0x90, v77
	v_add_u32_e32 v52, 0x98, v77
	v_mad_i64_i32 v[48:49], s[46:47], v48, s70, v[146:147]
	v_mad_i64_i32 v[52:53], s[46:47], v52, s70, v[146:147]
	v_lshl_add_u64 v[48:49], v[48:49], 0, v[148:149]
	v_lshl_add_u64 v[52:53], v[52:53], 0, v[148:149]
	v_fmamk_f32 v50, v50, 0x3a000000, v161
	v_rsq_f32_e32 v50, v50
	s_nop 0
	v_pk_mul_f32 v[44:45], v[44:45], v[50:51] op_sel_hi:[1,0]
	v_pk_mul_f32 v[40:41], v[40:41], v[50:51] op_sel_hi:[1,0]
	v_pk_mul_f32 v[38:39], v[38:39], v[50:51] op_sel_hi:[1,0]
	v_pk_mul_f32 v[36:37], v[36:37], v[50:51] op_sel_hi:[1,0]
	v_pk_mul_f32 v[46:47], v[46:47], v[50:51] op_sel_hi:[1,0]
	v_pk_mul_f32 v[42:43], v[42:43], v[50:51] op_sel_hi:[1,0]
	v_pk_mul_f32 v[34:35], v[34:35], v[50:51] op_sel_hi:[1,0]
	v_pk_mul_f32 v[32:33], v[32:33], v[50:51] op_sel_hi:[1,0]
	v_cvt_pk_bf16_f32 v44, v44, v45
	v_cvt_pk_bf16_f32 v45, v46, v47
	v_cvt_pk_bf16_f32 v40, v40, v41
	v_cvt_pk_bf16_f32 v41, v42, v43
	v_cvt_pk_bf16_f32 v36, v36, v37
	v_cvt_pk_bf16_f32 v37, v38, v39
	s_nop 0
	v_cvt_pk_bf16_f32 v38, v32, v33
	v_cvt_pk_bf16_f32 v39, v34, v35
	s_nop 0
	v_mov_b32_dpp v51, v44 row_ror:8 row_mask:0xf bank_mask:0xf
	v_mov_b32_dpp v54, v45 row_ror:8 row_mask:0xf bank_mask:0xf
	v_mov_b32_dpp v57, v36 row_ror:8 row_mask:0xf bank_mask:0xf
	v_mov_b32_dpp v58, v37 row_ror:8 row_mask:0xf bank_mask:0xf
	v_mov_b32_dpp v59, v38 row_ror:8 row_mask:0xf bank_mask:0xf
	v_mov_b32_dpp v60, v39 row_ror:8 row_mask:0xf bank_mask:0xf
	v_mov_b32_dpp v55, v40 row_ror:8 row_mask:0xf bank_mask:0xf
	v_mov_b32_dpp v56, v41 row_ror:8 row_mask:0xf bank_mask:0xf
	v_cndmask_b32_e64 v32, v57, v44, s[6:7]
	v_cndmask_b32_e64 v33, v58, v45, s[6:7]
	v_cndmask_b32_e64 v34, v59, v40, s[6:7]
	v_cndmask_b32_e64 v35, v60, v41, s[6:7]
	v_cndmask_b32_e64 v36, v36, v51, s[6:7]
	v_cndmask_b32_e64 v37, v37, v54, s[6:7]
	v_cndmask_b32_e64 v38, v38, v55, s[6:7]
	v_cndmask_b32_e64 v39, v39, v56, s[6:7]
	global_store_dwordx4 v[48:49], v[32:35], off
	global_store_dwordx4 v[52:53], v[36:39], off
	s_waitcnt vmcnt(13)
	s_nop 0
	v_mov_b32_e32 v34, v188
	s_nop 1
	v_mov_b32_e32 v35, 0
	v_add_u32_e32 v32, 0xa0, v77
	v_add_u32_e32 v36, 0xa8, v77
	v_mad_i64_i32 v[32:33], s[46:47], v32, s70, v[146:147]
	v_mad_i64_i32 v[36:37], s[46:47], v36, s70, v[146:147]
	v_lshl_add_u64 v[32:33], v[32:33], 0, v[148:149]
	v_lshl_add_u64 v[36:37], v[36:37], 0, v[148:149]
	s_mov_b64 s[46:47], s[38:39]
	v_fmamk_f32 v34, v34, 0x3a000000, v161
	v_rsq_f32_e32 v34, v34
	s_nop 0
	v_pk_mul_f32 v[28:29], v[28:29], v[34:35] op_sel_hi:[1,0]
	v_pk_mul_f32 v[24:25], v[24:25], v[34:35] op_sel_hi:[1,0]
	v_pk_mul_f32 v[22:23], v[22:23], v[34:35] op_sel_hi:[1,0]
	v_pk_mul_f32 v[20:21], v[20:21], v[34:35] op_sel_hi:[1,0]
	v_pk_mul_f32 v[30:31], v[30:31], v[34:35] op_sel_hi:[1,0]
	v_pk_mul_f32 v[26:27], v[26:27], v[34:35] op_sel_hi:[1,0]
	v_pk_mul_f32 v[18:19], v[18:19], v[34:35] op_sel_hi:[1,0]
	v_pk_mul_f32 v[16:17], v[16:17], v[34:35] op_sel_hi:[1,0]
	v_cvt_pk_bf16_f32 v28, v28, v29
	v_cvt_pk_bf16_f32 v29, v30, v31
	v_cvt_pk_bf16_f32 v24, v24, v25
	v_cvt_pk_bf16_f32 v25, v26, v27
	v_cvt_pk_bf16_f32 v20, v20, v21
	v_cvt_pk_bf16_f32 v21, v22, v23
	s_nop 0
	v_cvt_pk_bf16_f32 v22, v16, v17
	v_cvt_pk_bf16_f32 v23, v18, v19
	s_nop 0
	v_mov_b32_dpp v35, v28 row_ror:8 row_mask:0xf bank_mask:0xf
	v_mov_b32_dpp v38, v29 row_ror:8 row_mask:0xf bank_mask:0xf
	v_mov_b32_dpp v41, v20 row_ror:8 row_mask:0xf bank_mask:0xf
	v_mov_b32_dpp v42, v21 row_ror:8 row_mask:0xf bank_mask:0xf
	v_mov_b32_dpp v43, v22 row_ror:8 row_mask:0xf bank_mask:0xf
	v_mov_b32_dpp v44, v23 row_ror:8 row_mask:0xf bank_mask:0xf
	v_mov_b32_dpp v39, v24 row_ror:8 row_mask:0xf bank_mask:0xf
	v_mov_b32_dpp v40, v25 row_ror:8 row_mask:0xf bank_mask:0xf
	v_cndmask_b32_e64 v16, v41, v28, s[6:7]
	v_cndmask_b32_e64 v17, v42, v29, s[6:7]
	v_cndmask_b32_e64 v18, v43, v24, s[6:7]
	v_cndmask_b32_e64 v19, v44, v25, s[6:7]
	v_cndmask_b32_e64 v20, v20, v35, s[6:7]
	v_cndmask_b32_e64 v21, v21, v38, s[6:7]
	v_cndmask_b32_e64 v22, v22, v39, s[6:7]
	v_cndmask_b32_e64 v23, v23, v40, s[6:7]
	global_store_dwordx4 v[32:33], v[16:19], off
	global_store_dwordx4 v[36:37], v[20:23], off
	s_waitcnt vmcnt(14)
	s_nop 0
	v_mov_b32_e32 v18, v189
	s_nop 1
	v_mov_b32_e32 v19, 0
	v_add_u32_e32 v16, 0xb0, v77
	v_add_u32_e32 v20, 0xb8, v77
	v_mad_i64_i32 v[16:17], s[38:39], v16, s70, v[146:147]
	v_mad_i64_i32 v[20:21], s[38:39], v20, s70, v[146:147]
	v_lshl_add_u64 v[16:17], v[16:17], 0, v[148:149]
	v_lshl_add_u64 v[20:21], v[20:21], 0, v[148:149]
	v_fmamk_f32 v18, v18, 0x3a000000, v161
	v_rsq_f32_e32 v18, v18
	s_nop 0
	v_pk_mul_f32 v[12:13], v[12:13], v[18:19] op_sel_hi:[1,0]
	v_pk_mul_f32 v[8:9], v[8:9], v[18:19] op_sel_hi:[1,0]
	v_pk_mul_f32 v[6:7], v[6:7], v[18:19] op_sel_hi:[1,0]
	v_pk_mul_f32 v[4:5], v[4:5], v[18:19] op_sel_hi:[1,0]
	v_pk_mul_f32 v[14:15], v[14:15], v[18:19] op_sel_hi:[1,0]
	v_pk_mul_f32 v[10:11], v[10:11], v[18:19] op_sel_hi:[1,0]
	v_pk_mul_f32 v[2:3], v[2:3], v[18:19] op_sel_hi:[1,0]
	v_pk_mul_f32 v[0:1], v[0:1], v[18:19] op_sel_hi:[1,0]
	v_cvt_pk_bf16_f32 v12, v12, v13
	v_cvt_pk_bf16_f32 v13, v14, v15
	v_cvt_pk_bf16_f32 v8, v8, v9
	v_cvt_pk_bf16_f32 v9, v10, v11
	v_cvt_pk_bf16_f32 v4, v4, v5
	v_cvt_pk_bf16_f32 v5, v6, v7
	s_nop 0
	v_cvt_pk_bf16_f32 v6, v0, v1
	v_cvt_pk_bf16_f32 v7, v2, v3
	s_nop 0
	v_mov_b32_dpp v19, v12 row_ror:8 row_mask:0xf bank_mask:0xf
	v_mov_b32_dpp v22, v13 row_ror:8 row_mask:0xf bank_mask:0xf
	v_mov_b32_dpp v25, v4 row_ror:8 row_mask:0xf bank_mask:0xf
	v_mov_b32_dpp v26, v5 row_ror:8 row_mask:0xf bank_mask:0xf
	v_mov_b32_dpp v27, v6 row_ror:8 row_mask:0xf bank_mask:0xf
	v_mov_b32_dpp v28, v7 row_ror:8 row_mask:0xf bank_mask:0xf
	v_mov_b32_dpp v23, v8 row_ror:8 row_mask:0xf bank_mask:0xf
	v_mov_b32_dpp v24, v9 row_ror:8 row_mask:0xf bank_mask:0xf
	v_cndmask_b32_e64 v0, v25, v12, s[6:7]
	v_cndmask_b32_e64 v1, v26, v13, s[6:7]
	v_cndmask_b32_e64 v2, v27, v8, s[6:7]
	v_cndmask_b32_e64 v3, v28, v9, s[6:7]
	v_cndmask_b32_e64 v4, v4, v19, s[6:7]
	v_cndmask_b32_e64 v5, v5, v22, s[6:7]
	v_cndmask_b32_e64 v6, v6, v23, s[6:7]
	v_cndmask_b32_e64 v7, v7, v24, s[6:7]
	global_store_dwordx4 v[16:17], v[0:3], off
	global_store_dwordx4 v[20:21], v[4:7], off
	s_cbranch_vccz .LBB0_958
	s_waitcnt vmcnt(0)
	s_cmpk_gt_u32 s52, 0xff
	s_cbranch_scc1 .LBB0_966
	s_barrier

;     const bool lo = fr < 8;
;     const int r1 = row - fr + (fr & 7), cb = col0 + (lo ? 0 : boff);
;     const u32x4 l1 = *(const u32x4*)(P + (size_t)r1 * ld + cb), l2 = *(const u32x4*)(P + (size_t)(r1 + 8) * ld + cb);
; template <class Epi>
; __device__ __forceinline__ void gemm_phase(LAS unsigned char* lds, const Gemm g, const StaticOrder& S, const Epi& E) {
;     ...
; #pragma unroll
;         for (int a = 0; a < 2; ++a)
; #pragma unroll
;             for (int b = 0; b < 2; ++b)
; #pragma unroll
;                 for (int m = 0; m < 4; ++m)
; #pragma unroll
;                     for (int n = 0; n < 2; ++n) acc[a][b][m][n] = (f32x4){0.f, 0.f, 0.f, 0.f};
;         cur = nxt; cA = nA; cB = nB; ++ui;
.LBB0_1244:
	s_ashr_i32 s35, s34, 31
	s_xor_b64 s[38:39], s[50:51], -1
	s_lshl_b64 s[36:37], s[34:35], 20
	s_add_u32 s36, s53, s36
	s_addc_u32 s37, s54, s37
	s_and_b64 s[40:41], s[50:51], exec
	s_cselect_b32 s35, s37, s47
	s_cselect_b32 s43, s36, s46
	s_ashr_i32 s31, s30, 31
	s_lshl_b64 s[40:41], s[30:31], 20
	s_add_u32 s40, s55, s40
	s_addc_u32 s41, s56, s41
	s_and_b64 s[50:51], s[50:51], exec
	s_cselect_b32 s31, s41, s49
	s_cselect_b32 s70, s40, s48
	s_add_u32 s46, s46, 0x80080
	s_addc_u32 s47, s47, 0
	s_add_u32 s71, s48, 0x100
	v_mov_b32_e32 v0, 0
	s_addc_u32 s72, s49, 0
	s_mov_b32 s73, -2
	s_waitcnt lgkmcnt(0)
	v_mov_b32_e32 v1, v0
	v_mov_b32_e32 v2, v0
	v_mov_b32_e32 v3, v0
	v_mov_b32_e32 v4, v0
	v_mov_b32_e32 v5, v0
	v_mov_b32_e32 v6, v0
	v_mov_b32_e32 v7, v0
	v_mov_b32_e32 v16, v0
	v_mov_b32_e32 v17, v0
	v_mov_b32_e32 v18, v0
	v_mov_b32_e32 v19, v0
	s_waitcnt vmcnt(0)
	v_mov_b32_e32 v20, v0
	v_mov_b32_e32 v21, v0
	v_mov_b32_e32 v22, v0
	v_mov_b32_e32 v23, v0
	v_mov_b32_e32 v32, v0
	v_mov_b32_e32 v33, v0
	v_mov_b32_e32 v34, v0
	v_mov_b32_e32 v35, v0
	v_mov_b32_e32 v36, v0
	v_mov_b32_e32 v37, v0
	v_mov_b32_e32 v38, v0
	v_mov_b32_e32 v39, v0
	v_mov_b32_e32 v48, v0
	v_mov_b32_e32 v49, v0
	v_mov_b32_e32 v50, v0
	v_mov_b32_e32 v51, v0
	v_mov_b32_e32 v52, v0
	v_mov_b32_e32 v53, v0
	v_mov_b32_e32 v54, v0
	v_mov_b32_e32 v55, v0
	v_mov_b32_e32 v8, v0
	v_mov_b32_e32 v9, v0
	v_mov_b32_e32 v10, v0
	v_mov_b32_e32 v11, v0
	v_mov_b32_e32 v12, v0
	v_mov_b32_e32 v13, v0
	v_mov_b32_e32 v14, v0
	v_mov_b32_e32 v15, v0
	v_mov_b32_e32 v24, v0
	v_mov_b32_e32 v25, v0
	v_mov_b32_e32 v26, v0
	v_mov_b32_e32 v27, v0
	v_mov_b32_e32 v28, v0
	v_mov_b32_e32 v29, v0
	v_mov_b32_e32 v30, v0
	v_mov_b32_e32 v31, v0
	v_mov_b32_e32 v40, v0
	v_mov_b32_e32 v41, v0
	v_mov_b32_e32 v42, v0
	v_mov_b32_e32 v43, v0
	v_mov_b32_e32 v44, v0
	v_mov_b32_e32 v45, v0
	v_mov_b32_e32 v46, v0
	v_mov_b32_e32 v47, v0
	v_mov_b32_e32 v56, v0
	v_mov_b32_e32 v57, v0
	v_mov_b32_e32 v58, v0
	v_mov_b32_e32 v59, v0
	v_mov_b32_e32 v60, v0
	v_mov_b32_e32 v61, v0
	v_mov_b32_e32 v62, v0
	v_mov_b32_e32 v63, v0
	v_mov_b32_e32 v64, v0
	v_mov_b32_e32 v65, v0
	v_mov_b32_e32 v66, v0
	v_mov_b32_e32 v67, v0
	v_mov_b32_e32 v68, v0
	v_mov_b32_e32 v69, v0
	v_mov_b32_e32 v70, v0
	v_mov_b32_e32 v71, v0
	v_mov_b32_e32 v80, v0
	v_mov_b32_e32 v81, v0
	v_mov_b32_e32 v82, v0
	v_mov_b32_e32 v83, v0
	v_mov_b32_e32 v84, v0
	v_mov_b32_e32 v85, v0
	v_mov_b32_e32 v86, v0
	v_mov_b32_e32 v87, v0
	v_mov_b32_e32 v96, v0
	v_mov_b32_e32 v97, v0
	v_mov_b32_e32 v98, v0
	v_mov_b32_e32 v99, v0
	v_mov_b32_e32 v100, v0
	v_mov_b32_e32 v101, v0
	v_mov_b32_e32 v102, v0
	v_mov_b32_e32 v103, v0
	v_mov_b32_e32 v112, v0
	v_mov_b32_e32 v113, v0
	v_mov_b32_e32 v114, v0
	v_mov_b32_e32 v115, v0
	v_mov_b32_e32 v116, v0
	v_mov_b32_e32 v117, v0
	v_mov_b32_e32 v118, v0
	v_mov_b32_e32 v119, v0
	v_mov_b32_e32 v72, v0
	v_mov_b32_e32 v73, v0
	v_mov_b32_e32 v74, v0
	v_mov_b32_e32 v75, v0
	v_mov_b32_e32 v76, v0
	v_mov_b32_e32 v77, v0
	v_mov_b32_e32 v78, v0
	v_mov_b32_e32 v79, v0
	v_mov_b32_e32 v88, v0
	v_mov_b32_e32 v89, v0
	v_mov_b32_e32 v90, v0
	v_mov_b32_e32 v91, v0
	v_mov_b32_e32 v92, v0
	v_mov_b32_e32 v93, v0
	v_mov_b32_e32 v94, v0
	v_mov_b32_e32 v95, v0
	v_mov_b32_e32 v104, v0
	v_mov_b32_e32 v105, v0
	v_mov_b32_e32 v106, v0
	v_mov_b32_e32 v107, v0
	v_mov_b32_e32 v108, v0
	v_mov_b32_e32 v109, v0
	v_mov_b32_e32 v110, v0
	v_mov_b32_e32 v111, v0
	v_mov_b32_e32 v120, v0
	v_mov_b32_e32 v121, v0
	v_mov_b32_e32 v122, v0
	v_mov_b32_e32 v123, v0
	v_mov_b32_e32 v124, v0
	v_mov_b32_e32 v125, v0
	v_mov_b32_e32 v126, v0
	v_mov_b32_e32 v127, v0
	s_lshl_b32 s51, s44, 8
	s_add_i32 s51, s51, s64
	v_or_b32_e32 v148, s51, v152
	v_ashrrev_i32_e32 v149, 31, v148
	v_lshlrev_b64 v[160:161], 12, v[148:149]
	v_or_b32_e32 v148, 8, v148
	v_lshl_or_b32 v146, s42, 8, v153
	v_ashrrev_i32_e32 v149, 31, v148
	v_ashrrev_i32_e32 v147, 31, v146
	v_lshlrev_b64 v[162:163], 12, v[148:149]
	v_lshl_add_u64 v[158:159], s[10:11], 0, v[160:161]
	v_lshlrev_b64 v[146:147], 1, v[146:147]
	v_lshl_add_u64 v[148:149], s[10:11], 0, v[162:163]
	v_lshl_add_u64 v[158:159], v[158:159], 0, v[146:147]
	v_lshl_add_u64 v[148:149], v[148:149], 0, v[146:147]
	global_load_dwordx4 v[232:235], v[158:159], off
	global_load_dwordx4 v[236:239], v[148:149], off
; #define PG8_STAGE(bufoff, gbase, voff) do { _Pragma("unroll") for (int _i = 0; _i < 2; ++_i) \
;         __builtin_amdgcn_global_load_lds((const unsigned*)((const char*)(gbase) + (voff)[_i]), (LAS unsigned*)(lds + (bufoff) + ldsw + _i * 8192), 16, 0, 0); } while (0)
; #define PG8_LDA(dst, b, h) do { _Pragma("unroll") for (int m = 0; m < 4; ++m) _Pragma("unroll") for (int k = 0; k < 2; ++k) dst[m][k] = *(const LAS bf16x8*)(lds + PG8_SA(b, h) + aoff + m * 2048 + k * 1024); } while (0)
; #define PG8_LDB(dst, b, h) do { _Pragma("unroll") for (int n = 0; n < 2; ++n) _Pragma("unroll") for (int k = 0; k < 2; ++k) dst[n][k] = *(const LAS bf16x8*)(lds + PG8_SB(b, h) + boff + n * 2048 + k * 1024); } while (0)
; #define PG8_MMA(ai, bj, At, Bt) do { __builtin_amdgcn_s_setprio(1); _Pragma("unroll") for (int m = 0; m < 4; ++m) _Pragma("unroll") for (int n = 0; n < 2; ++n) _Pragma("unroll") for (int k = 0; k < 2; ++k) \
;         acc[ai][bj][m][n] = __builtin_amdgcn_mfma_f32_16x16x32_bf16(Bt[n][k], At[m][k], acc[ai][bj][m][n], 0, 0, 0); __builtin_amdgcn_s_setprio(0); } while (0)
; #define PG8_WAIT_L(n) asm volatile("s_waitcnt lgkmcnt(" #n ")" ::: "memory")
; #define PG8_BAR __builtin_amdgcn_s_barrier()
; #define PG8_SCHED __builtin_amdgcn_sched_barrier(0)
; template <class Epi>
; __device__ __forceinline__ void gemm_phase(LAS unsigned char* lds, const Gemm g, const StaticOrder& S, const Epi& E) {
;     ...
;         for (int t = 0; t < nt; t += 2) {
;             const bool last = (t == nt - 2);
;             const char* a1 = cA + (size_t)(t + 1) * kstep;
;             const char* a2 = last ? nA : cA + (size_t)(t + 2) * kstep; const char* b2 = last ? nB : cB + (size_t)(t + 2) * kstep;
;             const char* a3 = a2 + kstep; const char* b3 = b2 + kstep;
;             PG8_LDB(B0, 0, 0); PG8_SCHED; PG8_LDA(At, 0, 0); PG8_STAGE(PG8_SA(1, 1), a1 + hstep, voffA);
;             PG8_WAIT_L(8); PG8_BAR; PG8_WAIT_L(0); PG8_MMA(0, 0, At, B0); PG8_BAR; PG8_SCHED;
;             PG8_LDB(B1, 0, 1); PG8_STAGE(PG8_SB(0, 0), b2, voffB0);
;             PG8_BAR; PG8_WAIT_L(0); PG8_MMA(0, 1, At, B1); PG8_BAR;
;             PG8_LDA(At, 0, 1); PG8_STAGE(PG8_SA(0, 0), a2, voffA);
;             PG8_BAR; PG8_WAIT_L(0); PG8_MMA(1, 0, At, B0); PG8_BAR; PG8_SCHED;
.LBB0_1245:
	ds_read_b128 v[146:149], v154
	ds_read_b128 v[158:161], v154 offset:1024
	ds_read_b128 v[162:165], v154 offset:2048
	ds_read_b128 v[166:169], v154 offset:3072
	s_add_u32 s33, s46, 0xfff80080
	s_addc_u32 s48, s47, -1
	s_cmp_eq_u32 s73, 28
	s_cselect_b32 s49, s35, s48
	s_cselect_b32 s48, s43, s33
	s_cselect_b32 s51, s31, s72
	s_cselect_b32 s50, s70, s71
	v_lshl_add_u64 v[204:205], s[46:47], 0, v[140:141]
	s_add_i32 m0, s45, 0xc000
	ds_read_b128 v[170:173], v155
	ds_read_b128 v[174:177], v155 offset:1024
	ds_read_b128 v[178:181], v155 offset:2048
	ds_read_b128 v[182:185], v155 offset:3072
	ds_read_b128 v[186:189], v155 offset:4096
	ds_read_b128 v[190:193], v155 offset:5120
	ds_read_b128 v[194:197], v155 offset:6144
	ds_read_b128 v[198:201], v155 offset:7168
	global_load_lds_dwordx4 v[204:205], off
	v_lshl_add_u64 v[204:205], s[46:47], 0, v[142:143]
	s_add_i32 m0, s45, 0xe000
	s_nop 0
	global_load_lds_dwordx4 v[204:205], off
	s_waitcnt lgkmcnt(8)
	s_barrier
	s_waitcnt lgkmcnt(0)
	v_mfma_f32_16x16x32_bf16 v[124:127], v[146:149], v[170:173], v[124:127]
	v_mfma_f32_16x16x32_bf16 v[120:123], v[162:165], v[170:173], v[120:123]
	v_mfma_f32_16x16x32_bf16 v[108:111], v[146:149], v[178:181], v[108:111]
	v_mfma_f32_16x16x32_bf16 v[104:107], v[162:165], v[178:181], v[104:107]
	v_mfma_f32_16x16x32_bf16 v[92:95], v[146:149], v[186:189], v[92:95]
	v_mfma_f32_16x16x32_bf16 v[88:91], v[162:165], v[186:189], v[88:91]
	v_mfma_f32_16x16x32_bf16 v[76:79], v[146:149], v[194:197], v[76:79]
	v_mfma_f32_16x16x32_bf16 v[72:75], v[162:165], v[194:197], v[72:75]
	v_mfma_f32_16x16x32_bf16 v[124:127], v[158:161], v[174:177], v[124:127]
	v_mfma_f32_16x16x32_bf16 v[120:123], v[166:169], v[174:177], v[120:123]
	v_mfma_f32_16x16x32_bf16 v[108:111], v[158:161], v[182:185], v[108:111]
	v_mfma_f32_16x16x32_bf16 v[104:107], v[166:169], v[182:185], v[104:107]
	v_mfma_f32_16x16x32_bf16 v[92:95], v[158:161], v[190:193], v[92:95]
	v_mfma_f32_16x16x32_bf16 v[88:91], v[166:169], v[190:193], v[88:91]
	v_mfma_f32_16x16x32_bf16 v[76:79], v[158:161], v[198:201], v[76:79]
	v_mfma_f32_16x16x32_bf16 v[72:75], v[166:169], v[198:201], v[72:75]
	s_barrier
	s_add_i32 s33, s68, s57
	v_lshl_add_u64 v[220:221], s[50:51], 0, v[130:131]
	s_mov_b32 m0, s33
	ds_read_b128 v[204:207], v156
	ds_read_b128 v[208:211], v156 offset:1024
	ds_read_b128 v[212:215], v156 offset:2048
	ds_read_b128 v[216:219], v156 offset:3072
	global_load_lds_dwordx4 v[220:221], off
	v_lshl_add_u64 v[222:223], s[50:51], 0, v[136:137]
	s_add_i32 m0, s33, 0x2000
	s_nop 0
	global_load_lds_dwordx4 v[222:223], off
	s_barrier
	s_waitcnt lgkmcnt(0)
	v_mfma_f32_16x16x32_bf16 v[116:119], v[204:207], v[170:173], v[116:119]
	v_mfma_f32_16x16x32_bf16 v[112:115], v[212:215], v[170:173], v[112:115]
	v_mfma_f32_16x16x32_bf16 v[100:103], v[204:207], v[178:181], v[100:103]
	v_mfma_f32_16x16x32_bf16 v[96:99], v[212:215], v[178:181], v[96:99]
	v_mfma_f32_16x16x32_bf16 v[84:87], v[204:207], v[186:189], v[84:87]
	v_mfma_f32_16x16x32_bf16 v[80:83], v[212:215], v[186:189], v[80:83]
	v_mfma_f32_16x16x32_bf16 v[68:71], v[204:207], v[194:197], v[68:71]
	v_mfma_f32_16x16x32_bf16 v[64:67], v[212:215], v[194:197], v[64:67]
	v_mfma_f32_16x16x32_bf16 v[116:119], v[208:211], v[174:177], v[116:119]
	v_mfma_f32_16x16x32_bf16 v[112:115], v[216:219], v[174:177], v[112:115]
	v_mfma_f32_16x16x32_bf16 v[100:103], v[208:211], v[182:185], v[100:103]
	v_mfma_f32_16x16x32_bf16 v[96:99], v[216:219], v[182:185], v[96:99]
	v_mfma_f32_16x16x32_bf16 v[84:87], v[208:211], v[190:193], v[84:87]
	v_mfma_f32_16x16x32_bf16 v[80:83], v[216:219], v[190:193], v[80:83]
	v_mfma_f32_16x16x32_bf16 v[68:71], v[208:211], v[198:201], v[68:71]
	v_mfma_f32_16x16x32_bf16 v[64:67], v[216:219], v[198:201], v[64:67]
	s_mov_b32 m0, s45
	v_lshl_add_u64 v[224:225], s[48:49], 0, v[128:129]
	s_barrier
	ds_read_b128 v[170:173], v155 offset:16384
	ds_read_b128 v[174:177], v155 offset:17408
	ds_read_b128 v[178:181], v155 offset:18432
	ds_read_b128 v[182:185], v155 offset:19456
	ds_read_b128 v[186:189], v155 offset:20480
	ds_read_b128 v[190:193], v155 offset:21504
	ds_read_b128 v[194:197], v155 offset:22528
	ds_read_b128 v[198:201], v155 offset:23552
	global_load_lds_dwordx4 v[224:225], off
	v_lshl_add_u64 v[226:227], s[48:49], 0, v[134:135]
	s_mov_b32 m0, s58
	s_nop 0
	global_load_lds_dwordx4 v[226:227], off
	s_barrier
	s_waitcnt lgkmcnt(0)
	v_mfma_f32_16x16x32_bf16 v[60:63], v[146:149], v[170:173], v[60:63]
	v_mfma_f32_16x16x32_bf16 v[56:59], v[162:165], v[170:173], v[56:59]
	v_mfma_f32_16x16x32_bf16 v[44:47], v[146:149], v[178:181], v[44:47]
	v_mfma_f32_16x16x32_bf16 v[40:43], v[162:165], v[178:181], v[40:43]
	v_mfma_f32_16x16x32_bf16 v[28:31], v[146:149], v[186:189], v[28:31]
	v_mfma_f32_16x16x32_bf16 v[24:27], v[162:165], v[186:189], v[24:27]
	v_mfma_f32_16x16x32_bf16 v[12:15], v[146:149], v[194:197], v[12:15]
	v_mfma_f32_16x16x32_bf16 v[8:11], v[162:165], v[194:197], v[8:11]
	v_mfma_f32_16x16x32_bf16 v[60:63], v[158:161], v[174:177], v[60:63]
	v_mfma_f32_16x16x32_bf16 v[56:59], v[166:169], v[174:177], v[56:59]
	v_mfma_f32_16x16x32_bf16 v[44:47], v[158:161], v[182:185], v[44:47]
	v_mfma_f32_16x16x32_bf16 v[40:43], v[166:169], v[182:185], v[40:43]
	v_mfma_f32_16x16x32_bf16 v[28:31], v[158:161], v[190:193], v[28:31]
	v_mfma_f32_16x16x32_bf16 v[24:27], v[166:169], v[190:193], v[24:27]
	v_mfma_f32_16x16x32_bf16 v[12:15], v[158:161], v[198:201], v[12:15]
	v_mfma_f32_16x16x32_bf16 v[8:11], v[166:169], v[198:201], v[8:11]
	s_barrier
; #define PG8_STAGE(bufoff, gbase, voff) do { _Pragma("unroll") for (int _i = 0; _i < 2; ++_i) \
;         __builtin_amdgcn_global_load_lds((const unsigned*)((const char*)(gbase) + (voff)[_i]), (LAS unsigned*)(lds + (bufoff) + ldsw + _i * 8192), 16, 0, 0); } while (0)
; #define PG8_LDA(dst, b, h) do { _Pragma("unroll") for (int m = 0; m < 4; ++m) _Pragma("unroll") for (int k = 0; k < 2; ++k) dst[m][k] = *(const LAS bf16x8*)(lds + PG8_SA(b, h) + aoff + m * 2048 + k * 1024); } while (0)
; #define PG8_LDB(dst, b, h) do { _Pragma("unroll") for (int n = 0; n < 2; ++n) _Pragma("unroll") for (int k = 0; k < 2; ++k) dst[n][k] = *(const LAS bf16x8*)(lds + PG8_SB(b, h) + boff + n * 2048 + k * 1024); } while (0)
; #define PG8_MMA(ai, bj, At, Bt) do { __builtin_amdgcn_s_setprio(1); _Pragma("unroll") for (int m = 0; m < 4; ++m) _Pragma("unroll") for (int n = 0; n < 2; ++n) _Pragma("unroll") for (int k = 0; k < 2; ++k) \
;         acc[ai][bj][m][n] = __builtin_amdgcn_mfma_f32_16x16x32_bf16(Bt[n][k], At[m][k], acc[ai][bj][m][n], 0, 0, 0); __builtin_amdgcn_s_setprio(0); } while (0)
; #define PG8_WAIT_V(n) asm volatile("s_waitcnt vmcnt(" #n ")" ::: "memory")
; #define PG8_WAIT_L(n) asm volatile("s_waitcnt lgkmcnt(" #n ")" ::: "memory")
; #define PG8_BAR __builtin_amdgcn_s_barrier()
; #define PG8_SCHED __builtin_amdgcn_sched_barrier(0)
; template <class Epi>
; __device__ __forceinline__ void gemm_phase(LAS unsigned char* lds, const Gemm g, const StaticOrder& S, const Epi& E) {
;     ...
;             PG8_STAGE(PG8_SB(0, 1), b2, voffB1);
;             PG8_WAIT_V(6); PG8_BAR; PG8_MMA(1, 1, At, B1); PG8_BAR;
;             PG8_LDB(B0, 1, 0); PG8_SCHED; PG8_LDA(At, 1, 0); PG8_STAGE(PG8_SA(0, 1), a2 + hstep, voffA);
;             PG8_WAIT_L(8); PG8_BAR; PG8_WAIT_L(0); PG8_MMA(0, 0, At, B0); PG8_BAR; PG8_SCHED;
;             PG8_LDB(B1, 1, 1); PG8_STAGE(PG8_SB(1, 0), b3, voffB0);
;             PG8_BAR; PG8_WAIT_L(0); PG8_MMA(0, 1, At, B1); PG8_BAR;
;             PG8_LDA(At, 1, 1); PG8_STAGE(PG8_SA(1, 0), a3, voffA);
;             PG8_BAR; PG8_WAIT_L(0); PG8_MMA(1, 0, At, B0); PG8_BAR; PG8_SCHED;
	s_add_i32 s33, s69, s57
	v_lshl_add_u64 v[228:229], s[50:51], 0, v[132:133]
	s_mov_b32 m0, s33
	v_lshl_add_u64 v[230:231], s[50:51], 0, v[138:139]
	global_load_lds_dwordx4 v[228:229], off
	s_add_i32 m0, s33, 0x2000
	s_nop 0
	global_load_lds_dwordx4 v[230:231], off
	s_add_i32 s33, 0, 0x18000
	v_add_u32_e32 v157, s33, v151
	ds_read_b128 v[146:149], v157
	ds_read_b128 v[158:161], v157 offset:1024
	ds_read_b128 v[162:165], v157 offset:2048
	ds_read_b128 v[166:169], v157 offset:3072
	s_waitcnt vmcnt(6)
	s_barrier
	v_mfma_f32_16x16x32_bf16 v[52:55], v[204:207], v[170:173], v[52:55]
	v_mfma_f32_16x16x32_bf16 v[48:51], v[212:215], v[170:173], v[48:51]
	v_mfma_f32_16x16x32_bf16 v[36:39], v[204:207], v[178:181], v[36:39]
	v_mfma_f32_16x16x32_bf16 v[32:35], v[212:215], v[178:181], v[32:35]
	v_mfma_f32_16x16x32_bf16 v[20:23], v[204:207], v[186:189], v[20:23]
	v_mfma_f32_16x16x32_bf16 v[16:19], v[212:215], v[186:189], v[16:19]
	v_mfma_f32_16x16x32_bf16 v[4:7], v[204:207], v[194:197], v[4:7]
	v_mfma_f32_16x16x32_bf16 v[0:3], v[212:215], v[194:197], v[0:3]
	v_mfma_f32_16x16x32_bf16 v[52:55], v[208:211], v[174:177], v[52:55]
	v_mfma_f32_16x16x32_bf16 v[48:51], v[216:219], v[174:177], v[48:51]
	v_mfma_f32_16x16x32_bf16 v[36:39], v[208:211], v[182:185], v[36:39]
	v_mfma_f32_16x16x32_bf16 v[32:35], v[216:219], v[182:185], v[32:35]
	v_mfma_f32_16x16x32_bf16 v[20:23], v[208:211], v[190:193], v[20:23]
	v_mfma_f32_16x16x32_bf16 v[16:19], v[216:219], v[190:193], v[16:19]
	v_mfma_f32_16x16x32_bf16 v[4:7], v[208:211], v[198:201], v[4:7]
	v_mfma_f32_16x16x32_bf16 v[0:3], v[216:219], v[198:201], v[0:3]
	s_barrier
	s_add_u32 s48, s48, 0x80000
	s_addc_u32 s49, s49, 0
	s_mov_b32 m0, s59
	v_lshl_add_u64 v[204:205], s[48:49], 0, v[128:129]
	ds_read_b128 v[170:173], v155 offset:32768
	ds_read_b128 v[174:177], v155 offset:33792
	ds_read_b128 v[178:181], v155 offset:34816
	ds_read_b128 v[182:185], v155 offset:35840
	ds_read_b128 v[186:189], v155 offset:36864
	ds_read_b128 v[190:193], v155 offset:37888
	ds_read_b128 v[194:197], v155 offset:38912
	ds_read_b128 v[198:201], v155 offset:39936
	global_load_lds_dwordx4 v[204:205], off
	v_lshl_add_u64 v[204:205], s[48:49], 0, v[134:135]
	s_mov_b32 m0, s60
	s_nop 0
	global_load_lds_dwordx4 v[204:205], off
	s_waitcnt lgkmcnt(8)
	s_barrier
	s_waitcnt lgkmcnt(0)
	v_mfma_f32_16x16x32_bf16 v[124:127], v[146:149], v[170:173], v[124:127]
	v_mfma_f32_16x16x32_bf16 v[120:123], v[162:165], v[170:173], v[120:123]
	v_mfma_f32_16x16x32_bf16 v[108:111], v[146:149], v[178:181], v[108:111]
	v_mfma_f32_16x16x32_bf16 v[104:107], v[162:165], v[178:181], v[104:107]
	v_mfma_f32_16x16x32_bf16 v[92:95], v[146:149], v[186:189], v[92:95]
	v_mfma_f32_16x16x32_bf16 v[88:91], v[162:165], v[186:189], v[88:91]
	v_mfma_f32_16x16x32_bf16 v[76:79], v[146:149], v[194:197], v[76:79]
	v_mfma_f32_16x16x32_bf16 v[72:75], v[162:165], v[194:197], v[72:75]
	v_mfma_f32_16x16x32_bf16 v[124:127], v[158:161], v[174:177], v[124:127]
	v_mfma_f32_16x16x32_bf16 v[120:123], v[166:169], v[174:177], v[120:123]
	v_mfma_f32_16x16x32_bf16 v[108:111], v[158:161], v[182:185], v[108:111]
	v_mfma_f32_16x16x32_bf16 v[104:107], v[166:169], v[182:185], v[104:107]
	v_mfma_f32_16x16x32_bf16 v[92:95], v[158:161], v[190:193], v[92:95]
	v_mfma_f32_16x16x32_bf16 v[88:91], v[166:169], v[190:193], v[88:91]
	v_mfma_f32_16x16x32_bf16 v[76:79], v[158:161], v[198:201], v[76:79]
	v_mfma_f32_16x16x32_bf16 v[72:75], v[166:169], v[198:201], v[72:75]
	s_barrier
	s_add_i32 s48, 0, 0x1c000
	s_add_i32 s33, s33, s57
	v_add_u32_e32 v157, s48, v151
	v_lshl_add_u64 v[220:221], v[220:221], 0, s[26:27]
	s_mov_b32 m0, s33
	ds_read_b128 v[204:207], v157
	ds_read_b128 v[208:211], v157 offset:1024
	ds_read_b128 v[212:215], v157 offset:2048
	ds_read_b128 v[216:219], v157 offset:3072
	global_load_lds_dwordx4 v[220:221], off
	v_lshl_add_u64 v[220:221], v[222:223], 0, s[26:27]
	s_add_i32 m0, s33, 0x2000
	s_nop 0
	global_load_lds_dwordx4 v[220:221], off
	s_barrier
	s_waitcnt lgkmcnt(0)
	v_mfma_f32_16x16x32_bf16 v[116:119], v[204:207], v[170:173], v[116:119]
	v_mfma_f32_16x16x32_bf16 v[112:115], v[212:215], v[170:173], v[112:115]
	v_mfma_f32_16x16x32_bf16 v[100:103], v[204:207], v[178:181], v[100:103]
	v_mfma_f32_16x16x32_bf16 v[96:99], v[212:215], v[178:181], v[96:99]
	v_mfma_f32_16x16x32_bf16 v[84:87], v[204:207], v[186:189], v[84:87]
	v_mfma_f32_16x16x32_bf16 v[80:83], v[212:215], v[186:189], v[80:83]
	v_mfma_f32_16x16x32_bf16 v[68:71], v[204:207], v[194:197], v[68:71]
	v_mfma_f32_16x16x32_bf16 v[64:67], v[212:215], v[194:197], v[64:67]
	v_mfma_f32_16x16x32_bf16 v[116:119], v[208:211], v[174:177], v[116:119]
	v_mfma_f32_16x16x32_bf16 v[112:115], v[216:219], v[174:177], v[112:115]
	v_mfma_f32_16x16x32_bf16 v[100:103], v[208:211], v[182:185], v[100:103]
	v_mfma_f32_16x16x32_bf16 v[96:99], v[216:219], v[182:185], v[96:99]
	v_mfma_f32_16x16x32_bf16 v[84:87], v[208:211], v[190:193], v[84:87]
	v_mfma_f32_16x16x32_bf16 v[80:83], v[216:219], v[190:193], v[80:83]
	v_mfma_f32_16x16x32_bf16 v[68:71], v[208:211], v[198:201], v[68:71]
	v_mfma_f32_16x16x32_bf16 v[64:67], v[216:219], v[198:201], v[64:67]
	s_mov_b32 m0, s62
	v_lshl_add_u64 v[220:221], v[224:225], 0, s[26:27]
	s_barrier
	ds_read_b128 v[170:173], v155 offset:49152
	ds_read_b128 v[174:177], v155 offset:50176
	ds_read_b128 v[178:181], v155 offset:51200
	ds_read_b128 v[182:185], v155 offset:52224
	ds_read_b128 v[186:189], v155 offset:53248
	ds_read_b128 v[190:193], v155 offset:54272
	ds_read_b128 v[194:197], v155 offset:55296
	ds_read_b128 v[198:201], v155 offset:56320
	global_load_lds_dwordx4 v[220:221], off
	v_lshl_add_u64 v[220:221], v[226:227], 0, s[26:27]
	s_mov_b32 m0, s63
	s_nop 0
	global_load_lds_dwordx4 v[220:221], off
	s_barrier
; __device__ __forceinline__ unsigned dpp_ror8(unsigned x) { return (unsigned)__builtin_amdgcn_update_dpp(0, (int)x, 0x128, 0xf, 0xf, false); }
; #define PG8_STAGE(bufoff, gbase, voff) do { _Pragma("unroll") for (int _i = 0; _i < 2; ++_i) \
;         __builtin_amdgcn_global_load_lds((const unsigned*)((const char*)(gbase) + (voff)[_i]), (LAS unsigned*)(lds + (bufoff) + ldsw + _i * 8192), 16, 0, 0); } while (0)
; #define PG8_LDA(dst, b, h) do { _Pragma("unroll") for (int m = 0; m < 4; ++m) _Pragma("unroll") for (int k = 0; k < 2; ++k) dst[m][k] = *(const LAS bf16x8*)(lds + PG8_SA(b, h) + aoff + m * 2048 + k * 1024); } while (0)
; #define PG8_MMA(ai, bj, At, Bt) do { __builtin_amdgcn_s_setprio(1); _Pragma("unroll") for (int m = 0; m < 4; ++m) _Pragma("unroll") for (int n = 0; n < 2; ++n) _Pragma("unroll") for (int k = 0; k < 2; ++k) \
;         acc[ai][bj][m][n] = __builtin_amdgcn_mfma_f32_16x16x32_bf16(Bt[n][k], At[m][k], acc[ai][bj][m][n], 0, 0, 0); __builtin_amdgcn_s_setprio(0); } while (0)
; #define PG8_WAIT_V(n) asm volatile("s_waitcnt vmcnt(" #n ")" ::: "memory")
; #define PG8_WAIT_L(n) asm volatile("s_waitcnt lgkmcnt(" #n ")" ::: "memory")
; #define PG8_BAR __builtin_amdgcn_s_barrier()
; #define PG8_SCHED __builtin_amdgcn_sched_barrier(0)
;     const bool lo = fr < 8;
;     const int r1 = row - fr + (fr & 7), cb = col0 + (lo ? 0 : boff);
;     const u32x4 l1 = *(const u32x4*)(P + (size_t)r1 * ld + cb), l2 = *(const u32x4*)(P + (size_t)(r1 + 8) * ld + cb);
;     const u32x4 s1 = {dpp_ror8(l1.x), dpp_ror8(l1.y), dpp_ror8(l1.z), dpp_ror8(l1.w)}, s2 = {dpp_ror8(l2.x), dpp_ror8(l2.y), dpp_ror8(l2.z), dpp_ror8(l2.w)};
;     wA = lo ? l1 : s2; wB = lo ? s1 : l2;
; }
; template <class Epi>
; __device__ __forceinline__ void gemm_phase(LAS unsigned char* lds, const Gemm g, const StaticOrder& S, const Epi& E) {
;     ...
;             PG8_BAR; PG8_WAIT_L(0); PG8_MMA(0, 1, At, B1); PG8_BAR;
;             PG8_LDA(At, 1, 1); PG8_STAGE(PG8_SA(1, 0), a3, voffA);
;             PG8_BAR; PG8_WAIT_L(0); PG8_MMA(1, 0, At, B0); PG8_BAR; PG8_SCHED;
;             PG8_STAGE(PG8_SB(1, 1), b3, voffB1);
;             PG8_WAIT_V(6); PG8_BAR; PG8_MMA(1, 1, At, B1); PG8_BAR;
;         }
;         E(acc, cur, wr, wc, fr, fq);
	s_waitcnt lgkmcnt(0)
	v_mfma_f32_16x16x32_bf16 v[60:63], v[146:149], v[170:173], v[60:63]
	v_mfma_f32_16x16x32_bf16 v[56:59], v[162:165], v[170:173], v[56:59]
	v_mfma_f32_16x16x32_bf16 v[44:47], v[146:149], v[178:181], v[44:47]
	v_mfma_f32_16x16x32_bf16 v[40:43], v[162:165], v[178:181], v[40:43]
	v_mfma_f32_16x16x32_bf16 v[28:31], v[146:149], v[186:189], v[28:31]
	v_mfma_f32_16x16x32_bf16 v[24:27], v[162:165], v[186:189], v[24:27]
	v_mfma_f32_16x16x32_bf16 v[12:15], v[146:149], v[194:197], v[12:15]
	v_mfma_f32_16x16x32_bf16 v[8:11], v[162:165], v[194:197], v[8:11]
	v_mfma_f32_16x16x32_bf16 v[60:63], v[158:161], v[174:177], v[60:63]
	v_mfma_f32_16x16x32_bf16 v[56:59], v[166:169], v[174:177], v[56:59]
	v_mfma_f32_16x16x32_bf16 v[44:47], v[158:161], v[182:185], v[44:47]
	v_mfma_f32_16x16x32_bf16 v[40:43], v[166:169], v[182:185], v[40:43]
	v_mfma_f32_16x16x32_bf16 v[28:31], v[158:161], v[190:193], v[28:31]
	v_mfma_f32_16x16x32_bf16 v[24:27], v[166:169], v[190:193], v[24:27]
	v_mfma_f32_16x16x32_bf16 v[12:15], v[158:161], v[198:201], v[12:15]
	v_mfma_f32_16x16x32_bf16 v[8:11], v[166:169], v[198:201], v[8:11]
	s_barrier
	s_add_i32 s33, s48, s57
	v_lshl_add_u64 v[146:147], v[228:229], 0, s[26:27]
	s_mov_b32 m0, s33
	s_nop 0
	global_load_lds_dwordx4 v[146:147], off
	v_lshl_add_u64 v[146:147], v[230:231], 0, s[26:27]
	s_add_i32 m0, s33, 0x2000
	s_nop 0
	global_load_lds_dwordx4 v[146:147], off
	s_waitcnt vmcnt(6)
	s_barrier
	v_mfma_f32_16x16x32_bf16 v[52:55], v[204:207], v[170:173], v[52:55]
	v_mfma_f32_16x16x32_bf16 v[48:51], v[212:215], v[170:173], v[48:51]
	v_mfma_f32_16x16x32_bf16 v[36:39], v[204:207], v[178:181], v[36:39]
	v_mfma_f32_16x16x32_bf16 v[32:35], v[212:215], v[178:181], v[32:35]
	v_mfma_f32_16x16x32_bf16 v[20:23], v[204:207], v[186:189], v[20:23]
	v_mfma_f32_16x16x32_bf16 v[16:19], v[212:215], v[186:189], v[16:19]
	v_mfma_f32_16x16x32_bf16 v[4:7], v[204:207], v[194:197], v[4:7]
	v_mfma_f32_16x16x32_bf16 v[0:3], v[212:215], v[194:197], v[0:3]
	v_mfma_f32_16x16x32_bf16 v[52:55], v[208:211], v[174:177], v[52:55]
	v_mfma_f32_16x16x32_bf16 v[48:51], v[216:219], v[174:177], v[48:51]
	v_mfma_f32_16x16x32_bf16 v[36:39], v[208:211], v[182:185], v[36:39]
	v_mfma_f32_16x16x32_bf16 v[32:35], v[216:219], v[182:185], v[32:35]
	v_mfma_f32_16x16x32_bf16 v[20:23], v[208:211], v[190:193], v[20:23]
	v_mfma_f32_16x16x32_bf16 v[16:19], v[216:219], v[190:193], v[16:19]
	v_mfma_f32_16x16x32_bf16 v[4:7], v[208:211], v[198:201], v[4:7]
	v_mfma_f32_16x16x32_bf16 v[0:3], v[216:219], v[198:201], v[0:3]
	s_add_i32 s73, s73, 2
	s_add_u32 s46, s46, 0x100
	s_addc_u32 s47, s47, 0
	s_add_u32 s71, s71, 0x100
	s_addc_u32 s72, s72, 0
	s_cmp_gt_u32 s73, 29
	s_barrier
	s_cbranch_scc0 .LBB0_1245
	s_lshl_b32 s31, s44, 8
	s_add_i32 s31, s31, s64
	v_or_b32_e32 v148, s31, v152
	v_ashrrev_i32_e32 v149, 31, v148
	v_lshlrev_b64 v[166:167], 12, v[148:149]
	v_or_b32_e32 v148, 8, v148
	v_lshl_or_b32 v146, s42, 8, v153
	v_ashrrev_i32_e32 v149, 31, v148
	v_ashrrev_i32_e32 v147, 31, v146
	v_lshlrev_b64 v[168:169], 12, v[148:149]
	v_lshl_add_u64 v[158:159], s[10:11], 0, v[166:167]
	v_lshlrev_b64 v[146:147], 1, v[146:147]
	v_lshl_add_u64 v[148:149], s[10:11], 0, v[168:169]
	v_lshl_add_u64 v[158:159], v[158:159], 0, v[146:147]
	v_lshl_add_u64 v[148:149], v[148:149], 0, v[146:147]
	s_waitcnt vmcnt(8)
	s_nop 0
	v_mov_b64_e32 v[158:159], v[232:233]
	v_mov_b64_e32 v[160:161], v[234:235]
	s_nop 1
	s_nop 0
	v_mov_b64_e32 v[162:163], v[236:237]
	v_mov_b64_e32 v[164:165], v[238:239]
	s_nop 1
	v_or_b32_e32 v194, s31, v150
	v_or_b32_e32 v184, 16, v194
	v_sub_u32_e32 v185, v184, v150
	v_add_u32_e32 v186, v185, v152
	v_ashrrev_i32_e32 v187, 31, v186
	v_lshlrev_b64 v[190:191], 12, v[186:187]
	v_lshl_add_u64 v[192:193], v[190:191], 0, s[28:29]
	v_lshl_add_u64 v[186:187], s[10:11], 0, v[190:191]
	v_lshl_add_u64 v[188:189], s[10:11], 0, v[192:193]
	v_lshl_add_u64 v[186:187], v[186:187], 0, v[146:147]
	v_lshl_add_u64 v[188:189], v[188:189], 0, v[146:147]
	global_load_dwordx4 v[196:199], v[186:187], off
	global_load_dwordx4 v[204:207], v[188:189], off
	v_or_b32_e32 v194, s31, v150
	v_or_b32_e32 v184, 32, v194
	v_sub_u32_e32 v185, v184, v150
	v_add_u32_e32 v186, v185, v152
	v_ashrrev_i32_e32 v187, 31, v186
	v_lshlrev_b64 v[190:191], 12, v[186:187]
	v_lshl_add_u64 v[192:193], v[190:191], 0, s[28:29]
	v_lshl_add_u64 v[186:187], s[10:11], 0, v[190:191]
	v_lshl_add_u64 v[188:189], s[10:11], 0, v[192:193]
	v_lshl_add_u64 v[186:187], v[186:187], 0, v[146:147]
	v_lshl_add_u64 v[188:189], v[188:189], 0, v[146:147]
	global_load_dwordx4 v[208:211], v[186:187], off
	global_load_dwordx4 v[212:215], v[188:189], off
	v_or_b32_e32 v194, s31, v150
	v_or_b32_e32 v184, 48, v194
	v_sub_u32_e32 v185, v184, v150
	v_add_u32_e32 v186, v185, v152
	v_ashrrev_i32_e32 v187, 31, v186
	v_lshlrev_b64 v[190:191], 12, v[186:187]
	v_lshl_add_u64 v[192:193], v[190:191], 0, s[28:29]
	v_lshl_add_u64 v[186:187], s[10:11], 0, v[190:191]
	v_lshl_add_u64 v[188:189], s[10:11], 0, v[192:193]
	v_lshl_add_u64 v[186:187], v[186:187], 0, v[146:147]
	v_lshl_add_u64 v[188:189], v[188:189], 0, v[146:147]
	global_load_dwordx4 v[216:219], v[186:187], off
	global_load_dwordx4 v[220:223], v[188:189], off
	v_or_b32_e32 v194, s31, v150
	v_add_u32_e32 v184, 0x80, v194
	v_sub_u32_e32 v185, v184, v150
	v_add_u32_e32 v186, v185, v152
	v_ashrrev_i32_e32 v187, 31, v186
	v_lshlrev_b64 v[190:191], 12, v[186:187]
	v_lshl_add_u64 v[192:193], v[190:191], 0, s[28:29]
	v_lshl_add_u64 v[186:187], s[10:11], 0, v[190:191]
	v_lshl_add_u64 v[188:189], s[10:11], 0, v[192:193]
	v_lshl_add_u64 v[186:187], v[186:187], 0, v[146:147]
	v_lshl_add_u64 v[188:189], v[188:189], 0, v[146:147]
; __device__ __forceinline__ void store_pair_lines(bf16_t* O, int ldc, int row, int fr, int col0, u32x4 wA, u32x4 wB) {
;     const u32x4 sA = {dpp_ror8(wA.x), dpp_ror8(wA.y), dpp_ror8(wA.z), dpp_ror8(wA.w)}, sB = {dpp_ror8(wB.x), dpp_ror8(wB.y), dpp_ror8(wB.z), dpp_ror8(wB.w)};
;     const bool lo = fr < 8;
;     const u32x4 o1 = lo ? wA : sB, o2 = lo ? sA : wB;
;     const int r1 = row - fr + (fr & 7), cb = col0 + (lo ? 0 : 8);
;     *(u32x4*)(O + (size_t)r1 * ldc + cb) = o1;
;     *(u32x4*)(O + (size_t)(r1 + 8) * ldc + cb) = o2;
; }
;     const bool lo = fr < 8;
;     const int r1 = row - fr + (fr & 7), cb = col0 + (lo ? 0 : boff);
;     const u32x4 l1 = *(const u32x4*)(P + (size_t)r1 * ld + cb), l2 = *(const u32x4*)(P + (size_t)(r1 + 8) * ld + cb);
;     __device__ __forceinline__ void operator()(const f32x4 (&acc)[2][2][4][2], const Unit& u, int wr, int wc, int fr, int fq) const {
;     ...
;             for (int m = 0; m < 4; ++m) { const int row = row0 + ai * HALF + m * 16; const size_t off = (size_t)row * D + col0; float sq = 0.f; u32x4 w[2];
;                 const float sc = rsin ? __builtin_amdgcn_rcpf(rsin[row] * (1.f / D) + EPS) : 1.0f;
;                 u32x4 rr[2]; if (R) load_pair_lines(R, D, row, fr, col0, rr[0], rr[1]);
; #pragma unroll
;                 for (int bj = 0; bj < 2; ++bj) { f32x4 r0, r1;
;                     if (R) { const u32x4 rw = rr[bj]; r0 = (f32x4){bflo(rw.x), bfhi(rw.x), bflo(rw.y), bfhi(rw.y)}; r1 = (f32x4){bflo(rw.z), bfhi(rw.z), bflo(rw.w), bfhi(rw.w)}; }
;                     else { const float* rp = (row < 8192 ? src_p + off : src_s + (off - (size_t)8192 * D)) + 8 * bj; r0 = *(const f32x4*)rp; r1 = *(const f32x4*)(rp + 4); }
;                     const f32x4 o0 = r0 + acc[ai][bj][m][0] * sc, o1 = r1 + acc[ai][bj][m][1] * sc;
;                     sq += (o0[0] * o0[0] + o0[1] * o0[1]) + (o0[2] * o0[2] + o0[3] * o0[3]) + (o1[0] * o1[0] + o1[1] * o1[1]) + (o1[2] * o1[2] + o1[3] * o1[3]);
;                     w[bj].x = cvt_pk_bf16(o0[0], o0[1]); w[bj].y = cvt_pk_bf16(o0[2], o0[3]); w[bj].z = cvt_pk_bf16(o1[0], o1[1]); w[bj].w = cvt_pk_bf16(o1[2], o1[3]); }
;                 store_pair_lines(O, D, row, fr, col0, w[0], w[1]);
;                 if (ssout) { sq += __shfl_xor(sq, 16); sq += __shfl_xor(sq, 32); if (fq == 0) unsafeAtomicAdd(ssout + row, sq); } }
	global_load_dwordx4 v[224:227], v[186:187], off
	global_load_dwordx4 v[228:231], v[188:189], off
	v_or_b32_e32 v194, s31, v150
	v_add_u32_e32 v184, 0x90, v194
	v_sub_u32_e32 v185, v184, v150
	v_add_u32_e32 v186, v185, v152
	v_ashrrev_i32_e32 v187, 31, v186
	v_lshlrev_b64 v[190:191], 12, v[186:187]
	v_lshl_add_u64 v[192:193], v[190:191], 0, s[28:29]
	v_lshl_add_u64 v[186:187], s[10:11], 0, v[190:191]
	v_lshl_add_u64 v[188:189], s[10:11], 0, v[192:193]
	v_lshl_add_u64 v[186:187], v[186:187], 0, v[146:147]
	v_lshl_add_u64 v[188:189], v[188:189], 0, v[146:147]
	global_load_dwordx4 v[232:235], v[186:187], off
	global_load_dwordx4 v[236:239], v[188:189], off
	v_or_b32_e32 v194, s31, v150
	v_add_u32_e32 v184, 0xa0, v194
	v_sub_u32_e32 v185, v184, v150
	v_add_u32_e32 v186, v185, v152
	v_ashrrev_i32_e32 v187, 31, v186
	v_lshlrev_b64 v[190:191], 12, v[186:187]
	v_lshl_add_u64 v[192:193], v[190:191], 0, s[28:29]
	v_lshl_add_u64 v[186:187], s[10:11], 0, v[190:191]
	v_lshl_add_u64 v[188:189], s[10:11], 0, v[192:193]
	v_lshl_add_u64 v[186:187], v[186:187], 0, v[146:147]
	v_lshl_add_u64 v[188:189], v[188:189], 0, v[146:147]
	global_load_dwordx4 v[240:243], v[186:187], off
	global_load_dwordx4 v[244:247], v[188:189], off
	v_or_b32_e32 v148, s31, v150
	v_mov_b32_dpp v149, v158 row_ror:8 row_mask:0xf bank_mask:0xf
	v_mov_b32_dpp v157, v159 row_ror:8 row_mask:0xf bank_mask:0xf
	v_mov_b32_dpp v171, v161 row_ror:8 row_mask:0xf bank_mask:0xf
	v_mov_b32_dpp v172, v162 row_ror:8 row_mask:0xf bank_mask:0xf
	v_mov_b32_dpp v173, v163 row_ror:8 row_mask:0xf bank_mask:0xf
	v_mov_b32_dpp v170, v160 row_ror:8 row_mask:0xf bank_mask:0xf
	v_mov_b32_dpp v174, v164 row_ror:8 row_mask:0xf bank_mask:0xf
	v_mov_b32_dpp v175, v165 row_ror:8 row_mask:0xf bank_mask:0xf
	v_cndmask_b32_e64 v165, v165, v171, s[6:7]
	v_cndmask_b32_e64 v157, v163, v157, s[6:7]
	v_cndmask_b32_e64 v149, v162, v149, s[6:7]
	v_cndmask_b32_e64 v173, v173, v159, s[6:7]
	v_cndmask_b32_e64 v171, v172, v158, s[6:7]
	v_cndmask_b32_e64 v164, v164, v170, s[6:7]
	v_cndmask_b32_e64 v177, v175, v161, s[6:7]
	v_cndmask_b32_e64 v175, v174, v160, s[6:7]
	v_lshlrev_b32_e32 v158, 16, v149
	v_and_b32_e32 v159, 0xffff0000, v149
	v_lshlrev_b32_e32 v160, 16, v157
	v_and_b32_e32 v161, 0xffff0000, v157
	v_lshlrev_b32_e32 v170, 16, v171
	v_and_b32_e32 v171, 0xffff0000, v171
	v_lshlrev_b32_e32 v172, 16, v173
	v_and_b32_e32 v173, 0xffff0000, v173
	v_lshlrev_b32_e32 v174, 16, v175
	v_and_b32_e32 v175, 0xffff0000, v175
	v_pk_add_f32 v[160:161], v[118:119], v[160:161]
	v_pk_add_f32 v[158:159], v[116:117], v[158:159]
	v_pk_add_f32 v[116:117], v[126:127], v[172:173]
	v_pk_add_f32 v[118:119], v[124:125], v[170:171]
	v_lshlrev_b32_e32 v176, 16, v177
	v_and_b32_e32 v177, 0xffff0000, v177
	v_pk_add_f32 v[120:121], v[120:121], v[174:175]
	v_mul_f32_e32 v124, v119, v119
	v_mul_f32_e32 v125, v117, v117
	v_lshlrev_b32_e32 v162, 16, v164
	v_and_b32_e32 v163, 0xffff0000, v164
	v_lshlrev_b32_e32 v164, 16, v165
	v_and_b32_e32 v165, 0xffff0000, v165
	v_pk_add_f32 v[122:123], v[122:123], v[176:177]
	v_mul_f32_e32 v126, v121, v121
	v_fmac_f32_e32 v124, v118, v118
	v_fmac_f32_e32 v125, v116, v116
	v_pk_add_f32 v[114:115], v[114:115], v[164:165]
	v_mul_f32_e32 v127, v123, v123
	v_cvt_pk_bf16_f32 v119, v118, v119
	v_cvt_pk_bf16_f32 v117, v116, v117
	v_cvt_pk_bf16_f32 v121, v120, v121
	v_fmac_f32_e32 v126, v120, v120
	v_add_f32_e32 v116, v124, v125
	v_pk_add_f32 v[112:113], v[112:113], v[162:163]
	v_cvt_pk_bf16_f32 v123, v122, v123
	v_cvt_pk_bf16_f32 v149, v158, v159
	v_cvt_pk_bf16_f32 v157, v160, v161
	v_fmac_f32_e32 v127, v122, v122
	v_cvt_pk_bf16_f32 v162, v112, v113
	v_cvt_pk_bf16_f32 v163, v114, v115
	v_add_f32_e32 v116, v126, v116
	v_mov_b32_dpp v182, v149 row_ror:8 row_mask:0xf bank_mask:0xf
	v_mov_b32_dpp v120, v163 row_ror:8 row_mask:0xf bank_mask:0xf
	v_mul_f32_e32 v115, v115, v115
	v_mov_b32_dpp v178, v119 row_ror:8 row_mask:0xf bank_mask:0xf
	v_mov_b32_dpp v181, v123 row_ror:8 row_mask:0xf bank_mask:0xf
	v_add_f32_e32 v122, v127, v116
	v_cndmask_b32_e64 v116, v182, v119, s[6:7]
	v_cndmask_b32_e64 v119, v120, v123, s[6:7]
	v_fmac_f32_e32 v115, v114, v114
	v_mul_f32_e32 v114, v159, v159
	v_mul_f32_e32 v123, v161, v161
	v_fmac_f32_e32 v114, v158, v158
	v_fmac_f32_e32 v123, v160, v160
	v_mul_f32_e32 v113, v113, v113
	v_add_f32_e32 v114, v114, v123
	v_fmac_f32_e32 v113, v112, v112
	v_add_f32_e32 v112, v113, v114
	v_add_f32_e32 v112, v115, v112
	v_and_b32_e32 v113, 64, v203
	v_add_f32_e32 v115, v112, v122
	v_xor_b32_e32 v112, 16, v203
	v_add_u32_e32 v126, 64, v113
	v_cmp_lt_i32_e32 vcc, v112, v126
	v_mov_b32_e32 v118, 0
	v_mov_b32_dpp v183, v157 row_ror:8 row_mask:0xf bank_mask:0xf
	v_cndmask_b32_e32 v112, v203, v112, vcc
	v_lshlrev_b32_e32 v114, 2, v112
	v_mov_b32_e32 v127, v115
	s_nop 1
	v_permlane16_swap_b32_e32 v127, v115
	v_lshl_add_u64 v[112:113], s[16:17], 0, v[166:167]
	v_lshl_add_u64 v[124:125], v[112:113], 0, v[146:147]
	v_xor_b32_e32 v113, 32, v203
	v_cmp_lt_i32_e32 vcc, v113, v126
	s_waitcnt lgkmcnt(0)
	v_add_f32_e32 v112, v115, v127
	v_mov_b32_dpp v118, v162 row_ror:8 row_mask:0xf bank_mask:0xf
	v_cndmask_b32_e32 v113, v203, v113, vcc
	v_lshlrev_b32_e32 v115, 2, v113
	v_mov_b32_e32 v113, v112
	s_nop 1
	v_permlane32_swap_b32_e32 v113, v112
	v_mov_b32_dpp v179, v117 row_ror:8 row_mask:0xf bank_mask:0xf
	v_cndmask_b32_e64 v117, v183, v117, s[6:7]
	v_cndmask_b32_e64 v118, v118, v121, s[6:7]
	v_mov_b32_dpp v180, v121 row_ror:8 row_mask:0xf bank_mask:0xf
	global_store_dwordx4 v[124:125], v[116:119], off
	v_cndmask_b32_e64 v120, v149, v178, s[6:7]
	v_cndmask_b32_e64 v121, v157, v179, s[6:7]
	v_lshl_add_u64 v[116:117], s[16:17], 0, v[168:169]
	v_cndmask_b32_e64 v122, v162, v180, s[6:7]
	v_cndmask_b32_e64 v123, v163, v181, s[6:7]
	v_lshl_add_u64 v[116:117], v[116:117], 0, v[146:147]
	global_store_dwordx4 v[116:117], v[120:123], off
	s_and_saveexec_b64 s[42:43], s[8:9]
	s_cbranch_execz .LBB0_1248
	v_ashrrev_i32_e32 v149, 31, v148
	s_waitcnt lgkmcnt(0)
	v_add_f32_e32 v116, v112, v113
	v_lshl_add_u64 v[112:113], v[148:149], 2, s[18:19]
	global_atomic_add_f32 v[112:113], v116, off

;     __device__ __forceinline__ void operator()(const f32x4 (&acc)[2][2][4][2], const Unit& u, int wr, int wc, int fr, int fq) const {
;     ...
;             for (int m = 0; m < 4; ++m) { const int row = row0 + ai * HALF + m * 16; const float ri = __builtin_amdgcn_rsqf(sse[row] * (1.f / D) + EPS);
;                 u32x4 rr[2], ee[2]; load_pair_lines(R, D, row, fr, col0, rr[0], rr[1], 32); load_pair_lines(E, D, row, fr, col0, ee[0], ee[1], 32);
;                 float* orow = OUT + (size_t)(row - fr + (fr & 7)) * D + col0 + (lo ? 0 : 4);
; template <class Epi>
; __device__ __forceinline__ void gemm_phase(LAS unsigned char* lds, const Gemm g, const StaticOrder& S, const Epi& E) {
;     ...
; #pragma unroll
;         for (int a = 0; a < 2; ++a)
; #pragma unroll
;             for (int b = 0; b < 2; ++b)
; #pragma unroll
;                 for (int m = 0; m < 4; ++m)
; #pragma unroll
;                     for (int n = 0; n < 2; ++n) acc[a][b][m][n] = (f32x4){0.f, 0.f, 0.f, 0.f};
;         cur = nxt; cA = nA; cB = nB; ++ui;
.LBB0_1602:
	s_ashr_i32 s23, s22, 31
	s_xor_b64 s[26:27], s[38:39], -1
	s_lshl_b64 s[24:25], s[22:23], 20
	s_add_u32 s24, s8, s24
	s_addc_u32 s25, s9, s25
	s_and_b64 s[28:29], s[38:39], exec
	s_cselect_b32 s23, s25, s35
	s_cselect_b32 s54, s24, s34
	s_ashr_i32 s19, s18, 31
	s_lshl_b64 s[28:29], s[18:19], 20
	s_add_u32 s28, s33, s28
	s_addc_u32 s29, s40, s29
	s_and_b64 s[38:39], s[38:39], exec
	s_cselect_b32 s19, s29, s37
	s_cselect_b32 s55, s28, s36
	s_add_u32 s34, s34, 0x80080
	s_addc_u32 s35, s35, 0
	s_add_u32 s56, s36, 0x100
	v_mov_b32_e32 v0, 0
	s_addc_u32 s57, s37, 0
	s_mov_b32 s58, -2
	v_mov_b32_e32 v1, v0
	v_mov_b32_e32 v2, v0
	v_mov_b32_e32 v3, v0
	v_mov_b32_e32 v4, v0
	v_mov_b32_e32 v5, v0
	v_mov_b32_e32 v6, v0
	v_mov_b32_e32 v7, v0
	v_mov_b32_e32 v16, v0
	v_mov_b32_e32 v17, v0
	v_mov_b32_e32 v18, v0
	v_mov_b32_e32 v19, v0
	v_mov_b32_e32 v20, v0
	v_mov_b32_e32 v21, v0
	v_mov_b32_e32 v22, v0
	v_mov_b32_e32 v23, v0
	v_mov_b32_e32 v32, v0
	v_mov_b32_e32 v33, v0
	v_mov_b32_e32 v34, v0
	v_mov_b32_e32 v35, v0
	v_mov_b32_e32 v36, v0
	v_mov_b32_e32 v37, v0
	v_mov_b32_e32 v38, v0
	v_mov_b32_e32 v39, v0
	v_mov_b32_e32 v64, v0
	v_mov_b32_e32 v65, v0
	v_mov_b32_e32 v66, v0
	v_mov_b32_e32 v67, v0
	v_mov_b32_e32 v68, v0
	v_mov_b32_e32 v69, v0
	v_mov_b32_e32 v70, v0
	v_mov_b32_e32 v71, v0
	v_mov_b32_e32 v8, v0
	v_mov_b32_e32 v9, v0
	v_mov_b32_e32 v10, v0
	v_mov_b32_e32 v11, v0
	v_mov_b32_e32 v12, v0
	v_mov_b32_e32 v13, v0
	v_mov_b32_e32 v14, v0
	v_mov_b32_e32 v15, v0
	v_mov_b32_e32 v24, v0
	v_mov_b32_e32 v25, v0
	v_mov_b32_e32 v26, v0
	v_mov_b32_e32 v27, v0
	v_mov_b32_e32 v28, v0
	v_mov_b32_e32 v29, v0
	v_mov_b32_e32 v30, v0
	v_mov_b32_e32 v31, v0
	v_mov_b32_e32 v48, v0
	v_mov_b32_e32 v49, v0
	v_mov_b32_e32 v50, v0
	v_mov_b32_e32 v51, v0
	v_mov_b32_e32 v52, v0
	v_mov_b32_e32 v53, v0
	v_mov_b32_e32 v54, v0
	v_mov_b32_e32 v55, v0
	v_mov_b32_e32 v72, v0
	v_mov_b32_e32 v73, v0
	v_mov_b32_e32 v74, v0
	v_mov_b32_e32 v75, v0
	v_mov_b32_e32 v76, v0
	v_mov_b32_e32 v77, v0
	v_mov_b32_e32 v78, v0
	v_mov_b32_e32 v79, v0
	v_mov_b32_e32 v80, v0
	v_mov_b32_e32 v81, v0
	v_mov_b32_e32 v82, v0
	v_mov_b32_e32 v83, v0
	v_mov_b32_e32 v84, v0
	v_mov_b32_e32 v85, v0
	v_mov_b32_e32 v86, v0
	v_mov_b32_e32 v87, v0
	v_mov_b32_e32 v96, v0
	v_mov_b32_e32 v97, v0
	v_mov_b32_e32 v98, v0
	v_mov_b32_e32 v99, v0
	v_mov_b32_e32 v100, v0
	v_mov_b32_e32 v101, v0
	v_mov_b32_e32 v102, v0
	v_mov_b32_e32 v103, v0
	v_mov_b32_e32 v112, v0
	v_mov_b32_e32 v113, v0
	v_mov_b32_e32 v114, v0
	v_mov_b32_e32 v115, v0
	v_mov_b32_e32 v116, v0
	v_mov_b32_e32 v117, v0
	v_mov_b32_e32 v118, v0
	v_mov_b32_e32 v119, v0
	v_mov_b32_e32 v128, v0
	v_mov_b32_e32 v129, v0
	v_mov_b32_e32 v130, v0
	v_mov_b32_e32 v131, v0
	v_mov_b32_e32 v132, v0
	v_mov_b32_e32 v133, v0
	v_mov_b32_e32 v134, v0
	v_mov_b32_e32 v135, v0
	v_mov_b32_e32 v88, v0
	v_mov_b32_e32 v89, v0
	v_mov_b32_e32 v90, v0
	v_mov_b32_e32 v91, v0
	v_mov_b32_e32 v92, v0
	v_mov_b32_e32 v93, v0
	v_mov_b32_e32 v94, v0
	v_mov_b32_e32 v95, v0
	v_mov_b32_e32 v104, v0
	v_mov_b32_e32 v105, v0
	v_mov_b32_e32 v106, v0
	v_mov_b32_e32 v107, v0
	v_mov_b32_e32 v108, v0
	v_mov_b32_e32 v109, v0
	v_mov_b32_e32 v110, v0
	v_mov_b32_e32 v111, v0
	v_mov_b32_e32 v120, v0
	v_mov_b32_e32 v121, v0
	v_mov_b32_e32 v122, v0
	v_mov_b32_e32 v123, v0
	v_mov_b32_e32 v124, v0
	v_mov_b32_e32 v125, v0
	v_mov_b32_e32 v126, v0
	v_mov_b32_e32 v127, v0
	v_mov_b32_e32 v136, v0
	v_mov_b32_e32 v137, v0
	v_mov_b32_e32 v138, v0
	v_mov_b32_e32 v139, v0
	v_mov_b32_e32 v140, v0
	v_mov_b32_e32 v141, v0
	v_mov_b32_e32 v142, v0
	v_mov_b32_e32 v143, v0
	s_lshl_b32 s59, s30, 8
	s_add_i32 s59, s59, s49
	v_lshl_or_b32 v40, s53, 8, v178
	v_or_b32_e32 v62, s59, v176
	v_or_b32_e32 v42, v40, v177
	v_ashrrev_i32_e32 v63, 31, v62
	v_or_b32_e32 v60, s59, v174
	v_ashrrev_i32_e32 v43, 31, v42
	v_lshlrev_b64 v[44:45], 12, v[62:63]
	v_ashrrev_i32_e32 v61, 31, v60
	v_lshl_add_u64 v[46:47], s[8:9], 0, v[44:45]
	v_lshlrev_b64 v[56:57], 1, v[42:43]
	v_lshl_add_u64 v[58:59], v[60:61], 2, s[6:7]
	v_lshl_add_u64 v[42:43], v[46:47], 0, v[56:57]
	global_load_dword v234, v[58:59], off
	global_load_dwordx4 v[236:239], v[42:43], off
	v_or_b32_e32 v42, 8, v62
	v_ashrrev_i32_e32 v43, 31, v42
	v_lshlrev_b64 v[42:43], 12, v[42:43]
	v_lshl_add_u64 v[46:47], s[8:9], 0, v[42:43]
	v_lshl_add_u64 v[44:45], s[10:11], 0, v[44:45]
	v_lshl_add_u64 v[42:43], s[10:11], 0, v[42:43]
	v_lshl_add_u64 v[46:47], v[46:47], 0, v[56:57]
	v_lshl_add_u64 v[44:45], v[44:45], 0, v[56:57]
	v_lshl_add_u64 v[42:43], v[42:43], 0, v[56:57]
	global_load_dwordx4 v[240:243], v[46:47], off
	global_load_dwordx4 v[244:247], v[44:45], off
	global_load_dwordx4 v[248:251], v[42:43], off
; #define PG8_STAGE(bufoff, gbase, voff) do { _Pragma("unroll") for (int _i = 0; _i < 2; ++_i) \
;         __builtin_amdgcn_global_load_lds((const unsigned*)((const char*)(gbase) + (voff)[_i]), (LAS unsigned*)(lds + (bufoff) + ldsw + _i * 8192), 16, 0, 0); } while (0)
; #define PG8_LDA(dst, b, h) do { _Pragma("unroll") for (int m = 0; m < 4; ++m) _Pragma("unroll") for (int k = 0; k < 2; ++k) dst[m][k] = *(const LAS bf16x8*)(lds + PG8_SA(b, h) + aoff + m * 2048 + k * 1024); } while (0)
; #define PG8_LDB(dst, b, h) do { _Pragma("unroll") for (int n = 0; n < 2; ++n) _Pragma("unroll") for (int k = 0; k < 2; ++k) dst[n][k] = *(const LAS bf16x8*)(lds + PG8_SB(b, h) + boff + n * 2048 + k * 1024); } while (0)
; #define PG8_MMA(ai, bj, At, Bt) do { __builtin_amdgcn_s_setprio(1); _Pragma("unroll") for (int m = 0; m < 4; ++m) _Pragma("unroll") for (int n = 0; n < 2; ++n) _Pragma("unroll") for (int k = 0; k < 2; ++k) \
;         acc[ai][bj][m][n] = __builtin_amdgcn_mfma_f32_16x16x32_bf16(Bt[n][k], At[m][k], acc[ai][bj][m][n], 0, 0, 0); __builtin_amdgcn_s_setprio(0); } while (0)
; template <class Epi>
; __device__ __forceinline__ void gemm_phase(LAS unsigned char* lds, const Gemm g, const StaticOrder& S, const Epi& E) {
;     ...
;         for (int t = 0; t < nt; t += 2) {
;             const bool last = (t == nt - 2);
;             const char* a1 = cA + (size_t)(t + 1) * kstep;
;             const char* a2 = last ? nA : cA + (size_t)(t + 2) * kstep; const char* b2 = last ? nB : cB + (size_t)(t + 2) * kstep;
;             const char* a3 = a2 + kstep; const char* b3 = b2 + kstep;
;             PG8_LDB(B0, 0, 0); PG8_SCHED; PG8_LDA(At, 0, 0); PG8_STAGE(PG8_SA(1, 1), a1 + hstep, voffA);
;             PG8_WAIT_L(8); PG8_BAR; PG8_WAIT_L(0); PG8_MMA(0, 0, At, B0); PG8_BAR; PG8_SCHED;
;             PG8_LDB(B1, 0, 1); PG8_STAGE(PG8_SB(0, 0), b2, voffB0);
;             PG8_BAR; PG8_WAIT_L(0); PG8_MMA(0, 1, At, B1); PG8_BAR;
;             PG8_LDA(At, 0, 1); PG8_STAGE(PG8_SA(0, 0), a2, voffA);
;             PG8_BAR; PG8_WAIT_L(0); PG8_MMA(1, 0, At, B0); PG8_BAR; PG8_SCHED;
;             PG8_STAGE(PG8_SB(0, 1), b2, voffB1);
;             PG8_WAIT_V(6); PG8_BAR; PG8_MMA(1, 1, At, B1); PG8_BAR;
;             PG8_LDB(B0, 1, 0); PG8_SCHED; PG8_LDA(At, 1, 0); PG8_STAGE(PG8_SA(0, 1), a2 + hstep, voffA);
;             PG8_WAIT_L(8); PG8_BAR; PG8_WAIT_L(0); PG8_MMA(0, 0, At, B0); PG8_BAR; PG8_SCHED;
.LBB0_1603:
	ds_read_b128 v[40:43], v179
	ds_read_b128 v[44:47], v179 offset:1024
	ds_read_b128 v[56:59], v179 offset:2048
	ds_read_b128 v[60:63], v179 offset:3072
	s_add_u32 s36, s34, 0xfff80080
	s_addc_u32 s37, s35, -1
	s_cmp_eq_u32 s58, 28
	s_cselect_b32 s37, s23, s37
	s_cselect_b32 s36, s54, s36
	s_cselect_b32 s39, s19, s57
	s_cselect_b32 s38, s55, s56
	v_lshl_add_u64 v[172:173], s[34:35], 0, v[158:159]
	s_add_i32 m0, s31, 0xc000
	ds_read_b128 v[164:167], v180
	ds_read_b128 v[168:171], v180 offset:1024
	ds_read_b128 v[184:187], v180 offset:2048
	ds_read_b128 v[188:191], v180 offset:3072
	ds_read_b128 v[192:195], v180 offset:4096
	ds_read_b128 v[196:199], v180 offset:5120
	ds_read_b128 v[200:203], v180 offset:6144
	ds_read_b128 v[204:207], v180 offset:7168
	global_load_lds_dwordx4 v[172:173], off
	v_lshl_add_u64 v[172:173], s[34:35], 0, v[160:161]
	s_add_i32 m0, s31, 0xe000
	s_nop 0
	global_load_lds_dwordx4 v[172:173], off
	s_waitcnt lgkmcnt(8)
	s_barrier
	s_waitcnt lgkmcnt(0)
	v_mfma_f32_16x16x32_bf16 v[140:143], v[40:43], v[164:167], v[140:143]
	v_mfma_f32_16x16x32_bf16 v[136:139], v[56:59], v[164:167], v[136:139]
	v_mfma_f32_16x16x32_bf16 v[124:127], v[40:43], v[184:187], v[124:127]
	v_mfma_f32_16x16x32_bf16 v[120:123], v[56:59], v[184:187], v[120:123]
	v_mfma_f32_16x16x32_bf16 v[108:111], v[40:43], v[192:195], v[108:111]
	v_mfma_f32_16x16x32_bf16 v[104:107], v[56:59], v[192:195], v[104:107]
	v_mfma_f32_16x16x32_bf16 v[92:95], v[40:43], v[200:203], v[92:95]
	v_mfma_f32_16x16x32_bf16 v[88:91], v[56:59], v[200:203], v[88:91]
	v_mfma_f32_16x16x32_bf16 v[140:143], v[44:47], v[168:171], v[140:143]
	v_mfma_f32_16x16x32_bf16 v[136:139], v[60:63], v[168:171], v[136:139]
	v_mfma_f32_16x16x32_bf16 v[124:127], v[44:47], v[188:191], v[124:127]
	v_mfma_f32_16x16x32_bf16 v[120:123], v[60:63], v[188:191], v[120:123]
	v_mfma_f32_16x16x32_bf16 v[108:111], v[44:47], v[196:199], v[108:111]
	v_mfma_f32_16x16x32_bf16 v[104:107], v[60:63], v[196:199], v[104:107]
	v_mfma_f32_16x16x32_bf16 v[92:95], v[44:47], v[204:207], v[92:95]
	v_mfma_f32_16x16x32_bf16 v[88:91], v[60:63], v[204:207], v[88:91]
	s_barrier
	s_add_i32 s59, s51, s41
	v_lshl_add_u64 v[172:173], s[38:39], 0, v[146:147]
	s_mov_b32 m0, s59
	ds_read_b128 v[208:211], v181
	ds_read_b128 v[212:215], v181 offset:1024
	ds_read_b128 v[216:219], v181 offset:2048
	ds_read_b128 v[220:223], v181 offset:3072
	global_load_lds_dwordx4 v[172:173], off
	v_lshl_add_u64 v[224:225], s[38:39], 0, v[152:153]
	s_add_i32 m0, s59, 0x2000
	s_nop 0
	global_load_lds_dwordx4 v[224:225], off
	s_barrier
	s_waitcnt lgkmcnt(0)
	v_mfma_f32_16x16x32_bf16 v[132:135], v[208:211], v[164:167], v[132:135]
	v_mfma_f32_16x16x32_bf16 v[128:131], v[216:219], v[164:167], v[128:131]
	v_mfma_f32_16x16x32_bf16 v[116:119], v[208:211], v[184:187], v[116:119]
	v_mfma_f32_16x16x32_bf16 v[112:115], v[216:219], v[184:187], v[112:115]
	v_mfma_f32_16x16x32_bf16 v[100:103], v[208:211], v[192:195], v[100:103]
	v_mfma_f32_16x16x32_bf16 v[96:99], v[216:219], v[192:195], v[96:99]
	v_mfma_f32_16x16x32_bf16 v[84:87], v[208:211], v[200:203], v[84:87]
	v_mfma_f32_16x16x32_bf16 v[80:83], v[216:219], v[200:203], v[80:83]
	v_mfma_f32_16x16x32_bf16 v[132:135], v[212:215], v[168:171], v[132:135]
	v_mfma_f32_16x16x32_bf16 v[128:131], v[220:223], v[168:171], v[128:131]
	v_mfma_f32_16x16x32_bf16 v[116:119], v[212:215], v[188:191], v[116:119]
	v_mfma_f32_16x16x32_bf16 v[112:115], v[220:223], v[188:191], v[112:115]
	v_mfma_f32_16x16x32_bf16 v[100:103], v[212:215], v[196:199], v[100:103]
	v_mfma_f32_16x16x32_bf16 v[96:99], v[220:223], v[196:199], v[96:99]
	v_mfma_f32_16x16x32_bf16 v[84:87], v[212:215], v[204:207], v[84:87]
	v_mfma_f32_16x16x32_bf16 v[80:83], v[220:223], v[204:207], v[80:83]
	s_mov_b32 m0, s31
	v_lshl_add_u64 v[226:227], s[36:37], 0, v[144:145]
	s_barrier
	ds_read_b128 v[164:167], v180 offset:16384
	ds_read_b128 v[168:171], v180 offset:17408
	ds_read_b128 v[184:187], v180 offset:18432
	ds_read_b128 v[188:191], v180 offset:19456
	ds_read_b128 v[192:195], v180 offset:20480
	ds_read_b128 v[196:199], v180 offset:21504
	ds_read_b128 v[200:203], v180 offset:22528
	ds_read_b128 v[204:207], v180 offset:23552
	global_load_lds_dwordx4 v[226:227], off
	v_lshl_add_u64 v[228:229], s[36:37], 0, v[150:151]
	s_mov_b32 m0, s42
	s_nop 0
	global_load_lds_dwordx4 v[228:229], off
	s_barrier
	s_waitcnt lgkmcnt(0)
	v_mfma_f32_16x16x32_bf16 v[76:79], v[40:43], v[164:167], v[76:79]
	v_mfma_f32_16x16x32_bf16 v[72:75], v[56:59], v[164:167], v[72:75]
	v_mfma_f32_16x16x32_bf16 v[52:55], v[40:43], v[184:187], v[52:55]
	v_mfma_f32_16x16x32_bf16 v[48:51], v[56:59], v[184:187], v[48:51]
	v_mfma_f32_16x16x32_bf16 v[28:31], v[40:43], v[192:195], v[28:31]
	v_mfma_f32_16x16x32_bf16 v[24:27], v[56:59], v[192:195], v[24:27]
	v_mfma_f32_16x16x32_bf16 v[12:15], v[40:43], v[200:203], v[12:15]
	v_mfma_f32_16x16x32_bf16 v[8:11], v[56:59], v[200:203], v[8:11]
	v_mfma_f32_16x16x32_bf16 v[76:79], v[44:47], v[168:171], v[76:79]
	v_mfma_f32_16x16x32_bf16 v[72:75], v[60:63], v[168:171], v[72:75]
	v_mfma_f32_16x16x32_bf16 v[52:55], v[44:47], v[188:191], v[52:55]
	v_mfma_f32_16x16x32_bf16 v[48:51], v[60:63], v[188:191], v[48:51]
	v_mfma_f32_16x16x32_bf16 v[28:31], v[44:47], v[196:199], v[28:31]
	v_mfma_f32_16x16x32_bf16 v[24:27], v[60:63], v[196:199], v[24:27]
	v_mfma_f32_16x16x32_bf16 v[12:15], v[44:47], v[204:207], v[12:15]
	v_mfma_f32_16x16x32_bf16 v[8:11], v[60:63], v[204:207], v[8:11]
	s_barrier
	s_add_i32 s59, s52, s41
	v_lshl_add_u64 v[230:231], s[38:39], 0, v[148:149]
	s_mov_b32 m0, s59
	v_lshl_add_u64 v[232:233], s[38:39], 0, v[154:155]
	global_load_lds_dwordx4 v[230:231], off
	s_add_i32 m0, s59, 0x2000
	s_nop 0
	global_load_lds_dwordx4 v[232:233], off
	s_waitcnt vmcnt(6)
	s_barrier
; #define PG8_STAGE(bufoff, gbase, voff) do { _Pragma("unroll") for (int _i = 0; _i < 2; ++_i) \
;         __builtin_amdgcn_global_load_lds((const unsigned*)((const char*)(gbase) + (voff)[_i]), (LAS unsigned*)(lds + (bufoff) + ldsw + _i * 8192), 16, 0, 0); } while (0)
; #define PG8_LDA(dst, b, h) do { _Pragma("unroll") for (int m = 0; m < 4; ++m) _Pragma("unroll") for (int k = 0; k < 2; ++k) dst[m][k] = *(const LAS bf16x8*)(lds + PG8_SA(b, h) + aoff + m * 2048 + k * 1024); } while (0)
; #define PG8_LDB(dst, b, h) do { _Pragma("unroll") for (int n = 0; n < 2; ++n) _Pragma("unroll") for (int k = 0; k < 2; ++k) dst[n][k] = *(const LAS bf16x8*)(lds + PG8_SB(b, h) + boff + n * 2048 + k * 1024); } while (0)
; #define PG8_MMA(ai, bj, At, Bt) do { __builtin_amdgcn_s_setprio(1); _Pragma("unroll") for (int m = 0; m < 4; ++m) _Pragma("unroll") for (int n = 0; n < 2; ++n) _Pragma("unroll") for (int k = 0; k < 2; ++k) \
;         acc[ai][bj][m][n] = __builtin_amdgcn_mfma_f32_16x16x32_bf16(Bt[n][k], At[m][k], acc[ai][bj][m][n], 0, 0, 0); __builtin_amdgcn_s_setprio(0); } while (0)
; #define PG8_WAIT_V(n) asm volatile("s_waitcnt vmcnt(" #n ")" ::: "memory")
; #define PG8_WAIT_L(n) asm volatile("s_waitcnt lgkmcnt(" #n ")" ::: "memory")
; #define PG8_BAR __builtin_amdgcn_s_barrier()
; #define PG8_SCHED __builtin_amdgcn_sched_barrier(0)
; template <class Epi>
; __device__ __forceinline__ void gemm_phase(LAS unsigned char* lds, const Gemm g, const StaticOrder& S, const Epi& E) {
;     ...
;             PG8_WAIT_V(6); PG8_BAR; PG8_MMA(1, 1, At, B1); PG8_BAR;
;             PG8_LDB(B0, 1, 0); PG8_SCHED; PG8_LDA(At, 1, 0); PG8_STAGE(PG8_SA(0, 1), a2 + hstep, voffA);
;             PG8_WAIT_L(8); PG8_BAR; PG8_WAIT_L(0); PG8_MMA(0, 0, At, B0); PG8_BAR; PG8_SCHED;
;             PG8_LDB(B1, 1, 1); PG8_STAGE(PG8_SB(1, 0), b3, voffB0);
;             PG8_BAR; PG8_WAIT_L(0); PG8_MMA(0, 1, At, B1); PG8_BAR;
;             PG8_LDA(At, 1, 1); PG8_STAGE(PG8_SA(1, 0), a3, voffA);
;             PG8_BAR; PG8_WAIT_L(0); PG8_MMA(1, 0, At, B0); PG8_BAR; PG8_SCHED;
;             PG8_STAGE(PG8_SB(1, 1), b3, voffB1);
;             PG8_WAIT_V(6); PG8_BAR; PG8_MMA(1, 1, At, B1); PG8_BAR;
	v_mfma_f32_16x16x32_bf16 v[36:39], v[208:211], v[184:187], v[36:39]
	v_mfma_f32_16x16x32_bf16 v[32:35], v[216:219], v[184:187], v[32:35]
	v_mfma_f32_16x16x32_bf16 v[20:23], v[208:211], v[192:195], v[20:23]
	v_mfma_f32_16x16x32_bf16 v[16:19], v[216:219], v[192:195], v[16:19]
	v_mfma_f32_16x16x32_bf16 v[4:7], v[208:211], v[200:203], v[4:7]
	v_mfma_f32_16x16x32_bf16 v[0:3], v[216:219], v[200:203], v[0:3]
	v_mfma_f32_16x16x32_bf16 v[40:43], v[208:211], v[164:167], v[68:71]
	v_mfma_f32_16x16x32_bf16 v[44:47], v[216:219], v[164:167], v[64:67]
	v_mfma_f32_16x16x32_bf16 v[36:39], v[212:215], v[188:191], v[36:39]
	v_mfma_f32_16x16x32_bf16 v[32:35], v[220:223], v[188:191], v[32:35]
	v_mfma_f32_16x16x32_bf16 v[20:23], v[212:215], v[196:199], v[20:23]
	v_mfma_f32_16x16x32_bf16 v[16:19], v[220:223], v[196:199], v[16:19]
	v_mfma_f32_16x16x32_bf16 v[4:7], v[212:215], v[204:207], v[4:7]
	v_mfma_f32_16x16x32_bf16 v[0:3], v[220:223], v[204:207], v[0:3]
	v_mfma_f32_16x16x32_bf16 v[40:43], v[212:215], v[168:171], v[40:43]
	v_mfma_f32_16x16x32_bf16 v[44:47], v[220:223], v[168:171], v[44:47]
	s_add_i32 s38, 0, 0x18000
	v_add_u32_e32 v68, s38, v175
	s_barrier
	ds_read_b128 v[56:59], v68
	ds_read_b128 v[60:63], v68 offset:1024
	ds_read_b128 v[64:67], v68 offset:2048
	ds_read_b128 v[68:71], v68 offset:3072
	s_add_u32 s36, s36, 0x80000
	s_addc_u32 s37, s37, 0
	s_mov_b32 m0, s43
	v_lshl_add_u64 v[208:209], s[36:37], 0, v[144:145]
	ds_read_b128 v[164:167], v180 offset:32768
	ds_read_b128 v[168:171], v180 offset:33792
	ds_read_b128 v[184:187], v180 offset:34816
	ds_read_b128 v[188:191], v180 offset:35840
	ds_read_b128 v[192:195], v180 offset:36864
	ds_read_b128 v[196:199], v180 offset:37888
	ds_read_b128 v[200:203], v180 offset:38912
	ds_read_b128 v[204:207], v180 offset:39936
	global_load_lds_dwordx4 v[208:209], off
	v_lshl_add_u64 v[208:209], s[36:37], 0, v[150:151]
	s_mov_b32 m0, s44
	s_nop 0
	global_load_lds_dwordx4 v[208:209], off
	s_waitcnt lgkmcnt(8)
	s_barrier
	s_waitcnt lgkmcnt(0)
	v_mfma_f32_16x16x32_bf16 v[140:143], v[56:59], v[164:167], v[140:143]
	v_mfma_f32_16x16x32_bf16 v[136:139], v[64:67], v[164:167], v[136:139]
	v_mfma_f32_16x16x32_bf16 v[124:127], v[56:59], v[184:187], v[124:127]
	v_mfma_f32_16x16x32_bf16 v[120:123], v[64:67], v[184:187], v[120:123]
	v_mfma_f32_16x16x32_bf16 v[108:111], v[56:59], v[192:195], v[108:111]
	v_mfma_f32_16x16x32_bf16 v[104:107], v[64:67], v[192:195], v[104:107]
	v_mfma_f32_16x16x32_bf16 v[92:95], v[56:59], v[200:203], v[92:95]
	v_mfma_f32_16x16x32_bf16 v[88:91], v[64:67], v[200:203], v[88:91]
	v_mfma_f32_16x16x32_bf16 v[140:143], v[60:63], v[168:171], v[140:143]
	v_mfma_f32_16x16x32_bf16 v[136:139], v[68:71], v[168:171], v[136:139]
	v_mfma_f32_16x16x32_bf16 v[124:127], v[60:63], v[188:191], v[124:127]
	v_mfma_f32_16x16x32_bf16 v[120:123], v[68:71], v[188:191], v[120:123]
	v_mfma_f32_16x16x32_bf16 v[108:111], v[60:63], v[196:199], v[108:111]
	v_mfma_f32_16x16x32_bf16 v[104:107], v[68:71], v[196:199], v[104:107]
	v_mfma_f32_16x16x32_bf16 v[92:95], v[60:63], v[204:207], v[92:95]
	v_mfma_f32_16x16x32_bf16 v[88:91], v[68:71], v[204:207], v[88:91]
	s_barrier
	s_add_i32 s36, 0, 0x1c000
	s_add_i32 s37, s38, s41
	v_add_u32_e32 v183, s36, v175
	v_lshl_add_u64 v[172:173], v[172:173], 0, s[14:15]
	s_mov_b32 m0, s37
	ds_read_b128 v[208:211], v183
	ds_read_b128 v[212:215], v183 offset:1024
	ds_read_b128 v[216:219], v183 offset:2048
	ds_read_b128 v[220:223], v183 offset:3072
	global_load_lds_dwordx4 v[172:173], off
	v_lshl_add_u64 v[172:173], v[224:225], 0, s[14:15]
	s_add_i32 m0, s37, 0x2000
	s_nop 0
	global_load_lds_dwordx4 v[172:173], off
	s_barrier
	s_waitcnt lgkmcnt(0)
	v_mfma_f32_16x16x32_bf16 v[132:135], v[208:211], v[164:167], v[132:135]
	v_mfma_f32_16x16x32_bf16 v[128:131], v[216:219], v[164:167], v[128:131]
	v_mfma_f32_16x16x32_bf16 v[116:119], v[208:211], v[184:187], v[116:119]
	v_mfma_f32_16x16x32_bf16 v[112:115], v[216:219], v[184:187], v[112:115]
	v_mfma_f32_16x16x32_bf16 v[100:103], v[208:211], v[192:195], v[100:103]
	v_mfma_f32_16x16x32_bf16 v[96:99], v[216:219], v[192:195], v[96:99]
	v_mfma_f32_16x16x32_bf16 v[84:87], v[208:211], v[200:203], v[84:87]
	v_mfma_f32_16x16x32_bf16 v[80:83], v[216:219], v[200:203], v[80:83]
	v_mfma_f32_16x16x32_bf16 v[132:135], v[212:215], v[168:171], v[132:135]
	v_mfma_f32_16x16x32_bf16 v[128:131], v[220:223], v[168:171], v[128:131]
	v_mfma_f32_16x16x32_bf16 v[116:119], v[212:215], v[188:191], v[116:119]
	v_mfma_f32_16x16x32_bf16 v[112:115], v[220:223], v[188:191], v[112:115]
	v_mfma_f32_16x16x32_bf16 v[100:103], v[212:215], v[196:199], v[100:103]
	v_mfma_f32_16x16x32_bf16 v[96:99], v[220:223], v[196:199], v[96:99]
	v_mfma_f32_16x16x32_bf16 v[84:87], v[212:215], v[204:207], v[84:87]
	v_mfma_f32_16x16x32_bf16 v[80:83], v[220:223], v[204:207], v[80:83]
	s_mov_b32 m0, s47
	v_lshl_add_u64 v[172:173], v[226:227], 0, s[14:15]
	s_barrier
	ds_read_b128 v[164:167], v180 offset:49152
	ds_read_b128 v[168:171], v180 offset:50176
	ds_read_b128 v[184:187], v180 offset:51200
	ds_read_b128 v[188:191], v180 offset:52224
	ds_read_b128 v[192:195], v180 offset:53248
	ds_read_b128 v[196:199], v180 offset:54272
	ds_read_b128 v[200:203], v180 offset:55296
	ds_read_b128 v[204:207], v180 offset:56320
	global_load_lds_dwordx4 v[172:173], off
	v_lshl_add_u64 v[172:173], v[228:229], 0, s[14:15]
	s_mov_b32 m0, s48
	s_nop 0
	global_load_lds_dwordx4 v[172:173], off
	s_barrier
; __device__ __forceinline__ float bflo(unsigned w) { return __uint_as_float(w << 16); }
; __device__ __forceinline__ float bfhi(unsigned w) { return __uint_as_float(w & 0xffff0000u); }
; #define PG8_WAIT_V(n) asm volatile("s_waitcnt vmcnt(" #n ")" ::: "memory")
; #define PG8_BAR __builtin_amdgcn_s_barrier()
;     __device__ __forceinline__ void operator()(const f32x4 (&acc)[2][2][4][2], const Unit& u, int wr, int wc, int fr, int fq) const {
;         const int row0 = u.pm * BM + wr * 64 + fr, col0 = u.pn * BM + wc * 64 + 8 * fq;
;         f32x4 gv[2][2];
; #pragma unroll
;         for (int bj = 0; bj < 2; ++bj) { gv[bj][0] = *(const f32x4*)(g + col0 + 32 * bj); gv[bj][1] = *(const f32x4*)(g + col0 + 32 * bj + 4); }
;         const bool lo = fr < 8;
; #pragma unroll
;         for (int ai = 0; ai < 2; ++ai)
; #pragma unroll
;             for (int m = 0; m < 4; ++m) { const int row = row0 + ai * HALF + m * 16; const float ri = __builtin_amdgcn_rsqf(sse[row] * (1.f / D) + EPS);
;                 u32x4 rr[2], ee[2]; load_pair_lines(R, D, row, fr, col0, rr[0], rr[1], 32); load_pair_lines(E, D, row, fr, col0, ee[0], ee[1], 32);
;                 float* orow = OUT + (size_t)(row - fr + (fr & 7)) * D + col0 + (lo ? 0 : 4);
; #pragma unroll
;                 for (int bj = 0; bj < 2; ++bj) { const u32x4 rw = rr[bj], ew = ee[bj];
;                     const float r[8] = {bflo(rw.x), bfhi(rw.x), bflo(rw.y), bfhi(rw.y), bflo(rw.z), bfhi(rw.z), bflo(rw.w), bfhi(rw.w)};
;                     const float e[8] = {bflo(ew.x), bfhi(ew.x), bflo(ew.y), bfhi(ew.y), bflo(ew.z), bfhi(ew.z), bflo(ew.w), bfhi(ew.w)};
;                     float o[8];
; #pragma unroll
;                     for (int j = 0; j < 8; ++j) { const float a = acc[ai][bj][m][j >> 2][j & 3]; const float gg = gv[bj][j >> 2][j & 3];
;                         o[j] = r[j] + e[j] * ri * gg * __builtin_amdgcn_rcpf(1.f + __builtin_amdgcn_exp2f(-a * LOG2E)); }
; template <class Epi>
; __device__ __forceinline__ void gemm_phase(LAS unsigned char* lds, const Gemm g, const StaticOrder& S, const Epi& E) {
;     ...
;             PG8_WAIT_V(6); PG8_BAR; PG8_MMA(1, 1, At, B1); PG8_BAR;
;         }
;         E(acc, cur, wr, wc, fr, fq);
	s_waitcnt lgkmcnt(0)
	v_mfma_f32_16x16x32_bf16 v[76:79], v[56:59], v[164:167], v[76:79]
	v_mfma_f32_16x16x32_bf16 v[72:75], v[64:67], v[164:167], v[72:75]
	v_mfma_f32_16x16x32_bf16 v[52:55], v[56:59], v[184:187], v[52:55]
	v_mfma_f32_16x16x32_bf16 v[48:51], v[64:67], v[184:187], v[48:51]
	v_mfma_f32_16x16x32_bf16 v[28:31], v[56:59], v[192:195], v[28:31]
	v_mfma_f32_16x16x32_bf16 v[24:27], v[64:67], v[192:195], v[24:27]
	v_mfma_f32_16x16x32_bf16 v[12:15], v[56:59], v[200:203], v[12:15]
	v_mfma_f32_16x16x32_bf16 v[8:11], v[64:67], v[200:203], v[8:11]
	v_mfma_f32_16x16x32_bf16 v[76:79], v[60:63], v[168:171], v[76:79]
	v_mfma_f32_16x16x32_bf16 v[72:75], v[68:71], v[168:171], v[72:75]
	v_mfma_f32_16x16x32_bf16 v[52:55], v[60:63], v[188:191], v[52:55]
	v_mfma_f32_16x16x32_bf16 v[48:51], v[68:71], v[188:191], v[48:51]
	v_mfma_f32_16x16x32_bf16 v[28:31], v[60:63], v[196:199], v[28:31]
	v_mfma_f32_16x16x32_bf16 v[24:27], v[68:71], v[196:199], v[24:27]
	v_mfma_f32_16x16x32_bf16 v[12:15], v[60:63], v[204:207], v[12:15]
	v_mfma_f32_16x16x32_bf16 v[8:11], v[68:71], v[204:207], v[8:11]
	s_barrier
	s_add_i32 s36, s36, s41
	v_lshl_add_u64 v[56:57], v[230:231], 0, s[14:15]
	s_mov_b32 m0, s36
	s_nop 0
	global_load_lds_dwordx4 v[56:57], off
	v_lshl_add_u64 v[56:57], v[232:233], 0, s[14:15]
	s_add_i32 m0, s36, 0x2000
	s_nop 0
	global_load_lds_dwordx4 v[56:57], off
	s_waitcnt vmcnt(6)
	s_barrier
	v_mfma_f32_16x16x32_bf16 v[40:43], v[208:211], v[164:167], v[40:43]
	v_mfma_f32_16x16x32_bf16 v[68:71], v[212:215], v[168:171], v[40:43]
	v_mfma_f32_16x16x32_bf16 v[40:43], v[216:219], v[164:167], v[44:47]
	v_mfma_f32_16x16x32_bf16 v[36:39], v[208:211], v[184:187], v[36:39]
	v_mfma_f32_16x16x32_bf16 v[32:35], v[216:219], v[184:187], v[32:35]
	v_mfma_f32_16x16x32_bf16 v[20:23], v[208:211], v[192:195], v[20:23]
	v_mfma_f32_16x16x32_bf16 v[16:19], v[216:219], v[192:195], v[16:19]
	v_mfma_f32_16x16x32_bf16 v[4:7], v[208:211], v[200:203], v[4:7]
	v_mfma_f32_16x16x32_bf16 v[0:3], v[216:219], v[200:203], v[0:3]
	v_mfma_f32_16x16x32_bf16 v[64:67], v[220:223], v[168:171], v[40:43]
	v_mfma_f32_16x16x32_bf16 v[36:39], v[212:215], v[188:191], v[36:39]
	v_mfma_f32_16x16x32_bf16 v[32:35], v[220:223], v[188:191], v[32:35]
	v_mfma_f32_16x16x32_bf16 v[20:23], v[212:215], v[196:199], v[20:23]
	v_mfma_f32_16x16x32_bf16 v[16:19], v[220:223], v[196:199], v[16:19]
	v_mfma_f32_16x16x32_bf16 v[4:7], v[212:215], v[204:207], v[4:7]
	v_mfma_f32_16x16x32_bf16 v[0:3], v[220:223], v[204:207], v[0:3]
	s_add_i32 s58, s58, 2
	s_add_u32 s34, s34, 0x100
	s_addc_u32 s35, s35, 0
	s_add_u32 s56, s56, 0x100
	s_addc_u32 s57, s57, 0
	s_cmp_gt_u32 s58, 29
	s_barrier
	s_cbranch_scc0 .LBB0_1603
	s_lshl_b32 s19, s30, 8
	s_add_i32 s19, s19, s49
	v_lshl_or_b32 v40, s53, 8, v178
	v_or_b32_e32 v172, s19, v176
	v_or_b32_e32 v42, v40, v177
	v_ashrrev_i32_e32 v173, 31, v172
	v_or_b32_e32 v170, s19, v174
	v_ashrrev_i32_e32 v43, 31, v42
	v_lshlrev_b64 v[44:45], 12, v[172:173]
	v_ashrrev_i32_e32 v171, 31, v170
	v_lshl_add_u64 v[46:47], s[8:9], 0, v[44:45]
	v_lshlrev_b64 v[164:165], 1, v[42:43]
	v_lshl_add_u64 v[168:169], v[170:171], 2, s[6:7]
	v_lshl_add_u64 v[42:43], v[46:47], 0, v[164:165]
	s_waitcnt vmcnt(8)
	s_nop 0
	v_mov_b32_e32 v171, v234
	s_nop 1
	s_nop 0
	v_mov_b64_e32 v[184:185], v[236:237]
	v_mov_b64_e32 v[186:187], v[238:239]
	s_nop 1
	v_or_b32_e32 v42, 8, v172
	v_ashrrev_i32_e32 v43, 31, v42
	v_lshlrev_b64 v[42:43], 12, v[42:43]
	v_lshl_add_u64 v[46:47], s[8:9], 0, v[42:43]
	v_lshl_add_u64 v[44:45], s[10:11], 0, v[44:45]
	v_lshl_add_u64 v[42:43], s[10:11], 0, v[42:43]
	v_lshl_add_u64 v[46:47], v[46:47], 0, v[164:165]
	v_lshl_add_u64 v[44:45], v[44:45], 0, v[164:165]
	v_lshl_add_u64 v[42:43], v[42:43], 0, v[164:165]
	s_nop 0
	v_mov_b64_e32 v[188:189], v[240:241]
	v_mov_b64_e32 v[190:191], v[242:243]
	s_nop 1
	s_nop 0
	v_mov_b64_e32 v[192:193], v[244:245]
	v_mov_b64_e32 v[194:195], v[246:247]
	s_nop 1
	s_nop 0
	v_mov_b64_e32 v[196:197], v[248:249]
	v_mov_b64_e32 v[198:199], v[250:251]
	s_nop 1
	v_ashrrev_i32_e32 v41, 31, v40
	v_lshlrev_b64 v[166:167], 2, v[40:41]
	v_lshl_add_u64 v[44:45], s[12:13], 0, v[166:167]
	global_load_dwordx4 v[56:59], v[44:45], off
	global_load_dwordx4 v[60:63], v[44:45], off offset:16
	v_mul_f32_e32 v40, 0xbfb8aa3b, v140
	v_exp_f32_e32 v215, v40
	global_load_dwordx4 v[40:43], v[44:45], off offset:128
	s_nop 0
	global_load_dwordx4 v[44:47], v[44:45], off offset:144
	v_or_b32_e32 v216, 16, v170
	v_ashrrev_i32_e32 v217, 31, v216
	v_lshl_add_u64 v[218:219], v[216:217], 2, s[6:7]
	v_sub_u32_e32 v216, v216, v174
	v_add_u32_e32 v222, v216, v176
	v_ashrrev_i32_e32 v223, 31, v222
	v_lshlrev_b64 v[216:217], 12, v[222:223]
	v_lshl_add_u64 v[224:225], v[216:217], 0, s[16:17]
	global_load_dword v228, v[218:219], off
	v_lshl_add_u64 v[218:219], s[8:9], 0, v[216:217]
	v_lshl_add_u64 v[220:221], s[8:9], 0, v[224:225]
	v_lshl_add_u64 v[216:217], s[10:11], 0, v[216:217]
	v_lshl_add_u64 v[218:219], v[218:219], 0, v[164:165]
	v_lshl_add_u64 v[220:221], v[220:221], 0, v[164:165]
	v_lshl_add_u64 v[216:217], v[216:217], 0, v[164:165]
	global_load_dwordx4 v[232:235], v[218:219], off
	global_load_dwordx4 v[236:239], v[220:221], off
	global_load_dwordx4 v[240:243], v[216:217], off
	v_lshl_add_u64 v[216:217], s[10:11], 0, v[224:225]
	v_lshl_add_u64 v[216:217], v[216:217], 0, v[164:165]
	global_load_dwordx4 v[244:247], v[216:217], off
	v_mul_f32_e32 v141, 0xbfb8aa3b, v141
	v_mul_f32_e32 v136, 0xbfb8aa3b, v136
	v_mul_f32_e32 v137, 0xbfb8aa3b, v137
	v_exp_f32_e32 v141, v141
	v_mul_f32_e32 v142, 0xbfb8aa3b, v142
	v_exp_f32_e32 v136, v136
	v_exp_f32_e32 v137, v137
	v_exp_f32_e32 v142, v142
	v_mul_f32_e32 v143, 0xbfb8aa3b, v143
	v_exp_f32_e32 v143, v143
	v_add_f32_e32 v141, 1.0, v141
	v_add_f32_e32 v136, 1.0, v136
	v_add_f32_e32 v137, 1.0, v137
	v_rcp_f32_e32 v136, v136
	v_rcp_f32_e32 v137, v137
	v_mul_f32_e32 v138, 0xbfb8aa3b, v138
	v_mul_f32_e32 v139, 0xbfb8aa3b, v139
	v_exp_f32_e32 v138, v138
	v_exp_f32_e32 v139, v139
	v_add_f32_e32 v138, 1.0, v138
	v_add_f32_e32 v139, 1.0, v139
	v_rcp_f32_e32 v138, v138
	v_rcp_f32_e32 v139, v139
	v_mul_f32_e32 v128, 0xbfb8aa3b, v128
	v_mul_f32_e32 v129, 0xbfb8aa3b, v129
	v_exp_f32_e32 v128, v128
	v_exp_f32_e32 v129, v129
	v_mul_f32_e32 v132, 0xbfb8aa3b, v132
	v_mul_f32_e32 v133, 0xbfb8aa3b, v133
	v_exp_f32_e32 v132, v132
	v_exp_f32_e32 v133, v133
	v_lshlrev_b64 v[172:173], 13, v[172:173]
	v_add_f32_e32 v128, 1.0, v128
	v_add_f32_e32 v129, 1.0, v129
	v_lshl_add_u64 v[172:173], s[4:5], 0, v[172:173]
	v_rcp_f32_e32 v128, v128
	v_mul_f32_e32 v130, 0xbfb8aa3b, v130
	v_mul_f32_e32 v131, 0xbfb8aa3b, v131
	v_rcp_f32_e32 v129, v129
	v_lshl_add_u64 v[172:173], v[172:173], 0, v[166:167]
	v_exp_f32_e32 v130, v130
	v_exp_f32_e32 v131, v131
	v_lshl_add_u64 v[172:173], v[172:173], 0, v[156:157]
	s_waitcnt vmcnt(5)
; __device__ __forceinline__ float bflo(unsigned w) { return __uint_as_float(w << 16); }
; __device__ __forceinline__ float bfhi(unsigned w) { return __uint_as_float(w & 0xffff0000u); }
; __device__ __forceinline__ unsigned dpp_ror8(unsigned x) { return (unsigned)__builtin_amdgcn_update_dpp(0, (int)x, 0x128, 0xf, 0xf, false); }
;     __device__ __forceinline__ void operator()(const f32x4 (&acc)[2][2][4][2], const Unit& u, int wr, int wc, int fr, int fq) const {
;     ...
;             for (int m = 0; m < 4; ++m) { const int row = row0 + ai * HALF + m * 16; const float ri = __builtin_amdgcn_rsqf(sse[row] * (1.f / D) + EPS);
;                 u32x4 rr[2], ee[2]; load_pair_lines(R, D, row, fr, col0, rr[0], rr[1], 32); load_pair_lines(E, D, row, fr, col0, ee[0], ee[1], 32);
;                 float* orow = OUT + (size_t)(row - fr + (fr & 7)) * D + col0 + (lo ? 0 : 4);
; #pragma unroll
;                 for (int bj = 0; bj < 2; ++bj) { const u32x4 rw = rr[bj], ew = ee[bj];
;                     const float r[8] = {bflo(rw.x), bfhi(rw.x), bflo(rw.y), bfhi(rw.y), bflo(rw.z), bfhi(rw.z), bflo(rw.w), bfhi(rw.w)};
;                     const float e[8] = {bflo(ew.x), bfhi(ew.x), bflo(ew.y), bfhi(ew.y), bflo(ew.z), bfhi(ew.z), bflo(ew.w), bfhi(ew.w)};
;                     float o[8];
; #pragma unroll
;                     for (int j = 0; j < 8; ++j) { const float a = acc[ai][bj][m][j >> 2][j & 3]; const float gg = gv[bj][j >> 2][j & 3];
;                         o[j] = r[j] + e[j] * ri * gg * __builtin_amdgcn_rcpf(1.f + __builtin_amdgcn_exp2f(-a * LOG2E)); }
;                     f32x4 o1, o2;
; #pragma unroll
;                     for (int j = 0; j < 4; ++j) { const unsigned a = __float_as_uint(o[j]), b = __float_as_uint(o[4 + j]); const unsigned sa = dpp_ror8(a), sb = dpp_ror8(b);
;                         o1[j] = __uint_as_float(lo ? a : sb); o2[j] = __uint_as_float(lo ? sa : b); }
;                     *(f32x4*)(orow + 32 * bj) = o1; *(f32x4*)(orow + (size_t)8 * D + 32 * bj) = o2; } }
	v_fmamk_f32 v140, v171, 0x3a000000, v182
	v_rsq_f32_e32 v140, v140
	v_mov_b32_dpp v200, v185 row_ror:8 row_mask:0xf bank_mask:0xf
	v_mov_b32_dpp v183, v184 row_ror:8 row_mask:0xf bank_mask:0xf
	v_mov_b32_dpp v201, v186 row_ror:8 row_mask:0xf bank_mask:0xf
	v_mov_b32_dpp v202, v187 row_ror:8 row_mask:0xf bank_mask:0xf
	v_add_f32_e32 v132, 1.0, v132
	v_add_f32_e32 v133, 1.0, v133
	v_rcp_f32_e32 v132, v132
	v_mul_f32_e32 v134, 0xbfb8aa3b, v134
	v_mul_f32_e32 v135, 0xbfb8aa3b, v135
	v_mov_b32_dpp v204, v189 row_ror:8 row_mask:0xf bank_mask:0xf
	v_cndmask_b32_e64 v171, v189, v200, s[0:1]
	v_mov_b32_dpp v213, v198 row_ror:8 row_mask:0xf bank_mask:0xf
	v_cndmask_b32_e64 v200, v204, v185, s[0:1]
	v_cndmask_b32_e64 v189, v213, v194, s[0:1]
	v_rcp_f32_e32 v185, v141
	v_add_f32_e32 v141, 1.0, v142
	v_mov_b32_dpp v203, v188 row_ror:8 row_mask:0xf bank_mask:0xf
	v_mov_b32_dpp v205, v190 row_ror:8 row_mask:0xf bank_mask:0xf
	v_mov_b32_dpp v206, v191 row_ror:8 row_mask:0xf bank_mask:0xf
	v_cndmask_b32_e64 v183, v188, v183, s[0:1]
	v_rcp_f32_e32 v142, v141
	v_add_f32_e32 v141, 1.0, v143
	v_lshlrev_b32_e32 v188, 16, v189
	v_and_b32_e32 v189, 0xffff0000, v189
	v_cndmask_b32_e64 v190, v190, v201, s[0:1]
	v_cndmask_b32_e64 v201, v206, v187, s[0:1]
	v_cndmask_b32_e64 v187, v205, v186, s[0:1]
	v_pk_mul_f32 v[188:189], v[140:141], v[188:189] op_sel_hi:[0,1]
	v_cndmask_b32_e64 v191, v191, v202, s[0:1]
	v_mov_b32_dpp v211, v196 row_ror:8 row_mask:0xf bank_mask:0xf
	v_cndmask_b32_e64 v202, v203, v184, s[0:1]
	v_add_f32_e32 v184, 1.0, v215
	v_lshlrev_b32_e32 v186, 16, v187
	v_and_b32_e32 v187, 0xffff0000, v187
	v_pk_mul_f32 v[188:189], v[60:61], v[188:189]
	v_mov_b32_dpp v207, v192 row_ror:8 row_mask:0xf bank_mask:0xf
	v_cndmask_b32_e64 v192, v211, v192, s[0:1]
	v_rcp_f32_e32 v184, v184
	v_rcp_f32_e32 v143, v141
	v_pk_fma_f32 v[188:189], v[136:137], v[188:189], v[186:187]
	v_mov_b32_e32 v141, v157
	v_lshlrev_b32_e32 v186, 16, v192
	v_and_b32_e32 v187, 0xffff0000, v192
	v_mov_b32_dpp v141, v188 row_ror:8 row_mask:0xf bank_mask:0xf
	v_mov_b32_dpp v214, v199 row_ror:8 row_mask:0xf bank_mask:0xf
	v_pk_mul_f32 v[186:187], v[140:141], v[186:187] op_sel_hi:[0,1]
	v_mov_b32_dpp v210, v195 row_ror:8 row_mask:0xf bank_mask:0xf
	v_cndmask_b32_e64 v195, v214, v195, s[0:1]
	v_lshlrev_b32_e32 v136, 16, v202
	v_and_b32_e32 v137, 0xffff0000, v202
	v_pk_mul_f32 v[186:187], v[56:57], v[186:187]
	v_mov_b32_dpp v212, v197 row_ror:8 row_mask:0xf bank_mask:0xf
	v_pk_fma_f32 v[136:137], v[184:185], v[186:187], v[136:137]
	v_lshlrev_b32_e32 v186, 16, v195
	v_and_b32_e32 v187, 0xffff0000, v195
	v_pk_mul_f32 v[186:187], v[140:141], v[186:187] op_sel_hi:[0,1]
	v_mov_b32_dpp v208, v193 row_ror:8 row_mask:0xf bank_mask:0xf
	v_cndmask_b32_e64 v193, v212, v193, s[0:1]
	v_lshlrev_b32_e32 v184, 16, v201
	v_and_b32_e32 v185, 0xffff0000, v201
	v_pk_mul_f32 v[186:187], v[62:63], v[186:187]
	v_mov_b32_dpp v209, v194 row_ror:8 row_mask:0xf bank_mask:0xf
	v_pk_fma_f32 v[184:185], v[138:139], v[186:187], v[184:185]
	v_lshlrev_b32_e32 v186, 16, v193
	v_and_b32_e32 v187, 0xffff0000, v193
	v_pk_mul_f32 v[186:187], v[140:141], v[186:187] op_sel_hi:[0,1]
	v_lshlrev_b32_e32 v138, 16, v200
	v_and_b32_e32 v139, 0xffff0000, v200
	v_pk_mul_f32 v[186:187], v[58:59], v[186:187]
	v_cndmask_b32_e64 v194, v197, v208, s[0:1]
	v_pk_fma_f32 v[138:139], v[142:143], v[186:187], v[138:139]
	v_mov_b32_e32 v142, v157
	v_mov_b32_e32 v143, v157
	v_cndmask_b32_e64 v197, v199, v210, s[0:1]
	v_cndmask_b32_e64 v198, v198, v209, s[0:1]
	v_mov_b32_e32 v199, v157
	v_mov_b32_e32 v195, v157
	v_mov_b32_e32 v201, v157
	v_mov_b32_dpp v142, v138 row_ror:8 row_mask:0xf bank_mask:0xf
	v_mov_b32_dpp v143, v139 row_ror:8 row_mask:0xf bank_mask:0xf
	v_mov_b32_dpp v199, v189 row_ror:8 row_mask:0xf bank_mask:0xf
	v_mov_b32_e32 v192, v157
	v_mov_b32_e32 v202, v157
	v_mov_b32_dpp v195, v184 row_ror:8 row_mask:0xf bank_mask:0xf
	v_mov_b32_dpp v201, v185 row_ror:8 row_mask:0xf bank_mask:0xf
	v_cndmask_b32_e64 v187, v185, v143, s[0:1]
	v_cndmask_b32_e64 v186, v184, v142, s[0:1]
	v_lshlrev_b32_e32 v142, 16, v198
	v_and_b32_e32 v143, 0xffff0000, v198
	v_mov_b32_dpp v192, v136 row_ror:8 row_mask:0xf bank_mask:0xf
	v_mov_b32_dpp v202, v137 row_ror:8 row_mask:0xf bank_mask:0xf
	v_cndmask_b32_e64 v139, v201, v139, s[0:1]
	v_cndmask_b32_e64 v138, v195, v138, s[0:1]
	v_cndmask_b32_e64 v137, v199, v137, s[0:1]
	v_cndmask_b32_e64 v136, v141, v136, s[0:1]
	v_pk_mul_f32 v[142:143], v[140:141], v[142:143] op_sel_hi:[0,1]
	v_cndmask_b32_e64 v196, v196, v207, s[0:1]
	global_store_dwordx4 v[172:173], v[136:139], off
	v_rcp_f32_e32 v133, v133
	v_pk_mul_f32 v[142:143], v[44:45], v[142:143]
	v_lshlrev_b32_e32 v138, 16, v190
	v_and_b32_e32 v139, 0xffff0000, v190
	v_exp_f32_e32 v134, v134
	v_exp_f32_e32 v135, v135
	v_pk_fma_f32 v[138:139], v[128:129], v[142:143], v[138:139]
	v_lshlrev_b32_e32 v142, 16, v196
	v_and_b32_e32 v143, 0xffff0000, v196
	v_add_f32_e32 v130, 1.0, v130
	v_add_f32_e32 v131, 1.0, v131
	v_pk_mul_f32 v[142:143], v[140:141], v[142:143] op_sel_hi:[0,1]
	v_rcp_f32_e32 v130, v130
	v_rcp_f32_e32 v131, v131
	v_lshlrev_b32_e32 v128, 16, v183
	v_and_b32_e32 v129, 0xffff0000, v183
	v_pk_mul_f32 v[142:143], v[40:41], v[142:143]
	v_add_f32_e32 v134, 1.0, v134
	v_pk_fma_f32 v[128:129], v[132:133], v[142:143], v[128:129]
	v_lshlrev_b32_e32 v142, 16, v197
	v_and_b32_e32 v143, 0xffff0000, v197
	v_add_f32_e32 v135, 1.0, v135
	v_pk_mul_f32 v[142:143], v[140:141], v[142:143] op_sel_hi:[0,1]
	v_rcp_f32_e32 v134, v134
	v_rcp_f32_e32 v135, v135
	v_lshlrev_b32_e32 v132, 16, v191
	v_and_b32_e32 v133, 0xffff0000, v191
	v_pk_mul_f32 v[142:143], v[46:47], v[142:143]
; __device__ __forceinline__ float bflo(unsigned w) { return __uint_as_float(w << 16); }
; __device__ __forceinline__ float bfhi(unsigned w) { return __uint_as_float(w & 0xffff0000u); }
; __device__ __forceinline__ unsigned dpp_ror8(unsigned x) { return (unsigned)__builtin_amdgcn_update_dpp(0, (int)x, 0x128, 0xf, 0xf, false); }
;     __device__ __forceinline__ void operator()(const f32x4 (&acc)[2][2][4][2], const Unit& u, int wr, int wc, int fr, int fq) const {
;     ...
;             for (int m = 0; m < 4; ++m) { const int row = row0 + ai * HALF + m * 16; const float ri = __builtin_amdgcn_rsqf(sse[row] * (1.f / D) + EPS);
;                 u32x4 rr[2], ee[2]; load_pair_lines(R, D, row, fr, col0, rr[0], rr[1], 32); load_pair_lines(E, D, row, fr, col0, ee[0], ee[1], 32);
;                 float* orow = OUT + (size_t)(row - fr + (fr & 7)) * D + col0 + (lo ? 0 : 4);
; #pragma unroll
;                 for (int bj = 0; bj < 2; ++bj) { const u32x4 rw = rr[bj], ew = ee[bj];
;                     const float r[8] = {bflo(rw.x), bfhi(rw.x), bflo(rw.y), bfhi(rw.y), bflo(rw.z), bfhi(rw.z), bflo(rw.w), bfhi(rw.w)};
;                     const float e[8] = {bflo(ew.x), bfhi(ew.x), bflo(ew.y), bfhi(ew.y), bflo(ew.z), bfhi(ew.z), bflo(ew.w), bfhi(ew.w)};
;                     float o[8];
; #pragma unroll
;                     for (int j = 0; j < 8; ++j) { const float a = acc[ai][bj][m][j >> 2][j & 3]; const float gg = gv[bj][j >> 2][j & 3];
;                         o[j] = r[j] + e[j] * ri * gg * __builtin_amdgcn_rcpf(1.f + __builtin_amdgcn_exp2f(-a * LOG2E)); }
;                     f32x4 o1, o2;
; #pragma unroll
;                     for (int j = 0; j < 4; ++j) { const unsigned a = __float_as_uint(o[j]), b = __float_as_uint(o[4 + j]); const unsigned sa = dpp_ror8(a), sb = dpp_ror8(b);
;                         o1[j] = __uint_as_float(lo ? a : sb); o2[j] = __uint_as_float(lo ? sa : b); }
;                     *(f32x4*)(orow + 32 * bj) = o1; *(f32x4*)(orow + (size_t)8 * D + 32 * bj) = o2; } }
	v_add_co_u32_e32 v136, vcc, s45, v172
	v_pk_fma_f32 v[132:133], v[130:131], v[142:143], v[132:133]
	v_lshlrev_b32_e32 v142, 16, v194
	v_and_b32_e32 v143, 0xffff0000, v194
	v_cndmask_b32_e64 v185, v189, v202, s[0:1]
	v_cndmask_b32_e64 v184, v188, v192, s[0:1]
	v_addc_co_u32_e32 v137, vcc, 0, v173, vcc
	v_pk_mul_f32 v[140:141], v[140:141], v[142:143] op_sel_hi:[0,1]
	global_store_dwordx4 v[136:137], v[184:187], off
	v_mov_b32_e32 v188, v157
	v_lshlrev_b32_e32 v130, 16, v171
	v_mov_b32_e32 v184, v157
	v_mov_b32_e32 v185, v157
	v_mov_b32_e32 v187, v157
	v_and_b32_e32 v131, 0xffff0000, v171
	v_pk_mul_f32 v[140:141], v[42:43], v[140:141]
	v_mov_b32_dpp v184, v138 row_ror:8 row_mask:0xf bank_mask:0xf
	v_mov_b32_dpp v185, v139 row_ror:8 row_mask:0xf bank_mask:0xf
	v_mov_b32_e32 v183, v157
	v_mov_b32_e32 v186, v157
	v_mov_b32_dpp v187, v132 row_ror:8 row_mask:0xf bank_mask:0xf
	v_mov_b32_dpp v188, v133 row_ror:8 row_mask:0xf bank_mask:0xf
	v_pk_fma_f32 v[130:131], v[134:135], v[140:141], v[130:131]
	v_mov_b32_e32 v134, v157
	v_mov_b32_e32 v135, v157
	v_mov_b32_dpp v183, v128 row_ror:8 row_mask:0xf bank_mask:0xf
	v_mov_b32_dpp v186, v129 row_ror:8 row_mask:0xf bank_mask:0xf
	v_mov_b32_dpp v134, v130 row_ror:8 row_mask:0xf bank_mask:0xf
	v_mov_b32_dpp v135, v131 row_ror:8 row_mask:0xf bank_mask:0xf
	v_cndmask_b32_e64 v131, v188, v131, s[0:1]
	v_cndmask_b32_e64 v130, v187, v130, s[0:1]
	v_cndmask_b32_e64 v129, v185, v129, s[0:1]
	v_cndmask_b32_e64 v128, v184, v128, s[0:1]
	v_cndmask_b32_e64 v135, v133, v135, s[0:1]
	v_cndmask_b32_e64 v134, v132, v134, s[0:1]
	v_cndmask_b32_e64 v133, v139, v186, s[0:1]
	v_cndmask_b32_e64 v132, v138, v183, s[0:1]
	global_store_dwordx4 v[172:173], v[128:131], off offset:128
	global_store_dwordx4 v[136:137], v[132:135], off offset:128
	v_mov_b32_e32 v183, v157
	v_or_b32_e32 v128, 16, v170
	v_ashrrev_i32_e32 v129, 31, v128
	v_lshl_add_u64 v[130:131], v[128:129], 2, s[6:7]
	v_sub_u32_e32 v128, v128, v174
	v_add_u32_e32 v142, v128, v176
	v_ashrrev_i32_e32 v143, 31, v142
	v_lshlrev_b64 v[128:129], 12, v[142:143]
	v_lshl_add_u64 v[172:173], v[128:129], 0, s[16:17]
	s_waitcnt vmcnt(4)
	s_nop 0
	v_mov_b32_e32 v171, v228
	v_lshl_add_u64 v[130:131], s[8:9], 0, v[128:129]
	v_lshl_add_u64 v[134:135], s[8:9], 0, v[172:173]
	v_lshl_add_u64 v[128:129], s[10:11], 0, v[128:129]
	v_lshl_add_u64 v[130:131], v[130:131], 0, v[164:165]
	v_lshl_add_u64 v[134:135], v[134:135], 0, v[164:165]
	v_lshl_add_u64 v[128:129], v[128:129], 0, v[164:165]
	v_mov_b64_e32 v[130:131], v[232:233]
	v_mov_b64_e32 v[132:133], v[234:235]
	v_mov_b32_e32 v189, v157
	v_mov_b64_e32 v[134:135], v[236:237]
	v_mov_b64_e32 v[136:137], v[238:239]
	v_mov_b32_e32 v190, v157
	v_mov_b64_e32 v[138:139], v[240:241]
	v_mov_b64_e32 v[140:141], v[242:243]
	v_lshl_add_u64 v[128:129], s[10:11], 0, v[172:173]
	v_lshl_add_u64 v[128:129], v[128:129], 0, v[164:165]
	v_mov_b64_e32 v[184:185], v[244:245]
	v_mov_b64_e32 v[186:187], v[246:247]
	s_nop 1
	v_or_b32_e32 v216, 32, v170
	v_ashrrev_i32_e32 v217, 31, v216
	v_lshl_add_u64 v[218:219], v[216:217], 2, s[6:7]
	v_sub_u32_e32 v216, v216, v174
	v_add_u32_e32 v224, v216, v176
	v_ashrrev_i32_e32 v225, 31, v224
	v_lshlrev_b64 v[216:217], 12, v[224:225]
	v_lshl_add_u64 v[222:223], v[216:217], 0, s[16:17]
	v_lshl_add_u64 v[220:221], s[8:9], 0, v[222:223]
	global_load_dword v228, v[218:219], off
	v_lshl_add_u64 v[218:219], s[8:9], 0, v[216:217]
	v_lshl_add_u64 v[220:221], v[220:221], 0, v[164:165]
	v_lshl_add_u64 v[216:217], s[10:11], 0, v[216:217]
	v_lshl_add_u64 v[218:219], v[218:219], 0, v[164:165]
	global_load_dwordx4 v[232:235], v[220:221], off
	v_lshl_add_u64 v[216:217], v[216:217], 0, v[164:165]
	global_load_dwordx4 v[236:239], v[218:219], off
	global_load_dwordx4 v[240:243], v[216:217], off
	v_lshl_add_u64 v[216:217], s[10:11], 0, v[222:223]
	v_lshl_add_u64 v[216:217], v[216:217], 0, v[164:165]
	global_load_dwordx4 v[244:247], v[216:217], off
	v_mov_b32_e32 v173, v157
	v_mov_b32_e32 v129, v157
	v_mov_b32_e32 v172, v157
	v_mov_b32_e32 v188, v157
	v_mul_f32_e32 v120, 0xbfb8aa3b, v120
	v_mul_f32_e32 v121, 0xbfb8aa3b, v121
	v_mul_f32_e32 v124, 0xbfb8aa3b, v124
	v_exp_f32_e32 v120, v120
	v_exp_f32_e32 v121, v121
	v_mul_f32_e32 v122, 0xbfb8aa3b, v122
	v_mul_f32_e32 v123, 0xbfb8aa3b, v123
	v_add_f32_e32 v120, 1.0, v120
	v_add_f32_e32 v121, 1.0, v121
	v_rcp_f32_e32 v120, v120
	v_rcp_f32_e32 v121, v121
	v_exp_f32_e32 v122, v122
	v_exp_f32_e32 v123, v123
	v_mul_f32_e32 v126, 0xbfb8aa3b, v126
	v_mul_f32_e32 v127, 0xbfb8aa3b, v127
	v_exp_f32_e32 v126, v126
	v_exp_f32_e32 v127, v127
	v_add_f32_e32 v122, 1.0, v122
	v_add_f32_e32 v123, 1.0, v123
	v_rcp_f32_e32 v122, v122
	v_rcp_f32_e32 v123, v123
	v_add_f32_e32 v126, 1.0, v126
	v_add_f32_e32 v127, 1.0, v127
	v_mul_f32_e32 v112, 0xbfb8aa3b, v112
	v_mul_f32_e32 v113, 0xbfb8aa3b, v113
	v_rcp_f32_e32 v126, v126
	v_rcp_f32_e32 v127, v127
	v_exp_f32_e32 v112, v112
	v_exp_f32_e32 v113, v113
	v_mul_f32_e32 v116, 0xbfb8aa3b, v116
	v_mul_f32_e32 v117, 0xbfb8aa3b, v117
	v_exp_f32_e32 v116, v116
	v_exp_f32_e32 v117, v117
	v_add_f32_e32 v112, 1.0, v112
	v_add_f32_e32 v113, 1.0, v113
	v_rcp_f32_e32 v112, v112
	v_rcp_f32_e32 v113, v113
	v_mul_f32_e32 v114, 0xbfb8aa3b, v114
	v_mul_f32_e32 v115, 0xbfb8aa3b, v115
	v_add_f32_e32 v116, 1.0, v116
	v_add_f32_e32 v117, 1.0, v117
	v_exp_f32_e32 v114, v114
	v_exp_f32_e32 v115, v115
	v_rcp_f32_e32 v116, v116
	v_rcp_f32_e32 v117, v117
	v_mul_f32_e32 v118, 0xbfb8aa3b, v118
	v_mul_f32_e32 v119, 0xbfb8aa3b, v119
	v_exp_f32_e32 v118, v118
	v_exp_f32_e32 v119, v119
	v_add_f32_e32 v114, 1.0, v114
	v_add_f32_e32 v115, 1.0, v115
	v_rcp_f32_e32 v114, v114
	v_rcp_f32_e32 v115, v115
	v_add_f32_e32 v118, 1.0, v118
	v_add_f32_e32 v119, 1.0, v119
	v_rcp_f32_e32 v118, v118
	v_rcp_f32_e32 v119, v119
	v_mul_f32_e32 v104, 0xbfb8aa3b, v104
	v_mul_f32_e32 v105, 0xbfb8aa3b, v105
	v_mul_f32_e32 v108, 0xbfb8aa3b, v108
	v_exp_f32_e32 v104, v104
	s_waitcnt vmcnt(14)
; __device__ __forceinline__ float bflo(unsigned w) { return __uint_as_float(w << 16); }
; __device__ __forceinline__ float bfhi(unsigned w) { return __uint_as_float(w & 0xffff0000u); }
; __device__ __forceinline__ unsigned dpp_ror8(unsigned x) { return (unsigned)__builtin_amdgcn_update_dpp(0, (int)x, 0x128, 0xf, 0xf, false); }
;     __device__ __forceinline__ void operator()(const f32x4 (&acc)[2][2][4][2], const Unit& u, int wr, int wc, int fr, int fq) const {
;     ...
;             for (int m = 0; m < 4; ++m) { const int row = row0 + ai * HALF + m * 16; const float ri = __builtin_amdgcn_rsqf(sse[row] * (1.f / D) + EPS);
;                 u32x4 rr[2], ee[2]; load_pair_lines(R, D, row, fr, col0, rr[0], rr[1], 32); load_pair_lines(E, D, row, fr, col0, ee[0], ee[1], 32);
;                 float* orow = OUT + (size_t)(row - fr + (fr & 7)) * D + col0 + (lo ? 0 : 4);
; #pragma unroll
;                 for (int bj = 0; bj < 2; ++bj) { const u32x4 rw = rr[bj], ew = ee[bj];
;                     const float r[8] = {bflo(rw.x), bfhi(rw.x), bflo(rw.y), bfhi(rw.y), bflo(rw.z), bfhi(rw.z), bflo(rw.w), bfhi(rw.w)};
;                     const float e[8] = {bflo(ew.x), bfhi(ew.x), bflo(ew.y), bfhi(ew.y), bflo(ew.z), bfhi(ew.z), bflo(ew.w), bfhi(ew.w)};
;                     float o[8];
; #pragma unroll
;                     for (int j = 0; j < 8; ++j) { const float a = acc[ai][bj][m][j >> 2][j & 3]; const float gg = gv[bj][j >> 2][j & 3];
;                         o[j] = r[j] + e[j] * ri * gg * __builtin_amdgcn_rcpf(1.f + __builtin_amdgcn_exp2f(-a * LOG2E)); }
;                     f32x4 o1, o2;
; #pragma unroll
;                     for (int j = 0; j < 4; ++j) { const unsigned a = __float_as_uint(o[j]), b = __float_as_uint(o[4 + j]); const unsigned sa = dpp_ror8(a), sb = dpp_ror8(b);
;                         o1[j] = __uint_as_float(lo ? a : sb); o2[j] = __uint_as_float(lo ? sa : b); }
;                     *(f32x4*)(orow + 32 * bj) = o1; *(f32x4*)(orow + (size_t)8 * D + 32 * bj) = o2; } }
	v_fmamk_f32 v128, v171, 0x3a000000, v182
	v_mov_b32_e32 v171, v157
	v_rsq_f32_e32 v128, v128
	v_exp_f32_e32 v105, v105
	v_add_f32_e32 v104, 1.0, v104
	v_rcp_f32_e32 v104, v104
	v_mul_f32_e32 v106, 0xbfb8aa3b, v106
	v_mov_b32_dpp v171, v131 row_ror:8 row_mask:0xf bank_mask:0xf
	v_mov_b32_dpp v173, v133 row_ror:8 row_mask:0xf bank_mask:0xf
	v_mov_b32_dpp v183, v134 row_ror:8 row_mask:0xf bank_mask:0xf
	v_mov_b32_dpp v189, v136 row_ror:8 row_mask:0xf bank_mask:0xf
	v_mov_b32_dpp v190, v137 row_ror:8 row_mask:0xf bank_mask:0xf
	v_mov_b32_dpp v129, v130 row_ror:8 row_mask:0xf bank_mask:0xf
	v_mov_b32_dpp v172, v132 row_ror:8 row_mask:0xf bank_mask:0xf
	v_mov_b32_dpp v188, v135 row_ror:8 row_mask:0xf bank_mask:0xf
	v_cndmask_b32_e64 v190, v190, v133, s[0:1]
	v_cndmask_b32_e64 v183, v183, v130, s[0:1]
	v_cndmask_b32_e64 v133, v189, v132, s[0:1]
	v_cndmask_b32_e64 v171, v135, v171, s[0:1]
	v_cndmask_b32_e64 v137, v137, v173, s[0:1]
	v_mov_b32_e32 v130, v157
	v_mov_b32_e32 v132, v157
	v_mov_b32_e32 v135, v157
	v_mov_b32_e32 v173, v157
	v_cndmask_b32_e64 v129, v134, v129, s[0:1]
	v_cndmask_b32_e64 v136, v136, v172, s[0:1]
	v_mov_b32_dpp v130, v138 row_ror:8 row_mask:0xf bank_mask:0xf
	v_mov_b32_dpp v132, v140 row_ror:8 row_mask:0xf bank_mask:0xf
	v_mov_b32_e32 v134, v157
	v_mov_b32_dpp v135, v184 row_ror:8 row_mask:0xf bank_mask:0xf
	v_mov_b32_e32 v172, v157
	v_mov_b32_dpp v173, v186 row_ror:8 row_mask:0xf bank_mask:0xf
	v_cndmask_b32_e64 v188, v188, v131, s[0:1]
	v_mov_b32_e32 v131, v157
	v_mov_b32_dpp v134, v141 row_ror:8 row_mask:0xf bank_mask:0xf
	v_mov_b32_dpp v172, v185 row_ror:8 row_mask:0xf bank_mask:0xf
	v_cndmask_b32_e64 v138, v135, v138, s[0:1]
	v_cndmask_b32_e64 v135, v173, v140, s[0:1]
	v_cndmask_b32_e64 v173, v184, v130, s[0:1]
	v_cndmask_b32_e64 v184, v186, v132, s[0:1]
	v_exp_f32_e32 v132, v124
	v_mul_f32_e32 v124, 0xbfb8aa3b, v125
	v_mov_b32_dpp v131, v139 row_ror:8 row_mask:0xf bank_mask:0xf
	v_cndmask_b32_e64 v139, v172, v139, s[0:1]
	v_cndmask_b32_e64 v172, v187, v134, s[0:1]
	v_exp_f32_e32 v134, v124
	v_cndmask_b32_e64 v140, v185, v131, s[0:1]
	v_lshlrev_b64 v[130:131], 13, v[142:143]
	v_lshl_add_u64 v[130:131], s[4:5], 0, v[130:131]
	v_lshl_add_u64 v[130:131], v[130:131], 0, v[166:167]
	v_lshl_add_u64 v[124:125], v[130:131], 0, v[156:157]
	v_add_f32_e32 v131, 1.0, v134
	v_lshlrev_b32_e32 v134, 16, v135
	v_and_b32_e32 v135, 0xffff0000, v135
	v_add_f32_e32 v130, 1.0, v132
	v_pk_mul_f32 v[134:135], v[128:129], v[134:135] op_sel_hi:[0,1]
	v_rcp_f32_e32 v130, v130
	v_rcp_f32_e32 v131, v131
	v_lshlrev_b32_e32 v132, 16, v133
	v_and_b32_e32 v133, 0xffff0000, v133
	v_pk_mul_f32 v[134:135], v[60:61], v[134:135]
	v_mov_b32_e32 v189, v157
	v_pk_fma_f32 v[134:135], v[120:121], v[134:135], v[132:133]
	v_lshlrev_b32_e32 v132, 16, v138
	v_and_b32_e32 v133, 0xffff0000, v138
	v_mov_b32_dpp v189, v187 row_ror:8 row_mask:0xf bank_mask:0xf
	v_pk_mul_f32 v[132:133], v[128:129], v[132:133] op_sel_hi:[0,1]
	v_cndmask_b32_e64 v141, v189, v141, s[0:1]
	v_lshlrev_b32_e32 v120, 16, v183
	v_and_b32_e32 v121, 0xffff0000, v183
	v_pk_mul_f32 v[132:133], v[56:57], v[132:133]
	v_mov_b32_e32 v142, v157
	v_pk_fma_f32 v[120:121], v[130:131], v[132:133], v[120:121]
	v_lshlrev_b32_e32 v132, 16, v141
	v_and_b32_e32 v133, 0xffff0000, v141
	v_pk_mul_f32 v[132:133], v[128:129], v[132:133] op_sel_hi:[0,1]
	v_lshlrev_b32_e32 v130, 16, v190
	v_and_b32_e32 v131, 0xffff0000, v190
	v_pk_mul_f32 v[132:133], v[62:63], v[132:133]
	v_mov_b32_e32 v143, v157
	v_pk_fma_f32 v[130:131], v[122:123], v[132:133], v[130:131]
	v_lshlrev_b32_e32 v132, 16, v139
	v_and_b32_e32 v133, 0xffff0000, v139
	v_pk_mul_f32 v[132:133], v[128:129], v[132:133] op_sel_hi:[0,1]
	v_lshlrev_b32_e32 v122, 16, v188
	v_and_b32_e32 v123, 0xffff0000, v188
	v_pk_mul_f32 v[132:133], v[58:59], v[132:133]
	v_mov_b32_e32 v141, v157
	v_pk_fma_f32 v[122:123], v[126:127], v[132:133], v[122:123]
	v_mov_b32_e32 v126, v157
	v_mov_b32_e32 v127, v157
	v_mov_b32_e32 v185, v157
	v_mov_b32_dpp v126, v122 row_ror:8 row_mask:0xf bank_mask:0xf
	v_mov_b32_dpp v127, v123 row_ror:8 row_mask:0xf bank_mask:0xf
	v_mov_b32_dpp v142, v134 row_ror:8 row_mask:0xf bank_mask:0xf
	v_mov_b32_dpp v143, v135 row_ror:8 row_mask:0xf bank_mask:0xf
	v_mov_b32_e32 v138, v157
	v_mov_b32_e32 v183, v157
	v_mov_b32_dpp v141, v130 row_ror:8 row_mask:0xf bank_mask:0xf
	v_mov_b32_dpp v185, v131 row_ror:8 row_mask:0xf bank_mask:0xf
	v_cndmask_b32_e64 v133, v131, v127, s[0:1]
	v_cndmask_b32_e64 v132, v130, v126, s[0:1]
	v_lshlrev_b32_e32 v126, 16, v184
	v_and_b32_e32 v127, 0xffff0000, v184
	v_mov_b32_dpp v138, v120 row_ror:8 row_mask:0xf bank_mask:0xf
	v_mov_b32_dpp v183, v121 row_ror:8 row_mask:0xf bank_mask:0xf
	v_cndmask_b32_e64 v123, v185, v123, s[0:1]
	v_cndmask_b32_e64 v122, v141, v122, s[0:1]
	v_cndmask_b32_e64 v121, v143, v121, s[0:1]
	v_cndmask_b32_e64 v120, v142, v120, s[0:1]
	v_pk_mul_f32 v[126:127], v[128:129], v[126:127] op_sel_hi:[0,1]
	global_store_dwordx4 v[124:125], v[120:123], off
	v_pk_mul_f32 v[126:127], v[44:45], v[126:127]
	v_cndmask_b32_e64 v131, v135, v183, s[0:1]
	v_lshlrev_b32_e32 v122, 16, v136
	v_and_b32_e32 v123, 0xffff0000, v136
	v_pk_fma_f32 v[122:123], v[112:113], v[126:127], v[122:123]
	v_lshlrev_b32_e32 v126, 16, v173
	v_and_b32_e32 v127, 0xffff0000, v173
	v_pk_mul_f32 v[126:127], v[128:129], v[126:127] op_sel_hi:[0,1]
	v_lshlrev_b32_e32 v112, 16, v129
	v_and_b32_e32 v113, 0xffff0000, v129
	v_pk_mul_f32 v[126:127], v[40:41], v[126:127]
	v_mov_b32_e32 v129, v157
	v_pk_fma_f32 v[112:113], v[116:117], v[126:127], v[112:113]
	v_lshlrev_b32_e32 v126, 16, v172
	v_and_b32_e32 v127, 0xffff0000, v172
; __device__ __forceinline__ float bflo(unsigned w) { return __uint_as_float(w << 16); }
; __device__ __forceinline__ float bfhi(unsigned w) { return __uint_as_float(w & 0xffff0000u); }
; __device__ __forceinline__ unsigned dpp_ror8(unsigned x) { return (unsigned)__builtin_amdgcn_update_dpp(0, (int)x, 0x128, 0xf, 0xf, false); }
;     __device__ __forceinline__ void operator()(const f32x4 (&acc)[2][2][4][2], const Unit& u, int wr, int wc, int fr, int fq) const {
;     ...
;             for (int m = 0; m < 4; ++m) { const int row = row0 + ai * HALF + m * 16; const float ri = __builtin_amdgcn_rsqf(sse[row] * (1.f / D) + EPS);
;                 u32x4 rr[2], ee[2]; load_pair_lines(R, D, row, fr, col0, rr[0], rr[1], 32); load_pair_lines(E, D, row, fr, col0, ee[0], ee[1], 32);
;                 float* orow = OUT + (size_t)(row - fr + (fr & 7)) * D + col0 + (lo ? 0 : 4);
; #pragma unroll
;                 for (int bj = 0; bj < 2; ++bj) { const u32x4 rw = rr[bj], ew = ee[bj];
;                     const float r[8] = {bflo(rw.x), bfhi(rw.x), bflo(rw.y), bfhi(rw.y), bflo(rw.z), bfhi(rw.z), bflo(rw.w), bfhi(rw.w)};
;                     const float e[8] = {bflo(ew.x), bfhi(ew.x), bflo(ew.y), bfhi(ew.y), bflo(ew.z), bfhi(ew.z), bflo(ew.w), bfhi(ew.w)};
;                     float o[8];
; #pragma unroll
;                     for (int j = 0; j < 8; ++j) { const float a = acc[ai][bj][m][j >> 2][j & 3]; const float gg = gv[bj][j >> 2][j & 3];
;                         o[j] = r[j] + e[j] * ri * gg * __builtin_amdgcn_rcpf(1.f + __builtin_amdgcn_exp2f(-a * LOG2E)); }
;                     f32x4 o1, o2;
; #pragma unroll
;                     for (int j = 0; j < 4; ++j) { const unsigned a = __float_as_uint(o[j]), b = __float_as_uint(o[4 + j]); const unsigned sa = dpp_ror8(a), sb = dpp_ror8(b);
;                         o1[j] = __uint_as_float(lo ? a : sb); o2[j] = __uint_as_float(lo ? sa : b); }
;                     *(f32x4*)(orow + 32 * bj) = o1; *(f32x4*)(orow + (size_t)8 * D + 32 * bj) = o2; } }
	v_mov_b32_dpp v129, v112 row_ror:8 row_mask:0xf bank_mask:0xf
	v_pk_mul_f32 v[126:127], v[128:129], v[126:127] op_sel_hi:[0,1]
	v_lshlrev_b32_e32 v116, 16, v137
	v_and_b32_e32 v117, 0xffff0000, v137
	v_pk_mul_f32 v[126:127], v[46:47], v[126:127]
	v_add_co_u32_e32 v120, vcc, s45, v124
	v_pk_fma_f32 v[116:117], v[114:115], v[126:127], v[116:117]
	v_lshlrev_b32_e32 v126, 16, v140
	v_and_b32_e32 v127, 0xffff0000, v140
	v_cndmask_b32_e64 v130, v134, v138, s[0:1]
	v_addc_co_u32_e32 v121, vcc, 0, v125, vcc
	v_pk_mul_f32 v[126:127], v[128:129], v[126:127] op_sel_hi:[0,1]
	global_store_dwordx4 v[120:121], v[130:133], off
	v_mov_b32_e32 v134, v157
	v_lshlrev_b32_e32 v114, 16, v171
	v_mov_b32_e32 v130, v157
	v_mov_b32_e32 v131, v157
	v_mov_b32_e32 v133, v157
	v_and_b32_e32 v115, 0xffff0000, v171
	v_pk_mul_f32 v[126:127], v[42:43], v[126:127]
	v_mov_b32_dpp v130, v122 row_ror:8 row_mask:0xf bank_mask:0xf
	v_mov_b32_dpp v131, v123 row_ror:8 row_mask:0xf bank_mask:0xf
	v_mov_b32_e32 v132, v157
	v_mov_b32_dpp v133, v116 row_ror:8 row_mask:0xf bank_mask:0xf
	v_mov_b32_dpp v134, v117 row_ror:8 row_mask:0xf bank_mask:0xf
	v_pk_fma_f32 v[114:115], v[118:119], v[126:127], v[114:115]
	v_mov_b32_e32 v118, v157
	v_mov_b32_e32 v119, v157
	v_mov_b32_dpp v132, v113 row_ror:8 row_mask:0xf bank_mask:0xf
	v_mov_b32_dpp v118, v114 row_ror:8 row_mask:0xf bank_mask:0xf
	v_mov_b32_dpp v119, v115 row_ror:8 row_mask:0xf bank_mask:0xf
	v_cndmask_b32_e64 v115, v134, v115, s[0:1]
	v_cndmask_b32_e64 v114, v133, v114, s[0:1]
	v_cndmask_b32_e64 v113, v131, v113, s[0:1]
	v_cndmask_b32_e64 v112, v130, v112, s[0:1]
	v_cndmask_b32_e64 v119, v117, v119, s[0:1]
	v_cndmask_b32_e64 v118, v116, v118, s[0:1]
	v_cndmask_b32_e64 v117, v123, v132, s[0:1]
	v_cndmask_b32_e64 v116, v122, v129, s[0:1]
	global_store_dwordx4 v[124:125], v[112:115], off offset:128
	global_store_dwordx4 v[120:121], v[116:119], off offset:128
	v_mov_b32_e32 v137, v157
	v_or_b32_e32 v112, 32, v170
	v_ashrrev_i32_e32 v113, 31, v112
	v_lshl_add_u64 v[114:115], v[112:113], 2, s[6:7]
	v_sub_u32_e32 v112, v112, v174
	v_add_u32_e32 v130, v112, v176
	v_ashrrev_i32_e32 v131, 31, v130
	v_lshlrev_b64 v[112:113], 12, v[130:131]
	v_lshl_add_u64 v[126:127], v[112:113], 0, s[16:17]
	v_lshl_add_u64 v[118:119], s[8:9], 0, v[126:127]
	s_waitcnt vmcnt(4)
	s_nop 0
	v_mov_b32_e32 v132, v228
	v_lshl_add_u64 v[114:115], s[8:9], 0, v[112:113]
	v_lshl_add_u64 v[118:119], v[118:119], 0, v[164:165]
	v_lshl_add_u64 v[112:113], s[10:11], 0, v[112:113]
	v_lshl_add_u64 v[114:115], v[114:115], 0, v[164:165]
	v_mov_b64_e32 v[118:119], v[232:233]
	v_mov_b64_e32 v[120:121], v[234:235]
	v_lshl_add_u64 v[112:113], v[112:113], 0, v[164:165]
	v_mov_b64_e32 v[114:115], v[236:237]
	v_mov_b64_e32 v[116:117], v[238:239]
	v_mov_b32_e32 v138, v157
	v_mov_b64_e32 v[122:123], v[240:241]
	v_mov_b64_e32 v[124:125], v[242:243]
	v_lshl_add_u64 v[112:113], s[10:11], 0, v[126:127]
	v_lshl_add_u64 v[112:113], v[112:113], 0, v[164:165]
	v_mov_b64_e32 v[126:127], v[244:245]
	v_mov_b64_e32 v[128:129], v[246:247]
	s_nop 1
	v_or_b32_e32 v216, 48, v170
	v_ashrrev_i32_e32 v217, 31, v216
	v_lshl_add_u64 v[218:219], v[216:217], 2, s[6:7]
	v_sub_u32_e32 v216, v216, v174
	v_add_u32_e32 v224, v216, v176
	v_ashrrev_i32_e32 v225, 31, v224
	v_lshlrev_b64 v[216:217], 12, v[224:225]
	v_lshl_add_u64 v[222:223], v[216:217], 0, s[16:17]
	v_lshl_add_u64 v[220:221], s[8:9], 0, v[222:223]
	global_load_dword v228, v[218:219], off
	v_lshl_add_u64 v[218:219], s[8:9], 0, v[216:217]
	v_lshl_add_u64 v[220:221], v[220:221], 0, v[164:165]
	v_lshl_add_u64 v[216:217], s[10:11], 0, v[216:217]
	v_lshl_add_u64 v[218:219], v[218:219], 0, v[164:165]
	global_load_dwordx4 v[232:235], v[220:221], off
	v_lshl_add_u64 v[216:217], v[216:217], 0, v[164:165]
	global_load_dwordx4 v[236:239], v[218:219], off
	global_load_dwordx4 v[240:243], v[216:217], off
	v_lshl_add_u64 v[216:217], s[10:11], 0, v[222:223]
	v_lshl_add_u64 v[216:217], v[216:217], 0, v[164:165]
	global_load_dwordx4 v[244:247], v[216:217], off
	v_mov_b32_e32 v113, v157
	v_mov_b32_e32 v133, v157
	v_mov_b32_e32 v134, v157
	v_mov_b32_e32 v136, v157
	v_mov_b32_e32 v135, v157
	v_add_f32_e32 v105, 1.0, v105
	v_mul_f32_e32 v107, 0xbfb8aa3b, v107
	v_rcp_f32_e32 v105, v105
	v_exp_f32_e32 v106, v106
	v_exp_f32_e32 v107, v107
	v_mul_f32_e32 v110, 0xbfb8aa3b, v110
	v_mul_f32_e32 v111, 0xbfb8aa3b, v111
	v_exp_f32_e32 v110, v110
	v_exp_f32_e32 v111, v111
	v_add_f32_e32 v106, 1.0, v106
	v_add_f32_e32 v107, 1.0, v107
	v_rcp_f32_e32 v106, v106
	v_rcp_f32_e32 v107, v107
	v_add_f32_e32 v110, 1.0, v110
	v_add_f32_e32 v111, 1.0, v111
	v_mul_f32_e32 v96, 0xbfb8aa3b, v96
	v_mul_f32_e32 v97, 0xbfb8aa3b, v97
	v_rcp_f32_e32 v110, v110
	v_rcp_f32_e32 v111, v111
	v_exp_f32_e32 v96, v96
	v_exp_f32_e32 v97, v97
	v_mul_f32_e32 v100, 0xbfb8aa3b, v100
	v_mul_f32_e32 v101, 0xbfb8aa3b, v101
	v_exp_f32_e32 v100, v100
	v_exp_f32_e32 v101, v101
	v_add_f32_e32 v96, 1.0, v96
	v_add_f32_e32 v97, 1.0, v97
	v_rcp_f32_e32 v96, v96
	v_rcp_f32_e32 v97, v97
	v_mul_f32_e32 v98, 0xbfb8aa3b, v98
	v_mul_f32_e32 v99, 0xbfb8aa3b, v99
	v_add_f32_e32 v100, 1.0, v100
	v_add_f32_e32 v101, 1.0, v101
	v_exp_f32_e32 v98, v98
	v_exp_f32_e32 v99, v99
	v_rcp_f32_e32 v100, v100
	v_rcp_f32_e32 v101, v101
	v_mul_f32_e32 v102, 0xbfb8aa3b, v102
	v_mul_f32_e32 v103, 0xbfb8aa3b, v103
	v_exp_f32_e32 v102, v102
	v_exp_f32_e32 v103, v103
	v_add_f32_e32 v98, 1.0, v98
	v_add_f32_e32 v99, 1.0, v99
	v_rcp_f32_e32 v98, v98
	v_rcp_f32_e32 v99, v99
	v_add_f32_e32 v102, 1.0, v102
	v_add_f32_e32 v103, 1.0, v103
	v_rcp_f32_e32 v102, v102
	v_rcp_f32_e32 v103, v103
	v_mul_f32_e32 v88, 0xbfb8aa3b, v88
	v_mul_f32_e32 v89, 0xbfb8aa3b, v89
	v_mul_f32_e32 v92, 0xbfb8aa3b, v92
	v_exp_f32_e32 v88, v88
	v_exp_f32_e32 v89, v89
	v_mul_f32_e32 v90, 0xbfb8aa3b, v90
	v_mul_f32_e32 v91, 0xbfb8aa3b, v91
	v_add_f32_e32 v88, 1.0, v88
	v_add_f32_e32 v89, 1.0, v89
	v_rcp_f32_e32 v88, v88
	v_rcp_f32_e32 v89, v89
	v_exp_f32_e32 v90, v90
	v_exp_f32_e32 v91, v91
	s_waitcnt vmcnt(23)
; __device__ __forceinline__ float bflo(unsigned w) { return __uint_as_float(w << 16); }
; __device__ __forceinline__ float bfhi(unsigned w) { return __uint_as_float(w & 0xffff0000u); }
; __device__ __forceinline__ unsigned dpp_ror8(unsigned x) { return (unsigned)__builtin_amdgcn_update_dpp(0, (int)x, 0x128, 0xf, 0xf, false); }
;     __device__ __forceinline__ void operator()(const f32x4 (&acc)[2][2][4][2], const Unit& u, int wr, int wc, int fr, int fq) const {
;     ...
;             for (int m = 0; m < 4; ++m) { const int row = row0 + ai * HALF + m * 16; const float ri = __builtin_amdgcn_rsqf(sse[row] * (1.f / D) + EPS);
;                 u32x4 rr[2], ee[2]; load_pair_lines(R, D, row, fr, col0, rr[0], rr[1], 32); load_pair_lines(E, D, row, fr, col0, ee[0], ee[1], 32);
;                 float* orow = OUT + (size_t)(row - fr + (fr & 7)) * D + col0 + (lo ? 0 : 4);
; #pragma unroll
;                 for (int bj = 0; bj < 2; ++bj) { const u32x4 rw = rr[bj], ew = ee[bj];
;                     const float r[8] = {bflo(rw.x), bfhi(rw.x), bflo(rw.y), bfhi(rw.y), bflo(rw.z), bfhi(rw.z), bflo(rw.w), bfhi(rw.w)};
;                     const float e[8] = {bflo(ew.x), bfhi(ew.x), bflo(ew.y), bfhi(ew.y), bflo(ew.z), bfhi(ew.z), bflo(ew.w), bfhi(ew.w)};
;                     float o[8];
; #pragma unroll
;                     for (int j = 0; j < 8; ++j) { const float a = acc[ai][bj][m][j >> 2][j & 3]; const float gg = gv[bj][j >> 2][j & 3];
;                         o[j] = r[j] + e[j] * ri * gg * __builtin_amdgcn_rcpf(1.f + __builtin_amdgcn_exp2f(-a * LOG2E)); }
;                     f32x4 o1, o2;
; #pragma unroll
;                     for (int j = 0; j < 4; ++j) { const unsigned a = __float_as_uint(o[j]), b = __float_as_uint(o[4 + j]); const unsigned sa = dpp_ror8(a), sb = dpp_ror8(b);
;                         o1[j] = __uint_as_float(lo ? a : sb); o2[j] = __uint_as_float(lo ? sa : b); }
;                     *(f32x4*)(orow + 32 * bj) = o1; *(f32x4*)(orow + (size_t)8 * D + 32 * bj) = o2; } }
	v_fmamk_f32 v112, v132, 0x3a000000, v182
	v_mov_b32_e32 v132, v157
	v_rsq_f32_e32 v112, v112
	v_mul_f32_e32 v94, 0xbfb8aa3b, v94
	v_mul_f32_e32 v95, 0xbfb8aa3b, v95
	v_mov_b32_dpp v137, v120 row_ror:8 row_mask:0xf bank_mask:0xf
	v_mov_b32_dpp v138, v121 row_ror:8 row_mask:0xf bank_mask:0xf
	v_mov_b32_dpp v113, v114 row_ror:8 row_mask:0xf bank_mask:0xf
	v_mov_b32_dpp v132, v115 row_ror:8 row_mask:0xf bank_mask:0xf
	v_mov_b32_dpp v133, v116 row_ror:8 row_mask:0xf bank_mask:0xf
	v_mov_b32_dpp v134, v117 row_ror:8 row_mask:0xf bank_mask:0xf
	v_mov_b32_dpp v136, v119 row_ror:8 row_mask:0xf bank_mask:0xf
	v_cndmask_b32_e64 v138, v138, v117, s[0:1]
	v_cndmask_b32_e64 v117, v137, v116, s[0:1]
	v_mov_b32_e32 v116, v157
	v_mov_b32_dpp v135, v118 row_ror:8 row_mask:0xf bank_mask:0xf
	v_cndmask_b32_e64 v136, v136, v115, s[0:1]
	v_cndmask_b32_e64 v132, v119, v132, s[0:1]
	v_cndmask_b32_e64 v121, v121, v134, s[0:1]
	v_cndmask_b32_e64 v113, v118, v113, s[0:1]
	v_mov_b32_e32 v115, v157
	v_mov_b32_dpp v116, v124 row_ror:8 row_mask:0xf bank_mask:0xf
	v_mov_b32_e32 v118, v157
	v_mov_b32_e32 v119, v157
	v_mov_b32_e32 v134, v157
	v_cndmask_b32_e64 v135, v135, v114, s[0:1]
	v_cndmask_b32_e64 v120, v120, v133, s[0:1]
	v_mov_b32_e32 v114, v157
	v_mov_b32_dpp v115, v123 row_ror:8 row_mask:0xf bank_mask:0xf
	v_mov_b32_dpp v118, v125 row_ror:8 row_mask:0xf bank_mask:0xf
	v_mov_b32_dpp v119, v126 row_ror:8 row_mask:0xf bank_mask:0xf
	v_mov_b32_e32 v133, v157
	v_mov_b32_dpp v134, v128 row_ror:8 row_mask:0xf bank_mask:0xf
	v_cndmask_b32_e64 v128, v128, v116, s[0:1]
	v_exp_f32_e32 v116, v108
	v_mul_f32_e32 v108, 0xbfb8aa3b, v109
	v_mov_b32_dpp v114, v122 row_ror:8 row_mask:0xf bank_mask:0xf
	v_mov_b32_dpp v133, v127 row_ror:8 row_mask:0xf bank_mask:0xf
	v_cndmask_b32_e64 v122, v119, v122, s[0:1]
	v_cndmask_b32_e64 v119, v134, v124, s[0:1]
	v_cndmask_b32_e64 v124, v127, v115, s[0:1]
	v_cndmask_b32_e64 v127, v129, v118, s[0:1]
	v_exp_f32_e32 v118, v108
	v_cndmask_b32_e64 v126, v126, v114, s[0:1]
	v_lshlrev_b64 v[114:115], 13, v[130:131]
	v_lshl_add_u64 v[114:115], s[4:5], 0, v[114:115]
	v_lshl_add_u64 v[114:115], v[114:115], 0, v[166:167]
	v_lshl_add_u64 v[108:109], v[114:115], 0, v[156:157]
	v_add_f32_e32 v115, 1.0, v118
	v_lshlrev_b32_e32 v118, 16, v119
	v_and_b32_e32 v119, 0xffff0000, v119
	v_add_f32_e32 v114, 1.0, v116
	v_pk_mul_f32 v[118:119], v[112:113], v[118:119] op_sel_hi:[0,1]
	v_rcp_f32_e32 v114, v114
	v_rcp_f32_e32 v115, v115
	v_lshlrev_b32_e32 v116, 16, v117
	v_and_b32_e32 v117, 0xffff0000, v117
	v_pk_mul_f32 v[118:119], v[60:61], v[118:119]
	v_mov_b32_e32 v137, v157
	v_pk_fma_f32 v[118:119], v[104:105], v[118:119], v[116:117]
	v_lshlrev_b32_e32 v116, 16, v122
	v_and_b32_e32 v117, 0xffff0000, v122
	v_mov_b32_dpp v137, v129 row_ror:8 row_mask:0xf bank_mask:0xf
	v_pk_mul_f32 v[116:117], v[112:113], v[116:117] op_sel_hi:[0,1]
	v_cndmask_b32_e64 v125, v137, v125, s[0:1]
	v_lshlrev_b32_e32 v104, 16, v135
	v_and_b32_e32 v105, 0xffff0000, v135
	v_pk_mul_f32 v[116:117], v[56:57], v[116:117]
	v_cndmask_b32_e64 v123, v133, v123, s[0:1]
	v_pk_fma_f32 v[104:105], v[114:115], v[116:117], v[104:105]
	v_lshlrev_b32_e32 v116, 16, v125
	v_and_b32_e32 v117, 0xffff0000, v125
	v_pk_mul_f32 v[116:117], v[112:113], v[116:117] op_sel_hi:[0,1]
	v_lshlrev_b32_e32 v114, 16, v138
	v_and_b32_e32 v115, 0xffff0000, v138
	v_pk_mul_f32 v[116:117], v[62:63], v[116:117]
	v_mov_b32_e32 v129, v157
	v_pk_fma_f32 v[114:115], v[106:107], v[116:117], v[114:115]
	v_lshlrev_b32_e32 v116, 16, v123
	v_and_b32_e32 v117, 0xffff0000, v123
	v_pk_mul_f32 v[116:117], v[112:113], v[116:117] op_sel_hi:[0,1]
	v_lshlrev_b32_e32 v106, 16, v136
	v_and_b32_e32 v107, 0xffff0000, v136
	v_pk_mul_f32 v[116:117], v[58:59], v[116:117]
	v_mov_b32_e32 v130, v157
	v_pk_fma_f32 v[106:107], v[110:111], v[116:117], v[106:107]
	v_mov_b32_e32 v110, v157
	v_mov_b32_e32 v111, v157
	v_mov_b32_e32 v125, v157
	v_mov_b32_e32 v133, v157
	v_mov_b32_dpp v110, v106 row_ror:8 row_mask:0xf bank_mask:0xf
	v_mov_b32_dpp v111, v107 row_ror:8 row_mask:0xf bank_mask:0xf
	v_mov_b32_dpp v129, v118 row_ror:8 row_mask:0xf bank_mask:0xf
	v_mov_b32_dpp v130, v119 row_ror:8 row_mask:0xf bank_mask:0xf
	v_mov_b32_e32 v122, v157
	v_mov_b32_e32 v131, v157
	v_mov_b32_dpp v125, v114 row_ror:8 row_mask:0xf bank_mask:0xf
	v_mov_b32_dpp v133, v115 row_ror:8 row_mask:0xf bank_mask:0xf
	v_cndmask_b32_e64 v117, v115, v111, s[0:1]
	v_cndmask_b32_e64 v116, v114, v110, s[0:1]
	v_lshlrev_b32_e32 v110, 16, v128
	v_and_b32_e32 v111, 0xffff0000, v128
	v_mov_b32_dpp v122, v104 row_ror:8 row_mask:0xf bank_mask:0xf
	v_mov_b32_dpp v131, v105 row_ror:8 row_mask:0xf bank_mask:0xf
	v_cndmask_b32_e64 v107, v133, v107, s[0:1]
	v_cndmask_b32_e64 v106, v125, v106, s[0:1]
	v_cndmask_b32_e64 v105, v130, v105, s[0:1]
	v_cndmask_b32_e64 v104, v129, v104, s[0:1]
	v_pk_mul_f32 v[110:111], v[112:113], v[110:111] op_sel_hi:[0,1]
	global_store_dwordx4 v[108:109], v[104:107], off
	v_pk_mul_f32 v[110:111], v[44:45], v[110:111]
	v_cndmask_b32_e64 v115, v119, v131, s[0:1]
	v_lshlrev_b32_e32 v106, 16, v120
	v_and_b32_e32 v107, 0xffff0000, v120
	v_pk_fma_f32 v[106:107], v[96:97], v[110:111], v[106:107]
	v_lshlrev_b32_e32 v110, 16, v126
	v_and_b32_e32 v111, 0xffff0000, v126
	v_pk_mul_f32 v[110:111], v[112:113], v[110:111] op_sel_hi:[0,1]
	v_lshlrev_b32_e32 v96, 16, v113
	v_and_b32_e32 v97, 0xffff0000, v113
	v_pk_mul_f32 v[110:111], v[40:41], v[110:111]
	v_mov_b32_e32 v113, v157
	v_pk_fma_f32 v[96:97], v[100:101], v[110:111], v[96:97]
	v_lshlrev_b32_e32 v110, 16, v127
	v_and_b32_e32 v111, 0xffff0000, v127
	v_mov_b32_dpp v113, v96 row_ror:8 row_mask:0xf bank_mask:0xf
; __device__ __forceinline__ float bflo(unsigned w) { return __uint_as_float(w << 16); }
; __device__ __forceinline__ float bfhi(unsigned w) { return __uint_as_float(w & 0xffff0000u); }
;     const bool lo = fr < 8;
;     const int r1 = row - fr + (fr & 7), cb = col0 + (lo ? 0 : boff);
;     const u32x4 l1 = *(const u32x4*)(P + (size_t)r1 * ld + cb), l2 = *(const u32x4*)(P + (size_t)(r1 + 8) * ld + cb);
;     const u32x4 s1 = {dpp_ror8(l1.x), dpp_ror8(l1.y), dpp_ror8(l1.z), dpp_ror8(l1.w)}, s2 = {dpp_ror8(l2.x), dpp_ror8(l2.y), dpp_ror8(l2.z), dpp_ror8(l2.w)};
;     wA = lo ? l1 : s2; wB = lo ? s1 : l2;
; }
;     __device__ __forceinline__ void operator()(const f32x4 (&acc)[2][2][4][2], const Unit& u, int wr, int wc, int fr, int fq) const {
;     ...
;             for (int m = 0; m < 4; ++m) { const int row = row0 + ai * HALF + m * 16; const float ri = __builtin_amdgcn_rsqf(sse[row] * (1.f / D) + EPS);
;                 u32x4 rr[2], ee[2]; load_pair_lines(R, D, row, fr, col0, rr[0], rr[1], 32); load_pair_lines(E, D, row, fr, col0, ee[0], ee[1], 32);
;                 float* orow = OUT + (size_t)(row - fr + (fr & 7)) * D + col0 + (lo ? 0 : 4);
; #pragma unroll
;                 for (int bj = 0; bj < 2; ++bj) { const u32x4 rw = rr[bj], ew = ee[bj];
;                     const float r[8] = {bflo(rw.x), bfhi(rw.x), bflo(rw.y), bfhi(rw.y), bflo(rw.z), bfhi(rw.z), bflo(rw.w), bfhi(rw.w)};
;                     const float e[8] = {bflo(ew.x), bfhi(ew.x), bflo(ew.y), bfhi(ew.y), bflo(ew.z), bfhi(ew.z), bflo(ew.w), bfhi(ew.w)};
;                     float o[8];
; #pragma unroll
;                     for (int j = 0; j < 8; ++j) { const float a = acc[ai][bj][m][j >> 2][j & 3]; const float gg = gv[bj][j >> 2][j & 3];
;                         o[j] = r[j] + e[j] * ri * gg * __builtin_amdgcn_rcpf(1.f + __builtin_amdgcn_exp2f(-a * LOG2E)); }
;                     f32x4 o1, o2;
; #pragma unroll
;                     for (int j = 0; j < 4; ++j) { const unsigned a = __float_as_uint(o[j]), b = __float_as_uint(o[4 + j]); const unsigned sa = dpp_ror8(a), sb = dpp_ror8(b);
;                         o1[j] = __uint_as_float(lo ? a : sb); o2[j] = __uint_as_float(lo ? sa : b); }
;                     *(f32x4*)(orow + 32 * bj) = o1; *(f32x4*)(orow + (size_t)8 * D + 32 * bj) = o2; } }
	v_pk_mul_f32 v[110:111], v[112:113], v[110:111] op_sel_hi:[0,1]
	v_lshlrev_b32_e32 v100, 16, v121
	v_and_b32_e32 v101, 0xffff0000, v121
	v_pk_mul_f32 v[110:111], v[46:47], v[110:111]
	v_add_co_u32_e32 v104, vcc, s45, v108
	v_pk_fma_f32 v[100:101], v[98:99], v[110:111], v[100:101]
	v_lshlrev_b32_e32 v110, 16, v124
	v_and_b32_e32 v111, 0xffff0000, v124
	v_cndmask_b32_e64 v114, v118, v122, s[0:1]
	v_addc_co_u32_e32 v105, vcc, 0, v109, vcc
	v_pk_mul_f32 v[110:111], v[112:113], v[110:111] op_sel_hi:[0,1]
	global_store_dwordx4 v[104:105], v[114:117], off
	v_mov_b32_e32 v118, v157
	v_lshlrev_b32_e32 v98, 16, v132
	v_mov_b32_e32 v114, v157
	v_mov_b32_e32 v115, v157
	v_mov_b32_e32 v117, v157
	v_and_b32_e32 v99, 0xffff0000, v132
	v_pk_mul_f32 v[110:111], v[42:43], v[110:111]
	v_mov_b32_dpp v114, v106 row_ror:8 row_mask:0xf bank_mask:0xf
	v_mov_b32_dpp v115, v107 row_ror:8 row_mask:0xf bank_mask:0xf
	v_mov_b32_e32 v116, v157
	v_mov_b32_dpp v117, v100 row_ror:8 row_mask:0xf bank_mask:0xf
	v_mov_b32_dpp v118, v101 row_ror:8 row_mask:0xf bank_mask:0xf
	v_pk_fma_f32 v[98:99], v[102:103], v[110:111], v[98:99]
	v_mov_b32_e32 v102, v157
	v_mov_b32_e32 v103, v157
	v_mov_b32_dpp v116, v97 row_ror:8 row_mask:0xf bank_mask:0xf
	v_mov_b32_dpp v102, v98 row_ror:8 row_mask:0xf bank_mask:0xf
	v_mov_b32_dpp v103, v99 row_ror:8 row_mask:0xf bank_mask:0xf
	v_cndmask_b32_e64 v99, v118, v99, s[0:1]
	v_cndmask_b32_e64 v98, v117, v98, s[0:1]
	v_cndmask_b32_e64 v97, v115, v97, s[0:1]
	v_cndmask_b32_e64 v96, v114, v96, s[0:1]
	v_cndmask_b32_e64 v103, v101, v103, s[0:1]
	v_cndmask_b32_e64 v102, v100, v102, s[0:1]
	v_cndmask_b32_e64 v101, v107, v116, s[0:1]
	v_cndmask_b32_e64 v100, v106, v113, s[0:1]
	global_store_dwordx4 v[108:109], v[96:99], off offset:128
	global_store_dwordx4 v[104:105], v[100:103], off offset:128
	v_mov_b32_e32 v121, v157
	v_or_b32_e32 v96, 48, v170
	v_ashrrev_i32_e32 v97, 31, v96
	v_lshl_add_u64 v[98:99], v[96:97], 2, s[6:7]
	v_sub_u32_e32 v96, v96, v174
	v_add_u32_e32 v114, v96, v176
	v_ashrrev_i32_e32 v115, 31, v114
	v_lshlrev_b64 v[96:97], 12, v[114:115]
	v_lshl_add_u64 v[110:111], v[96:97], 0, s[16:17]
	v_lshl_add_u64 v[102:103], s[8:9], 0, v[110:111]
	s_waitcnt vmcnt(4)
	s_nop 0
	v_mov_b32_e32 v116, v228
	v_lshl_add_u64 v[98:99], s[8:9], 0, v[96:97]
	v_lshl_add_u64 v[102:103], v[102:103], 0, v[164:165]
	v_lshl_add_u64 v[96:97], s[10:11], 0, v[96:97]
	v_lshl_add_u64 v[98:99], v[98:99], 0, v[164:165]
	v_mov_b64_e32 v[102:103], v[232:233]
	v_mov_b64_e32 v[104:105], v[234:235]
	v_lshl_add_u64 v[96:97], v[96:97], 0, v[164:165]
	v_mov_b64_e32 v[98:99], v[236:237]
	v_mov_b64_e32 v[100:101], v[238:239]
	v_mov_b32_e32 v122, v157
	v_mov_b64_e32 v[106:107], v[240:241]
	v_mov_b64_e32 v[108:109], v[242:243]
	v_lshl_add_u64 v[96:97], s[10:11], 0, v[110:111]
	v_lshl_add_u64 v[96:97], v[96:97], 0, v[164:165]
	v_mov_b64_e32 v[110:111], v[244:245]
	v_mov_b64_e32 v[112:113], v[246:247]
	s_nop 1
	global_load_dword v228, v[168:169], off offset:512
	v_sub_u32_e32 v217, v170, v174
	v_add_u32_e32 v217, v217, v176
	v_add_u32_e32 v226, 0x80, v217
	v_ashrrev_i32_e32 v227, 31, v226
	v_lshlrev_b64 v[222:223], 12, v[226:227]
	v_lshl_add_u64 v[224:225], v[222:223], 0, s[16:17]
	v_lshl_add_u64 v[218:219], s[8:9], 0, v[222:223]
	v_lshl_add_u64 v[220:221], s[8:9], 0, v[224:225]
	v_lshl_add_u64 v[218:219], v[218:219], 0, v[164:165]
	v_lshl_add_u64 v[220:221], v[220:221], 0, v[164:165]
	global_load_dwordx4 v[232:235], v[218:219], off
	v_lshl_add_u64 v[222:223], s[10:11], 0, v[222:223]
	global_load_dwordx4 v[236:239], v[220:221], off
	v_lshl_add_u64 v[222:223], v[222:223], 0, v[164:165]
	v_lshl_add_u64 v[224:225], s[10:11], 0, v[224:225]
	global_load_dwordx4 v[240:243], v[222:223], off
	v_lshl_add_u64 v[224:225], v[224:225], 0, v[164:165]
	global_load_dwordx4 v[244:247], v[224:225], off
	v_mov_b32_e32 v97, v157
	v_mov_b32_e32 v117, v157
	v_mov_b32_e32 v118, v157
	v_mov_b32_e32 v120, v157
	v_mov_b32_e32 v119, v157
	v_exp_f32_e32 v94, v94
	v_exp_f32_e32 v95, v95
	v_add_f32_e32 v90, 1.0, v90
	v_add_f32_e32 v91, 1.0, v91
	v_rcp_f32_e32 v90, v90
	v_rcp_f32_e32 v91, v91
	v_add_f32_e32 v94, 1.0, v94
	v_add_f32_e32 v95, 1.0, v95
	v_mul_f32_e32 v80, 0xbfb8aa3b, v80
	v_mul_f32_e32 v81, 0xbfb8aa3b, v81
	v_rcp_f32_e32 v94, v94
	v_rcp_f32_e32 v95, v95
	v_exp_f32_e32 v80, v80
	v_exp_f32_e32 v81, v81
	v_mul_f32_e32 v84, 0xbfb8aa3b, v84
	v_mul_f32_e32 v85, 0xbfb8aa3b, v85
	v_exp_f32_e32 v84, v84
	v_exp_f32_e32 v85, v85
	v_add_f32_e32 v80, 1.0, v80
	v_add_f32_e32 v81, 1.0, v81
	v_rcp_f32_e32 v80, v80
	v_rcp_f32_e32 v81, v81
	v_mul_f32_e32 v82, 0xbfb8aa3b, v82
	v_mul_f32_e32 v83, 0xbfb8aa3b, v83
	v_add_f32_e32 v84, 1.0, v84
	v_add_f32_e32 v85, 1.0, v85
	v_exp_f32_e32 v82, v82
	v_exp_f32_e32 v83, v83
	v_rcp_f32_e32 v84, v84
	v_rcp_f32_e32 v85, v85
	v_mul_f32_e32 v86, 0xbfb8aa3b, v86
	v_mul_f32_e32 v87, 0xbfb8aa3b, v87
	v_exp_f32_e32 v86, v86
	v_exp_f32_e32 v87, v87
	v_add_f32_e32 v82, 1.0, v82
	v_add_f32_e32 v83, 1.0, v83
	v_rcp_f32_e32 v82, v82
	v_rcp_f32_e32 v83, v83
	v_add_f32_e32 v86, 1.0, v86
	v_add_f32_e32 v87, 1.0, v87
	v_rcp_f32_e32 v86, v86
	v_rcp_f32_e32 v87, v87
	v_mul_f32_e32 v72, 0xbfb8aa3b, v72
	v_mul_f32_e32 v73, 0xbfb8aa3b, v73
	v_mul_f32_e32 v76, 0xbfb8aa3b, v76
	v_exp_f32_e32 v72, v72
	v_exp_f32_e32 v73, v73
	v_mul_f32_e32 v74, 0xbfb8aa3b, v74
	v_mul_f32_e32 v75, 0xbfb8aa3b, v75
	v_add_f32_e32 v72, 1.0, v72
	v_add_f32_e32 v73, 1.0, v73
	v_rcp_f32_e32 v72, v72
	v_rcp_f32_e32 v73, v73
	v_exp_f32_e32 v74, v74
	v_exp_f32_e32 v75, v75
	v_mul_f32_e32 v78, 0xbfb8aa3b, v78
	v_mul_f32_e32 v79, 0xbfb8aa3b, v79
	v_exp_f32_e32 v78, v78
	v_exp_f32_e32 v79, v79
	v_add_f32_e32 v74, 1.0, v74
	v_add_f32_e32 v75, 1.0, v75
	v_rcp_f32_e32 v74, v74
	s_waitcnt vmcnt(32)
; __device__ __forceinline__ float bflo(unsigned w) { return __uint_as_float(w << 16); }
; __device__ __forceinline__ float bfhi(unsigned w) { return __uint_as_float(w & 0xffff0000u); }
;     const bool lo = fr < 8;
;     const int r1 = row - fr + (fr & 7), cb = col0 + (lo ? 0 : boff);
;     const u32x4 l1 = *(const u32x4*)(P + (size_t)r1 * ld + cb), l2 = *(const u32x4*)(P + (size_t)(r1 + 8) * ld + cb);
;     const u32x4 s1 = {dpp_ror8(l1.x), dpp_ror8(l1.y), dpp_ror8(l1.z), dpp_ror8(l1.w)}, s2 = {dpp_ror8(l2.x), dpp_ror8(l2.y), dpp_ror8(l2.z), dpp_ror8(l2.w)};
;     wA = lo ? l1 : s2; wB = lo ? s1 : l2;
; }
;     __device__ __forceinline__ void operator()(const f32x4 (&acc)[2][2][4][2], const Unit& u, int wr, int wc, int fr, int fq) const {
;     ...
;             for (int m = 0; m < 4; ++m) { const int row = row0 + ai * HALF + m * 16; const float ri = __builtin_amdgcn_rsqf(sse[row] * (1.f / D) + EPS);
;                 u32x4 rr[2], ee[2]; load_pair_lines(R, D, row, fr, col0, rr[0], rr[1], 32); load_pair_lines(E, D, row, fr, col0, ee[0], ee[1], 32);
;                 float* orow = OUT + (size_t)(row - fr + (fr & 7)) * D + col0 + (lo ? 0 : 4);
; #pragma unroll
;                 for (int bj = 0; bj < 2; ++bj) { const u32x4 rw = rr[bj], ew = ee[bj];
;                     const float r[8] = {bflo(rw.x), bfhi(rw.x), bflo(rw.y), bfhi(rw.y), bflo(rw.z), bfhi(rw.z), bflo(rw.w), bfhi(rw.w)};
;                     const float e[8] = {bflo(ew.x), bfhi(ew.x), bflo(ew.y), bfhi(ew.y), bflo(ew.z), bfhi(ew.z), bflo(ew.w), bfhi(ew.w)};
;                     float o[8];
; #pragma unroll
;                     for (int j = 0; j < 8; ++j) { const float a = acc[ai][bj][m][j >> 2][j & 3]; const float gg = gv[bj][j >> 2][j & 3];
;                         o[j] = r[j] + e[j] * ri * gg * __builtin_amdgcn_rcpf(1.f + __builtin_amdgcn_exp2f(-a * LOG2E)); }
;                     f32x4 o1, o2;
; #pragma unroll
;                     for (int j = 0; j < 4; ++j) { const unsigned a = __float_as_uint(o[j]), b = __float_as_uint(o[4 + j]); const unsigned sa = dpp_ror8(a), sb = dpp_ror8(b);
;                         o1[j] = __uint_as_float(lo ? a : sb); o2[j] = __uint_as_float(lo ? sa : b); }
;                     *(f32x4*)(orow + 32 * bj) = o1; *(f32x4*)(orow + (size_t)8 * D + 32 * bj) = o2; } }
	v_fmamk_f32 v96, v116, 0x3a000000, v182
	v_mov_b32_e32 v116, v157
	v_rsq_f32_e32 v96, v96
	v_rcp_f32_e32 v75, v75
	v_add_f32_e32 v78, 1.0, v78
	v_mov_b32_dpp v121, v104 row_ror:8 row_mask:0xf bank_mask:0xf
	v_mov_b32_dpp v122, v105 row_ror:8 row_mask:0xf bank_mask:0xf
	v_mov_b32_dpp v97, v98 row_ror:8 row_mask:0xf bank_mask:0xf
	v_mov_b32_dpp v116, v99 row_ror:8 row_mask:0xf bank_mask:0xf
	v_mov_b32_dpp v117, v100 row_ror:8 row_mask:0xf bank_mask:0xf
	v_mov_b32_dpp v118, v101 row_ror:8 row_mask:0xf bank_mask:0xf
	v_mov_b32_dpp v120, v103 row_ror:8 row_mask:0xf bank_mask:0xf
	v_cndmask_b32_e64 v122, v122, v101, s[0:1]
	v_cndmask_b32_e64 v101, v121, v100, s[0:1]
	v_mov_b32_e32 v100, v157
	v_mov_b32_dpp v119, v102 row_ror:8 row_mask:0xf bank_mask:0xf
	v_cndmask_b32_e64 v120, v120, v99, s[0:1]
	v_cndmask_b32_e64 v116, v103, v116, s[0:1]
	v_cndmask_b32_e64 v105, v105, v118, s[0:1]
	v_cndmask_b32_e64 v97, v102, v97, s[0:1]
	v_mov_b32_e32 v99, v157
	v_mov_b32_dpp v100, v108 row_ror:8 row_mask:0xf bank_mask:0xf
	v_mov_b32_e32 v102, v157
	v_mov_b32_e32 v103, v157
	v_mov_b32_e32 v118, v157
	v_cndmask_b32_e64 v119, v119, v98, s[0:1]
	v_cndmask_b32_e64 v104, v104, v117, s[0:1]
	v_mov_b32_e32 v98, v157
	v_mov_b32_dpp v99, v107 row_ror:8 row_mask:0xf bank_mask:0xf
	v_mov_b32_dpp v102, v109 row_ror:8 row_mask:0xf bank_mask:0xf
	v_mov_b32_dpp v103, v110 row_ror:8 row_mask:0xf bank_mask:0xf
	v_mov_b32_e32 v117, v157
	v_mov_b32_dpp v118, v112 row_ror:8 row_mask:0xf bank_mask:0xf
	v_cndmask_b32_e64 v112, v112, v100, s[0:1]
	v_exp_f32_e32 v100, v92
	v_mul_f32_e32 v92, 0xbfb8aa3b, v93
	v_mov_b32_dpp v98, v106 row_ror:8 row_mask:0xf bank_mask:0xf
	v_mov_b32_dpp v117, v111 row_ror:8 row_mask:0xf bank_mask:0xf
	v_cndmask_b32_e64 v106, v103, v106, s[0:1]
	v_cndmask_b32_e64 v103, v118, v108, s[0:1]
	v_cndmask_b32_e64 v108, v111, v99, s[0:1]
	v_cndmask_b32_e64 v111, v113, v102, s[0:1]
	v_exp_f32_e32 v102, v92
	v_cndmask_b32_e64 v110, v110, v98, s[0:1]
	v_lshlrev_b64 v[98:99], 13, v[114:115]
	v_lshl_add_u64 v[98:99], s[4:5], 0, v[98:99]
	v_lshl_add_u64 v[98:99], v[98:99], 0, v[166:167]
	v_lshl_add_u64 v[92:93], v[98:99], 0, v[156:157]
	v_add_f32_e32 v99, 1.0, v102
	v_lshlrev_b32_e32 v102, 16, v103
	v_and_b32_e32 v103, 0xffff0000, v103
	v_add_f32_e32 v98, 1.0, v100
	v_pk_mul_f32 v[102:103], v[96:97], v[102:103] op_sel_hi:[0,1]
	v_rcp_f32_e32 v98, v98
	v_rcp_f32_e32 v99, v99
	v_lshlrev_b32_e32 v100, 16, v101
	v_and_b32_e32 v101, 0xffff0000, v101
	v_pk_mul_f32 v[102:103], v[60:61], v[102:103]
	v_mov_b32_e32 v121, v157
	v_pk_fma_f32 v[102:103], v[88:89], v[102:103], v[100:101]
	v_lshlrev_b32_e32 v100, 16, v106
	v_and_b32_e32 v101, 0xffff0000, v106
	v_mov_b32_dpp v121, v113 row_ror:8 row_mask:0xf bank_mask:0xf
	v_pk_mul_f32 v[100:101], v[96:97], v[100:101] op_sel_hi:[0,1]
	v_cndmask_b32_e64 v109, v121, v109, s[0:1]
	v_lshlrev_b32_e32 v88, 16, v119
	v_and_b32_e32 v89, 0xffff0000, v119
	v_pk_mul_f32 v[100:101], v[56:57], v[100:101]
	v_cndmask_b32_e64 v107, v117, v107, s[0:1]
	v_pk_fma_f32 v[88:89], v[98:99], v[100:101], v[88:89]
	v_lshlrev_b32_e32 v100, 16, v109
	v_and_b32_e32 v101, 0xffff0000, v109
	v_pk_mul_f32 v[100:101], v[96:97], v[100:101] op_sel_hi:[0,1]
	v_lshlrev_b32_e32 v98, 16, v122
	v_and_b32_e32 v99, 0xffff0000, v122
	v_pk_mul_f32 v[100:101], v[62:63], v[100:101]
	v_mov_b32_e32 v113, v157
	v_pk_fma_f32 v[98:99], v[90:91], v[100:101], v[98:99]
	v_lshlrev_b32_e32 v100, 16, v107
	v_and_b32_e32 v101, 0xffff0000, v107
	v_pk_mul_f32 v[100:101], v[96:97], v[100:101] op_sel_hi:[0,1]
	v_lshlrev_b32_e32 v90, 16, v120
	v_and_b32_e32 v91, 0xffff0000, v120
	v_pk_mul_f32 v[100:101], v[58:59], v[100:101]
	v_mov_b32_e32 v114, v157
	v_pk_fma_f32 v[90:91], v[94:95], v[100:101], v[90:91]
	v_mov_b32_e32 v94, v157
	v_mov_b32_e32 v95, v157
	v_mov_b32_e32 v109, v157
	v_mov_b32_e32 v117, v157
	v_mov_b32_dpp v94, v90 row_ror:8 row_mask:0xf bank_mask:0xf
	v_mov_b32_dpp v95, v91 row_ror:8 row_mask:0xf bank_mask:0xf
	v_mov_b32_dpp v113, v102 row_ror:8 row_mask:0xf bank_mask:0xf
	v_mov_b32_dpp v114, v103 row_ror:8 row_mask:0xf bank_mask:0xf
	v_mov_b32_e32 v106, v157
	v_mov_b32_e32 v115, v157
	v_mov_b32_dpp v109, v98 row_ror:8 row_mask:0xf bank_mask:0xf
	v_mov_b32_dpp v117, v99 row_ror:8 row_mask:0xf bank_mask:0xf
	v_cndmask_b32_e64 v101, v99, v95, s[0:1]
	v_cndmask_b32_e64 v100, v98, v94, s[0:1]
	v_lshlrev_b32_e32 v94, 16, v112
	v_and_b32_e32 v95, 0xffff0000, v112
	v_mov_b32_dpp v106, v88 row_ror:8 row_mask:0xf bank_mask:0xf
	v_mov_b32_dpp v115, v89 row_ror:8 row_mask:0xf bank_mask:0xf
	v_cndmask_b32_e64 v91, v117, v91, s[0:1]
	v_cndmask_b32_e64 v90, v109, v90, s[0:1]
	v_cndmask_b32_e64 v89, v114, v89, s[0:1]
	v_cndmask_b32_e64 v88, v113, v88, s[0:1]
	v_pk_mul_f32 v[94:95], v[96:97], v[94:95] op_sel_hi:[0,1]
	global_store_dwordx4 v[92:93], v[88:91], off
	v_pk_mul_f32 v[94:95], v[44:45], v[94:95]
	v_cndmask_b32_e64 v99, v103, v115, s[0:1]
	v_lshlrev_b32_e32 v90, 16, v104
	v_and_b32_e32 v91, 0xffff0000, v104
	v_pk_fma_f32 v[90:91], v[80:81], v[94:95], v[90:91]
	v_lshlrev_b32_e32 v94, 16, v110
	v_and_b32_e32 v95, 0xffff0000, v110
	v_pk_mul_f32 v[94:95], v[96:97], v[94:95] op_sel_hi:[0,1]
	v_lshlrev_b32_e32 v80, 16, v97
	v_and_b32_e32 v81, 0xffff0000, v97
	v_pk_mul_f32 v[94:95], v[40:41], v[94:95]
	v_mov_b32_e32 v97, v157
	v_pk_fma_f32 v[80:81], v[84:85], v[94:95], v[80:81]
	v_lshlrev_b32_e32 v94, 16, v111
	v_and_b32_e32 v95, 0xffff0000, v111
	v_mov_b32_dpp v97, v80 row_ror:8 row_mask:0xf bank_mask:0xf
	v_pk_mul_f32 v[94:95], v[96:97], v[94:95] op_sel_hi:[0,1]
	v_lshlrev_b32_e32 v84, 16, v105
	v_and_b32_e32 v85, 0xffff0000, v105
	v_pk_mul_f32 v[94:95], v[46:47], v[94:95]
; __device__ __forceinline__ float bflo(unsigned w) { return __uint_as_float(w << 16); }
; __device__ __forceinline__ float bfhi(unsigned w) { return __uint_as_float(w & 0xffff0000u); }
;     const bool lo = fr < 8;
;     const int r1 = row - fr + (fr & 7), cb = col0 + (lo ? 0 : boff);
;     const u32x4 l1 = *(const u32x4*)(P + (size_t)r1 * ld + cb), l2 = *(const u32x4*)(P + (size_t)(r1 + 8) * ld + cb);
;     const u32x4 s1 = {dpp_ror8(l1.x), dpp_ror8(l1.y), dpp_ror8(l1.z), dpp_ror8(l1.w)}, s2 = {dpp_ror8(l2.x), dpp_ror8(l2.y), dpp_ror8(l2.z), dpp_ror8(l2.w)};
;     wA = lo ? l1 : s2; wB = lo ? s1 : l2;
; }
;     __device__ __forceinline__ void operator()(const f32x4 (&acc)[2][2][4][2], const Unit& u, int wr, int wc, int fr, int fq) const {
;     ...
;             for (int m = 0; m < 4; ++m) { const int row = row0 + ai * HALF + m * 16; const float ri = __builtin_amdgcn_rsqf(sse[row] * (1.f / D) + EPS);
;                 u32x4 rr[2], ee[2]; load_pair_lines(R, D, row, fr, col0, rr[0], rr[1], 32); load_pair_lines(E, D, row, fr, col0, ee[0], ee[1], 32);
;                 float* orow = OUT + (size_t)(row - fr + (fr & 7)) * D + col0 + (lo ? 0 : 4);
; #pragma unroll
;                 for (int bj = 0; bj < 2; ++bj) { const u32x4 rw = rr[bj], ew = ee[bj];
;                     const float r[8] = {bflo(rw.x), bfhi(rw.x), bflo(rw.y), bfhi(rw.y), bflo(rw.z), bfhi(rw.z), bflo(rw.w), bfhi(rw.w)};
;                     const float e[8] = {bflo(ew.x), bfhi(ew.x), bflo(ew.y), bfhi(ew.y), bflo(ew.z), bfhi(ew.z), bflo(ew.w), bfhi(ew.w)};
;                     float o[8];
; #pragma unroll
;                     for (int j = 0; j < 8; ++j) { const float a = acc[ai][bj][m][j >> 2][j & 3]; const float gg = gv[bj][j >> 2][j & 3];
;                         o[j] = r[j] + e[j] * ri * gg * __builtin_amdgcn_rcpf(1.f + __builtin_amdgcn_exp2f(-a * LOG2E)); }
;                     f32x4 o1, o2;
; #pragma unroll
;                     for (int j = 0; j < 4; ++j) { const unsigned a = __float_as_uint(o[j]), b = __float_as_uint(o[4 + j]); const unsigned sa = dpp_ror8(a), sb = dpp_ror8(b);
;                         o1[j] = __uint_as_float(lo ? a : sb); o2[j] = __uint_as_float(lo ? sa : b); }
;                     *(f32x4*)(orow + 32 * bj) = o1; *(f32x4*)(orow + (size_t)8 * D + 32 * bj) = o2; } }
	v_add_co_u32_e32 v88, vcc, s45, v92
	v_pk_fma_f32 v[84:85], v[82:83], v[94:95], v[84:85]
	v_lshlrev_b32_e32 v94, 16, v108
	v_and_b32_e32 v95, 0xffff0000, v108
	v_cndmask_b32_e64 v98, v102, v106, s[0:1]
	v_addc_co_u32_e32 v89, vcc, 0, v93, vcc
	v_pk_mul_f32 v[94:95], v[96:97], v[94:95] op_sel_hi:[0,1]
	global_store_dwordx4 v[88:89], v[98:101], off
	v_mov_b32_e32 v102, v157
	v_lshlrev_b32_e32 v82, 16, v116
	v_mov_b32_e32 v98, v157
	v_mov_b32_e32 v99, v157
	v_mov_b32_e32 v101, v157
	v_and_b32_e32 v83, 0xffff0000, v116
	v_pk_mul_f32 v[94:95], v[42:43], v[94:95]
	v_mov_b32_dpp v98, v90 row_ror:8 row_mask:0xf bank_mask:0xf
	v_mov_b32_dpp v99, v91 row_ror:8 row_mask:0xf bank_mask:0xf
	v_mov_b32_e32 v100, v157
	v_mov_b32_dpp v101, v84 row_ror:8 row_mask:0xf bank_mask:0xf
	v_mov_b32_dpp v102, v85 row_ror:8 row_mask:0xf bank_mask:0xf
	v_pk_fma_f32 v[82:83], v[86:87], v[94:95], v[82:83]
	v_mov_b32_e32 v86, v157
	v_mov_b32_e32 v87, v157
	v_mov_b32_dpp v100, v81 row_ror:8 row_mask:0xf bank_mask:0xf
	v_mov_b32_dpp v86, v82 row_ror:8 row_mask:0xf bank_mask:0xf
	v_mov_b32_dpp v87, v83 row_ror:8 row_mask:0xf bank_mask:0xf
	v_cndmask_b32_e64 v83, v102, v83, s[0:1]
	v_cndmask_b32_e64 v82, v101, v82, s[0:1]
	v_cndmask_b32_e64 v81, v99, v81, s[0:1]
	v_cndmask_b32_e64 v80, v98, v80, s[0:1]
	v_cndmask_b32_e64 v87, v85, v87, s[0:1]
	v_cndmask_b32_e64 v86, v84, v86, s[0:1]
	v_cndmask_b32_e64 v85, v91, v100, s[0:1]
	v_cndmask_b32_e64 v84, v90, v97, s[0:1]
	global_store_dwordx4 v[92:93], v[80:83], off offset:128
	global_store_dwordx4 v[88:89], v[84:87], off offset:128
	s_waitcnt vmcnt(4)
	s_nop 0
	v_mov_b32_e32 v80, v228
	v_sub_u32_e32 v81, v170, v174
	v_add_u32_e32 v81, v81, v176
	v_add_u32_e32 v98, 0x80, v81
	v_ashrrev_i32_e32 v99, 31, v98
	v_lshlrev_b64 v[90:91], 12, v[98:99]
	v_lshl_add_u64 v[94:95], v[90:91], 0, s[16:17]
	v_lshl_add_u64 v[82:83], s[8:9], 0, v[90:91]
	v_lshl_add_u64 v[86:87], s[8:9], 0, v[94:95]
	v_lshl_add_u64 v[82:83], v[82:83], 0, v[164:165]
	v_lshl_add_u64 v[86:87], v[86:87], 0, v[164:165]
	v_mov_b64_e32 v[82:83], v[232:233]
	v_mov_b64_e32 v[84:85], v[234:235]
	v_lshl_add_u64 v[90:91], s[10:11], 0, v[90:91]
	v_mov_b64_e32 v[86:87], v[236:237]
	v_mov_b64_e32 v[88:89], v[238:239]
	v_lshl_add_u64 v[90:91], v[90:91], 0, v[164:165]
	v_lshl_add_u64 v[94:95], s[10:11], 0, v[94:95]
	v_mov_b64_e32 v[90:91], v[240:241]
	v_mov_b64_e32 v[92:93], v[242:243]
	v_lshl_add_u64 v[94:95], v[94:95], 0, v[164:165]
	v_mov_b64_e32 v[94:95], v[244:245]
	v_mov_b64_e32 v[96:97], v[246:247]
	s_nop 1
	v_add_u32_e32 v222, 0x90, v81
	v_ashrrev_i32_e32 v223, 31, v222
	global_load_dword v228, v[168:169], off offset:576
	v_lshlrev_b64 v[216:217], 12, v[222:223]
	v_lshl_add_u64 v[224:225], v[216:217], 0, s[16:17]
	v_lshl_add_u64 v[220:221], s[8:9], 0, v[224:225]
	v_lshl_add_u64 v[218:219], s[8:9], 0, v[216:217]
	v_lshl_add_u64 v[220:221], v[220:221], 0, v[164:165]
	v_lshl_add_u64 v[216:217], s[10:11], 0, v[216:217]
	v_lshl_add_u64 v[218:219], v[218:219], 0, v[164:165]
	global_load_dwordx4 v[232:235], v[220:221], off
	v_lshl_add_u64 v[216:217], v[216:217], 0, v[164:165]
	global_load_dwordx4 v[236:239], v[218:219], off
	global_load_dwordx4 v[240:243], v[216:217], off
	v_lshl_add_u64 v[216:217], s[10:11], 0, v[224:225]
	v_lshl_add_u64 v[216:217], v[216:217], 0, v[164:165]
	global_load_dwordx4 v[244:247], v[216:217], off
	v_mov_b32_e32 v106, v157
	v_mov_b32_e32 v107, v157
	v_mov_b32_e32 v100, v157
	v_mov_b32_e32 v101, v157
	v_mov_b32_e32 v102, v157
	v_mov_b32_e32 v103, v157
	v_mov_b32_e32 v105, v157
	v_mov_b32_e32 v104, v157
	v_add_f32_e32 v79, 1.0, v79
	v_mul_f32_e32 v64, 0xbfb8aa3b, v64
	v_mul_f32_e32 v65, 0xbfb8aa3b, v65
	v_rcp_f32_e32 v78, v78
	v_rcp_f32_e32 v79, v79
	v_exp_f32_e32 v64, v64
	v_exp_f32_e32 v65, v65
	v_mul_f32_e32 v68, 0xbfb8aa3b, v68
	v_mul_f32_e32 v69, 0xbfb8aa3b, v69
	v_exp_f32_e32 v68, v68
	v_exp_f32_e32 v69, v69
	v_add_f32_e32 v64, 1.0, v64
	v_add_f32_e32 v65, 1.0, v65
	v_rcp_f32_e32 v64, v64
	v_mul_f32_e32 v66, 0xbfb8aa3b, v66
	v_mul_f32_e32 v67, 0xbfb8aa3b, v67
	v_rcp_f32_e32 v65, v65
	v_exp_f32_e32 v66, v66
	v_exp_f32_e32 v67, v67
	v_add_f32_e32 v68, 1.0, v68
	v_add_f32_e32 v69, 1.0, v69
	v_rcp_f32_e32 v68, v68
	v_mul_f32_e32 v70, 0xbfb8aa3b, v70
	v_mul_f32_e32 v71, 0xbfb8aa3b, v71
	v_rcp_f32_e32 v69, v69
	v_exp_f32_e32 v70, v70
	v_exp_f32_e32 v71, v71
	v_add_f32_e32 v66, 1.0, v66
	v_add_f32_e32 v67, 1.0, v67
	v_rcp_f32_e32 v66, v66
	v_rcp_f32_e32 v67, v67
	v_add_f32_e32 v70, 1.0, v70
	v_add_f32_e32 v71, 1.0, v71
	v_rcp_f32_e32 v70, v70
	v_rcp_f32_e32 v71, v71
	v_mul_f32_e32 v48, 0xbfb8aa3b, v48
	v_mul_f32_e32 v49, 0xbfb8aa3b, v49
	v_mul_f32_e32 v52, 0xbfb8aa3b, v52
	v_exp_f32_e32 v48, v48
	v_exp_f32_e32 v49, v49
	v_mul_f32_e32 v50, 0xbfb8aa3b, v50
	v_mul_f32_e32 v51, 0xbfb8aa3b, v51
	v_add_f32_e32 v48, 1.0, v48
	v_add_f32_e32 v49, 1.0, v49
	v_rcp_f32_e32 v48, v48
	v_rcp_f32_e32 v49, v49
	v_exp_f32_e32 v50, v50
	v_exp_f32_e32 v51, v51
	v_mul_f32_e32 v54, 0xbfb8aa3b, v54
	v_mul_f32_e32 v55, 0xbfb8aa3b, v55
	v_exp_f32_e32 v54, v54
	v_exp_f32_e32 v55, v55
	v_add_f32_e32 v50, 1.0, v50
	s_waitcnt vmcnt(41)
; __device__ __forceinline__ float bflo(unsigned w) { return __uint_as_float(w << 16); }
; __device__ __forceinline__ float bfhi(unsigned w) { return __uint_as_float(w & 0xffff0000u); }
;     const bool lo = fr < 8;
;     const int r1 = row - fr + (fr & 7), cb = col0 + (lo ? 0 : boff);
;     const u32x4 l1 = *(const u32x4*)(P + (size_t)r1 * ld + cb), l2 = *(const u32x4*)(P + (size_t)(r1 + 8) * ld + cb);
;     const u32x4 s1 = {dpp_ror8(l1.x), dpp_ror8(l1.y), dpp_ror8(l1.z), dpp_ror8(l1.w)}, s2 = {dpp_ror8(l2.x), dpp_ror8(l2.y), dpp_ror8(l2.z), dpp_ror8(l2.w)};
;     wA = lo ? l1 : s2; wB = lo ? s1 : l2;
; }
;     __device__ __forceinline__ void operator()(const f32x4 (&acc)[2][2][4][2], const Unit& u, int wr, int wc, int fr, int fq) const {
;     ...
;             for (int m = 0; m < 4; ++m) { const int row = row0 + ai * HALF + m * 16; const float ri = __builtin_amdgcn_rsqf(sse[row] * (1.f / D) + EPS);
;                 u32x4 rr[2], ee[2]; load_pair_lines(R, D, row, fr, col0, rr[0], rr[1], 32); load_pair_lines(E, D, row, fr, col0, ee[0], ee[1], 32);
;                 float* orow = OUT + (size_t)(row - fr + (fr & 7)) * D + col0 + (lo ? 0 : 4);
; #pragma unroll
;                 for (int bj = 0; bj < 2; ++bj) { const u32x4 rw = rr[bj], ew = ee[bj];
;                     const float r[8] = {bflo(rw.x), bfhi(rw.x), bflo(rw.y), bfhi(rw.y), bflo(rw.z), bfhi(rw.z), bflo(rw.w), bfhi(rw.w)};
;                     const float e[8] = {bflo(ew.x), bfhi(ew.x), bflo(ew.y), bfhi(ew.y), bflo(ew.z), bfhi(ew.z), bflo(ew.w), bfhi(ew.w)};
;                     float o[8];
; #pragma unroll
;                     for (int j = 0; j < 8; ++j) { const float a = acc[ai][bj][m][j >> 2][j & 3]; const float gg = gv[bj][j >> 2][j & 3];
;                         o[j] = r[j] + e[j] * ri * gg * __builtin_amdgcn_rcpf(1.f + __builtin_amdgcn_exp2f(-a * LOG2E)); }
;                     f32x4 o1, o2;
; #pragma unroll
;                     for (int j = 0; j < 4; ++j) { const unsigned a = __float_as_uint(o[j]), b = __float_as_uint(o[4 + j]); const unsigned sa = dpp_ror8(a), sb = dpp_ror8(b);
;                         o1[j] = __uint_as_float(lo ? a : sb); o2[j] = __uint_as_float(lo ? sa : b); }
;                     *(f32x4*)(orow + 32 * bj) = o1; *(f32x4*)(orow + (size_t)8 * D + 32 * bj) = o2; } }
	v_fmamk_f32 v80, v80, 0x3a000000, v182
	v_rsq_f32_e32 v80, v80
	v_add_f32_e32 v51, 1.0, v51
	v_rcp_f32_e32 v50, v50
	v_rcp_f32_e32 v51, v51
	v_add_f32_e32 v54, 1.0, v54
	v_add_f32_e32 v55, 1.0, v55
	v_mul_f32_e32 v32, 0xbfb8aa3b, v32
	v_mul_f32_e32 v33, 0xbfb8aa3b, v33
	v_rcp_f32_e32 v54, v54
	v_rcp_f32_e32 v55, v55
	v_mov_b32_dpp v100, v82 row_ror:8 row_mask:0xf bank_mask:0xf
	v_mov_b32_dpp v101, v83 row_ror:8 row_mask:0xf bank_mask:0xf
	v_mov_b32_dpp v106, v88 row_ror:8 row_mask:0xf bank_mask:0xf
	v_mov_b32_dpp v107, v89 row_ror:8 row_mask:0xf bank_mask:0xf
	v_mov_b32_dpp v102, v84 row_ror:8 row_mask:0xf bank_mask:0xf
	v_mov_b32_dpp v103, v85 row_ror:8 row_mask:0xf bank_mask:0xf
	v_mov_b32_dpp v105, v87 row_ror:8 row_mask:0xf bank_mask:0xf
	v_cndmask_b32_e64 v107, v107, v85, s[0:1]
	v_cndmask_b32_e64 v85, v106, v84, s[0:1]
	v_mov_b32_e32 v84, v157
	v_mov_b32_dpp v104, v86 row_ror:8 row_mask:0xf bank_mask:0xf
	v_cndmask_b32_e64 v105, v105, v83, s[0:1]
	v_cndmask_b32_e64 v101, v87, v101, s[0:1]
	v_cndmask_b32_e64 v89, v89, v103, s[0:1]
	v_cndmask_b32_e64 v100, v86, v100, s[0:1]
	v_mov_b32_e32 v83, v157
	v_mov_b32_dpp v84, v92 row_ror:8 row_mask:0xf bank_mask:0xf
	v_mov_b32_e32 v86, v157
	v_mov_b32_e32 v87, v157
	v_mov_b32_e32 v103, v157
	v_cndmask_b32_e64 v104, v104, v82, s[0:1]
	v_cndmask_b32_e64 v88, v88, v102, s[0:1]
	v_mov_b32_e32 v82, v157
	v_mov_b32_dpp v83, v91 row_ror:8 row_mask:0xf bank_mask:0xf
	v_mov_b32_dpp v86, v93 row_ror:8 row_mask:0xf bank_mask:0xf
	v_mov_b32_dpp v87, v94 row_ror:8 row_mask:0xf bank_mask:0xf
	v_mov_b32_e32 v102, v157
	v_mov_b32_dpp v103, v96 row_ror:8 row_mask:0xf bank_mask:0xf
	v_cndmask_b32_e64 v96, v96, v84, s[0:1]
	v_exp_f32_e32 v84, v76
	v_mul_f32_e32 v76, 0xbfb8aa3b, v77
	v_mov_b32_dpp v82, v90 row_ror:8 row_mask:0xf bank_mask:0xf
	v_mov_b32_dpp v102, v95 row_ror:8 row_mask:0xf bank_mask:0xf
	v_cndmask_b32_e64 v90, v87, v90, s[0:1]
	v_cndmask_b32_e64 v87, v103, v92, s[0:1]
	v_cndmask_b32_e64 v92, v95, v83, s[0:1]
	v_cndmask_b32_e64 v95, v97, v86, s[0:1]
	v_exp_f32_e32 v86, v76
	v_cndmask_b32_e64 v94, v94, v82, s[0:1]
	v_lshlrev_b64 v[82:83], 13, v[98:99]
	v_lshl_add_u64 v[82:83], s[4:5], 0, v[82:83]
	v_lshl_add_u64 v[82:83], v[82:83], 0, v[166:167]
	v_lshl_add_u64 v[76:77], v[82:83], 0, v[156:157]
	v_add_f32_e32 v83, 1.0, v86
	v_lshlrev_b32_e32 v86, 16, v87
	v_and_b32_e32 v87, 0xffff0000, v87
	v_add_f32_e32 v82, 1.0, v84
	v_pk_mul_f32 v[86:87], v[80:81], v[86:87] op_sel_hi:[0,1]
	v_rcp_f32_e32 v82, v82
	v_rcp_f32_e32 v83, v83
	v_lshlrev_b32_e32 v84, 16, v85
	v_and_b32_e32 v85, 0xffff0000, v85
	v_pk_mul_f32 v[86:87], v[60:61], v[86:87]
	v_mov_b32_e32 v106, v157
	v_pk_fma_f32 v[86:87], v[72:73], v[86:87], v[84:85]
	v_lshlrev_b32_e32 v84, 16, v90
	v_and_b32_e32 v85, 0xffff0000, v90
	v_mov_b32_dpp v106, v97 row_ror:8 row_mask:0xf bank_mask:0xf
	v_pk_mul_f32 v[84:85], v[80:81], v[84:85] op_sel_hi:[0,1]
	v_cndmask_b32_e64 v93, v106, v93, s[0:1]
	v_lshlrev_b32_e32 v72, 16, v104
	v_and_b32_e32 v73, 0xffff0000, v104
	v_pk_mul_f32 v[84:85], v[56:57], v[84:85]
	v_cndmask_b32_e64 v91, v102, v91, s[0:1]
	v_pk_fma_f32 v[72:73], v[82:83], v[84:85], v[72:73]
	v_lshlrev_b32_e32 v84, 16, v93
	v_and_b32_e32 v85, 0xffff0000, v93
	v_pk_mul_f32 v[84:85], v[80:81], v[84:85] op_sel_hi:[0,1]
	v_lshlrev_b32_e32 v82, 16, v107
	v_and_b32_e32 v83, 0xffff0000, v107
	v_pk_mul_f32 v[84:85], v[62:63], v[84:85]
	v_mov_b32_e32 v97, v157
	v_pk_fma_f32 v[82:83], v[74:75], v[84:85], v[82:83]
	v_lshlrev_b32_e32 v84, 16, v91
	v_and_b32_e32 v85, 0xffff0000, v91
	v_pk_mul_f32 v[84:85], v[80:81], v[84:85] op_sel_hi:[0,1]
	v_lshlrev_b32_e32 v74, 16, v105
	v_and_b32_e32 v75, 0xffff0000, v105
	v_pk_mul_f32 v[84:85], v[58:59], v[84:85]
	v_mov_b32_e32 v98, v157
	v_pk_fma_f32 v[74:75], v[78:79], v[84:85], v[74:75]
	v_mov_b32_e32 v78, v157
	v_mov_b32_e32 v79, v157
	v_mov_b32_e32 v93, v157
	v_mov_b32_e32 v102, v157
	v_mov_b32_dpp v78, v74 row_ror:8 row_mask:0xf bank_mask:0xf
	v_mov_b32_dpp v79, v75 row_ror:8 row_mask:0xf bank_mask:0xf
	v_mov_b32_dpp v97, v86 row_ror:8 row_mask:0xf bank_mask:0xf
	v_mov_b32_dpp v98, v87 row_ror:8 row_mask:0xf bank_mask:0xf
	v_mov_b32_e32 v90, v157
	v_mov_b32_e32 v99, v157
	v_mov_b32_dpp v93, v82 row_ror:8 row_mask:0xf bank_mask:0xf
	v_mov_b32_dpp v102, v83 row_ror:8 row_mask:0xf bank_mask:0xf
	v_cndmask_b32_e64 v85, v83, v79, s[0:1]
	v_cndmask_b32_e64 v84, v82, v78, s[0:1]
	v_lshlrev_b32_e32 v78, 16, v96
	v_and_b32_e32 v79, 0xffff0000, v96
	v_mov_b32_dpp v90, v72 row_ror:8 row_mask:0xf bank_mask:0xf
	v_mov_b32_dpp v99, v73 row_ror:8 row_mask:0xf bank_mask:0xf
	v_cndmask_b32_e64 v75, v102, v75, s[0:1]
	v_cndmask_b32_e64 v74, v93, v74, s[0:1]
	v_cndmask_b32_e64 v73, v98, v73, s[0:1]
	v_cndmask_b32_e64 v72, v97, v72, s[0:1]
	v_pk_mul_f32 v[78:79], v[80:81], v[78:79] op_sel_hi:[0,1]
	global_store_dwordx4 v[76:77], v[72:75], off
	v_pk_mul_f32 v[78:79], v[44:45], v[78:79]
	v_cndmask_b32_e64 v83, v87, v99, s[0:1]
	v_lshlrev_b32_e32 v74, 16, v88
	v_and_b32_e32 v75, 0xffff0000, v88
	v_pk_fma_f32 v[74:75], v[64:65], v[78:79], v[74:75]
	v_lshlrev_b32_e32 v78, 16, v94
	v_and_b32_e32 v79, 0xffff0000, v94
	v_pk_mul_f32 v[78:79], v[80:81], v[78:79] op_sel_hi:[0,1]
	v_lshlrev_b32_e32 v64, 16, v100
	v_and_b32_e32 v65, 0xffff0000, v100
	v_pk_mul_f32 v[78:79], v[40:41], v[78:79]
	v_add_co_u32_e32 v72, vcc, s45, v76
	v_pk_fma_f32 v[64:65], v[68:69], v[78:79], v[64:65]
	v_lshlrev_b32_e32 v78, 16, v95
	v_and_b32_e32 v79, 0xffff0000, v95
	v_pk_mul_f32 v[78:79], v[80:81], v[78:79] op_sel_hi:[0,1]
	v_lshlrev_b32_e32 v68, 16, v89
	v_and_b32_e32 v69, 0xffff0000, v89
	v_pk_mul_f32 v[78:79], v[46:47], v[78:79]
	v_cndmask_b32_e64 v82, v86, v90, s[0:1]
; __device__ __forceinline__ float bflo(unsigned w) { return __uint_as_float(w << 16); }
; __device__ __forceinline__ float bfhi(unsigned w) { return __uint_as_float(w & 0xffff0000u); }
;     const bool lo = fr < 8;
;     const int r1 = row - fr + (fr & 7), cb = col0 + (lo ? 0 : boff);
;     const u32x4 l1 = *(const u32x4*)(P + (size_t)r1 * ld + cb), l2 = *(const u32x4*)(P + (size_t)(r1 + 8) * ld + cb);
;     const u32x4 s1 = {dpp_ror8(l1.x), dpp_ror8(l1.y), dpp_ror8(l1.z), dpp_ror8(l1.w)}, s2 = {dpp_ror8(l2.x), dpp_ror8(l2.y), dpp_ror8(l2.z), dpp_ror8(l2.w)};
;     wA = lo ? l1 : s2; wB = lo ? s1 : l2;
; }
;     __device__ __forceinline__ void operator()(const f32x4 (&acc)[2][2][4][2], const Unit& u, int wr, int wc, int fr, int fq) const {
;     ...
;             for (int m = 0; m < 4; ++m) { const int row = row0 + ai * HALF + m * 16; const float ri = __builtin_amdgcn_rsqf(sse[row] * (1.f / D) + EPS);
;                 u32x4 rr[2], ee[2]; load_pair_lines(R, D, row, fr, col0, rr[0], rr[1], 32); load_pair_lines(E, D, row, fr, col0, ee[0], ee[1], 32);
;                 float* orow = OUT + (size_t)(row - fr + (fr & 7)) * D + col0 + (lo ? 0 : 4);
; #pragma unroll
;                 for (int bj = 0; bj < 2; ++bj) { const u32x4 rw = rr[bj], ew = ee[bj];
;                     const float r[8] = {bflo(rw.x), bfhi(rw.x), bflo(rw.y), bfhi(rw.y), bflo(rw.z), bfhi(rw.z), bflo(rw.w), bfhi(rw.w)};
;                     const float e[8] = {bflo(ew.x), bfhi(ew.x), bflo(ew.y), bfhi(ew.y), bflo(ew.z), bfhi(ew.z), bflo(ew.w), bfhi(ew.w)};
;                     float o[8];
; #pragma unroll
;                     for (int j = 0; j < 8; ++j) { const float a = acc[ai][bj][m][j >> 2][j & 3]; const float gg = gv[bj][j >> 2][j & 3];
;                         o[j] = r[j] + e[j] * ri * gg * __builtin_amdgcn_rcpf(1.f + __builtin_amdgcn_exp2f(-a * LOG2E)); }
;                     f32x4 o1, o2;
; #pragma unroll
;                     for (int j = 0; j < 4; ++j) { const unsigned a = __float_as_uint(o[j]), b = __float_as_uint(o[4 + j]); const unsigned sa = dpp_ror8(a), sb = dpp_ror8(b);
;                         o1[j] = __uint_as_float(lo ? a : sb); o2[j] = __uint_as_float(lo ? sa : b); }
;                     *(f32x4*)(orow + 32 * bj) = o1; *(f32x4*)(orow + (size_t)8 * D + 32 * bj) = o2; } }
	v_pk_fma_f32 v[68:69], v[66:67], v[78:79], v[68:69]
	v_lshlrev_b32_e32 v78, 16, v92
	v_and_b32_e32 v79, 0xffff0000, v92
	v_addc_co_u32_e32 v73, vcc, 0, v77, vcc
	v_pk_mul_f32 v[78:79], v[80:81], v[78:79] op_sel_hi:[0,1]
	global_store_dwordx4 v[72:73], v[82:85], off
	v_mov_b32_e32 v86, v157
	v_mov_b32_e32 v87, v157
	v_mov_b32_e32 v82, v157
	v_mov_b32_e32 v83, v157
	v_lshlrev_b32_e32 v66, 16, v101
	v_and_b32_e32 v67, 0xffff0000, v101
	v_pk_mul_f32 v[78:79], v[42:43], v[78:79]
	v_mov_b32_dpp v82, v74 row_ror:8 row_mask:0xf bank_mask:0xf
	v_mov_b32_dpp v83, v75 row_ror:8 row_mask:0xf bank_mask:0xf
	v_mov_b32_e32 v84, v157
	v_mov_b32_e32 v85, v157
	v_mov_b32_dpp v86, v68 row_ror:8 row_mask:0xf bank_mask:0xf
	v_mov_b32_dpp v87, v69 row_ror:8 row_mask:0xf bank_mask:0xf
	v_pk_fma_f32 v[66:67], v[70:71], v[78:79], v[66:67]
	v_mov_b32_e32 v70, v157
	v_mov_b32_e32 v71, v157
	v_add_u32_e32 v78, 0x90, v81
	v_mov_b32_dpp v84, v64 row_ror:8 row_mask:0xf bank_mask:0xf
	v_mov_b32_dpp v85, v65 row_ror:8 row_mask:0xf bank_mask:0xf
	v_mov_b32_dpp v70, v66 row_ror:8 row_mask:0xf bank_mask:0xf
	v_mov_b32_dpp v71, v67 row_ror:8 row_mask:0xf bank_mask:0xf
	v_cndmask_b32_e64 v67, v87, v67, s[0:1]
	v_cndmask_b32_e64 v66, v86, v66, s[0:1]
	v_cndmask_b32_e64 v65, v83, v65, s[0:1]
	v_cndmask_b32_e64 v64, v82, v64, s[0:1]
	v_ashrrev_i32_e32 v79, 31, v78
	v_cndmask_b32_e64 v71, v69, v71, s[0:1]
	v_cndmask_b32_e64 v70, v68, v70, s[0:1]
	v_cndmask_b32_e64 v69, v75, v85, s[0:1]
	v_cndmask_b32_e64 v68, v74, v84, s[0:1]
	global_store_dwordx4 v[76:77], v[64:67], off offset:128
	global_store_dwordx4 v[72:73], v[68:71], off offset:128
	s_waitcnt vmcnt(4)
	s_nop 0
	v_mov_b32_e32 v80, v228
	v_lshlrev_b64 v[64:65], 12, v[78:79]
	v_lshl_add_u64 v[82:83], v[64:65], 0, s[16:17]
	v_lshl_add_u64 v[70:71], s[8:9], 0, v[82:83]
	v_lshl_add_u64 v[66:67], s[8:9], 0, v[64:65]
	v_lshl_add_u64 v[70:71], v[70:71], 0, v[164:165]
	v_lshl_add_u64 v[64:65], s[10:11], 0, v[64:65]
	v_lshl_add_u64 v[66:67], v[66:67], 0, v[164:165]
	v_mov_b64_e32 v[70:71], v[232:233]
	v_mov_b64_e32 v[72:73], v[234:235]
	v_lshl_add_u64 v[64:65], v[64:65], 0, v[164:165]
	v_mov_b64_e32 v[66:67], v[236:237]
	v_mov_b64_e32 v[68:69], v[238:239]
	v_mov_b32_e32 v90, v157
	v_mov_b64_e32 v[74:75], v[240:241]
	v_mov_b64_e32 v[76:77], v[242:243]
	v_lshl_add_u64 v[64:65], s[10:11], 0, v[82:83]
	v_lshl_add_u64 v[64:65], v[64:65], 0, v[164:165]
	v_mov_b64_e32 v[82:83], v[244:245]
	v_mov_b64_e32 v[84:85], v[246:247]
	s_nop 1
	global_load_dword v228, v[168:169], off offset:640
	v_add_u32_e32 v220, 0xa0, v81
	v_ashrrev_i32_e32 v221, 31, v220
	v_lshlrev_b64 v[216:217], 12, v[220:221]
	v_lshl_add_u64 v[224:225], v[216:217], 0, s[16:17]
	v_lshl_add_u64 v[222:223], s[8:9], 0, v[224:225]
	v_lshl_add_u64 v[218:219], s[8:9], 0, v[216:217]
	v_lshl_add_u64 v[222:223], v[222:223], 0, v[164:165]
	v_lshl_add_u64 v[216:217], s[10:11], 0, v[216:217]
	v_lshl_add_u64 v[218:219], v[218:219], 0, v[164:165]
	global_load_dwordx4 v[232:235], v[222:223], off
	v_lshl_add_u64 v[216:217], v[216:217], 0, v[164:165]
	global_load_dwordx4 v[236:239], v[218:219], off
	global_load_dwordx4 v[240:243], v[216:217], off
	v_lshl_add_u64 v[216:217], s[10:11], 0, v[224:225]
	v_lshl_add_u64 v[216:217], v[216:217], 0, v[164:165]
	global_load_dwordx4 v[244:247], v[216:217], off
	v_mov_b32_e32 v91, v157
	v_mov_b32_e32 v65, v157
	v_mov_b32_e32 v86, v157
	v_mov_b32_e32 v87, v157
	v_mov_b32_e32 v89, v157
	v_mov_b32_e32 v88, v157
	v_exp_f32_e32 v32, v32
	v_exp_f32_e32 v33, v33
	v_mul_f32_e32 v36, 0xbfb8aa3b, v36
	v_mul_f32_e32 v37, 0xbfb8aa3b, v37
	v_exp_f32_e32 v36, v36
	v_exp_f32_e32 v37, v37
	v_add_f32_e32 v32, 1.0, v32
	v_add_f32_e32 v33, 1.0, v33
	v_rcp_f32_e32 v32, v32
	v_rcp_f32_e32 v33, v33
	v_mul_f32_e32 v34, 0xbfb8aa3b, v34
	v_mul_f32_e32 v35, 0xbfb8aa3b, v35
	v_add_f32_e32 v36, 1.0, v36
	v_add_f32_e32 v37, 1.0, v37
	v_exp_f32_e32 v34, v34
	v_exp_f32_e32 v35, v35
	v_rcp_f32_e32 v36, v36
	v_rcp_f32_e32 v37, v37
	v_mul_f32_e32 v38, 0xbfb8aa3b, v38
	v_mul_f32_e32 v39, 0xbfb8aa3b, v39
	v_exp_f32_e32 v38, v38
	v_exp_f32_e32 v39, v39
	v_add_f32_e32 v34, 1.0, v34
	v_add_f32_e32 v35, 1.0, v35
	v_rcp_f32_e32 v34, v34
	v_rcp_f32_e32 v35, v35
	v_add_f32_e32 v38, 1.0, v38
	v_add_f32_e32 v39, 1.0, v39
	v_rcp_f32_e32 v38, v38
	v_rcp_f32_e32 v39, v39
	v_mul_f32_e32 v24, 0xbfb8aa3b, v24
	v_mul_f32_e32 v25, 0xbfb8aa3b, v25
	v_mul_f32_e32 v28, 0xbfb8aa3b, v28
	v_exp_f32_e32 v24, v24
	v_exp_f32_e32 v25, v25
	v_mul_f32_e32 v26, 0xbfb8aa3b, v26
	v_mul_f32_e32 v27, 0xbfb8aa3b, v27
	v_add_f32_e32 v24, 1.0, v24
	v_add_f32_e32 v25, 1.0, v25
	v_rcp_f32_e32 v24, v24
	v_rcp_f32_e32 v25, v25
	v_exp_f32_e32 v26, v26
	v_exp_f32_e32 v27, v27
	v_mul_f32_e32 v30, 0xbfb8aa3b, v30
	v_mul_f32_e32 v31, 0xbfb8aa3b, v31
	v_exp_f32_e32 v30, v30
	v_exp_f32_e32 v31, v31
	v_add_f32_e32 v26, 1.0, v26
	v_add_f32_e32 v27, 1.0, v27
	v_rcp_f32_e32 v26, v26
	v_rcp_f32_e32 v27, v27
	v_add_f32_e32 v30, 1.0, v30
	v_add_f32_e32 v31, 1.0, v31
	v_mul_f32_e32 v16, 0xbfb8aa3b, v16
	v_mul_f32_e32 v17, 0xbfb8aa3b, v17
	v_rcp_f32_e32 v30, v30
	v_rcp_f32_e32 v31, v31
	v_exp_f32_e32 v16, v16
	s_waitcnt vmcnt(50)
; __device__ __forceinline__ float bflo(unsigned w) { return __uint_as_float(w << 16); }
; __device__ __forceinline__ float bfhi(unsigned w) { return __uint_as_float(w & 0xffff0000u); }
;     const bool lo = fr < 8;
;     const int r1 = row - fr + (fr & 7), cb = col0 + (lo ? 0 : boff);
;     const u32x4 l1 = *(const u32x4*)(P + (size_t)r1 * ld + cb), l2 = *(const u32x4*)(P + (size_t)(r1 + 8) * ld + cb);
;     const u32x4 s1 = {dpp_ror8(l1.x), dpp_ror8(l1.y), dpp_ror8(l1.z), dpp_ror8(l1.w)}, s2 = {dpp_ror8(l2.x), dpp_ror8(l2.y), dpp_ror8(l2.z), dpp_ror8(l2.w)};
;     wA = lo ? l1 : s2; wB = lo ? s1 : l2;
; }
;     __device__ __forceinline__ void operator()(const f32x4 (&acc)[2][2][4][2], const Unit& u, int wr, int wc, int fr, int fq) const {
;     ...
;             for (int m = 0; m < 4; ++m) { const int row = row0 + ai * HALF + m * 16; const float ri = __builtin_amdgcn_rsqf(sse[row] * (1.f / D) + EPS);
;                 u32x4 rr[2], ee[2]; load_pair_lines(R, D, row, fr, col0, rr[0], rr[1], 32); load_pair_lines(E, D, row, fr, col0, ee[0], ee[1], 32);
;                 float* orow = OUT + (size_t)(row - fr + (fr & 7)) * D + col0 + (lo ? 0 : 4);
; #pragma unroll
;                 for (int bj = 0; bj < 2; ++bj) { const u32x4 rw = rr[bj], ew = ee[bj];
;                     const float r[8] = {bflo(rw.x), bfhi(rw.x), bflo(rw.y), bfhi(rw.y), bflo(rw.z), bfhi(rw.z), bflo(rw.w), bfhi(rw.w)};
;                     const float e[8] = {bflo(ew.x), bfhi(ew.x), bflo(ew.y), bfhi(ew.y), bflo(ew.z), bfhi(ew.z), bflo(ew.w), bfhi(ew.w)};
;                     float o[8];
; #pragma unroll
;                     for (int j = 0; j < 8; ++j) { const float a = acc[ai][bj][m][j >> 2][j & 3]; const float gg = gv[bj][j >> 2][j & 3];
;                         o[j] = r[j] + e[j] * ri * gg * __builtin_amdgcn_rcpf(1.f + __builtin_amdgcn_exp2f(-a * LOG2E)); }
;                     f32x4 o1, o2;
; #pragma unroll
;                     for (int j = 0; j < 4; ++j) { const unsigned a = __float_as_uint(o[j]), b = __float_as_uint(o[4 + j]); const unsigned sa = dpp_ror8(a), sb = dpp_ror8(b);
;                         o1[j] = __uint_as_float(lo ? a : sb); o2[j] = __uint_as_float(lo ? sa : b); }
;                     *(f32x4*)(orow + 32 * bj) = o1; *(f32x4*)(orow + (size_t)8 * D + 32 * bj) = o2; } }
	v_fmamk_f32 v64, v80, 0x3a000000, v182
	v_mov_b32_e32 v80, v157
	v_rsq_f32_e32 v64, v64
	v_exp_f32_e32 v17, v17
	v_mul_f32_e32 v20, 0xbfb8aa3b, v20
	v_mul_f32_e32 v21, 0xbfb8aa3b, v21
	v_exp_f32_e32 v20, v20
	v_exp_f32_e32 v21, v21
	v_mov_b32_dpp v90, v72 row_ror:8 row_mask:0xf bank_mask:0xf
	v_mov_b32_dpp v91, v73 row_ror:8 row_mask:0xf bank_mask:0xf
	v_mov_b32_dpp v65, v66 row_ror:8 row_mask:0xf bank_mask:0xf
	v_mov_b32_dpp v80, v67 row_ror:8 row_mask:0xf bank_mask:0xf
	v_mov_b32_dpp v86, v68 row_ror:8 row_mask:0xf bank_mask:0xf
	v_mov_b32_dpp v87, v69 row_ror:8 row_mask:0xf bank_mask:0xf
	v_mov_b32_dpp v89, v71 row_ror:8 row_mask:0xf bank_mask:0xf
	v_cndmask_b32_e64 v91, v91, v69, s[0:1]
	v_cndmask_b32_e64 v69, v90, v68, s[0:1]
	v_mov_b32_e32 v68, v157
	v_mov_b32_dpp v88, v70 row_ror:8 row_mask:0xf bank_mask:0xf
	v_cndmask_b32_e64 v89, v89, v67, s[0:1]
	v_cndmask_b32_e64 v80, v71, v80, s[0:1]
	v_cndmask_b32_e64 v73, v73, v87, s[0:1]
	v_cndmask_b32_e64 v65, v70, v65, s[0:1]
	v_mov_b32_e32 v67, v157
	v_mov_b32_dpp v68, v76 row_ror:8 row_mask:0xf bank_mask:0xf
	v_mov_b32_e32 v70, v157
	v_mov_b32_e32 v71, v157
	v_mov_b32_e32 v87, v157
	v_cndmask_b32_e64 v88, v88, v66, s[0:1]
	v_cndmask_b32_e64 v72, v72, v86, s[0:1]
	v_mov_b32_e32 v66, v157
	v_mov_b32_dpp v67, v75 row_ror:8 row_mask:0xf bank_mask:0xf
	v_mov_b32_dpp v70, v77 row_ror:8 row_mask:0xf bank_mask:0xf
	v_mov_b32_dpp v71, v82 row_ror:8 row_mask:0xf bank_mask:0xf
	v_mov_b32_e32 v86, v157
	v_mov_b32_dpp v87, v84 row_ror:8 row_mask:0xf bank_mask:0xf
	v_cndmask_b32_e64 v84, v84, v68, s[0:1]
	v_exp_f32_e32 v68, v52
	v_mul_f32_e32 v52, 0xbfb8aa3b, v53
	v_mov_b32_dpp v66, v74 row_ror:8 row_mask:0xf bank_mask:0xf
	v_mov_b32_dpp v86, v83 row_ror:8 row_mask:0xf bank_mask:0xf
	v_cndmask_b32_e64 v74, v71, v74, s[0:1]
	v_cndmask_b32_e64 v71, v87, v76, s[0:1]
	v_cndmask_b32_e64 v76, v83, v67, s[0:1]
	v_cndmask_b32_e64 v83, v85, v70, s[0:1]
	v_exp_f32_e32 v70, v52
	v_cndmask_b32_e64 v82, v82, v66, s[0:1]
	v_lshlrev_b64 v[66:67], 13, v[78:79]
	v_lshl_add_u64 v[66:67], s[4:5], 0, v[66:67]
	v_lshl_add_u64 v[66:67], v[66:67], 0, v[166:167]
	v_lshl_add_u64 v[52:53], v[66:67], 0, v[156:157]
	v_add_f32_e32 v67, 1.0, v70
	v_lshlrev_b32_e32 v70, 16, v71
	v_and_b32_e32 v71, 0xffff0000, v71
	v_add_f32_e32 v66, 1.0, v68
	v_pk_mul_f32 v[70:71], v[64:65], v[70:71] op_sel_hi:[0,1]
	v_rcp_f32_e32 v66, v66
	v_rcp_f32_e32 v67, v67
	v_lshlrev_b32_e32 v68, 16, v69
	v_and_b32_e32 v69, 0xffff0000, v69
	v_pk_mul_f32 v[70:71], v[60:61], v[70:71]
	v_mov_b32_e32 v90, v157
	v_pk_fma_f32 v[70:71], v[48:49], v[70:71], v[68:69]
	v_lshlrev_b32_e32 v68, 16, v74
	v_and_b32_e32 v69, 0xffff0000, v74
	v_mov_b32_dpp v90, v85 row_ror:8 row_mask:0xf bank_mask:0xf
	v_pk_mul_f32 v[68:69], v[64:65], v[68:69] op_sel_hi:[0,1]
	v_cndmask_b32_e64 v77, v90, v77, s[0:1]
	v_lshlrev_b32_e32 v48, 16, v88
	v_and_b32_e32 v49, 0xffff0000, v88
	v_pk_mul_f32 v[68:69], v[56:57], v[68:69]
	v_cndmask_b32_e64 v75, v86, v75, s[0:1]
	v_pk_fma_f32 v[48:49], v[66:67], v[68:69], v[48:49]
	v_lshlrev_b32_e32 v68, 16, v77
	v_and_b32_e32 v69, 0xffff0000, v77
	v_pk_mul_f32 v[68:69], v[64:65], v[68:69] op_sel_hi:[0,1]
	v_lshlrev_b32_e32 v66, 16, v91
	v_and_b32_e32 v67, 0xffff0000, v91
	v_pk_mul_f32 v[68:69], v[62:63], v[68:69]
	v_mov_b32_e32 v78, v157
	v_pk_fma_f32 v[66:67], v[50:51], v[68:69], v[66:67]
	v_lshlrev_b32_e32 v68, 16, v75
	v_and_b32_e32 v69, 0xffff0000, v75
	v_pk_mul_f32 v[68:69], v[64:65], v[68:69] op_sel_hi:[0,1]
	v_lshlrev_b32_e32 v50, 16, v89
	v_and_b32_e32 v51, 0xffff0000, v89
	v_pk_mul_f32 v[68:69], v[58:59], v[68:69]
	v_mov_b32_e32 v79, v157
	v_pk_fma_f32 v[50:51], v[54:55], v[68:69], v[50:51]
	v_mov_b32_e32 v54, v157
	v_mov_b32_e32 v55, v157
	v_mov_b32_e32 v77, v157
	v_mov_b32_e32 v86, v157
	v_mov_b32_dpp v54, v50 row_ror:8 row_mask:0xf bank_mask:0xf
	v_mov_b32_dpp v55, v51 row_ror:8 row_mask:0xf bank_mask:0xf
	v_mov_b32_dpp v78, v70 row_ror:8 row_mask:0xf bank_mask:0xf
	v_mov_b32_dpp v79, v71 row_ror:8 row_mask:0xf bank_mask:0xf
	v_mov_b32_e32 v74, v157
	v_mov_b32_e32 v85, v157
	v_mov_b32_dpp v77, v66 row_ror:8 row_mask:0xf bank_mask:0xf
	v_mov_b32_dpp v86, v67 row_ror:8 row_mask:0xf bank_mask:0xf
	v_cndmask_b32_e64 v69, v67, v55, s[0:1]
	v_cndmask_b32_e64 v68, v66, v54, s[0:1]
	v_lshlrev_b32_e32 v54, 16, v84
	v_and_b32_e32 v55, 0xffff0000, v84
	v_mov_b32_dpp v74, v48 row_ror:8 row_mask:0xf bank_mask:0xf
	v_mov_b32_dpp v85, v49 row_ror:8 row_mask:0xf bank_mask:0xf
	v_cndmask_b32_e64 v51, v86, v51, s[0:1]
	v_cndmask_b32_e64 v50, v77, v50, s[0:1]
	v_cndmask_b32_e64 v49, v79, v49, s[0:1]
	v_cndmask_b32_e64 v48, v78, v48, s[0:1]
	v_pk_mul_f32 v[54:55], v[64:65], v[54:55] op_sel_hi:[0,1]
	global_store_dwordx4 v[52:53], v[48:51], off
	v_pk_mul_f32 v[54:55], v[44:45], v[54:55]
	v_cndmask_b32_e64 v67, v71, v85, s[0:1]
	v_lshlrev_b32_e32 v50, 16, v72
	v_and_b32_e32 v51, 0xffff0000, v72
	v_pk_fma_f32 v[50:51], v[32:33], v[54:55], v[50:51]
	v_lshlrev_b32_e32 v54, 16, v82
	v_and_b32_e32 v55, 0xffff0000, v82
	v_pk_mul_f32 v[54:55], v[64:65], v[54:55] op_sel_hi:[0,1]
	v_lshlrev_b32_e32 v32, 16, v65
	v_and_b32_e32 v33, 0xffff0000, v65
	v_pk_mul_f32 v[54:55], v[40:41], v[54:55]
	v_mov_b32_e32 v65, v157
	v_pk_fma_f32 v[32:33], v[36:37], v[54:55], v[32:33]
	v_lshlrev_b32_e32 v54, 16, v83
	v_and_b32_e32 v55, 0xffff0000, v83
	v_mov_b32_dpp v65, v32 row_ror:8 row_mask:0xf bank_mask:0xf
	v_pk_mul_f32 v[54:55], v[64:65], v[54:55] op_sel_hi:[0,1]
	v_lshlrev_b32_e32 v36, 16, v73
	v_and_b32_e32 v37, 0xffff0000, v73
	v_pk_mul_f32 v[54:55], v[46:47], v[54:55]
	v_add_co_u32_e32 v48, vcc, s45, v52
	v_pk_fma_f32 v[36:37], v[34:35], v[54:55], v[36:37]
	v_lshlrev_b32_e32 v54, 16, v76
; __device__ __forceinline__ float bflo(unsigned w) { return __uint_as_float(w << 16); }
; __device__ __forceinline__ float bfhi(unsigned w) { return __uint_as_float(w & 0xffff0000u); }
;     const bool lo = fr < 8;
;     const int r1 = row - fr + (fr & 7), cb = col0 + (lo ? 0 : boff);
;     const u32x4 l1 = *(const u32x4*)(P + (size_t)r1 * ld + cb), l2 = *(const u32x4*)(P + (size_t)(r1 + 8) * ld + cb);
;     const u32x4 s1 = {dpp_ror8(l1.x), dpp_ror8(l1.y), dpp_ror8(l1.z), dpp_ror8(l1.w)}, s2 = {dpp_ror8(l2.x), dpp_ror8(l2.y), dpp_ror8(l2.z), dpp_ror8(l2.w)};
;     wA = lo ? l1 : s2; wB = lo ? s1 : l2;
; }
;     __device__ __forceinline__ void operator()(const f32x4 (&acc)[2][2][4][2], const Unit& u, int wr, int wc, int fr, int fq) const {
;     ...
;             for (int m = 0; m < 4; ++m) { const int row = row0 + ai * HALF + m * 16; const float ri = __builtin_amdgcn_rsqf(sse[row] * (1.f / D) + EPS);
;                 u32x4 rr[2], ee[2]; load_pair_lines(R, D, row, fr, col0, rr[0], rr[1], 32); load_pair_lines(E, D, row, fr, col0, ee[0], ee[1], 32);
;                 float* orow = OUT + (size_t)(row - fr + (fr & 7)) * D + col0 + (lo ? 0 : 4);
; #pragma unroll
;                 for (int bj = 0; bj < 2; ++bj) { const u32x4 rw = rr[bj], ew = ee[bj];
;                     const float r[8] = {bflo(rw.x), bfhi(rw.x), bflo(rw.y), bfhi(rw.y), bflo(rw.z), bfhi(rw.z), bflo(rw.w), bfhi(rw.w)};
;                     const float e[8] = {bflo(ew.x), bfhi(ew.x), bflo(ew.y), bfhi(ew.y), bflo(ew.z), bfhi(ew.z), bflo(ew.w), bfhi(ew.w)};
;                     float o[8];
; #pragma unroll
;                     for (int j = 0; j < 8; ++j) { const float a = acc[ai][bj][m][j >> 2][j & 3]; const float gg = gv[bj][j >> 2][j & 3];
;                         o[j] = r[j] + e[j] * ri * gg * __builtin_amdgcn_rcpf(1.f + __builtin_amdgcn_exp2f(-a * LOG2E)); }
;                     f32x4 o1, o2;
; #pragma unroll
;                     for (int j = 0; j < 4; ++j) { const unsigned a = __float_as_uint(o[j]), b = __float_as_uint(o[4 + j]); const unsigned sa = dpp_ror8(a), sb = dpp_ror8(b);
;                         o1[j] = __uint_as_float(lo ? a : sb); o2[j] = __uint_as_float(lo ? sa : b); }
;                     *(f32x4*)(orow + 32 * bj) = o1; *(f32x4*)(orow + (size_t)8 * D + 32 * bj) = o2; } }
	v_and_b32_e32 v55, 0xffff0000, v76
	v_pk_mul_f32 v[54:55], v[64:65], v[54:55] op_sel_hi:[0,1]
	v_cndmask_b32_e64 v66, v70, v74, s[0:1]
	v_addc_co_u32_e32 v49, vcc, 0, v53, vcc
	v_lshlrev_b32_e32 v34, 16, v80
	v_and_b32_e32 v35, 0xffff0000, v80
	v_pk_mul_f32 v[54:55], v[42:43], v[54:55]
	global_store_dwordx4 v[48:49], v[66:69], off
	v_mov_b32_e32 v70, v157
	v_pk_fma_f32 v[34:35], v[38:39], v[54:55], v[34:35]
	v_mov_b32_e32 v66, v157
	v_mov_b32_e32 v67, v157
	v_mov_b32_e32 v69, v157
	v_mov_b32_e32 v38, v157
	v_mov_b32_dpp v66, v50 row_ror:8 row_mask:0xf bank_mask:0xf
	v_mov_b32_dpp v67, v51 row_ror:8 row_mask:0xf bank_mask:0xf
	v_mov_b32_e32 v68, v157
	v_mov_b32_dpp v69, v36 row_ror:8 row_mask:0xf bank_mask:0xf
	v_mov_b32_dpp v70, v37 row_ror:8 row_mask:0xf bank_mask:0xf
	v_mov_b32_dpp v38, v34 row_ror:8 row_mask:0xf bank_mask:0xf
	v_mov_b32_e32 v39, v157
	v_mov_b32_dpp v68, v33 row_ror:8 row_mask:0xf bank_mask:0xf
	v_cndmask_b32_e64 v34, v69, v34, s[0:1]
	v_mov_b32_dpp v39, v35 row_ror:8 row_mask:0xf bank_mask:0xf
	v_cndmask_b32_e64 v35, v70, v35, s[0:1]
	v_cndmask_b32_e64 v33, v67, v33, s[0:1]
	v_cndmask_b32_e64 v32, v66, v32, s[0:1]
	v_cndmask_b32_e64 v38, v36, v38, s[0:1]
	v_cndmask_b32_e64 v39, v37, v39, s[0:1]
	v_cndmask_b32_e64 v37, v51, v68, s[0:1]
	v_cndmask_b32_e64 v36, v50, v65, s[0:1]
	global_store_dwordx4 v[52:53], v[32:35], off offset:128
	global_store_dwordx4 v[48:49], v[36:39], off offset:128
	s_waitcnt vmcnt(4)
	s_nop 0
	v_mov_b32_e32 v68, v228
	v_mov_b32_e32 v73, v157
	v_add_u32_e32 v38, 0xa0, v81
	v_ashrrev_i32_e32 v39, 31, v38
	v_lshlrev_b64 v[32:33], 12, v[38:39]
	v_lshl_add_u64 v[64:65], v[32:33], 0, s[16:17]
	v_lshl_add_u64 v[48:49], s[8:9], 0, v[64:65]
	v_lshl_add_u64 v[34:35], s[8:9], 0, v[32:33]
	v_lshl_add_u64 v[48:49], v[48:49], 0, v[164:165]
	v_lshl_add_u64 v[32:33], s[10:11], 0, v[32:33]
	v_lshl_add_u64 v[34:35], v[34:35], 0, v[164:165]
	v_mov_b64_e32 v[48:49], v[232:233]
	v_mov_b64_e32 v[50:51], v[234:235]
	v_lshl_add_u64 v[32:33], v[32:33], 0, v[164:165]
	v_mov_b64_e32 v[34:35], v[236:237]
	v_mov_b64_e32 v[36:37], v[238:239]
	v_mov_b32_e32 v74, v157
	v_mov_b64_e32 v[52:53], v[240:241]
	v_mov_b64_e32 v[54:55], v[242:243]
	v_lshl_add_u64 v[32:33], s[10:11], 0, v[64:65]
	v_lshl_add_u64 v[32:33], v[32:33], 0, v[164:165]
	v_mov_b64_e32 v[64:65], v[244:245]
	v_mov_b64_e32 v[66:67], v[246:247]
	s_nop 1
	v_add_u32_e32 v224, 0xb0, v81
	v_ashrrev_i32_e32 v225, 31, v224
	global_load_dword v228, v[168:169], off offset:704
	v_lshlrev_b64 v[216:217], 12, v[224:225]
	v_lshl_add_u64 v[222:223], v[216:217], 0, s[16:17]
	v_lshl_add_u64 v[220:221], s[8:9], 0, v[222:223]
	v_lshl_add_u64 v[218:219], s[8:9], 0, v[216:217]
	v_lshl_add_u64 v[220:221], v[220:221], 0, v[164:165]
	v_lshl_add_u64 v[216:217], s[10:11], 0, v[216:217]
	v_lshl_add_u64 v[218:219], v[218:219], 0, v[164:165]
	global_load_dwordx4 v[232:235], v[220:221], off
	v_lshl_add_u64 v[216:217], v[216:217], 0, v[164:165]
	global_load_dwordx4 v[236:239], v[218:219], off
	global_load_dwordx4 v[240:243], v[216:217], off
	v_lshl_add_u64 v[216:217], s[10:11], 0, v[222:223]
	v_lshl_add_u64 v[216:217], v[216:217], 0, v[164:165]
	global_load_dwordx4 v[244:247], v[216:217], off
	v_mov_b32_e32 v69, v157
	v_mov_b32_e32 v70, v157
	v_mov_b32_e32 v71, v157
	v_mov_b32_e32 v72, v157
	v_mov_b32_e32 v33, v157
	v_add_f32_e32 v16, 1.0, v16
	v_add_f32_e32 v17, 1.0, v17
	v_rcp_f32_e32 v16, v16
	v_rcp_f32_e32 v17, v17
	v_mul_f32_e32 v18, 0xbfb8aa3b, v18
	v_mul_f32_e32 v19, 0xbfb8aa3b, v19
	v_add_f32_e32 v20, 1.0, v20
	v_add_f32_e32 v21, 1.0, v21
	v_exp_f32_e32 v18, v18
	v_exp_f32_e32 v19, v19
	v_rcp_f32_e32 v20, v20
	v_rcp_f32_e32 v21, v21
	v_mul_f32_e32 v22, 0xbfb8aa3b, v22
	v_mul_f32_e32 v23, 0xbfb8aa3b, v23
	v_exp_f32_e32 v22, v22
	v_exp_f32_e32 v23, v23
	v_add_f32_e32 v18, 1.0, v18
	v_add_f32_e32 v19, 1.0, v19
	v_rcp_f32_e32 v18, v18
	v_rcp_f32_e32 v19, v19
	v_add_f32_e32 v22, 1.0, v22
	v_add_f32_e32 v23, 1.0, v23
	v_rcp_f32_e32 v22, v22
	v_rcp_f32_e32 v23, v23
	v_mul_f32_e32 v8, 0xbfb8aa3b, v8
	v_mul_f32_e32 v9, 0xbfb8aa3b, v9
	v_mul_f32_e32 v12, 0xbfb8aa3b, v12
	v_exp_f32_e32 v8, v8
	v_exp_f32_e32 v9, v9
	v_mul_f32_e32 v10, 0xbfb8aa3b, v10
	v_mul_f32_e32 v11, 0xbfb8aa3b, v11
	v_add_f32_e32 v8, 1.0, v8
	v_add_f32_e32 v9, 1.0, v9
	v_rcp_f32_e32 v8, v8
	v_rcp_f32_e32 v9, v9
	v_exp_f32_e32 v10, v10
	v_exp_f32_e32 v11, v11
	v_mul_f32_e32 v14, 0xbfb8aa3b, v14
	v_mul_f32_e32 v15, 0xbfb8aa3b, v15
	v_exp_f32_e32 v14, v14
	v_exp_f32_e32 v15, v15
	v_add_f32_e32 v10, 1.0, v10
	v_add_f32_e32 v11, 1.0, v11
	v_rcp_f32_e32 v10, v10
	v_rcp_f32_e32 v11, v11
	v_add_f32_e32 v14, 1.0, v14
	v_add_f32_e32 v15, 1.0, v15
	v_mul_f32_e32 v0, 0xbfb8aa3b, v0
	v_mul_f32_e32 v1, 0xbfb8aa3b, v1
	v_rcp_f32_e32 v14, v14
	v_rcp_f32_e32 v15, v15
	v_exp_f32_e32 v0, v0
	v_exp_f32_e32 v1, v1
	v_mul_f32_e32 v4, 0xbfb8aa3b, v4
	v_mul_f32_e32 v5, 0xbfb8aa3b, v5
	v_exp_f32_e32 v4, v4
	s_waitcnt vmcnt(59)
; __device__ __forceinline__ float bflo(unsigned w) { return __uint_as_float(w << 16); }
; __device__ __forceinline__ float bfhi(unsigned w) { return __uint_as_float(w & 0xffff0000u); }
;     const bool lo = fr < 8;
;     const int r1 = row - fr + (fr & 7), cb = col0 + (lo ? 0 : boff);
;     const u32x4 l1 = *(const u32x4*)(P + (size_t)r1 * ld + cb), l2 = *(const u32x4*)(P + (size_t)(r1 + 8) * ld + cb);
;     const u32x4 s1 = {dpp_ror8(l1.x), dpp_ror8(l1.y), dpp_ror8(l1.z), dpp_ror8(l1.w)}, s2 = {dpp_ror8(l2.x), dpp_ror8(l2.y), dpp_ror8(l2.z), dpp_ror8(l2.w)};
;     wA = lo ? l1 : s2; wB = lo ? s1 : l2;
; }
;     __device__ __forceinline__ void operator()(const f32x4 (&acc)[2][2][4][2], const Unit& u, int wr, int wc, int fr, int fq) const {
;     ...
;             for (int m = 0; m < 4; ++m) { const int row = row0 + ai * HALF + m * 16; const float ri = __builtin_amdgcn_rsqf(sse[row] * (1.f / D) + EPS);
;                 u32x4 rr[2], ee[2]; load_pair_lines(R, D, row, fr, col0, rr[0], rr[1], 32); load_pair_lines(E, D, row, fr, col0, ee[0], ee[1], 32);
;                 float* orow = OUT + (size_t)(row - fr + (fr & 7)) * D + col0 + (lo ? 0 : 4);
; #pragma unroll
;                 for (int bj = 0; bj < 2; ++bj) { const u32x4 rw = rr[bj], ew = ee[bj];
;                     const float r[8] = {bflo(rw.x), bfhi(rw.x), bflo(rw.y), bfhi(rw.y), bflo(rw.z), bfhi(rw.z), bflo(rw.w), bfhi(rw.w)};
;                     const float e[8] = {bflo(ew.x), bfhi(ew.x), bflo(ew.y), bfhi(ew.y), bflo(ew.z), bfhi(ew.z), bflo(ew.w), bfhi(ew.w)};
;                     float o[8];
; #pragma unroll
;                     for (int j = 0; j < 8; ++j) { const float a = acc[ai][bj][m][j >> 2][j & 3]; const float gg = gv[bj][j >> 2][j & 3];
;                         o[j] = r[j] + e[j] * ri * gg * __builtin_amdgcn_rcpf(1.f + __builtin_amdgcn_exp2f(-a * LOG2E)); }
;                     f32x4 o1, o2;
; #pragma unroll
;                     for (int j = 0; j < 4; ++j) { const unsigned a = __float_as_uint(o[j]), b = __float_as_uint(o[4 + j]); const unsigned sa = dpp_ror8(a), sb = dpp_ror8(b);
;                         o1[j] = __uint_as_float(lo ? a : sb); o2[j] = __uint_as_float(lo ? sa : b); }
;                     *(f32x4*)(orow + 32 * bj) = o1; *(f32x4*)(orow + (size_t)8 * D + 32 * bj) = o2; } }
	v_fmamk_f32 v32, v68, 0x3a000000, v182
	v_mov_b32_e32 v68, v157
	v_rsq_f32_e32 v32, v32
	v_exp_f32_e32 v5, v5
	v_add_f32_e32 v0, 1.0, v0
	v_add_f32_e32 v1, 1.0, v1
	v_rcp_f32_e32 v0, v0
	v_rcp_f32_e32 v1, v1
	v_mul_f32_e32 v2, 0xbfb8aa3b, v2
	v_mul_f32_e32 v3, 0xbfb8aa3b, v3
	v_add_f32_e32 v4, 1.0, v4
	v_mov_b32_dpp v73, v50 row_ror:8 row_mask:0xf bank_mask:0xf
	v_mov_b32_dpp v74, v51 row_ror:8 row_mask:0xf bank_mask:0xf
	v_mov_b32_dpp v69, v36 row_ror:8 row_mask:0xf bank_mask:0xf
	v_mov_b32_dpp v70, v37 row_ror:8 row_mask:0xf bank_mask:0xf
	v_mov_b32_dpp v71, v48 row_ror:8 row_mask:0xf bank_mask:0xf
	v_mov_b32_dpp v72, v49 row_ror:8 row_mask:0xf bank_mask:0xf
	v_cndmask_b32_e64 v74, v74, v37, s[0:1]
	v_cndmask_b32_e64 v37, v73, v36, s[0:1]
	v_mov_b32_e32 v36, v157
	v_mov_b32_dpp v33, v34 row_ror:8 row_mask:0xf bank_mask:0xf
	v_mov_b32_dpp v68, v35 row_ror:8 row_mask:0xf bank_mask:0xf
	v_cndmask_b32_e64 v72, v72, v35, s[0:1]
	v_cndmask_b32_e64 v71, v71, v34, s[0:1]
	v_cndmask_b32_e64 v51, v51, v70, s[0:1]
	v_mov_b32_e32 v34, v157
	v_mov_b32_e32 v35, v157
	v_mov_b32_dpp v36, v54 row_ror:8 row_mask:0xf bank_mask:0xf
	v_mov_b32_e32 v70, v157
	v_cndmask_b32_e64 v49, v49, v68, s[0:1]
	v_cndmask_b32_e64 v33, v48, v33, s[0:1]
	v_cndmask_b32_e64 v48, v50, v69, s[0:1]
	v_mov_b32_dpp v34, v52 row_ror:8 row_mask:0xf bank_mask:0xf
	v_mov_b32_dpp v35, v53 row_ror:8 row_mask:0xf bank_mask:0xf
	v_mov_b32_e32 v68, v157
	v_mov_b32_e32 v69, v157
	v_mov_b32_dpp v70, v66 row_ror:8 row_mask:0xf bank_mask:0xf
	v_cndmask_b32_e64 v66, v66, v36, s[0:1]
	v_exp_f32_e32 v36, v28
	v_mul_f32_e32 v28, 0xbfb8aa3b, v29
	v_mov_b32_dpp v68, v64 row_ror:8 row_mask:0xf bank_mask:0xf
	v_mov_b32_dpp v69, v65 row_ror:8 row_mask:0xf bank_mask:0xf
	v_cndmask_b32_e64 v65, v65, v35, s[0:1]
	v_cndmask_b32_e64 v64, v64, v34, s[0:1]
	v_lshlrev_b64 v[34:35], 13, v[38:39]
	v_exp_f32_e32 v38, v28
	v_lshl_add_u64 v[34:35], s[4:5], 0, v[34:35]
	v_cndmask_b32_e64 v54, v70, v54, s[0:1]
	v_lshl_add_u64 v[34:35], v[34:35], 0, v[166:167]
	v_lshl_add_u64 v[28:29], v[34:35], 0, v[156:157]
	v_add_f32_e32 v35, 1.0, v38
	v_lshlrev_b32_e32 v38, 16, v54
	v_and_b32_e32 v39, 0xffff0000, v54
	v_add_f32_e32 v34, 1.0, v36
	v_pk_mul_f32 v[38:39], v[32:33], v[38:39] op_sel_hi:[0,1]
	v_cndmask_b32_e64 v52, v68, v52, s[0:1]
	v_rcp_f32_e32 v34, v34
	v_rcp_f32_e32 v35, v35
	v_lshlrev_b32_e32 v36, 16, v37
	v_and_b32_e32 v37, 0xffff0000, v37
	v_pk_mul_f32 v[38:39], v[60:61], v[38:39]
	v_mov_b32_e32 v73, v157
	v_pk_fma_f32 v[38:39], v[24:25], v[38:39], v[36:37]
	v_lshlrev_b32_e32 v36, 16, v52
	v_and_b32_e32 v37, 0xffff0000, v52
	v_mov_b32_e32 v50, v157
	v_mov_b32_dpp v73, v67 row_ror:8 row_mask:0xf bank_mask:0xf
	v_pk_mul_f32 v[36:37], v[32:33], v[36:37] op_sel_hi:[0,1]
	v_mov_b32_dpp v50, v55 row_ror:8 row_mask:0xf bank_mask:0xf
	v_cndmask_b32_e64 v55, v73, v55, s[0:1]
	v_lshlrev_b32_e32 v24, 16, v71
	v_and_b32_e32 v25, 0xffff0000, v71
	v_pk_mul_f32 v[36:37], v[56:57], v[36:37]
	v_cndmask_b32_e64 v53, v69, v53, s[0:1]
	v_pk_fma_f32 v[24:25], v[34:35], v[36:37], v[24:25]
	v_lshlrev_b32_e32 v36, 16, v55
	v_and_b32_e32 v37, 0xffff0000, v55
	v_pk_mul_f32 v[36:37], v[32:33], v[36:37] op_sel_hi:[0,1]
	v_lshlrev_b32_e32 v34, 16, v74
	v_and_b32_e32 v35, 0xffff0000, v74
	v_pk_mul_f32 v[36:37], v[62:63], v[36:37]
	v_cndmask_b32_e64 v50, v67, v50, s[0:1]
	v_pk_fma_f32 v[34:35], v[26:27], v[36:37], v[34:35]
	v_lshlrev_b32_e32 v36, 16, v53
	v_and_b32_e32 v37, 0xffff0000, v53
	v_pk_mul_f32 v[36:37], v[32:33], v[36:37] op_sel_hi:[0,1]
	v_lshlrev_b32_e32 v26, 16, v72
	v_and_b32_e32 v27, 0xffff0000, v72
	v_pk_mul_f32 v[36:37], v[58:59], v[36:37]
	v_mov_b32_e32 v54, v157
	v_pk_fma_f32 v[26:27], v[30:31], v[36:37], v[26:27]
	v_mov_b32_e32 v30, v157
	v_mov_b32_e32 v31, v157
	v_mov_b32_e32 v67, v157
	v_mov_b32_e32 v55, v157
	v_mov_b32_e32 v69, v157
	v_mov_b32_dpp v30, v26 row_ror:8 row_mask:0xf bank_mask:0xf
	v_mov_b32_dpp v31, v27 row_ror:8 row_mask:0xf bank_mask:0xf
	v_mov_b32_dpp v54, v38 row_ror:8 row_mask:0xf bank_mask:0xf
	v_mov_b32_dpp v67, v39 row_ror:8 row_mask:0xf bank_mask:0xf
	v_mov_b32_e32 v52, v157
	v_mov_b32_e32 v68, v157
	v_mov_b32_dpp v55, v34 row_ror:8 row_mask:0xf bank_mask:0xf
	v_mov_b32_dpp v69, v35 row_ror:8 row_mask:0xf bank_mask:0xf
	v_cndmask_b32_e64 v37, v35, v31, s[0:1]
	v_cndmask_b32_e64 v36, v34, v30, s[0:1]
	v_lshlrev_b32_e32 v30, 16, v66
	v_and_b32_e32 v31, 0xffff0000, v66
	v_mov_b32_dpp v52, v24 row_ror:8 row_mask:0xf bank_mask:0xf
	v_mov_b32_dpp v68, v25 row_ror:8 row_mask:0xf bank_mask:0xf
	v_cndmask_b32_e64 v27, v69, v27, s[0:1]
	v_cndmask_b32_e64 v26, v55, v26, s[0:1]
	v_cndmask_b32_e64 v25, v67, v25, s[0:1]
	v_cndmask_b32_e64 v24, v54, v24, s[0:1]
	v_pk_mul_f32 v[30:31], v[32:33], v[30:31] op_sel_hi:[0,1]
	global_store_dwordx4 v[28:29], v[24:27], off
	v_pk_mul_f32 v[30:31], v[44:45], v[30:31]
	v_cndmask_b32_e64 v35, v39, v68, s[0:1]
	v_lshlrev_b32_e32 v26, 16, v48
	v_and_b32_e32 v27, 0xffff0000, v48
	v_pk_fma_f32 v[26:27], v[16:17], v[30:31], v[26:27]
	v_lshlrev_b32_e32 v30, 16, v64
	v_and_b32_e32 v31, 0xffff0000, v64
	v_pk_mul_f32 v[30:31], v[32:33], v[30:31] op_sel_hi:[0,1]
	v_lshlrev_b32_e32 v16, 16, v33
	v_and_b32_e32 v17, 0xffff0000, v33
	v_pk_mul_f32 v[30:31], v[40:41], v[30:31]
	v_mov_b32_e32 v33, v157
	v_pk_fma_f32 v[16:17], v[20:21], v[30:31], v[16:17]
	v_lshlrev_b32_e32 v30, 16, v50
	v_and_b32_e32 v31, 0xffff0000, v50
	v_mov_b32_dpp v33, v16 row_ror:8 row_mask:0xf bank_mask:0xf
	v_pk_mul_f32 v[30:31], v[32:33], v[30:31] op_sel_hi:[0,1]
	v_add_co_u32_e32 v24, vcc, s45, v28
	v_lshlrev_b32_e32 v20, 16, v51
	v_and_b32_e32 v21, 0xffff0000, v51
	v_pk_mul_f32 v[30:31], v[46:47], v[30:31]
; __device__ __forceinline__ float bflo(unsigned w) { return __uint_as_float(w << 16); }
; __device__ __forceinline__ float bfhi(unsigned w) { return __uint_as_float(w & 0xffff0000u); }
;     const bool lo = fr < 8;
;     const int r1 = row - fr + (fr & 7), cb = col0 + (lo ? 0 : boff);
;     const u32x4 l1 = *(const u32x4*)(P + (size_t)r1 * ld + cb), l2 = *(const u32x4*)(P + (size_t)(r1 + 8) * ld + cb);
;     const u32x4 s1 = {dpp_ror8(l1.x), dpp_ror8(l1.y), dpp_ror8(l1.z), dpp_ror8(l1.w)}, s2 = {dpp_ror8(l2.x), dpp_ror8(l2.y), dpp_ror8(l2.z), dpp_ror8(l2.w)};
;     wA = lo ? l1 : s2; wB = lo ? s1 : l2;
; }
;     __device__ __forceinline__ void operator()(const f32x4 (&acc)[2][2][4][2], const Unit& u, int wr, int wc, int fr, int fq) const {
;     ...
;             for (int m = 0; m < 4; ++m) { const int row = row0 + ai * HALF + m * 16; const float ri = __builtin_amdgcn_rsqf(sse[row] * (1.f / D) + EPS);
;                 u32x4 rr[2], ee[2]; load_pair_lines(R, D, row, fr, col0, rr[0], rr[1], 32); load_pair_lines(E, D, row, fr, col0, ee[0], ee[1], 32);
;                 float* orow = OUT + (size_t)(row - fr + (fr & 7)) * D + col0 + (lo ? 0 : 4);
; #pragma unroll
;                 for (int bj = 0; bj < 2; ++bj) { const u32x4 rw = rr[bj], ew = ee[bj];
;                     const float r[8] = {bflo(rw.x), bfhi(rw.x), bflo(rw.y), bfhi(rw.y), bflo(rw.z), bfhi(rw.z), bflo(rw.w), bfhi(rw.w)};
;                     const float e[8] = {bflo(ew.x), bfhi(ew.x), bflo(ew.y), bfhi(ew.y), bflo(ew.z), bfhi(ew.z), bflo(ew.w), bfhi(ew.w)};
;                     float o[8];
; #pragma unroll
;                     for (int j = 0; j < 8; ++j) { const float a = acc[ai][bj][m][j >> 2][j & 3]; const float gg = gv[bj][j >> 2][j & 3];
;                         o[j] = r[j] + e[j] * ri * gg * __builtin_amdgcn_rcpf(1.f + __builtin_amdgcn_exp2f(-a * LOG2E)); }
;                     f32x4 o1, o2;
; #pragma unroll
;                     for (int j = 0; j < 4; ++j) { const unsigned a = __float_as_uint(o[j]), b = __float_as_uint(o[4 + j]); const unsigned sa = dpp_ror8(a), sb = dpp_ror8(b);
;                         o1[j] = __uint_as_float(lo ? a : sb); o2[j] = __uint_as_float(lo ? sa : b); }
;                     *(f32x4*)(orow + 32 * bj) = o1; *(f32x4*)(orow + (size_t)8 * D + 32 * bj) = o2; } }
	v_cndmask_b32_e64 v34, v38, v52, s[0:1]
	v_addc_co_u32_e32 v25, vcc, 0, v29, vcc
	v_pk_fma_f32 v[20:21], v[18:19], v[30:31], v[20:21]
	v_lshlrev_b32_e32 v30, 16, v65
	v_and_b32_e32 v31, 0xffff0000, v65
	global_store_dwordx4 v[24:25], v[34:37], off
	v_pk_mul_f32 v[30:31], v[32:33], v[30:31] op_sel_hi:[0,1]
	v_mov_b32_e32 v38, v157
	v_mov_b32_e32 v34, v157
	v_mov_b32_e32 v35, v157
	v_mov_b32_e32 v37, v157
	v_mov_b32_dpp v34, v26 row_ror:8 row_mask:0xf bank_mask:0xf
	v_lshlrev_b32_e32 v18, 16, v49
	v_and_b32_e32 v19, 0xffff0000, v49
	v_pk_mul_f32 v[30:31], v[42:43], v[30:31]
	v_mov_b32_dpp v35, v27 row_ror:8 row_mask:0xf bank_mask:0xf
	v_mov_b32_e32 v36, v157
	v_mov_b32_dpp v37, v20 row_ror:8 row_mask:0xf bank_mask:0xf
	v_mov_b32_dpp v38, v21 row_ror:8 row_mask:0xf bank_mask:0xf
	v_pk_fma_f32 v[18:19], v[22:23], v[30:31], v[18:19]
	v_mov_b32_e32 v22, v157
	v_mov_b32_e32 v23, v157
	v_cndmask_b32_e64 v16, v34, v16, s[0:1]
	v_add_u32_e32 v34, 0xb0, v81
	v_mov_b32_dpp v36, v17 row_ror:8 row_mask:0xf bank_mask:0xf
	v_mov_b32_dpp v22, v18 row_ror:8 row_mask:0xf bank_mask:0xf
	v_mov_b32_dpp v23, v19 row_ror:8 row_mask:0xf bank_mask:0xf
	v_cndmask_b32_e64 v19, v38, v19, s[0:1]
	v_cndmask_b32_e64 v18, v37, v18, s[0:1]
	v_cndmask_b32_e64 v17, v35, v17, s[0:1]
	v_ashrrev_i32_e32 v35, 31, v34
	v_cndmask_b32_e64 v23, v21, v23, s[0:1]
	v_cndmask_b32_e64 v22, v20, v22, s[0:1]
	v_cndmask_b32_e64 v21, v27, v36, s[0:1]
	v_cndmask_b32_e64 v20, v26, v33, s[0:1]
	global_store_dwordx4 v[28:29], v[16:19], off offset:128
	global_store_dwordx4 v[24:25], v[20:23], off offset:128
	s_waitcnt vmcnt(4)
	s_nop 0
	v_mov_b32_e32 v36, v228
	v_lshlrev_b64 v[16:17], 12, v[34:35]
	v_lshl_add_u64 v[30:31], v[16:17], 0, s[16:17]
	v_lshl_add_u64 v[22:23], s[8:9], 0, v[30:31]
	v_lshl_add_u64 v[18:19], s[8:9], 0, v[16:17]
	v_lshl_add_u64 v[22:23], v[22:23], 0, v[164:165]
	v_lshl_add_u64 v[16:17], s[10:11], 0, v[16:17]
	v_lshl_add_u64 v[18:19], v[18:19], 0, v[164:165]
	v_mov_b64_e32 v[22:23], v[232:233]
	v_mov_b64_e32 v[24:25], v[234:235]
	v_lshl_add_u64 v[16:17], v[16:17], 0, v[164:165]
	v_mov_b64_e32 v[18:19], v[236:237]
	v_mov_b64_e32 v[20:21], v[238:239]
	v_mov_b32_e32 v49, v157
	v_mov_b64_e32 v[26:27], v[240:241]
	v_mov_b64_e32 v[28:29], v[242:243]
	v_lshl_add_u64 v[16:17], s[10:11], 0, v[30:31]
	v_lshl_add_u64 v[16:17], v[16:17], 0, v[164:165]
	v_mov_b64_e32 v[30:31], v[244:245]
	v_mov_b64_e32 v[32:33], v[246:247]
	s_nop 1
	v_mov_b32_e32 v50, v157
	v_mov_b32_e32 v17, v157
	v_mov_b32_e32 v37, v157
	v_mov_b32_e32 v38, v157
	v_mov_b32_e32 v48, v157
	v_mov_b32_e32 v39, v157
	v_add_f32_e32 v5, 1.0, v5
	v_exp_f32_e32 v2, v2
	v_exp_f32_e32 v3, v3
	v_rcp_f32_e32 v4, v4
	v_rcp_f32_e32 v5, v5
	v_mul_f32_e32 v6, 0xbfb8aa3b, v6
	v_mul_f32_e32 v7, 0xbfb8aa3b, v7
	v_exp_f32_e32 v6, v6
	v_exp_f32_e32 v7, v7
	v_add_f32_e32 v2, 1.0, v2
	v_add_f32_e32 v3, 1.0, v3
	v_rcp_f32_e32 v2, v2
	v_rcp_f32_e32 v3, v3
	v_add_f32_e32 v6, 1.0, v6
	v_add_f32_e32 v7, 1.0, v7
	v_rcp_f32_e32 v6, v6
	v_rcp_f32_e32 v7, v7
	s_mov_b32 s53, s18
	s_mov_b32 s30, s22
	s_mov_b64 s[36:37], s[28:29]
	s_mov_b64 s[34:35], s[24:25]
	s_waitcnt vmcnt(63)
; __device__ __forceinline__ float bflo(unsigned w) { return __uint_as_float(w << 16); }
; #define PG8_BAR __builtin_amdgcn_s_barrier()
;     __device__ __forceinline__ void operator()(const f32x4 (&acc)[2][2][4][2], const Unit& u, int wr, int wc, int fr, int fq) const {
;     ...
;             for (int m = 0; m < 4; ++m) { const int row = row0 + ai * HALF + m * 16; const float ri = __builtin_amdgcn_rsqf(sse[row] * (1.f / D) + EPS);
;                 u32x4 rr[2], ee[2]; load_pair_lines(R, D, row, fr, col0, rr[0], rr[1], 32); load_pair_lines(E, D, row, fr, col0, ee[0], ee[1], 32);
;                 float* orow = OUT + (size_t)(row - fr + (fr & 7)) * D + col0 + (lo ? 0 : 4);
; #pragma unroll
;                 for (int bj = 0; bj < 2; ++bj) { const u32x4 rw = rr[bj], ew = ee[bj];
;                     const float r[8] = {bflo(rw.x), bfhi(rw.x), bflo(rw.y), bfhi(rw.y), bflo(rw.z), bfhi(rw.z), bflo(rw.w), bfhi(rw.w)};
;                     const float e[8] = {bflo(ew.x), bfhi(ew.x), bflo(ew.y), bfhi(ew.y), bflo(ew.z), bfhi(ew.z), bflo(ew.w), bfhi(ew.w)};
;                     float o[8];
; #pragma unroll
;                     for (int j = 0; j < 8; ++j) { const float a = acc[ai][bj][m][j >> 2][j & 3]; const float gg = gv[bj][j >> 2][j & 3];
;                         o[j] = r[j] + e[j] * ri * gg * __builtin_amdgcn_rcpf(1.f + __builtin_amdgcn_exp2f(-a * LOG2E)); }
;                     f32x4 o1, o2;
; #pragma unroll
;                     for (int j = 0; j < 4; ++j) { const unsigned a = __float_as_uint(o[j]), b = __float_as_uint(o[4 + j]); const unsigned sa = dpp_ror8(a), sb = dpp_ror8(b);
;                         o1[j] = __uint_as_float(lo ? a : sb); o2[j] = __uint_as_float(lo ? sa : b); }
;                     *(f32x4*)(orow + 32 * bj) = o1; *(f32x4*)(orow + (size_t)8 * D + 32 * bj) = o2; } }
; template <class Epi>
; __device__ __forceinline__ void gemm_phase(LAS unsigned char* lds, const Gemm g, const StaticOrder& S, const Epi& E) {
;     ...
;         if (!has_next) break;
; #pragma unroll
;         for (int a = 0; a < 2; ++a)
; #pragma unroll
;             for (int b = 0; b < 2; ++b)
; #pragma unroll
;                 for (int m = 0; m < 4; ++m)
; #pragma unroll
;                     for (int n = 0; n < 2; ++n) acc[a][b][m][n] = (f32x4){0.f, 0.f, 0.f, 0.f};
;         cur = nxt; cA = nA; cB = nB; ++ui;
;     }
;     PG8_WAIT_V(0);
;     if (wr == 0) PG8_BAR;
;     PG8_BAR;
	v_fmamk_f32 v16, v36, 0x3a000000, v182
	v_mov_b32_e32 v36, v157
	v_rsq_f32_e32 v16, v16
	v_mov_b32_dpp v49, v24 row_ror:8 row_mask:0xf bank_mask:0xf
	v_mov_b32_dpp v50, v25 row_ror:8 row_mask:0xf bank_mask:0xf
	v_mov_b32_dpp v17, v18 row_ror:8 row_mask:0xf bank_mask:0xf
	v_mov_b32_dpp v36, v19 row_ror:8 row_mask:0xf bank_mask:0xf
	v_mov_b32_dpp v37, v20 row_ror:8 row_mask:0xf bank_mask:0xf
	v_mov_b32_dpp v38, v21 row_ror:8 row_mask:0xf bank_mask:0xf
	v_mov_b32_dpp v48, v23 row_ror:8 row_mask:0xf bank_mask:0xf
	v_cndmask_b32_e64 v50, v50, v21, s[0:1]
	v_cndmask_b32_e64 v21, v49, v20, s[0:1]
	v_mov_b32_e32 v20, v157
	v_mov_b32_dpp v39, v22 row_ror:8 row_mask:0xf bank_mask:0xf
	v_cndmask_b32_e64 v48, v48, v19, s[0:1]
	v_cndmask_b32_e64 v36, v23, v36, s[0:1]
	v_cndmask_b32_e64 v25, v25, v38, s[0:1]
	v_cndmask_b32_e64 v17, v22, v17, s[0:1]
	v_mov_b32_e32 v19, v157
	v_mov_b32_dpp v20, v28 row_ror:8 row_mask:0xf bank_mask:0xf
	v_mov_b32_e32 v22, v157
	v_mov_b32_e32 v23, v157
	v_mov_b32_e32 v38, v157
	v_cndmask_b32_e64 v39, v39, v18, s[0:1]
	v_cndmask_b32_e64 v24, v24, v37, s[0:1]
	v_mov_b32_e32 v18, v157
	v_mov_b32_dpp v19, v27 row_ror:8 row_mask:0xf bank_mask:0xf
	v_mov_b32_dpp v22, v29 row_ror:8 row_mask:0xf bank_mask:0xf
	v_mov_b32_dpp v23, v30 row_ror:8 row_mask:0xf bank_mask:0xf
	v_mov_b32_e32 v37, v157
	v_mov_b32_dpp v38, v32 row_ror:8 row_mask:0xf bank_mask:0xf
	v_cndmask_b32_e64 v32, v32, v20, s[0:1]
	v_exp_f32_e32 v20, v12
	v_mul_f32_e32 v12, 0xbfb8aa3b, v13
	v_mov_b32_dpp v18, v26 row_ror:8 row_mask:0xf bank_mask:0xf
	v_mov_b32_dpp v37, v31 row_ror:8 row_mask:0xf bank_mask:0xf
	v_cndmask_b32_e64 v26, v23, v26, s[0:1]
	v_cndmask_b32_e64 v23, v38, v28, s[0:1]
	v_cndmask_b32_e64 v28, v31, v19, s[0:1]
	v_cndmask_b32_e64 v31, v33, v22, s[0:1]
	v_exp_f32_e32 v22, v12
	v_cndmask_b32_e64 v30, v30, v18, s[0:1]
	v_lshlrev_b64 v[18:19], 13, v[34:35]
	v_lshl_add_u64 v[18:19], s[4:5], 0, v[18:19]
	v_lshl_add_u64 v[18:19], v[18:19], 0, v[166:167]
	v_lshl_add_u64 v[12:13], v[18:19], 0, v[156:157]
	v_add_f32_e32 v19, 1.0, v22
	v_lshlrev_b32_e32 v22, 16, v23
	v_and_b32_e32 v23, 0xffff0000, v23
	v_add_f32_e32 v18, 1.0, v20
	v_pk_mul_f32 v[22:23], v[16:17], v[22:23] op_sel_hi:[0,1]
	v_rcp_f32_e32 v18, v18
	v_rcp_f32_e32 v19, v19
	v_lshlrev_b32_e32 v20, 16, v21
	v_and_b32_e32 v21, 0xffff0000, v21
	v_pk_mul_f32 v[22:23], v[60:61], v[22:23]
	v_mov_b32_e32 v49, v157
	v_pk_fma_f32 v[22:23], v[8:9], v[22:23], v[20:21]
	v_lshlrev_b32_e32 v20, 16, v26
	v_and_b32_e32 v21, 0xffff0000, v26
	v_mov_b32_dpp v49, v33 row_ror:8 row_mask:0xf bank_mask:0xf
	v_pk_mul_f32 v[20:21], v[16:17], v[20:21] op_sel_hi:[0,1]
	v_cndmask_b32_e64 v29, v49, v29, s[0:1]
	v_lshlrev_b32_e32 v8, 16, v39
	v_and_b32_e32 v9, 0xffff0000, v39
	v_pk_mul_f32 v[20:21], v[56:57], v[20:21]
	v_cndmask_b32_e64 v27, v37, v27, s[0:1]
	v_pk_fma_f32 v[8:9], v[18:19], v[20:21], v[8:9]
	v_lshlrev_b32_e32 v20, 16, v29
	v_and_b32_e32 v21, 0xffff0000, v29
	v_pk_mul_f32 v[20:21], v[16:17], v[20:21] op_sel_hi:[0,1]
	v_lshlrev_b32_e32 v18, 16, v50
	v_and_b32_e32 v19, 0xffff0000, v50
	v_pk_mul_f32 v[20:21], v[62:63], v[20:21]
	v_mov_b32_e32 v33, v157
	v_pk_fma_f32 v[18:19], v[10:11], v[20:21], v[18:19]
	v_lshlrev_b32_e32 v20, 16, v27
	v_and_b32_e32 v21, 0xffff0000, v27
	v_pk_mul_f32 v[20:21], v[16:17], v[20:21] op_sel_hi:[0,1]
	v_lshlrev_b32_e32 v10, 16, v48
	v_and_b32_e32 v11, 0xffff0000, v48
	v_pk_mul_f32 v[20:21], v[58:59], v[20:21]
	v_mov_b32_e32 v34, v157
	v_pk_fma_f32 v[10:11], v[14:15], v[20:21], v[10:11]
	v_mov_b32_e32 v14, v157
	v_mov_b32_e32 v15, v157
	v_mov_b32_e32 v29, v157
	v_mov_b32_e32 v37, v157
	v_mov_b32_dpp v14, v10 row_ror:8 row_mask:0xf bank_mask:0xf
	v_mov_b32_dpp v15, v11 row_ror:8 row_mask:0xf bank_mask:0xf
	v_mov_b32_dpp v33, v22 row_ror:8 row_mask:0xf bank_mask:0xf
	v_mov_b32_dpp v34, v23 row_ror:8 row_mask:0xf bank_mask:0xf
	v_mov_b32_e32 v26, v157
	v_mov_b32_e32 v35, v157
	v_mov_b32_dpp v29, v18 row_ror:8 row_mask:0xf bank_mask:0xf
	v_mov_b32_dpp v37, v19 row_ror:8 row_mask:0xf bank_mask:0xf
	v_cndmask_b32_e64 v21, v19, v15, s[0:1]
	v_cndmask_b32_e64 v20, v18, v14, s[0:1]
	v_lshlrev_b32_e32 v14, 16, v32
	v_and_b32_e32 v15, 0xffff0000, v32
	v_mov_b32_dpp v26, v8 row_ror:8 row_mask:0xf bank_mask:0xf
	v_mov_b32_dpp v35, v9 row_ror:8 row_mask:0xf bank_mask:0xf
	v_cndmask_b32_e64 v11, v37, v11, s[0:1]
	v_cndmask_b32_e64 v10, v29, v10, s[0:1]
	v_cndmask_b32_e64 v9, v34, v9, s[0:1]
	v_cndmask_b32_e64 v8, v33, v8, s[0:1]
	v_pk_mul_f32 v[14:15], v[16:17], v[14:15] op_sel_hi:[0,1]
	global_store_dwordx4 v[12:13], v[8:11], off
	v_pk_mul_f32 v[14:15], v[44:45], v[14:15]
	v_cndmask_b32_e64 v19, v23, v35, s[0:1]
	v_lshlrev_b32_e32 v10, 16, v24
	v_and_b32_e32 v11, 0xffff0000, v24
	v_pk_fma_f32 v[10:11], v[0:1], v[14:15], v[10:11]
	v_lshlrev_b32_e32 v14, 16, v30
	v_and_b32_e32 v15, 0xffff0000, v30
	v_pk_mul_f32 v[14:15], v[16:17], v[14:15] op_sel_hi:[0,1]
	v_lshlrev_b32_e32 v0, 16, v17
	v_and_b32_e32 v1, 0xffff0000, v17
	v_pk_mul_f32 v[14:15], v[40:41], v[14:15]
	v_mov_b32_e32 v17, v157
	v_pk_fma_f32 v[0:1], v[4:5], v[14:15], v[0:1]
	v_lshlrev_b32_e32 v14, 16, v31
	v_and_b32_e32 v15, 0xffff0000, v31
	v_mov_b32_dpp v17, v0 row_ror:8 row_mask:0xf bank_mask:0xf
	v_pk_mul_f32 v[14:15], v[16:17], v[14:15] op_sel_hi:[0,1]
	v_lshlrev_b32_e32 v4, 16, v25
	v_and_b32_e32 v5, 0xffff0000, v25
	v_pk_mul_f32 v[14:15], v[46:47], v[14:15]
	v_add_co_u32_e32 v8, vcc, s45, v12
	v_pk_fma_f32 v[4:5], v[2:3], v[14:15], v[4:5]
	v_lshlrev_b32_e32 v14, 16, v28
	v_and_b32_e32 v15, 0xffff0000, v28
	v_cndmask_b32_e64 v18, v22, v26, s[0:1]
	v_addc_co_u32_e32 v9, vcc, 0, v13, vcc
	v_pk_mul_f32 v[14:15], v[16:17], v[14:15] op_sel_hi:[0,1]
	global_store_dwordx4 v[8:9], v[18:21], off
	v_mov_b32_e32 v22, v157
	v_lshlrev_b32_e32 v2, 16, v36
	v_mov_b32_e32 v18, v157
	v_mov_b32_e32 v19, v157
	v_mov_b32_e32 v21, v157
	v_and_b32_e32 v3, 0xffff0000, v36
	v_pk_mul_f32 v[14:15], v[42:43], v[14:15]
	v_mov_b32_dpp v18, v10 row_ror:8 row_mask:0xf bank_mask:0xf
	v_mov_b32_dpp v19, v11 row_ror:8 row_mask:0xf bank_mask:0xf
	v_mov_b32_e32 v20, v157
	v_mov_b32_dpp v21, v4 row_ror:8 row_mask:0xf bank_mask:0xf
	v_mov_b32_dpp v22, v5 row_ror:8 row_mask:0xf bank_mask:0xf
	v_pk_fma_f32 v[2:3], v[6:7], v[14:15], v[2:3]
	v_mov_b32_e32 v6, v157
	v_mov_b32_e32 v7, v157
	v_mov_b32_dpp v20, v1 row_ror:8 row_mask:0xf bank_mask:0xf
	v_mov_b32_dpp v6, v2 row_ror:8 row_mask:0xf bank_mask:0xf
	v_mov_b32_dpp v7, v3 row_ror:8 row_mask:0xf bank_mask:0xf
	v_cndmask_b32_e64 v3, v22, v3, s[0:1]
	v_cndmask_b32_e64 v2, v21, v2, s[0:1]
	v_cndmask_b32_e64 v1, v19, v1, s[0:1]
	v_cndmask_b32_e64 v0, v18, v0, s[0:1]
	s_and_b64 vcc, exec, s[26:27]
	v_cndmask_b32_e64 v7, v5, v7, s[0:1]
	v_cndmask_b32_e64 v6, v4, v6, s[0:1]
	v_cndmask_b32_e64 v5, v11, v20, s[0:1]
	v_cndmask_b32_e64 v4, v10, v17, s[0:1]
	global_store_dwordx4 v[12:13], v[0:3], off offset:128
	global_store_dwordx4 v[8:9], v[4:7], off offset:128
	s_cbranch_vccz .LBB0_1595
	s_waitcnt vmcnt(0)
	s_cmpk_gt_u32 s3, 0xff
	s_cbranch_scc1 .LBB0_1607
	s_barrier
